# all v_pk_mul/add/fma_f32 split into two scalar VALU ops (same results)
# baseline (speedup 1.0000x reference)
; #define GAS __attribute__((address_space(1)))
; template <int MODE, bool XBF>
; __device__ __forceinline__ void rmsnorm_rows(const void* x, const float* gain, bf16_t* H, int gw, int NGW, int lane, const LAS float* WF, const float* fbias, float* LF) {
;     ...
;     for (int row0 = gw * RB; row0 < T; row0 += NGW * RB) {
;         f32x4 v[RB][2][2]; float s[RB];
; #pragma unroll
;         for (int r = 0; r < RB; ++r)
; #pragma unroll
;             for (int j = 0; j < 2; ++j) { const size_t xo = (size_t)(row0 + r) * D + 512 * j + lane * 8;
;                 if (XBF) unpack8h(*(const GAS u32x4*)((const bf16_t*)x + xo), v[r][j][0], v[r][j][1]);
;                 else { v[r][j][0] = *(const GAS f32x4*)((const float*)x + xo); v[r][j][1] = *(const GAS f32x4*)((const float*)x + xo + 4); } }
; #pragma unroll
;         for (int r = 0; r < RB; ++r) { s[r] = 0.f;
; #pragma unroll
;             for (int j = 0; j < 2; ++j)
; #pragma unroll
;                 for (int e = 0; e < 2; ++e) s[r] += (v[r][j][e][0] * v[r][j][e][0] + v[r][j][e][1] * v[r][j][e][1]) + (v[r][j][e][2] * v[r][j][e][2] + v[r][j][e][3] * v[r][j][e][3]); }
; #pragma unroll
;         for (int o = 1; o < 64; o <<= 1)
; #pragma unroll
;             for (int r = 0; r < RB; ++r) s[r] += __shfl_xor(s[r], o);
.LBB0_50:
	s_waitcnt lgkmcnt(0)
	v_lshl_add_u64 v[16:17], v[150:151], 0, s[26:27]
	v_lshl_add_u64 v[20:21], v[150:151], 0, s[28:29]
	global_load_dwordx4 v[32:35], v[16:17], off offset:16
	global_load_dwordx4 v[36:39], v[20:21], off offset:16
	v_lshl_add_u64 v[16:17], v[150:151], 0, s[30:31]
	v_add_co_u32_e32 v24, vcc, 0xffffd000, v150
	global_load_dwordx4 v[16:19], v[16:17], off offset:16
	s_nop 0
	v_addc_co_u32_e32 v25, vcc, -1, v151, vcc
	v_lshl_add_u64 v[20:21], v[150:151], 0, s[34:35]
	v_add_co_u32_e32 v48, vcc, s17, v150
	global_load_dwordx4 v[20:23], v[20:21], off offset:16
	s_nop 0
	global_load_dwordx4 v[44:47], v[24:25], off offset:-2064
	global_load_dwordx4 v[40:43], v[24:25], off offset:-16
	v_addc_co_u32_e32 v49, vcc, -1, v151, vcc
	global_load_dwordx4 v[28:31], v[48:49], off offset:-2064
	global_load_dwordx4 v[24:27], v[48:49], off offset:-16
	v_add_co_u32_e32 v48, vcc, s19, v150
	v_mov_b64_e32 v[86:87], s[42:43]
	v_add_co_u32_e64 v90, s[10:11], s19, v148
	s_and_b32 s48, s16, 0xffc
	s_nop 0
	v_addc_co_u32_e64 v91, s[10:11], -1, v149, s[10:11]
	s_ashr_i32 s10, s16, 12
	s_ashr_i32 s11, s10, 31
	s_lshl_b64 s[10:11], s[10:11], 17
	s_waitcnt vmcnt(0)
	v_mul_f32_e32 v50, v34, v34
	v_mul_f32_e32 v51, v35, v35
	v_mul_f32_e32 v52, v32, v32
	v_mul_f32_e32 v53, v33, v33
	s_waitcnt vmcnt(6)
	v_mul_f32_e32 v67, v39, v39
	v_pk_mov_b32 v[58:59], v[52:53], v[50:51] op_sel:[1,0]
	v_mov_b32_e32 v53, v51
	s_waitcnt vmcnt(5)
	v_mul_f32_e32 v54, v18, v18
	v_mul_f32_e32 v55, v19, v19
	v_mul_f32_e32 v56, v16, v16
	v_mul_f32_e32 v57, v17, v17
	v_add_f32_e32 v52, v58, v52
	v_add_f32_e32 v53, v59, v53
	v_pk_mov_b32 v[50:51], v[56:57], v[54:55] op_sel:[1,0]
	v_mov_b32_e32 v57, v55
	v_add_f32_e32 v50, v50, v56
	v_add_f32_e32 v51, v51, v57
	s_waitcnt vmcnt(3)
	v_mul_f32_e32 v54, v46, v46
	v_mul_f32_e32 v55, v47, v47
	v_mul_f32_e32 v60, v44, v44
	v_mul_f32_e32 v61, v45, v45
	s_waitcnt vmcnt(2)
	v_mul_f32_e32 v64, v43, v43
	v_pk_mov_b32 v[56:57], v[60:61], v[54:55] op_sel:[1,0]
	v_mov_b32_e32 v61, v55
	s_waitcnt vmcnt(1)
	v_mul_f32_e32 v54, v30, v30
	v_mul_f32_e32 v55, v31, v31
	v_mul_f32_e32 v58, v28, v28
	v_mul_f32_e32 v59, v29, v29
	v_add_f32_e32 v56, v56, v60
	v_add_f32_e32 v57, v57, v61
	v_pk_mov_b32 v[60:61], v[58:59], v[54:55] op_sel:[1,0]
	v_mov_b32_e32 v59, v55
	v_mul_f32_e32 v69, v22, v22
	v_mul_f32_e32 v62, v41, v41
	v_fma_f32 v65, v43, v43, v64
	v_fma_f32 v64, v42, v42, v64
	s_waitcnt vmcnt(0)
	v_mul_f32_e32 v66, v25, v25
	v_mul_f32_e32 v68, v27, v27
	v_add_f32_e32 v58, v60, v58
	v_add_f32_e32 v59, v61, v59
	v_mul_f32_e32 v49, v38, v38
	v_mul_f32_e32 v70, v23, v23
	v_mul_f32_e32 v71, v36, v36
	v_mul_f32_e32 v72, v37, v37
	v_mul_f32_e32 v73, v20, v20
	v_mul_f32_e32 v74, v21, v21
	v_fma_f32 v63, v41, v41, v62
	v_fma_f32 v62, v40, v40, v62
	v_add_f32_e32 v52, v52, v53
	v_mov_b32_e32 v53, v52
	v_add_f32_e32 v50, v50, v51
	v_mov_b32_e32 v51, v50
	v_mov_b32_e32 v65, v67
	v_fma_f32 v54, v24, v24, v66
	v_fma_f32 v55, v25, v25, v66
	v_fma_f32 v66, v26, v26, v68
	v_fma_f32 v67, v27, v27, v68
	v_add_f32_e32 v56, v56, v57
	v_mov_b32_e32 v57, v56
	v_add_f32_e32 v58, v58, v59
	v_mov_b32_e32 v59, v58
	v_mov_b32_e32 v63, v49
	v_mov_b32_e32 v53, v72
	v_mov_b32_e32 v51, v74
	v_mov_b32_e32 v55, v69
	v_mov_b32_e32 v67, v70
	v_mov_b32_e32 v57, v71
	v_mov_b32_e32 v59, v73
	v_add_f32_e32 v62, v62, v64
	v_add_f32_e32 v63, v63, v65
	v_add_f32_e32 v54, v54, v66
	v_add_f32_e32 v55, v55, v67
	v_add_f32_e32 v52, v56, v52
	v_add_f32_e32 v53, v57, v53
	v_add_f32_e32 v50, v58, v50
	v_add_f32_e32 v51, v59, v51
	v_add_f32_e32 v52, v52, v62
	v_add_f32_e32 v53, v53, v63
	v_add_f32_e32 v50, v50, v54
	v_add_f32_e32 v51, v51, v55
	v_mov_b32_e32 v55, v52
	v_mov_b32_e32 v54, v50
	v_mov_b32_e32 v52, v51
	v_add_f32_e32 v50, v54, v52
	v_add_f32_e32 v51, v55, v53
	ds_bpermute_b32 v53, v211, v51
	ds_bpermute_b32 v52, v211, v50
	v_addc_co_u32_e32 v49, vcc, -1, v151, vcc
	global_load_dwordx4 v[72:75], v[48:49], off offset:-2064
	v_lshl_add_u64 v[54:55], v[150:151], 0, s[38:39]
	s_waitcnt lgkmcnt(0)
	v_add_f32_e32 v50, v50, v52
	v_add_f32_e32 v51, v51, v53
	ds_bpermute_b32 v53, v210, v51
	ds_bpermute_b32 v52, v210, v50
	global_load_dwordx4 v[76:79], v[54:55], off offset:16
	global_load_dwordx4 v[64:67], v[150:151], off offset:-4096
	global_load_dwordx4 v[68:71], v[48:49], off offset:-16
	global_load_dwordx4 v[60:63], v[150:151], off offset:-2064
	global_load_dwordx4 v[56:59], v[150:151], off offset:-2048
	s_waitcnt lgkmcnt(0)
	v_add_f32_e32 v50, v50, v52
	v_add_f32_e32 v51, v51, v53
	ds_bpermute_b32 v53, v209, v51
	ds_bpermute_b32 v52, v209, v50
	s_waitcnt lgkmcnt(0)
	v_add_f32_e32 v48, v50, v52
	v_add_f32_e32 v49, v51, v53
	ds_bpermute_b32 v51, v208, v49
	ds_bpermute_b32 v50, v208, v48
	s_waitcnt lgkmcnt(0)
	v_add_f32_e32 v48, v48, v50
	v_add_f32_e32 v49, v49, v51
	ds_bpermute_b32 v51, v207, v49
	ds_bpermute_b32 v50, v207, v48
	s_waitcnt lgkmcnt(0)
	v_add_f32_e32 v80, v48, v50
	v_add_f32_e32 v81, v49, v51
	global_load_dwordx4 v[48:51], v[150:151], off
	global_load_dwordx4 v[52:55], v[150:151], off offset:-16
	ds_bpermute_b32 v83, v206, v81
	ds_bpermute_b32 v82, v206, v80
	ds_read_b128 v[96:99], v212 offset:17472
	ds_read_b128 v[104:107], v212 offset:17504
	ds_read_b128 v[108:111], v212 offset:17520
	ds_read_b128 v[112:115], v212 offset:17536
	s_waitcnt lgkmcnt(4)
; #define GAS __attribute__((address_space(1)))
; template <int MODE, bool XBF>
; __device__ __forceinline__ void rmsnorm_rows(const void* x, const float* gain, bf16_t* H, int gw, int NGW, int lane, const LAS float* WF, const float* fbias, float* LF) {
;     ...
;         for (int r = 0; r < RB; ++r) { s[r] = 0.f;
; #pragma unroll
;             for (int j = 0; j < 2; ++j)
; #pragma unroll
;                 for (int e = 0; e < 2; ++e) s[r] += (v[r][j][e][0] * v[r][j][e][0] + v[r][j][e][1] * v[r][j][e][1]) + (v[r][j][e][2] * v[r][j][e][2] + v[r][j][e][3] * v[r][j][e][3]); }
; #pragma unroll
;         for (int o = 1; o < 64; o <<= 1)
; #pragma unroll
;             for (int r = 0; r < RB; ++r) s[r] += __shfl_xor(s[r], o);
; #pragma unroll
;         for (int r = 0; r < RB; ++r) {
;             const int row = row0 + r;
;             const float rstd = rsqrtf(s[r] * (1.f / D) + 1e-6f);
;             const size_t hrow = MODE == 2 ? (size_t)row + (row >> 12) + 1 : (size_t)row;
; #pragma unroll
;             for (int j = 0; j < 2; ++j) { v[r][j][0] = v[r][j][0] * rstd * g[j][0]; v[r][j][1] = v[r][j][1] * rstd * g[j][1];
;                 *(GAS u32x4*)(H + hrow * D + 512 * j + lane * 8) = pack8(v[r][j][0], v[r][j][1]); }
	v_add_f32_e32 v80, v80, v82
	v_add_f32_e32 v81, v81, v83
	ds_read_b128 v[120:123], v212 offset:17568
	ds_read_b128 v[140:143], v212 offset:17584
	v_fma_f32 v88, v80, s40, v86
	v_fma_f32 v89, v81, s40, v86
	ds_read_b128 v[136:139], v212 offset:17600
	ds_read_b128 v[132:135], v212 offset:17616
	v_mul_f32_e32 v80, 0x4b800000, v89
	v_cmp_gt_f32_e32 vcc, s41, v89
	ds_read_b128 v[128:131], v212 offset:17632
	s_nop 0
	v_cndmask_b32_e32 v80, v89, v80, vcc
	v_rsq_f32_e32 v80, v80
	s_nop 0
	v_mul_f32_e32 v81, 0x45800000, v80
	v_cndmask_b32_e32 v80, v80, v81, vcc
	v_mul_f32_e32 v44, v44, v80
	v_mul_f32_e32 v45, v45, v80
	v_mul_f32_e32 v46, v46, v80
	v_mul_f32_e32 v47, v47, v80
	v_mul_f32_e32 v92, v32, v80
	v_mul_f32_e32 v93, v33, v80
	v_mul_f32_e32 v34, v34, v80
	v_mul_f32_e32 v35, v35, v80
	v_mul_f32_e32 v40, v40, v80
	v_mul_f32_e32 v41, v41, v80
	v_mul_f32_e32 v42, v42, v80
	v_mul_f32_e32 v43, v43, v80
	v_mul_f32_e32 v94, v36, v80
	v_mul_f32_e32 v95, v37, v80
	v_mul_f32_e32 v38, v38, v80
	v_mul_f32_e32 v39, v39, v80
	v_mul_f32_e32 v82, v6, v46
	v_mul_f32_e32 v83, v7, v47
	v_mul_f32_e32 v32, v4, v44
	v_mul_f32_e32 v33, v5, v45
	v_mul_f32_e32 v84, v2, v34
	v_mul_f32_e32 v85, v3, v35
	v_mul_f32_e32 v80, v0, v92
	v_mul_f32_e32 v81, v1, v93
	v_cvt_pk_bf16_f32 v34, v32, v33
	v_cvt_pk_bf16_f32 v35, v82, v83
	v_cvt_pk_bf16_f32 v36, v80, v81
	v_cvt_pk_bf16_f32 v37, v84, v85
	global_store_dwordx4 v[90:91], v[34:37], off offset:-3072
	v_cmp_gt_f32_e32 vcc, s41, v88
	v_mul_f32_e32 v116, v14, v42
	v_mul_f32_e32 v117, v15, v43
	v_mul_f32_e32 v36, 0x4b800000, v88
	v_mul_f32_e32 v100, v12, v40
	v_mul_f32_e32 v101, v13, v41
	v_mul_f32_e32 v170, v10, v38
	v_mul_f32_e32 v171, v11, v39
	v_mul_f32_e32 v124, v8, v94
	v_mul_f32_e32 v125, v9, v95
	v_cndmask_b32_e32 v36, v88, v36, vcc
	v_cvt_pk_bf16_f32 v34, v100, v101
	v_cvt_pk_bf16_f32 v35, v116, v117
	v_rsq_f32_e32 v44, v36
	v_cvt_pk_bf16_f32 v36, v124, v125
	v_cvt_pk_bf16_f32 v37, v170, v171
	global_store_dwordx4 v[90:91], v[34:37], off offset:-2048
	v_mul_f32_e32 v45, 0x45800000, v44
	ds_read_b128 v[92:95], v212 offset:17456
	s_waitcnt vmcnt(9)
	v_mul_f32_e32 v34, v74, v74
	v_mul_f32_e32 v35, v75, v75
	v_mul_f32_e32 v36, v72, v72
	v_mul_f32_e32 v37, v73, v73
	s_nop 0
	v_pk_mov_b32 v[38:39], v[36:37], v[34:35] op_sel:[1,0]
	v_mov_b32_e32 v37, v35
	v_add_f32_e32 v34, v38, v36
	v_add_f32_e32 v35, v39, v37
	s_waitcnt vmcnt(8)
	v_mul_f32_e32 v36, v78, v78
	v_mul_f32_e32 v37, v79, v79
	v_mul_f32_e32 v38, v76, v76
	v_mul_f32_e32 v39, v77, v77
	v_add_f32_e32 v34, v34, v35
	v_mov_b32_e32 v35, v34
	v_pk_mov_b32 v[40:41], v[38:39], v[36:37] op_sel:[1,0]
	v_mov_b32_e32 v39, v37
	v_add_f32_e32 v36, v40, v38
	v_add_f32_e32 v37, v41, v39
	s_waitcnt vmcnt(7)
	v_mul_f32_e32 v35, v64, v64
	v_add_f32_e32 v36, v36, v37
	v_mov_b32_e32 v37, v36
	s_waitcnt vmcnt(6)
	v_mul_f32_e32 v38, v71, v71
	v_mul_f32_e32 v37, v65, v65
	v_add_f32_e32 v34, v34, v36
	v_add_f32_e32 v35, v35, v37
	v_mul_f32_e32 v36, v69, v69
	v_fma_f32 v37, v69, v69, v36
	v_fma_f32 v36, v68, v68, v36
	v_fma_f32 v39, v71, v71, v38
	v_fma_f32 v38, v70, v70, v38
	v_mul_f32_e32 v37, v66, v66
	v_mul_f32_e32 v39, v67, v67
	v_add_f32_e32 v36, v36, v38
	v_add_f32_e32 v37, v37, v39
	s_waitcnt vmcnt(5)
	v_mul_f32_e32 v38, v60, v60
	v_mul_f32_e32 v39, v61, v61
	v_add_f32_e32 v34, v34, v36
	v_add_f32_e32 v35, v35, v37
	v_mul_f32_e32 v36, v62, v62
	v_mul_f32_e32 v37, v63, v63
	s_nop 0
	v_pk_mov_b32 v[40:41], v[38:39], v[36:37] op_sel:[1,0]
	v_mov_b32_e32 v39, v37
	v_add_f32_e32 v36, v40, v38
	v_add_f32_e32 v37, v41, v39
	s_waitcnt vmcnt(4)
	v_mul_f32_e32 v38, v58, v58
	v_mul_f32_e32 v39, v59, v59
	v_mul_f32_e32 v40, v56, v56
	v_mul_f32_e32 v41, v57, v57
	v_add_f32_e32 v36, v36, v37
	v_mov_b32_e32 v37, v36
	v_pk_mov_b32 v[42:43], v[40:41], v[38:39] op_sel:[1,0]
	v_mov_b32_e32 v41, v39
	v_add_f32_e32 v38, v42, v40
	v_add_f32_e32 v39, v43, v41
	s_waitcnt vmcnt(3)
	v_mul_f32_e32 v37, v48, v48
	v_add_f32_e32 v38, v38, v39
	v_mov_b32_e32 v39, v38
	s_waitcnt vmcnt(2)
	v_mul_f32_e32 v40, v55, v55
	v_mul_f32_e32 v39, v49, v49
	v_add_f32_e32 v36, v36, v38
	v_add_f32_e32 v37, v37, v39
	v_mul_f32_e32 v38, v53, v53
	v_fma_f32 v39, v53, v53, v38
	v_fma_f32 v38, v52, v52, v38
	v_fma_f32 v41, v55, v55, v40
	v_fma_f32 v40, v54, v54, v40
	v_mul_f32_e32 v39, v50, v50
	v_mul_f32_e32 v41, v51, v51
	v_add_f32_e32 v38, v38, v40
	v_add_f32_e32 v39, v39, v41
	ds_read_b128 v[40:43], v212 offset:112
	v_add_f32_e32 v36, v36, v38
	v_add_f32_e32 v37, v37, v39
	v_mov_b32_e32 v39, v34
	v_mov_b32_e32 v38, v36
	v_mov_b32_e32 v34, v37
	v_add_f32_e32 v34, v38, v34
	v_add_f32_e32 v35, v39, v35
	ds_bpermute_b32 v37, v211, v35
	ds_bpermute_b32 v36, v211, v34
	v_cndmask_b32_e32 v38, v44, v45, vcc
	v_mul_f32_e32 v28, v28, v38
	v_mul_f32_e32 v29, v29, v38
	v_mul_f32_e32 v30, v30, v38
	v_mul_f32_e32 v31, v31, v38
	v_mul_f32_e32 v202, v4, v28
	v_mul_f32_e32 v203, v5, v29
	s_waitcnt lgkmcnt(0)
	v_add_f32_e32 v34, v34, v36
	v_add_f32_e32 v35, v35, v37
	ds_bpermute_b32 v37, v210, v35
	ds_bpermute_b32 v36, v210, v34
	v_mul_f32_e32 v200, v6, v30
	v_mul_f32_e32 v201, v7, v31
	v_mul_f32_e32 v16, v16, v38
	v_mul_f32_e32 v17, v17, v38
	v_mul_f32_e32 v18, v18, v38
	v_mul_f32_e32 v19, v19, v38
	v_mul_f32_e32 v198, v0, v16
	v_mul_f32_e32 v199, v1, v17
	s_waitcnt lgkmcnt(0)
	v_add_f32_e32 v28, v34, v36
	v_add_f32_e32 v29, v35, v37
	ds_bpermute_b32 v31, v209, v29
	ds_bpermute_b32 v30, v209, v28
	v_mul_f32_e32 v196, v2, v18
	v_mul_f32_e32 v197, v3, v19
	v_cvt_pk_bf16_f32 v16, v202, v203
	v_cvt_pk_bf16_f32 v17, v200, v201
	v_cvt_pk_bf16_f32 v18, v198, v199
	s_waitcnt lgkmcnt(0)
; #define LAS __attribute__((address_space(3)))
; #define GAS __attribute__((address_space(1)))
; template <int MODE, bool XBF>
; __device__ __forceinline__ void rmsnorm_rows(const void* x, const float* gain, bf16_t* H, int gw, int NGW, int lane, const LAS float* WF, const float* fbias, float* LF) {
;     ...
;         for (int o = 1; o < 64; o <<= 1)
; #pragma unroll
;             for (int r = 0; r < RB; ++r) s[r] += __shfl_xor(s[r], o);
; #pragma unroll
;         for (int r = 0; r < RB; ++r) {
;             const int row = row0 + r;
;             const float rstd = rsqrtf(s[r] * (1.f / D) + 1e-6f);
;             const size_t hrow = MODE == 2 ? (size_t)row + (row >> 12) + 1 : (size_t)row;
; #pragma unroll
;             for (int j = 0; j < 2; ++j) { v[r][j][0] = v[r][j][0] * rstd * g[j][0]; v[r][j][1] = v[r][j][1] * rstd * g[j][1];
;                 *(GAS u32x4*)(H + hrow * D + 512 * j + lane * 8) = pack8(v[r][j][0], v[r][j][1]); }
;     ...
;             for (int j = 0; j < 2; ++j)
; #pragma unroll
;                 for (int e = 0; e < 2; ++e)
; #pragma unroll
;                     for (int c = 0; c < 4; ++c) {
;                         const LAS float* wp = WF + (512 * j + lane * 8 + 4 * e + c) * 8;
;                         const f32x4 w0 = *(const LAS f32x4*)wp, w1 = *(const LAS f32x4*)(wp + 4);
; #pragma unroll
;                         for (int r = 0; r < RB; ++r) {
;                             const float hv = v[r][j][e][c];
;                             dt[r][0] += hv * w0[0]; dt[r][1] += hv * w0[1]; dt[r][2] += hv * w0[2]; dt[r][3] += hv * w0[3];
;                             dt[r][4] += hv * w1[0]; dt[r][5] += hv * w1[1]; dt[r][6] += hv * w1[2]; dt[r][7] += hv * w1[3];
;                         }
	v_add_f32_e32 v28, v28, v30
	v_add_f32_e32 v29, v29, v31
	ds_bpermute_b32 v31, v208, v29
	ds_bpermute_b32 v30, v208, v28
	v_cvt_pk_bf16_f32 v19, v196, v197
	global_store_dwordx4 v[90:91], v[16:19], off offset:-1024
	v_mul_f32_e32 v20, v20, v38
	v_mul_f32_e32 v21, v21, v38
	v_mul_f32_e32 v22, v22, v38
	v_mul_f32_e32 v23, v23, v38
	v_mul_f32_e32 v16, v24, v38
	v_mul_f32_e32 v17, v25, v38
	s_waitcnt lgkmcnt(0)
	v_add_f32_e32 v24, v28, v30
	v_add_f32_e32 v25, v29, v31
	v_mul_f32_e32 v18, v26, v38
	v_mul_f32_e32 v19, v27, v38
	ds_bpermute_b32 v27, v207, v25
	ds_bpermute_b32 v26, v207, v24
	v_mul_f32_e32 v192, v14, v18
	v_mul_f32_e32 v193, v15, v19
	v_mul_f32_e32 v190, v8, v20
	v_mul_f32_e32 v191, v9, v21
	v_mul_f32_e32 v194, v12, v16
	v_mul_f32_e32 v195, v13, v17
	v_mul_f32_e32 v188, v10, v22
	v_mul_f32_e32 v189, v11, v23
	s_waitcnt lgkmcnt(0)
	v_add_f32_e32 v18, v24, v26
	v_add_f32_e32 v19, v25, v27
	ds_bpermute_b32 v25, v206, v19
	ds_bpermute_b32 v24, v206, v18
	v_cvt_pk_bf16_f32 v16, v194, v195
	v_cvt_pk_bf16_f32 v17, v192, v193
	ds_read_b128 v[28:31], v212 offset:16
	ds_read_b128 v[36:39], v212 offset:64
	s_waitcnt lgkmcnt(2)
	v_add_f32_e32 v18, v18, v24
	v_add_f32_e32 v19, v19, v25
	ds_read_b128 v[44:47], v212 offset:96
	v_fma_f32 v20, v18, s40, v86
	v_fma_f32 v21, v19, s40, v86
	v_cvt_pk_bf16_f32 v19, v188, v189
	v_mul_f32_e32 v18, 0x4b800000, v21
	v_cmp_gt_f32_e32 vcc, s41, v21
	s_waitcnt lgkmcnt(2)
	v_fma_f32 v220, v28, v32, 0
	v_fma_f32 v221, v29, v32, 0
	v_cndmask_b32_e32 v18, v21, v18, vcc
	v_rsq_f32_e32 v21, v18
	v_cvt_pk_bf16_f32 v18, v190, v191
	global_store_dwordx4 v[148:149], v[16:19], off offset:-4096
	v_fma_f32 v222, v30, v32, 0
	v_fma_f32 v223, v31, v32, 0
	v_mul_f32_e32 v16, 0x45800000, v21
	v_cndmask_b32_e32 v22, v21, v16, vcc
	v_mul_f32_e32 v16, v72, v22
	v_mul_f32_e32 v17, v73, v22
	v_mul_f32_e32 v18, v74, v22
	v_mul_f32_e32 v19, v75, v22
	v_mul_f32_e32 v24, v76, v22
	v_mul_f32_e32 v25, v77, v22
	v_mul_f32_e32 v26, v78, v22
	v_mul_f32_e32 v27, v79, v22
	v_mul_f32_e32 v184, v6, v18
	v_mul_f32_e32 v185, v7, v19
	v_mul_f32_e32 v186, v4, v16
	v_mul_f32_e32 v187, v5, v17
	v_mul_f32_e32 v180, v2, v26
	v_mul_f32_e32 v181, v3, v27
	v_mul_f32_e32 v182, v0, v24
	v_mul_f32_e32 v183, v1, v25
	v_cvt_pk_bf16_f32 v16, v186, v187
	v_cvt_pk_bf16_f32 v17, v184, v185
	v_cvt_pk_bf16_f32 v18, v182, v183
	v_cvt_pk_bf16_f32 v19, v180, v181
	global_store_dwordx4 v[148:149], v[16:19], off offset:-3072
	v_cmp_gt_f32_e32 vcc, s41, v20
	v_mul_f32_e32 v24, v64, v22
	v_mul_f32_e32 v25, v65, v22
	v_mul_f32_e32 v18, v70, v22
	v_mul_f32_e32 v19, v71, v22
	v_mul_f32_e32 v16, v68, v22
	v_mul_f32_e32 v17, v69, v22
	v_mul_f32_e32 v176, v14, v18
	v_mul_f32_e32 v177, v15, v19
	v_mul_f32_e32 v18, 0x4b800000, v20
	v_cndmask_b32_e32 v18, v20, v18, vcc
	v_rsq_f32_e32 v20, v18
	v_mul_f32_e32 v23, v67, v22
	v_mul_f32_e32 v22, v66, v22
	v_mul_f32_e32 v178, v12, v16
	v_mul_f32_e32 v179, v13, v17
	v_mul_f32_e32 v172, v10, v22
	v_mul_f32_e32 v173, v11, v23
	v_mul_f32_e32 v174, v8, v24
	v_mul_f32_e32 v175, v9, v25
	v_cvt_pk_bf16_f32 v16, v178, v179
	v_cvt_pk_bf16_f32 v17, v176, v177
	v_cvt_pk_bf16_f32 v18, v174, v175
	v_cvt_pk_bf16_f32 v19, v172, v173
	global_store_dwordx4 v[148:149], v[16:19], off offset:-2048
	ds_read_b128 v[68:71], v212 offset:192
	ds_read_b128 v[64:67], v212 offset:208
	v_mul_f32_e32 v16, 0x45800000, v20
	v_cndmask_b32_e32 v20, v20, v16, vcc
	v_mul_f32_e32 v16, v60, v20
	v_mul_f32_e32 v17, v61, v20
	v_mul_f32_e32 v18, v62, v20
	v_mul_f32_e32 v19, v63, v20
	v_mul_f32_e32 v22, v56, v20
	v_mul_f32_e32 v23, v57, v20
	v_mul_f32_e32 v24, v58, v20
	v_mul_f32_e32 v25, v59, v20
	v_mul_f32_e32 v166, v6, v18
	v_mul_f32_e32 v167, v7, v19
	v_mul_f32_e32 v168, v4, v16
	v_mul_f32_e32 v169, v5, v17
	v_mul_f32_e32 v162, v2, v24
	v_mul_f32_e32 v163, v3, v25
	v_mul_f32_e32 v164, v0, v22
	v_mul_f32_e32 v165, v1, v23
	v_cvt_pk_bf16_f32 v16, v168, v169
	v_cvt_pk_bf16_f32 v17, v166, v167
	v_cvt_pk_bf16_f32 v18, v164, v165
	v_cvt_pk_bf16_f32 v19, v162, v163
	global_store_dwordx4 v[148:149], v[16:19], off offset:-1024
	v_mul_f32_e32 v22, v48, v20
	v_mul_f32_e32 v23, v49, v20
	ds_read_b128 v[24:27], v212
	v_mul_f32_e32 v16, v52, v20
	v_mul_f32_e32 v17, v53, v20
	v_mul_f32_e32 v18, v54, v20
	v_mul_f32_e32 v19, v55, v20
	v_mul_f32_e32 v21, v51, v20
	v_mul_f32_e32 v20, v50, v20
	v_mul_f32_e32 v158, v14, v18
	v_mul_f32_e32 v159, v15, v19
	v_mul_f32_e32 v160, v12, v16
	v_mul_f32_e32 v161, v13, v17
	v_mul_f32_e32 v154, v10, v20
	v_mul_f32_e32 v155, v11, v21
	v_mul_f32_e32 v156, v8, v22
	v_mul_f32_e32 v157, v9, v23
	v_cvt_pk_bf16_f32 v16, v160, v161
	v_cvt_pk_bf16_f32 v17, v158, v159
	v_cvt_pk_bf16_f32 v18, v156, v157
	v_cvt_pk_bf16_f32 v19, v154, v155
	ds_read_b128 v[20:23], v212 offset:32
	global_store_dwordx4 v[148:149], v[16:19], off
	ds_read_b128 v[16:19], v212 offset:48
	s_waitcnt lgkmcnt(2)
	v_fma_f32 v153, v24, v32, 0
	v_fma_f32 v204, v25, v32, 0
	v_fma_f32 v218, v26, v32, 0
	v_fma_f32 v219, v27, v32, 0
	s_waitcnt lgkmcnt(1)
	v_fmac_f32_e32 v153, v33, v20
	v_fmac_f32_e32 v204, v33, v21
	v_fmac_f32_e32 v218, v33, v22
	v_fmac_f32_e32 v219, v33, v23
	s_waitcnt lgkmcnt(0)
	v_fmac_f32_e32 v220, v33, v16
	v_fmac_f32_e32 v221, v33, v17
	v_fmac_f32_e32 v222, v33, v18
	v_fmac_f32_e32 v223, v33, v19
	ds_read_b128 v[32:35], v212 offset:80
	flat_load_dword v217, v[144:145]
	ds_read_b128 v[52:55], v212 offset:128
	ds_read_b128 v[48:51], v212 offset:144
	ds_read_b128 v[60:63], v212 offset:160
	ds_read_b128 v[56:59], v212 offset:176
	v_fmac_f32_e32 v153, v82, v36
	v_fmac_f32_e32 v204, v82, v37
	v_fmac_f32_e32 v218, v82, v38
	v_fmac_f32_e32 v219, v82, v39
	s_waitcnt lgkmcnt(0)
; #define LAS __attribute__((address_space(3)))
; template <int MODE, bool XBF>
; __device__ __forceinline__ void rmsnorm_rows(const void* x, const float* gain, bf16_t* H, int gw, int NGW, int lane, const LAS float* WF, const float* fbias, float* LF) {
;     ...
;             for (int j = 0; j < 2; ++j)
; #pragma unroll
;                 for (int e = 0; e < 2; ++e)
; #pragma unroll
;                     for (int c = 0; c < 4; ++c) {
;                         const LAS float* wp = WF + (512 * j + lane * 8 + 4 * e + c) * 8;
;                         const f32x4 w0 = *(const LAS f32x4*)wp, w1 = *(const LAS f32x4*)(wp + 4);
; #pragma unroll
;                         for (int r = 0; r < RB; ++r) {
;                             const float hv = v[r][j][e][c];
;                             dt[r][0] += hv * w0[0]; dt[r][1] += hv * w0[1]; dt[r][2] += hv * w0[2]; dt[r][3] += hv * w0[3];
;                             dt[r][4] += hv * w1[0]; dt[r][5] += hv * w1[1]; dt[r][6] += hv * w1[2]; dt[r][7] += hv * w1[3];
;                         }
;                     }
;             const bool hi32 = (lane & 32) != 0, hi16 = (lane & 16) != 0, hi8 = (lane & 8) != 0;
;             const int hsel = (hi32 ? 4 : 0) + (hi16 ? 2 : 0) + (hi8 ? 1 : 0);
;             const float fb = fbias[hsel];
; #pragma unroll
;             for (int r = 0; r < RB; ++r) {
;                 float d4[4], d2[2], d1;
; #pragma unroll
;                 for (int k = 0; k < 4; ++k) { const float send = hi32 ? dt[r][k] : dt[r][k + 4], keep = hi32 ? dt[r][k + 4] : dt[r][k]; d4[k] = keep + __shfl_xor(send, 32); }
; #pragma unroll
;                 for (int k = 0; k < 2; ++k) { const float send = hi16 ? d4[k] : d4[k + 2], keep = hi16 ? d4[k + 2] : d4[k]; d2[k] = keep + __shfl_xor(send, 16); }
;                 { const float send = hi8 ? d2[0] : d2[1], keep = hi8 ? d2[1] : d2[0]; d1 = keep + __shfl_xor(send, 8); }
;                 d1 += __shfl_xor(d1, 4); d1 += __shfl_xor(d1, 2); d1 += __shfl_xor(d1, 1);
	v_fmac_f32_e32 v220, v82, v32
	v_fmac_f32_e32 v221, v82, v33
	v_fmac_f32_e32 v222, v82, v34
	v_fmac_f32_e32 v223, v82, v35
	ds_read_b128 v[72:75], v212 offset:224
	ds_read_b128 v[76:79], v212 offset:240
	v_fmac_f32_e32 v153, v83, v44
	v_fmac_f32_e32 v204, v83, v45
	v_fmac_f32_e32 v218, v83, v46
	v_fmac_f32_e32 v219, v83, v47
	v_fmac_f32_e32 v220, v83, v40
	v_fmac_f32_e32 v221, v83, v41
	v_fmac_f32_e32 v222, v83, v42
	v_fmac_f32_e32 v223, v83, v43
	v_fmac_f32_e32 v153, v80, v52
	v_fmac_f32_e32 v204, v80, v53
	v_fmac_f32_e32 v218, v80, v54
	v_fmac_f32_e32 v219, v80, v55
	v_fmac_f32_e32 v220, v80, v48
	v_fmac_f32_e32 v221, v80, v49
	v_fmac_f32_e32 v222, v80, v50
	v_fmac_f32_e32 v223, v80, v51
	v_fmac_f32_e32 v153, v81, v60
	v_fmac_f32_e32 v204, v81, v61
	v_fmac_f32_e32 v218, v81, v62
	v_fmac_f32_e32 v219, v81, v63
	v_fmac_f32_e32 v220, v81, v56
	v_fmac_f32_e32 v221, v81, v57
	v_fmac_f32_e32 v222, v81, v58
	v_fmac_f32_e32 v223, v81, v59
	v_fmac_f32_e32 v153, v84, v68
	v_fmac_f32_e32 v204, v84, v69
	v_fmac_f32_e32 v218, v84, v70
	v_fmac_f32_e32 v219, v84, v71
	v_fmac_f32_e32 v220, v84, v64
	v_fmac_f32_e32 v221, v84, v65
	v_fmac_f32_e32 v222, v84, v66
	v_fmac_f32_e32 v223, v84, v67
	s_waitcnt lgkmcnt(0)
	v_fmac_f32_e32 v153, v85, v72
	v_fmac_f32_e32 v204, v85, v73
	v_fmac_f32_e32 v218, v85, v74
	v_fmac_f32_e32 v219, v85, v75
	v_fmac_f32_e32 v220, v85, v76
	ds_read_b128 v[80:83], v212 offset:17408
	v_fmac_f32_e32 v221, v85, v77
	v_fmac_f32_e32 v222, v85, v78
	v_fmac_f32_e32 v223, v85, v79
	ds_read_b128 v[84:87], v212 offset:17424
	ds_read_b128 v[88:91], v212 offset:17440
	s_waitcnt lgkmcnt(0)
	v_fmac_f32_e32 v153, v100, v80
	v_fmac_f32_e32 v204, v100, v81
	v_fmac_f32_e32 v218, v100, v82
	v_fmac_f32_e32 v219, v100, v83
	v_fmac_f32_e32 v220, v100, v84
	v_fmac_f32_e32 v221, v100, v85
	v_fmac_f32_e32 v222, v100, v86
	v_fmac_f32_e32 v223, v100, v87
	v_fmac_f32_e32 v153, v101, v88
	v_fmac_f32_e32 v204, v101, v89
	v_fmac_f32_e32 v218, v101, v90
	v_fmac_f32_e32 v219, v101, v91
	v_fmac_f32_e32 v220, v101, v92
	v_fmac_f32_e32 v221, v101, v93
	v_fmac_f32_e32 v222, v101, v94
	v_fmac_f32_e32 v223, v101, v95
	ds_read_b128 v[100:103], v212 offset:17488
	v_fmac_f32_e32 v153, v116, v96
	v_fmac_f32_e32 v204, v116, v97
	v_fmac_f32_e32 v218, v116, v98
	v_fmac_f32_e32 v219, v116, v99
	s_waitcnt lgkmcnt(0)
	v_fmac_f32_e32 v220, v116, v100
	v_fmac_f32_e32 v221, v116, v101
	v_fmac_f32_e32 v222, v116, v102
	v_fmac_f32_e32 v223, v116, v103
	v_fmac_f32_e32 v153, v117, v104
	v_fmac_f32_e32 v204, v117, v105
	v_fmac_f32_e32 v218, v117, v106
	v_fmac_f32_e32 v219, v117, v107
	v_fmac_f32_e32 v220, v117, v108
	v_fmac_f32_e32 v221, v117, v109
	v_fmac_f32_e32 v222, v117, v110
	v_fmac_f32_e32 v223, v117, v111
	ds_read_b128 v[116:119], v212 offset:17552
	v_fmac_f32_e32 v153, v124, v112
	v_fmac_f32_e32 v204, v124, v113
	v_fmac_f32_e32 v218, v124, v114
	v_fmac_f32_e32 v219, v124, v115
	s_waitcnt lgkmcnt(0)
	v_fmac_f32_e32 v220, v124, v116
	v_fmac_f32_e32 v221, v124, v117
	v_fmac_f32_e32 v222, v124, v118
	v_fmac_f32_e32 v223, v124, v119
	v_fmac_f32_e32 v153, v125, v120
	v_fmac_f32_e32 v204, v125, v121
	v_fmac_f32_e32 v218, v125, v122
	v_fmac_f32_e32 v219, v125, v123
	v_fmac_f32_e32 v220, v125, v140
	v_fmac_f32_e32 v221, v125, v141
	v_fmac_f32_e32 v222, v125, v142
	v_fmac_f32_e32 v223, v125, v143
	ds_read_b128 v[124:127], v212 offset:17648
	v_fmac_f32_e32 v153, v170, v136
	v_fmac_f32_e32 v220, v170, v132
	v_fmac_f32_e32 v153, v171, v128
	v_fmac_f32_e32 v204, v170, v137
	s_waitcnt lgkmcnt(0)
	v_fmac_f32_e32 v220, v171, v124
	v_fmac_f32_e32 v218, v170, v138
	v_fmac_f32_e32 v219, v170, v139
	v_fmac_f32_e32 v221, v170, v133
	v_fmac_f32_e32 v222, v170, v134
	v_fmac_f32_e32 v223, v170, v135
	v_cndmask_b32_e64 v170, v153, v220, s[2:3]
	ds_bpermute_b32 v170, v206, v170
	v_fmac_f32_e32 v204, v171, v129
	v_fmac_f32_e32 v221, v171, v125
	v_cndmask_b32_e64 v153, v220, v153, s[2:3]
	v_fmac_f32_e32 v218, v171, v130
	v_fmac_f32_e32 v222, v171, v126
	s_waitcnt lgkmcnt(0)
	v_add_f32_e32 v153, v153, v170
	v_cndmask_b32_e64 v170, v204, v221, s[2:3]
	v_fmac_f32_e32 v219, v171, v131
	v_fmac_f32_e32 v223, v171, v127
	v_cndmask_b32_e64 v171, v221, v204, s[2:3]
	ds_bpermute_b32 v170, v206, v170
	v_cndmask_b32_e64 v204, v218, v222, s[2:3]
	ds_bpermute_b32 v204, v206, v204
	v_cndmask_b32_e64 v220, v219, v223, s[2:3]
	ds_bpermute_b32 v220, v206, v220
	s_waitcnt lgkmcnt(0)
	v_add_f32_e32 v170, v171, v170
	v_cndmask_b32_e64 v171, v222, v218, s[2:3]
	v_add_f32_e32 v171, v171, v204
	v_cndmask_b32_e64 v204, v223, v219, s[2:3]
	v_add_f32_e32 v204, v204, v220
	v_cndmask_b32_e64 v218, v153, v171, s[4:5]
	v_cndmask_b32_e64 v219, v170, v204, s[4:5]
	ds_bpermute_b32 v218, v207, v218
	ds_bpermute_b32 v219, v207, v219
	v_cndmask_b32_e64 v153, v171, v153, s[4:5]
	v_cndmask_b32_e64 v170, v204, v170, s[4:5]
	s_waitcnt lgkmcnt(0)
	v_add_f32_e32 v153, v153, v218
	v_add_f32_e32 v170, v170, v219
	v_cndmask_b32_e64 v171, v153, v170, s[6:7]
	ds_bpermute_b32 v171, v208, v171
	v_cndmask_b32_e64 v153, v170, v153, s[6:7]
	s_waitcnt lgkmcnt(0)
	v_add_f32_e32 v153, v153, v171
	ds_bpermute_b32 v170, v209, v153
	s_waitcnt lgkmcnt(0)
	v_add_f32_e32 v153, v153, v170
	ds_bpermute_b32 v170, v210, v153
	s_waitcnt lgkmcnt(0)
	v_add_f32_e32 v153, v153, v170
	ds_bpermute_b32 v218, v211, v153
	v_lshl_add_u64 v[170:171], v[146:147], 0, s[10:11]
	s_and_saveexec_b64 s[10:11], s[8:9]
	s_cbranch_execz .LBB0_52
; template <int MODE, bool XBF>
; __device__ __forceinline__ void rmsnorm_rows(const void* x, const float* gain, bf16_t* H, int gw, int NGW, int lane, const LAS float* WF, const float* fbias, float* LF) {
;     ...
;                 if ((lane & 7) == 0) {
;                     const int row = row0 + r;
;                     const float z = d1 + fb;
;                     LF[((size_t)(row >> 12) * 8 + hsel) * S + (row & 4095)] = fminf(z, 0.f) - log1pf(__expf(-fabsf(z)));
;                 }
	s_waitcnt lgkmcnt(0)
	v_add_f32_e32 v153, v153, v218
	s_waitcnt vmcnt(0)
	v_add_f32_e32 v153, v217, v153
	v_mul_f32_e64 v204, |v153|, s43
	v_exp_f32_e32 v204, v204
	v_min_f32_e32 v232, 0, v153
	s_lshl_b32 s14, s48, 2
	v_add_f32_e32 v153, 1.0, v204
	v_add_f32_e32 v218, -1.0, v153
	v_sub_f32_e32 v219, v218, v153
	v_sub_f32_e32 v218, v204, v218
	v_add_f32_e32 v219, 1.0, v219
	v_frexp_mant_f32_e32 v220, v153
	v_add_f32_e32 v221, v218, v219
	v_cvt_f64_f32_e32 v[218:219], v153
	v_frexp_exp_i32_f64_e32 v218, v[218:219]
	v_cmp_gt_f32_e32 vcc, s44, v220
	s_nop 1
	v_subbrev_co_u32_e32 v226, vcc, 0, v218, vcc
	v_sub_u32_e32 v218, 0, v226
	v_ldexp_f32 v153, v153, v218
	v_add_f32_e32 v220, -1.0, v153
	v_add_f32_e32 v219, 1.0, v220
	v_ldexp_f32 v218, v221, v218
	v_sub_f32_e32 v219, v153, v219
	v_add_f32_e32 v221, v218, v219
	v_add_f32_e32 v219, 1.0, v153
	v_add_f32_e32 v222, -1.0, v219
	v_sub_f32_e32 v153, v153, v222
	v_add_f32_e32 v153, v218, v153
	v_add_f32_e32 v227, v219, v153
	v_rcp_f32_e32 v228, v227
	v_sub_f32_e32 v218, v227, v219
	v_add_f32_e32 v219, v220, v221
	v_sub_f32_e32 v153, v153, v218
	v_mul_f32_e32 v230, v219, v228
	v_sub_f32_e32 v218, v219, v220
	v_mul_f32_e32 v220, v227, v230
	v_fma_f32 v222, v230, v227, -v220
	v_fmac_f32_e32 v222, v230, v153
	v_sub_f32_e32 v229, v221, v218
	v_add_f32_e32 v218, v220, v222
	v_sub_f32_e32 v221, v219, v218
	v_add_f32_e64 v224, v218, -v220
	v_add_f32_e64 v225, v219, -v221
	v_mov_b32_e32 v223, v218
	v_add_f32_e64 v218, v224, -v222
	v_add_f32_e64 v219, v225, -v223
	v_cmp_neq_f32_e32 vcc, s46, v204
	v_add_f32_e32 v219, v229, v219
	v_add_f32_e32 v218, v218, v219
	v_add_f32_e32 v219, v221, v218
	v_mul_f32_e32 v229, v228, v219
	v_mul_f32_e32 v220, v227, v229
	v_fma_f32 v222, v229, v227, -v220
	v_fmac_f32_e32 v222, v229, v153
	v_sub_f32_e32 v153, v221, v219
	v_add_f32_e32 v153, v218, v153
	v_add_f32_e32 v218, v220, v222
	v_sub_f32_e32 v221, v219, v218
	v_add_f32_e64 v224, v218, -v220
	v_add_f32_e64 v225, v219, -v221
	v_mov_b32_e32 v223, v218
	v_add_f32_e64 v218, v224, -v222
	v_add_f32_e64 v219, v225, -v223
	s_nop 0
	v_add_f32_e32 v153, v153, v219
	v_add_f32_e32 v153, v218, v153
	v_add_f32_e32 v219, v230, v229
	v_add_f32_e32 v153, v221, v153
	v_sub_f32_e32 v218, v219, v230
	v_mul_f32_e32 v153, v228, v153
	v_sub_f32_e32 v218, v229, v218
	v_add_f32_e32 v220, v218, v153
	v_add_f32_e32 v222, v219, v220
	v_cvt_f32_i32_e32 v218, v226
	v_mul_f32_e32 v223, v222, v222
	v_sub_f32_e32 v219, v222, v219
	v_fmamk_f32 v153, v223, 0x3e9b6dac, v213
	v_sub_f32_e32 v219, v220, v219
	v_fmaak_f32 v153, v223, v153, 0x3f2aaada
	v_ldexp_f32 v224, v219, 1
	v_mul_f32_e32 v219, v222, v223
	v_ldexp_f32 v221, v222, 1
	v_mul_f32_e32 v222, v218, v152
	v_mul_f32_e32 v223, v219, v153
	s_nop 0
	v_fma_f32 v220, v218, s45, -v222
	v_fmac_f32_e32 v220, 0xb102e308, v218
	v_add_f32_e32 v218, v222, v220
	v_add_f32_e32 v219, v223, v221
	s_nop 0
	v_sub_f32_e32 v153, v219, v221
	v_sub_f32_e32 v153, v223, v153
	v_add_f32_e32 v225, v224, v153
	v_mov_b32_e32 v224, v222
	v_add_f32_e64 v222, v218, -v222
	v_add_f32_e64 v223, v219, -v223
	v_add_f32_e32 v226, v218, v224
	v_add_f32_e32 v227, v219, v225
	v_mov_b32_e32 v221, v218
	v_mov_b32_e32 v223, v227
	v_add_f32_e64 v228, v220, -v222
	v_add_f32_e64 v229, v221, -v223
	v_add_f32_e32 v220, v220, v222
	v_add_f32_e32 v221, v221, v223
	v_mov_b32_e32 v224, v225
	v_add_f32_e64 v222, v221, -v218
	v_add_f32_e64 v223, v220, -v219
	v_add_f32_e64 v230, v226, -v222
	v_add_f32_e64 v231, v227, -v222
	v_mov_b32_e32 v226, v227
	v_mov_b32_e32 v227, v221
	v_pk_mov_b32 v[222:223], v[218:219], v[222:223] op_sel:[1,0]
	v_mov_b32_e32 v225, v218
	v_add_f32_e64 v222, v226, -v222
	v_add_f32_e64 v223, v227, -v223
	v_mov_b32_e32 v230, v228
	v_add_f32_e64 v218, v224, -v222
	v_add_f32_e64 v219, v225, -v223
	v_mov_b32_e32 v229, v221
	v_add_f32_e32 v222, v230, v218
	v_add_f32_e32 v223, v231, v219
	s_nop 0
	v_add_f32_e32 v224, v222, v223
	v_add_f32_e32 v225, v223, v222
	s_nop 0
	v_pk_add_f32 v[220:221], v[220:221], v[224:225] op_sel:[1,0] op_sel_hi:[0,1]
	v_mov_b32_e32 v223, v220
	v_add_f32_e64 v226, v222, -v228
	v_add_f32_e64 v227, v223, -v229
	v_mov_b32_e32 v219, v224
	v_sub_f32_e32 v153, v222, v226
	v_add_f32_e64 v218, v218, -v226
	v_add_f32_e64 v219, v219, -v227
	v_sub_f32_e32 v153, v228, v153
	v_add_f32_e32 v153, v218, v153
	v_add_f32_e32 v153, v153, v219
	v_add_f32_e32 v153, v220, v153
	v_cndmask_b32_e32 v153, v214, v153, vcc
	v_cmp_ngt_f32_e32 vcc, -1.0, v204
	v_lshl_add_u64 v[218:219], v[170:171], 0, s[14:15]
	s_nop 0
	v_cndmask_b32_e32 v153, v215, v153, vcc
	v_cmp_neq_f32_e32 vcc, -1.0, v204
	s_nop 1
	v_cndmask_b32_e32 v153, v216, v153, vcc
	v_cmp_lt_f32_e64 vcc, |v204|, s47
	s_nop 1
	v_cndmask_b32_e32 v153, v153, v204, vcc
	v_sub_f32_e32 v153, v232, v153
	flat_store_dword v[218:219], v153
; template <int MODE, bool XBF>
; __device__ __forceinline__ void rmsnorm_rows(const void* x, const float* gain, bf16_t* H, int gw, int NGW, int lane, const LAS float* WF, const float* fbias, float* LF) {
;     ...
;                         for (int r = 0; r < RB; ++r) {
;                             const float hv = v[r][j][e][c];
;                             dt[r][0] += hv * w0[0]; dt[r][1] += hv * w0[1]; dt[r][2] += hv * w0[2]; dt[r][3] += hv * w0[3];
;                             dt[r][4] += hv * w1[0]; dt[r][5] += hv * w1[1]; dt[r][6] += hv * w1[2]; dt[r][7] += hv * w1[3];
;                         }
;                     }
;             const bool hi32 = (lane & 32) != 0, hi16 = (lane & 16) != 0, hi8 = (lane & 8) != 0;
;             const int hsel = (hi32 ? 4 : 0) + (hi16 ? 2 : 0) + (hi8 ? 1 : 0);
;             const float fb = fbias[hsel];
; #pragma unroll
;             for (int r = 0; r < RB; ++r) {
;                 float d4[4], d2[2], d1;
; #pragma unroll
;                 for (int k = 0; k < 4; ++k) { const float send = hi32 ? dt[r][k] : dt[r][k + 4], keep = hi32 ? dt[r][k + 4] : dt[r][k]; d4[k] = keep + __shfl_xor(send, 32); }
; #pragma unroll
;                 for (int k = 0; k < 2; ++k) { const float send = hi16 ? d4[k] : d4[k + 2], keep = hi16 ? d4[k + 2] : d4[k]; d2[k] = keep + __shfl_xor(send, 16); }
;                 { const float send = hi8 ? d2[0] : d2[1], keep = hi8 ? d2[1] : d2[0]; d1 = keep + __shfl_xor(send, 8); }
;                 d1 += __shfl_xor(d1, 4); d1 += __shfl_xor(d1, 2); d1 += __shfl_xor(d1, 1);
.LBB0_52:
	s_or_b64 exec, exec, s[10:11]
	v_fma_f32 v153, v24, v202, 0
	v_fma_f32 v220, v28, v202, 0
	v_fmac_f32_e32 v153, v20, v203
	v_fmac_f32_e32 v220, v203, v16
	v_fma_f32 v204, v25, v202, 0
	s_waitcnt lgkmcnt(0)
	v_fma_f32 v218, v26, v202, 0
	v_fma_f32 v219, v27, v202, 0
	v_fma_f32 v221, v29, v202, 0
	v_fma_f32 v222, v30, v202, 0
	v_fma_f32 v202, v31, v202, 0
	v_fmac_f32_e32 v153, v200, v36
	v_fmac_f32_e32 v220, v200, v32
	v_fmac_f32_e32 v204, v21, v203
	v_fmac_f32_e32 v218, v22, v203
	v_fmac_f32_e32 v219, v23, v203
	v_fmac_f32_e32 v221, v203, v17
	v_fmac_f32_e32 v222, v203, v18
	v_fmac_f32_e32 v202, v203, v19
	v_fmac_f32_e32 v153, v201, v44
	v_fmac_f32_e32 v220, v201, v40
	v_fmac_f32_e32 v204, v200, v37
	v_fmac_f32_e32 v218, v200, v38
	v_fmac_f32_e32 v219, v200, v39
	v_fmac_f32_e32 v221, v200, v33
	v_fmac_f32_e32 v222, v200, v34
	v_fmac_f32_e32 v202, v200, v35
	v_fmac_f32_e32 v153, v198, v52
	v_fmac_f32_e32 v220, v198, v48
	v_fmac_f32_e32 v204, v201, v45
	v_fmac_f32_e32 v218, v201, v46
	v_fmac_f32_e32 v219, v201, v47
	v_fmac_f32_e32 v221, v201, v41
	v_fmac_f32_e32 v222, v201, v42
	v_fmac_f32_e32 v202, v201, v43
	v_fmac_f32_e32 v153, v199, v60
	v_fmac_f32_e32 v220, v199, v56
	v_fmac_f32_e32 v204, v198, v53
	v_fmac_f32_e32 v218, v198, v54
	v_fmac_f32_e32 v219, v198, v55
	v_fmac_f32_e32 v221, v198, v49
	v_fmac_f32_e32 v222, v198, v50
	v_fmac_f32_e32 v202, v198, v51
	v_fmac_f32_e32 v153, v196, v68
	v_fmac_f32_e32 v220, v196, v64
	v_fmac_f32_e32 v204, v199, v61
	v_fmac_f32_e32 v218, v199, v62
	v_fmac_f32_e32 v219, v199, v63
	v_fmac_f32_e32 v221, v199, v57
	v_fmac_f32_e32 v222, v199, v58
	v_fmac_f32_e32 v202, v199, v59
	v_fmac_f32_e32 v153, v197, v72
	v_fmac_f32_e32 v220, v197, v76
	v_fmac_f32_e32 v204, v196, v69
	v_fmac_f32_e32 v218, v196, v70
	v_fmac_f32_e32 v219, v196, v71
	v_fmac_f32_e32 v221, v196, v65
	v_fmac_f32_e32 v222, v196, v66
	v_fmac_f32_e32 v202, v196, v67
	v_fmac_f32_e32 v153, v194, v80
	v_fmac_f32_e32 v220, v194, v84
	v_fmac_f32_e32 v204, v197, v73
	v_fmac_f32_e32 v218, v197, v74
	v_fmac_f32_e32 v219, v197, v75
	v_fmac_f32_e32 v221, v197, v77
	v_fmac_f32_e32 v222, v197, v78
	v_fmac_f32_e32 v202, v197, v79
	v_fmac_f32_e32 v153, v195, v88
	v_fmac_f32_e32 v220, v195, v92
	v_fmac_f32_e32 v204, v194, v81
	v_fmac_f32_e32 v218, v194, v82
	v_fmac_f32_e32 v219, v194, v83
	v_fmac_f32_e32 v221, v194, v85
	v_fmac_f32_e32 v222, v194, v86
	v_fmac_f32_e32 v202, v194, v87
	v_fmac_f32_e32 v153, v192, v96
	v_fmac_f32_e32 v220, v192, v100
	v_fmac_f32_e32 v204, v195, v89
	v_fmac_f32_e32 v218, v195, v90
	v_fmac_f32_e32 v219, v195, v91
	v_fmac_f32_e32 v221, v195, v93
	v_fmac_f32_e32 v222, v195, v94
	v_fmac_f32_e32 v202, v195, v95
	v_fmac_f32_e32 v153, v193, v104
	v_fmac_f32_e32 v220, v193, v108
	v_fmac_f32_e32 v204, v192, v97
	v_fmac_f32_e32 v218, v192, v98
	v_fmac_f32_e32 v219, v192, v99
	v_fmac_f32_e32 v221, v192, v101
	v_fmac_f32_e32 v222, v192, v102
	v_fmac_f32_e32 v202, v192, v103
	v_fmac_f32_e32 v153, v190, v112
	v_fmac_f32_e32 v220, v190, v116
	v_fmac_f32_e32 v204, v193, v105
	v_fmac_f32_e32 v218, v193, v106
	v_fmac_f32_e32 v219, v193, v107
	v_fmac_f32_e32 v221, v193, v109
	v_fmac_f32_e32 v222, v193, v110
	v_fmac_f32_e32 v202, v193, v111
	v_fmac_f32_e32 v153, v191, v120
	v_fmac_f32_e32 v220, v191, v140
	v_fmac_f32_e32 v204, v190, v113
	v_fmac_f32_e32 v218, v190, v114
	v_fmac_f32_e32 v219, v190, v115
	v_fmac_f32_e32 v221, v190, v117
	v_fmac_f32_e32 v222, v190, v118
	v_fmac_f32_e32 v202, v190, v119
	v_fmac_f32_e32 v153, v188, v136
	v_fmac_f32_e32 v220, v188, v132
	v_fmac_f32_e32 v204, v191, v121
	v_fmac_f32_e32 v218, v191, v122
	v_fmac_f32_e32 v219, v191, v123
	v_fmac_f32_e32 v221, v191, v141
	v_fmac_f32_e32 v222, v191, v142
	v_fmac_f32_e32 v202, v191, v143
	v_fmac_f32_e32 v153, v189, v128
	v_fmac_f32_e32 v220, v189, v124
	v_fmac_f32_e32 v204, v188, v137
	v_fmac_f32_e32 v218, v188, v138
	v_fmac_f32_e32 v219, v188, v139
	v_fmac_f32_e32 v221, v188, v133
	v_fmac_f32_e32 v222, v188, v134
	v_fmac_f32_e32 v202, v188, v135
	v_cndmask_b32_e64 v188, v153, v220, s[2:3]
	ds_bpermute_b32 v188, v206, v188
	v_fmac_f32_e32 v204, v189, v129
	v_fmac_f32_e32 v221, v189, v125
	v_cndmask_b32_e64 v153, v220, v153, s[2:3]
	v_fmac_f32_e32 v218, v189, v130
	v_fmac_f32_e32 v222, v189, v126
	s_waitcnt lgkmcnt(0)
	v_add_f32_e32 v153, v153, v188
	v_cndmask_b32_e64 v188, v204, v221, s[2:3]
	v_fmac_f32_e32 v219, v189, v131
	v_fmac_f32_e32 v202, v189, v127
	ds_bpermute_b32 v188, v206, v188
	v_cndmask_b32_e64 v190, v218, v222, s[2:3]
	ds_bpermute_b32 v190, v206, v190
	v_cndmask_b32_e64 v191, v219, v202, s[2:3]
	ds_bpermute_b32 v191, v206, v191
	v_cndmask_b32_e64 v189, v221, v204, s[2:3]
	s_waitcnt lgkmcnt(0)
	v_add_f32_e32 v188, v189, v188
	v_cndmask_b32_e64 v189, v222, v218, s[2:3]
	v_add_f32_e32 v189, v189, v190
	v_cndmask_b32_e64 v190, v202, v219, s[2:3]
	v_add_f32_e32 v190, v190, v191
	v_cndmask_b32_e64 v191, v153, v189, s[4:5]
	v_cndmask_b32_e64 v192, v188, v190, s[4:5]
	ds_bpermute_b32 v191, v207, v191
	ds_bpermute_b32 v192, v207, v192
	v_cndmask_b32_e64 v153, v189, v153, s[4:5]
	v_cndmask_b32_e64 v188, v190, v188, s[4:5]
	s_waitcnt lgkmcnt(0)
	v_add_f32_e32 v153, v153, v191
	v_add_f32_e32 v188, v188, v192
	v_cndmask_b32_e64 v189, v153, v188, s[6:7]
	ds_bpermute_b32 v189, v208, v189
	v_cndmask_b32_e64 v153, v188, v153, s[6:7]
	s_waitcnt lgkmcnt(0)
	v_add_f32_e32 v153, v153, v189
	ds_bpermute_b32 v188, v209, v153
	s_waitcnt lgkmcnt(0)
	v_add_f32_e32 v153, v153, v188
	ds_bpermute_b32 v188, v210, v153
	s_waitcnt lgkmcnt(0)
	v_add_f32_e32 v153, v153, v188
	ds_bpermute_b32 v188, v211, v153
	s_and_saveexec_b64 s[10:11], s[8:9]
	s_cbranch_execz .LBB0_54
; template <int MODE, bool XBF>
; __device__ __forceinline__ void rmsnorm_rows(const void* x, const float* gain, bf16_t* H, int gw, int NGW, int lane, const LAS float* WF, const float* fbias, float* LF) {
;     ...
;                 if ((lane & 7) == 0) {
;                     const int row = row0 + r;
;                     const float z = d1 + fb;
;                     LF[((size_t)(row >> 12) * 8 + hsel) * S + (row & 4095)] = fminf(z, 0.f) - log1pf(__expf(-fabsf(z)));
;                 }
	s_waitcnt lgkmcnt(0)
	v_add_f32_e32 v153, v153, v188
	s_waitcnt vmcnt(0)
	v_add_f32_e32 v153, v217, v153
	v_mul_f32_e64 v188, |v153|, s43
	v_exp_f32_e32 v202, v188
	v_min_f32_e32 v203, 0, v153
	s_lshl_b32 s14, s48, 2
	v_add_f32_e32 v153, 1.0, v202
	v_add_f32_e32 v188, -1.0, v153
	v_sub_f32_e32 v189, v188, v153
	v_sub_f32_e32 v188, v202, v188
	v_add_f32_e32 v189, 1.0, v189
	v_frexp_mant_f32_e32 v190, v153
	v_add_f32_e32 v191, v188, v189
	v_cvt_f64_f32_e32 v[188:189], v153
	v_frexp_exp_i32_f64_e32 v188, v[188:189]
	v_cmp_gt_f32_e32 vcc, s44, v190
	s_nop 1
	v_subbrev_co_u32_e32 v196, vcc, 0, v188, vcc
	v_sub_u32_e32 v188, 0, v196
	v_ldexp_f32 v153, v153, v188
	v_add_f32_e32 v190, -1.0, v153
	v_add_f32_e32 v189, 1.0, v190
	v_ldexp_f32 v188, v191, v188
	v_sub_f32_e32 v189, v153, v189
	v_add_f32_e32 v191, v188, v189
	v_add_f32_e32 v189, 1.0, v153
	v_add_f32_e32 v192, -1.0, v189
	v_sub_f32_e32 v153, v153, v192
	v_add_f32_e32 v153, v188, v153
	v_add_f32_e32 v197, v189, v153
	v_rcp_f32_e32 v198, v197
	v_sub_f32_e32 v188, v197, v189
	v_add_f32_e32 v189, v190, v191
	v_sub_f32_e32 v153, v153, v188
	v_mul_f32_e32 v200, v189, v198
	v_sub_f32_e32 v188, v189, v190
	v_mul_f32_e32 v190, v197, v200
	v_fma_f32 v192, v200, v197, -v190
	v_fmac_f32_e32 v192, v200, v153
	v_sub_f32_e32 v199, v191, v188
	v_add_f32_e32 v188, v190, v192
	v_sub_f32_e32 v191, v189, v188
	v_add_f32_e64 v194, v188, -v190
	v_add_f32_e64 v195, v189, -v191
	v_mov_b32_e32 v193, v188
	v_add_f32_e64 v188, v194, -v192
	v_add_f32_e64 v189, v195, -v193
	v_cmp_neq_f32_e32 vcc, s46, v202
	v_add_f32_e32 v189, v199, v189
	v_add_f32_e32 v188, v188, v189
	v_add_f32_e32 v189, v191, v188
	v_mul_f32_e32 v199, v198, v189
	v_mul_f32_e32 v190, v197, v199
	v_fma_f32 v192, v199, v197, -v190
	v_fmac_f32_e32 v192, v199, v153
	v_sub_f32_e32 v153, v191, v189
	v_add_f32_e32 v153, v188, v153
	v_add_f32_e32 v188, v190, v192
	v_sub_f32_e32 v191, v189, v188
	v_add_f32_e64 v194, v188, -v190
	v_add_f32_e64 v195, v189, -v191
	v_mov_b32_e32 v193, v188
	v_add_f32_e64 v188, v194, -v192
	v_add_f32_e64 v189, v195, -v193
	s_nop 0
	v_add_f32_e32 v153, v153, v189
	v_add_f32_e32 v153, v188, v153
	v_add_f32_e32 v189, v200, v199
	v_add_f32_e32 v153, v191, v153
	v_sub_f32_e32 v188, v189, v200
	v_mul_f32_e32 v153, v198, v153
	v_sub_f32_e32 v188, v199, v188
	v_add_f32_e32 v190, v188, v153
	v_add_f32_e32 v192, v189, v190
	v_cvt_f32_i32_e32 v188, v196
	v_mul_f32_e32 v193, v192, v192
	v_sub_f32_e32 v189, v192, v189
	v_fmamk_f32 v153, v193, 0x3e9b6dac, v213
	v_sub_f32_e32 v189, v190, v189
	v_fmaak_f32 v153, v193, v153, 0x3f2aaada
	v_ldexp_f32 v194, v189, 1
	v_mul_f32_e32 v189, v192, v193
	v_ldexp_f32 v191, v192, 1
	v_mul_f32_e32 v192, v188, v152
	v_mul_f32_e32 v193, v189, v153
	s_nop 0
	v_fma_f32 v190, v188, s45, -v192
	v_fmac_f32_e32 v190, 0xb102e308, v188
	v_add_f32_e32 v188, v192, v190
	v_add_f32_e32 v189, v193, v191
	s_nop 0
	v_sub_f32_e32 v153, v189, v191
	v_sub_f32_e32 v153, v193, v153
	v_add_f32_e32 v195, v194, v153
	v_mov_b32_e32 v194, v192
	v_add_f32_e64 v192, v188, -v192
	v_add_f32_e64 v193, v189, -v193
	v_add_f32_e32 v196, v188, v194
	v_add_f32_e32 v197, v189, v195
	v_mov_b32_e32 v191, v188
	v_mov_b32_e32 v193, v197
	v_add_f32_e64 v198, v190, -v192
	v_add_f32_e64 v199, v191, -v193
	v_add_f32_e32 v190, v190, v192
	v_add_f32_e32 v191, v191, v193
	v_mov_b32_e32 v194, v195
	v_add_f32_e64 v192, v191, -v188
	v_add_f32_e64 v193, v190, -v189
	v_add_f32_e64 v200, v196, -v192
	v_add_f32_e64 v201, v197, -v192
	v_mov_b32_e32 v196, v197
	v_mov_b32_e32 v197, v191
	v_pk_mov_b32 v[192:193], v[188:189], v[192:193] op_sel:[1,0]
	v_mov_b32_e32 v195, v188
	v_add_f32_e64 v192, v196, -v192
	v_add_f32_e64 v193, v197, -v193
	v_mov_b32_e32 v200, v198
	v_add_f32_e64 v188, v194, -v192
	v_add_f32_e64 v189, v195, -v193
	v_mov_b32_e32 v199, v191
	v_add_f32_e32 v192, v200, v188
	v_add_f32_e32 v193, v201, v189
	s_nop 0
	v_add_f32_e32 v194, v192, v193
	v_add_f32_e32 v195, v193, v192
	s_nop 0
	v_pk_add_f32 v[190:191], v[190:191], v[194:195] op_sel:[1,0] op_sel_hi:[0,1]
	v_mov_b32_e32 v193, v190
	v_add_f32_e64 v196, v192, -v198
	v_add_f32_e64 v197, v193, -v199
	v_mov_b32_e32 v189, v194
	v_sub_f32_e32 v153, v192, v196
	v_add_f32_e64 v188, v188, -v196
	v_add_f32_e64 v189, v189, -v197
	v_sub_f32_e32 v153, v198, v153
	v_add_f32_e32 v153, v188, v153
	v_add_f32_e32 v153, v153, v189
	v_add_f32_e32 v153, v190, v153
	v_cndmask_b32_e32 v153, v214, v153, vcc
	v_cmp_ngt_f32_e32 vcc, -1.0, v202
	v_lshl_add_u64 v[188:189], v[170:171], 0, s[14:15]
	s_nop 0
	v_cndmask_b32_e32 v153, v215, v153, vcc
	v_cmp_neq_f32_e32 vcc, -1.0, v202
	s_nop 1
	v_cndmask_b32_e32 v153, v216, v153, vcc
	v_cmp_lt_f32_e64 vcc, |v202|, s47
	s_nop 1
	v_cndmask_b32_e32 v153, v153, v202, vcc
	v_sub_f32_e32 v153, v203, v153
	flat_store_dword v[188:189], v153 offset:4
; template <int MODE, bool XBF>
; __device__ __forceinline__ void rmsnorm_rows(const void* x, const float* gain, bf16_t* H, int gw, int NGW, int lane, const LAS float* WF, const float* fbias, float* LF) {
;     ...
;                         for (int r = 0; r < RB; ++r) {
;                             const float hv = v[r][j][e][c];
;                             dt[r][0] += hv * w0[0]; dt[r][1] += hv * w0[1]; dt[r][2] += hv * w0[2]; dt[r][3] += hv * w0[3];
;                             dt[r][4] += hv * w1[0]; dt[r][5] += hv * w1[1]; dt[r][6] += hv * w1[2]; dt[r][7] += hv * w1[3];
;                         }
;                     }
;             const bool hi32 = (lane & 32) != 0, hi16 = (lane & 16) != 0, hi8 = (lane & 8) != 0;
;             const int hsel = (hi32 ? 4 : 0) + (hi16 ? 2 : 0) + (hi8 ? 1 : 0);
;             const float fb = fbias[hsel];
; #pragma unroll
;             for (int r = 0; r < RB; ++r) {
;                 float d4[4], d2[2], d1;
; #pragma unroll
;                 for (int k = 0; k < 4; ++k) { const float send = hi32 ? dt[r][k] : dt[r][k + 4], keep = hi32 ? dt[r][k + 4] : dt[r][k]; d4[k] = keep + __shfl_xor(send, 32); }
; #pragma unroll
;                 for (int k = 0; k < 2; ++k) { const float send = hi16 ? d4[k] : d4[k + 2], keep = hi16 ? d4[k + 2] : d4[k]; d2[k] = keep + __shfl_xor(send, 16); }
;                 { const float send = hi8 ? d2[0] : d2[1], keep = hi8 ? d2[1] : d2[0]; d1 = keep + __shfl_xor(send, 8); }
;                 d1 += __shfl_xor(d1, 4); d1 += __shfl_xor(d1, 2); d1 += __shfl_xor(d1, 1);
.LBB0_54:
	s_or_b64 exec, exec, s[10:11]
	v_fma_f32 v153, v24, v186, 0
	v_fma_f32 v191, v28, v186, 0
	v_fmac_f32_e32 v153, v20, v187
	v_fmac_f32_e32 v191, v16, v187
	s_waitcnt lgkmcnt(0)
	v_fma_f32 v188, v25, v186, 0
	v_fma_f32 v189, v26, v186, 0
	v_fma_f32 v190, v27, v186, 0
	v_fma_f32 v192, v29, v186, 0
	v_fma_f32 v193, v30, v186, 0
	v_fma_f32 v186, v31, v186, 0
	v_fmac_f32_e32 v153, v184, v36
	v_fmac_f32_e32 v191, v184, v32
	v_fmac_f32_e32 v188, v21, v187
	v_fmac_f32_e32 v189, v22, v187
	v_fmac_f32_e32 v190, v23, v187
	v_fmac_f32_e32 v192, v17, v187
	v_fmac_f32_e32 v193, v18, v187
	v_fmac_f32_e32 v186, v19, v187
	v_fmac_f32_e32 v153, v185, v44
	v_fmac_f32_e32 v191, v185, v40
	v_fmac_f32_e32 v188, v184, v37
	v_fmac_f32_e32 v189, v184, v38
	v_fmac_f32_e32 v190, v184, v39
	v_fmac_f32_e32 v192, v184, v33
	v_fmac_f32_e32 v193, v184, v34
	v_fmac_f32_e32 v186, v184, v35
	v_fmac_f32_e32 v153, v182, v52
	v_fmac_f32_e32 v191, v182, v48
	v_fmac_f32_e32 v188, v185, v45
	v_fmac_f32_e32 v189, v185, v46
	v_fmac_f32_e32 v190, v185, v47
	v_fmac_f32_e32 v192, v185, v41
	v_fmac_f32_e32 v193, v185, v42
	v_fmac_f32_e32 v186, v185, v43
	v_fmac_f32_e32 v153, v183, v60
	v_fmac_f32_e32 v191, v183, v56
	v_fmac_f32_e32 v188, v182, v53
	v_fmac_f32_e32 v189, v182, v54
	v_fmac_f32_e32 v190, v182, v55
	v_fmac_f32_e32 v192, v182, v49
	v_fmac_f32_e32 v193, v182, v50
	v_fmac_f32_e32 v186, v182, v51
	v_fmac_f32_e32 v153, v180, v68
	v_fmac_f32_e32 v191, v180, v64
	v_fmac_f32_e32 v188, v183, v61
	v_fmac_f32_e32 v189, v183, v62
	v_fmac_f32_e32 v190, v183, v63
	v_fmac_f32_e32 v192, v183, v57
	v_fmac_f32_e32 v193, v183, v58
	v_fmac_f32_e32 v186, v183, v59
	v_fmac_f32_e32 v153, v181, v72
	v_fmac_f32_e32 v191, v181, v76
	v_fmac_f32_e32 v188, v180, v69
	v_fmac_f32_e32 v189, v180, v70
	v_fmac_f32_e32 v190, v180, v71
	v_fmac_f32_e32 v192, v180, v65
	v_fmac_f32_e32 v193, v180, v66
	v_fmac_f32_e32 v186, v180, v67
	v_fmac_f32_e32 v153, v178, v80
	v_fmac_f32_e32 v191, v178, v84
	v_fmac_f32_e32 v188, v181, v73
	v_fmac_f32_e32 v189, v181, v74
	v_fmac_f32_e32 v190, v181, v75
	v_fmac_f32_e32 v192, v181, v77
	v_fmac_f32_e32 v193, v181, v78
	v_fmac_f32_e32 v186, v181, v79
	v_fmac_f32_e32 v153, v179, v88
	v_fmac_f32_e32 v191, v179, v92
	v_fmac_f32_e32 v188, v178, v81
	v_fmac_f32_e32 v189, v178, v82
	v_fmac_f32_e32 v190, v178, v83
	v_fmac_f32_e32 v192, v178, v85
	v_fmac_f32_e32 v193, v178, v86
	v_fmac_f32_e32 v186, v178, v87
	v_fmac_f32_e32 v153, v176, v96
	v_fmac_f32_e32 v191, v176, v100
	v_fmac_f32_e32 v188, v179, v89
	v_fmac_f32_e32 v189, v179, v90
	v_fmac_f32_e32 v190, v179, v91
	v_fmac_f32_e32 v192, v179, v93
	v_fmac_f32_e32 v193, v179, v94
	v_fmac_f32_e32 v186, v179, v95
	v_fmac_f32_e32 v153, v177, v104
	v_fmac_f32_e32 v191, v177, v108
	v_fmac_f32_e32 v188, v176, v97
	v_fmac_f32_e32 v189, v176, v98
	v_fmac_f32_e32 v190, v176, v99
	v_fmac_f32_e32 v192, v176, v101
	v_fmac_f32_e32 v193, v176, v102
	v_fmac_f32_e32 v186, v176, v103
	v_fmac_f32_e32 v153, v174, v112
	v_fmac_f32_e32 v191, v174, v116
	v_fmac_f32_e32 v188, v177, v105
	v_fmac_f32_e32 v189, v177, v106
	v_fmac_f32_e32 v190, v177, v107
	v_fmac_f32_e32 v192, v177, v109
	v_fmac_f32_e32 v193, v177, v110
	v_fmac_f32_e32 v186, v177, v111
	v_fmac_f32_e32 v153, v175, v120
	v_fmac_f32_e32 v191, v175, v140
	v_fmac_f32_e32 v188, v174, v113
	v_fmac_f32_e32 v189, v174, v114
	v_fmac_f32_e32 v190, v174, v115
	v_fmac_f32_e32 v192, v174, v117
	v_fmac_f32_e32 v193, v174, v118
	v_fmac_f32_e32 v186, v174, v119
	v_fmac_f32_e32 v153, v172, v136
	v_fmac_f32_e32 v191, v172, v132
	v_fmac_f32_e32 v188, v175, v121
	v_fmac_f32_e32 v189, v175, v122
	v_fmac_f32_e32 v190, v175, v123
	v_fmac_f32_e32 v192, v175, v141
	v_fmac_f32_e32 v193, v175, v142
	v_fmac_f32_e32 v186, v175, v143
	v_fmac_f32_e32 v153, v173, v128
	v_fmac_f32_e32 v191, v173, v124
	v_fmac_f32_e32 v188, v172, v137
	v_fmac_f32_e32 v189, v172, v138
	v_fmac_f32_e32 v190, v172, v139
	v_fmac_f32_e32 v192, v172, v133
	v_fmac_f32_e32 v193, v172, v134
	v_fmac_f32_e32 v186, v172, v135
	v_cndmask_b32_e64 v172, v153, v191, s[2:3]
	ds_bpermute_b32 v172, v206, v172
	v_fmac_f32_e32 v188, v173, v129
	v_fmac_f32_e32 v192, v173, v125
	v_cndmask_b32_e64 v153, v191, v153, s[2:3]
	v_fmac_f32_e32 v189, v173, v130
	v_fmac_f32_e32 v193, v173, v126
	s_waitcnt lgkmcnt(0)
	v_add_f32_e32 v153, v153, v172
	v_cndmask_b32_e64 v172, v188, v192, s[2:3]
	v_fmac_f32_e32 v190, v173, v131
	v_fmac_f32_e32 v186, v173, v127
	ds_bpermute_b32 v172, v206, v172
	v_cndmask_b32_e64 v174, v189, v193, s[2:3]
	ds_bpermute_b32 v174, v206, v174
	v_cndmask_b32_e64 v175, v190, v186, s[2:3]
	ds_bpermute_b32 v175, v206, v175
	v_cndmask_b32_e64 v173, v192, v188, s[2:3]
	s_waitcnt lgkmcnt(0)
	v_add_f32_e32 v172, v173, v172
	v_cndmask_b32_e64 v173, v193, v189, s[2:3]
	v_add_f32_e32 v173, v173, v174
	v_cndmask_b32_e64 v174, v186, v190, s[2:3]
	v_add_f32_e32 v174, v174, v175
	v_cndmask_b32_e64 v175, v153, v173, s[4:5]
	v_cndmask_b32_e64 v176, v172, v174, s[4:5]
	ds_bpermute_b32 v175, v207, v175
	ds_bpermute_b32 v176, v207, v176
	v_cndmask_b32_e64 v153, v173, v153, s[4:5]
	v_cndmask_b32_e64 v172, v174, v172, s[4:5]
	s_waitcnt lgkmcnt(0)
	v_add_f32_e32 v153, v153, v175
	v_add_f32_e32 v172, v172, v176
	v_cndmask_b32_e64 v173, v153, v172, s[6:7]
	ds_bpermute_b32 v173, v208, v173
	v_cndmask_b32_e64 v153, v172, v153, s[6:7]
	s_waitcnt lgkmcnt(0)
	v_add_f32_e32 v153, v153, v173
	ds_bpermute_b32 v172, v209, v153
	s_waitcnt lgkmcnt(0)
	v_add_f32_e32 v153, v153, v172
	ds_bpermute_b32 v172, v210, v153
	s_waitcnt lgkmcnt(0)
	v_add_f32_e32 v153, v153, v172
	ds_bpermute_b32 v172, v211, v153
	s_and_saveexec_b64 s[10:11], s[8:9]
	s_cbranch_execz .LBB0_56
; template <int MODE, bool XBF>
; __device__ __forceinline__ void rmsnorm_rows(const void* x, const float* gain, bf16_t* H, int gw, int NGW, int lane, const LAS float* WF, const float* fbias, float* LF) {
;     ...
;                 if ((lane & 7) == 0) {
;                     const int row = row0 + r;
;                     const float z = d1 + fb;
;                     LF[((size_t)(row >> 12) * 8 + hsel) * S + (row & 4095)] = fminf(z, 0.f) - log1pf(__expf(-fabsf(z)));
;                 }
	s_waitcnt lgkmcnt(0)
	v_add_f32_e32 v153, v153, v172
	s_waitcnt vmcnt(0)
	v_add_f32_e32 v153, v217, v153
	v_mul_f32_e64 v172, |v153|, s43
	v_exp_f32_e32 v186, v172
	v_min_f32_e32 v187, 0, v153
	s_lshl_b32 s14, s48, 2
	v_add_f32_e32 v153, 1.0, v186
	v_add_f32_e32 v172, -1.0, v153
	v_sub_f32_e32 v173, v172, v153
	v_sub_f32_e32 v172, v186, v172
	v_add_f32_e32 v173, 1.0, v173
	v_frexp_mant_f32_e32 v174, v153
	v_add_f32_e32 v175, v172, v173
	v_cvt_f64_f32_e32 v[172:173], v153
	v_frexp_exp_i32_f64_e32 v172, v[172:173]
	v_cmp_gt_f32_e32 vcc, s44, v174
	s_nop 1
	v_subbrev_co_u32_e32 v180, vcc, 0, v172, vcc
	v_sub_u32_e32 v172, 0, v180
	v_ldexp_f32 v153, v153, v172
	v_add_f32_e32 v174, -1.0, v153
	v_add_f32_e32 v173, 1.0, v174
	v_ldexp_f32 v172, v175, v172
	v_sub_f32_e32 v173, v153, v173
	v_add_f32_e32 v175, v172, v173
	v_add_f32_e32 v173, 1.0, v153
	v_add_f32_e32 v176, -1.0, v173
	v_sub_f32_e32 v153, v153, v176
	v_add_f32_e32 v153, v172, v153
	v_add_f32_e32 v181, v173, v153
	v_rcp_f32_e32 v182, v181
	v_sub_f32_e32 v172, v181, v173
	v_add_f32_e32 v173, v174, v175
	v_sub_f32_e32 v153, v153, v172
	v_mul_f32_e32 v184, v173, v182
	v_sub_f32_e32 v172, v173, v174
	v_mul_f32_e32 v174, v181, v184
	v_fma_f32 v176, v184, v181, -v174
	v_fmac_f32_e32 v176, v184, v153
	v_sub_f32_e32 v183, v175, v172
	v_add_f32_e32 v172, v174, v176
	v_sub_f32_e32 v175, v173, v172
	v_add_f32_e64 v178, v172, -v174
	v_add_f32_e64 v179, v173, -v175
	v_mov_b32_e32 v177, v172
	v_add_f32_e64 v172, v178, -v176
	v_add_f32_e64 v173, v179, -v177
	v_cmp_neq_f32_e32 vcc, s46, v186
	v_add_f32_e32 v173, v183, v173
	v_add_f32_e32 v172, v172, v173
	v_add_f32_e32 v173, v175, v172
	v_mul_f32_e32 v183, v182, v173
	v_mul_f32_e32 v174, v181, v183
	v_fma_f32 v176, v183, v181, -v174
	v_fmac_f32_e32 v176, v183, v153
	v_sub_f32_e32 v153, v175, v173
	v_add_f32_e32 v153, v172, v153
	v_add_f32_e32 v172, v174, v176
	v_sub_f32_e32 v175, v173, v172
	v_add_f32_e64 v178, v172, -v174
	v_add_f32_e64 v179, v173, -v175
	v_mov_b32_e32 v177, v172
	v_add_f32_e64 v172, v178, -v176
	v_add_f32_e64 v173, v179, -v177
	s_nop 0
	v_add_f32_e32 v153, v153, v173
	v_add_f32_e32 v153, v172, v153
	v_add_f32_e32 v173, v184, v183
	v_add_f32_e32 v153, v175, v153
	v_sub_f32_e32 v172, v173, v184
	v_mul_f32_e32 v153, v182, v153
	v_sub_f32_e32 v172, v183, v172
	v_add_f32_e32 v174, v172, v153
	v_add_f32_e32 v176, v173, v174
	v_cvt_f32_i32_e32 v172, v180
	v_mul_f32_e32 v177, v176, v176
	v_sub_f32_e32 v173, v176, v173
	v_fmamk_f32 v153, v177, 0x3e9b6dac, v213
	v_sub_f32_e32 v173, v174, v173
	v_fmaak_f32 v153, v177, v153, 0x3f2aaada
	v_ldexp_f32 v178, v173, 1
	v_mul_f32_e32 v173, v176, v177
	v_ldexp_f32 v175, v176, 1
	v_mul_f32_e32 v176, v172, v152
	v_mul_f32_e32 v177, v173, v153
	s_nop 0
	v_fma_f32 v174, v172, s45, -v176
	v_fmac_f32_e32 v174, 0xb102e308, v172
	v_add_f32_e32 v172, v176, v174
	v_add_f32_e32 v173, v177, v175
	s_nop 0
	v_sub_f32_e32 v153, v173, v175
	v_sub_f32_e32 v153, v177, v153
	v_add_f32_e32 v179, v178, v153
	v_mov_b32_e32 v178, v176
	v_add_f32_e64 v176, v172, -v176
	v_add_f32_e64 v177, v173, -v177
	v_add_f32_e32 v180, v172, v178
	v_add_f32_e32 v181, v173, v179
	v_mov_b32_e32 v175, v172
	v_mov_b32_e32 v177, v181
	v_add_f32_e64 v182, v174, -v176
	v_add_f32_e64 v183, v175, -v177
	v_add_f32_e32 v174, v174, v176
	v_add_f32_e32 v175, v175, v177
	v_mov_b32_e32 v178, v179
	v_add_f32_e64 v176, v175, -v172
	v_add_f32_e64 v177, v174, -v173
	v_add_f32_e64 v184, v180, -v176
	v_add_f32_e64 v185, v181, -v176
	v_mov_b32_e32 v180, v181
	v_mov_b32_e32 v181, v175
	v_pk_mov_b32 v[176:177], v[172:173], v[176:177] op_sel:[1,0]
	v_mov_b32_e32 v179, v172
	v_add_f32_e64 v176, v180, -v176
	v_add_f32_e64 v177, v181, -v177
	v_mov_b32_e32 v184, v182
	v_add_f32_e64 v172, v178, -v176
	v_add_f32_e64 v173, v179, -v177
	v_mov_b32_e32 v183, v175
	v_add_f32_e32 v176, v184, v172
	v_add_f32_e32 v177, v185, v173
	s_nop 0
	v_add_f32_e32 v178, v176, v177
	v_add_f32_e32 v179, v177, v176
	s_nop 0
	v_pk_add_f32 v[174:175], v[174:175], v[178:179] op_sel:[1,0] op_sel_hi:[0,1]
	v_mov_b32_e32 v177, v174
	v_add_f32_e64 v180, v176, -v182
	v_add_f32_e64 v181, v177, -v183
	v_mov_b32_e32 v173, v178
	v_sub_f32_e32 v153, v176, v180
	v_add_f32_e64 v172, v172, -v180
	v_add_f32_e64 v173, v173, -v181
	v_sub_f32_e32 v153, v182, v153
	v_add_f32_e32 v153, v172, v153
	v_add_f32_e32 v153, v153, v173
	v_add_f32_e32 v153, v174, v153
	v_cndmask_b32_e32 v153, v214, v153, vcc
	v_cmp_ngt_f32_e32 vcc, -1.0, v186
	v_lshl_add_u64 v[172:173], v[170:171], 0, s[14:15]
	s_nop 0
	v_cndmask_b32_e32 v153, v215, v153, vcc
	v_cmp_neq_f32_e32 vcc, -1.0, v186
	s_nop 1
	v_cndmask_b32_e32 v153, v216, v153, vcc
	v_cmp_lt_f32_e64 vcc, |v186|, s47
	s_nop 1
	v_cndmask_b32_e32 v153, v153, v186, vcc
	v_sub_f32_e32 v153, v187, v153
	flat_store_dword v[172:173], v153 offset:8
; template <int MODE, bool XBF>
; __device__ __forceinline__ void rmsnorm_rows(const void* x, const float* gain, bf16_t* H, int gw, int NGW, int lane, const LAS float* WF, const float* fbias, float* LF) {
;     ...
;                         for (int r = 0; r < RB; ++r) {
;                             const float hv = v[r][j][e][c];
;                             dt[r][0] += hv * w0[0]; dt[r][1] += hv * w0[1]; dt[r][2] += hv * w0[2]; dt[r][3] += hv * w0[3];
;                             dt[r][4] += hv * w1[0]; dt[r][5] += hv * w1[1]; dt[r][6] += hv * w1[2]; dt[r][7] += hv * w1[3];
;                         }
;                     }
;             const bool hi32 = (lane & 32) != 0, hi16 = (lane & 16) != 0, hi8 = (lane & 8) != 0;
;             const int hsel = (hi32 ? 4 : 0) + (hi16 ? 2 : 0) + (hi8 ? 1 : 0);
;             const float fb = fbias[hsel];
; #pragma unroll
;             for (int r = 0; r < RB; ++r) {
;                 float d4[4], d2[2], d1;
; #pragma unroll
;                 for (int k = 0; k < 4; ++k) { const float send = hi32 ? dt[r][k] : dt[r][k + 4], keep = hi32 ? dt[r][k + 4] : dt[r][k]; d4[k] = keep + __shfl_xor(send, 32); }
; #pragma unroll
;                 for (int k = 0; k < 2; ++k) { const float send = hi16 ? d4[k] : d4[k + 2], keep = hi16 ? d4[k + 2] : d4[k]; d2[k] = keep + __shfl_xor(send, 16); }
;                 { const float send = hi8 ? d2[0] : d2[1], keep = hi8 ? d2[1] : d2[0]; d1 = keep + __shfl_xor(send, 8); }
;                 d1 += __shfl_xor(d1, 4); d1 += __shfl_xor(d1, 2); d1 += __shfl_xor(d1, 1);
.LBB0_56:
	s_or_b64 exec, exec, s[10:11]
	v_fma_f32 v24, v24, v168, 0
	v_fma_f32 v28, v28, v168, 0
	v_fmac_f32_e32 v24, v20, v169
	v_fmac_f32_e32 v28, v16, v169
	v_fmac_f32_e32 v24, v36, v166
	v_fmac_f32_e32 v28, v166, v32
	v_fmac_f32_e32 v24, v167, v44
	v_fmac_f32_e32 v28, v167, v40
	v_fmac_f32_e32 v24, v164, v52
	v_fmac_f32_e32 v28, v164, v48
	v_fmac_f32_e32 v24, v165, v60
	v_fmac_f32_e32 v28, v165, v56
	v_fma_f32 v25, v25, v168, 0
	v_fma_f32 v29, v29, v168, 0
	v_fmac_f32_e32 v24, v162, v68
	v_fmac_f32_e32 v28, v162, v64
	v_fma_f32 v26, v26, v168, 0
	v_fma_f32 v30, v30, v168, 0
	v_fmac_f32_e32 v25, v21, v169
	v_fmac_f32_e32 v29, v17, v169
	v_fmac_f32_e32 v24, v163, v72
	v_fmac_f32_e32 v28, v163, v76
	v_fma_f32 v27, v27, v168, 0
	v_fma_f32 v31, v31, v168, 0
	v_fmac_f32_e32 v26, v22, v169
	v_fmac_f32_e32 v30, v18, v169
	v_fmac_f32_e32 v25, v37, v166
	v_fmac_f32_e32 v29, v166, v33
	v_fmac_f32_e32 v24, v160, v80
	v_fmac_f32_e32 v28, v160, v84
	v_fmac_f32_e32 v27, v23, v169
	v_fmac_f32_e32 v31, v19, v169
	v_fmac_f32_e32 v26, v38, v166
	v_fmac_f32_e32 v30, v166, v34
	v_fmac_f32_e32 v25, v167, v45
	v_fmac_f32_e32 v29, v167, v41
	v_fmac_f32_e32 v24, v161, v88
	v_fmac_f32_e32 v28, v161, v92
	v_fmac_f32_e32 v27, v39, v166
	v_fmac_f32_e32 v31, v166, v35
	v_fmac_f32_e32 v26, v167, v46
	v_fmac_f32_e32 v30, v167, v42
	v_fmac_f32_e32 v25, v164, v53
	v_fmac_f32_e32 v29, v164, v49
	v_fmac_f32_e32 v24, v158, v96
	v_fmac_f32_e32 v28, v158, v100
	v_fmac_f32_e32 v27, v167, v47
	v_fmac_f32_e32 v31, v167, v43
	v_fmac_f32_e32 v26, v164, v54
	v_fmac_f32_e32 v30, v164, v50
	v_fmac_f32_e32 v25, v165, v61
	v_fmac_f32_e32 v29, v165, v57
	v_fmac_f32_e32 v24, v159, v104
	v_fmac_f32_e32 v28, v159, v108
	v_fmac_f32_e32 v27, v164, v55
	v_fmac_f32_e32 v31, v164, v51
	v_fmac_f32_e32 v26, v165, v62
	v_fmac_f32_e32 v30, v165, v58
	v_fmac_f32_e32 v25, v162, v69
	v_fmac_f32_e32 v29, v162, v65
	v_fmac_f32_e32 v24, v156, v112
	v_fmac_f32_e32 v28, v156, v116
	v_fmac_f32_e32 v27, v165, v63
	v_fmac_f32_e32 v31, v165, v59
	v_fmac_f32_e32 v26, v162, v70
	v_fmac_f32_e32 v30, v162, v66
	v_fmac_f32_e32 v25, v163, v73
	v_fmac_f32_e32 v29, v163, v77
	v_fmac_f32_e32 v24, v157, v120
	v_fmac_f32_e32 v28, v157, v140
	v_fmac_f32_e32 v27, v162, v71
	v_fmac_f32_e32 v31, v162, v67
	v_fmac_f32_e32 v26, v163, v74
	v_fmac_f32_e32 v30, v163, v78
	v_fmac_f32_e32 v25, v160, v81
	v_fmac_f32_e32 v29, v160, v85
	v_fmac_f32_e32 v24, v154, v136
	v_fmac_f32_e32 v28, v154, v132
	v_fmac_f32_e32 v27, v163, v75
	v_fmac_f32_e32 v31, v163, v79
	v_fmac_f32_e32 v26, v160, v82
	v_fmac_f32_e32 v30, v160, v86
	v_fmac_f32_e32 v25, v161, v89
	v_fmac_f32_e32 v29, v161, v93
	v_fmac_f32_e32 v24, v155, v128
	v_fmac_f32_e32 v28, v155, v124
	v_fmac_f32_e32 v27, v160, v83
	v_fmac_f32_e32 v31, v160, v87
	v_fmac_f32_e32 v26, v161, v90
	v_fmac_f32_e32 v30, v161, v94
	v_fmac_f32_e32 v25, v158, v97
	v_fmac_f32_e32 v29, v158, v101
	v_cndmask_b32_e64 v16, v24, v28, s[2:3]
	v_fmac_f32_e32 v27, v161, v91
	v_fmac_f32_e32 v31, v161, v95
	v_fmac_f32_e32 v26, v158, v98
	v_fmac_f32_e32 v30, v158, v102
	v_fmac_f32_e32 v25, v159, v105
	v_fmac_f32_e32 v29, v159, v109
	ds_bpermute_b32 v16, v206, v16
	v_fmac_f32_e32 v27, v158, v99
	v_fmac_f32_e32 v31, v158, v103
	v_fmac_f32_e32 v26, v159, v106
	v_fmac_f32_e32 v30, v159, v110
	v_fmac_f32_e32 v25, v156, v113
	v_fmac_f32_e32 v29, v156, v117
	v_fmac_f32_e32 v27, v159, v107
	v_fmac_f32_e32 v31, v159, v111
	v_fmac_f32_e32 v26, v156, v114
	v_fmac_f32_e32 v30, v156, v118
	v_fmac_f32_e32 v25, v157, v121
	v_fmac_f32_e32 v29, v157, v141
	v_fmac_f32_e32 v27, v156, v115
	v_fmac_f32_e32 v31, v156, v119
	v_fmac_f32_e32 v26, v157, v122
	v_fmac_f32_e32 v30, v157, v142
	v_fmac_f32_e32 v25, v154, v137
	v_fmac_f32_e32 v29, v154, v133
	v_fmac_f32_e32 v27, v157, v123
	v_fmac_f32_e32 v31, v157, v143
	v_fmac_f32_e32 v26, v154, v138
	v_fmac_f32_e32 v30, v154, v134
	v_fmac_f32_e32 v25, v155, v129
	v_fmac_f32_e32 v29, v155, v125
	v_cndmask_b32_e64 v17, v28, v24, s[2:3]
	v_fmac_f32_e32 v27, v154, v139
	v_fmac_f32_e32 v31, v154, v135
	v_fmac_f32_e32 v26, v155, v130
	v_fmac_f32_e32 v30, v155, v126
	s_waitcnt lgkmcnt(0)
	v_add_f32_e32 v16, v17, v16
	v_cndmask_b32_e64 v17, v25, v29, s[2:3]
	v_fmac_f32_e32 v27, v155, v131
	v_fmac_f32_e32 v31, v155, v127
	ds_bpermute_b32 v17, v206, v17
	v_cndmask_b32_e64 v19, v26, v30, s[2:3]
	ds_bpermute_b32 v19, v206, v19
	v_cndmask_b32_e64 v20, v27, v31, s[2:3]
	ds_bpermute_b32 v20, v206, v20
	v_cndmask_b32_e64 v18, v29, v25, s[2:3]
	s_waitcnt lgkmcnt(0)
	v_add_f32_e32 v17, v18, v17
	v_cndmask_b32_e64 v18, v30, v26, s[2:3]
	v_add_f32_e32 v18, v18, v19
	v_cndmask_b32_e64 v19, v31, v27, s[2:3]
	v_add_f32_e32 v19, v19, v20
	v_cndmask_b32_e64 v20, v16, v18, s[4:5]
	v_cndmask_b32_e64 v21, v17, v19, s[4:5]
	ds_bpermute_b32 v20, v207, v20
	ds_bpermute_b32 v21, v207, v21
	v_cndmask_b32_e64 v16, v18, v16, s[4:5]
	v_cndmask_b32_e64 v17, v19, v17, s[4:5]
	s_waitcnt lgkmcnt(0)
	v_add_f32_e32 v16, v16, v20
	v_add_f32_e32 v17, v17, v21
	v_cndmask_b32_e64 v18, v16, v17, s[6:7]
	ds_bpermute_b32 v18, v208, v18
	v_cndmask_b32_e64 v16, v17, v16, s[6:7]
	s_waitcnt lgkmcnt(0)
	v_add_f32_e32 v16, v16, v18
	ds_bpermute_b32 v17, v209, v16
	s_waitcnt lgkmcnt(0)
	v_add_f32_e32 v16, v16, v17
	ds_bpermute_b32 v17, v210, v16
	s_waitcnt lgkmcnt(0)
	v_add_f32_e32 v16, v16, v17
	ds_bpermute_b32 v17, v211, v16
	s_and_saveexec_b64 s[10:11], s[8:9]
	s_cbranch_execz .LBB0_49
; template <int MODE, bool XBF>
; __device__ __forceinline__ void rmsnorm_rows(const void* x, const float* gain, bf16_t* H, int gw, int NGW, int lane, const LAS float* WF, const float* fbias, float* LF) {
;     ...
;                 if ((lane & 7) == 0) {
;                     const int row = row0 + r;
;                     const float z = d1 + fb;
;                     LF[((size_t)(row >> 12) * 8 + hsel) * S + (row & 4095)] = fminf(z, 0.f) - log1pf(__expf(-fabsf(z)));
;                 }
	s_waitcnt lgkmcnt(0)
	v_add_f32_e32 v16, v16, v17
	s_waitcnt vmcnt(0)
	v_add_f32_e32 v16, v217, v16
	v_mul_f32_e64 v17, |v16|, s43
	v_exp_f32_e32 v30, v17
	v_min_f32_e32 v31, 0, v16
	s_lshl_b32 s14, s48, 2
	v_add_f32_e32 v18, 1.0, v30
	v_add_f32_e32 v16, -1.0, v18
	v_sub_f32_e32 v17, v16, v18
	v_sub_f32_e32 v16, v30, v16
	v_add_f32_e32 v17, 1.0, v17
	v_frexp_mant_f32_e32 v19, v18
	v_add_f32_e32 v20, v16, v17
	v_cvt_f64_f32_e32 v[16:17], v18
	v_frexp_exp_i32_f64_e32 v16, v[16:17]
	v_cmp_gt_f32_e32 vcc, s44, v19
	s_nop 1
	v_subbrev_co_u32_e32 v24, vcc, 0, v16, vcc
	v_sub_u32_e32 v16, 0, v24
	v_ldexp_f32 v17, v18, v16
	v_ldexp_f32 v16, v20, v16
	v_add_f32_e32 v18, -1.0, v17
	v_add_f32_e32 v20, 1.0, v17
	v_add_f32_e32 v19, 1.0, v18
	v_add_f32_e32 v21, -1.0, v20
	v_sub_f32_e32 v19, v17, v19
	v_sub_f32_e32 v17, v17, v21
	v_add_f32_e32 v19, v16, v19
	v_add_f32_e32 v16, v16, v17
	v_add_f32_e32 v25, v20, v16
	v_rcp_f32_e32 v27, v25
	v_sub_f32_e32 v17, v25, v20
	v_sub_f32_e32 v26, v16, v17
	v_add_f32_e32 v17, v18, v19
	v_mul_f32_e32 v29, v17, v27
	v_sub_f32_e32 v16, v17, v18
	v_mul_f32_e32 v18, v25, v29
	v_fma_f32 v20, v29, v25, -v18
	v_fmac_f32_e32 v20, v29, v26
	v_sub_f32_e32 v28, v19, v16
	v_add_f32_e32 v16, v18, v20
	v_sub_f32_e32 v19, v17, v16
	v_add_f32_e64 v22, v16, -v18
	v_add_f32_e64 v23, v17, -v19
	v_mov_b32_e32 v21, v16
	v_add_f32_e64 v16, v22, -v20
	v_add_f32_e64 v17, v23, -v21
	v_cmp_neq_f32_e32 vcc, s46, v30
	v_add_f32_e32 v17, v28, v17
	v_add_f32_e32 v16, v16, v17
	v_add_f32_e32 v17, v19, v16
	v_mul_f32_e32 v28, v27, v17
	v_mul_f32_e32 v18, v25, v28
	v_fma_f32 v20, v28, v25, -v18
	v_fmac_f32_e32 v20, v28, v26
	v_sub_f32_e32 v19, v19, v17
	v_add_f32_e32 v25, v16, v19
	v_add_f32_e32 v16, v18, v20
	v_sub_f32_e32 v19, v17, v16
	v_add_f32_e64 v22, v16, -v18
	v_add_f32_e64 v23, v17, -v19
	v_mov_b32_e32 v21, v16
	v_add_f32_e64 v16, v22, -v20
	v_add_f32_e64 v17, v23, -v21
	s_nop 0
	v_add_f32_e32 v17, v25, v17
	v_add_f32_e32 v16, v16, v17
	v_add_f32_e32 v17, v29, v28
	v_add_f32_e32 v16, v19, v16
	v_sub_f32_e32 v18, v17, v29
	v_mul_f32_e32 v16, v27, v16
	v_sub_f32_e32 v18, v28, v18
	v_add_f32_e32 v18, v18, v16
	v_add_f32_e32 v20, v17, v18
	v_mul_f32_e32 v21, v20, v20
	v_fmamk_f32 v16, v21, 0x3e9b6dac, v213
	v_fmaak_f32 v153, v21, v16, 0x3f2aaada
	v_cvt_f32_i32_e32 v16, v24
	v_sub_f32_e32 v17, v20, v17
	v_sub_f32_e32 v17, v18, v17
	v_ldexp_f32 v22, v17, 1
	v_mul_f32_e32 v17, v20, v21
	v_ldexp_f32 v19, v20, 1
	v_mul_f32_e32 v20, v16, v152
	v_mul_f32_e32 v21, v17, v153
	s_nop 0
	v_fma_f32 v18, v16, s45, -v20
	v_fmac_f32_e32 v18, 0xb102e308, v16
	v_add_f32_e32 v16, v20, v18
	v_add_f32_e32 v17, v21, v19
	s_nop 0
	v_sub_f32_e32 v19, v17, v19
	v_sub_f32_e32 v19, v21, v19
	v_add_f32_e32 v23, v22, v19
	v_mov_b32_e32 v22, v20
	v_add_f32_e64 v20, v16, -v20
	v_add_f32_e64 v21, v17, -v21
	v_add_f32_e32 v24, v16, v22
	v_add_f32_e32 v25, v17, v23
	v_mov_b32_e32 v19, v16
	v_mov_b32_e32 v21, v25
	v_add_f32_e64 v26, v18, -v20
	v_add_f32_e64 v27, v19, -v21
	v_add_f32_e32 v18, v18, v20
	v_add_f32_e32 v19, v19, v21
	v_mov_b32_e32 v22, v23
	v_add_f32_e64 v20, v19, -v16
	v_add_f32_e64 v21, v18, -v17
	v_add_f32_e64 v28, v24, -v20
	v_add_f32_e64 v29, v25, -v20
	v_mov_b32_e32 v24, v25
	v_mov_b32_e32 v25, v19
	v_pk_mov_b32 v[20:21], v[16:17], v[20:21] op_sel:[1,0]
	v_mov_b32_e32 v23, v16
	v_add_f32_e64 v20, v24, -v20
	v_add_f32_e64 v21, v25, -v21
	v_mov_b32_e32 v28, v26
	v_add_f32_e64 v16, v22, -v20
	v_add_f32_e64 v17, v23, -v21
	v_mov_b32_e32 v27, v19
	v_add_f32_e32 v20, v28, v16
	v_add_f32_e32 v21, v29, v17
	s_nop 0
	v_add_f32_e32 v22, v20, v21
	v_add_f32_e32 v23, v21, v20
	s_nop 0
	v_pk_add_f32 v[18:19], v[18:19], v[22:23] op_sel:[1,0] op_sel_hi:[0,1]
	v_mov_b32_e32 v21, v18
	v_add_f32_e64 v24, v20, -v26
	v_add_f32_e64 v25, v21, -v27
	v_mov_b32_e32 v17, v22
	v_sub_f32_e32 v19, v20, v24
	v_add_f32_e64 v16, v16, -v24
	v_add_f32_e64 v17, v17, -v25
	v_sub_f32_e32 v19, v26, v19
	v_add_f32_e32 v16, v16, v19
	v_add_f32_e32 v16, v16, v17
	v_add_f32_e32 v16, v18, v16
	v_cndmask_b32_e32 v16, v214, v16, vcc
	v_cmp_ngt_f32_e32 vcc, -1.0, v30
	s_nop 1
	v_cndmask_b32_e32 v16, v215, v16, vcc
	v_cmp_neq_f32_e32 vcc, -1.0, v30
	s_nop 1
	v_cndmask_b32_e32 v16, v216, v16, vcc
	v_cmp_lt_f32_e64 vcc, |v30|, s47
	s_nop 1
	v_cndmask_b32_e32 v16, v16, v30, vcc
	v_sub_f32_e32 v18, v31, v16
	v_lshl_add_u64 v[16:17], v[170:171], 0, s[14:15]
	flat_store_dword v[16:17], v18 offset:12
	s_branch .LBB0_49

; #define GAS __attribute__((address_space(1)))
;     __device__ __forceinline__ void operator()(const Acc& acc, const Unit& u, int wr, int wc, int fr, int fq) const {
;     ...
;             const float* gn = kind == 0 ? qg : kg; const float sc = kind == 0 ? QSCALE : 1.f;
;             f32x4 gv[2][2];
; #pragma unroll
;             for (int bj = 0; bj < 2; ++bj)
; #pragma unroll
;                 for (int n = 0; n < 2; ++n) gv[bj][n] = *(const GAS f32x4*)(gn + 32 * bj + 8 * fq + 4 * n);
;             const int colb = kind * 512 + half * 256 + wc * 64 + 8 * fq;
; #pragma unroll
;             for (int ai = 0; ai < 2; ++ai)
; #pragma unroll
;                 for (int m = 0; m < 4; ++m) {
;                     float ss = 0.f;
; #pragma unroll
;                     for (int bj = 0; bj < 2; ++bj)
; #pragma unroll
;                         for (int n = 0; n < 2; ++n) { const f32x4 x = acc[ai][bj][m][n]; ss += (x[0] * x[0] + x[1] * x[1]) + (x[2] * x[2] + x[3] * x[3]); }
;                     ss += __shfl_xor(ss, 16); ss += __shfl_xor(ss, 32);
;                     const float rs = rsqrtf(ss * (1.f / 64.f) + 1e-6f) * sc;
;                     bf16_t* rowp = P + (size_t)(row0 + ai * HALF + m * 16) * NPROJ + colb;
; #pragma unroll
;                     for (int bj = 0; bj < 2; ++bj) *(GAS u32x4*)(rowp + 32 * bj) = pack8(acc[ai][bj][m][0] * rs * gv[bj][0], acc[ai][bj][m][1] * rs * gv[bj][1]);
.LBB0_191:
	s_cmp_lt_u32 s30, 2
	s_cselect_b64 vcc, -1, 0
	s_and_b64 s[4:5], vcc, exec
	s_cselect_b32 s4, s23, s45
	s_cselect_b32 s5, s19, s44
	v_lshlrev_b32_e32 v156, 3, v140
	v_mov_b32_e32 v128, s5
	v_mov_b32_e32 v129, s4
	v_ashrrev_i32_e32 v157, 31, v156
	v_lshl_add_u64 v[132:133], v[156:157], 2, v[128:129]
	global_load_dwordx4 v[136:139], v[132:133], off offset:16
	global_load_dwordx4 v[140:143], v[132:133], off
	global_load_dwordx4 v[128:131], v[132:133], off offset:144
	s_nop 0
	global_load_dwordx4 v[132:135], v[132:133], off offset:128
	v_mul_f32_e32 v158, v126, v126
	v_mul_f32_e32 v159, v127, v127
	v_mul_f32_e32 v160, v124, v124
	v_mul_f32_e32 v161, v125, v125
	v_mul_f32_e32 v157, v112, v112
	v_pk_mov_b32 v[174:175], v[160:161], v[158:159] op_sel:[1,0]
	v_mov_b32_e32 v161, v159
	v_add_f32_e32 v158, v174, v160
	v_add_f32_e32 v159, v175, v161
	v_mul_f32_e32 v160, v122, v122
	v_mul_f32_e32 v161, v123, v123
	v_mul_f32_e32 v174, v120, v120
	v_mul_f32_e32 v175, v121, v121
	v_mul_f32_e32 v173, v113, v113
	v_pk_mov_b32 v[176:177], v[174:175], v[160:161] op_sel:[1,0]
	v_mov_b32_e32 v175, v161
	v_add_f32_e32 v160, v176, v174
	v_add_f32_e32 v161, v177, v175
	v_add_f32_e32 v158, v158, v159
	v_mov_b32_e32 v159, v158
	v_add_f32_e32 v160, v160, v161
	v_mov_b32_e32 v161, v160
	v_mov_b32_e32 v159, v157
	v_mov_b32_e32 v161, v173
	v_add_f32_e32 v158, v158, v160
	v_add_f32_e32 v159, v159, v161
	v_mul_f32_e32 v160, v117, v117
	v_mul_f32_e32 v174, v114, v114
	v_fma_f32 v161, v117, v117, v160
	v_fma_f32 v160, v116, v116, v160
	v_mul_f32_e32 v176, v115, v115
	v_mov_b32_e32 v161, v174
	v_mul_f32_e32 v174, v119, v119
	v_fma_f32 v175, v119, v119, v174
	v_fma_f32 v174, v118, v118, v174
	v_mul_f32_e32 v157, v96, v96
	v_mov_b32_e32 v175, v176
	v_add_f32_e32 v160, v160, v174
	v_add_f32_e32 v161, v161, v175
	v_mul_f32_e32 v174, v108, v108
	v_mul_f32_e32 v175, v109, v109
	v_add_f32_e32 v158, v158, v160
	v_add_f32_e32 v159, v159, v161
	v_mul_f32_e32 v160, v110, v110
	v_mul_f32_e32 v161, v111, v111
	v_mul_f32_e32 v173, v97, v97
	v_pk_mov_b32 v[176:177], v[174:175], v[160:161] op_sel:[1,0]
	v_mov_b32_e32 v175, v161
	v_add_f32_e32 v160, v176, v174
	v_add_f32_e32 v161, v177, v175
	v_mul_f32_e32 v174, v106, v106
	v_mul_f32_e32 v175, v107, v107
	v_mul_f32_e32 v176, v104, v104
	v_mul_f32_e32 v177, v105, v105
	v_add_f32_e32 v160, v160, v161
	v_mov_b32_e32 v161, v160
	v_pk_mov_b32 v[178:179], v[176:177], v[174:175] op_sel:[1,0]
	v_mov_b32_e32 v177, v175
	v_add_f32_e32 v174, v178, v176
	v_add_f32_e32 v175, v179, v177
	v_mov_b32_e32 v161, v157
	v_add_f32_e32 v174, v174, v175
	v_mov_b32_e32 v175, v174
	v_mul_f32_e32 v176, v98, v98
	v_mov_b32_e32 v175, v173
	v_add_f32_e32 v160, v160, v174
	v_add_f32_e32 v161, v161, v175
	v_mul_f32_e32 v174, v101, v101
	v_fma_f32 v175, v101, v101, v174
	v_fma_f32 v174, v100, v100, v174
	v_mul_f32_e32 v178, v99, v99
	v_mov_b32_e32 v175, v176
	v_mul_f32_e32 v176, v103, v103
	v_fma_f32 v177, v103, v103, v176
	v_fma_f32 v176, v102, v102, v176
	v_cndmask_b32_e32 v172, 1.0, v170, vcc
	v_mov_b32_e32 v177, v178
	v_add_f32_e32 v174, v174, v176
	v_add_f32_e32 v175, v175, v177
	s_lshl_b32 s5, s25, 8
	v_add_f32_e32 v160, v160, v174
	v_add_f32_e32 v161, v161, v175
	v_mov_b32_e32 v175, v158
	v_mov_b32_e32 v174, v160
	v_mov_b32_e32 v158, v161
	v_add_f32_e32 v158, v174, v158
	v_add_f32_e32 v159, v175, v159
	ds_bpermute_b32 v161, v164, v159
	ds_bpermute_b32 v160, v164, v158
	s_lshl_b32 s4, s21, 9
	s_or_b32 s5, s5, s58
	s_or_b32 s4, s5, s4
	v_add_u32_e32 v174, s4, v156
	s_waitcnt lgkmcnt(0)
	v_add_f32_e32 v158, v158, v160
	v_add_f32_e32 v159, v159, v161
	ds_bpermute_b32 v161, v165, v159
	ds_bpermute_b32 v160, v165, v158
	v_ashrrev_i32_e32 v175, 31, v174
	v_mov_b64_e32 v[156:157], s[12:13]
	v_mad_i64_i32 v[178:179], s[4:5], v171, s65, v[156:157]
	s_waitcnt lgkmcnt(0)
	v_add_f32_e32 v158, v158, v160
	v_add_f32_e32 v159, v159, v161
	v_mov_b64_e32 v[160:161], s[18:19]
	v_fma_f32 v176, v158, s16, v160
	v_fma_f32 v177, v159, s16, v160
	s_nop 0
	v_mul_f32_e32 v158, 0x4b800000, v177
	v_cmp_gt_f32_e32 vcc, s66, v177
	s_nop 1
	v_cndmask_b32_e32 v158, v177, v158, vcc
	v_rsq_f32_e32 v173, v158
	v_lshlrev_b64 v[158:159], 1, v[174:175]
	v_lshl_add_u64 v[174:175], v[178:179], 0, v[158:159]
	v_mul_f32_e32 v177, 0x45800000, v173
	v_cndmask_b32_e32 v173, v173, v177, vcc
	v_mul_f32_e32 v178, v172, v173
	v_mul_f32_e32 v124, v124, v178
	v_mul_f32_e32 v125, v125, v178
	v_mul_f32_e32 v126, v126, v178
	v_mul_f32_e32 v127, v127, v178
	v_mul_f32_e32 v120, v120, v178
	v_mul_f32_e32 v121, v121, v178
	v_mul_f32_e32 v122, v122, v178
	v_mul_f32_e32 v123, v123, v178
	s_waitcnt vmcnt(0)
; #define GAS __attribute__((address_space(1)))
;     __device__ __forceinline__ void operator()(const Acc& acc, const Unit& u, int wr, int wc, int fr, int fq) const {
;     ...
;             for (int ai = 0; ai < 2; ++ai)
; #pragma unroll
;                 for (int m = 0; m < 4; ++m) {
;                     float ss = 0.f;
; #pragma unroll
;                     for (int bj = 0; bj < 2; ++bj)
; #pragma unroll
;                         for (int n = 0; n < 2; ++n) { const f32x4 x = acc[ai][bj][m][n]; ss += (x[0] * x[0] + x[1] * x[1]) + (x[2] * x[2] + x[3] * x[3]); }
;                     ss += __shfl_xor(ss, 16); ss += __shfl_xor(ss, 32);
;                     const float rs = rsqrtf(ss * (1.f / 64.f) + 1e-6f) * sc;
;                     bf16_t* rowp = P + (size_t)(row0 + ai * HALF + m * 16) * NPROJ + colb;
; #pragma unroll
;                     for (int bj = 0; bj < 2; ++bj) *(GAS u32x4*)(rowp + 32 * bj) = pack8(acc[ai][bj][m][0] * rs * gv[bj][0], acc[ai][bj][m][1] * rs * gv[bj][1]);
	v_mul_f32_e32 v126, v142, v126
	v_mul_f32_e32 v127, v143, v127
	v_mul_f32_e32 v124, v140, v124
	v_mul_f32_e32 v125, v141, v125
	v_mul_f32_e32 v180, v138, v122
	v_mul_f32_e32 v181, v139, v123
	v_mul_f32_e32 v122, v136, v120
	v_mul_f32_e32 v123, v137, v121
	v_mul_f32_e32 v116, v116, v178
	v_mul_f32_e32 v117, v117, v178
	v_cvt_pk_bf16_f32 v120, v124, v125
	v_cvt_pk_bf16_f32 v121, v126, v127
	v_cvt_pk_bf16_f32 v122, v122, v123
	v_cvt_pk_bf16_f32 v123, v180, v181
	v_mul_f32_e32 v116, v132, v116
	v_mul_f32_e32 v117, v133, v117
	v_mul_f32_e32 v112, v112, v178
	v_mul_f32_e32 v113, v113, v178
	v_mul_f32_e32 v114, v114, v178
	v_mul_f32_e32 v115, v115, v178
	global_store_dwordx4 v[174:175], v[120:123], off
	v_cmp_gt_f32_e32 vcc, s66, v176
	v_mul_f32_e32 v118, v118, v178
	v_mul_f32_e32 v119, v119, v178
	v_mul_f32_e32 v120, v130, v114
	v_mul_f32_e32 v121, v131, v115
	v_mul_f32_e32 v114, v128, v112
	v_mul_f32_e32 v115, v129, v113
	v_cvt_pk_bf16_f32 v112, v116, v117
	v_mul_f32_e32 v116, 0x4b800000, v176
	v_cndmask_b32_e32 v116, v176, v116, vcc
	v_rsq_f32_e32 v116, v116
	v_mul_f32_e32 v118, v134, v118
	v_mul_f32_e32 v119, v135, v119
	v_cvt_pk_bf16_f32 v114, v114, v115
	v_cvt_pk_bf16_f32 v113, v118, v119
	v_cvt_pk_bf16_f32 v115, v120, v121
	global_store_dwordx4 v[174:175], v[112:115], off offset:64
	s_nop 1
	v_mul_f32_e32 v112, 0x45800000, v116
	v_cndmask_b32_e32 v112, v116, v112, vcc
	v_mul_f32_e32 v112, v172, v112
	v_or_b32_e32 v113, 16, v171
	v_mul_f32_e32 v108, v108, v112
	v_mul_f32_e32 v109, v109, v112
	v_mul_f32_e32 v110, v110, v112
	v_mul_f32_e32 v111, v111, v112
	v_mul_f32_e32 v104, v104, v112
	v_mul_f32_e32 v105, v105, v112
	v_mul_f32_e32 v106, v106, v112
	v_mul_f32_e32 v107, v107, v112
	v_mad_i64_i32 v[114:115], s[4:5], v113, s65, v[156:157]
	v_mul_f32_e32 v110, v142, v110
	v_mul_f32_e32 v111, v143, v111
	v_mul_f32_e32 v108, v140, v108
	v_mul_f32_e32 v109, v141, v109
	v_mul_f32_e32 v116, v138, v106
	v_mul_f32_e32 v117, v139, v107
	v_mul_f32_e32 v106, v136, v104
	v_mul_f32_e32 v107, v137, v105
	v_lshl_add_u64 v[114:115], v[114:115], 0, v[158:159]
	v_cvt_pk_bf16_f32 v104, v108, v109
	v_cvt_pk_bf16_f32 v105, v110, v111
	v_cvt_pk_bf16_f32 v106, v106, v107
	v_cvt_pk_bf16_f32 v107, v116, v117
	global_store_dwordx4 v[114:115], v[104:107], off
	v_mul_f32_e32 v100, v100, v112
	v_mul_f32_e32 v101, v101, v112
	v_mul_f32_e32 v102, v102, v112
	v_mul_f32_e32 v103, v103, v112
	v_mul_f32_e32 v104, v94, v94
	v_mul_f32_e32 v105, v95, v95
	v_mul_f32_e32 v106, v92, v92
	v_mul_f32_e32 v107, v93, v93
	v_mul_f32_e32 v96, v96, v112
	v_mul_f32_e32 v97, v97, v112
	v_pk_mov_b32 v[108:109], v[106:107], v[104:105] op_sel:[1,0]
	v_mov_b32_e32 v107, v105
	v_add_f32_e32 v104, v108, v106
	v_add_f32_e32 v105, v109, v107
	v_mul_f32_e32 v106, v90, v90
	v_mul_f32_e32 v107, v91, v91
	v_mul_f32_e32 v108, v88, v88
	v_mul_f32_e32 v109, v89, v89
	v_add_f32_e32 v104, v104, v105
	v_mov_b32_e32 v105, v104
	v_pk_mov_b32 v[110:111], v[108:109], v[106:107] op_sel:[1,0]
	v_mov_b32_e32 v109, v107
	v_add_f32_e32 v106, v110, v108
	v_add_f32_e32 v107, v111, v109
	v_mul_f32_e32 v108, v76, v76
	v_mul_f32_e32 v109, v77, v77
	v_add_f32_e32 v106, v106, v107
	v_mov_b32_e32 v107, v106
	v_mov_b32_e32 v105, v108
	v_mov_b32_e32 v107, v109
	v_add_f32_e32 v104, v104, v106
	v_add_f32_e32 v105, v105, v107
	v_mul_f32_e32 v106, v85, v85
	v_mul_f32_e32 v108, v87, v87
	v_mul_f32_e32 v110, v78, v78
	v_mul_f32_e32 v111, v79, v79
	v_fma_f32 v107, v85, v85, v106
	v_fma_f32 v106, v84, v84, v106
	v_fma_f32 v109, v87, v87, v108
	v_fma_f32 v108, v86, v86, v108
	v_mov_b32_e32 v107, v110
	v_mov_b32_e32 v109, v111
	v_add_f32_e32 v106, v106, v108
	v_add_f32_e32 v107, v107, v109
	v_mul_f32_e32 v108, v80, v80
	v_mul_f32_e32 v109, v81, v81
	v_add_f32_e32 v104, v104, v106
	v_add_f32_e32 v105, v105, v107
	v_mul_f32_e32 v106, v82, v82
	v_mul_f32_e32 v107, v83, v83
	v_mul_f32_e32 v98, v98, v112
	v_mul_f32_e32 v99, v99, v112
	v_pk_mov_b32 v[110:111], v[108:109], v[106:107] op_sel:[1,0]
	v_mov_b32_e32 v109, v107
	v_add_f32_e32 v106, v110, v108
	v_add_f32_e32 v107, v111, v109
	v_mul_f32_e32 v108, v74, v74
	v_mul_f32_e32 v109, v75, v75
	v_mul_f32_e32 v110, v72, v72
	v_mul_f32_e32 v111, v73, v73
	v_add_f32_e32 v106, v106, v107
	v_mov_b32_e32 v107, v106
	v_pk_mov_b32 v[112:113], v[110:111], v[108:109] op_sel:[1,0]
	v_mov_b32_e32 v111, v109
	v_add_f32_e32 v108, v112, v110
	v_add_f32_e32 v109, v113, v111
	v_mul_f32_e32 v110, v64, v64
	v_mul_f32_e32 v111, v65, v65
	v_add_f32_e32 v108, v108, v109
	v_mov_b32_e32 v109, v108
	v_mov_b32_e32 v107, v110
	v_mov_b32_e32 v109, v111
	v_add_f32_e32 v106, v106, v108
	v_add_f32_e32 v107, v107, v109
	v_mul_f32_e32 v108, v69, v69
	v_mul_f32_e32 v110, v71, v71
	v_mul_f32_e32 v112, v66, v66
	v_mul_f32_e32 v113, v67, v67
	v_fma_f32 v109, v69, v69, v108
	v_fma_f32 v108, v68, v68, v108
	v_fma_f32 v111, v71, v71, v110
	v_fma_f32 v110, v70, v70, v110
	v_mov_b32_e32 v109, v112
	v_mov_b32_e32 v111, v113
	v_add_f32_e32 v108, v108, v110
	v_add_f32_e32 v109, v109, v111
	v_mul_f32_e32 v100, v132, v100
	v_mul_f32_e32 v101, v133, v101
	v_add_f32_e32 v106, v106, v108
	v_add_f32_e32 v107, v107, v109
	v_mov_b32_e32 v109, v104
	v_mov_b32_e32 v108, v106
	v_mov_b32_e32 v104, v107
	v_add_f32_e32 v104, v108, v104
	v_add_f32_e32 v105, v109, v105
	ds_bpermute_b32 v107, v164, v105
	ds_bpermute_b32 v106, v164, v104
	v_mul_f32_e32 v102, v134, v102
	v_mul_f32_e32 v103, v135, v103
	v_mul_f32_e32 v108, v130, v98
	v_mul_f32_e32 v109, v131, v99
	v_mul_f32_e32 v98, v128, v96
	v_mul_f32_e32 v99, v129, v97
	v_cvt_pk_bf16_f32 v96, v100, v101
	s_waitcnt lgkmcnt(0)
; #define GAS __attribute__((address_space(1)))
;     __device__ __forceinline__ void operator()(const Acc& acc, const Unit& u, int wr, int wc, int fr, int fq) const {
;     ...
;             for (int ai = 0; ai < 2; ++ai)
; #pragma unroll
;                 for (int m = 0; m < 4; ++m) {
;                     float ss = 0.f;
; #pragma unroll
;                     for (int bj = 0; bj < 2; ++bj)
; #pragma unroll
;                         for (int n = 0; n < 2; ++n) { const f32x4 x = acc[ai][bj][m][n]; ss += (x[0] * x[0] + x[1] * x[1]) + (x[2] * x[2] + x[3] * x[3]); }
;                     ss += __shfl_xor(ss, 16); ss += __shfl_xor(ss, 32);
;                     const float rs = rsqrtf(ss * (1.f / 64.f) + 1e-6f) * sc;
;                     bf16_t* rowp = P + (size_t)(row0 + ai * HALF + m * 16) * NPROJ + colb;
; #pragma unroll
;                     for (int bj = 0; bj < 2; ++bj) *(GAS u32x4*)(rowp + 32 * bj) = pack8(acc[ai][bj][m][0] * rs * gv[bj][0], acc[ai][bj][m][1] * rs * gv[bj][1]);
	v_add_f32_e32 v100, v104, v106
	v_add_f32_e32 v101, v105, v107
	v_cvt_pk_bf16_f32 v97, v102, v103
	ds_bpermute_b32 v103, v165, v101
	ds_bpermute_b32 v102, v165, v100
	v_cvt_pk_bf16_f32 v98, v98, v99
	v_cvt_pk_bf16_f32 v99, v108, v109
	global_store_dwordx4 v[114:115], v[96:99], off offset:64
	s_waitcnt lgkmcnt(0)
	s_nop 0
	v_add_f32_e32 v96, v100, v102
	v_add_f32_e32 v97, v101, v103
	v_or_b32_e32 v98, 32, v171
	v_fma_f32 v96, v96, s16, v160
	v_fma_f32 v97, v97, s16, v160
	s_nop 0
	v_mul_f32_e32 v99, 0x4b800000, v97
	v_cmp_gt_f32_e32 vcc, s66, v97
	s_nop 1
	v_cndmask_b32_e32 v97, v97, v99, vcc
	v_rsq_f32_e32 v97, v97
	v_mad_i64_i32 v[98:99], s[4:5], v98, s65, v[156:157]
	v_lshl_add_u64 v[98:99], v[98:99], 0, v[158:159]
	v_mul_f32_e32 v100, 0x45800000, v97
	v_cndmask_b32_e32 v97, v97, v100, vcc
	v_mul_f32_e32 v100, v172, v97
	v_mul_f32_e32 v92, v92, v100
	v_mul_f32_e32 v93, v93, v100
	v_mul_f32_e32 v94, v94, v100
	v_mul_f32_e32 v95, v95, v100
	v_mul_f32_e32 v88, v88, v100
	v_mul_f32_e32 v89, v89, v100
	v_mul_f32_e32 v90, v90, v100
	v_mul_f32_e32 v91, v91, v100
	v_mul_f32_e32 v94, v142, v94
	v_mul_f32_e32 v95, v143, v95
	v_mul_f32_e32 v92, v140, v92
	v_mul_f32_e32 v93, v141, v93
	v_mul_f32_e32 v102, v138, v90
	v_mul_f32_e32 v103, v139, v91
	v_mul_f32_e32 v90, v136, v88
	v_mul_f32_e32 v91, v137, v89
	v_mul_f32_e32 v84, v84, v100
	v_mul_f32_e32 v85, v85, v100
	v_cvt_pk_bf16_f32 v88, v92, v93
	v_cvt_pk_bf16_f32 v89, v94, v95
	v_cvt_pk_bf16_f32 v90, v90, v91
	v_cvt_pk_bf16_f32 v91, v102, v103
	v_mul_f32_e32 v84, v132, v84
	v_mul_f32_e32 v85, v133, v85
	v_mul_f32_e32 v76, v76, v100
	v_mul_f32_e32 v77, v77, v100
	v_mul_f32_e32 v78, v78, v100
	v_mul_f32_e32 v79, v79, v100
	global_store_dwordx4 v[98:99], v[88:91], off
	v_cmp_gt_f32_e32 vcc, s66, v96
	v_mul_f32_e32 v86, v86, v100
	v_mul_f32_e32 v87, v87, v100
	v_mul_f32_e32 v88, v130, v78
	v_mul_f32_e32 v89, v131, v79
	v_mul_f32_e32 v78, v128, v76
	v_mul_f32_e32 v79, v129, v77
	v_cvt_pk_bf16_f32 v76, v84, v85
	v_mul_f32_e32 v84, 0x4b800000, v96
	v_cndmask_b32_e32 v84, v96, v84, vcc
	v_rsq_f32_e32 v84, v84
	v_mul_f32_e32 v86, v134, v86
	v_mul_f32_e32 v87, v135, v87
	v_cvt_pk_bf16_f32 v78, v78, v79
	v_cvt_pk_bf16_f32 v77, v86, v87
	v_cvt_pk_bf16_f32 v79, v88, v89
	global_store_dwordx4 v[98:99], v[76:79], off offset:64
	s_nop 1
	v_mul_f32_e32 v76, 0x45800000, v84
	v_cndmask_b32_e32 v76, v84, v76, vcc
	v_mul_f32_e32 v76, v172, v76
	v_or_b32_e32 v77, 48, v171
	v_mul_f32_e32 v80, v80, v76
	v_mul_f32_e32 v81, v81, v76
	v_mul_f32_e32 v82, v82, v76
	v_mul_f32_e32 v83, v83, v76
	v_mul_f32_e32 v72, v72, v76
	v_mul_f32_e32 v73, v73, v76
	v_mul_f32_e32 v74, v74, v76
	v_mul_f32_e32 v75, v75, v76
	v_mad_i64_i32 v[78:79], s[4:5], v77, s65, v[156:157]
	v_mul_f32_e32 v82, v142, v82
	v_mul_f32_e32 v83, v143, v83
	v_mul_f32_e32 v80, v140, v80
	v_mul_f32_e32 v81, v141, v81
	v_mul_f32_e32 v84, v138, v74
	v_mul_f32_e32 v85, v139, v75
	v_mul_f32_e32 v74, v136, v72
	v_mul_f32_e32 v75, v137, v73
	v_lshl_add_u64 v[78:79], v[78:79], 0, v[158:159]
	v_cvt_pk_bf16_f32 v72, v80, v81
	v_cvt_pk_bf16_f32 v73, v82, v83
	v_cvt_pk_bf16_f32 v74, v74, v75
	v_cvt_pk_bf16_f32 v75, v84, v85
	global_store_dwordx4 v[78:79], v[72:75], off
	v_mul_f32_e32 v68, v68, v76
	v_mul_f32_e32 v69, v69, v76
	v_mul_f32_e32 v70, v70, v76
	v_mul_f32_e32 v71, v71, v76
	v_mul_f32_e32 v72, v62, v62
	v_mul_f32_e32 v73, v63, v63
	v_mul_f32_e32 v74, v60, v60
	v_mul_f32_e32 v75, v61, v61
	v_mul_f32_e32 v64, v64, v76
	v_mul_f32_e32 v65, v65, v76
	v_mul_f32_e32 v66, v66, v76
	v_mul_f32_e32 v67, v67, v76
	v_pk_mov_b32 v[76:77], v[74:75], v[72:73] op_sel:[1,0]
	v_mov_b32_e32 v75, v73
	v_add_f32_e32 v72, v76, v74
	v_add_f32_e32 v73, v77, v75
	v_mul_f32_e32 v74, v58, v58
	v_mul_f32_e32 v75, v59, v59
	v_mul_f32_e32 v76, v56, v56
	v_mul_f32_e32 v77, v57, v57
	v_add_f32_e32 v72, v72, v73
	v_mov_b32_e32 v73, v72
	v_pk_mov_b32 v[80:81], v[76:77], v[74:75] op_sel:[1,0]
	v_mov_b32_e32 v77, v75
	v_add_f32_e32 v74, v80, v76
	v_add_f32_e32 v75, v81, v77
	v_mul_f32_e32 v76, v44, v44
	v_mul_f32_e32 v77, v45, v45
	v_add_f32_e32 v74, v74, v75
	v_mov_b32_e32 v75, v74
	v_mov_b32_e32 v73, v76
	v_mov_b32_e32 v75, v77
	v_add_f32_e32 v72, v72, v74
	v_add_f32_e32 v73, v73, v75
	v_mul_f32_e32 v74, v53, v53
	v_mul_f32_e32 v76, v55, v55
	v_mul_f32_e32 v80, v46, v46
	v_mul_f32_e32 v81, v47, v47
	v_fma_f32 v75, v53, v53, v74
	v_fma_f32 v74, v52, v52, v74
	v_fma_f32 v77, v55, v55, v76
	v_fma_f32 v76, v54, v54, v76
	v_mov_b32_e32 v75, v80
	v_mov_b32_e32 v77, v81
	v_add_f32_e32 v74, v74, v76
	v_add_f32_e32 v75, v75, v77
	v_mul_f32_e32 v76, v48, v48
	v_mul_f32_e32 v77, v49, v49
	v_add_f32_e32 v72, v72, v74
	v_add_f32_e32 v73, v73, v75
	v_mul_f32_e32 v74, v50, v50
	v_mul_f32_e32 v75, v51, v51
	v_mul_f32_e32 v68, v132, v68
	v_mul_f32_e32 v69, v133, v69
	v_pk_mov_b32 v[80:81], v[76:77], v[74:75] op_sel:[1,0]
	v_mov_b32_e32 v77, v75
	v_add_f32_e32 v74, v80, v76
	v_add_f32_e32 v75, v81, v77
	v_mul_f32_e32 v76, v42, v42
	v_mul_f32_e32 v77, v43, v43
	v_mul_f32_e32 v80, v40, v40
	v_mul_f32_e32 v81, v41, v41
	v_add_f32_e32 v74, v74, v75
	v_mov_b32_e32 v75, v74
	v_pk_mov_b32 v[82:83], v[80:81], v[76:77] op_sel:[1,0]
	v_mov_b32_e32 v81, v77
	v_add_f32_e32 v76, v82, v80
	v_add_f32_e32 v77, v83, v81
	v_mul_f32_e32 v80, v32, v32
	v_mul_f32_e32 v81, v33, v33
	v_add_f32_e32 v76, v76, v77
	v_mov_b32_e32 v77, v76
	v_mov_b32_e32 v75, v80
	v_mov_b32_e32 v77, v81
	v_add_f32_e32 v74, v74, v76
	v_add_f32_e32 v75, v75, v77
	v_mul_f32_e32 v76, v37, v37
	v_mul_f32_e32 v80, v39, v39
	v_mul_f32_e32 v82, v34, v34
	v_mul_f32_e32 v83, v35, v35
	v_fma_f32 v77, v37, v37, v76
	v_fma_f32 v76, v36, v36, v76
	v_fma_f32 v81, v39, v39, v80
	v_fma_f32 v80, v38, v38, v80
	v_mov_b32_e32 v77, v82
	v_mov_b32_e32 v81, v83
	v_add_f32_e32 v76, v76, v80
	v_add_f32_e32 v77, v77, v81
	v_mul_f32_e32 v70, v134, v70
	v_mul_f32_e32 v71, v135, v71
	v_add_f32_e32 v74, v74, v76
	v_add_f32_e32 v75, v75, v77
	v_mov_b32_e32 v77, v72
	v_mov_b32_e32 v76, v74
	v_mov_b32_e32 v72, v75
	v_add_f32_e32 v72, v76, v72
	v_add_f32_e32 v73, v77, v73
	ds_bpermute_b32 v75, v164, v73
	ds_bpermute_b32 v74, v164, v72
	v_mul_f32_e32 v76, v130, v66
	v_mul_f32_e32 v77, v131, v67
	v_mul_f32_e32 v66, v128, v64
	v_mul_f32_e32 v67, v129, v65
	v_cvt_pk_bf16_f32 v64, v68, v69
	v_cvt_pk_bf16_f32 v65, v70, v71
	s_waitcnt lgkmcnt(0)
; #define GAS __attribute__((address_space(1)))
;     __device__ __forceinline__ void operator()(const Acc& acc, const Unit& u, int wr, int wc, int fr, int fq) const {
;     ...
;             for (int ai = 0; ai < 2; ++ai)
; #pragma unroll
;                 for (int m = 0; m < 4; ++m) {
;                     float ss = 0.f;
; #pragma unroll
;                     for (int bj = 0; bj < 2; ++bj)
; #pragma unroll
;                         for (int n = 0; n < 2; ++n) { const f32x4 x = acc[ai][bj][m][n]; ss += (x[0] * x[0] + x[1] * x[1]) + (x[2] * x[2] + x[3] * x[3]); }
;                     ss += __shfl_xor(ss, 16); ss += __shfl_xor(ss, 32);
;                     const float rs = rsqrtf(ss * (1.f / 64.f) + 1e-6f) * sc;
;                     bf16_t* rowp = P + (size_t)(row0 + ai * HALF + m * 16) * NPROJ + colb;
; #pragma unroll
;                     for (int bj = 0; bj < 2; ++bj) *(GAS u32x4*)(rowp + 32 * bj) = pack8(acc[ai][bj][m][0] * rs * gv[bj][0], acc[ai][bj][m][1] * rs * gv[bj][1]);
	v_add_f32_e32 v68, v72, v74
	v_add_f32_e32 v69, v73, v75
	ds_bpermute_b32 v71, v165, v69
	ds_bpermute_b32 v70, v165, v68
	v_cvt_pk_bf16_f32 v66, v66, v67
	v_cvt_pk_bf16_f32 v67, v76, v77
	global_store_dwordx4 v[78:79], v[64:67], off offset:64
	s_waitcnt lgkmcnt(0)
	s_nop 0
	v_add_f32_e32 v64, v68, v70
	v_add_f32_e32 v65, v69, v71
	v_add_u32_e32 v66, 0x80, v171
	v_fma_f32 v64, v64, s16, v160
	v_fma_f32 v65, v65, s16, v160
	s_nop 0
	v_mul_f32_e32 v67, 0x4b800000, v65
	v_cmp_gt_f32_e32 vcc, s66, v65
	s_nop 1
	v_cndmask_b32_e32 v65, v65, v67, vcc
	v_rsq_f32_e32 v65, v65
	v_mad_i64_i32 v[66:67], s[4:5], v66, s65, v[156:157]
	v_lshl_add_u64 v[66:67], v[66:67], 0, v[158:159]
	v_mul_f32_e32 v68, 0x45800000, v65
	v_cndmask_b32_e32 v65, v65, v68, vcc
	v_mul_f32_e32 v68, v172, v65
	v_mul_f32_e32 v60, v60, v68
	v_mul_f32_e32 v61, v61, v68
	v_mul_f32_e32 v62, v62, v68
	v_mul_f32_e32 v63, v63, v68
	v_mul_f32_e32 v56, v56, v68
	v_mul_f32_e32 v57, v57, v68
	v_mul_f32_e32 v58, v58, v68
	v_mul_f32_e32 v59, v59, v68
	v_mul_f32_e32 v62, v142, v62
	v_mul_f32_e32 v63, v143, v63
	v_mul_f32_e32 v60, v140, v60
	v_mul_f32_e32 v61, v141, v61
	v_mul_f32_e32 v70, v138, v58
	v_mul_f32_e32 v71, v139, v59
	v_mul_f32_e32 v58, v136, v56
	v_mul_f32_e32 v59, v137, v57
	v_mul_f32_e32 v52, v52, v68
	v_mul_f32_e32 v53, v53, v68
	v_cvt_pk_bf16_f32 v56, v60, v61
	v_cvt_pk_bf16_f32 v57, v62, v63
	v_cvt_pk_bf16_f32 v58, v58, v59
	v_cvt_pk_bf16_f32 v59, v70, v71
	v_mul_f32_e32 v52, v132, v52
	v_mul_f32_e32 v53, v133, v53
	v_mul_f32_e32 v44, v44, v68
	v_mul_f32_e32 v45, v45, v68
	v_mul_f32_e32 v46, v46, v68
	v_mul_f32_e32 v47, v47, v68
	global_store_dwordx4 v[66:67], v[56:59], off
	v_cmp_gt_f32_e32 vcc, s66, v64
	v_mul_f32_e32 v54, v54, v68
	v_mul_f32_e32 v55, v55, v68
	v_mul_f32_e32 v56, v130, v46
	v_mul_f32_e32 v57, v131, v47
	v_mul_f32_e32 v46, v128, v44
	v_mul_f32_e32 v47, v129, v45
	v_cvt_pk_bf16_f32 v44, v52, v53
	v_mul_f32_e32 v52, 0x4b800000, v64
	v_cndmask_b32_e32 v52, v64, v52, vcc
	v_rsq_f32_e32 v52, v52
	v_mul_f32_e32 v54, v134, v54
	v_mul_f32_e32 v55, v135, v55
	v_cvt_pk_bf16_f32 v46, v46, v47
	v_cvt_pk_bf16_f32 v45, v54, v55
	v_cvt_pk_bf16_f32 v47, v56, v57
	global_store_dwordx4 v[66:67], v[44:47], off offset:64
	s_nop 1
	v_mul_f32_e32 v44, 0x45800000, v52
	v_cndmask_b32_e32 v44, v52, v44, vcc
	v_mul_f32_e32 v44, v172, v44
	v_add_u32_e32 v45, 0x90, v171
	v_mul_f32_e32 v48, v48, v44
	v_mul_f32_e32 v49, v49, v44
	v_mul_f32_e32 v50, v50, v44
	v_mul_f32_e32 v51, v51, v44
	v_mul_f32_e32 v40, v40, v44
	v_mul_f32_e32 v41, v41, v44
	v_mul_f32_e32 v42, v42, v44
	v_mul_f32_e32 v43, v43, v44
	v_mad_i64_i32 v[46:47], s[4:5], v45, s65, v[156:157]
	v_mul_f32_e32 v50, v142, v50
	v_mul_f32_e32 v51, v143, v51
	v_mul_f32_e32 v48, v140, v48
	v_mul_f32_e32 v49, v141, v49
	v_mul_f32_e32 v52, v138, v42
	v_mul_f32_e32 v53, v139, v43
	v_mul_f32_e32 v42, v136, v40
	v_mul_f32_e32 v43, v137, v41
	v_lshl_add_u64 v[46:47], v[46:47], 0, v[158:159]
	v_cvt_pk_bf16_f32 v40, v48, v49
	v_cvt_pk_bf16_f32 v41, v50, v51
	v_cvt_pk_bf16_f32 v42, v42, v43
	v_cvt_pk_bf16_f32 v43, v52, v53
	global_store_dwordx4 v[46:47], v[40:43], off
	v_mul_f32_e32 v36, v36, v44
	v_mul_f32_e32 v37, v37, v44
	v_mul_f32_e32 v38, v38, v44
	v_mul_f32_e32 v39, v39, v44
	v_mul_f32_e32 v40, v30, v30
	v_mul_f32_e32 v41, v31, v31
	v_mul_f32_e32 v42, v28, v28
	v_mul_f32_e32 v43, v29, v29
	v_mul_f32_e32 v32, v32, v44
	v_mul_f32_e32 v33, v33, v44
	v_mul_f32_e32 v34, v34, v44
	v_mul_f32_e32 v35, v35, v44
	v_pk_mov_b32 v[44:45], v[42:43], v[40:41] op_sel:[1,0]
	v_mov_b32_e32 v43, v41
	v_add_f32_e32 v40, v44, v42
	v_add_f32_e32 v41, v45, v43
	v_mul_f32_e32 v42, v26, v26
	v_mul_f32_e32 v43, v27, v27
	v_mul_f32_e32 v44, v24, v24
	v_mul_f32_e32 v45, v25, v25
	v_add_f32_e32 v40, v40, v41
	v_mov_b32_e32 v41, v40
	v_pk_mov_b32 v[48:49], v[44:45], v[42:43] op_sel:[1,0]
	v_mov_b32_e32 v45, v43
	v_add_f32_e32 v42, v48, v44
	v_add_f32_e32 v43, v49, v45
	v_mul_f32_e32 v44, v12, v12
	v_mul_f32_e32 v45, v13, v13
	v_add_f32_e32 v42, v42, v43
	v_mov_b32_e32 v43, v42
	v_mov_b32_e32 v41, v44
	v_mov_b32_e32 v43, v45
	v_add_f32_e32 v40, v40, v42
	v_add_f32_e32 v41, v41, v43
	v_mul_f32_e32 v42, v21, v21
	v_mul_f32_e32 v44, v23, v23
	v_mul_f32_e32 v48, v14, v14
	v_mul_f32_e32 v49, v15, v15
	v_fma_f32 v43, v21, v21, v42
	v_fma_f32 v42, v20, v20, v42
	v_fma_f32 v45, v23, v23, v44
	v_fma_f32 v44, v22, v22, v44
	v_mov_b32_e32 v43, v48
	v_mov_b32_e32 v45, v49
	v_add_f32_e32 v42, v42, v44
	v_add_f32_e32 v43, v43, v45
	v_mul_f32_e32 v44, v16, v16
	v_mul_f32_e32 v45, v17, v17
	v_add_f32_e32 v40, v40, v42
	v_add_f32_e32 v41, v41, v43
	v_mul_f32_e32 v42, v18, v18
	v_mul_f32_e32 v43, v19, v19
	v_mul_f32_e32 v36, v132, v36
	v_mul_f32_e32 v37, v133, v37
	v_pk_mov_b32 v[48:49], v[44:45], v[42:43] op_sel:[1,0]
	v_mov_b32_e32 v45, v43
	v_add_f32_e32 v42, v48, v44
	v_add_f32_e32 v43, v49, v45
	v_mul_f32_e32 v44, v10, v10
	v_mul_f32_e32 v45, v11, v11
	v_mul_f32_e32 v48, v8, v8
	v_mul_f32_e32 v49, v9, v9
	v_add_f32_e32 v42, v42, v43
	v_mov_b32_e32 v43, v42
	v_pk_mov_b32 v[50:51], v[48:49], v[44:45] op_sel:[1,0]
	v_mov_b32_e32 v49, v45
	v_add_f32_e32 v44, v50, v48
	v_add_f32_e32 v45, v51, v49
	v_mul_f32_e32 v48, v0, v0
	v_mul_f32_e32 v49, v1, v1
	v_add_f32_e32 v44, v44, v45
	v_mov_b32_e32 v45, v44
	v_mov_b32_e32 v43, v48
	v_mov_b32_e32 v45, v49
	v_add_f32_e32 v42, v42, v44
	v_add_f32_e32 v43, v43, v45
	v_mul_f32_e32 v44, v5, v5
	v_mul_f32_e32 v48, v7, v7
	v_mul_f32_e32 v50, v2, v2
	v_mul_f32_e32 v51, v3, v3
	v_fma_f32 v45, v5, v5, v44
	v_fma_f32 v44, v4, v4, v44
	v_fma_f32 v49, v7, v7, v48
	v_fma_f32 v48, v6, v6, v48
	v_mov_b32_e32 v45, v50
	v_mov_b32_e32 v49, v51
	v_add_f32_e32 v44, v44, v48
	v_add_f32_e32 v45, v45, v49
	v_mul_f32_e32 v38, v134, v38
	v_mul_f32_e32 v39, v135, v39
	v_add_f32_e32 v42, v42, v44
	v_add_f32_e32 v43, v43, v45
	v_mov_b32_e32 v45, v40
	v_mov_b32_e32 v44, v42
	v_mov_b32_e32 v40, v43
	v_add_f32_e32 v40, v44, v40
	v_add_f32_e32 v41, v45, v41
	ds_bpermute_b32 v43, v164, v41
	ds_bpermute_b32 v42, v164, v40
	v_mul_f32_e32 v44, v130, v34
	v_mul_f32_e32 v45, v131, v35
	v_mul_f32_e32 v34, v128, v32
	v_mul_f32_e32 v35, v129, v33
	v_cvt_pk_bf16_f32 v32, v36, v37
	v_cvt_pk_bf16_f32 v33, v38, v39
	s_waitcnt lgkmcnt(0)
; #define GAS __attribute__((address_space(1)))
;     __device__ __forceinline__ void operator()(const Acc& acc, const Unit& u, int wr, int wc, int fr, int fq) const {
;     ...
;             for (int ai = 0; ai < 2; ++ai)
; #pragma unroll
;                 for (int m = 0; m < 4; ++m) {
;                     float ss = 0.f;
; #pragma unroll
;                     for (int bj = 0; bj < 2; ++bj)
; #pragma unroll
;                         for (int n = 0; n < 2; ++n) { const f32x4 x = acc[ai][bj][m][n]; ss += (x[0] * x[0] + x[1] * x[1]) + (x[2] * x[2] + x[3] * x[3]); }
;                     ss += __shfl_xor(ss, 16); ss += __shfl_xor(ss, 32);
;                     const float rs = rsqrtf(ss * (1.f / 64.f) + 1e-6f) * sc;
;                     bf16_t* rowp = P + (size_t)(row0 + ai * HALF + m * 16) * NPROJ + colb;
; #pragma unroll
;                     for (int bj = 0; bj < 2; ++bj) *(GAS u32x4*)(rowp + 32 * bj) = pack8(acc[ai][bj][m][0] * rs * gv[bj][0], acc[ai][bj][m][1] * rs * gv[bj][1]);
	v_add_f32_e32 v36, v40, v42
	v_add_f32_e32 v37, v41, v43
	ds_bpermute_b32 v39, v165, v37
	ds_bpermute_b32 v38, v165, v36
	v_cvt_pk_bf16_f32 v34, v34, v35
	v_cvt_pk_bf16_f32 v35, v44, v45
	global_store_dwordx4 v[46:47], v[32:35], off offset:64
	s_waitcnt lgkmcnt(0)
	s_nop 0
	v_add_f32_e32 v32, v36, v38
	v_add_f32_e32 v33, v37, v39
	v_add_u32_e32 v34, 0xa0, v171
	v_fma_f32 v32, v32, s16, v160
	v_fma_f32 v33, v33, s16, v160
	s_nop 0
	v_mul_f32_e32 v35, 0x4b800000, v33
	v_cmp_gt_f32_e32 vcc, s66, v33
	s_nop 1
	v_cndmask_b32_e32 v33, v33, v35, vcc
	v_rsq_f32_e32 v33, v33
	v_mad_i64_i32 v[34:35], s[4:5], v34, s65, v[156:157]
	v_lshl_add_u64 v[34:35], v[34:35], 0, v[158:159]
	v_mul_f32_e32 v36, 0x45800000, v33
	v_cndmask_b32_e32 v33, v33, v36, vcc
	v_mul_f32_e32 v36, v172, v33
	v_mul_f32_e32 v28, v28, v36
	v_mul_f32_e32 v29, v29, v36
	v_mul_f32_e32 v30, v30, v36
	v_mul_f32_e32 v31, v31, v36
	v_mul_f32_e32 v24, v24, v36
	v_mul_f32_e32 v25, v25, v36
	v_mul_f32_e32 v26, v26, v36
	v_mul_f32_e32 v27, v27, v36
	v_mul_f32_e32 v30, v142, v30
	v_mul_f32_e32 v31, v143, v31
	v_mul_f32_e32 v28, v140, v28
	v_mul_f32_e32 v29, v141, v29
	v_mul_f32_e32 v38, v138, v26
	v_mul_f32_e32 v39, v139, v27
	v_mul_f32_e32 v26, v136, v24
	v_mul_f32_e32 v27, v137, v25
	v_mul_f32_e32 v20, v20, v36
	v_mul_f32_e32 v21, v21, v36
	v_cvt_pk_bf16_f32 v24, v28, v29
	v_cvt_pk_bf16_f32 v25, v30, v31
	v_cvt_pk_bf16_f32 v26, v26, v27
	v_cvt_pk_bf16_f32 v27, v38, v39
	v_mul_f32_e32 v20, v132, v20
	v_mul_f32_e32 v21, v133, v21
	v_mul_f32_e32 v12, v12, v36
	v_mul_f32_e32 v13, v13, v36
	v_mul_f32_e32 v14, v14, v36
	v_mul_f32_e32 v15, v15, v36
	global_store_dwordx4 v[34:35], v[24:27], off
	v_cmp_gt_f32_e32 vcc, s66, v32
	v_mul_f32_e32 v22, v22, v36
	v_mul_f32_e32 v23, v23, v36
	v_mul_f32_e32 v24, v130, v14
	v_mul_f32_e32 v25, v131, v15
	v_mul_f32_e32 v14, v128, v12
	v_mul_f32_e32 v15, v129, v13
	v_cvt_pk_bf16_f32 v12, v20, v21
	v_mul_f32_e32 v20, 0x4b800000, v32
	v_cndmask_b32_e32 v20, v32, v20, vcc
	v_rsq_f32_e32 v20, v20
	v_mul_f32_e32 v22, v134, v22
	v_mul_f32_e32 v23, v135, v23
	v_cvt_pk_bf16_f32 v14, v14, v15
	v_cvt_pk_bf16_f32 v13, v22, v23
	v_cvt_pk_bf16_f32 v15, v24, v25
	global_store_dwordx4 v[34:35], v[12:15], off offset:64
	s_nop 1
	v_mul_f32_e32 v12, 0x45800000, v20
	v_cndmask_b32_e32 v12, v20, v12, vcc
	v_mul_f32_e32 v12, v172, v12
	v_add_u32_e32 v13, 0xb0, v171
	v_mad_i64_i32 v[14:15], s[4:5], v13, s65, v[156:157]
	v_mul_f32_e32 v16, v16, v12
	v_mul_f32_e32 v17, v17, v12
	v_mul_f32_e32 v18, v18, v12
	v_mul_f32_e32 v19, v19, v12
	v_mul_f32_e32 v8, v8, v12
	v_mul_f32_e32 v9, v9, v12
	v_mul_f32_e32 v10, v10, v12
	v_mul_f32_e32 v11, v11, v12
	v_mul_f32_e32 v4, v4, v12
	v_mul_f32_e32 v5, v5, v12
	v_mul_f32_e32 v6, v6, v12
	v_mul_f32_e32 v7, v7, v12
	v_mul_f32_e32 v0, v0, v12
	v_mul_f32_e32 v1, v1, v12
	v_mul_f32_e32 v2, v2, v12
	v_mul_f32_e32 v3, v3, v12
	v_lshl_add_u64 v[14:15], v[14:15], 0, v[158:159]
	v_mul_f32_e32 v18, v142, v18
	v_mul_f32_e32 v19, v143, v19
	v_mul_f32_e32 v16, v140, v16
	v_mul_f32_e32 v17, v141, v17
	v_mul_f32_e32 v20, v138, v10
	v_mul_f32_e32 v21, v139, v11
	v_mul_f32_e32 v10, v136, v8
	v_mul_f32_e32 v11, v137, v9
	v_mul_f32_e32 v6, v134, v6
	v_mul_f32_e32 v7, v135, v7
	v_mul_f32_e32 v4, v132, v4
	v_mul_f32_e32 v5, v133, v5
	v_mul_f32_e32 v2, v130, v2
	v_mul_f32_e32 v3, v131, v3
	v_mul_f32_e32 v0, v128, v0
	v_mul_f32_e32 v1, v129, v1
	v_cvt_pk_bf16_f32 v8, v16, v17
	v_cvt_pk_bf16_f32 v9, v18, v19
	v_cvt_pk_bf16_f32 v10, v10, v11
	v_cvt_pk_bf16_f32 v11, v20, v21
	v_cvt_pk_bf16_f32 v128, v4, v5
	v_cvt_pk_bf16_f32 v129, v6, v7
	v_cvt_pk_bf16_f32 v130, v0, v1
	v_cvt_pk_bf16_f32 v131, v2, v3
	v_lshl_add_u64 v[132:133], v[14:15], 0, 64
	global_store_dwordx4 v[14:15], v[8:11], off
	s_andn2_b64 vcc, exec, s[2:3]
	s_mov_b64 s[2:3], -1
	global_store_dwordx4 v[132:133], v[128:131], off
	s_cbranch_vccnz .LBB0_116

; #define GAS __attribute__((address_space(1)))
; __device__ __forceinline__ unsigned cvt_pk_bf16(float lo, float hi) { const f32x2 v = {lo, hi}; return __builtin_bit_cast(unsigned, __builtin_convertvector(v, b16x2_t)); }
; __device__ __forceinline__ float bf_lo(unsigned u) { return __uint_as_float(u << 16); }
; __device__ __forceinline__ float bf_hi(unsigned u) { return __uint_as_float(u & 0xffff0000u); }
; __device__ __forceinline__ void attn_phase(LAS unsigned char* lds, const int wid, const bf16_t* P, const float* LF, bf16_t* CAT, const float* qgain, const float* kgain) {
;     ...
;             float base = inc - c[7];
;             for (int i = 0; i < wid; ++i) base += red[i];
; #pragma unroll
;             for (int i = 0; i < 8; ++i) CB[tid * 8 + i] = -(base + c[i]) * LOG2E;
;         }
;         __syncthreads();
;     ...
;             const float ltot = lsum + __shfl_xor(lsum, 32);
;             const float inv = 1.f / ltot;
; #pragma unroll
;             for (int db = 0; db < 2; ++db)
; #pragma unroll
;                 for (int i4 = 0; i4 < 4; ++i4) {
;                     const int d0 = db * 32 + 8 * i4 + 4 * hh;
;                     const u32x2 gt = *(const GAS u32x2*)(P + (tok0 + qrow) * NPROJ + 1536 + hd * 64 + d0);
;                     u32x2 o; o.x = cvt_pk_bf16(O[db][4 * i4 + 0] * inv * bf_lo(gt.x), O[db][4 * i4 + 1] * inv * bf_hi(gt.x));
;                     o.y = cvt_pk_bf16(O[db][4 * i4 + 2] * inv * bf_lo(gt.y), O[db][4 * i4 + 3] * inv * bf_hi(gt.y));
;                     *(GAS u32x2*)(CAT + (tok0 + qrow) * D + hd * 64 + d0) = o;
;                 }
.LBB0_257:
	s_ashr_i32 s20, s68, 5
	s_ashr_i32 s21, s20, 31
	s_lshl_b32 s18, s18, 7
	v_add_f32_e32 v2, v2, v10
	v_add_f32_e32 v3, v3, v10
	s_lshl_b64 s[52:53], s[20:21], 12
	s_and_b32 s40, s18, 0x380
	s_mul_hi_i32 s19, s20, 0x1400000
	s_mul_i32 s18, s20, 0x1400000
	s_lshl_b32 s20, s68, 5
	v_mul_f32_e32 v12, s48, v2
	v_mul_f32_e32 v13, s48, v3
	v_add_f32_e32 v2, v8, v10
	v_add_f32_e32 v3, v9, v10
	s_and_b32 s20, s20, 0x380
	s_and_b32 s69, s68, 3
	v_mul_f32_e32 v14, s48, v2
	v_mul_f32_e32 v15, s48, v3
	v_add_f32_e32 v2, v6, v10
	v_add_f32_e32 v3, v7, v10
	v_add_f32_e32 v4, v4, v10
	v_add_f32_e32 v5, v5, v10
	s_or_b32 s18, s18, s20
	v_mul_f32_e32 v2, s48, v2
	v_mul_f32_e32 v3, s48, v3
	v_mul_f32_e32 v4, s48, v4
	v_mul_f32_e32 v5, s48, v5
	v_lshl_add_u64 v[120:121], v[108:109], 0, s[40:41]
	v_lshl_add_u64 v[122:123], s[52:53], 0, v[104:105]
	v_lshl_add_u64 v[124:125], v[110:111], 0, s[40:41]
	s_xor_b32 s70, s69, 15
	s_xor_b32 s71, s69, 7
	s_or_b32 s72, s69, 8
	v_lshl_add_u64 v[126:127], v[114:115], 0, s[40:41]
	v_lshl_add_u64 v[128:129], v[116:117], 0, s[40:41]
	v_lshl_add_u64 v[130:131], v[118:119], 0, s[18:19]
	s_mov_b32 s73, 0
	ds_write_b128 v156, v[12:15]
	ds_write_b128 v156, v[2:5] offset:16
	s_waitcnt lgkmcnt(0)
	s_barrier
	s_branch .LBB0_259
.LBB0_258:
	v_lshl_add_u64 v[2:3], v[126:127], 0, v[138:139]
	global_load_dwordx2 v[4:5], v[2:3], off offset:3072
	ds_bpermute_b32 v1, v146, v135
	v_lshlrev_b64 v[6:7], 11, v[132:133]
	v_lshl_add_u64 v[6:7], v[128:129], 0, v[6:7]
	s_add_i32 s73, s73, 1
	s_cmp_eq_u32 s73, 4
	s_waitcnt lgkmcnt(0)
	v_add_f32_e32 v1, v135, v1
	v_div_scale_f32 v8, s[18:19], v1, v1, 1.0
	v_rcp_f32_e32 v9, v8
	v_div_scale_f32 v10, vcc, 1.0, v1, 1.0
	v_fma_f32 v11, -v8, v9, 1.0
	v_fmac_f32_e32 v9, v11, v9
	v_mul_f32_e32 v11, v10, v9
	v_fma_f32 v12, -v8, v11, v10
	v_fmac_f32_e32 v11, v12, v9
	v_fma_f32 v8, -v8, v11, v10
	v_div_fmas_f32 v8, v8, v9, v11
	v_div_fixup_f32 v8, v8, v1, 1.0
	v_mul_f32_e32 v10, v32, v8
	v_mul_f32_e32 v11, v33, v8
	v_mul_f32_e32 v12, v34, v8
	v_mul_f32_e32 v13, v35, v8
	s_waitcnt vmcnt(0)
	v_lshlrev_b32_e32 v14, 16, v4
	v_and_b32_e32 v15, 0xffff0000, v4
	v_lshlrev_b32_e32 v4, 16, v5
	v_and_b32_e32 v5, 0xffff0000, v5
	v_mul_f32_e32 v10, v10, v14
	v_mul_f32_e32 v11, v11, v15
	v_mul_f32_e32 v4, v12, v4
	v_mul_f32_e32 v5, v13, v5
	v_cvt_pk_bf16_f32 v10, v10, v11
	v_cvt_pk_bf16_f32 v11, v4, v5
	global_store_dwordx2 v[6:7], v[10:11], off
	global_load_dwordx2 v[4:5], v[2:3], off offset:3088
	v_mul_f32_e32 v10, v36, v8
	v_mul_f32_e32 v11, v37, v8
	v_mul_f32_e32 v12, v38, v8
	v_mul_f32_e32 v13, v39, v8
	s_waitcnt vmcnt(0)
	v_lshlrev_b32_e32 v14, 16, v4
	v_and_b32_e32 v15, 0xffff0000, v4
	v_lshlrev_b32_e32 v4, 16, v5
	v_and_b32_e32 v5, 0xffff0000, v5
	v_mul_f32_e32 v10, v10, v14
	v_mul_f32_e32 v11, v11, v15
	v_mul_f32_e32 v4, v12, v4
	v_mul_f32_e32 v5, v13, v5
	v_cvt_pk_bf16_f32 v10, v10, v11
	v_cvt_pk_bf16_f32 v11, v4, v5
	global_store_dwordx2 v[6:7], v[10:11], off offset:16
	global_load_dwordx2 v[4:5], v[2:3], off offset:3104
	v_mul_f32_e32 v10, v40, v8
	v_mul_f32_e32 v11, v41, v8
	v_mul_f32_e32 v12, v42, v8
	v_mul_f32_e32 v13, v43, v8
	s_waitcnt vmcnt(0)
	v_lshlrev_b32_e32 v14, 16, v4
	v_and_b32_e32 v15, 0xffff0000, v4
	v_lshlrev_b32_e32 v4, 16, v5
	v_and_b32_e32 v5, 0xffff0000, v5
	v_mul_f32_e32 v10, v10, v14
	v_mul_f32_e32 v11, v11, v15
	v_mul_f32_e32 v4, v12, v4
	v_mul_f32_e32 v5, v13, v5
	v_cvt_pk_bf16_f32 v10, v10, v11
	v_cvt_pk_bf16_f32 v11, v4, v5
	global_store_dwordx2 v[6:7], v[10:11], off offset:32
	global_load_dwordx2 v[4:5], v[2:3], off offset:3120
	v_mul_f32_e32 v10, v44, v8
	v_mul_f32_e32 v11, v45, v8
	v_mul_f32_e32 v12, v46, v8
	v_mul_f32_e32 v13, v47, v8
	s_waitcnt vmcnt(0)
	v_lshlrev_b32_e32 v14, 16, v4
	v_and_b32_e32 v15, 0xffff0000, v4
	v_lshlrev_b32_e32 v4, 16, v5
	v_and_b32_e32 v5, 0xffff0000, v5
	v_mul_f32_e32 v10, v10, v14
	v_mul_f32_e32 v11, v11, v15
	v_mul_f32_e32 v4, v12, v4
	v_mul_f32_e32 v5, v13, v5
	v_cvt_pk_bf16_f32 v10, v10, v11
	v_cvt_pk_bf16_f32 v11, v4, v5
	global_store_dwordx2 v[6:7], v[10:11], off offset:48
	global_load_dwordx2 v[4:5], v[2:3], off offset:3136
	v_mul_f32_e32 v10, v16, v8
	v_mul_f32_e32 v11, v17, v8
	v_mul_f32_e32 v12, v18, v8
	v_mul_f32_e32 v13, v19, v8
	s_waitcnt vmcnt(0)
	v_lshlrev_b32_e32 v14, 16, v4
	v_and_b32_e32 v15, 0xffff0000, v4
	v_lshlrev_b32_e32 v4, 16, v5
	v_and_b32_e32 v5, 0xffff0000, v5
	v_mul_f32_e32 v10, v10, v14
	v_mul_f32_e32 v11, v11, v15
	v_mul_f32_e32 v4, v12, v4
	v_mul_f32_e32 v5, v13, v5
	v_cvt_pk_bf16_f32 v10, v10, v11
	v_cvt_pk_bf16_f32 v11, v4, v5
	global_store_dwordx2 v[6:7], v[10:11], off offset:64
	global_load_dwordx2 v[4:5], v[2:3], off offset:3152
	v_mul_f32_e32 v10, v20, v8
	v_mul_f32_e32 v11, v21, v8
	v_mul_f32_e32 v12, v22, v8
	v_mul_f32_e32 v13, v23, v8
	s_waitcnt vmcnt(0)
	v_lshlrev_b32_e32 v14, 16, v4
	v_and_b32_e32 v15, 0xffff0000, v4
	v_lshlrev_b32_e32 v4, 16, v5
	v_and_b32_e32 v5, 0xffff0000, v5
	v_mul_f32_e32 v10, v10, v14
	v_mul_f32_e32 v11, v11, v15
	v_mul_f32_e32 v4, v12, v4
	v_mul_f32_e32 v5, v13, v5
	v_cvt_pk_bf16_f32 v10, v10, v11
	v_cvt_pk_bf16_f32 v11, v4, v5
	global_store_dwordx2 v[6:7], v[10:11], off offset:80
	global_load_dwordx2 v[4:5], v[2:3], off offset:3168
	v_mul_f32_e32 v10, v24, v8
	v_mul_f32_e32 v11, v25, v8
	v_mul_f32_e32 v12, v26, v8
	v_mul_f32_e32 v13, v27, v8
	s_waitcnt vmcnt(0)
	v_lshlrev_b32_e32 v14, 16, v4
	v_and_b32_e32 v15, 0xffff0000, v4
	v_lshlrev_b32_e32 v4, 16, v5
	v_and_b32_e32 v5, 0xffff0000, v5
	v_mul_f32_e32 v10, v10, v14
	v_mul_f32_e32 v11, v11, v15
	v_mul_f32_e32 v4, v12, v4
	v_mul_f32_e32 v5, v13, v5
	v_cvt_pk_bf16_f32 v10, v10, v11
	v_cvt_pk_bf16_f32 v11, v4, v5
	global_store_dwordx2 v[6:7], v[10:11], off offset:96
	global_load_dwordx2 v[2:3], v[2:3], off offset:3184
	v_mul_f32_e32 v4, v28, v8
	v_mul_f32_e32 v5, v29, v8
	v_mul_f32_e32 v9, v31, v8
	v_mul_f32_e32 v8, v30, v8
	s_waitcnt vmcnt(0)
	v_lshlrev_b32_e32 v10, 16, v2
	v_and_b32_e32 v11, 0xffff0000, v2
	v_lshlrev_b32_e32 v2, 16, v3
	v_and_b32_e32 v3, 0xffff0000, v3
	v_mul_f32_e32 v4, v4, v10
	v_mul_f32_e32 v5, v5, v11
	v_mul_f32_e32 v2, v8, v2
	v_mul_f32_e32 v3, v9, v3
	v_cvt_pk_bf16_f32 v4, v4, v5
	v_cvt_pk_bf16_f32 v5, v2, v3
	global_store_dwordx2 v[6:7], v[4:5], off offset:112
	s_cbranch_scc1 .LBB0_246

; #define LAS __attribute__((address_space(3)))
; __device__ __forceinline__ void attn_phase(LAS unsigned char* lds, const int wid, const bf16_t* P, const float* LF, bf16_t* CAT, const float* qgain, const float* kgain) {
;     ...
;                 if (kt * 64 <= q0 + 31 && !done_w) {
;                     const LAS unsigned char* kb_ = KB + cb * 64 * KPITCH;
;                     const LAS unsigned char* vb_ = VB + cb * 64 * VPITCH;
;                     f32x16 sacc[2];
; #pragma unroll
;                     for (int kb = 0; kb < 2; ++kb) {
; #pragma unroll
;                         for (int i = 0; i < 16; ++i) sacc[kb][i] = 0.f;
; #pragma unroll
;                         for (int ds = 0; ds < 4; ++ds) {
;                             const bf16x8 a = *(const LAS bf16x8*)(kb_ + (kb * 32 + r32) * KPITCH + (16 * ds + 8 * hh) * 2);
;                             sacc[kb] = __builtin_amdgcn_mfma_f32_32x32x16_bf16(a, qf[ds], sacc[kb], 0, 0, 0);
;                         }
;                     }
;                     const bool diag = (kt * 64 + 63 > q0);
;                     float mloc = -1e30f;
; #pragma unroll
;                     for (int kb = 0; kb < 2; ++kb)
; #pragma unroll
;                         for (int i4 = 0; i4 < 4; ++i4) {
;                             const int kl = kb * 32 + 8 * i4 + 4 * hh;
;                             const f32x4 bias = *(const LAS f32x4*)(CB + kt * 64 + kl);
; #pragma unroll
;                             for (int jj = 0; jj < 4; ++jj) {
;                                 float sv = sacc[kb][4 * i4 + jj] + bias[jj];
;                                 if (diag && (kt * 64 + kl + jj > qrow)) sv = -1e30f;
;                                 sacc[kb][4 * i4 + jj] = sv; mloc = fmaxf(mloc, sv);
;                             }
;                         }
.LBB0_268:
	s_and_b32 s80, s20, 1
	s_cmp_le_i32 s77, s76
	s_cselect_b64 s[18:19], -1, 0
	v_cmp_eq_u32_e32 vcc, 0, v165
	s_and_b64 s[56:57], s[18:19], vcc
	s_and_saveexec_b64 s[58:59], s[56:57]
	s_cbranch_execz .LBB0_270
	s_mul_i32 s18, s80, 0x2400
	v_add3_u32 v1, v160, s18, v162
	ds_read_b128 v[2:5], v1 offset:16384
	ds_read_b128 v[6:9], v1 offset:16416
	v_add_u32_e32 v14, s78, v159
	s_add_i32 s18, s77, 63
	v_add_u32_e32 v15, s77, v112
	s_waitcnt lgkmcnt(1)
	v_mfma_f32_32x32x16_bf16 v[64:79], v[2:5], v[88:91], 0
	ds_read_b128 v[2:5], v1 offset:16448
	s_cmp_gt_i32 s18, s74
	v_cmp_gt_i32_e32 vcc, v15, v134
	s_cselect_b64 s[60:61], -1, 0
	v_cmp_ge_i32_e64 s[18:19], v15, v134
	s_and_b64 vcc, s[60:61], vcc
	s_waitcnt lgkmcnt(1)
	v_mfma_f32_32x32x16_bf16 v[64:79], v[6:9], v[92:95], v[64:79]
	ds_read_b128 v[6:9], v1 offset:16480
	ds_read_b128 v[10:13], v1 offset:20992
	s_waitcnt lgkmcnt(2)
	v_mfma_f32_32x32x16_bf16 v[64:79], v[2:5], v[96:99], v[64:79]
	ds_read_b128 v[2:5], v14 offset:4
	ds_read_b128 v[168:171], v14 offset:36
	ds_read_b128 v[172:175], v1 offset:21024
	ds_read_b128 v[176:179], v1 offset:21056
	ds_read_b128 v[180:183], v1 offset:21088
	v_add_u32_e32 v1, 2, v15
	v_cmp_gt_i32_e64 s[20:21], v1, v134
	s_waitcnt lgkmcnt(6)
	v_mfma_f32_32x32x16_bf16 v[64:79], v[6:9], v[100:103], v[64:79]
	s_waitcnt lgkmcnt(5)
	v_mfma_f32_32x32x16_bf16 v[48:63], v[10:13], v[88:91], 0
	s_waitcnt lgkmcnt(4)
	s_nop 8
	v_add_f32_e32 v1, v64, v2
	v_add_u32_e32 v10, 3, v15
	v_add_f32_e32 v2, v65, v3
	v_cndmask_b32_e32 v1, v1, v164, vcc
	s_and_b64 vcc, s[60:61], s[18:19]
	v_add_u32_e32 v11, 8, v15
	v_cmp_gt_i32_e64 s[24:25], v10, v134
	v_add_f32_e32 v3, v66, v4
	v_cndmask_b32_e32 v10, v2, v164, vcc
	s_and_b64 vcc, s[60:61], s[20:21]
	v_cmp_gt_i32_e64 s[26:27], v11, v134
	v_add_f32_e32 v4, v67, v5
	v_cndmask_b32_e32 v12, v3, v164, vcc
	s_and_b64 vcc, s[60:61], s[24:25]
	s_waitcnt lgkmcnt(3)
	v_add_f32_e32 v5, v68, v168
	v_cndmask_b32_e32 v13, v4, v164, vcc
	s_and_b64 vcc, s[60:61], s[26:27]
	v_cndmask_b32_e32 v64, v5, v164, vcc
	v_cmp_ge_i32_e32 vcc, v11, v134
	v_add_f32_e32 v3, v69, v169
	s_and_b64 vcc, s[60:61], vcc
	v_max3_f32 v2, v1, s67, v10
	v_cndmask_b32_e32 v11, v3, v164, vcc
	v_add_u32_e32 v3, 10, v15
	v_max3_f32 v2, v2, v12, v13
	v_cmp_gt_i32_e32 vcc, v3, v134
	v_max3_f32 v6, v2, v64, v11
	v_add_f32_e32 v2, v70, v170
	s_and_b64 vcc, s[60:61], vcc
	v_cndmask_b32_e32 v65, v2, v164, vcc
	v_add_u32_e32 v2, 11, v15
	v_cmp_gt_i32_e32 vcc, v2, v134
	ds_read_b128 v[2:5], v14 offset:68
	s_waitcnt lgkmcnt(3)
	v_mfma_f32_32x32x16_bf16 v[48:63], v[172:175], v[92:95], v[48:63]
	v_add_f32_e32 v7, v71, v171
	s_and_b64 vcc, s[60:61], vcc
	v_add_u32_e32 v68, 16, v15
	v_cndmask_b32_e32 v66, v7, v164, vcc
	v_cmp_gt_i32_e32 vcc, v68, v134
	v_max3_f32 v67, v6, v65, v66
	ds_read_b128 v[6:9], v14 offset:100
	s_waitcnt lgkmcnt(1)
	v_add_f32_e32 v2, v72, v2
	s_and_b64 vcc, s[60:61], vcc
	v_cndmask_b32_e32 v69, v2, v164, vcc
	v_cmp_ge_i32_e32 vcc, v68, v134
	v_add_f32_e32 v2, v73, v3
	s_and_b64 vcc, s[60:61], vcc
	v_add_f32_e32 v3, v74, v4
	v_add_u32_e32 v4, 18, v15
	v_cndmask_b32_e32 v68, v2, v164, vcc
	v_cmp_gt_i32_e32 vcc, v4, v134
	v_mfma_f32_32x32x16_bf16 v[48:63], v[176:179], v[96:99], v[48:63]
	s_and_b64 vcc, s[60:61], vcc
	v_add_u32_e32 v4, 19, v15
	v_max3_f32 v2, v67, v69, v68
	v_cndmask_b32_e32 v67, v3, v164, vcc
	v_cmp_gt_i32_e32 vcc, v4, v134
	v_add_f32_e32 v3, v75, v5
	s_and_b64 vcc, s[60:61], vcc
	v_cndmask_b32_e32 v70, v3, v164, vcc
	v_add_u32_e32 v3, 24, v15
	v_cmp_gt_i32_e32 vcc, v3, v134
	s_waitcnt lgkmcnt(0)
	v_add_f32_e32 v4, v76, v6
	s_and_b64 vcc, s[60:61], vcc
	v_cndmask_b32_e32 v71, v4, v164, vcc
	v_cmp_ge_i32_e32 vcc, v3, v134
	v_add_f32_e32 v4, v77, v7
	s_and_b64 vcc, s[60:61], vcc
	v_add_u32_e32 v3, 26, v15
	v_mfma_f32_32x32x16_bf16 v[48:63], v[180:183], v[100:103], v[48:63]
	v_max3_f32 v2, v2, v67, v70
	v_cndmask_b32_e32 v72, v4, v164, vcc
	v_cmp_gt_i32_e32 vcc, v3, v134
	v_max3_f32 v6, v2, v71, v72
	v_add_f32_e32 v2, v78, v8
	s_and_b64 vcc, s[60:61], vcc
	v_cndmask_b32_e32 v73, v2, v164, vcc
	v_add_u32_e32 v2, 27, v15
	v_cmp_gt_i32_e32 vcc, v2, v134
	ds_read_b128 v[2:5], v14 offset:132
	v_add_f32_e32 v7, v79, v9
	s_and_b64 vcc, s[60:61], vcc
	v_add_u32_e32 v76, 32, v15
	v_cndmask_b32_e32 v74, v7, v164, vcc
	v_cmp_gt_i32_e32 vcc, v76, v134
	v_max3_f32 v75, v6, v73, v74
	ds_read_b128 v[6:9], v14 offset:164
	s_waitcnt lgkmcnt(1)
	v_add_f32_e32 v2, v48, v2
	s_and_b64 vcc, s[60:61], vcc
	v_cndmask_b32_e32 v48, v2, v164, vcc
	v_cmp_ge_i32_e32 vcc, v76, v134
	v_add_f32_e32 v2, v49, v3
	s_and_b64 vcc, s[60:61], vcc
	v_add_f32_e32 v3, v50, v4
	v_add_u32_e32 v4, 34, v15
	v_cndmask_b32_e32 v49, v2, v164, vcc
	v_cmp_gt_i32_e32 vcc, v4, v134
	s_and_b64 vcc, s[60:61], vcc
	v_add_u32_e32 v4, 35, v15
	v_cndmask_b32_e32 v50, v3, v164, vcc
	v_cmp_gt_i32_e32 vcc, v4, v134
	v_add_f32_e32 v3, v51, v5
	s_and_b64 vcc, s[60:61], vcc
	v_cndmask_b32_e32 v51, v3, v164, vcc
	v_add_u32_e32 v3, 40, v15
	v_cmp_gt_i32_e32 vcc, v3, v134
	s_waitcnt lgkmcnt(0)
	v_add_f32_e32 v4, v52, v6
	s_and_b64 vcc, s[60:61], vcc
	v_cndmask_b32_e32 v52, v4, v164, vcc
	v_cmp_ge_i32_e32 vcc, v3, v134
	v_max3_f32 v2, v75, v48, v49
	v_add_f32_e32 v4, v53, v7
	s_and_b64 vcc, s[60:61], vcc
	v_add_u32_e32 v3, 42, v15
	v_max3_f32 v2, v2, v50, v51
	v_cndmask_b32_e32 v53, v4, v164, vcc
	v_cmp_gt_i32_e32 vcc, v3, v134
	v_max3_f32 v6, v2, v52, v53
	v_add_f32_e32 v2, v54, v8
	s_and_b64 vcc, s[60:61], vcc
	v_cndmask_b32_e32 v54, v2, v164, vcc
	v_add_u32_e32 v2, 43, v15
	v_cmp_gt_i32_e32 vcc, v2, v134
	ds_read_b128 v[2:5], v14 offset:196
	v_add_f32_e32 v7, v55, v9
	s_and_b64 vcc, s[60:61], vcc
	v_add_u32_e32 v76, 48, v15
	v_cndmask_b32_e32 v55, v7, v164, vcc
	v_cmp_gt_i32_e32 vcc, v76, v134
	v_max3_f32 v75, v6, v54, v55
	ds_read_b128 v[6:9], v14 offset:228
	s_waitcnt lgkmcnt(1)
; #define LAS __attribute__((address_space(3)))
; __device__ __forceinline__ void attn_phase(LAS unsigned char* lds, const int wid, const bf16_t* P, const float* LF, bf16_t* CAT, const float* qgain, const float* kgain) {
;     ...
;                     const bool diag = (kt * 64 + 63 > q0);
;                     float mloc = -1e30f;
; #pragma unroll
;                     for (int kb = 0; kb < 2; ++kb)
; #pragma unroll
;                         for (int i4 = 0; i4 < 4; ++i4) {
;                             const int kl = kb * 32 + 8 * i4 + 4 * hh;
;                             const f32x4 bias = *(const LAS f32x4*)(CB + kt * 64 + kl);
; #pragma unroll
;                             for (int jj = 0; jj < 4; ++jj) {
;                                 float sv = sacc[kb][4 * i4 + jj] + bias[jj];
;                                 if (diag && (kt * 64 + kl + jj > qrow)) sv = -1e30f;
;                                 sacc[kb][4 * i4 + jj] = sv; mloc = fmaxf(mloc, sv);
;                             }
;                         }
;                     mloc = fmaxf(mloc, __shfl_xor(mloc, 32));
;                     const float mnew = fmaxf(mrun, mloc);
;                     const float alpha = fexp2(mrun - mnew); mrun = mnew;
;                     float ps = 0.f;
; #pragma unroll
;                     for (int kb = 0; kb < 2; ++kb)
; #pragma unroll
;                         for (int i = 0; i < 16; ++i) { const float p = fexp2(sacc[kb][i] - mnew); sacc[kb][i] = p; ps += p; }
;                     lsum = lsum * alpha + ps;
; #pragma unroll
;                     for (int i = 0; i < 16; ++i) { O[0][i] *= alpha; O[1][i] *= alpha; }
; #pragma unroll
;                     for (int kb = 0; kb < 2; ++kb)
; #pragma unroll
;                         for (int s2 = 0; s2 < 2; ++s2) {
;                             u32x4 pw; pw.x = cvt_pk_bf16(sacc[kb][8 * s2 + 0], sacc[kb][8 * s2 + 1]); pw.y = cvt_pk_bf16(sacc[kb][8 * s2 + 2], sacc[kb][8 * s2 + 3]);
;                             pw.z = cvt_pk_bf16(sacc[kb][8 * s2 + 4], sacc[kb][8 * s2 + 5]); pw.w = cvt_pk_bf16(sacc[kb][8 * s2 + 6], sacc[kb][8 * s2 + 7]);
;                             const bf16x8 pf = __builtin_bit_cast(bf16x8, pw);
; #pragma unroll
;                             for (int db = 0; db < 2; ++db) {
;                                 const LAS unsigned char* vp = vb_ + (db * 32 + r32) * VPITCH + (kb * 32 + 16 * s2 + 4 * hh) * 2;
	v_add_f32_e32 v2, v56, v2
	s_and_b64 vcc, s[60:61], vcc
	v_cndmask_b32_e32 v56, v2, v164, vcc
	v_cmp_ge_i32_e32 vcc, v76, v134
	v_add_f32_e32 v2, v57, v3
	s_and_b64 vcc, s[60:61], vcc
	v_add_f32_e32 v3, v58, v4
	v_add_u32_e32 v4, 50, v15
	v_cndmask_b32_e32 v57, v2, v164, vcc
	v_cmp_gt_i32_e32 vcc, v4, v134
	s_and_b64 vcc, s[60:61], vcc
	v_add_u32_e32 v4, 51, v15
	v_cndmask_b32_e32 v58, v3, v164, vcc
	v_cmp_gt_i32_e32 vcc, v4, v134
	v_add_f32_e32 v3, v59, v5
	s_and_b64 vcc, s[60:61], vcc
	v_cndmask_b32_e32 v59, v3, v164, vcc
	v_add_u32_e32 v3, 56, v15
	v_cmp_gt_i32_e32 vcc, v3, v134
	s_waitcnt lgkmcnt(0)
	v_add_f32_e32 v4, v60, v6
	s_and_b64 vcc, s[60:61], vcc
	v_cndmask_b32_e32 v60, v4, v164, vcc
	v_cmp_ge_i32_e32 vcc, v3, v134
	v_add_f32_e32 v4, v61, v7
	s_and_b64 vcc, s[60:61], vcc
	v_cndmask_b32_e32 v61, v4, v164, vcc
	v_add_u32_e32 v4, 58, v15
	v_cmp_gt_i32_e32 vcc, v4, v134
	v_add_f32_e32 v3, v62, v8
	s_and_b64 vcc, s[60:61], vcc
	v_add_u32_e32 v4, 59, v15
	v_max3_f32 v2, v75, v56, v57
	v_cndmask_b32_e32 v62, v3, v164, vcc
	v_cmp_gt_i32_e32 vcc, v4, v134
	v_max3_f32 v2, v2, v58, v59
	v_add_f32_e32 v3, v63, v9
	s_and_b64 vcc, s[60:61], vcc
	v_max3_f32 v2, v2, v60, v61
	v_cndmask_b32_e32 v15, v3, v164, vcc
	v_max3_f32 v2, v2, v62, v15
	ds_bpermute_b32 v3, v146, v2
	s_mul_i32 s18, s80, 0x2200
	s_waitcnt lgkmcnt(0)
	v_max3_f32 v63, v166, v2, v3
	v_sub_f32_e32 v1, v1, v63
	v_exp_f32_e32 v1, v1
	v_sub_f32_e32 v3, v10, v63
	v_exp_f32_e32 v6, v3
	v_sub_f32_e32 v3, v12, v63
	v_exp_f32_e32 v7, v3
	v_sub_f32_e32 v3, v13, v63
	v_exp_f32_e32 v8, v3
	v_sub_f32_e32 v4, v64, v63
	v_add_f32_e32 v3, 0, v1
	v_exp_f32_e32 v9, v4
	v_sub_f32_e32 v4, v11, v63
	v_add_f32_e32 v3, v6, v3
	v_exp_f32_e32 v10, v4
	v_sub_f32_e32 v4, v65, v63
	v_add_f32_e32 v3, v7, v3
	v_exp_f32_e32 v11, v4
	v_sub_f32_e32 v4, v66, v63
	v_add_f32_e32 v3, v8, v3
	v_exp_f32_e32 v12, v4
	v_sub_f32_e32 v4, v69, v63
	v_add_f32_e32 v3, v9, v3
	v_exp_f32_e32 v64, v4
	v_sub_f32_e32 v4, v68, v63
	v_add_f32_e32 v3, v10, v3
	v_exp_f32_e32 v65, v4
	v_sub_f32_e32 v4, v67, v63
	v_add_f32_e32 v3, v11, v3
	v_exp_f32_e32 v66, v4
	v_sub_f32_e32 v4, v70, v63
	v_add_f32_e32 v3, v12, v3
	v_exp_f32_e32 v67, v4
	v_sub_f32_e32 v4, v71, v63
	v_add_f32_e32 v3, v64, v3
	v_exp_f32_e32 v68, v4
	v_sub_f32_e32 v4, v72, v63
	v_add_f32_e32 v3, v65, v3
	v_exp_f32_e32 v69, v4
	v_sub_f32_e32 v4, v73, v63
	v_add_f32_e32 v3, v66, v3
	v_exp_f32_e32 v70, v4
	v_sub_f32_e32 v4, v74, v63
	v_add_f32_e32 v3, v67, v3
	v_exp_f32_e32 v71, v4
	v_sub_f32_e32 v4, v48, v63
	v_add_f32_e32 v3, v68, v3
	v_exp_f32_e32 v48, v4
	v_sub_f32_e32 v4, v49, v63
	v_add_f32_e32 v3, v69, v3
	v_exp_f32_e32 v49, v4
	v_sub_f32_e32 v4, v50, v63
	v_add_f32_e32 v3, v70, v3
	v_exp_f32_e32 v50, v4
	v_sub_f32_e32 v4, v51, v63
	v_add_f32_e32 v3, v71, v3
	v_exp_f32_e32 v51, v4
	v_sub_f32_e32 v4, v52, v63
	v_add_f32_e32 v3, v48, v3
	v_exp_f32_e32 v52, v4
	v_sub_f32_e32 v4, v53, v63
	v_add_f32_e32 v3, v49, v3
	v_exp_f32_e32 v53, v4
	v_sub_f32_e32 v4, v54, v63
	v_add_f32_e32 v3, v50, v3
	v_exp_f32_e32 v54, v4
	v_add_f32_e32 v3, v51, v3
	v_sub_f32_e32 v2, v166, v63
	v_add_f32_e32 v3, v52, v3
	v_add3_u32 v13, v161, s18, v163
	v_add_f32_e32 v3, v53, v3
	v_exp_f32_e32 v14, v2
	v_sub_f32_e32 v2, v55, v63
	v_add_u32_e32 v73, 0x8800, v13
	v_add_f32_e32 v72, v54, v3
	v_exp_f32_e32 v55, v2
	ds_read2_b64 v[2:5], v73 offset1:2
	v_cvt_pk_bf16_f32 v6, v1, v6
	v_add_u32_e32 v1, 0x9800, v13
	v_cvt_pk_bf16_f32 v7, v7, v8
	v_cvt_pk_bf16_f32 v8, v9, v10
	v_cvt_pk_bf16_f32 v9, v11, v12
	ds_read2_b64 v[10:13], v1 offset0:32 offset1:34
	v_mul_f32_e32 v46, v46, v14
	v_mul_f32_e32 v47, v47, v14
	v_mul_f32_e32 v44, v44, v14
	v_mul_f32_e32 v45, v45, v14
	v_mul_f32_e32 v42, v42, v14
	v_mul_f32_e32 v43, v43, v14
	v_mul_f32_e32 v40, v40, v14
	v_mul_f32_e32 v41, v41, v14
	v_mul_f32_e32 v38, v38, v14
	v_mul_f32_e32 v39, v39, v14
	v_mul_f32_e32 v36, v36, v14
	v_mul_f32_e32 v37, v37, v14
	v_mul_f32_e32 v34, v34, v14
	v_mul_f32_e32 v35, v35, v14
	v_mul_f32_e32 v32, v32, v14
	v_mul_f32_e32 v33, v33, v14
	v_mul_f32_e32 v30, v30, v14
	v_mul_f32_e32 v31, v31, v14
	v_mul_f32_e32 v28, v28, v14
	v_mul_f32_e32 v29, v29, v14
	s_waitcnt lgkmcnt(1)
	v_mfma_f32_32x32x16_bf16 v[32:47], v[2:5], v[6:9], v[32:47]
	ds_read2_b64 v[2:5], v73 offset0:4 offset1:6
	v_mul_f32_e64 v26, v26, v14
	v_mul_f32_e64 v27, v27, v14
	v_mul_f32_e64 v24, v24, v14
	v_mul_f32_e64 v25, v25, v14
	v_mul_f32_e32 v22, v22, v14
	v_mul_f32_e32 v23, v23, v14
	v_mul_f32_e32 v20, v20, v14
	v_mul_f32_e32 v21, v21, v14
	v_mul_f32_e32 v18, v18, v14
	v_mul_f32_e32 v19, v19, v14
	v_mul_f32_e32 v16, v16, v14
	v_mul_f32_e32 v17, v17, v14
	v_mov_b32_e32 v166, v63
	s_waitcnt lgkmcnt(1)
	v_mfma_f32_32x32x16_bf16 v[16:31], v[10:13], v[6:9], v[16:31]
	v_sub_f32_e32 v6, v56, v63
	v_exp_f32_e32 v56, v6
	ds_read2_b64 v[10:13], v1 offset0:36 offset1:38
	v_cvt_pk_bf16_f32 v6, v64, v65
	v_cvt_pk_bf16_f32 v7, v66, v67
	v_cvt_pk_bf16_f32 v8, v68, v69
	v_cvt_pk_bf16_f32 v9, v70, v71
	s_waitcnt lgkmcnt(1)
	s_nop 0
	v_mfma_f32_32x32x16_bf16 v[32:47], v[2:5], v[6:9], v[32:47]
	v_add_f32_e32 v2, v55, v72
	v_add_f32_e32 v64, v56, v2
	v_sub_f32_e32 v2, v57, v63
	v_exp_f32_e32 v57, v2
	v_sub_f32_e32 v2, v58, v63
	v_exp_f32_e32 v58, v2
	ds_read2_b64 v[2:5], v73 offset0:8 offset1:10
	s_waitcnt lgkmcnt(1)
	v_mfma_f32_32x32x16_bf16 v[16:31], v[10:13], v[6:9], v[16:31]
	ds_read2_b64 v[10:13], v1 offset0:40 offset1:42
	v_sub_f32_e32 v6, v59, v63
	v_exp_f32_e32 v59, v6
	v_cvt_pk_bf16_f32 v6, v48, v49
	v_cvt_pk_bf16_f32 v7, v50, v51
	v_cvt_pk_bf16_f32 v8, v52, v53
	v_cvt_pk_bf16_f32 v9, v54, v55
	s_waitcnt lgkmcnt(1)
	s_nop 0
	v_mfma_f32_32x32x16_bf16 v[32:47], v[2:5], v[6:9], v[32:47]
	v_sub_f32_e32 v2, v60, v63
	v_exp_f32_e32 v48, v2
	v_sub_f32_e32 v2, v61, v63
	v_exp_f32_e32 v49, v2
	v_sub_f32_e32 v2, v62, v63
	v_exp_f32_e32 v50, v2
	ds_read2_b64 v[2:5], v73 offset0:12 offset1:14
	s_waitcnt lgkmcnt(1)
	v_mfma_f32_32x32x16_bf16 v[16:31], v[10:13], v[6:9], v[16:31]
	ds_read2_b64 v[10:13], v1 offset0:44 offset1:46
	v_sub_f32_e32 v6, v15, v63
	v_exp_f32_e32 v15, v6
	v_cvt_pk_bf16_f32 v6, v56, v57
	v_cvt_pk_bf16_f32 v7, v58, v59
	v_cvt_pk_bf16_f32 v8, v48, v49
	v_cvt_pk_bf16_f32 v9, v50, v15
	v_add_f32_e32 v1, v57, v64
	v_add_f32_e32 v1, v58, v1
	s_waitcnt lgkmcnt(1)
	v_mfma_f32_32x32x16_bf16 v[32:47], v[2:5], v[6:9], v[32:47]
	v_add_f32_e32 v1, v59, v1
	v_add_f32_e32 v1, v48, v1
	v_add_f32_e32 v1, v49, v1
	v_add_f32_e32 v1, v50, v1
	v_add_f32_e32 v1, v15, v1
	v_fmac_f32_e32 v1, v135, v14
	v_mov_b32_e32 v135, v1
	s_waitcnt lgkmcnt(0)
	v_mfma_f32_32x32x16_bf16 v[16:31], v[10:13], v[6:9], v[16:31]

; #define GAS __attribute__((address_space(1)))
;     __device__ __forceinline__ void operator()(const Acc& acc, const Unit& u, int wr, int wc, int fr, int fq) const {
;         const int row0 = u.pm * BM + wr * 64 + fr, col0 = u.pn * BM + wc * 32 + 8 * fq;
; #pragma unroll
;         for (int ai = 0; ai < 2; ++ai)
; #pragma unroll
;             for (int m = 0; m < 4; ++m) {
;                 const size_t off = (size_t)(row0 + ai * HALF + m * 16) * D + col0;
; #pragma unroll
;                 for (int bj = 0; bj < 2; ++bj) {
;                     const size_t p = off + bj * HALF;
;                     f32x4 b0, b1;
;                     if (BASE_F32) { b0 = *(const GAS f32x4*)((const float*)base + p); b1 = *(const GAS f32x4*)((const float*)base + p + 4); }
;                     else unpack8h(*(const GAS u32x4*)((const bf16_t*)base + p), b0, b1);
;                     b0 += acc[ai][bj][m][0]; b1 += acc[ai][bj][m][1];
;                     if (OUT_F32) { *(GAS f32x4*)((float*)out + p) = b0; *(GAS f32x4*)((float*)out + p + 4) = b1; }
;                     else *(GAS u32x4*)((bf16_t*)out + p) = pack8h(b0, b1);
;                 }
;                 asm volatile("" ::: "memory");
;             }
.LBB0_352:
	v_mov_b32_e32 v140, v143
	s_lshl_b32 s25, s34, 8
	s_add_i32 s25, s25, s55
	v_and_or_b32 v156, v140, 15, s25
	s_lshl_b32 s25, s63, 8
	v_ashrrev_i32_e32 v140, 1, v140
	s_or_b32 s25, s25, s56
	v_and_b32_e32 v140, -8, v140
	v_add_u32_e32 v158, s25, v140
	v_ashrrev_i32_e32 v157, 31, v156
	v_ashrrev_i32_e32 v159, 31, v158
	v_lshlrev_b64 v[140:141], 10, v[156:157]
	v_lshl_add_u64 v[140:141], v[140:141], 0, v[158:159]
	v_lshl_add_u64 v[160:161], v[140:141], 2, s[6:7]
	global_load_dwordx4 v[148:151], v[160:161], off
	global_load_dwordx4 v[152:155], v[160:161], off offset:16
	v_lshl_add_u64 v[162:163], v[140:141], 1, s[12:13]
	s_andn2_b64 vcc, exec, s[2:3]
	s_mov_b64 s[2:3], -1
	s_waitcnt vmcnt(0)
	v_add_f32_e32 v126, v126, v150
	v_add_f32_e32 v127, v127, v151
	v_add_f32_e32 v124, v124, v148
	v_add_f32_e32 v125, v125, v149
	v_add_f32_e32 v122, v122, v154
	v_add_f32_e32 v123, v123, v155
	v_add_f32_e32 v148, v120, v152
	v_add_f32_e32 v149, v121, v153
	v_cvt_pk_f16_f32 v123, v122, v123
	v_cvt_pk_f16_f32 v121, v126, v127
	v_cvt_pk_f16_f32 v122, v148, v149
	v_cvt_pk_f16_f32 v120, v124, v125
	global_store_dwordx4 v[162:163], v[120:123], off
	global_load_dwordx4 v[120:123], v[160:161], off offset:512
	s_nop 0
	global_load_dwordx4 v[124:127], v[160:161], off offset:528
	v_or_b32_e32 v148, 16, v156
	v_ashrrev_i32_e32 v149, 31, v148
	v_lshlrev_b64 v[148:149], 10, v[148:149]
	v_lshl_add_u64 v[148:149], v[148:149], 0, v[158:159]
	v_lshl_add_u64 v[150:151], v[148:149], 2, s[6:7]
	s_waitcnt vmcnt(1)
	v_add_f32_e32 v118, v118, v122
	v_add_f32_e32 v119, v119, v123
	v_add_f32_e32 v116, v116, v120
	v_add_f32_e32 v117, v117, v121
	s_waitcnt vmcnt(0)
	v_add_f32_e32 v114, v114, v126
	v_add_f32_e32 v115, v115, v127
	v_add_f32_e32 v120, v112, v124
	v_add_f32_e32 v121, v113, v125
	v_cvt_pk_f16_f32 v115, v114, v115
	v_cvt_pk_f16_f32 v113, v118, v119
	v_cvt_pk_f16_f32 v114, v120, v121
	v_cvt_pk_f16_f32 v112, v116, v117
	global_store_dwordx4 v[162:163], v[112:115], off offset:256
	global_load_dwordx4 v[112:115], v[150:151], off
	global_load_dwordx4 v[116:119], v[150:151], off offset:16
	v_lshl_add_u64 v[120:121], v[148:149], 1, s[12:13]
	s_waitcnt vmcnt(1)
	v_add_f32_e32 v110, v110, v114
	v_add_f32_e32 v111, v111, v115
	v_add_f32_e32 v108, v108, v112
	v_add_f32_e32 v109, v109, v113
	s_waitcnt vmcnt(0)
	v_add_f32_e32 v106, v106, v118
	v_add_f32_e32 v107, v107, v119
	v_add_f32_e32 v112, v104, v116
	v_add_f32_e32 v113, v105, v117
	v_cvt_pk_f16_f32 v107, v106, v107
	v_cvt_pk_f16_f32 v105, v110, v111
	v_cvt_pk_f16_f32 v106, v112, v113
	v_cvt_pk_f16_f32 v104, v108, v109
	global_store_dwordx4 v[120:121], v[104:107], off
	global_load_dwordx4 v[104:107], v[150:151], off offset:512
	s_nop 0
	global_load_dwordx4 v[108:111], v[150:151], off offset:528
	v_or_b32_e32 v112, 32, v156
	v_ashrrev_i32_e32 v113, 31, v112
	v_lshlrev_b64 v[112:113], 10, v[112:113]
	v_lshl_add_u64 v[112:113], v[112:113], 0, v[158:159]
	v_lshl_add_u64 v[114:115], v[112:113], 2, s[6:7]
	s_waitcnt vmcnt(1)
	v_add_f32_e32 v102, v102, v106
	v_add_f32_e32 v103, v103, v107
	v_add_f32_e32 v100, v100, v104
	v_add_f32_e32 v101, v101, v105
	s_waitcnt vmcnt(0)
	v_add_f32_e32 v98, v98, v110
	v_add_f32_e32 v99, v99, v111
	v_add_f32_e32 v104, v96, v108
	v_add_f32_e32 v105, v97, v109
	v_cvt_pk_f16_f32 v99, v98, v99
	v_cvt_pk_f16_f32 v97, v102, v103
	v_cvt_pk_f16_f32 v98, v104, v105
	v_cvt_pk_f16_f32 v96, v100, v101
	global_store_dwordx4 v[120:121], v[96:99], off offset:256
	global_load_dwordx4 v[96:99], v[114:115], off
	global_load_dwordx4 v[100:103], v[114:115], off offset:16
	v_lshl_add_u64 v[104:105], v[112:113], 1, s[12:13]
	s_waitcnt vmcnt(1)
	v_add_f32_e32 v94, v94, v98
	v_add_f32_e32 v95, v95, v99
	v_add_f32_e32 v92, v92, v96
	v_add_f32_e32 v93, v93, v97
	s_waitcnt vmcnt(0)
	v_add_f32_e32 v90, v90, v102
	v_add_f32_e32 v91, v91, v103
	v_add_f32_e32 v96, v88, v100
	v_add_f32_e32 v97, v89, v101
	v_cvt_pk_f16_f32 v91, v90, v91
	v_cvt_pk_f16_f32 v89, v94, v95
	v_cvt_pk_f16_f32 v90, v96, v97
	v_cvt_pk_f16_f32 v88, v92, v93
	global_store_dwordx4 v[104:105], v[88:91], off
	global_load_dwordx4 v[88:91], v[114:115], off offset:512
	s_nop 0
	global_load_dwordx4 v[92:95], v[114:115], off offset:528
	v_or_b32_e32 v96, 48, v156
	v_ashrrev_i32_e32 v97, 31, v96
	v_lshlrev_b64 v[96:97], 10, v[96:97]
	v_lshl_add_u64 v[96:97], v[96:97], 0, v[158:159]
	v_lshl_add_u64 v[98:99], v[96:97], 2, s[6:7]
	s_waitcnt vmcnt(1)
	v_add_f32_e32 v86, v86, v90
	v_add_f32_e32 v87, v87, v91
	v_add_f32_e32 v84, v84, v88
	v_add_f32_e32 v85, v85, v89
	s_waitcnt vmcnt(0)
	v_add_f32_e32 v82, v82, v94
	v_add_f32_e32 v83, v83, v95
	v_add_f32_e32 v88, v80, v92
	v_add_f32_e32 v89, v81, v93
	v_cvt_pk_f16_f32 v83, v82, v83
	v_cvt_pk_f16_f32 v81, v86, v87
	v_cvt_pk_f16_f32 v82, v88, v89
	v_cvt_pk_f16_f32 v80, v84, v85
	global_store_dwordx4 v[104:105], v[80:83], off offset:256
	global_load_dwordx4 v[80:83], v[98:99], off
	global_load_dwordx4 v[84:87], v[98:99], off offset:16
	v_lshl_add_u64 v[88:89], v[96:97], 1, s[12:13]
	s_waitcnt vmcnt(1)
	v_add_f32_e32 v78, v78, v82
	v_add_f32_e32 v79, v79, v83
	v_add_f32_e32 v76, v76, v80
	v_add_f32_e32 v77, v77, v81
	s_waitcnt vmcnt(0)
	v_add_f32_e32 v74, v74, v86
	v_add_f32_e32 v75, v75, v87
	v_add_f32_e32 v80, v72, v84
	v_add_f32_e32 v81, v73, v85
	v_cvt_pk_f16_f32 v75, v74, v75
	v_cvt_pk_f16_f32 v73, v78, v79
	v_cvt_pk_f16_f32 v74, v80, v81
	v_cvt_pk_f16_f32 v72, v76, v77
	global_store_dwordx4 v[88:89], v[72:75], off
	global_load_dwordx4 v[72:75], v[98:99], off offset:512
	s_nop 0
	global_load_dwordx4 v[76:79], v[98:99], off offset:528
	v_lshl_add_u64 v[80:81], v[140:141], 0, s[14:15]
	v_lshl_add_u64 v[82:83], v[80:81], 2, s[6:7]
	s_waitcnt vmcnt(1)
; #define GAS __attribute__((address_space(1)))
;     __device__ __forceinline__ void operator()(const Acc& acc, const Unit& u, int wr, int wc, int fr, int fq) const {
;         const int row0 = u.pm * BM + wr * 64 + fr, col0 = u.pn * BM + wc * 32 + 8 * fq;
; #pragma unroll
;         for (int ai = 0; ai < 2; ++ai)
; #pragma unroll
;             for (int m = 0; m < 4; ++m) {
;                 const size_t off = (size_t)(row0 + ai * HALF + m * 16) * D + col0;
; #pragma unroll
;                 for (int bj = 0; bj < 2; ++bj) {
;                     const size_t p = off + bj * HALF;
;                     f32x4 b0, b1;
;                     if (BASE_F32) { b0 = *(const GAS f32x4*)((const float*)base + p); b1 = *(const GAS f32x4*)((const float*)base + p + 4); }
;                     else unpack8h(*(const GAS u32x4*)((const bf16_t*)base + p), b0, b1);
;                     b0 += acc[ai][bj][m][0]; b1 += acc[ai][bj][m][1];
;                     if (OUT_F32) { *(GAS f32x4*)((float*)out + p) = b0; *(GAS f32x4*)((float*)out + p + 4) = b1; }
;                     else *(GAS u32x4*)((bf16_t*)out + p) = pack8h(b0, b1);
;                 }
;                 asm volatile("" ::: "memory");
;             }
	v_add_f32_e32 v70, v70, v74
	v_add_f32_e32 v71, v71, v75
	v_add_f32_e32 v68, v68, v72
	v_add_f32_e32 v69, v69, v73
	s_waitcnt vmcnt(0)
	v_add_f32_e32 v66, v66, v78
	v_add_f32_e32 v67, v67, v79
	v_add_f32_e32 v72, v64, v76
	v_add_f32_e32 v73, v65, v77
	v_cvt_pk_f16_f32 v67, v66, v67
	v_cvt_pk_f16_f32 v65, v70, v71
	v_cvt_pk_f16_f32 v66, v72, v73
	v_cvt_pk_f16_f32 v64, v68, v69
	global_store_dwordx4 v[88:89], v[64:67], off offset:256
	global_load_dwordx4 v[64:67], v[82:83], off
	global_load_dwordx4 v[68:71], v[82:83], off offset:16
	v_lshl_add_u64 v[72:73], v[80:81], 1, s[12:13]
	s_waitcnt vmcnt(1)
	v_add_f32_e32 v62, v62, v66
	v_add_f32_e32 v63, v63, v67
	v_add_f32_e32 v60, v60, v64
	v_add_f32_e32 v61, v61, v65
	s_waitcnt vmcnt(0)
	v_add_f32_e32 v58, v58, v70
	v_add_f32_e32 v59, v59, v71
	v_add_f32_e32 v64, v56, v68
	v_add_f32_e32 v65, v57, v69
	v_cvt_pk_f16_f32 v59, v58, v59
	v_cvt_pk_f16_f32 v57, v62, v63
	v_cvt_pk_f16_f32 v58, v64, v65
	v_cvt_pk_f16_f32 v56, v60, v61
	global_store_dwordx4 v[72:73], v[56:59], off
	global_load_dwordx4 v[56:59], v[82:83], off offset:512
	s_nop 0
	global_load_dwordx4 v[60:63], v[82:83], off offset:528
	v_lshl_add_u64 v[64:65], v[140:141], 0, s[16:17]
	v_lshl_add_u64 v[66:67], v[64:65], 2, s[6:7]
	s_waitcnt vmcnt(1)
	v_add_f32_e32 v54, v54, v58
	v_add_f32_e32 v55, v55, v59
	v_add_f32_e32 v52, v52, v56
	v_add_f32_e32 v53, v53, v57
	s_waitcnt vmcnt(0)
	v_add_f32_e32 v50, v50, v62
	v_add_f32_e32 v51, v51, v63
	v_add_f32_e32 v56, v48, v60
	v_add_f32_e32 v57, v49, v61
	v_cvt_pk_f16_f32 v51, v50, v51
	v_cvt_pk_f16_f32 v49, v54, v55
	v_cvt_pk_f16_f32 v50, v56, v57
	v_cvt_pk_f16_f32 v48, v52, v53
	global_store_dwordx4 v[72:73], v[48:51], off offset:256
	global_load_dwordx4 v[48:51], v[66:67], off
	global_load_dwordx4 v[52:55], v[66:67], off offset:16
	v_lshl_add_u64 v[56:57], v[64:65], 1, s[12:13]
	s_waitcnt vmcnt(1)
	v_add_f32_e32 v46, v46, v50
	v_add_f32_e32 v47, v47, v51
	v_add_f32_e32 v44, v44, v48
	v_add_f32_e32 v45, v45, v49
	s_waitcnt vmcnt(0)
	v_add_f32_e32 v42, v42, v54
	v_add_f32_e32 v43, v43, v55
	v_add_f32_e32 v48, v40, v52
	v_add_f32_e32 v49, v41, v53
	v_cvt_pk_f16_f32 v43, v42, v43
	v_cvt_pk_f16_f32 v41, v46, v47
	v_cvt_pk_f16_f32 v42, v48, v49
	v_cvt_pk_f16_f32 v40, v44, v45
	global_store_dwordx4 v[56:57], v[40:43], off
	global_load_dwordx4 v[40:43], v[66:67], off offset:512
	s_nop 0
	global_load_dwordx4 v[44:47], v[66:67], off offset:528
	v_lshl_add_u64 v[48:49], v[140:141], 0, s[18:19]
	v_lshl_add_u64 v[50:51], v[48:49], 2, s[6:7]
	s_waitcnt vmcnt(1)
	v_add_f32_e32 v38, v38, v42
	v_add_f32_e32 v39, v39, v43
	v_add_f32_e32 v36, v36, v40
	v_add_f32_e32 v37, v37, v41
	s_waitcnt vmcnt(0)
	v_add_f32_e32 v34, v34, v46
	v_add_f32_e32 v35, v35, v47
	v_add_f32_e32 v40, v32, v44
	v_add_f32_e32 v41, v33, v45
	v_cvt_pk_f16_f32 v35, v34, v35
	v_cvt_pk_f16_f32 v33, v38, v39
	v_cvt_pk_f16_f32 v34, v40, v41
	v_cvt_pk_f16_f32 v32, v36, v37
	global_store_dwordx4 v[56:57], v[32:35], off offset:256
	global_load_dwordx4 v[32:35], v[50:51], off
	global_load_dwordx4 v[36:39], v[50:51], off offset:16
	v_lshl_add_u64 v[40:41], v[48:49], 1, s[12:13]
	s_waitcnt vmcnt(1)
	v_add_f32_e32 v30, v30, v34
	v_add_f32_e32 v31, v31, v35
	v_add_f32_e32 v28, v28, v32
	v_add_f32_e32 v29, v29, v33
	s_waitcnt vmcnt(0)
	v_add_f32_e32 v26, v26, v38
	v_add_f32_e32 v27, v27, v39
	v_add_f32_e32 v32, v24, v36
	v_add_f32_e32 v33, v25, v37
	v_cvt_pk_f16_f32 v27, v26, v27
	v_cvt_pk_f16_f32 v25, v30, v31
	v_cvt_pk_f16_f32 v26, v32, v33
	v_cvt_pk_f16_f32 v24, v28, v29
	global_store_dwordx4 v[40:41], v[24:27], off
	global_load_dwordx4 v[24:27], v[50:51], off offset:512
	s_nop 0
	global_load_dwordx4 v[28:31], v[50:51], off offset:528
	v_lshl_add_u64 v[32:33], v[140:141], 0, s[20:21]
	v_lshl_add_u64 v[34:35], v[32:33], 2, s[6:7]
	s_waitcnt vmcnt(1)
	v_add_f32_e32 v22, v22, v26
	v_add_f32_e32 v23, v23, v27
	v_add_f32_e32 v20, v20, v24
	v_add_f32_e32 v21, v21, v25
	s_waitcnt vmcnt(0)
	v_add_f32_e32 v18, v18, v30
	v_add_f32_e32 v19, v19, v31
	v_add_f32_e32 v24, v16, v28
	v_add_f32_e32 v25, v17, v29
	v_cvt_pk_f16_f32 v19, v18, v19
	v_cvt_pk_f16_f32 v17, v22, v23
	v_cvt_pk_f16_f32 v18, v24, v25
	v_cvt_pk_f16_f32 v16, v20, v21
	global_store_dwordx4 v[40:41], v[16:19], off offset:256
	global_load_dwordx4 v[16:19], v[34:35], off
	global_load_dwordx4 v[20:23], v[34:35], off offset:16
	v_lshl_add_u64 v[24:25], v[32:33], 1, s[12:13]
	s_waitcnt vmcnt(1)
	v_add_f32_e32 v14, v14, v18
	v_add_f32_e32 v15, v15, v19
	v_add_f32_e32 v12, v12, v16
	v_add_f32_e32 v13, v13, v17
	s_waitcnt vmcnt(0)
	v_add_f32_e32 v10, v10, v22
	v_add_f32_e32 v11, v11, v23
	v_add_f32_e32 v16, v8, v20
	v_add_f32_e32 v17, v9, v21
	v_cvt_pk_f16_f32 v11, v10, v11
	v_cvt_pk_f16_f32 v9, v14, v15
	v_cvt_pk_f16_f32 v10, v16, v17
	v_cvt_pk_f16_f32 v8, v12, v13
	global_store_dwordx4 v[24:25], v[8:11], off
	global_load_dwordx4 v[8:11], v[34:35], off offset:512
	s_nop 0
	global_load_dwordx4 v[12:15], v[34:35], off offset:528
	s_waitcnt vmcnt(1)
	v_add_f32_e32 v6, v6, v10
	v_add_f32_e32 v7, v7, v11
	v_add_f32_e32 v4, v4, v8
	v_add_f32_e32 v5, v5, v9
	s_waitcnt vmcnt(0)
	v_add_f32_e32 v2, v2, v14
	v_add_f32_e32 v3, v3, v15
	v_add_f32_e32 v8, v0, v12
	v_add_f32_e32 v9, v1, v13
	v_cvt_pk_f16_f32 v3, v2, v3
	v_cvt_pk_f16_f32 v1, v6, v7
	v_cvt_pk_f16_f32 v2, v8, v9
	v_cvt_pk_f16_f32 v0, v4, v5
	global_store_dwordx4 v[24:25], v[0:3], off offset:256
	s_cbranch_vccnz .LBB0_341
	s_andn2_b64 vcc, exec, s[8:9]
	s_cbranch_vccnz .LBB0_340
	s_barrier
	s_branch .LBB0_340

; #define GAS __attribute__((address_space(1)))
; template <int MODE, bool XBF>
; __device__ __forceinline__ void rmsnorm_rows(const void* x, const float* gain, bf16_t* H, int gw, int NGW, int lane, const LAS float* WF, const float* fbias, float* LF) {
;     ...
;     for (int row0 = gw * RB; row0 < T; row0 += NGW * RB) {
;         f32x4 v[RB][2][2]; float s[RB];
; #pragma unroll
;         for (int r = 0; r < RB; ++r)
; #pragma unroll
;             for (int j = 0; j < 2; ++j) { const size_t xo = (size_t)(row0 + r) * D + 512 * j + lane * 8;
;                 if (XBF) unpack8h(*(const GAS u32x4*)((const bf16_t*)x + xo), v[r][j][0], v[r][j][1]);
;                 else { v[r][j][0] = *(const GAS f32x4*)((const float*)x + xo); v[r][j][1] = *(const GAS f32x4*)((const float*)x + xo + 4); } }
.LBB0_421:
	v_lshl_add_u64 v[18:19], s[28:29], 0, v[16:17]
	v_add_co_u32_e64 v36, s[2:3], s19, v18
	v_add_co_u32_e32 v30, vcc, 0x5800000, v18
	s_nop 0
	v_addc_co_u32_e64 v37, s[2:3], 0, v19, s[2:3]
	v_add_co_u32_e64 v38, s[2:3], s21, v18
	v_addc_co_u32_e32 v31, vcc, 0, v19, vcc
	s_nop 0
	v_addc_co_u32_e64 v39, s[2:3], 0, v19, s[2:3]
	v_add_co_u32_e64 v44, s[2:3], s23, v18
	v_lshl_add_u64 v[26:27], s[24:25], 0, v[16:17]
	s_nop 0
	v_addc_co_u32_e64 v45, s[2:3], 0, v19, s[2:3]
	global_load_dwordx4 v[32:35], v[38:39], off offset:-4096
	global_load_dwordx4 v[40:43], v[36:37], off offset:1024
	global_load_dwordx4 v[48:51], v[36:37], off offset:2048
	global_load_dwordx4 v[56:59], v[36:37], off offset:3072
	global_load_dwordx4 v[64:67], v[38:39], off
	global_load_dwordx4 v[72:75], v[38:39], off offset:1024
	global_load_dwordx4 v[80:83], v[38:39], off offset:2048
	global_load_dwordx4 v[88:91], v[38:39], off offset:3072
	global_load_dwordx4 v[96:99], v[44:45], off
	global_load_dwordx4 v[104:107], v[44:45], off offset:1024
	global_load_dwordx4 v[112:115], v[44:45], off offset:2048
	global_load_dwordx4 v[120:123], v[44:45], off offset:3072
	global_load_dwordx4 v[128:131], v[30:31], off
	global_load_dwordx4 v[136:139], v[30:31], off offset:1024
	global_load_dwordx4 v[144:147], v[30:31], off offset:2048
	global_load_dwordx4 v[152:155], v[30:31], off offset:3072
	v_add_co_u32_e64 v22, s[2:3], s35, v26
	v_mov_b64_e32 v[20:21], s[34:35]
	s_nop 0
	v_addc_co_u32_e64 v23, s[2:3], 0, v27, s[2:3]
	v_add_co_u32_e64 v24, s[2:3], s38, v26
	s_add_i32 s18, s18, s20
	s_nop 0
	v_addc_co_u32_e64 v25, s[2:3], 0, v27, s[2:3]
	v_add_co_u32_e64 v28, s[2:3], s39, v26
	s_add_u32 s24, s24, s26
	s_nop 0
	v_addc_co_u32_e64 v29, s[2:3], 0, v27, s[2:3]
	v_add_co_u32_e64 v26, s[2:3], s40, v26
	s_addc_u32 s25, s25, s27
	s_nop 0
	v_addc_co_u32_e64 v27, s[2:3], 0, v27, s[2:3]
	s_add_u32 s28, s28, s26
	s_addc_u32 s29, s29, s27
	s_cmp_lt_i32 s18, 0x8000
	s_waitcnt vmcnt(0)
	v_cvt_f32_f16_e32 v18, v32
	v_cvt_f32_f16_sdwa v19, v32 dst_sel:DWORD dst_unused:UNUSED_PAD src0_sel:WORD_1
	v_cvt_f32_f16_e32 v30, v33
	v_cvt_f32_f16_sdwa v31, v33 dst_sel:DWORD dst_unused:UNUSED_PAD src0_sel:WORD_1
	v_cvt_f32_f16_e32 v32, v34
	v_cvt_f32_f16_sdwa v33, v34 dst_sel:DWORD dst_unused:UNUSED_PAD src0_sel:WORD_1
	v_cvt_f32_f16_e32 v34, v35
	v_cvt_f32_f16_sdwa v35, v35 dst_sel:DWORD dst_unused:UNUSED_PAD src0_sel:WORD_1
	v_cvt_f32_f16_e32 v36, v40
	v_cvt_f32_f16_sdwa v37, v40 dst_sel:DWORD dst_unused:UNUSED_PAD src0_sel:WORD_1
	v_cvt_f32_f16_e32 v40, v41
	v_cvt_f32_f16_e32 v44, v48
	v_cvt_f32_f16_sdwa v45, v48 dst_sel:DWORD dst_unused:UNUSED_PAD src0_sel:WORD_1
	v_cvt_f32_f16_e32 v46, v49
	v_cvt_f32_f16_sdwa v47, v49 dst_sel:DWORD dst_unused:UNUSED_PAD src0_sel:WORD_1
	v_cvt_f32_f16_e32 v48, v50
	v_cvt_f32_f16_sdwa v49, v50 dst_sel:DWORD dst_unused:UNUSED_PAD src0_sel:WORD_1
	v_cvt_f32_f16_e32 v50, v51
	v_cvt_f32_f16_sdwa v51, v51 dst_sel:DWORD dst_unused:UNUSED_PAD src0_sel:WORD_1
	v_cvt_f32_f16_sdwa v41, v41 dst_sel:DWORD dst_unused:UNUSED_PAD src0_sel:WORD_1
	v_cvt_f32_f16_e32 v52, v56
	v_cvt_f32_f16_sdwa v53, v56 dst_sel:DWORD dst_unused:UNUSED_PAD src0_sel:WORD_1
	v_cvt_f32_f16_e32 v56, v57
	v_cvt_f32_f16_e32 v60, v64
	v_cvt_f32_f16_sdwa v61, v64 dst_sel:DWORD dst_unused:UNUSED_PAD src0_sel:WORD_1
	v_cvt_f32_f16_e32 v62, v65
	v_cvt_f32_f16_sdwa v63, v65 dst_sel:DWORD dst_unused:UNUSED_PAD src0_sel:WORD_1
	v_cvt_f32_f16_e32 v64, v66
	v_cvt_f32_f16_sdwa v65, v66 dst_sel:DWORD dst_unused:UNUSED_PAD src0_sel:WORD_1
	v_cvt_f32_f16_e32 v66, v67
	v_cvt_f32_f16_sdwa v67, v67 dst_sel:DWORD dst_unused:UNUSED_PAD src0_sel:WORD_1
	v_cvt_f32_f16_e32 v68, v72
	v_cvt_f32_f16_sdwa v69, v72 dst_sel:DWORD dst_unused:UNUSED_PAD src0_sel:WORD_1
	v_cvt_f32_f16_e32 v72, v73
	v_cvt_f32_f16_e32 v76, v80
	v_cvt_f32_f16_sdwa v77, v80 dst_sel:DWORD dst_unused:UNUSED_PAD src0_sel:WORD_1
	v_cvt_f32_f16_e32 v78, v81
	v_cvt_f32_f16_sdwa v79, v81 dst_sel:DWORD dst_unused:UNUSED_PAD src0_sel:WORD_1
	v_cvt_f32_f16_e32 v80, v82
	v_cvt_f32_f16_sdwa v81, v82 dst_sel:DWORD dst_unused:UNUSED_PAD src0_sel:WORD_1
	v_cvt_f32_f16_e32 v82, v83
	v_cvt_f32_f16_sdwa v83, v83 dst_sel:DWORD dst_unused:UNUSED_PAD src0_sel:WORD_1
	v_cvt_f32_f16_e32 v84, v88
	v_cvt_f32_f16_sdwa v85, v88 dst_sel:DWORD dst_unused:UNUSED_PAD src0_sel:WORD_1
	v_cvt_f32_f16_e32 v88, v89
	v_cvt_f32_f16_e32 v92, v96
	v_cvt_f32_f16_sdwa v93, v96 dst_sel:DWORD dst_unused:UNUSED_PAD src0_sel:WORD_1
	v_cvt_f32_f16_e32 v94, v97
	v_cvt_f32_f16_sdwa v95, v97 dst_sel:DWORD dst_unused:UNUSED_PAD src0_sel:WORD_1
	v_cvt_f32_f16_e32 v96, v98
	v_cvt_f32_f16_sdwa v97, v98 dst_sel:DWORD dst_unused:UNUSED_PAD src0_sel:WORD_1
	v_cvt_f32_f16_e32 v98, v99
	v_cvt_f32_f16_sdwa v99, v99 dst_sel:DWORD dst_unused:UNUSED_PAD src0_sel:WORD_1
	v_cvt_f32_f16_e32 v108, v112
	v_cvt_f32_f16_sdwa v109, v112 dst_sel:DWORD dst_unused:UNUSED_PAD src0_sel:WORD_1
	v_cvt_f32_f16_e32 v110, v113
	v_cvt_f32_f16_sdwa v111, v113 dst_sel:DWORD dst_unused:UNUSED_PAD src0_sel:WORD_1
	v_cvt_f32_f16_e32 v112, v114
	v_cvt_f32_f16_sdwa v113, v114 dst_sel:DWORD dst_unused:UNUSED_PAD src0_sel:WORD_1
	v_cvt_f32_f16_e32 v114, v115
	v_cvt_f32_f16_sdwa v115, v115 dst_sel:DWORD dst_unused:UNUSED_PAD src0_sel:WORD_1
	v_cvt_f32_f16_e32 v124, v128
	v_cvt_f32_f16_sdwa v125, v128 dst_sel:DWORD dst_unused:UNUSED_PAD src0_sel:WORD_1
	v_cvt_f32_f16_e32 v126, v129
	v_cvt_f32_f16_sdwa v127, v129 dst_sel:DWORD dst_unused:UNUSED_PAD src0_sel:WORD_1
	v_cvt_f32_f16_e32 v128, v130
	v_cvt_f32_f16_sdwa v129, v130 dst_sel:DWORD dst_unused:UNUSED_PAD src0_sel:WORD_1
	v_cvt_f32_f16_e32 v130, v131
	v_cvt_f32_f16_sdwa v131, v131 dst_sel:DWORD dst_unused:UNUSED_PAD src0_sel:WORD_1
; #define GAS __attribute__((address_space(1)))
; template <int MODE, bool XBF>
; __device__ __forceinline__ void rmsnorm_rows(const void* x, const float* gain, bf16_t* H, int gw, int NGW, int lane, const LAS float* WF, const float* fbias, float* LF) {
;     ...
;                 if (XBF) unpack8h(*(const GAS u32x4*)((const bf16_t*)x + xo), v[r][j][0], v[r][j][1]);
;                 else { v[r][j][0] = *(const GAS f32x4*)((const float*)x + xo); v[r][j][1] = *(const GAS f32x4*)((const float*)x + xo + 4); } }
; #pragma unroll
;         for (int r = 0; r < RB; ++r) { s[r] = 0.f;
; #pragma unroll
;             for (int j = 0; j < 2; ++j)
; #pragma unroll
;                 for (int e = 0; e < 2; ++e) s[r] += (v[r][j][e][0] * v[r][j][e][0] + v[r][j][e][1] * v[r][j][e][1]) + (v[r][j][e][2] * v[r][j][e][2] + v[r][j][e][3] * v[r][j][e][3]); }
	v_cvt_f32_f16_e32 v140, v144
	v_cvt_f32_f16_sdwa v141, v144 dst_sel:DWORD dst_unused:UNUSED_PAD src0_sel:WORD_1
	v_cvt_f32_f16_e32 v142, v145
	v_cvt_f32_f16_sdwa v143, v145 dst_sel:DWORD dst_unused:UNUSED_PAD src0_sel:WORD_1
	v_cvt_f32_f16_e32 v144, v146
	v_cvt_f32_f16_sdwa v145, v146 dst_sel:DWORD dst_unused:UNUSED_PAD src0_sel:WORD_1
	v_cvt_f32_f16_e32 v146, v147
	v_cvt_f32_f16_sdwa v147, v147 dst_sel:DWORD dst_unused:UNUSED_PAD src0_sel:WORD_1
	v_cvt_f32_f16_sdwa v39, v43 dst_sel:DWORD dst_unused:UNUSED_PAD src0_sel:WORD_1
	v_cvt_f32_f16_e32 v38, v43
	v_cvt_f32_f16_sdwa v57, v57 dst_sel:DWORD dst_unused:UNUSED_PAD src0_sel:WORD_1
	v_cvt_f32_f16_sdwa v73, v73 dst_sel:DWORD dst_unused:UNUSED_PAD src0_sel:WORD_1
	v_cvt_f32_f16_sdwa v89, v89 dst_sel:DWORD dst_unused:UNUSED_PAD src0_sel:WORD_1
	v_cvt_f32_f16_sdwa v55, v59 dst_sel:DWORD dst_unused:UNUSED_PAD src0_sel:WORD_1
	v_cvt_f32_f16_e32 v54, v59
	v_cvt_f32_f16_sdwa v71, v75 dst_sel:DWORD dst_unused:UNUSED_PAD src0_sel:WORD_1
	v_cvt_f32_f16_e32 v70, v75
	v_cvt_f32_f16_sdwa v87, v91 dst_sel:DWORD dst_unused:UNUSED_PAD src0_sel:WORD_1
	v_cvt_f32_f16_e32 v86, v91
	v_cvt_f32_f16_e32 v100, v104
	v_cvt_f32_f16_sdwa v101, v104 dst_sel:DWORD dst_unused:UNUSED_PAD src0_sel:WORD_1
	v_cvt_f32_f16_e32 v104, v105
	v_cvt_f32_f16_e32 v116, v120
	v_cvt_f32_f16_sdwa v117, v120 dst_sel:DWORD dst_unused:UNUSED_PAD src0_sel:WORD_1
	v_cvt_f32_f16_e32 v120, v121
	v_cvt_f32_f16_e32 v132, v136
	v_cvt_f32_f16_sdwa v133, v136 dst_sel:DWORD dst_unused:UNUSED_PAD src0_sel:WORD_1
	v_cvt_f32_f16_e32 v136, v137
	v_cvt_f32_f16_e32 v148, v152
	v_cvt_f32_f16_sdwa v149, v152 dst_sel:DWORD dst_unused:UNUSED_PAD src0_sel:WORD_1
	v_cvt_f32_f16_e32 v152, v153
	v_cvt_f32_f16_sdwa v43, v42 dst_sel:DWORD dst_unused:UNUSED_PAD src0_sel:WORD_1
	v_cvt_f32_f16_e32 v42, v42
	v_cvt_f32_f16_sdwa v59, v58 dst_sel:DWORD dst_unused:UNUSED_PAD src0_sel:WORD_1
	v_cvt_f32_f16_e32 v58, v58
	v_cvt_f32_f16_sdwa v105, v105 dst_sel:DWORD dst_unused:UNUSED_PAD src0_sel:WORD_1
	v_cvt_f32_f16_sdwa v121, v121 dst_sel:DWORD dst_unused:UNUSED_PAD src0_sel:WORD_1
	v_cvt_f32_f16_sdwa v137, v137 dst_sel:DWORD dst_unused:UNUSED_PAD src0_sel:WORD_1
	v_cvt_f32_f16_sdwa v153, v153 dst_sel:DWORD dst_unused:UNUSED_PAD src0_sel:WORD_1
	v_mul_f32_e32 v164, v30, v30
	v_mul_f32_e32 v165, v31, v31
	v_mul_f32_e32 v166, v18, v18
	v_mul_f32_e32 v167, v19, v19
	v_mul_f32_e32 v168, v34, v34
	v_mul_f32_e32 v169, v35, v35
	v_mul_f32_e32 v170, v32, v32
	v_mul_f32_e32 v171, v33, v33
	v_mul_f32_e32 v172, v36, v36
	v_mul_f32_e32 v174, v40, v40
	v_mul_f32_e32 v176, v46, v46
	v_mul_f32_e32 v177, v47, v47
	v_mul_f32_e32 v178, v44, v44
	v_mul_f32_e32 v179, v45, v45
	v_mul_f32_e32 v180, v50, v50
	v_mul_f32_e32 v181, v51, v51
	v_mul_f32_e32 v182, v48, v48
	v_mul_f32_e32 v183, v49, v49
	v_cvt_f32_f16_sdwa v75, v74 dst_sel:DWORD dst_unused:UNUSED_PAD src0_sel:WORD_1
	v_cvt_f32_f16_e32 v74, v74
	v_cvt_f32_f16_sdwa v91, v90 dst_sel:DWORD dst_unused:UNUSED_PAD src0_sel:WORD_1
	v_cvt_f32_f16_e32 v90, v90
	v_cvt_f32_f16_sdwa v103, v107 dst_sel:DWORD dst_unused:UNUSED_PAD src0_sel:WORD_1
	v_cvt_f32_f16_e32 v102, v107
	v_cvt_f32_f16_sdwa v107, v106 dst_sel:DWORD dst_unused:UNUSED_PAD src0_sel:WORD_1
	v_cvt_f32_f16_e32 v106, v106
	v_cvt_f32_f16_sdwa v119, v123 dst_sel:DWORD dst_unused:UNUSED_PAD src0_sel:WORD_1
	v_cvt_f32_f16_e32 v118, v123
	v_cvt_f32_f16_sdwa v123, v122 dst_sel:DWORD dst_unused:UNUSED_PAD src0_sel:WORD_1
	v_cvt_f32_f16_e32 v122, v122
	v_cvt_f32_f16_sdwa v135, v139 dst_sel:DWORD dst_unused:UNUSED_PAD src0_sel:WORD_1
	v_cvt_f32_f16_e32 v134, v139
	v_cvt_f32_f16_sdwa v139, v138 dst_sel:DWORD dst_unused:UNUSED_PAD src0_sel:WORD_1
	v_cvt_f32_f16_e32 v138, v138
	v_cvt_f32_f16_sdwa v151, v155 dst_sel:DWORD dst_unused:UNUSED_PAD src0_sel:WORD_1
	v_cvt_f32_f16_e32 v150, v155
	v_cvt_f32_f16_sdwa v155, v154 dst_sel:DWORD dst_unused:UNUSED_PAD src0_sel:WORD_1
	v_cvt_f32_f16_e32 v154, v154
	v_mul_f32_e32 v184, v52, v52
	v_mul_f32_e32 v186, v56, v56
	v_mul_f32_e32 v188, v62, v62
	v_mul_f32_e32 v189, v63, v63
	v_mul_f32_e32 v190, v60, v60
	v_mul_f32_e32 v191, v61, v61
	v_mul_f32_e32 v192, v66, v66
	v_mul_f32_e32 v193, v67, v67
	v_mul_f32_e32 v194, v64, v64
	v_mul_f32_e32 v195, v65, v65
	v_mul_f32_e32 v196, v68, v68
	v_mul_f32_e32 v198, v72, v72
	v_mul_f32_e32 v200, v78, v78
	v_mul_f32_e32 v201, v79, v79
	v_mul_f32_e32 v202, v76, v76
	v_mul_f32_e32 v203, v77, v77
	v_mul_f32_e32 v206, v82, v82
	v_mul_f32_e32 v207, v83, v83
	v_mul_f32_e32 v208, v80, v80
	v_mul_f32_e32 v209, v81, v81
	v_mul_f32_e32 v210, v84, v84
	v_mul_f32_e32 v212, v88, v88
	v_mul_f32_e32 v214, v94, v94
	v_mul_f32_e32 v215, v95, v95
	v_mul_f32_e32 v216, v92, v92
	v_mul_f32_e32 v217, v93, v93
	v_mul_f32_e32 v218, v98, v98
	v_mul_f32_e32 v219, v99, v99
	v_mul_f32_e32 v220, v96, v96
	v_mul_f32_e32 v221, v97, v97
	v_mul_f32_e32 v226, v110, v110
	v_mul_f32_e32 v227, v111, v111
	v_mul_f32_e32 v228, v108, v108
	v_mul_f32_e32 v229, v109, v109
	v_mul_f32_e32 v230, v114, v114
	v_mul_f32_e32 v231, v115, v115
	v_mul_f32_e32 v232, v112, v112
	v_mul_f32_e32 v233, v113, v113
	v_mul_f32_e32 v238, v126, v126
	v_mul_f32_e32 v239, v127, v127
	v_mul_f32_e32 v240, v124, v124
	v_mul_f32_e32 v241, v125, v125
	v_mul_f32_e32 v242, v130, v130
	v_mul_f32_e32 v243, v131, v131
	v_mul_f32_e32 v244, v128, v128
	v_mul_f32_e32 v245, v129, v129
	v_mul_f32_e32 v246, v142, v142
	v_mul_f32_e32 v247, v143, v143
	v_mul_f32_e32 v248, v140, v140
	v_mul_f32_e32 v249, v141, v141
	v_mul_f32_e32 v250, v146, v146
	v_mul_f32_e32 v251, v147, v147
	v_mul_f32_e32 v252, v144, v144
	v_mul_f32_e32 v253, v145, v145
	v_pk_mov_b32 v[204:205], v[166:167], v[164:165] op_sel:[1,0]
; template <int MODE, bool XBF>
; __device__ __forceinline__ void rmsnorm_rows(const void* x, const float* gain, bf16_t* H, int gw, int NGW, int lane, const LAS float* WF, const float* fbias, float* LF) {
;     ...
;         for (int r = 0; r < RB; ++r) { s[r] = 0.f;
; #pragma unroll
;             for (int j = 0; j < 2; ++j)
; #pragma unroll
;                 for (int e = 0; e < 2; ++e) s[r] += (v[r][j][e][0] * v[r][j][e][0] + v[r][j][e][1] * v[r][j][e][1]) + (v[r][j][e][2] * v[r][j][e][2] + v[r][j][e][3] * v[r][j][e][3]); }
	v_mov_b32_e32 v167, v165
	v_pk_mov_b32 v[164:165], v[170:171], v[168:169] op_sel:[1,0]
	v_mov_b32_e32 v171, v169
	v_pk_mov_b32 v[168:169], v[178:179], v[176:177] op_sel:[1,0]
	v_mov_b32_e32 v179, v177
	v_pk_mov_b32 v[176:177], v[182:183], v[180:181] op_sel:[1,0]
	v_mov_b32_e32 v183, v181
	v_fma_f32 v173, v37, v37, v172
	v_fma_f32 v172, v36, v36, v172
	v_fma_f32 v175, v41, v41, v174
	v_fma_f32 v174, v40, v40, v174
	v_pk_mov_b32 v[180:181], v[190:191], v[188:189] op_sel:[1,0]
	v_mov_b32_e32 v191, v189
	v_pk_mov_b32 v[188:189], v[194:195], v[192:193] op_sel:[1,0]
	v_mov_b32_e32 v195, v193
	v_pk_mov_b32 v[192:193], v[202:203], v[200:201] op_sel:[1,0]
	v_mov_b32_e32 v203, v201
	v_pk_mov_b32 v[200:201], v[208:209], v[206:207] op_sel:[1,0]
	v_mov_b32_e32 v209, v207
	v_pk_mov_b32 v[206:207], v[216:217], v[214:215] op_sel:[1,0]
	v_mov_b32_e32 v217, v215
	v_pk_mov_b32 v[214:215], v[220:221], v[218:219] op_sel:[1,0]
	v_mov_b32_e32 v221, v219
	v_pk_mov_b32 v[218:219], v[228:229], v[226:227] op_sel:[1,0]
	v_mov_b32_e32 v229, v227
	v_pk_mov_b32 v[226:227], v[232:233], v[230:231] op_sel:[1,0]
	v_mov_b32_e32 v233, v231
	v_pk_mov_b32 v[230:231], v[240:241], v[238:239] op_sel:[1,0]
	v_mov_b32_e32 v241, v239
	v_pk_mov_b32 v[238:239], v[244:245], v[242:243] op_sel:[1,0]
	v_mov_b32_e32 v245, v243
	v_pk_mov_b32 v[242:243], v[248:249], v[246:247] op_sel:[1,0]
	v_mov_b32_e32 v249, v247
	v_pk_mov_b32 v[246:247], v[252:253], v[250:251] op_sel:[1,0]
	v_mov_b32_e32 v253, v251
	v_add_f32_e32 v166, v204, v166
	v_add_f32_e32 v167, v205, v167
	v_add_f32_e32 v164, v164, v170
	v_add_f32_e32 v165, v165, v171
	v_add_f32_e32 v168, v168, v178
	v_add_f32_e32 v169, v169, v179
	v_fma_f32 v185, v53, v53, v184
	v_fma_f32 v184, v52, v52, v184
	v_fma_f32 v187, v57, v57, v186
	v_fma_f32 v186, v56, v56, v186
	v_fma_f32 v197, v69, v69, v196
	v_fma_f32 v196, v68, v68, v196
	v_fma_f32 v199, v73, v73, v198
	v_fma_f32 v198, v72, v72, v198
	v_fma_f32 v211, v85, v85, v210
	v_fma_f32 v210, v84, v84, v210
	v_fma_f32 v213, v89, v89, v212
	v_fma_f32 v212, v88, v88, v212
	v_mul_f32_e32 v172, v38, v38
	v_mul_f32_e32 v174, v39, v39
	v_add_f32_e32 v176, v176, v182
	v_add_f32_e32 v177, v177, v183
	v_mul_f32_e32 v222, v100, v100
	v_mul_f32_e32 v224, v104, v104
	v_mul_f32_e32 v234, v116, v116
	v_mul_f32_e32 v236, v120, v120
	v_mul_f32_e32 v250, v132, v132
	v_mul_f32_e32 v204, v136, v136
	v_mul_f32_e32 v170, v148, v148
	v_mul_f32_e32 v178, v152, v152
	v_mul_f32_e32 v184, v54, v54
	v_mul_f32_e32 v186, v55, v55
	v_add_f32_e32 v180, v180, v190
	v_add_f32_e32 v181, v181, v191
	v_add_f32_e32 v182, v188, v194
	v_add_f32_e32 v183, v189, v195
	v_mul_f32_e32 v196, v70, v70
	v_mul_f32_e32 v198, v71, v71
	v_add_f32_e32 v188, v192, v202
	v_add_f32_e32 v189, v193, v203
	v_add_f32_e32 v190, v200, v208
	v_add_f32_e32 v191, v201, v209
	v_mul_f32_e32 v210, v86, v86
	v_mul_f32_e32 v212, v87, v87
	v_add_f32_e32 v192, v206, v216
	v_add_f32_e32 v193, v207, v217
	v_add_f32_e32 v194, v214, v220
	v_add_f32_e32 v195, v215, v221
	v_add_f32_e32 v200, v218, v228
	v_add_f32_e32 v201, v219, v229
	v_add_f32_e32 v202, v226, v232
	v_add_f32_e32 v203, v227, v233
	v_add_f32_e32 v206, v230, v240
	v_add_f32_e32 v207, v231, v241
	v_add_f32_e32 v208, v238, v244
	v_add_f32_e32 v209, v239, v245
	v_add_f32_e32 v214, v242, v248
	v_add_f32_e32 v215, v243, v249
	v_add_f32_e32 v216, v246, v252
	v_add_f32_e32 v217, v247, v253
	v_add_f32_e32 v167, v166, v167
	v_add_f32_e32 v166, v166, v166
	v_add_f32_e32 v165, v164, v165
	v_add_f32_e32 v164, v164, v164
	v_add_f32_e32 v172, v172, v174
	v_add_f32_e32 v173, v173, v175
	v_add_f32_e32 v169, v168, v169
	v_add_f32_e32 v168, v168, v168
	v_add_f32_e32 v174, v176, v176
	v_add_f32_e32 v175, v176, v177
	v_fma_f32 v223, v101, v101, v222
	v_fma_f32 v222, v100, v100, v222
	v_fma_f32 v225, v105, v105, v224
	v_fma_f32 v224, v104, v104, v224
	v_fma_f32 v235, v117, v117, v234
	v_fma_f32 v234, v116, v116, v234
	v_fma_f32 v237, v121, v121, v236
	v_fma_f32 v236, v120, v120, v236
	v_fma_f32 v251, v133, v133, v250
	v_fma_f32 v250, v132, v132, v250
	v_fma_f32 v205, v137, v137, v204
	v_fma_f32 v204, v136, v136, v204
	v_fma_f32 v171, v149, v149, v170
	v_fma_f32 v170, v148, v148, v170
	v_fma_f32 v179, v153, v153, v178
	v_fma_f32 v178, v152, v152, v178
	v_add_f32_e32 v176, v184, v186
	v_add_f32_e32 v177, v185, v187
	v_add_f32_e32 v181, v180, v181
	v_add_f32_e32 v180, v180, v180
	v_add_f32_e32 v183, v182, v183
	v_add_f32_e32 v182, v182, v182
	v_add_f32_e32 v184, v196, v198
	v_add_f32_e32 v185, v197, v199
	v_add_f32_e32 v186, v188, v188
	v_add_f32_e32 v187, v188, v189
	v_add_f32_e32 v188, v190, v190
	v_add_f32_e32 v189, v190, v191
	v_add_f32_e32 v190, v210, v212
	v_add_f32_e32 v191, v211, v213
	v_add_f32_e32 v193, v192, v193
	v_add_f32_e32 v192, v192, v192
	v_add_f32_e32 v195, v194, v195
	v_add_f32_e32 v194, v194, v194
	v_add_f32_e32 v198, v200, v200
	v_add_f32_e32 v199, v200, v201
	v_add_f32_e32 v200, v202, v202
	v_add_f32_e32 v201, v202, v203
	v_add_f32_e32 v207, v206, v207
	v_add_f32_e32 v206, v206, v206
	v_add_f32_e32 v209, v208, v209
	v_add_f32_e32 v208, v208, v208
	v_add_f32_e32 v210, v214, v214
	v_add_f32_e32 v211, v214, v215
	v_add_f32_e32 v212, v216, v216
	v_add_f32_e32 v213, v216, v217
	v_mul_f32_e32 v166, v42, v42
	v_mul_f32_e32 v164, v43, v43
	v_mul_f32_e32 v168, v58, v58
	v_mul_f32_e32 v174, v59, v59
	v_mul_f32_e32 v222, v102, v102
	v_mul_f32_e32 v224, v103, v103
	v_mul_f32_e32 v234, v118, v118
	v_mul_f32_e32 v236, v119, v119
	v_mul_f32_e32 v250, v134, v134
	v_mul_f32_e32 v204, v135, v135
	v_mul_f32_e32 v170, v150, v150
	v_mul_f32_e32 v178, v151, v151
	v_mul_f32_e32 v180, v74, v74
	v_mul_f32_e32 v182, v75, v75
; template <int MODE, bool XBF>
; __device__ __forceinline__ void rmsnorm_rows(const void* x, const float* gain, bf16_t* H, int gw, int NGW, int lane, const LAS float* WF, const float* fbias, float* LF) {
;     ...
; #pragma unroll
;         for (int o = 1; o < 64; o <<= 1)
; #pragma unroll
;             for (int r = 0; r < RB; ++r) s[r] += __shfl_xor(s[r], o);
	v_mul_f32_e32 v186, v90, v90
	v_mul_f32_e32 v188, v91, v91
	v_mul_f32_e32 v192, v106, v106
	v_mul_f32_e32 v194, v107, v107
	v_mul_f32_e32 v198, v122, v122
	v_mul_f32_e32 v200, v123, v123
	v_mul_f32_e32 v206, v138, v138
	v_mul_f32_e32 v208, v139, v139
	v_mul_f32_e32 v210, v154, v154
	v_mul_f32_e32 v212, v155, v155
	v_add_f32_e32 v164, v166, v164
	v_add_f32_e32 v165, v167, v165
	v_add_f32_e32 v166, v168, v174
	v_add_f32_e32 v167, v169, v175
	v_add_f32_e32 v196, v222, v224
	v_add_f32_e32 v197, v223, v225
	v_add_f32_e32 v202, v234, v236
	v_add_f32_e32 v203, v235, v237
	v_add_f32_e32 v204, v250, v204
	v_add_f32_e32 v205, v251, v205
	v_add_f32_e32 v170, v170, v178
	v_add_f32_e32 v171, v171, v179
	v_add_f32_e32 v168, v180, v182
	v_add_f32_e32 v169, v181, v183
	v_add_f32_e32 v174, v186, v188
	v_add_f32_e32 v175, v187, v189
	v_add_f32_e32 v178, v192, v194
	v_add_f32_e32 v179, v193, v195
	v_add_f32_e32 v180, v198, v200
	v_add_f32_e32 v181, v199, v201
	v_add_f32_e32 v182, v206, v208
	v_add_f32_e32 v183, v207, v209
	v_add_f32_e32 v186, v210, v212
	v_add_f32_e32 v187, v211, v213
	v_add_f32_e32 v164, v164, v172
	v_add_f32_e32 v165, v165, v173
	v_add_f32_e32 v166, v166, v176
	v_add_f32_e32 v167, v167, v177
	v_add_f32_e32 v168, v168, v184
	v_add_f32_e32 v169, v169, v185
	v_add_f32_e32 v172, v174, v190
	v_add_f32_e32 v173, v175, v191
	v_add_f32_e32 v174, v178, v196
	v_add_f32_e32 v175, v179, v197
	v_add_f32_e32 v176, v180, v202
	v_add_f32_e32 v177, v181, v203
	v_add_f32_e32 v178, v182, v204
	v_add_f32_e32 v179, v183, v205
	v_add_f32_e32 v170, v186, v170
	v_add_f32_e32 v171, v187, v171
	v_mov_b32_e32 v180, v166
	v_mov_b32_e32 v181, v164
	v_mov_b32_e32 v164, v167
	v_mov_b32_e32 v166, v172
	v_mov_b32_e32 v167, v168
	v_mov_b32_e32 v168, v173
	v_mov_b32_e32 v172, v176
	v_mov_b32_e32 v173, v174
	v_mov_b32_e32 v174, v177
	v_mov_b32_e32 v176, v170
	v_mov_b32_e32 v177, v178
	v_mov_b32_e32 v178, v171
	v_add_f32_e32 v164, v180, v164
	v_add_f32_e32 v165, v181, v165
	v_add_f32_e32 v166, v166, v168
	v_add_f32_e32 v167, v167, v169
	v_add_f32_e32 v168, v172, v174
	v_add_f32_e32 v169, v173, v175
	v_add_f32_e32 v170, v176, v178
	v_add_f32_e32 v171, v177, v179
	ds_bpermute_b32 v173, v157, v165
	ds_bpermute_b32 v172, v157, v164
	ds_bpermute_b32 v175, v157, v167
	ds_bpermute_b32 v174, v157, v166
	ds_bpermute_b32 v177, v157, v169
	ds_bpermute_b32 v176, v157, v168
	ds_bpermute_b32 v179, v157, v171
	ds_bpermute_b32 v178, v157, v170
	s_waitcnt lgkmcnt(6)
	v_add_f32_e32 v164, v164, v172
	v_add_f32_e32 v165, v165, v173
	s_waitcnt lgkmcnt(4)
	v_add_f32_e32 v166, v166, v174
	v_add_f32_e32 v167, v167, v175
	s_waitcnt lgkmcnt(2)
	v_add_f32_e32 v168, v168, v176
	v_add_f32_e32 v169, v169, v177
	ds_bpermute_b32 v173, v158, v165
	s_waitcnt lgkmcnt(1)
	v_add_f32_e32 v170, v170, v178
	v_add_f32_e32 v171, v171, v179
	ds_bpermute_b32 v172, v158, v164
	ds_bpermute_b32 v175, v158, v167
	ds_bpermute_b32 v174, v158, v166
	ds_bpermute_b32 v177, v158, v169
	ds_bpermute_b32 v176, v158, v168
	ds_bpermute_b32 v179, v158, v171
	ds_bpermute_b32 v178, v158, v170
	s_waitcnt lgkmcnt(6)
	v_add_f32_e32 v164, v164, v172
	v_add_f32_e32 v165, v165, v173
	s_waitcnt lgkmcnt(4)
	v_add_f32_e32 v166, v166, v174
	v_add_f32_e32 v167, v167, v175
	s_waitcnt lgkmcnt(2)
	v_add_f32_e32 v168, v168, v176
	v_add_f32_e32 v169, v169, v177
	ds_bpermute_b32 v173, v159, v165
	s_waitcnt lgkmcnt(1)
	v_add_f32_e32 v170, v170, v178
	v_add_f32_e32 v171, v171, v179
	ds_bpermute_b32 v172, v159, v164
	ds_bpermute_b32 v175, v159, v167
	ds_bpermute_b32 v174, v159, v166
	ds_bpermute_b32 v177, v159, v169
	ds_bpermute_b32 v176, v159, v168
	ds_bpermute_b32 v179, v159, v171
	ds_bpermute_b32 v178, v159, v170
	s_waitcnt lgkmcnt(6)
	v_add_f32_e32 v164, v164, v172
	v_add_f32_e32 v165, v165, v173
	s_waitcnt lgkmcnt(4)
	v_add_f32_e32 v166, v166, v174
	v_add_f32_e32 v167, v167, v175
	s_waitcnt lgkmcnt(2)
	v_add_f32_e32 v168, v168, v176
	v_add_f32_e32 v169, v169, v177
	ds_bpermute_b32 v173, v160, v165
	s_waitcnt lgkmcnt(1)
	v_add_f32_e32 v170, v170, v178
	v_add_f32_e32 v171, v171, v179
	ds_bpermute_b32 v172, v160, v164
	ds_bpermute_b32 v175, v160, v167
	ds_bpermute_b32 v174, v160, v166
	ds_bpermute_b32 v177, v160, v169
	ds_bpermute_b32 v176, v160, v168
	ds_bpermute_b32 v179, v160, v171
	ds_bpermute_b32 v178, v160, v170
	s_waitcnt lgkmcnt(6)
	v_add_f32_e32 v164, v164, v172
	v_add_f32_e32 v165, v165, v173
	s_waitcnt lgkmcnt(4)
	v_add_f32_e32 v166, v166, v174
	v_add_f32_e32 v167, v167, v175
	s_waitcnt lgkmcnt(2)
	v_add_f32_e32 v168, v168, v176
	v_add_f32_e32 v169, v169, v177
	ds_bpermute_b32 v173, v161, v165
	s_waitcnt lgkmcnt(1)
	v_add_f32_e32 v170, v170, v178
	v_add_f32_e32 v171, v171, v179
	ds_bpermute_b32 v172, v161, v164
	ds_bpermute_b32 v175, v161, v167
	ds_bpermute_b32 v174, v161, v166
	ds_bpermute_b32 v177, v161, v169
	ds_bpermute_b32 v176, v161, v168
	ds_bpermute_b32 v179, v161, v171
	ds_bpermute_b32 v178, v161, v170
	s_waitcnt lgkmcnt(6)
	v_add_f32_e32 v164, v164, v172
	v_add_f32_e32 v165, v165, v173
	s_waitcnt lgkmcnt(4)
	v_add_f32_e32 v166, v166, v174
	v_add_f32_e32 v167, v167, v175
	s_waitcnt lgkmcnt(2)
	v_add_f32_e32 v168, v168, v176
	v_add_f32_e32 v169, v169, v177
	ds_bpermute_b32 v173, v162, v165
	s_waitcnt lgkmcnt(1)
	v_add_f32_e32 v170, v170, v178
	v_add_f32_e32 v171, v171, v179
	ds_bpermute_b32 v172, v162, v164
	ds_bpermute_b32 v175, v162, v167
	ds_bpermute_b32 v174, v162, v166
	ds_bpermute_b32 v177, v162, v169
	ds_bpermute_b32 v176, v162, v168
	ds_bpermute_b32 v179, v162, v171
	ds_bpermute_b32 v178, v162, v170
	s_waitcnt lgkmcnt(6)
	v_add_f32_e32 v164, v164, v172
	v_add_f32_e32 v165, v165, v173
	s_waitcnt lgkmcnt(4)
; template <int MODE, bool XBF>
; __device__ __forceinline__ void rmsnorm_rows(const void* x, const float* gain, bf16_t* H, int gw, int NGW, int lane, const LAS float* WF, const float* fbias, float* LF) {
;     ...
;         for (int r = 0; r < RB; ++r) {
;             const int row = row0 + r;
;             const float rstd = rsqrtf(s[r] * (1.f / D) + 1e-6f);
;             const size_t hrow = MODE == 2 ? (size_t)row + (row >> 12) + 1 : (size_t)row;
; #pragma unroll
;             for (int j = 0; j < 2; ++j) { v[r][j][0] = v[r][j][0] * rstd * g[j][0]; v[r][j][1] = v[r][j][1] * rstd * g[j][1];
	v_add_f32_e32 v166, v166, v174
	v_add_f32_e32 v167, v167, v175
	s_waitcnt lgkmcnt(2)
	v_add_f32_e32 v168, v168, v176
	v_add_f32_e32 v169, v169, v177
	v_fma_f32 v164, v164, s30, v20
	v_fma_f32 v165, v165, s30, v20
	s_waitcnt lgkmcnt(0)
	v_add_f32_e32 v170, v170, v178
	v_add_f32_e32 v171, v171, v179
	v_fma_f32 v166, v166, s30, v20
	v_fma_f32 v167, v167, s30, v20
	v_fma_f32 v168, v168, s30, v20
	v_fma_f32 v169, v169, s30, v20
	v_fma_f32 v21, v171, s30, v20
	v_fma_f32 v20, v170, s30, v20
	v_mul_f32_e32 v163, 0x4b800000, v165
	v_cmp_gt_f32_e64 s[2:3], s31, v165
	v_mul_f32_e32 v170, 0x4b800000, v164
	v_cmp_gt_f32_e32 vcc, s31, v164
	v_mul_f32_e32 v171, 0x4b800000, v167
	v_mul_f32_e32 v172, 0x4b800000, v166
	v_cmp_gt_f32_e64 s[4:5], s31, v166
	v_cmp_gt_f32_e64 s[6:7], s31, v167
	v_mul_f32_e32 v173, 0x4b800000, v169
	v_mul_f32_e32 v174, 0x4b800000, v168
	v_cmp_gt_f32_e64 s[8:9], s31, v168
	v_cmp_gt_f32_e64 s[10:11], s31, v169
	v_mul_f32_e32 v175, 0x4b800000, v21
	v_mul_f32_e32 v176, 0x4b800000, v20
	v_cmp_gt_f32_e64 s[12:13], s31, v20
	v_cndmask_b32_e64 v163, v165, v163, s[2:3]
	v_cmp_gt_f32_e64 s[14:15], s31, v21
	v_cndmask_b32_e32 v164, v164, v170, vcc
	v_cndmask_b32_e64 v165, v167, v171, s[6:7]
	v_cndmask_b32_e64 v166, v166, v172, s[4:5]
	v_cndmask_b32_e64 v167, v169, v173, s[10:11]
	v_cndmask_b32_e64 v168, v168, v174, s[8:9]
	v_cndmask_b32_e64 v21, v21, v175, s[14:15]
	v_cndmask_b32_e64 v20, v20, v176, s[12:13]
	v_rsq_f32_e32 v163, v163
	v_rsq_f32_e32 v164, v164
	v_rsq_f32_e32 v165, v165
	v_rsq_f32_e32 v169, v166
	v_rsq_f32_e32 v167, v167
	v_rsq_f32_e32 v171, v168
	v_rsq_f32_e32 v21, v21
	v_rsq_f32_e32 v173, v20
	v_mul_f32_e32 v20, 0x45800000, v163
	v_mul_f32_e32 v166, 0x45800000, v164
	v_mul_f32_e32 v168, 0x45800000, v165
	v_mul_f32_e32 v170, 0x45800000, v169
	v_mul_f32_e32 v172, 0x45800000, v167
	v_mul_f32_e32 v174, 0x45800000, v171
	v_mul_f32_e32 v175, 0x45800000, v21
	v_mul_f32_e32 v176, 0x45800000, v173
	v_cndmask_b32_e64 v20, v163, v20, s[2:3]
	v_cndmask_b32_e32 v164, v164, v166, vcc
	v_cndmask_b32_e64 v166, v165, v168, s[6:7]
	v_cndmask_b32_e64 v168, v169, v170, s[4:5]
	v_cndmask_b32_e64 v170, v167, v172, s[10:11]
	v_cndmask_b32_e64 v172, v171, v174, s[8:9]
	v_cndmask_b32_e64 v174, v21, v175, s[14:15]
	v_cndmask_b32_e64 v176, v173, v176, s[12:13]
	v_mul_f32_e32 v18, v20, v18
	v_mul_f32_e32 v19, v20, v19
	v_mul_f32_e32 v30, v20, v30
	v_mul_f32_e32 v31, v20, v31
	v_mul_f32_e32 v32, v20, v32
	v_mul_f32_e32 v33, v20, v33
	v_mul_f32_e32 v34, v20, v34
	v_mul_f32_e32 v35, v20, v35
	v_mul_f32_e32 v36, v20, v36
	v_mul_f32_e32 v37, v20, v37
	v_mul_f32_e32 v40, v20, v40
	v_mul_f32_e32 v41, v20, v41
	v_mul_f32_e32 v42, v20, v42
	v_mul_f32_e32 v43, v20, v43
	v_mul_f32_e32 v21, v20, v39
	v_mul_f32_e32 v20, v20, v38
	v_mul_f32_e32 v38, v164, v44
	v_mul_f32_e32 v39, v164, v45
	v_mul_f32_e32 v44, v164, v46
	v_mul_f32_e32 v45, v164, v47
	v_mul_f32_e32 v46, v164, v48
	v_mul_f32_e32 v47, v164, v49
	v_mul_f32_e32 v48, v164, v50
	v_mul_f32_e32 v49, v164, v51
	v_mul_f32_e32 v50, v164, v52
	v_mul_f32_e32 v51, v164, v53
	v_mul_f32_e32 v52, v164, v56
	v_mul_f32_e32 v53, v164, v57
	v_mul_f32_e32 v56, v164, v58
	v_mul_f32_e32 v57, v164, v59
	v_mul_f32_e32 v54, v164, v54
	v_mul_f32_e32 v55, v164, v55
	v_mul_f32_e32 v58, v166, v60
	v_mul_f32_e32 v59, v166, v61
	v_mul_f32_e32 v60, v166, v62
	v_mul_f32_e32 v61, v166, v63
	v_mul_f32_e32 v62, v166, v64
	v_mul_f32_e32 v63, v166, v65
	v_mul_f32_e32 v64, v166, v66
	v_mul_f32_e32 v65, v166, v67
	v_mul_f32_e32 v66, v166, v68
	v_mul_f32_e32 v67, v166, v69
	v_mul_f32_e32 v68, v166, v72
	v_mul_f32_e32 v69, v166, v73
	v_mul_f32_e32 v72, v166, v74
	v_mul_f32_e32 v73, v166, v75
	v_mul_f32_e32 v70, v166, v70
	v_mul_f32_e32 v71, v166, v71
	v_mul_f32_e32 v74, v168, v76
	v_mul_f32_e32 v75, v168, v77
	v_mul_f32_e32 v76, v168, v78
	v_mul_f32_e32 v77, v168, v79
	v_mul_f32_e32 v78, v168, v80
	v_mul_f32_e32 v79, v168, v81
	v_mul_f32_e32 v80, v168, v82
	v_mul_f32_e32 v81, v168, v83
	v_mul_f32_e32 v82, v168, v84
	v_mul_f32_e32 v83, v168, v85
	v_mul_f32_e32 v84, v168, v88
	v_mul_f32_e32 v85, v168, v89
	v_mul_f32_e32 v88, v168, v90
	v_mul_f32_e32 v89, v168, v91
	v_mul_f32_e32 v86, v168, v86
	v_mul_f32_e32 v87, v168, v87
	v_mul_f32_e32 v90, v170, v92
	v_mul_f32_e32 v91, v170, v93
	v_mul_f32_e32 v92, v170, v94
	v_mul_f32_e32 v93, v170, v95
	v_mul_f32_e32 v94, v170, v96
	v_mul_f32_e32 v95, v170, v97
	v_mul_f32_e32 v96, v170, v98
	v_mul_f32_e32 v97, v170, v99
	v_mul_f32_e32 v98, v170, v100
	v_mul_f32_e32 v99, v170, v101
	v_mul_f32_e32 v100, v170, v104
	v_mul_f32_e32 v101, v170, v105
	v_mul_f32_e32 v104, v170, v106
	v_mul_f32_e32 v105, v170, v107
	v_mul_f32_e32 v102, v170, v102
	v_mul_f32_e32 v103, v170, v103
	v_mul_f32_e32 v106, v172, v108
	v_mul_f32_e32 v107, v172, v109
	v_mul_f32_e32 v108, v172, v110
	v_mul_f32_e32 v109, v172, v111
	v_mul_f32_e32 v110, v172, v112
	v_mul_f32_e32 v111, v172, v113
	v_mul_f32_e32 v112, v172, v114
	v_mul_f32_e32 v113, v172, v115
	v_mul_f32_e32 v114, v172, v116
	v_mul_f32_e32 v115, v172, v117
	v_mul_f32_e32 v116, v172, v120
	v_mul_f32_e32 v117, v172, v121
	v_mul_f32_e32 v120, v172, v122
	v_mul_f32_e32 v121, v172, v123
	v_mul_f32_e32 v118, v172, v118
	v_mul_f32_e32 v119, v172, v119
	v_mul_f32_e32 v122, v174, v124
	v_mul_f32_e32 v123, v174, v125
	v_mul_f32_e32 v124, v174, v126
	v_mul_f32_e32 v125, v174, v127
	v_mul_f32_e32 v126, v174, v128
	v_mul_f32_e32 v127, v174, v129
	v_mul_f32_e32 v128, v174, v130
	v_mul_f32_e32 v129, v174, v131
	v_mul_f32_e32 v130, v174, v132
	v_mul_f32_e32 v131, v174, v133
	v_mul_f32_e32 v132, v174, v136
	v_mul_f32_e32 v133, v174, v137
	v_mul_f32_e32 v136, v174, v138
	v_mul_f32_e32 v137, v174, v139
; template <int MODE, bool XBF>
; __device__ __forceinline__ void rmsnorm_rows(const void* x, const float* gain, bf16_t* H, int gw, int NGW, int lane, const LAS float* WF, const float* fbias, float* LF) {
;     ...
;             for (int j = 0; j < 2; ++j) { v[r][j][0] = v[r][j][0] * rstd * g[j][0]; v[r][j][1] = v[r][j][1] * rstd * g[j][1];
	v_mul_f32_e32 v134, v174, v134
	v_mul_f32_e32 v135, v174, v135
	v_mul_f32_e32 v138, v176, v140
	v_mul_f32_e32 v139, v176, v141
	v_mul_f32_e32 v140, v176, v142
	v_mul_f32_e32 v141, v176, v143
	v_mul_f32_e32 v142, v176, v144
	v_mul_f32_e32 v143, v176, v145
	v_mul_f32_e32 v144, v176, v146
	v_mul_f32_e32 v145, v176, v147
	v_mul_f32_e32 v146, v176, v148
	v_mul_f32_e32 v147, v176, v149
	v_mul_f32_e32 v148, v176, v152
	v_mul_f32_e32 v149, v176, v153
	v_mul_f32_e32 v152, v176, v154
	v_mul_f32_e32 v153, v176, v155
	v_mul_f32_e32 v150, v176, v150
	v_mul_f32_e32 v151, v176, v151
	v_mul_f32_e32 v30, v6, v30
	v_mul_f32_e32 v31, v7, v31
	v_mul_f32_e32 v18, v4, v18
	v_mul_f32_e32 v19, v5, v19
	v_mul_f32_e32 v34, v2, v34
	v_mul_f32_e32 v35, v3, v35
	v_mul_f32_e32 v32, v0, v32
	v_mul_f32_e32 v33, v1, v33
	v_mul_f32_e32 v40, v14, v40
	v_mul_f32_e32 v41, v15, v41
	v_mul_f32_e32 v36, v12, v36
	v_mul_f32_e32 v37, v13, v37
	v_mul_f32_e32 v154, v10, v20
	v_mul_f32_e32 v155, v11, v21
	v_mul_f32_e32 v42, v8, v42
	v_mul_f32_e32 v43, v9, v43
	v_mul_f32_e32 v44, v6, v44
	v_mul_f32_e32 v45, v7, v45
	v_mul_f32_e32 v38, v4, v38
	v_mul_f32_e32 v39, v5, v39
	v_mul_f32_e32 v48, v2, v48
	v_mul_f32_e32 v49, v3, v49
	v_mul_f32_e32 v46, v0, v46
	v_mul_f32_e32 v47, v1, v47
	v_mul_f32_e32 v52, v14, v52
	v_mul_f32_e32 v53, v15, v53
	v_mul_f32_e32 v50, v12, v50
	v_mul_f32_e32 v51, v13, v51
	v_mul_f32_e32 v54, v10, v54
	v_mul_f32_e32 v55, v11, v55
	v_mul_f32_e32 v56, v8, v56
	v_mul_f32_e32 v57, v9, v57
	v_mul_f32_e32 v60, v6, v60
	v_mul_f32_e32 v61, v7, v61
	v_mul_f32_e32 v58, v4, v58
	v_mul_f32_e32 v59, v5, v59
	v_mul_f32_e32 v64, v2, v64
	v_mul_f32_e32 v65, v3, v65
	v_mul_f32_e32 v62, v0, v62
	v_mul_f32_e32 v63, v1, v63
	v_mul_f32_e32 v68, v14, v68
	v_mul_f32_e32 v69, v15, v69
	v_mul_f32_e32 v66, v12, v66
	v_mul_f32_e32 v67, v13, v67
	v_mul_f32_e32 v70, v10, v70
	v_mul_f32_e32 v71, v11, v71
	v_mul_f32_e32 v72, v8, v72
	v_mul_f32_e32 v73, v9, v73
	v_mul_f32_e32 v76, v6, v76
	v_mul_f32_e32 v77, v7, v77
	v_mul_f32_e32 v74, v4, v74
	v_mul_f32_e32 v75, v5, v75
	v_mul_f32_e32 v80, v2, v80
	v_mul_f32_e32 v81, v3, v81
	v_mul_f32_e32 v78, v0, v78
	v_mul_f32_e32 v79, v1, v79
	v_mul_f32_e32 v84, v14, v84
	v_mul_f32_e32 v85, v15, v85
	v_mul_f32_e32 v82, v12, v82
	v_mul_f32_e32 v83, v13, v83
	v_mul_f32_e32 v86, v10, v86
	v_mul_f32_e32 v87, v11, v87
	v_mul_f32_e32 v88, v8, v88
	v_mul_f32_e32 v89, v9, v89
	v_mul_f32_e32 v92, v6, v92
	v_mul_f32_e32 v93, v7, v93
	v_mul_f32_e32 v90, v4, v90
	v_mul_f32_e32 v91, v5, v91
	v_mul_f32_e32 v96, v2, v96
	v_mul_f32_e32 v97, v3, v97
	v_mul_f32_e32 v94, v0, v94
	v_mul_f32_e32 v95, v1, v95
	v_mul_f32_e32 v100, v14, v100
	v_mul_f32_e32 v101, v15, v101
	v_mul_f32_e32 v98, v12, v98
	v_mul_f32_e32 v99, v13, v99
	v_mul_f32_e32 v102, v10, v102
	v_mul_f32_e32 v103, v11, v103
	v_mul_f32_e32 v104, v8, v104
	v_mul_f32_e32 v105, v9, v105
	v_mul_f32_e32 v108, v6, v108
	v_mul_f32_e32 v109, v7, v109
	v_mul_f32_e32 v106, v4, v106
	v_mul_f32_e32 v107, v5, v107
	v_mul_f32_e32 v112, v2, v112
	v_mul_f32_e32 v113, v3, v113
	v_mul_f32_e32 v110, v0, v110
	v_mul_f32_e32 v111, v1, v111
	v_mul_f32_e32 v116, v14, v116
	v_mul_f32_e32 v117, v15, v117
	v_mul_f32_e32 v114, v12, v114
	v_mul_f32_e32 v115, v13, v115
	v_mul_f32_e32 v118, v10, v118
	v_mul_f32_e32 v119, v11, v119
	v_mul_f32_e32 v120, v8, v120
	v_mul_f32_e32 v121, v9, v121
	v_mul_f32_e32 v124, v6, v124
	v_mul_f32_e32 v125, v7, v125
	v_mul_f32_e32 v122, v4, v122
	v_mul_f32_e32 v123, v5, v123
	v_mul_f32_e32 v128, v2, v128
	v_mul_f32_e32 v129, v3, v129
	v_mul_f32_e32 v126, v0, v126
	v_mul_f32_e32 v127, v1, v127
	v_mul_f32_e32 v132, v14, v132
	v_mul_f32_e32 v133, v15, v133
	v_mul_f32_e32 v130, v12, v130
	v_mul_f32_e32 v131, v13, v131
; #define GAS __attribute__((address_space(1)))
; template <int MODE, bool XBF>
; __device__ __forceinline__ void rmsnorm_rows(const void* x, const float* gain, bf16_t* H, int gw, int NGW, int lane, const LAS float* WF, const float* fbias, float* LF) {
;     ...
;     for (int row0 = gw * RB; row0 < T; row0 += NGW * RB) {
;     ...
;             for (int j = 0; j < 2; ++j) { v[r][j][0] = v[r][j][0] * rstd * g[j][0]; v[r][j][1] = v[r][j][1] * rstd * g[j][1];
;                 *(GAS u32x4*)(H + hrow * D + 512 * j + lane * 8) = pack8(v[r][j][0], v[r][j][1]); }
	v_mul_f32_e32 v134, v10, v134
	v_mul_f32_e32 v135, v11, v135
	v_mul_f32_e32 v136, v8, v136
	v_mul_f32_e32 v137, v9, v137
	v_mul_f32_e32 v140, v6, v140
	v_mul_f32_e32 v141, v7, v141
	v_mul_f32_e32 v138, v4, v138
	v_mul_f32_e32 v139, v5, v139
	v_mul_f32_e32 v144, v2, v144
	v_mul_f32_e32 v145, v3, v145
	v_mul_f32_e32 v142, v0, v142
	v_mul_f32_e32 v143, v1, v143
	v_mul_f32_e32 v148, v14, v148
	v_mul_f32_e32 v149, v15, v149
	v_mul_f32_e32 v146, v12, v146
	v_mul_f32_e32 v147, v13, v147
	v_mul_f32_e32 v150, v10, v150
	v_mul_f32_e32 v151, v11, v151
	v_mul_f32_e32 v152, v8, v152
	v_mul_f32_e32 v153, v9, v153
	v_cvt_pk_bf16_f32 v18, v18, v19
	v_cvt_pk_bf16_f32 v19, v30, v31
	v_cvt_pk_bf16_f32 v20, v32, v33
	v_cvt_pk_bf16_f32 v21, v34, v35
	v_cvt_pk_bf16_f32 v30, v36, v37
	v_cvt_pk_bf16_f32 v31, v40, v41
	v_cvt_pk_bf16_f32 v32, v42, v43
	v_cvt_pk_bf16_f32 v33, v154, v155
	v_cvt_pk_bf16_f32 v34, v38, v39
	v_cvt_pk_bf16_f32 v35, v44, v45
	v_cvt_pk_bf16_f32 v36, v46, v47
	v_cvt_pk_bf16_f32 v37, v48, v49
	v_cvt_pk_bf16_f32 v38, v50, v51
	v_cvt_pk_bf16_f32 v39, v52, v53
	v_cvt_pk_bf16_f32 v40, v56, v57
	v_cvt_pk_bf16_f32 v41, v54, v55
	v_cvt_pk_bf16_f32 v42, v58, v59
	v_cvt_pk_bf16_f32 v43, v60, v61
	v_cvt_pk_bf16_f32 v44, v62, v63
	v_cvt_pk_bf16_f32 v45, v64, v65
	v_cvt_pk_bf16_f32 v46, v66, v67
	v_cvt_pk_bf16_f32 v47, v68, v69
	v_cvt_pk_bf16_f32 v48, v72, v73
	v_cvt_pk_bf16_f32 v49, v70, v71
	v_cvt_pk_bf16_f32 v50, v74, v75
	v_cvt_pk_bf16_f32 v51, v76, v77
	v_cvt_pk_bf16_f32 v52, v78, v79
	v_cvt_pk_bf16_f32 v53, v80, v81
	v_cvt_pk_bf16_f32 v54, v82, v83
	v_cvt_pk_bf16_f32 v55, v84, v85
	v_cvt_pk_bf16_f32 v56, v88, v89
	v_cvt_pk_bf16_f32 v57, v86, v87
	v_cvt_pk_bf16_f32 v58, v90, v91
	v_cvt_pk_bf16_f32 v59, v92, v93
	v_cvt_pk_bf16_f32 v60, v94, v95
	v_cvt_pk_bf16_f32 v61, v96, v97
	v_cvt_pk_bf16_f32 v62, v98, v99
	v_cvt_pk_bf16_f32 v63, v100, v101
	v_cvt_pk_bf16_f32 v64, v104, v105
	v_cvt_pk_bf16_f32 v65, v102, v103
	v_cvt_pk_bf16_f32 v66, v106, v107
	v_cvt_pk_bf16_f32 v67, v108, v109
	v_cvt_pk_bf16_f32 v68, v110, v111
	v_cvt_pk_bf16_f32 v69, v112, v113
	v_cvt_pk_bf16_f32 v70, v114, v115
	v_cvt_pk_bf16_f32 v71, v116, v117
	v_cvt_pk_bf16_f32 v72, v120, v121
	v_cvt_pk_bf16_f32 v73, v118, v119
	v_cvt_pk_bf16_f32 v74, v122, v123
	v_cvt_pk_bf16_f32 v75, v124, v125
	v_cvt_pk_bf16_f32 v76, v126, v127
	v_cvt_pk_bf16_f32 v77, v128, v129
	v_cvt_pk_bf16_f32 v78, v130, v131
	v_cvt_pk_bf16_f32 v79, v132, v133
	v_cvt_pk_bf16_f32 v80, v136, v137
	v_cvt_pk_bf16_f32 v81, v134, v135
	v_cvt_pk_bf16_f32 v82, v138, v139
	v_cvt_pk_bf16_f32 v83, v140, v141
	v_cvt_pk_bf16_f32 v84, v142, v143
	v_cvt_pk_bf16_f32 v85, v144, v145
	v_cvt_pk_bf16_f32 v86, v146, v147
	v_cvt_pk_bf16_f32 v87, v148, v149
	v_cvt_pk_bf16_f32 v88, v152, v153
	v_cvt_pk_bf16_f32 v89, v150, v151
	global_store_dwordx4 v[24:25], v[18:21], off
	global_store_dwordx4 v[24:25], v[30:33], off offset:1024
	global_store_dwordx4 v[24:25], v[34:37], off offset:2048
	global_store_dwordx4 v[24:25], v[38:41], off offset:3072
	global_store_dwordx4 v[26:27], v[42:45], off offset:-4096
	global_store_dwordx4 v[28:29], v[46:49], off offset:1024
	global_store_dwordx4 v[28:29], v[50:53], off offset:2048
	global_store_dwordx4 v[28:29], v[54:57], off offset:3072
	global_store_dwordx4 v[26:27], v[58:61], off
	global_store_dwordx4 v[26:27], v[62:65], off offset:1024
	global_store_dwordx4 v[26:27], v[66:69], off offset:2048
	global_store_dwordx4 v[26:27], v[70:73], off offset:3072
	global_store_dwordx4 v[24:25], v[74:77], off offset:-4096
	global_store_dwordx4 v[22:23], v[78:81], off offset:1024
	global_store_dwordx4 v[22:23], v[82:85], off offset:2048
	global_store_dwordx4 v[22:23], v[86:89], off offset:3072
	s_cbranch_scc1 .LBB0_421

; #define GAS __attribute__((address_space(1)))
; __device__ __forceinline__ float fsigmoid(float x) { return frcp(1.f + fexp2(-x * LOG2E)); }
;     __device__ __forceinline__ void operator()(const Acc& acc, const Unit& u, int wr, int wc, int fr, int fq) const {
;     ...
;                     for (int j = 0; j < 4; ++j) { const float gx = acc[ai][0][m][n][j]; o[n][j] = gx * fsigmoid(gx) * acc[ai][1][m][n][j]; }
;                 *(GAS u32x4*)(ACT + (size_t)(row0 + ai * HALF + m * 16) * F + col0) = pack8(o[0], o[1]);
.LBB0_484:
	v_mul_f32_e32 v148, 0xbfb8aa3b, v124
	v_mul_f32_e32 v149, 0xbfb8aa3b, v125
	v_exp_f32_e32 v148, v148
	v_exp_f32_e32 v149, v149
	v_mov_b32_e32 v147, v141
	s_lshl_b32 s13, s20, 8
	v_add_f32_e32 v148, 1.0, v148
	v_add_f32_e32 v149, 1.0, v149
	v_rcp_f32_e32 v148, v148
	v_rcp_f32_e32 v149, v149
	s_add_i32 s13, s13, s46
	v_and_or_b32 v146, v147, 15, s13
	s_lshl_b32 s13, s55, 7
	v_ashrrev_i32_e32 v147, 1, v147
	s_or_b32 s13, s13, s47
	v_and_b32_e32 v147, -8, v147
	v_add_u32_e32 v150, s13, v147
	v_mul_f32_e32 v124, v124, v148
	v_mul_f32_e32 v125, v125, v149
	v_mul_f32_e32 v147, 0xbfb8aa3b, v126
	v_mul_f32_e32 v148, 0xbfb8aa3b, v127
	v_exp_f32_e32 v147, v147
	v_exp_f32_e32 v148, v148
	v_mul_f32_e32 v116, v124, v116
	v_mul_f32_e32 v117, v125, v117
	v_ashrrev_i32_e32 v151, 31, v150
	v_add_f32_e32 v124, 1.0, v147
	v_add_f32_e32 v125, 1.0, v148
	v_mul_f32_e32 v147, 0xbfb8aa3b, v120
	v_rcp_f32_e32 v124, v124
	v_rcp_f32_e32 v125, v125
	v_exp_f32_e32 v147, v147
	v_mul_f32_e32 v148, 0xbfb8aa3b, v121
	v_exp_f32_e32 v148, v148
	v_mul_f32_e32 v124, v126, v124
	v_mul_f32_e32 v125, v127, v125
	v_add_f32_e32 v126, 1.0, v147
	v_mul_f32_e32 v147, 0xbfb8aa3b, v122
	v_add_f32_e32 v127, 1.0, v148
	v_exp_f32_e32 v147, v147
	v_mul_f32_e32 v148, 0xbfb8aa3b, v123
	v_exp_f32_e32 v149, v148
	v_rcp_f32_e32 v126, v126
	v_add_f32_e32 v147, 1.0, v147
	v_rcp_f32_e32 v127, v127
	v_rcp_f32_e32 v148, v147
	v_add_f32_e32 v147, 1.0, v149
	v_rcp_f32_e32 v149, v147
	v_mul_f32_e32 v120, v120, v126
	v_mul_f32_e32 v121, v121, v127
	v_mul_f32_e32 v118, v124, v118
	v_mul_f32_e32 v119, v125, v119
	v_mul_f32_e32 v112, v120, v112
	v_mul_f32_e32 v113, v121, v113
	v_mul_f32_e32 v120, v122, v148
	v_mul_f32_e32 v121, v123, v149
	v_cvt_pk_bf16_f32 v116, v116, v117
	v_mul_f32_e32 v114, v120, v114
	v_mul_f32_e32 v115, v121, v115
	v_cvt_pk_bf16_f32 v117, v118, v119
	v_cvt_pk_bf16_f32 v119, v114, v115
	v_mul_f32_e32 v114, 0xbfb8aa3b, v108
	v_exp_f32_e32 v114, v114
	v_mul_f32_e32 v115, 0xbfb8aa3b, v109
	v_exp_f32_e32 v115, v115
	v_cvt_pk_bf16_f32 v118, v112, v113
	v_add_f32_e32 v114, 1.0, v114
	v_mov_b64_e32 v[112:113], s[10:11]
	v_rcp_f32_e32 v122, v114
	v_add_f32_e32 v114, 1.0, v115
	v_mad_i64_i32 v[120:121], s[24:25], v146, s54, v[112:113]
	v_rcp_f32_e32 v123, v114
	v_lshlrev_b64 v[114:115], 1, v[150:151]
	v_lshl_add_u64 v[120:121], v[120:121], 0, v[114:115]
	global_store_dwordx4 v[120:121], v[116:119], off
	v_mul_f32_e32 v108, v108, v122
	v_mul_f32_e32 v109, v109, v123
	s_andn2_b64 vcc, exec, s[2:3]
	v_mul_f32_e32 v116, 0xbfb8aa3b, v110
	v_mul_f32_e32 v117, 0xbfb8aa3b, v111
	v_exp_f32_e32 v116, v116
	v_exp_f32_e32 v117, v117
	v_mul_f32_e32 v100, v108, v100
	v_mul_f32_e32 v101, v109, v101
	s_mov_b64 s[2:3], -1
	v_add_f32_e32 v108, 1.0, v116
	v_add_f32_e32 v109, 1.0, v117
	v_mul_f32_e32 v116, 0xbfb8aa3b, v104
	v_mul_f32_e32 v117, 0xbfb8aa3b, v105
	v_rcp_f32_e32 v108, v108
	v_rcp_f32_e32 v109, v109
	v_exp_f32_e32 v116, v116
	v_exp_f32_e32 v117, v117
	v_mul_f32_e32 v108, v110, v108
	v_mul_f32_e32 v109, v111, v109
	v_add_f32_e32 v110, 1.0, v116
	v_add_f32_e32 v111, 1.0, v117
	v_mul_f32_e32 v116, 0xbfb8aa3b, v106
	v_mul_f32_e32 v117, 0xbfb8aa3b, v107
	v_exp_f32_e32 v116, v116
	v_exp_f32_e32 v117, v117
	v_rcp_f32_e32 v110, v110
	v_rcp_f32_e32 v111, v111
	v_add_f32_e32 v116, 1.0, v116
	v_add_f32_e32 v117, 1.0, v117
	v_rcp_f32_e32 v116, v116
	v_rcp_f32_e32 v117, v117
	v_mul_f32_e32 v104, v104, v110
	v_mul_f32_e32 v105, v105, v111
	v_mul_f32_e32 v102, v108, v102
	v_mul_f32_e32 v103, v109, v103
	v_mul_f32_e32 v104, v104, v96
	v_mul_f32_e32 v105, v105, v97
	v_mul_f32_e32 v96, v106, v116
	v_mul_f32_e32 v97, v107, v117
	s_nop 0
	v_mul_f32_e32 v106, v96, v98
	v_mul_f32_e32 v107, v97, v99
	v_cvt_pk_bf16_f32 v96, v100, v101
	v_mul_f32_e32 v100, 0xbfb8aa3b, v92
	v_mul_f32_e32 v101, 0xbfb8aa3b, v93
	v_exp_f32_e32 v100, v100
	v_exp_f32_e32 v101, v101
	v_cvt_pk_bf16_f32 v97, v102, v103
	v_or_b32_e32 v102, 16, v146
	v_mad_i64_i32 v[102:103], s[24:25], v102, s54, v[112:113]
	v_cvt_pk_bf16_f32 v98, v104, v105
	v_cvt_pk_bf16_f32 v99, v106, v107
	v_add_f32_e32 v100, 1.0, v100
	v_add_f32_e32 v101, 1.0, v101
	v_lshl_add_u64 v[102:103], v[102:103], 0, v[114:115]
	v_rcp_f32_e32 v100, v100
	v_rcp_f32_e32 v101, v101
	global_store_dwordx4 v[102:103], v[96:99], off
	v_mul_f32_e32 v92, v92, v100
	v_mul_f32_e32 v93, v93, v101
	s_nop 0
	v_mul_f32_e32 v96, 0xbfb8aa3b, v94
	v_mul_f32_e32 v97, 0xbfb8aa3b, v95
	v_exp_f32_e32 v96, v96
	v_exp_f32_e32 v97, v97
	v_mul_f32_e32 v84, v92, v84
	v_mul_f32_e32 v85, v93, v85
	v_add_f32_e32 v92, 1.0, v96
	v_add_f32_e32 v93, 1.0, v97
	v_mul_f32_e32 v96, 0xbfb8aa3b, v88
	v_mul_f32_e32 v97, 0xbfb8aa3b, v89
	v_rcp_f32_e32 v92, v92
	v_rcp_f32_e32 v93, v93
	v_exp_f32_e32 v96, v96
	v_exp_f32_e32 v97, v97
	v_mul_f32_e32 v92, v94, v92
	v_mul_f32_e32 v93, v95, v93
	v_add_f32_e32 v94, 1.0, v96
	v_add_f32_e32 v95, 1.0, v97
	v_mul_f32_e32 v96, 0xbfb8aa3b, v90
	v_mul_f32_e32 v97, 0xbfb8aa3b, v91
	v_exp_f32_e32 v96, v96
	v_exp_f32_e32 v97, v97
	v_rcp_f32_e32 v94, v94
	v_rcp_f32_e32 v95, v95
	v_add_f32_e32 v96, 1.0, v96
	v_add_f32_e32 v97, 1.0, v97
	v_rcp_f32_e32 v96, v96
	v_rcp_f32_e32 v97, v97
	v_mul_f32_e32 v88, v88, v94
	v_mul_f32_e32 v89, v89, v95
	v_mul_f32_e32 v86, v92, v86
	v_mul_f32_e32 v87, v93, v87
	v_mul_f32_e32 v88, v88, v80
	v_mul_f32_e32 v89, v89, v81
	v_mul_f32_e32 v80, v90, v96
	v_mul_f32_e32 v81, v91, v97
	s_nop 0
	v_mul_f32_e32 v90, v80, v82
	v_mul_f32_e32 v91, v81, v83
	v_cvt_pk_bf16_f32 v80, v84, v85
	v_mul_f32_e32 v84, 0xbfb8aa3b, v76
	v_mul_f32_e32 v85, 0xbfb8aa3b, v77
	v_exp_f32_e32 v84, v84
	v_exp_f32_e32 v85, v85
	v_cvt_pk_bf16_f32 v81, v86, v87
	v_or_b32_e32 v86, 32, v146
; #define GAS __attribute__((address_space(1)))
; __device__ __forceinline__ float fsigmoid(float x) { return frcp(1.f + fexp2(-x * LOG2E)); }
;     __device__ __forceinline__ void operator()(const Acc& acc, const Unit& u, int wr, int wc, int fr, int fq) const {
;     ...
;                     for (int j = 0; j < 4; ++j) { const float gx = acc[ai][0][m][n][j]; o[n][j] = gx * fsigmoid(gx) * acc[ai][1][m][n][j]; }
;                 *(GAS u32x4*)(ACT + (size_t)(row0 + ai * HALF + m * 16) * F + col0) = pack8(o[0], o[1]);
	v_mad_i64_i32 v[86:87], s[24:25], v86, s54, v[112:113]
	v_cvt_pk_bf16_f32 v82, v88, v89
	v_cvt_pk_bf16_f32 v83, v90, v91
	v_add_f32_e32 v84, 1.0, v84
	v_add_f32_e32 v85, 1.0, v85
	v_lshl_add_u64 v[86:87], v[86:87], 0, v[114:115]
	v_rcp_f32_e32 v84, v84
	v_rcp_f32_e32 v85, v85
	global_store_dwordx4 v[86:87], v[80:83], off
	v_mul_f32_e32 v76, v76, v84
	v_mul_f32_e32 v77, v77, v85
	s_nop 0
	v_mul_f32_e32 v80, 0xbfb8aa3b, v78
	v_mul_f32_e32 v81, 0xbfb8aa3b, v79
	v_exp_f32_e32 v80, v80
	v_exp_f32_e32 v81, v81
	v_mul_f32_e32 v68, v76, v68
	v_mul_f32_e32 v69, v77, v69
	v_add_f32_e32 v76, 1.0, v80
	v_add_f32_e32 v77, 1.0, v81
	v_mul_f32_e32 v80, 0xbfb8aa3b, v72
	v_mul_f32_e32 v81, 0xbfb8aa3b, v73
	v_rcp_f32_e32 v76, v76
	v_rcp_f32_e32 v77, v77
	v_exp_f32_e32 v80, v80
	v_exp_f32_e32 v81, v81
	v_mul_f32_e32 v76, v78, v76
	v_mul_f32_e32 v77, v79, v77
	v_add_f32_e32 v78, 1.0, v80
	v_add_f32_e32 v79, 1.0, v81
	v_mul_f32_e32 v80, 0xbfb8aa3b, v74
	v_mul_f32_e32 v81, 0xbfb8aa3b, v75
	v_exp_f32_e32 v80, v80
	v_exp_f32_e32 v81, v81
	v_rcp_f32_e32 v78, v78
	v_rcp_f32_e32 v79, v79
	v_add_f32_e32 v80, 1.0, v80
	v_add_f32_e32 v81, 1.0, v81
	v_rcp_f32_e32 v80, v80
	v_rcp_f32_e32 v81, v81
	v_mul_f32_e32 v72, v72, v78
	v_mul_f32_e32 v73, v73, v79
	v_mul_f32_e32 v70, v76, v70
	v_mul_f32_e32 v71, v77, v71
	v_mul_f32_e32 v72, v72, v64
	v_mul_f32_e32 v73, v73, v65
	v_mul_f32_e32 v64, v74, v80
	v_mul_f32_e32 v65, v75, v81
	s_nop 0
	v_mul_f32_e32 v74, v64, v66
	v_mul_f32_e32 v75, v65, v67
	v_cvt_pk_bf16_f32 v64, v68, v69
	v_mul_f32_e32 v69, 0xbfb8aa3b, v60
	v_cvt_pk_bf16_f32 v65, v70, v71
	v_exp_f32_e32 v70, v69
	v_mul_f32_e32 v69, 0xbfb8aa3b, v61
	v_exp_f32_e32 v71, v69
	v_or_b32_e32 v68, 48, v146
	v_mad_i64_i32 v[68:69], s[24:25], v68, s54, v[112:113]
	v_cvt_pk_bf16_f32 v66, v72, v73
	v_cvt_pk_bf16_f32 v67, v74, v75
	v_add_f32_e32 v70, 1.0, v70
	v_add_f32_e32 v71, 1.0, v71
	v_lshl_add_u64 v[68:69], v[68:69], 0, v[114:115]
	v_rcp_f32_e32 v70, v70
	v_rcp_f32_e32 v71, v71
	global_store_dwordx4 v[68:69], v[64:67], off
	v_mul_f32_e32 v60, v60, v70
	v_mul_f32_e32 v61, v61, v71
	s_nop 0
	v_mul_f32_e32 v64, 0xbfb8aa3b, v62
	v_mul_f32_e32 v65, 0xbfb8aa3b, v63
	v_exp_f32_e32 v64, v64
	v_exp_f32_e32 v65, v65
	v_mul_f32_e32 v52, v60, v52
	v_mul_f32_e32 v53, v61, v53
	v_add_u32_e32 v66, 0x80, v146
	v_add_f32_e32 v60, 1.0, v64
	v_add_f32_e32 v61, 1.0, v65
	v_mul_f32_e32 v64, 0xbfb8aa3b, v56
	v_mul_f32_e32 v65, 0xbfb8aa3b, v57
	v_rcp_f32_e32 v60, v60
	v_rcp_f32_e32 v61, v61
	v_exp_f32_e32 v64, v64
	v_exp_f32_e32 v65, v65
	v_mul_f32_e32 v60, v62, v60
	v_mul_f32_e32 v61, v63, v61
	v_add_f32_e32 v62, 1.0, v64
	v_add_f32_e32 v63, 1.0, v65
	v_mul_f32_e32 v64, 0xbfb8aa3b, v58
	v_mul_f32_e32 v65, 0xbfb8aa3b, v59
	v_exp_f32_e32 v64, v64
	v_exp_f32_e32 v65, v65
	v_rcp_f32_e32 v62, v62
	v_rcp_f32_e32 v63, v63
	v_add_f32_e32 v64, 1.0, v64
	v_add_f32_e32 v65, 1.0, v65
	v_rcp_f32_e32 v64, v64
	v_rcp_f32_e32 v65, v65
	v_mul_f32_e32 v56, v56, v62
	v_mul_f32_e32 v57, v57, v63
	v_mul_f32_e32 v54, v60, v54
	v_mul_f32_e32 v55, v61, v55
	v_mul_f32_e32 v56, v56, v48
	v_mul_f32_e32 v57, v57, v49
	v_mul_f32_e32 v48, v58, v64
	v_mul_f32_e32 v49, v59, v65
	s_nop 0
	v_mul_f32_e32 v58, v48, v50
	v_mul_f32_e32 v59, v49, v51
	v_mul_f32_e32 v51, 0xbfb8aa3b, v44
	v_cvt_pk_bf16_f32 v48, v52, v53
	v_exp_f32_e32 v52, v51
	v_mul_f32_e32 v51, 0xbfb8aa3b, v45
	v_exp_f32_e32 v53, v51
	v_cvt_pk_bf16_f32 v49, v54, v55
	v_mad_i64_i32 v[54:55], s[24:25], v66, s54, v[112:113]
	v_cvt_pk_bf16_f32 v50, v56, v57
	v_cvt_pk_bf16_f32 v51, v58, v59
	v_add_f32_e32 v52, 1.0, v52
	v_add_f32_e32 v53, 1.0, v53
	v_lshl_add_u64 v[54:55], v[54:55], 0, v[114:115]
	v_rcp_f32_e32 v52, v52
	v_rcp_f32_e32 v53, v53
	global_store_dwordx4 v[54:55], v[48:51], off
	v_mul_f32_e32 v44, v44, v52
	v_mul_f32_e32 v45, v45, v53
	s_nop 0
	v_mul_f32_e32 v48, 0xbfb8aa3b, v46
	v_mul_f32_e32 v49, 0xbfb8aa3b, v47
	v_exp_f32_e32 v48, v48
	v_exp_f32_e32 v49, v49
	v_mul_f32_e32 v36, v44, v36
	v_mul_f32_e32 v37, v45, v37
	v_add_f32_e32 v44, 1.0, v48
	v_add_f32_e32 v45, 1.0, v49
	v_mul_f32_e32 v48, 0xbfb8aa3b, v40
	v_mul_f32_e32 v49, 0xbfb8aa3b, v41
	v_rcp_f32_e32 v44, v44
	v_rcp_f32_e32 v45, v45
	v_exp_f32_e32 v48, v48
	v_exp_f32_e32 v49, v49
	v_mul_f32_e32 v44, v46, v44
	v_mul_f32_e32 v45, v47, v45
	v_add_f32_e32 v46, 1.0, v48
	v_add_f32_e32 v47, 1.0, v49
	v_mul_f32_e32 v48, 0xbfb8aa3b, v42
; #define GAS __attribute__((address_space(1)))
; __device__ __forceinline__ float fsigmoid(float x) { return frcp(1.f + fexp2(-x * LOG2E)); }
;     __device__ __forceinline__ void operator()(const Acc& acc, const Unit& u, int wr, int wc, int fr, int fq) const {
;     ...
;                     for (int j = 0; j < 4; ++j) { const float gx = acc[ai][0][m][n][j]; o[n][j] = gx * fsigmoid(gx) * acc[ai][1][m][n][j]; }
;                 *(GAS u32x4*)(ACT + (size_t)(row0 + ai * HALF + m * 16) * F + col0) = pack8(o[0], o[1]);
	v_mul_f32_e32 v49, 0xbfb8aa3b, v43
	v_exp_f32_e32 v48, v48
	v_exp_f32_e32 v49, v49
	v_rcp_f32_e32 v46, v46
	v_rcp_f32_e32 v47, v47
	v_add_f32_e32 v48, 1.0, v48
	v_add_f32_e32 v49, 1.0, v49
	v_rcp_f32_e32 v48, v48
	v_rcp_f32_e32 v49, v49
	v_mul_f32_e32 v40, v40, v46
	v_mul_f32_e32 v41, v41, v47
	v_mul_f32_e32 v38, v44, v38
	v_mul_f32_e32 v39, v45, v39
	v_mul_f32_e32 v40, v40, v32
	v_mul_f32_e32 v41, v41, v33
	v_mul_f32_e32 v32, v42, v48
	v_mul_f32_e32 v33, v43, v49
	s_nop 0
	v_mul_f32_e32 v42, v32, v34
	v_mul_f32_e32 v43, v33, v35
	v_cvt_pk_bf16_f32 v32, v36, v37
	v_mul_f32_e32 v36, 0xbfb8aa3b, v28
	v_mul_f32_e32 v37, 0xbfb8aa3b, v29
	v_exp_f32_e32 v36, v36
	v_exp_f32_e32 v37, v37
	v_cvt_pk_bf16_f32 v33, v38, v39
	v_add_u32_e32 v38, 0x90, v146
	v_mad_i64_i32 v[38:39], s[24:25], v38, s54, v[112:113]
	v_cvt_pk_bf16_f32 v34, v40, v41
	v_cvt_pk_bf16_f32 v35, v42, v43
	v_add_f32_e32 v36, 1.0, v36
	v_add_f32_e32 v37, 1.0, v37
	v_lshl_add_u64 v[38:39], v[38:39], 0, v[114:115]
	v_rcp_f32_e32 v36, v36
	v_rcp_f32_e32 v37, v37
	global_store_dwordx4 v[38:39], v[32:35], off
	v_mul_f32_e32 v28, v28, v36
	v_mul_f32_e32 v29, v29, v37
	s_nop 0
	v_mul_f32_e32 v32, 0xbfb8aa3b, v30
	v_mul_f32_e32 v33, 0xbfb8aa3b, v31
	v_exp_f32_e32 v32, v32
	v_exp_f32_e32 v33, v33
	v_mul_f32_e32 v20, v28, v20
	v_mul_f32_e32 v21, v29, v21
	v_add_f32_e32 v28, 1.0, v32
	v_add_f32_e32 v29, 1.0, v33
	v_mul_f32_e32 v32, 0xbfb8aa3b, v24
	v_mul_f32_e32 v33, 0xbfb8aa3b, v25
	v_rcp_f32_e32 v28, v28
	v_rcp_f32_e32 v29, v29
	v_exp_f32_e32 v32, v32
	v_exp_f32_e32 v33, v33
	v_mul_f32_e32 v28, v30, v28
	v_mul_f32_e32 v29, v31, v29
	v_add_f32_e32 v30, 1.0, v32
	v_add_f32_e32 v31, 1.0, v33
	v_mul_f32_e32 v32, 0xbfb8aa3b, v26
	v_mul_f32_e32 v33, 0xbfb8aa3b, v27
	v_exp_f32_e32 v32, v32
	v_exp_f32_e32 v33, v33
	v_rcp_f32_e32 v30, v30
	v_rcp_f32_e32 v31, v31
	v_add_f32_e32 v32, 1.0, v32
	v_add_f32_e32 v33, 1.0, v33
	v_rcp_f32_e32 v32, v32
	v_rcp_f32_e32 v33, v33
	v_mul_f32_e32 v24, v24, v30
	v_mul_f32_e32 v25, v25, v31
	v_mul_f32_e32 v22, v28, v22
	v_mul_f32_e32 v23, v29, v23
	v_mul_f32_e32 v24, v24, v16
	v_mul_f32_e32 v25, v25, v17
	v_mul_f32_e32 v16, v26, v32
	v_mul_f32_e32 v17, v27, v33
	s_nop 0
	v_mul_f32_e32 v26, v16, v18
	v_mul_f32_e32 v27, v17, v19
	v_cvt_pk_bf16_f32 v16, v20, v21
	v_mul_f32_e32 v20, 0xbfb8aa3b, v12
	v_mul_f32_e32 v21, 0xbfb8aa3b, v13
	v_exp_f32_e32 v20, v20
	v_exp_f32_e32 v21, v21
	v_cvt_pk_bf16_f32 v17, v22, v23
	v_add_u32_e32 v22, 0xa0, v146
	v_mad_i64_i32 v[22:23], s[24:25], v22, s54, v[112:113]
	v_cvt_pk_bf16_f32 v18, v24, v25
	v_cvt_pk_bf16_f32 v19, v26, v27
	v_add_f32_e32 v20, 1.0, v20
	v_add_f32_e32 v21, 1.0, v21
	v_lshl_add_u64 v[22:23], v[22:23], 0, v[114:115]
	v_rcp_f32_e32 v20, v20
	v_rcp_f32_e32 v21, v21
	global_store_dwordx4 v[22:23], v[16:19], off
	v_mul_f32_e32 v12, v12, v20
	v_mul_f32_e32 v13, v13, v21
	s_nop 0
	v_mul_f32_e32 v16, 0xbfb8aa3b, v14
	v_mul_f32_e32 v17, 0xbfb8aa3b, v15
	v_exp_f32_e32 v16, v16
	v_exp_f32_e32 v17, v17
	v_mul_f32_e32 v4, v12, v4
	v_mul_f32_e32 v5, v13, v5
	v_add_f32_e32 v12, 1.0, v16
	v_add_f32_e32 v13, 1.0, v17
	v_mul_f32_e32 v16, 0xbfb8aa3b, v8
	v_mul_f32_e32 v17, 0xbfb8aa3b, v9
	v_rcp_f32_e32 v12, v12
	v_rcp_f32_e32 v13, v13
	v_exp_f32_e32 v16, v16
	v_exp_f32_e32 v17, v17
	v_mul_f32_e32 v12, v14, v12
	v_mul_f32_e32 v13, v15, v13
	v_add_f32_e32 v14, 1.0, v16
	v_add_f32_e32 v15, 1.0, v17
	v_mul_f32_e32 v16, 0xbfb8aa3b, v10
	v_mul_f32_e32 v17, 0xbfb8aa3b, v11
	v_exp_f32_e32 v16, v16
	v_exp_f32_e32 v17, v17
	v_rcp_f32_e32 v14, v14
	v_rcp_f32_e32 v15, v15
	v_add_f32_e32 v16, 1.0, v16
	v_add_f32_e32 v17, 1.0, v17
	v_rcp_f32_e32 v16, v16
	v_rcp_f32_e32 v17, v17
	v_mul_f32_e32 v8, v8, v14
	v_mul_f32_e32 v9, v9, v15
	v_mul_f32_e32 v6, v12, v6
	v_mul_f32_e32 v7, v13, v7
	v_mul_f32_e32 v8, v8, v0
	v_mul_f32_e32 v9, v9, v1
	v_mul_f32_e32 v0, v10, v16
	v_mul_f32_e32 v1, v11, v17
	s_nop 0
	v_mul_f32_e32 v10, v0, v2
	v_mul_f32_e32 v11, v1, v3
	v_cvt_pk_bf16_f32 v0, v4, v5
	v_add_u32_e32 v4, 0xb0, v146
	v_mad_i64_i32 v[4:5], s[24:25], v4, s54, v[112:113]
	v_cvt_pk_bf16_f32 v1, v6, v7
	v_cvt_pk_bf16_f32 v2, v8, v9
	v_cvt_pk_bf16_f32 v3, v10, v11
	v_lshl_add_u64 v[4:5], v[4:5], 0, v[114:115]
	global_store_dwordx4 v[4:5], v[0:3], off
	s_cbranch_vccnz .LBB0_477
	s_andn2_b64 vcc, exec, s[6:7]
	s_cbranch_vccnz .LBB0_476
	s_barrier
	s_branch .LBB0_476

; #define GAS __attribute__((address_space(1)))
;     __device__ __forceinline__ void operator()(const Acc& acc, const Unit& u, int wr, int wc, int fr, int fq) const {
;         const int row0 = u.pm * BM + wr * 64 + fr, col0 = u.pn * BM + wc * 32 + 8 * fq;
; #pragma unroll
;         for (int ai = 0; ai < 2; ++ai)
; #pragma unroll
;             for (int m = 0; m < 4; ++m) {
;                 const size_t off = (size_t)(row0 + ai * HALF + m * 16) * D + col0;
; #pragma unroll
;                 for (int bj = 0; bj < 2; ++bj) {
;                     const size_t p = off + bj * HALF;
;                     f32x4 b0, b1;
;                     if (BASE_F32) { b0 = *(const GAS f32x4*)((const float*)base + p); b1 = *(const GAS f32x4*)((const float*)base + p + 4); }
;                     else unpack8h(*(const GAS u32x4*)((const bf16_t*)base + p), b0, b1);
;                     b0 += acc[ai][bj][m][0]; b1 += acc[ai][bj][m][1];
;                     if (OUT_F32) { *(GAS f32x4*)((float*)out + p) = b0; *(GAS f32x4*)((float*)out + p + 4) = b1; }
;                     else *(GAS u32x4*)((bf16_t*)out + p) = pack8h(b0, b1);
;                 }
;                 asm volatile("" ::: "memory");
;             }
.LBB0_558:
	v_mov_b32_e32 v140, v147
	s_lshl_b32 s28, s60, 8
	s_add_i32 s28, s28, s50
	v_and_or_b32 v144, v140, 15, s28
	s_lshl_b32 s28, s61, 8
	v_ashrrev_i32_e32 v140, 1, v140
	s_or_b32 s28, s28, s51
	v_and_b32_e32 v140, -8, v140
	v_add_u32_e32 v142, s28, v140
	v_ashrrev_i32_e32 v145, 31, v144
	v_ashrrev_i32_e32 v143, 31, v142
	v_lshlrev_b64 v[140:141], 10, v[144:145]
	v_lshl_add_u64 v[140:141], v[140:141], 0, v[142:143]
	v_lshlrev_b64 v[140:141], 1, v[140:141]
	v_lshl_add_u64 v[156:157], s[12:13], 0, v[140:141]
	global_load_dwordx4 v[152:155], v[156:157], off
	v_lshl_add_u64 v[158:159], s[14:15], 0, v[140:141]
	s_and_b64 vcc, exec, s[2:3]
	s_mov_b64 s[2:3], -1
	s_waitcnt vmcnt(0)
	v_cvt_f32_f16_e32 v160, v153
	v_cvt_f32_f16_sdwa v161, v153 dst_sel:DWORD dst_unused:UNUSED_PAD src0_sel:WORD_1
	v_cvt_f32_f16_e32 v162, v152
	v_cvt_f32_f16_sdwa v163, v152 dst_sel:DWORD dst_unused:UNUSED_PAD src0_sel:WORD_1
	v_cvt_f32_f16_e32 v152, v155
	v_cvt_f32_f16_e32 v164, v154
	v_cvt_f32_f16_sdwa v165, v154 dst_sel:DWORD dst_unused:UNUSED_PAD src0_sel:WORD_1
	v_cvt_f32_f16_sdwa v153, v155 dst_sel:DWORD dst_unused:UNUSED_PAD src0_sel:WORD_1
	v_add_f32_e32 v124, v124, v162
	v_add_f32_e32 v125, v125, v163
	v_add_f32_e32 v126, v126, v160
	v_add_f32_e32 v127, v127, v161
	v_add_f32_e32 v120, v120, v164
	v_add_f32_e32 v121, v121, v165
	v_add_f32_e32 v122, v122, v152
	v_add_f32_e32 v123, v123, v153
	s_nop 0
	v_cvt_pk_f16_f32 v123, v122, v123
	v_cvt_pk_f16_f32 v122, v120, v121
	v_cvt_pk_f16_f32 v121, v126, v127
	v_cvt_pk_f16_f32 v120, v124, v125
	global_store_dwordx4 v[158:159], v[120:123], off
	global_load_dwordx4 v[120:123], v[156:157], off offset:256
	v_or_b32_e32 v124, 16, v144
	v_ashrrev_i32_e32 v125, 31, v124
	v_lshlrev_b64 v[124:125], 10, v[124:125]
	v_lshl_add_u64 v[124:125], v[124:125], 0, v[142:143]
	v_lshlrev_b64 v[124:125], 1, v[124:125]
	v_lshl_add_u64 v[126:127], s[12:13], 0, v[124:125]
	s_waitcnt vmcnt(0)
	v_cvt_f32_f16_e32 v152, v121
	v_cvt_f32_f16_sdwa v153, v121 dst_sel:DWORD dst_unused:UNUSED_PAD src0_sel:WORD_1
	v_cvt_f32_f16_e32 v154, v120
	v_cvt_f32_f16_sdwa v155, v120 dst_sel:DWORD dst_unused:UNUSED_PAD src0_sel:WORD_1
	v_cvt_f32_f16_e32 v120, v123
	v_cvt_f32_f16_e32 v156, v122
	v_cvt_f32_f16_sdwa v157, v122 dst_sel:DWORD dst_unused:UNUSED_PAD src0_sel:WORD_1
	v_cvt_f32_f16_sdwa v121, v123 dst_sel:DWORD dst_unused:UNUSED_PAD src0_sel:WORD_1
	v_add_f32_e32 v116, v116, v154
	v_add_f32_e32 v117, v117, v155
	v_add_f32_e32 v118, v118, v152
	v_add_f32_e32 v119, v119, v153
	v_add_f32_e32 v112, v112, v156
	v_add_f32_e32 v113, v113, v157
	v_add_f32_e32 v114, v114, v120
	v_add_f32_e32 v115, v115, v121
	s_nop 0
	v_cvt_pk_f16_f32 v115, v114, v115
	v_cvt_pk_f16_f32 v114, v112, v113
	v_cvt_pk_f16_f32 v113, v118, v119
	v_cvt_pk_f16_f32 v112, v116, v117
	global_store_dwordx4 v[158:159], v[112:115], off offset:256
	global_load_dwordx4 v[112:115], v[126:127], off
	v_lshl_add_u64 v[116:117], s[14:15], 0, v[124:125]
	s_waitcnt vmcnt(0)
	v_cvt_f32_f16_e32 v118, v113
	v_cvt_f32_f16_sdwa v119, v113 dst_sel:DWORD dst_unused:UNUSED_PAD src0_sel:WORD_1
	v_cvt_f32_f16_e32 v120, v112
	v_cvt_f32_f16_sdwa v121, v112 dst_sel:DWORD dst_unused:UNUSED_PAD src0_sel:WORD_1
	v_cvt_f32_f16_e32 v112, v115
	v_cvt_f32_f16_e32 v122, v114
	v_cvt_f32_f16_sdwa v123, v114 dst_sel:DWORD dst_unused:UNUSED_PAD src0_sel:WORD_1
	v_cvt_f32_f16_sdwa v113, v115 dst_sel:DWORD dst_unused:UNUSED_PAD src0_sel:WORD_1
	v_add_f32_e32 v108, v108, v120
	v_add_f32_e32 v109, v109, v121
	v_add_f32_e32 v110, v110, v118
	v_add_f32_e32 v111, v111, v119
	v_add_f32_e32 v104, v104, v122
	v_add_f32_e32 v105, v105, v123
	v_add_f32_e32 v106, v106, v112
	v_add_f32_e32 v107, v107, v113
	s_nop 0
	v_cvt_pk_f16_f32 v107, v106, v107
	v_cvt_pk_f16_f32 v106, v104, v105
	v_cvt_pk_f16_f32 v105, v110, v111
	v_cvt_pk_f16_f32 v104, v108, v109
	global_store_dwordx4 v[116:117], v[104:107], off
	global_load_dwordx4 v[104:107], v[126:127], off offset:256
	v_or_b32_e32 v108, 32, v144
	v_ashrrev_i32_e32 v109, 31, v108
	v_lshlrev_b64 v[108:109], 10, v[108:109]
	v_lshl_add_u64 v[108:109], v[108:109], 0, v[142:143]
	v_lshlrev_b64 v[108:109], 1, v[108:109]
	v_lshl_add_u64 v[110:111], s[12:13], 0, v[108:109]
	s_waitcnt vmcnt(0)
	v_cvt_f32_f16_e32 v112, v105
	v_cvt_f32_f16_sdwa v113, v105 dst_sel:DWORD dst_unused:UNUSED_PAD src0_sel:WORD_1
	v_cvt_f32_f16_e32 v114, v104
	v_cvt_f32_f16_sdwa v115, v104 dst_sel:DWORD dst_unused:UNUSED_PAD src0_sel:WORD_1
	v_cvt_f32_f16_e32 v104, v107
	v_cvt_f32_f16_e32 v118, v106
	v_cvt_f32_f16_sdwa v119, v106 dst_sel:DWORD dst_unused:UNUSED_PAD src0_sel:WORD_1
	v_cvt_f32_f16_sdwa v105, v107 dst_sel:DWORD dst_unused:UNUSED_PAD src0_sel:WORD_1
	v_add_f32_e32 v100, v100, v114
	v_add_f32_e32 v101, v101, v115
	v_add_f32_e32 v102, v102, v112
	v_add_f32_e32 v103, v103, v113
	v_add_f32_e32 v96, v96, v118
	v_add_f32_e32 v97, v97, v119
	v_add_f32_e32 v98, v98, v104
	v_add_f32_e32 v99, v99, v105
	s_nop 0
	v_cvt_pk_f16_f32 v99, v98, v99
	v_cvt_pk_f16_f32 v98, v96, v97
	v_cvt_pk_f16_f32 v97, v102, v103
	v_cvt_pk_f16_f32 v96, v100, v101
	global_store_dwordx4 v[116:117], v[96:99], off offset:256
	global_load_dwordx4 v[96:99], v[110:111], off
	v_lshl_add_u64 v[100:101], s[14:15], 0, v[108:109]
	s_waitcnt vmcnt(0)
; #define GAS __attribute__((address_space(1)))
;     __device__ __forceinline__ void operator()(const Acc& acc, const Unit& u, int wr, int wc, int fr, int fq) const {
;         const int row0 = u.pm * BM + wr * 64 + fr, col0 = u.pn * BM + wc * 32 + 8 * fq;
; #pragma unroll
;         for (int ai = 0; ai < 2; ++ai)
; #pragma unroll
;             for (int m = 0; m < 4; ++m) {
;                 const size_t off = (size_t)(row0 + ai * HALF + m * 16) * D + col0;
; #pragma unroll
;                 for (int bj = 0; bj < 2; ++bj) {
;                     const size_t p = off + bj * HALF;
;                     f32x4 b0, b1;
;                     if (BASE_F32) { b0 = *(const GAS f32x4*)((const float*)base + p); b1 = *(const GAS f32x4*)((const float*)base + p + 4); }
;                     else unpack8h(*(const GAS u32x4*)((const bf16_t*)base + p), b0, b1);
;                     b0 += acc[ai][bj][m][0]; b1 += acc[ai][bj][m][1];
;                     if (OUT_F32) { *(GAS f32x4*)((float*)out + p) = b0; *(GAS f32x4*)((float*)out + p + 4) = b1; }
;                     else *(GAS u32x4*)((bf16_t*)out + p) = pack8h(b0, b1);
;                 }
;                 asm volatile("" ::: "memory");
;             }
	v_cvt_f32_f16_e32 v102, v97
	v_cvt_f32_f16_sdwa v103, v97 dst_sel:DWORD dst_unused:UNUSED_PAD src0_sel:WORD_1
	v_cvt_f32_f16_e32 v104, v96
	v_cvt_f32_f16_sdwa v105, v96 dst_sel:DWORD dst_unused:UNUSED_PAD src0_sel:WORD_1
	v_cvt_f32_f16_e32 v96, v99
	v_cvt_f32_f16_e32 v106, v98
	v_cvt_f32_f16_sdwa v107, v98 dst_sel:DWORD dst_unused:UNUSED_PAD src0_sel:WORD_1
	v_cvt_f32_f16_sdwa v97, v99 dst_sel:DWORD dst_unused:UNUSED_PAD src0_sel:WORD_1
	v_add_f32_e32 v92, v92, v104
	v_add_f32_e32 v93, v93, v105
	v_add_f32_e32 v94, v94, v102
	v_add_f32_e32 v95, v95, v103
	v_add_f32_e32 v88, v88, v106
	v_add_f32_e32 v89, v89, v107
	v_add_f32_e32 v90, v90, v96
	v_add_f32_e32 v91, v91, v97
	s_nop 0
	v_cvt_pk_f16_f32 v91, v90, v91
	v_cvt_pk_f16_f32 v90, v88, v89
	v_cvt_pk_f16_f32 v89, v94, v95
	v_cvt_pk_f16_f32 v88, v92, v93
	global_store_dwordx4 v[100:101], v[88:91], off
	global_load_dwordx4 v[88:91], v[110:111], off offset:256
	v_or_b32_e32 v92, 48, v144
	v_ashrrev_i32_e32 v93, 31, v92
	v_lshlrev_b64 v[92:93], 10, v[92:93]
	v_lshl_add_u64 v[92:93], v[92:93], 0, v[142:143]
	v_lshlrev_b64 v[92:93], 1, v[92:93]
	v_lshl_add_u64 v[94:95], s[12:13], 0, v[92:93]
	s_waitcnt vmcnt(0)
	v_cvt_f32_f16_e32 v96, v89
	v_cvt_f32_f16_sdwa v97, v89 dst_sel:DWORD dst_unused:UNUSED_PAD src0_sel:WORD_1
	v_cvt_f32_f16_e32 v98, v88
	v_cvt_f32_f16_sdwa v99, v88 dst_sel:DWORD dst_unused:UNUSED_PAD src0_sel:WORD_1
	v_cvt_f32_f16_e32 v88, v91
	v_cvt_f32_f16_e32 v102, v90
	v_cvt_f32_f16_sdwa v103, v90 dst_sel:DWORD dst_unused:UNUSED_PAD src0_sel:WORD_1
	v_cvt_f32_f16_sdwa v89, v91 dst_sel:DWORD dst_unused:UNUSED_PAD src0_sel:WORD_1
	v_add_f32_e32 v84, v84, v98
	v_add_f32_e32 v85, v85, v99
	v_add_f32_e32 v86, v86, v96
	v_add_f32_e32 v87, v87, v97
	v_add_f32_e32 v80, v80, v102
	v_add_f32_e32 v81, v81, v103
	v_add_f32_e32 v82, v82, v88
	v_add_f32_e32 v83, v83, v89
	s_nop 0
	v_cvt_pk_f16_f32 v83, v82, v83
	v_cvt_pk_f16_f32 v82, v80, v81
	v_cvt_pk_f16_f32 v81, v86, v87
	v_cvt_pk_f16_f32 v80, v84, v85
	global_store_dwordx4 v[100:101], v[80:83], off offset:256
	global_load_dwordx4 v[80:83], v[94:95], off
	v_lshl_add_u64 v[84:85], s[14:15], 0, v[92:93]
	s_waitcnt vmcnt(0)
	v_cvt_f32_f16_e32 v86, v81
	v_cvt_f32_f16_sdwa v87, v81 dst_sel:DWORD dst_unused:UNUSED_PAD src0_sel:WORD_1
	v_cvt_f32_f16_e32 v88, v80
	v_cvt_f32_f16_sdwa v89, v80 dst_sel:DWORD dst_unused:UNUSED_PAD src0_sel:WORD_1
	v_cvt_f32_f16_e32 v80, v83
	v_cvt_f32_f16_e32 v90, v82
	v_cvt_f32_f16_sdwa v91, v82 dst_sel:DWORD dst_unused:UNUSED_PAD src0_sel:WORD_1
	v_cvt_f32_f16_sdwa v81, v83 dst_sel:DWORD dst_unused:UNUSED_PAD src0_sel:WORD_1
	v_add_f32_e32 v76, v76, v88
	v_add_f32_e32 v77, v77, v89
	v_add_f32_e32 v78, v78, v86
	v_add_f32_e32 v79, v79, v87
	v_add_f32_e32 v72, v72, v90
	v_add_f32_e32 v73, v73, v91
	v_add_f32_e32 v74, v74, v80
	v_add_f32_e32 v75, v75, v81
	s_nop 0
	v_cvt_pk_f16_f32 v75, v74, v75
	v_cvt_pk_f16_f32 v74, v72, v73
	v_cvt_pk_f16_f32 v73, v78, v79
	v_cvt_pk_f16_f32 v72, v76, v77
	global_store_dwordx4 v[84:85], v[72:75], off
	global_load_dwordx4 v[72:75], v[94:95], off offset:256
	v_lshl_add_u64 v[76:77], v[140:141], 0, s[16:17]
	v_lshl_add_u64 v[78:79], s[12:13], 0, v[76:77]
	s_waitcnt vmcnt(0)
	v_cvt_f32_f16_e32 v80, v73
	v_cvt_f32_f16_sdwa v81, v73 dst_sel:DWORD dst_unused:UNUSED_PAD src0_sel:WORD_1
	v_cvt_f32_f16_e32 v82, v72
	v_cvt_f32_f16_sdwa v83, v72 dst_sel:DWORD dst_unused:UNUSED_PAD src0_sel:WORD_1
	v_cvt_f32_f16_e32 v72, v75
	v_cvt_f32_f16_e32 v86, v74
	v_cvt_f32_f16_sdwa v87, v74 dst_sel:DWORD dst_unused:UNUSED_PAD src0_sel:WORD_1
	v_cvt_f32_f16_sdwa v73, v75 dst_sel:DWORD dst_unused:UNUSED_PAD src0_sel:WORD_1
	v_add_f32_e32 v68, v68, v82
	v_add_f32_e32 v69, v69, v83
	v_add_f32_e32 v70, v70, v80
	v_add_f32_e32 v71, v71, v81
	v_add_f32_e32 v64, v64, v86
	v_add_f32_e32 v65, v65, v87
	v_add_f32_e32 v66, v66, v72
	v_add_f32_e32 v67, v67, v73
	s_nop 0
	v_cvt_pk_f16_f32 v67, v66, v67
	v_cvt_pk_f16_f32 v66, v64, v65
	v_cvt_pk_f16_f32 v65, v70, v71
	v_cvt_pk_f16_f32 v64, v68, v69
	global_store_dwordx4 v[84:85], v[64:67], off offset:256
	global_load_dwordx4 v[64:67], v[78:79], off
	v_lshl_add_u64 v[68:69], s[14:15], 0, v[76:77]
	s_waitcnt vmcnt(0)
	v_cvt_f32_f16_e32 v70, v65
	v_cvt_f32_f16_sdwa v71, v65 dst_sel:DWORD dst_unused:UNUSED_PAD src0_sel:WORD_1
	v_cvt_f32_f16_e32 v72, v64
	v_cvt_f32_f16_sdwa v73, v64 dst_sel:DWORD dst_unused:UNUSED_PAD src0_sel:WORD_1
	v_cvt_f32_f16_e32 v64, v67
	v_cvt_f32_f16_e32 v74, v66
	v_cvt_f32_f16_sdwa v75, v66 dst_sel:DWORD dst_unused:UNUSED_PAD src0_sel:WORD_1
	v_cvt_f32_f16_sdwa v65, v67 dst_sel:DWORD dst_unused:UNUSED_PAD src0_sel:WORD_1
	v_add_f32_e32 v60, v60, v72
	v_add_f32_e32 v61, v61, v73
	v_add_f32_e32 v62, v62, v70
	v_add_f32_e32 v63, v63, v71
	v_add_f32_e32 v56, v56, v74
	v_add_f32_e32 v57, v57, v75
	v_add_f32_e32 v58, v58, v64
	v_add_f32_e32 v59, v59, v65
	s_nop 0
	v_cvt_pk_f16_f32 v59, v58, v59
	v_cvt_pk_f16_f32 v58, v56, v57
	v_cvt_pk_f16_f32 v57, v62, v63
	v_cvt_pk_f16_f32 v56, v60, v61
	global_store_dwordx4 v[68:69], v[56:59], off
	global_load_dwordx4 v[56:59], v[78:79], off offset:256
	v_lshl_add_u64 v[60:61], v[140:141], 0, s[18:19]
	v_lshl_add_u64 v[62:63], s[12:13], 0, v[60:61]
	s_waitcnt vmcnt(0)
; #define GAS __attribute__((address_space(1)))
;     __device__ __forceinline__ void operator()(const Acc& acc, const Unit& u, int wr, int wc, int fr, int fq) const {
;         const int row0 = u.pm * BM + wr * 64 + fr, col0 = u.pn * BM + wc * 32 + 8 * fq;
; #pragma unroll
;         for (int ai = 0; ai < 2; ++ai)
; #pragma unroll
;             for (int m = 0; m < 4; ++m) {
;                 const size_t off = (size_t)(row0 + ai * HALF + m * 16) * D + col0;
; #pragma unroll
;                 for (int bj = 0; bj < 2; ++bj) {
;                     const size_t p = off + bj * HALF;
;                     f32x4 b0, b1;
;                     if (BASE_F32) { b0 = *(const GAS f32x4*)((const float*)base + p); b1 = *(const GAS f32x4*)((const float*)base + p + 4); }
;                     else unpack8h(*(const GAS u32x4*)((const bf16_t*)base + p), b0, b1);
;                     b0 += acc[ai][bj][m][0]; b1 += acc[ai][bj][m][1];
;                     if (OUT_F32) { *(GAS f32x4*)((float*)out + p) = b0; *(GAS f32x4*)((float*)out + p + 4) = b1; }
;                     else *(GAS u32x4*)((bf16_t*)out + p) = pack8h(b0, b1);
;                 }
;                 asm volatile("" ::: "memory");
;             }
	v_cvt_f32_f16_e32 v64, v57
	v_cvt_f32_f16_sdwa v65, v57 dst_sel:DWORD dst_unused:UNUSED_PAD src0_sel:WORD_1
	v_cvt_f32_f16_e32 v66, v56
	v_cvt_f32_f16_sdwa v67, v56 dst_sel:DWORD dst_unused:UNUSED_PAD src0_sel:WORD_1
	v_cvt_f32_f16_e32 v56, v59
	v_cvt_f32_f16_e32 v70, v58
	v_cvt_f32_f16_sdwa v71, v58 dst_sel:DWORD dst_unused:UNUSED_PAD src0_sel:WORD_1
	v_cvt_f32_f16_sdwa v57, v59 dst_sel:DWORD dst_unused:UNUSED_PAD src0_sel:WORD_1
	v_add_f32_e32 v52, v52, v66
	v_add_f32_e32 v53, v53, v67
	v_add_f32_e32 v54, v54, v64
	v_add_f32_e32 v55, v55, v65
	v_add_f32_e32 v48, v48, v70
	v_add_f32_e32 v49, v49, v71
	v_add_f32_e32 v50, v50, v56
	v_add_f32_e32 v51, v51, v57
	s_nop 0
	v_cvt_pk_f16_f32 v51, v50, v51
	v_cvt_pk_f16_f32 v50, v48, v49
	v_cvt_pk_f16_f32 v49, v54, v55
	v_cvt_pk_f16_f32 v48, v52, v53
	global_store_dwordx4 v[68:69], v[48:51], off offset:256
	global_load_dwordx4 v[48:51], v[62:63], off
	v_lshl_add_u64 v[52:53], s[14:15], 0, v[60:61]
	s_waitcnt vmcnt(0)
	v_cvt_f32_f16_e32 v54, v49
	v_cvt_f32_f16_sdwa v55, v49 dst_sel:DWORD dst_unused:UNUSED_PAD src0_sel:WORD_1
	v_cvt_f32_f16_e32 v56, v48
	v_cvt_f32_f16_sdwa v57, v48 dst_sel:DWORD dst_unused:UNUSED_PAD src0_sel:WORD_1
	v_cvt_f32_f16_e32 v48, v51
	v_cvt_f32_f16_e32 v58, v50
	v_cvt_f32_f16_sdwa v59, v50 dst_sel:DWORD dst_unused:UNUSED_PAD src0_sel:WORD_1
	v_cvt_f32_f16_sdwa v49, v51 dst_sel:DWORD dst_unused:UNUSED_PAD src0_sel:WORD_1
	v_add_f32_e32 v44, v44, v56
	v_add_f32_e32 v45, v45, v57
	v_add_f32_e32 v46, v46, v54
	v_add_f32_e32 v47, v47, v55
	v_add_f32_e32 v40, v40, v58
	v_add_f32_e32 v41, v41, v59
	v_add_f32_e32 v42, v42, v48
	v_add_f32_e32 v43, v43, v49
	s_nop 0
	v_cvt_pk_f16_f32 v43, v42, v43
	v_cvt_pk_f16_f32 v42, v40, v41
	v_cvt_pk_f16_f32 v41, v46, v47
	v_cvt_pk_f16_f32 v40, v44, v45
	global_store_dwordx4 v[52:53], v[40:43], off
	global_load_dwordx4 v[40:43], v[62:63], off offset:256
	v_lshl_add_u64 v[44:45], v[140:141], 0, s[20:21]
	v_lshl_add_u64 v[46:47], s[12:13], 0, v[44:45]
	s_waitcnt vmcnt(0)
	v_cvt_f32_f16_e32 v48, v41
	v_cvt_f32_f16_sdwa v49, v41 dst_sel:DWORD dst_unused:UNUSED_PAD src0_sel:WORD_1
	v_cvt_f32_f16_e32 v50, v40
	v_cvt_f32_f16_sdwa v51, v40 dst_sel:DWORD dst_unused:UNUSED_PAD src0_sel:WORD_1
	v_cvt_f32_f16_e32 v40, v43
	v_cvt_f32_f16_e32 v54, v42
	v_cvt_f32_f16_sdwa v55, v42 dst_sel:DWORD dst_unused:UNUSED_PAD src0_sel:WORD_1
	v_cvt_f32_f16_sdwa v41, v43 dst_sel:DWORD dst_unused:UNUSED_PAD src0_sel:WORD_1
	v_add_f32_e32 v36, v36, v50
	v_add_f32_e32 v37, v37, v51
	v_add_f32_e32 v38, v38, v48
	v_add_f32_e32 v39, v39, v49
	v_add_f32_e32 v32, v32, v54
	v_add_f32_e32 v33, v33, v55
	v_add_f32_e32 v34, v34, v40
	v_add_f32_e32 v35, v35, v41
	s_nop 0
	v_cvt_pk_f16_f32 v35, v34, v35
	v_cvt_pk_f16_f32 v34, v32, v33
	v_cvt_pk_f16_f32 v33, v38, v39
	v_cvt_pk_f16_f32 v32, v36, v37
	global_store_dwordx4 v[52:53], v[32:35], off offset:256
	global_load_dwordx4 v[32:35], v[46:47], off
	v_lshl_add_u64 v[36:37], s[14:15], 0, v[44:45]
	s_waitcnt vmcnt(0)
	v_cvt_f32_f16_e32 v38, v33
	v_cvt_f32_f16_sdwa v39, v33 dst_sel:DWORD dst_unused:UNUSED_PAD src0_sel:WORD_1
	v_cvt_f32_f16_e32 v40, v32
	v_cvt_f32_f16_sdwa v41, v32 dst_sel:DWORD dst_unused:UNUSED_PAD src0_sel:WORD_1
	v_cvt_f32_f16_e32 v32, v35
	v_cvt_f32_f16_e32 v42, v34
	v_cvt_f32_f16_sdwa v43, v34 dst_sel:DWORD dst_unused:UNUSED_PAD src0_sel:WORD_1
	v_cvt_f32_f16_sdwa v33, v35 dst_sel:DWORD dst_unused:UNUSED_PAD src0_sel:WORD_1
	v_add_f32_e32 v28, v28, v40
	v_add_f32_e32 v29, v29, v41
	v_add_f32_e32 v30, v30, v38
	v_add_f32_e32 v31, v31, v39
	v_add_f32_e32 v24, v24, v42
	v_add_f32_e32 v25, v25, v43
	v_add_f32_e32 v26, v26, v32
	v_add_f32_e32 v27, v27, v33
	s_nop 0
	v_cvt_pk_f16_f32 v27, v26, v27
	v_cvt_pk_f16_f32 v26, v24, v25
	v_cvt_pk_f16_f32 v25, v30, v31
	v_cvt_pk_f16_f32 v24, v28, v29
	global_store_dwordx4 v[36:37], v[24:27], off
	global_load_dwordx4 v[24:27], v[46:47], off offset:256
	v_lshl_add_u64 v[28:29], v[140:141], 0, s[24:25]
	v_lshl_add_u64 v[30:31], s[12:13], 0, v[28:29]
	s_waitcnt vmcnt(0)
	v_cvt_f32_f16_e32 v32, v25
	v_cvt_f32_f16_sdwa v33, v25 dst_sel:DWORD dst_unused:UNUSED_PAD src0_sel:WORD_1
	v_cvt_f32_f16_e32 v34, v24
	v_cvt_f32_f16_sdwa v35, v24 dst_sel:DWORD dst_unused:UNUSED_PAD src0_sel:WORD_1
	v_cvt_f32_f16_e32 v24, v27
	v_cvt_f32_f16_e32 v38, v26
	v_cvt_f32_f16_sdwa v39, v26 dst_sel:DWORD dst_unused:UNUSED_PAD src0_sel:WORD_1
	v_cvt_f32_f16_sdwa v25, v27 dst_sel:DWORD dst_unused:UNUSED_PAD src0_sel:WORD_1
	v_add_f32_e32 v20, v20, v34
	v_add_f32_e32 v21, v21, v35
	v_add_f32_e32 v22, v22, v32
	v_add_f32_e32 v23, v23, v33
	v_add_f32_e32 v16, v16, v38
	v_add_f32_e32 v17, v17, v39
	v_add_f32_e32 v18, v18, v24
	v_add_f32_e32 v19, v19, v25
	s_nop 0
	v_cvt_pk_f16_f32 v19, v18, v19
	v_cvt_pk_f16_f32 v18, v16, v17
	v_cvt_pk_f16_f32 v17, v22, v23
	v_cvt_pk_f16_f32 v16, v20, v21
	global_store_dwordx4 v[36:37], v[16:19], off offset:256
	global_load_dwordx4 v[16:19], v[30:31], off
	v_lshl_add_u64 v[20:21], s[14:15], 0, v[28:29]
	s_waitcnt vmcnt(0)
	v_cvt_f32_f16_e32 v22, v17
	v_cvt_f32_f16_sdwa v23, v17 dst_sel:DWORD dst_unused:UNUSED_PAD src0_sel:WORD_1
	v_cvt_f32_f16_e32 v24, v16
	v_cvt_f32_f16_sdwa v25, v16 dst_sel:DWORD dst_unused:UNUSED_PAD src0_sel:WORD_1
	v_cvt_f32_f16_e32 v16, v19
	v_cvt_f32_f16_e32 v26, v18
	v_cvt_f32_f16_sdwa v27, v18 dst_sel:DWORD dst_unused:UNUSED_PAD src0_sel:WORD_1
	v_cvt_f32_f16_sdwa v17, v19 dst_sel:DWORD dst_unused:UNUSED_PAD src0_sel:WORD_1
	v_add_f32_e32 v12, v12, v24
	v_add_f32_e32 v13, v13, v25
	v_add_f32_e32 v14, v14, v22
	v_add_f32_e32 v15, v15, v23
	v_add_f32_e32 v8, v8, v26
	v_add_f32_e32 v9, v9, v27
	v_add_f32_e32 v10, v10, v16
	v_add_f32_e32 v11, v11, v17
	s_nop 0
	v_cvt_pk_f16_f32 v11, v10, v11
	v_cvt_pk_f16_f32 v10, v8, v9
	v_cvt_pk_f16_f32 v9, v14, v15
	v_cvt_pk_f16_f32 v8, v12, v13
	global_store_dwordx4 v[20:21], v[8:11], off
	global_load_dwordx4 v[8:11], v[30:31], off offset:256
	s_waitcnt vmcnt(0)
	v_cvt_f32_f16_e32 v12, v9
	v_cvt_f32_f16_sdwa v13, v9 dst_sel:DWORD dst_unused:UNUSED_PAD src0_sel:WORD_1
	v_cvt_f32_f16_e32 v14, v8
	v_cvt_f32_f16_sdwa v15, v8 dst_sel:DWORD dst_unused:UNUSED_PAD src0_sel:WORD_1
	v_cvt_f32_f16_e32 v8, v11
	v_cvt_f32_f16_e32 v16, v10
	v_cvt_f32_f16_sdwa v17, v10 dst_sel:DWORD dst_unused:UNUSED_PAD src0_sel:WORD_1
	v_cvt_f32_f16_sdwa v9, v11 dst_sel:DWORD dst_unused:UNUSED_PAD src0_sel:WORD_1
	v_add_f32_e32 v4, v4, v14
	v_add_f32_e32 v5, v5, v15
	v_add_f32_e32 v6, v6, v12
	v_add_f32_e32 v7, v7, v13
	v_add_f32_e32 v0, v0, v16
	v_add_f32_e32 v1, v1, v17
	v_add_f32_e32 v2, v2, v8
	v_add_f32_e32 v3, v3, v9
	s_nop 0
	v_cvt_pk_f16_f32 v3, v2, v3
	v_cvt_pk_f16_f32 v2, v0, v1
	v_cvt_pk_f16_f32 v1, v6, v7
	v_cvt_pk_f16_f32 v0, v4, v5
	global_store_dwordx4 v[20:21], v[0:3], off offset:256
	s_cbranch_vccnz .LBB0_543
	s_andn2_b64 vcc, exec, s[8:9]
	s_cbranch_vccnz .LBB0_542
	s_barrier
	s_branch .LBB0_542

; #define GAS __attribute__((address_space(1)))
; __device__ __forceinline__ void rmsnorm_rows_rwkv(const bf16_t* x, const float* gain, const float* mu_r, const float* mu_k, bf16_t* H, bf16_t* XR, bf16_t* XK, int gw, int NGW, int lane) {
;     ...
;         for (int r = 0; r <= RB; ++r) {
;             const float rstd = (first && r == 0) ? 0.f : rsqrtf(s[r] * (1.f / D) + 1e-6f);
; #pragma unroll
;             for (int j = 0; j < 2; ++j)
; #pragma unroll
;                 for (int e = 0; e < 2; ++e) v[r][j][e] = v[r][j][e] * rstd * g[j][e];
;         }
; #pragma unroll
;         for (int r = 1; r <= RB; ++r) {
;             const int row = row0 + r - 1;
;             const size_t hrow = (size_t)row + (row >> 12) + 1;
; #pragma unroll
;             for (int j = 0; j < 2; ++j) {
;                 const size_t co = (size_t)512 * j + lane * 8;
;                 *(GAS u32x4*)(H + hrow * D + co) = pack8(v[r][j][0], v[r][j][1]);
;                 const f32x4 d0 = v[r - 1][j][0] - v[r][j][0], d1 = v[r - 1][j][1] - v[r][j][1];
;                 *(GAS u32x4*)(XR + (size_t)row * D + co) = pack8(v[r][j][0] + d0 * mr[j][0], v[r][j][1] + d1 * mr[j][1]);
;                 *(GAS u32x4*)(XK + (size_t)row * D + co) = pack8(v[r][j][0] + d0 * mk[j][0], v[r][j][1] + d1 * mk[j][1]);
.LBB0_759:
	s_waitcnt lgkmcnt(2)
	v_add_f32_e32 v152, v152, v154
	v_add_f32_e32 v153, v153, v155
	v_cvt_f32_f16_e32 v140, v54
	v_fma_f32 v152, v152, s28, v62
	v_fma_f32 v153, v153, s28, v62
	v_mov_b32_e32 v54, v97
	v_mul_f32_e32 v97, 0x4b800000, v153
	v_cmp_gt_f32_e32 vcc, s40, v153
	v_cvt_f32_f16_e32 v132, v50
	v_cvt_f32_f16_e32 v144, v52
	v_cndmask_b32_e32 v97, v153, v97, vcc
	v_rsq_f32_e32 v97, v97
	v_mov_b32_e32 v52, v103
	v_cvt_f32_f16_e32 v142, v53
	v_cvt_f32_f16_e32 v134, v49
	v_mul_f32_e32 v103, 0x45800000, v97
	v_cvt_f32_f16_e32 v136, v48
	v_mov_b32_e32 v48, v111
	v_mov_b32_e32 v49, v115
	v_mul_f32_e32 v174, v146, v132
	v_mul_f32_e32 v175, v146, v133
	v_cndmask_b32_e32 v132, v97, v103, vcc
	v_cvt_f32_f16_e32 v130, v51
	v_mul_f32_e32 v48, v132, v48
	v_mul_f32_e32 v49, v132, v49
	s_ashr_i32 s5, s45, 12
	v_cvt_f32_f16_e32 v138, v55
	v_mul_f32_e32 v166, v146, v140
	v_mul_f32_e32 v167, v146, v141
	v_mul_f32_e32 v140, v8, v48
	v_mul_f32_e32 v141, v9, v49
	v_mov_b32_e32 v48, v95
	v_mov_b32_e32 v49, v105
	s_ashr_i32 s7, s5, 31
	v_mul_f32_e32 v48, v132, v48
	v_mul_f32_e32 v49, v132, v49
	s_add_u32 s6, s12, s26
	v_mov_b32_e32 v50, v107
	v_mov_b32_e32 v51, v117
	v_mul_f32_e32 v154, v146, v142
	v_mul_f32_e32 v155, v146, v143
	v_mul_f32_e32 v142, v18, v48
	v_mul_f32_e32 v143, v19, v49
	v_mov_b32_e32 v48, v91
	v_mov_b32_e32 v49, v99
	s_addc_u32 s46, s13, s27
	v_mov_b32_e32 v53, v121
	v_mul_f32_e32 v172, v146, v130
	v_mul_f32_e32 v173, v146, v131
	v_mov_b32_e32 v130, v101
	v_mov_b32_e32 v131, v109
	v_mul_f32_e32 v50, v132, v50
	v_mul_f32_e32 v51, v132, v51
	v_mul_f32_e32 v48, v132, v48
	v_mul_f32_e32 v49, v132, v49
	s_add_u32 s6, s6, s5
	v_mov_b32_e32 v55, v125
	v_mul_f32_e32 v164, v146, v138
	v_mul_f32_e32 v165, v146, v139
	v_mul_f32_e32 v168, v146, v134
	v_mul_f32_e32 v169, v146, v135
	v_mul_f32_e32 v130, v132, v130
	v_mul_f32_e32 v131, v132, v131
	v_mul_f32_e32 v138, v16, v50
	v_mul_f32_e32 v139, v17, v51
	v_mul_f32_e32 v50, v132, v52
	v_mul_f32_e32 v51, v132, v53
	v_mul_f32_e32 v134, v22, v48
	v_mul_f32_e32 v135, v23, v49
	v_mov_b32_e32 v48, v89
	v_mov_b32_e32 v49, v93
	s_addc_u32 s7, s46, s7
	v_mul_f32_e32 v162, v146, v144
	v_mul_f32_e32 v163, v146, v145
	v_mul_f32_e32 v144, v10, v130
	v_mul_f32_e32 v145, v11, v131
	v_mul_f32_e32 v130, v20, v50
	v_mul_f32_e32 v131, v21, v51
	v_mul_f32_e32 v48, v132, v48
	v_mul_f32_e32 v49, v132, v49
	v_mul_f32_e32 v50, v132, v54
	v_mul_f32_e32 v51, v132, v55
	s_lshl_b64 s[6:7], s[6:7], 11
	v_mul_f32_e32 v170, v146, v136
	v_mul_f32_e32 v171, v146, v137
	v_mul_f32_e32 v54, v12, v50
	v_mul_f32_e32 v55, v13, v51
	v_mul_f32_e32 v132, v14, v48
	v_mul_f32_e32 v133, v15, v49
	v_cvt_pk_bf16_f32 v50, v140, v141
	v_cvt_pk_bf16_f32 v51, v144, v145
	v_cvt_pk_bf16_f32 v52, v138, v139
	v_cvt_pk_bf16_f32 v53, v142, v143
	v_lshl_add_u64 v[48:49], v[60:61], 0, s[6:7]
	v_fma_f32 v146, v10, v154, -v144
	v_fma_f32 v147, v11, v155, -v145
	global_store_dwordx4 v[48:49], v[50:53], off offset:2048
	v_fma_f32 v154, v16, v166, -v138
	v_fma_f32 v155, v17, v167, -v139
	v_fma_f32 v166, v18, v164, -v142
	v_fma_f32 v167, v19, v165, -v143
	v_fma_f32 v52, v8, v162, -v140
	v_fma_f32 v53, v9, v163, -v141
	v_fma_f32 v50, v6, v146, v144
	v_fma_f32 v51, v7, v147, v145
	v_fma_f32 v136, v4, v52, v140
	v_fma_f32 v137, v5, v53, v141
	v_cvt_pk_bf16_f32 v163, v50, v51
	v_lshl_add_u64 v[50:51], s[20:21], 0, v[56:57]
	v_fma_f32 v176, v2, v166, v142
	v_fma_f32 v177, v3, v167, v143
	v_fma_f32 v164, v0, v154, v138
	v_fma_f32 v165, v1, v155, v139
	v_cvt_pk_bf16_f32 v162, v136, v137
	v_add_co_u32_e32 v136, vcc, s41, v50
	v_cvt_pk_bf16_f32 v164, v164, v165
	v_cvt_pk_bf16_f32 v165, v176, v177
	v_addc_co_u32_e32 v137, vcc, 0, v51, vcc
	v_fma_f32 v52, v32, v52, v140
	v_fma_f32 v53, v33, v53, v141
	global_store_dwordx4 v[136:137], v[162:165], off
	v_fma_f32 v146, v34, v146, v144
	v_fma_f32 v147, v35, v147, v145
	v_fma_f32 v166, v42, v166, v142
	v_fma_f32 v167, v43, v167, v143
	v_cvt_pk_bf16_f32 v162, v52, v53
	v_lshl_add_u64 v[52:53], s[16:17], 0, v[56:57]
	v_fma_f32 v154, v40, v154, v138
	v_fma_f32 v155, v41, v155, v139
	v_cvt_pk_bf16_f32 v163, v146, v147
	v_add_co_u32_e32 v146, vcc, s42, v52
	v_cvt_pk_bf16_f32 v164, v154, v155
	v_cvt_pk_bf16_f32 v165, v166, v167
	v_addc_co_u32_e32 v147, vcc, 0, v53, vcc
	global_store_dwordx4 v[146:147], v[162:165], off
	v_fma_f32 v154, v20, v170, -v130
	v_fma_f32 v155, v21, v171, -v131
	v_fma_f32 v166, v22, v168, -v134
	v_fma_f32 v167, v23, v169, -v135
	v_cvt_pk_bf16_f32 v162, v130, v131
	v_cvt_pk_bf16_f32 v163, v134, v135
	v_cvt_pk_bf16_f32 v164, v54, v55
	v_cvt_pk_bf16_f32 v165, v132, v133
	v_fma_f32 v168, v12, v174, -v54
	v_fma_f32 v169, v13, v175, -v55
	v_fma_f32 v170, v14, v172, -v132
	v_fma_f32 v171, v15, v173, -v133
	global_store_dwordx4 v[48:49], v[162:165], off offset:3072
	v_fma_f32 v172, v26, v170, v132
	v_fma_f32 v173, v27, v171, v133
	v_fma_f32 v174, v24, v168, v54
	v_fma_f32 v175, v25, v169, v55
	v_fma_f32 v164, v30, v166, v134
	v_fma_f32 v165, v31, v167, v135
	v_fma_f32 v162, v28, v154, v130
	v_fma_f32 v163, v29, v155, v131
	v_fma_f32 v154, v44, v154, v130
	v_fma_f32 v155, v45, v155, v131
	v_cvt_pk_bf16_f32 v162, v162, v163
	v_cvt_pk_bf16_f32 v163, v164, v165
	v_cvt_pk_bf16_f32 v164, v174, v175
	v_cvt_pk_bf16_f32 v165, v172, v173
	global_store_dwordx4 v[136:137], v[162:165], off offset:1024
	v_fma_f32 v168, v36, v168, v54
	v_fma_f32 v169, v37, v169, v55
	v_cmp_ne_u32_e32 vcc, 1, v112
	v_fma_f32 v164, v46, v166, v134
	v_fma_f32 v165, v47, v167, v135
	v_fma_f32 v166, v38, v170, v132
	v_fma_f32 v167, v39, v171, v133
	v_cmp_gt_f32_e64 s[2:3], s40, v152
	v_cvt_pk_bf16_f32 v162, v154, v155
	v_cvt_pk_bf16_f32 v163, v164, v165
	v_cvt_pk_bf16_f32 v164, v168, v169
	v_cvt_pk_bf16_f32 v165, v166, v167
	global_store_dwordx4 v[146:147], v[162:165], off offset:1024
	s_cbranch_vccz .LBB0_763
; #define GAS __attribute__((address_space(1)))
; __device__ __forceinline__ void rmsnorm_rows_rwkv(const bf16_t* x, const float* gain, const float* mu_r, const float* mu_k, bf16_t* H, bf16_t* XR, bf16_t* XK, int gw, int NGW, int lane) {
;     ...
;         for (int r = 0; r <= RB; ++r) {
;             const float rstd = (first && r == 0) ? 0.f : rsqrtf(s[r] * (1.f / D) + 1e-6f);
; #pragma unroll
;             for (int j = 0; j < 2; ++j)
; #pragma unroll
;                 for (int e = 0; e < 2; ++e) v[r][j][e] = v[r][j][e] * rstd * g[j][e];
;         }
; #pragma unroll
;         for (int r = 1; r <= RB; ++r) {
;             const int row = row0 + r - 1;
;             const size_t hrow = (size_t)row + (row >> 12) + 1;
; #pragma unroll
;             for (int j = 0; j < 2; ++j) {
;                 const size_t co = (size_t)512 * j + lane * 8;
;                 *(GAS u32x4*)(H + hrow * D + co) = pack8(v[r][j][0], v[r][j][1]);
;                 const f32x4 d0 = v[r - 1][j][0] - v[r][j][0], d1 = v[r - 1][j][1] - v[r][j][1];
;                 *(GAS u32x4*)(XR + (size_t)row * D + co) = pack8(v[r][j][0] + d0 * mr[j][0], v[r][j][1] + d1 * mr[j][1]);
;                 *(GAS u32x4*)(XK + (size_t)row * D + co) = pack8(v[r][j][0] + d0 * mk[j][0], v[r][j][1] + d1 * mk[j][1]);
.LBB0_760:
	v_mov_b32_e32 v103, v120
	v_mov_b32_e32 v120, v73
	v_mul_f32_e32 v73, 0x4b800000, v152
	v_cndmask_b32_e64 v73, v152, v73, s[2:3]
	v_rsq_f32_e32 v89, v73
	v_mov_b32_e32 v107, v116
	v_mov_b32_e32 v116, v79
	v_mov_b32_e32 v117, v119
	v_mov_b32_e32 v79, v118
	s_waitcnt lgkmcnt(0)
	v_add_f32_e32 v118, v148, v150
	v_add_f32_e32 v119, v149, v151
	v_mul_f32_e32 v91, 0x45800000, v89
	v_mov_b32_e32 v73, v122
	v_cndmask_b32_e64 v122, v89, v91, s[2:3]
	v_mov_b32_e32 v91, v98
	v_mov_b32_e32 v89, v92
	v_fma_f32 v92, v118, s28, v62
	v_fma_f32 v93, v119, s28, v62
	v_mul_f32_e32 v98, v122, v90
	v_mul_f32_e32 v99, v122, v91
	v_mul_f32_e32 v90, 0x4b800000, v93
	v_cmp_gt_f32_e32 vcc, s40, v93
	v_mov_b32_e32 v95, v104
	v_mul_f32_e32 v118, v122, v88
	v_mul_f32_e32 v119, v122, v89
	v_cndmask_b32_e32 v90, v93, v90, vcc
	v_rsq_f32_e32 v90, v90
	v_mul_f32_e32 v104, v122, v94
	v_mul_f32_e32 v105, v122, v95
	v_mov_b32_e32 v91, v85
	v_mov_b32_e32 v97, v124
	v_mul_f32_e32 v88, 0x45800000, v90
	v_cndmask_b32_e32 v94, v90, v88, vcc
	v_mov_b32_e32 v90, v77
	v_mul_f32_e32 v90, v94, v90
	v_mul_f32_e32 v91, v94, v91
	v_mov_b32_e32 v112, v87
	v_mov_b32_e32 v113, v127
	v_mul_f32_e32 v152, v122, v96
	v_mul_f32_e32 v153, v122, v97
	v_mul_f32_e32 v96, v10, v90
	v_mul_f32_e32 v97, v11, v91
	v_mov_b32_e32 v90, v71
	v_mov_b32_e32 v91, v81
	v_mov_b32_e32 v111, v114
	v_mov_b32_e32 v114, v83
	v_mov_b32_e32 v115, v129
	v_mov_b32_e32 v121, v123
	v_mul_f32_e32 v88, v94, v112
	v_mul_f32_e32 v89, v94, v113
	v_mul_f32_e32 v90, v94, v90
	v_mul_f32_e32 v91, v94, v91
	v_mul_f32_e32 v112, v8, v88
	v_mul_f32_e32 v113, v9, v89
	v_mul_f32_e32 v88, v94, v114
	v_mul_f32_e32 v89, v94, v115
	v_mul_f32_e32 v114, v18, v90
	v_mul_f32_e32 v115, v19, v91
	v_mul_f32_e32 v90, v94, v116
	v_mul_f32_e32 v91, v94, v117
	v_mul_f32_e32 v116, v94, v120
	v_mul_f32_e32 v117, v94, v121
	v_mov_b32_e32 v120, v65
	v_mul_f32_e32 v65, 0x4b800000, v92
	v_cmp_gt_f32_e32 vcc, s40, v92
	v_mov_b32_e32 v101, v108
	v_mul_f32_e32 v110, v122, v110
	v_mul_f32_e32 v111, v122, v111
	v_cndmask_b32_e32 v65, v92, v65, vcc
	v_rsq_f32_e32 v65, v65
	v_mul_f32_e32 v100, v122, v100
	v_mul_f32_e32 v101, v122, v101
	v_mul_f32_e32 v106, v122, v106
	v_mul_f32_e32 v107, v122, v107
	v_mul_f32_e32 v162, v16, v88
	v_mul_f32_e32 v163, v17, v89
	v_mov_b32_e32 v88, v67
	v_mov_b32_e32 v89, v75
	v_mov_b32_e32 v121, v69
	v_mul_f32_e32 v67, 0x45800000, v65
	v_mov_b32_e32 v87, v126
	v_mov_b32_e32 v83, v128
	v_mul_f32_e32 v108, v10, v100
	v_mul_f32_e32 v109, v11, v101
	v_mul_f32_e32 v124, v8, v110
	v_mul_f32_e32 v125, v9, v111
	v_mul_f32_e32 v126, v18, v104
	v_mul_f32_e32 v127, v19, v105
	v_mul_f32_e32 v128, v16, v106
	v_mul_f32_e32 v129, v17, v107
	v_mul_f32_e32 v88, v94, v88
	v_mul_f32_e32 v89, v94, v89
	v_mul_f32_e32 v92, v94, v120
	v_mul_f32_e32 v93, v94, v121
	v_mul_f32_e32 v94, v12, v116
	v_mul_f32_e32 v95, v13, v117
	v_cndmask_b32_e32 v116, v65, v67, vcc
	v_xor_b32_e32 v175, 0x80000000, v11
	v_xor_b32_e32 v174, 0x80000000, v10
	v_xor_b32_e32 v177, 0x80000000, v19
	v_xor_b32_e32 v176, 0x80000000, v18
	v_mov_b32_e32 v67, v74
	v_mul_f32_e32 v170, v116, v72
	v_mul_f32_e32 v171, v116, v73
	v_cvt_pk_bf16_f32 v72, v124, v125
	v_cvt_pk_bf16_f32 v73, v108, v109
	v_cvt_pk_bf16_f32 v74, v128, v129
	v_cvt_pk_bf16_f32 v75, v126, v127
	v_lshl_add_u64 v[172:173], v[48:49], 0, s[30:31]
	v_fma_f32 v144, v174, v100, v144
	v_fma_f32 v145, v175, v101, v145
	v_fma_f32 v140, -v8, v110, v140
	v_fma_f32 v141, -v9, v111, v141
	v_fma_f32 v142, v176, v104, v142
	v_fma_f32 v143, v177, v105, v143
	v_fma_f32 v138, -v16, v106, v138
	v_fma_f32 v139, -v17, v107, v139
	global_store_dwordx4 v[172:173], v[72:75], off offset:2048
	v_fma_f32 v178, v2, v142, v126
	v_fma_f32 v179, v3, v143, v127
	v_fma_f32 v180, v0, v138, v128
	v_fma_f32 v181, v1, v139, v129
	v_fma_f32 v74, v6, v144, v108
	v_fma_f32 v75, v7, v145, v109
	v_fma_f32 v72, v4, v140, v124
	v_fma_f32 v73, v5, v141, v125
	v_mul_f32_e32 v102, v122, v102
	v_mul_f32_e32 v103, v122, v103
	v_cvt_pk_bf16_f32 v72, v72, v73
	v_cvt_pk_bf16_f32 v73, v74, v75
	v_cvt_pk_bf16_f32 v74, v180, v181
	v_cvt_pk_bf16_f32 v75, v178, v179
	global_store_dwordx4 v[136:137], v[72:75], off offset:2048
	v_mul_f32_e32 v148, v22, v98
	v_mul_f32_e32 v149, v23, v99
	v_mul_f32_e32 v150, v20, v102
	v_mul_f32_e32 v151, v21, v103
	v_fma_f32 v74, v34, v144, v108
	v_fma_f32 v75, v35, v145, v109
	v_fma_f32 v72, v32, v140, v124
	v_fma_f32 v73, v33, v141, v125
	v_fma_f32 v108, v42, v142, v126
	v_fma_f32 v109, v43, v143, v127
	v_fma_f32 v124, v40, v138, v128
	v_fma_f32 v125, v41, v139, v129
	v_mul_f32_e32 v122, v14, v118
	v_mul_f32_e32 v123, v15, v119
	v_mul_f32_e32 v154, v12, v152
	v_mul_f32_e32 v155, v13, v153
	v_cvt_pk_bf16_f32 v72, v72, v73
	v_cvt_pk_bf16_f32 v73, v74, v75
	v_cvt_pk_bf16_f32 v74, v124, v125
	v_cvt_pk_bf16_f32 v75, v108, v109
	v_xor_b32_e32 v109, 0x80000000, v23
	v_xor_b32_e32 v108, 0x80000000, v22
	v_xor_b32_e32 v129, 0x80000000, v15
	v_xor_b32_e32 v128, 0x80000000, v14
	global_store_dwordx4 v[146:147], v[72:75], off offset:2048
	v_fma_f32 v124, v108, v98, v134
	v_fma_f32 v125, v109, v99, v135
	v_fma_f32 v126, -v20, v102, v130
	v_fma_f32 v127, -v21, v103, v131
	v_cvt_pk_bf16_f32 v72, v150, v151
	v_cvt_pk_bf16_f32 v73, v148, v149
	v_cvt_pk_bf16_f32 v74, v154, v155
	v_cvt_pk_bf16_f32 v75, v122, v123
	v_fma_f32 v130, v128, v118, v132
	v_fma_f32 v131, v129, v119, v133
	v_fma_f32 v54, -v12, v152, v54
	v_fma_f32 v55, -v13, v153, v55
	global_store_dwordx4 v[172:173], v[72:75], off offset:3072
	v_fma_f32 v132, v26, v130, v122
	v_fma_f32 v133, v27, v131, v123
	v_fma_f32 v134, v24, v54, v154
	v_fma_f32 v135, v25, v55, v155
	v_fma_f32 v74, v30, v124, v148
; #define GAS __attribute__((address_space(1)))
; __device__ __forceinline__ void rmsnorm_rows_rwkv(const bf16_t* x, const float* gain, const float* mu_r, const float* mu_k, bf16_t* H, bf16_t* XR, bf16_t* XK, int gw, int NGW, int lane) {
;     ...
;         for (int r = 0; r <= RB; ++r) {
;             const float rstd = (first && r == 0) ? 0.f : rsqrtf(s[r] * (1.f / D) + 1e-6f);
; #pragma unroll
;             for (int j = 0; j < 2; ++j)
; #pragma unroll
;                 for (int e = 0; e < 2; ++e) v[r][j][e] = v[r][j][e] * rstd * g[j][e];
;         }
; #pragma unroll
;         for (int r = 1; r <= RB; ++r) {
;             const int row = row0 + r - 1;
;             const size_t hrow = (size_t)row + (row >> 12) + 1;
; #pragma unroll
;             for (int j = 0; j < 2; ++j) {
;                 const size_t co = (size_t)512 * j + lane * 8;
;                 *(GAS u32x4*)(H + hrow * D + co) = pack8(v[r][j][0], v[r][j][1]);
;                 const f32x4 d0 = v[r - 1][j][0] - v[r][j][0], d1 = v[r - 1][j][1] - v[r][j][1];
;                 *(GAS u32x4*)(XR + (size_t)row * D + co) = pack8(v[r][j][0] + d0 * mr[j][0], v[r][j][1] + d1 * mr[j][1]);
;                 *(GAS u32x4*)(XK + (size_t)row * D + co) = pack8(v[r][j][0] + d0 * mk[j][0], v[r][j][1] + d1 * mk[j][1]);
	v_fma_f32 v75, v31, v125, v149
	v_fma_f32 v72, v28, v126, v150
	v_fma_f32 v73, v29, v127, v151
	v_fma_f32 v122, v38, v130, v122
	v_fma_f32 v123, v39, v131, v123
	v_cvt_pk_bf16_f32 v72, v72, v73
	v_cvt_pk_bf16_f32 v73, v74, v75
	v_cvt_pk_bf16_f32 v74, v134, v135
	v_cvt_pk_bf16_f32 v75, v132, v133
	global_store_dwordx4 v[136:137], v[72:75], off offset:3072
	v_fma_f32 v54, v36, v54, v154
	v_fma_f32 v55, v37, v55, v155
	v_fma_f32 v110, v8, v110, -v112
	v_fma_f32 v111, v9, v111, -v113
	v_fma_f32 v74, v46, v124, v148
	v_fma_f32 v75, v47, v125, v149
	v_fma_f32 v72, v44, v126, v150
	v_fma_f32 v73, v45, v127, v151
	v_fma_f32 v100, v10, v100, -v96
	v_fma_f32 v101, v11, v101, -v97
	v_cvt_pk_bf16_f32 v72, v72, v73
	v_cvt_pk_bf16_f32 v73, v74, v75
	v_cvt_pk_bf16_f32 v74, v54, v55
	v_cvt_pk_bf16_f32 v75, v122, v123
	global_store_dwordx4 v[146:147], v[72:75], off offset:3072
	v_lshl_add_u64 v[54:55], v[48:49], 0, s[10:11]
	v_fma_f32 v104, v18, v104, -v114
	v_fma_f32 v105, v19, v105, -v115
	v_cvt_pk_bf16_f32 v72, v112, v113
	v_cvt_pk_bf16_f32 v73, v96, v97
	v_cvt_pk_bf16_f32 v74, v162, v163
	v_cvt_pk_bf16_f32 v75, v114, v115
	global_store_dwordx4 v[54:55], v[72:75], off offset:2048
	v_fma_f32 v106, v16, v106, -v162
	v_fma_f32 v107, v17, v107, -v163
	v_fma_f32 v122, v2, v104, v114
	v_fma_f32 v123, v3, v105, v115
	v_fma_f32 v74, v6, v100, v96
	v_fma_f32 v75, v7, v101, v97
	v_fma_f32 v72, v4, v110, v112
	v_fma_f32 v73, v5, v111, v113
	v_fma_f32 v124, v0, v106, v162
	v_fma_f32 v125, v1, v107, v163
	v_cvt_pk_bf16_f32 v72, v72, v73
	v_cvt_pk_bf16_f32 v73, v74, v75
	v_cvt_pk_bf16_f32 v75, v122, v123
	v_add_co_u32_e32 v122, vcc, s43, v50
	v_cvt_pk_bf16_f32 v74, v124, v125
	s_nop 0
	v_addc_co_u32_e32 v123, vcc, 0, v51, vcc
	global_store_dwordx4 v[122:123], v[72:75], off
	v_fma_f32 v50, v34, v100, v96
	v_fma_f32 v51, v35, v101, v97
	v_fma_f32 v100, v42, v104, v114
	v_fma_f32 v101, v43, v105, v115
	v_fma_f32 v74, v40, v106, v162
	v_fma_f32 v75, v41, v107, v163
	v_mul_f32_e32 v88, v22, v88
	v_mul_f32_e32 v89, v23, v89
	v_mul_f32_e32 v90, v20, v90
	v_mul_f32_e32 v91, v21, v91
	v_mul_f32_e32 v92, v14, v92
	v_mul_f32_e32 v93, v15, v93
	v_fma_f32 v72, v32, v110, v112
	v_fma_f32 v73, v33, v111, v113
	v_cvt_pk_bf16_f32 v74, v74, v75
	v_cvt_pk_bf16_f32 v75, v100, v101
	v_add_co_u32_e32 v100, vcc, s44, v52
	v_cvt_pk_bf16_f32 v72, v72, v73
	v_cvt_pk_bf16_f32 v73, v50, v51
	v_addc_co_u32_e32 v101, vcc, 0, v53, vcc
	v_cvt_pk_bf16_f32 v50, v90, v91
	v_cvt_pk_bf16_f32 v51, v88, v89
	v_cvt_pk_bf16_f32 v52, v94, v95
	v_cvt_pk_bf16_f32 v53, v92, v93
	global_store_dwordx4 v[100:101], v[72:75], off
	global_store_dwordx4 v[54:55], v[50:53], off offset:3072
	v_fma_f32 v54, v20, v102, -v90
	v_fma_f32 v55, v21, v103, -v91
	v_fma_f32 v72, v22, v98, -v88
	v_fma_f32 v73, v23, v99, -v89
	v_fma_f32 v74, v12, v152, -v94
	v_fma_f32 v75, v13, v153, -v95
	v_fma_f32 v98, v14, v118, -v92
	v_fma_f32 v99, v15, v119, -v93
	v_fma_f32 v52, v30, v72, v88
	v_fma_f32 v53, v31, v73, v89
	v_fma_f32 v50, v28, v54, v90
	v_fma_f32 v51, v29, v55, v91
	v_fma_f32 v102, v26, v98, v92
	v_fma_f32 v103, v27, v99, v93
	v_fma_f32 v104, v24, v74, v94
	v_fma_f32 v105, v25, v75, v95
	v_mov_b32_e32 v77, v84
	v_mov_b32_e32 v71, v80
	v_cvt_pk_bf16_f32 v50, v50, v51
	v_cvt_pk_bf16_f32 v51, v52, v53
	v_cvt_pk_bf16_f32 v52, v104, v105
	v_cvt_pk_bf16_f32 v53, v102, v103
	v_mul_f32_e32 v86, v116, v86
	v_mul_f32_e32 v87, v116, v87
	v_mul_f32_e32 v76, v116, v76
	v_mul_f32_e32 v77, v116, v77
	v_mul_f32_e32 v82, v116, v82
	v_mul_f32_e32 v83, v116, v83
	v_mul_f32_e32 v80, v116, v70
	v_mul_f32_e32 v81, v116, v71
	global_store_dwordx4 v[122:123], v[50:53], off offset:1024
	v_mul_f32_e32 v84, v10, v76
	v_mul_f32_e32 v85, v11, v77
	v_mul_f32_e32 v120, v8, v86
	v_mul_f32_e32 v121, v9, v87
	v_fma_f32 v52, v46, v72, v88
	v_fma_f32 v53, v47, v73, v89
	v_fma_f32 v50, v44, v54, v90
	v_fma_f32 v51, v45, v55, v91
	v_fma_f32 v54, v38, v98, v92
	v_fma_f32 v55, v39, v99, v93
	v_fma_f32 v72, v36, v74, v94
	v_fma_f32 v73, v37, v75, v95
	v_mul_f32_e32 v164, v18, v80
	v_mul_f32_e32 v165, v19, v81
	v_mul_f32_e32 v166, v16, v82
	v_mul_f32_e32 v167, v17, v83
	v_cvt_pk_bf16_f32 v50, v50, v51
	v_cvt_pk_bf16_f32 v51, v52, v53
	v_cvt_pk_bf16_f32 v52, v72, v73
	v_cvt_pk_bf16_f32 v53, v54, v55
	global_store_dwordx4 v[100:101], v[50:53], off offset:1024
	v_lshl_add_u64 v[54:55], v[48:49], 0, s[34:35]
	v_fma_f32 v72, v174, v76, v96
	v_fma_f32 v73, v175, v77, v97
	v_cvt_pk_bf16_f32 v50, v120, v121
	v_cvt_pk_bf16_f32 v51, v84, v85
	v_cvt_pk_bf16_f32 v52, v166, v167
	v_cvt_pk_bf16_f32 v53, v164, v165
	global_store_dwordx4 v[54:55], v[50:53], off offset:2048
	v_fma_f32 v74, -v16, v82, v162
	v_fma_f32 v75, -v17, v83, v163
	v_fma_f32 v76, v176, v80, v114
	v_fma_f32 v77, v177, v81, v115
	v_fma_f32 v52, -v8, v86, v112
	v_fma_f32 v53, -v9, v87, v113
	v_fma_f32 v50, v6, v72, v84
	v_fma_f32 v51, v7, v73, v85
	v_fma_f32 v48, v4, v52, v120
	v_fma_f32 v49, v5, v53, v121
	v_fma_f32 v80, v2, v76, v164
	v_fma_f32 v81, v3, v77, v165
	v_fma_f32 v82, v0, v74, v166
	v_fma_f32 v83, v1, v75, v167
	s_add_i32 s45, s45, s14
	v_mov_b32_e32 v65, v68
	v_cvt_pk_bf16_f32 v48, v48, v49
	v_cvt_pk_bf16_f32 v49, v50, v51
	v_cvt_pk_bf16_f32 v50, v82, v83
	v_cvt_pk_bf16_f32 v51, v80, v81
	s_add_u32 s16, s16, s18
	v_mul_f32_e32 v78, v116, v78
	v_mul_f32_e32 v79, v116, v79
	v_mul_f32_e32 v168, v116, v66
	v_mul_f32_e32 v169, v116, v67
	v_mul_f32_e32 v117, v116, v65
	v_mul_f32_e32 v116, v116, v64
	global_store_dwordx4 v[122:123], v[48:51], off offset:2048
	s_addc_u32 s17, s17, s19
	v_mul_f32_e32 v66, v22, v168
	v_mul_f32_e32 v67, v23, v169
	v_fma_f32 v50, v34, v72, v84
	v_fma_f32 v51, v35, v73, v85
; #define GAS __attribute__((address_space(1)))
; __device__ __forceinline__ void rmsnorm_rows_rwkv(const bf16_t* x, const float* gain, const float* mu_r, const float* mu_k, bf16_t* H, bf16_t* XR, bf16_t* XK, int gw, int NGW, int lane) {
;     ...
;     for (int row0 = gw * RB; row0 < T; row0 += NGW * RB) {
;         const bool first = (row0 & 4095) == 0;
;         f32x4 v[RB + 1][2][2]; float s[RB + 1];
; #pragma unroll
;         for (int r = 0; r <= RB; ++r)
; #pragma unroll
;             for (int j = 0; j < 2; ++j) unpack8h(*(const GAS u32x4*)(x + (size_t)(row0 - 1 + r + (first && r == 0 ? 1 : 0)) * D + 512 * j + lane * 8), v[r][j][0], v[r][j][1]);
;     ...
;         for (int r = 1; r <= RB; ++r) {
;             const int row = row0 + r - 1;
;             const size_t hrow = (size_t)row + (row >> 12) + 1;
; #pragma unroll
;             for (int j = 0; j < 2; ++j) {
;                 const size_t co = (size_t)512 * j + lane * 8;
;                 *(GAS u32x4*)(H + hrow * D + co) = pack8(v[r][j][0], v[r][j][1]);
;                 const f32x4 d0 = v[r - 1][j][0] - v[r][j][0], d1 = v[r - 1][j][1] - v[r][j][1];
;                 *(GAS u32x4*)(XR + (size_t)row * D + co) = pack8(v[r][j][0] + d0 * mr[j][0], v[r][j][1] + d1 * mr[j][1]);
;                 *(GAS u32x4*)(XK + (size_t)row * D + co) = pack8(v[r][j][0] + d0 * mk[j][0], v[r][j][1] + d1 * mk[j][1]);
	v_fma_f32 v48, v32, v52, v120
	v_fma_f32 v49, v33, v53, v121
	v_fma_f32 v52, v42, v76, v164
	v_fma_f32 v53, v43, v77, v165
	v_fma_f32 v72, v40, v74, v166
	v_fma_f32 v73, v41, v75, v167
	v_mul_f32_e32 v70, v20, v78
	v_mul_f32_e32 v71, v21, v79
	v_mul_f32_e32 v64, v14, v116
	v_mul_f32_e32 v65, v15, v117
	v_mul_f32_e32 v68, v12, v170
	v_mul_f32_e32 v69, v13, v171
	v_cvt_pk_bf16_f32 v48, v48, v49
	v_cvt_pk_bf16_f32 v49, v50, v51
	v_cvt_pk_bf16_f32 v50, v72, v73
	v_cvt_pk_bf16_f32 v51, v52, v53
	s_add_u32 s20, s20, s18
	global_store_dwordx4 v[100:101], v[48:51], off offset:2048
	s_addc_u32 s21, s21, s19
	v_fma_f32 v52, -v20, v78, v90
	v_fma_f32 v53, -v21, v79, v91
	v_cvt_pk_bf16_f32 v48, v70, v71
	v_cvt_pk_bf16_f32 v49, v66, v67
	v_cvt_pk_bf16_f32 v50, v68, v69
	v_cvt_pk_bf16_f32 v51, v64, v65
	global_store_dwordx4 v[54:55], v[48:51], off offset:3072
	v_fma_f32 v54, v108, v168, v88
	v_fma_f32 v55, v109, v169, v89
	v_fma_f32 v72, -v12, v170, v94
	v_fma_f32 v73, -v13, v171, v95
	v_fma_f32 v74, v128, v116, v92
	v_fma_f32 v75, v129, v117, v93
	s_add_u32 s26, s26, s14
	v_fma_f32 v50, v30, v54, v66
	v_fma_f32 v51, v31, v55, v67
	v_fma_f32 v48, v28, v52, v70
	v_fma_f32 v49, v29, v53, v71
	v_fma_f32 v76, v26, v74, v64
	v_fma_f32 v77, v27, v75, v65
	v_fma_f32 v78, v24, v72, v68
	v_fma_f32 v79, v25, v73, v69
	s_addc_u32 s27, s27, s15
	v_cvt_pk_bf16_f32 v48, v48, v49
	v_cvt_pk_bf16_f32 v49, v50, v51
	v_cvt_pk_bf16_f32 v50, v78, v79
	v_cvt_pk_bf16_f32 v51, v76, v77
	s_add_u32 s24, s24, s18
	global_store_dwordx4 v[122:123], v[48:51], off offset:3072
	s_addc_u32 s25, s25, s19
	s_cmp_lt_i32 s45, 0x8000
	v_fma_f32 v50, v46, v54, v66
	v_fma_f32 v51, v47, v55, v67
	v_fma_f32 v48, v44, v52, v70
	v_fma_f32 v49, v45, v53, v71
	v_fma_f32 v52, v38, v74, v64
	v_fma_f32 v53, v39, v75, v65
	v_fma_f32 v54, v36, v72, v68
	v_fma_f32 v55, v37, v73, v69
	v_cvt_pk_bf16_f32 v48, v48, v49
	v_cvt_pk_bf16_f32 v49, v50, v51
	v_cvt_pk_bf16_f32 v50, v54, v55
	v_cvt_pk_bf16_f32 v51, v52, v53
	global_store_dwordx4 v[100:101], v[48:51], off offset:3072
	s_cbranch_scc0 .LBB0_764
.LBB0_761:
	s_nop 0
	v_lshl_add_u64 v[48:49], s[24:25], 0, v[56:57]
	v_add_co_u32_e32 v80, vcc, s39, v48
	s_and_b32 s2, s45, 0xffc
	s_nop 0
	v_addc_co_u32_e32 v81, vcc, 0, v49, vcc
	s_cmp_eq_u32 s2, 0
	v_add_co_u32_e32 v48, vcc, s38, v48
	s_cselect_b64 s[2:3], -1, 0
	s_add_u32 s6, s29, s26
	v_addc_co_u32_e32 v49, vcc, 0, v49, vcc
	v_mov_b32_e32 v113, s4
	v_cndmask_b32_e64 v112, 0, 1, s[2:3]
	s_addc_u32 s7, s23, s27
	global_load_dwordx4 v[64:67], v[80:81], off offset:-4096
	global_load_dwordx4 v[68:71], v[48:49], off offset:1024
	global_load_dwordx4 v[72:75], v[48:49], off offset:2048
	global_load_dwordx4 v[76:79], v[48:49], off offset:3072
	global_load_dwordx4 v[126:129], v[80:81], off
	v_lshl_add_u64 v[48:49], s[6:7], 0, v[112:113]
	global_load_dwordx4 v[130:133], v[80:81], off offset:1024
	global_load_dwordx4 v[144:147], v[80:81], off offset:2048
	v_lshlrev_b64 v[48:49], 11, v[48:49]
	v_lshl_add_u64 v[82:83], v[58:59], 0, v[48:49]
	global_load_dwordx4 v[52:55], v[82:83], off
	global_load_dwordx4 v[48:51], v[82:83], off offset:1024
	global_load_dwordx4 v[148:151], v[80:81], off offset:3072
	s_and_b64 vcc, exec, s[2:3]
	s_waitcnt vmcnt(0)
	v_cvt_f32_f16_sdwa v99, v69 dst_sel:DWORD dst_unused:UNUSED_PAD src0_sel:WORD_1
	v_cvt_f32_f16_sdwa v108, v73 dst_sel:DWORD dst_unused:UNUSED_PAD src0_sel:WORD_1
	v_cvt_f32_f16_sdwa v109, v65 dst_sel:DWORD dst_unused:UNUSED_PAD src0_sel:WORD_1
	v_cvt_f32_f16_sdwa v115, v64 dst_sel:DWORD dst_unused:UNUSED_PAD src0_sel:WORD_1
	v_cvt_f32_f16_sdwa v114, v72 dst_sel:DWORD dst_unused:UNUSED_PAD src0_sel:WORD_1
	v_cvt_f32_f16_e32 v102, v76
	v_cvt_f32_f16_sdwa v120, v76 dst_sel:DWORD dst_unused:UNUSED_PAD src0_sel:WORD_1
	v_cvt_f32_f16_e32 v76, v145
	v_cvt_f32_f16_sdwa v84, v145 dst_sel:DWORD dst_unused:UNUSED_PAD src0_sel:WORD_1
	v_cvt_f32_f16_sdwa v143, v53 dst_sel:DWORD dst_unused:UNUSED_PAD src0_sel:WORD_1
	v_cvt_f32_f16_sdwa v145, v52 dst_sel:DWORD dst_unused:UNUSED_PAD src0_sel:WORD_1
	v_cvt_f32_f16_e32 v101, v65
	v_cvt_f32_f16_e32 v111, v64
	v_cvt_f32_f16_e32 v100, v73
	v_cvt_f32_f16_e32 v110, v72
	v_cvt_f32_f16_sdwa v105, v67 dst_sel:DWORD dst_unused:UNUSED_PAD src0_sel:WORD_1
	v_cvt_f32_f16_sdwa v117, v66 dst_sel:DWORD dst_unused:UNUSED_PAD src0_sel:WORD_1
	v_cvt_f32_f16_sdwa v104, v75 dst_sel:DWORD dst_unused:UNUSED_PAD src0_sel:WORD_1
	v_cvt_f32_f16_sdwa v116, v74 dst_sel:DWORD dst_unused:UNUSED_PAD src0_sel:WORD_1
	v_cvt_f32_f16_e32 v90, v77
	v_cvt_f32_f16_sdwa v98, v77 dst_sel:DWORD dst_unused:UNUSED_PAD src0_sel:WORD_1
	v_cvt_f32_f16_e32 v77, v127
	v_cvt_f32_f16_e32 v87, v126
	v_cvt_f32_f16_sdwa v85, v127 dst_sel:DWORD dst_unused:UNUSED_PAD src0_sel:WORD_1
	v_cvt_f32_f16_sdwa v127, v126 dst_sel:DWORD dst_unused:UNUSED_PAD src0_sel:WORD_1
	v_cvt_f32_f16_sdwa v139, v55 dst_sel:DWORD dst_unused:UNUSED_PAD src0_sel:WORD_1
	v_cvt_f32_f16_sdwa v141, v54 dst_sel:DWORD dst_unused:UNUSED_PAD src0_sel:WORD_1
	v_cvt_f32_f16_sdwa v126, v144 dst_sel:DWORD dst_unused:UNUSED_PAD src0_sel:WORD_1
	v_cvt_f32_f16_e32 v95, v67
	v_cvt_f32_f16_e32 v107, v66
	v_cvt_f32_f16_e32 v94, v75
	v_cvt_f32_f16_e32 v106, v74
	v_cvt_f32_f16_e32 v86, v144
	v_cvt_f32_f16_sdwa v121, v68 dst_sel:DWORD dst_unused:UNUSED_PAD src0_sel:WORD_1
	v_cvt_f32_f16_e32 v89, v71
	v_cvt_f32_f16_e32 v97, v70
	v_cvt_f32_f16_sdwa v93, v71 dst_sel:DWORD dst_unused:UNUSED_PAD src0_sel:WORD_1
	v_cvt_f32_f16_sdwa v125, v70 dst_sel:DWORD dst_unused:UNUSED_PAD src0_sel:WORD_1
	v_cvt_f32_f16_e32 v88, v79
	v_cvt_f32_f16_e32 v96, v78
	v_cvt_f32_f16_sdwa v92, v79 dst_sel:DWORD dst_unused:UNUSED_PAD src0_sel:WORD_1
; #define GAS __attribute__((address_space(1)))
; __device__ __forceinline__ void rmsnorm_rows_rwkv(const bf16_t* x, const float* gain, const float* mu_r, const float* mu_k, bf16_t* H, bf16_t* XR, bf16_t* XK, int gw, int NGW, int lane) {
;     ...
;             for (int j = 0; j < 2; ++j) unpack8h(*(const GAS u32x4*)(x + (size_t)(row0 - 1 + r + (first && r == 0 ? 1 : 0)) * D + 512 * j + lane * 8), v[r][j][0], v[r][j][1]);
; #pragma unroll
;         for (int r = 0; r <= RB; ++r) { s[r] = 0.f;
; #pragma unroll
;             for (int j = 0; j < 2; ++j)
; #pragma unroll
;                 for (int e = 0; e < 2; ++e) s[r] += (v[r][j][e][0] * v[r][j][e][0] + v[r][j][e][1] * v[r][j][e][1]) + (v[r][j][e][2] * v[r][j][e][2] + v[r][j][e][3] * v[r][j][e][3]); }
; #pragma unroll
;         for (int o = 1; o < 64; o <<= 1)
; #pragma unroll
;             for (int r = 0; r <= RB; ++r) s[r] += __shfl_xor(s[r], o);
	v_cvt_f32_f16_sdwa v124, v78 dst_sel:DWORD dst_unused:UNUSED_PAD src0_sel:WORD_1
	v_cvt_f32_f16_e32 v71, v129
	v_cvt_f32_f16_e32 v83, v128
	v_cvt_f32_f16_sdwa v81, v129 dst_sel:DWORD dst_unused:UNUSED_PAD src0_sel:WORD_1
	v_cvt_f32_f16_sdwa v129, v128 dst_sel:DWORD dst_unused:UNUSED_PAD src0_sel:WORD_1
	v_cvt_f32_f16_e32 v79, v130
	v_cvt_f32_f16_sdwa v119, v130 dst_sel:DWORD dst_unused:UNUSED_PAD src0_sel:WORD_1
	v_cvt_f32_f16_e32 v70, v147
	v_cvt_f32_f16_e32 v82, v146
	v_cvt_f32_f16_sdwa v80, v147 dst_sel:DWORD dst_unused:UNUSED_PAD src0_sel:WORD_1
	v_cvt_f32_f16_sdwa v128, v146 dst_sel:DWORD dst_unused:UNUSED_PAD src0_sel:WORD_1
	v_cvt_f32_f16_e32 v66, v149
	v_cvt_f32_f16_e32 v78, v148
	v_cvt_f32_f16_sdwa v74, v149 dst_sel:DWORD dst_unused:UNUSED_PAD src0_sel:WORD_1
	v_cvt_f32_f16_sdwa v118, v148 dst_sel:DWORD dst_unused:UNUSED_PAD src0_sel:WORD_1
	v_mul_f32_e32 v113, v145, v145
	v_mul_f32_e32 v130, v143, v143
	v_mul_f32_e32 v146, v114, v114
	v_mul_f32_e32 v147, v115, v115
	v_mul_f32_e32 v148, v108, v108
	v_mul_f32_e32 v149, v109, v109
	v_cvt_f32_f16_e32 v91, v69
	v_cvt_f32_f16_e32 v103, v68
	v_cvt_f32_f16_sdwa v135, v49 dst_sel:DWORD dst_unused:UNUSED_PAD src0_sel:WORD_1
	v_cvt_f32_f16_sdwa v137, v48 dst_sel:DWORD dst_unused:UNUSED_PAD src0_sel:WORD_1
	v_fma_mix_f32 v113, v52, v52, v113 op_sel_hi:[1,1,0]
	v_fma_mix_f32 v130, v53, v53, v130 op_sel_hi:[1,1,0]
	v_fma_f32 v146, v110, v110, v146
	v_fma_f32 v147, v111, v111, v147
	v_fma_f32 v148, v100, v100, v148
	v_fma_f32 v149, v101, v101, v149
	v_cvt_f32_f16_sdwa v75, v131 dst_sel:DWORD dst_unused:UNUSED_PAD src0_sel:WORD_1
	v_cvt_f32_f16_e32 v73, v132
	v_cvt_f32_f16_sdwa v123, v132 dst_sel:DWORD dst_unused:UNUSED_PAD src0_sel:WORD_1
	v_cvt_f32_f16_e32 v64, v151
	v_cvt_f32_f16_e32 v72, v150
	v_cvt_f32_f16_sdwa v68, v151 dst_sel:DWORD dst_unused:UNUSED_PAD src0_sel:WORD_1
	v_cvt_f32_f16_sdwa v122, v150 dst_sel:DWORD dst_unused:UNUSED_PAD src0_sel:WORD_1
	v_add_f32_e32 v113, v113, v130
	v_mul_f32_e32 v130, v141, v141
	v_mul_f32_e32 v132, v139, v139
	v_add_f32_e32 v146, v146, v148
	v_add_f32_e32 v147, v147, v149
	v_mul_f32_e32 v148, v116, v116
	v_mul_f32_e32 v149, v117, v117
	v_mul_f32_e32 v150, v104, v104
	v_mul_f32_e32 v151, v105, v105
	v_mul_f32_e32 v164, v126, v126
	v_mul_f32_e32 v165, v127, v127
	v_mul_f32_e32 v166, v84, v84
	v_mul_f32_e32 v167, v85, v85
	v_cvt_f32_f16_e32 v67, v131
	v_fma_mix_f32 v130, v54, v54, v130 op_sel_hi:[1,1,0]
	v_fma_mix_f32 v132, v55, v55, v132 op_sel_hi:[1,1,0]
	v_fma_f32 v148, v106, v106, v148
	v_fma_f32 v149, v107, v107, v149
	v_fma_f32 v150, v94, v94, v150
	v_fma_f32 v151, v95, v95, v151
	v_fma_f32 v164, v86, v86, v164
	v_fma_f32 v165, v87, v87, v165
	v_fma_f32 v166, v76, v76, v166
	v_fma_f32 v167, v77, v77, v167
	v_cvt_f32_f16_e32 v65, v133
	v_cvt_f32_f16_sdwa v69, v133 dst_sel:DWORD dst_unused:UNUSED_PAD src0_sel:WORD_1
	v_cvt_f32_f16_sdwa v131, v51 dst_sel:DWORD dst_unused:UNUSED_PAD src0_sel:WORD_1
	v_cvt_f32_f16_sdwa v133, v50 dst_sel:DWORD dst_unused:UNUSED_PAD src0_sel:WORD_1
	v_add_f32_e32 v130, v130, v132
	v_add_f32_e32 v148, v148, v150
	v_add_f32_e32 v149, v149, v151
	v_mul_f32_e32 v150, v120, v120
	v_mul_f32_e32 v151, v121, v121
	v_mul_f32_e32 v152, v98, v98
	v_mul_f32_e32 v153, v99, v99
	v_add_f32_e32 v164, v164, v166
	v_add_f32_e32 v165, v165, v167
	v_mul_f32_e32 v166, v128, v128
	v_mul_f32_e32 v167, v129, v129
	v_mul_f32_e32 v168, v80, v80
	v_mul_f32_e32 v169, v81, v81
	v_add_f32_e32 v113, v113, v130
	v_mul_f32_e32 v130, v137, v137
	v_mul_f32_e32 v132, v135, v135
	v_fma_f32 v150, v102, v102, v150
	v_fma_f32 v151, v103, v103, v151
	v_fma_f32 v152, v90, v90, v152
	v_fma_f32 v153, v91, v91, v153
	v_fma_f32 v166, v82, v82, v166
	v_fma_f32 v167, v83, v83, v167
	v_fma_f32 v168, v70, v70, v168
	v_fma_f32 v169, v71, v71, v169
	v_fma_mix_f32 v130, v48, v48, v130 op_sel_hi:[1,1,0]
	v_fma_mix_f32 v132, v49, v49, v132 op_sel_hi:[1,1,0]
	v_mul_f32_e32 v154, v124, v124
	v_mul_f32_e32 v155, v125, v125
	v_mul_f32_e32 v162, v92, v92
	v_mul_f32_e32 v163, v93, v93
	v_add_f32_e32 v166, v166, v168
	v_add_f32_e32 v167, v167, v169
	v_mul_f32_e32 v168, v118, v118
	v_mul_f32_e32 v169, v119, v119
	v_mul_f32_e32 v170, v74, v74
	v_mul_f32_e32 v171, v75, v75
	v_add_f32_e32 v146, v146, v148
	v_add_f32_e32 v147, v147, v149
	v_add_f32_e32 v148, v150, v152
	v_add_f32_e32 v149, v151, v153
	v_add_f32_e32 v130, v130, v132
	v_fma_f32 v168, v78, v78, v168
	v_fma_f32 v169, v79, v79, v169
	v_fma_f32 v170, v66, v66, v170
	v_fma_f32 v171, v67, v67, v171
	v_add_f32_e32 v146, v146, v148
	v_add_f32_e32 v147, v147, v149
	v_fma_f32 v148, v96, v96, v154
	v_fma_f32 v149, v97, v97, v155
	v_fma_f32 v150, v88, v88, v162
	v_fma_f32 v151, v89, v89, v163
	v_add_f32_e32 v113, v113, v130
	v_mul_f32_e32 v130, v133, v133
	v_mul_f32_e32 v132, v131, v131
	v_mul_f32_e32 v172, v122, v122
	v_mul_f32_e32 v173, v123, v123
	v_mul_f32_e32 v174, v68, v68
	v_mul_f32_e32 v175, v69, v69
	v_add_f32_e32 v148, v148, v150
	v_add_f32_e32 v149, v149, v151
	v_add_f32_e32 v150, v164, v166
	v_add_f32_e32 v151, v165, v167
	v_add_f32_e32 v152, v168, v170
	v_add_f32_e32 v153, v169, v171
	v_fma_mix_f32 v130, v50, v50, v130 op_sel_hi:[1,1,0]
	v_fma_mix_f32 v132, v51, v51, v132 op_sel_hi:[1,1,0]
	v_add_f32_e32 v150, v150, v152
	v_add_f32_e32 v151, v151, v153
	v_fma_f32 v152, v72, v72, v172
	v_fma_f32 v153, v73, v73, v173
	v_fma_f32 v154, v64, v64, v174
	v_fma_f32 v155, v65, v65, v175
	v_add_f32_e32 v130, v130, v132
	v_add_f32_e32 v152, v152, v154
	v_add_f32_e32 v153, v153, v155
	v_add_f32_e32 v113, v130, v113
	v_add_f32_e32 v146, v148, v146
	v_add_f32_e32 v147, v149, v147
	v_add_f32_e32 v150, v152, v150
	v_add_f32_e32 v151, v153, v151
	ds_bpermute_b32 v130, v156, v113
	ds_bpermute_b32 v149, v156, v147
	ds_bpermute_b32 v148, v156, v146
	ds_bpermute_b32 v153, v156, v151
	ds_bpermute_b32 v152, v156, v150
	s_waitcnt lgkmcnt(4)
; __device__ __forceinline__ void rmsnorm_rows_rwkv(const bf16_t* x, const float* gain, const float* mu_r, const float* mu_k, bf16_t* H, bf16_t* XR, bf16_t* XK, int gw, int NGW, int lane) {
;     ...
; #pragma unroll
;         for (int o = 1; o < 64; o <<= 1)
; #pragma unroll
;             for (int r = 0; r <= RB; ++r) s[r] += __shfl_xor(s[r], o);
; #pragma unroll
;         for (int r = 0; r <= RB; ++r) {
;             const float rstd = (first && r == 0) ? 0.f : rsqrtf(s[r] * (1.f / D) + 1e-6f);
	v_add_f32_e32 v113, v113, v130
	ds_bpermute_b32 v130, v157, v113
	s_waitcnt lgkmcnt(3)
	v_add_f32_e32 v146, v146, v148
	v_add_f32_e32 v147, v147, v149
	ds_bpermute_b32 v149, v157, v147
	s_waitcnt lgkmcnt(2)
	v_add_f32_e32 v150, v150, v152
	v_add_f32_e32 v151, v151, v153
	ds_bpermute_b32 v148, v157, v146
	ds_bpermute_b32 v153, v157, v151
	ds_bpermute_b32 v152, v157, v150
	s_waitcnt lgkmcnt(4)
	v_add_f32_e32 v113, v113, v130
	ds_bpermute_b32 v130, v158, v113
	s_waitcnt lgkmcnt(3)
	v_add_f32_e32 v146, v146, v148
	v_add_f32_e32 v147, v147, v149
	ds_bpermute_b32 v149, v158, v147
	s_waitcnt lgkmcnt(2)
	v_add_f32_e32 v150, v150, v152
	v_add_f32_e32 v151, v151, v153
	ds_bpermute_b32 v148, v158, v146
	ds_bpermute_b32 v153, v158, v151
	ds_bpermute_b32 v152, v158, v150
	s_waitcnt lgkmcnt(4)
	v_add_f32_e32 v113, v113, v130
	ds_bpermute_b32 v130, v159, v113
	s_waitcnt lgkmcnt(3)
	v_add_f32_e32 v146, v146, v148
	v_add_f32_e32 v147, v147, v149
	ds_bpermute_b32 v149, v159, v147
	s_waitcnt lgkmcnt(2)
	v_add_f32_e32 v150, v150, v152
	v_add_f32_e32 v151, v151, v153
	ds_bpermute_b32 v148, v159, v146
	ds_bpermute_b32 v153, v159, v151
	ds_bpermute_b32 v152, v159, v150
	s_waitcnt lgkmcnt(4)
	v_add_f32_e32 v113, v113, v130
	ds_bpermute_b32 v130, v160, v113
	s_waitcnt lgkmcnt(3)
	v_add_f32_e32 v146, v146, v148
	v_add_f32_e32 v147, v147, v149
	ds_bpermute_b32 v149, v160, v147
	s_waitcnt lgkmcnt(2)
	v_add_f32_e32 v150, v150, v152
	v_add_f32_e32 v151, v151, v153
	ds_bpermute_b32 v148, v160, v146
	ds_bpermute_b32 v163, v160, v151
	ds_bpermute_b32 v162, v160, v150
	s_waitcnt lgkmcnt(4)
	v_add_f32_e32 v113, v113, v130
	ds_bpermute_b32 v130, v161, v113
	s_waitcnt lgkmcnt(3)
	v_add_f32_e32 v152, v146, v148
	v_add_f32_e32 v153, v147, v149
	ds_bpermute_b32 v155, v161, v153
	s_waitcnt lgkmcnt(2)
	v_add_f32_e32 v148, v150, v162
	v_add_f32_e32 v149, v151, v163
	ds_bpermute_b32 v154, v161, v152
	ds_bpermute_b32 v151, v161, v149
	ds_bpermute_b32 v150, v161, v148
	v_mov_b32_e32 v146, 0
	s_cbranch_vccnz .LBB0_759
	s_waitcnt lgkmcnt(4)
	v_add_f32_e32 v113, v113, v130
	v_fmamk_f32 v113, v113, 0x3a800000, v62
	v_mul_f32_e32 v130, 0x4b800000, v113
	v_cmp_gt_f32_e32 vcc, s40, v113
	s_nop 1
	v_cndmask_b32_e32 v113, v113, v130, vcc
	v_rsq_f32_e32 v113, v113
	s_nop 0
	v_mul_f32_e32 v130, 0x45800000, v113
	v_cndmask_b32_e32 v146, v113, v130, vcc
	s_branch .LBB0_759

; __device__ __forceinline__ float fsigmoid(float x) { return frcp(1.f + fexp2(-x * LOG2E)); }
;     __device__ __forceinline__ void operator()(const Acc& acc, const Unit& u, int wr, int wc, int fr, int fq) const {
;     ...
;                         const int c = colb + 128 * bj;
;                         f32x4 v0 = acc[ai][bj][m][0], v1 = acc[ai][bj][m][1];
;                         if (c < 64) {
; #pragma unroll
;                             for (int j = 0; j < 4; ++j) { v0[j] = 2.f * fsigmoid(2.f * v0[j]) - 1.f; v1[j] = 2.f * fsigmoid(2.f * v1[j]) - 1.f; }
.LBB0_839:
	s_andn2_saveexec_b64 s[6:7], s[6:7]
	s_cbranch_execz .LBB0_841
	v_add_f32_e32 v141, v124, v124
	v_add_f32_e32 v144, v120, v120
	v_mul_f32_e32 v141, 0xbfb8aa3b, v141
	v_mul_f32_e32 v144, 0xbfb8aa3b, v144
	v_exp_f32_e32 v141, v141
	v_exp_f32_e32 v145, v144
	v_add_f32_e32 v144, v125, v125
	v_mul_f32_e32 v144, 0xbfb8aa3b, v144
	v_exp_f32_e32 v146, v144
	v_add_f32_e32 v141, 1.0, v141
	v_rcp_f32_e32 v144, v141
	v_add_f32_e32 v141, 1.0, v145
	v_rcp_f32_e32 v148, v141
	v_add_f32_e32 v141, 1.0, v146
	v_add_f32_e32 v147, v122, v122
	v_rcp_f32_e32 v145, v141
	v_add_f32_e32 v141, v121, v121
	v_add_f32_e32 v146, v126, v126
	v_mul_f32_e32 v147, 0xbfb8aa3b, v147
	v_add_f32_e32 v149, v127, v127
	v_add_f32_e32 v150, v123, v123
	v_mul_f32_e32 v141, 0xbfb8aa3b, v141
	v_mul_f32_e32 v146, 0xbfb8aa3b, v146
	v_exp_f32_e32 v147, v147
	v_mul_f32_e32 v149, 0xbfb8aa3b, v149
	v_mul_f32_e32 v150, 0xbfb8aa3b, v150
	v_exp_f32_e32 v141, v141
	v_exp_f32_e32 v146, v146
	v_exp_f32_e32 v149, v149
	v_exp_f32_e32 v150, v150
	v_add_f32_e32 v147, 1.0, v147
	v_add_f32_e32 v141, 1.0, v141
	v_add_f32_e32 v146, 1.0, v146
	v_rcp_f32_e32 v152, v147
	v_add_f32_e32 v147, 1.0, v149
	v_add_f32_e32 v149, 1.0, v150
	v_rcp_f32_e32 v146, v146
	v_rcp_f32_e32 v147, v147
	v_rcp_f32_e32 v153, v149
	v_rcp_f32_e32 v149, v141
	v_fma_f32 v150, v146, 2.0, -1.0
	v_fma_f32 v151, v147, 2.0, -1.0
	v_fma_f32 v146, v144, 2.0, -1.0
	v_fma_f32 v147, v145, 2.0, -1.0
	v_fma_f32 v152, v152, 2.0, -1.0
	v_fma_f32 v153, v153, 2.0, -1.0
	v_fma_f32 v148, v148, 2.0, -1.0
	v_fma_f32 v149, v149, 2.0, -1.0

; __device__ __forceinline__ float fsigmoid(float x) { return frcp(1.f + fexp2(-x * LOG2E)); }
;     __device__ __forceinline__ void operator()(const Acc& acc, const Unit& u, int wr, int wc, int fr, int fq) const {
;     ...
;                         const int c = colb + 128 * bj;
;                         f32x4 v0 = acc[ai][bj][m][0], v1 = acc[ai][bj][m][1];
;                         if (c < 64) {
; #pragma unroll
;                             for (int j = 0; j < 4; ++j) { v0[j] = 2.f * fsigmoid(2.f * v0[j]) - 1.f; v1[j] = 2.f * fsigmoid(2.f * v1[j]) - 1.f; }
.LBB0_845:
	s_andn2_saveexec_b64 s[50:51], s[50:51]
	s_cbranch_execz .LBB0_847
	v_add_f32_e32 v147, v104, v104
	v_mul_f32_e32 v147, 0xbfb8aa3b, v147
	v_add_f32_e32 v148, v109, v109
	v_exp_f32_e32 v147, v147
	v_mul_f32_e32 v148, 0xbfb8aa3b, v148
	v_exp_f32_e32 v149, v148
	v_add_f32_e32 v152, v111, v111
	v_add_f32_e32 v147, 1.0, v147
	v_add_f32_e32 v151, v106, v106
	v_mul_f32_e32 v152, 0xbfb8aa3b, v152
	v_add_f32_e32 v146, v108, v108
	v_rcp_f32_e32 v148, v147
	v_add_f32_e32 v147, 1.0, v149
	v_add_f32_e32 v149, v105, v105
	v_add_f32_e32 v150, v110, v110
	v_mul_f32_e32 v151, 0xbfb8aa3b, v151
	v_exp_f32_e32 v153, v152
	v_add_f32_e32 v152, v107, v107
	v_mul_f32_e32 v146, 0xbfb8aa3b, v146
	v_mul_f32_e32 v149, 0xbfb8aa3b, v149
	v_mul_f32_e32 v150, 0xbfb8aa3b, v150
	v_exp_f32_e32 v151, v151
	v_mul_f32_e32 v152, 0xbfb8aa3b, v152
	v_exp_f32_e32 v146, v146
	v_exp_f32_e32 v149, v149
	v_exp_f32_e32 v150, v150
	v_exp_f32_e32 v162, v152
	v_add_f32_e32 v151, 1.0, v151
	v_add_f32_e32 v146, 1.0, v146
	v_add_f32_e32 v149, 1.0, v149
	v_add_f32_e32 v150, 1.0, v150
	v_rcp_f32_e32 v152, v151
	v_add_f32_e32 v151, 1.0, v153
	v_add_f32_e32 v153, 1.0, v162
	v_rcp_f32_e32 v146, v146
	v_rcp_f32_e32 v147, v147
	v_rcp_f32_e32 v150, v150
	v_rcp_f32_e32 v151, v151
	v_rcp_f32_e32 v153, v153
	v_rcp_f32_e32 v149, v149
	v_fma_f32 v146, v146, 2.0, -1.0
	v_fma_f32 v147, v147, 2.0, -1.0
	v_fma_f32 v150, v150, 2.0, -1.0
	v_fma_f32 v151, v151, 2.0, -1.0
	v_fma_f32 v152, v152, 2.0, -1.0
	v_fma_f32 v153, v153, 2.0, -1.0
	v_fma_f32 v148, v148, 2.0, -1.0
	v_fma_f32 v149, v149, 2.0, -1.0

; __device__ __forceinline__ float fsigmoid(float x) { return frcp(1.f + fexp2(-x * LOG2E)); }
;     __device__ __forceinline__ void operator()(const Acc& acc, const Unit& u, int wr, int wc, int fr, int fq) const {
;     ...
;                         const int c = colb + 128 * bj;
;                         f32x4 v0 = acc[ai][bj][m][0], v1 = acc[ai][bj][m][1];
;                         if (c < 64) {
; #pragma unroll
;                             for (int j = 0; j < 4; ++j) { v0[j] = 2.f * fsigmoid(2.f * v0[j]) - 1.f; v1[j] = 2.f * fsigmoid(2.f * v1[j]) - 1.f; }
.LBB0_851:
	s_andn2_saveexec_b64 s[50:51], s[50:51]
	s_cbranch_execz .LBB0_853
	v_add_f32_e32 v145, v112, v112
	v_mul_f32_e32 v145, 0xbfb8aa3b, v145
	v_add_f32_e32 v146, v117, v117
	v_exp_f32_e32 v145, v145
	v_mul_f32_e32 v146, 0xbfb8aa3b, v146
	v_exp_f32_e32 v146, v146
	v_add_f32_e32 v147, v118, v118
	v_add_f32_e32 v145, 1.0, v145
	v_rcp_f32_e32 v148, v145
	v_add_f32_e32 v145, 1.0, v146
	v_add_f32_e32 v146, v113, v113
	v_add_f32_e32 v149, v114, v114
	v_mul_f32_e32 v146, 0xbfb8aa3b, v146
	v_mul_f32_e32 v147, 0xbfb8aa3b, v147
	v_mul_f32_e32 v149, 0xbfb8aa3b, v149
	v_exp_f32_e32 v146, v146
	v_exp_f32_e32 v147, v147
	v_exp_f32_e32 v149, v149
	v_add_f32_e32 v144, v116, v116
	v_add_f32_e32 v150, 1.0, v146
	v_add_f32_e32 v146, 1.0, v147
	v_add_f32_e32 v147, 1.0, v149
	v_add_f32_e32 v149, v119, v119
	v_add_f32_e32 v151, v115, v115
	v_mul_f32_e32 v144, 0xbfb8aa3b, v144
	v_mul_f32_e32 v149, 0xbfb8aa3b, v149
	v_mul_f32_e32 v151, 0xbfb8aa3b, v151
	v_exp_f32_e32 v144, v144
	v_exp_f32_e32 v149, v149
	v_exp_f32_e32 v151, v151
	v_rcp_f32_e32 v152, v147
	v_add_f32_e32 v144, 1.0, v144
	v_add_f32_e32 v147, 1.0, v149
	v_add_f32_e32 v149, 1.0, v151
	v_rcp_f32_e32 v144, v144
	v_rcp_f32_e32 v145, v145
	v_rcp_f32_e32 v146, v146
	v_rcp_f32_e32 v147, v147
	v_rcp_f32_e32 v153, v149
	v_rcp_f32_e32 v149, v150
	v_fma_f32 v150, v146, 2.0, -1.0
	v_fma_f32 v151, v147, 2.0, -1.0
	v_fma_f32 v146, v144, 2.0, -1.0
	v_fma_f32 v147, v145, 2.0, -1.0
	v_fma_f32 v152, v152, 2.0, -1.0
	v_fma_f32 v153, v153, 2.0, -1.0
	v_fma_f32 v148, v148, 2.0, -1.0
	v_fma_f32 v149, v149, 2.0, -1.0

; __device__ __forceinline__ float fsigmoid(float x) { return frcp(1.f + fexp2(-x * LOG2E)); }
;     __device__ __forceinline__ void operator()(const Acc& acc, const Unit& u, int wr, int wc, int fr, int fq) const {
;     ...
;                         const int c = colb + 128 * bj;
;                         f32x4 v0 = acc[ai][bj][m][0], v1 = acc[ai][bj][m][1];
;                         if (c < 64) {
; #pragma unroll
;                             for (int j = 0; j < 4; ++j) { v0[j] = 2.f * fsigmoid(2.f * v0[j]) - 1.f; v1[j] = 2.f * fsigmoid(2.f * v1[j]) - 1.f; }
.LBB0_857:
	s_andn2_saveexec_b64 s[50:51], s[50:51]
	s_cbranch_execz .LBB0_859
	v_add_f32_e32 v147, v88, v88
	v_mul_f32_e32 v147, 0xbfb8aa3b, v147
	v_add_f32_e32 v148, v93, v93
	v_exp_f32_e32 v147, v147
	v_mul_f32_e32 v148, 0xbfb8aa3b, v148
	v_exp_f32_e32 v149, v148
	v_add_f32_e32 v152, v95, v95
	v_add_f32_e32 v147, 1.0, v147
	v_add_f32_e32 v151, v90, v90
	v_mul_f32_e32 v152, 0xbfb8aa3b, v152
	v_add_f32_e32 v146, v92, v92
	v_rcp_f32_e32 v148, v147
	v_add_f32_e32 v147, 1.0, v149
	v_add_f32_e32 v149, v89, v89
	v_add_f32_e32 v150, v94, v94
	v_mul_f32_e32 v151, 0xbfb8aa3b, v151
	v_exp_f32_e32 v153, v152
	v_add_f32_e32 v152, v91, v91
	v_mul_f32_e32 v146, 0xbfb8aa3b, v146
	v_mul_f32_e32 v149, 0xbfb8aa3b, v149
	v_mul_f32_e32 v150, 0xbfb8aa3b, v150
	v_exp_f32_e32 v151, v151
	v_mul_f32_e32 v152, 0xbfb8aa3b, v152
	v_exp_f32_e32 v146, v146
	v_exp_f32_e32 v149, v149
	v_exp_f32_e32 v150, v150
	v_exp_f32_e32 v162, v152
	v_add_f32_e32 v151, 1.0, v151
	v_add_f32_e32 v146, 1.0, v146
	v_add_f32_e32 v149, 1.0, v149
	v_add_f32_e32 v150, 1.0, v150
	v_rcp_f32_e32 v152, v151
	v_add_f32_e32 v151, 1.0, v153
	v_add_f32_e32 v153, 1.0, v162
	v_rcp_f32_e32 v146, v146
	v_rcp_f32_e32 v147, v147
	v_rcp_f32_e32 v150, v150
	v_rcp_f32_e32 v151, v151
	v_rcp_f32_e32 v153, v153
	v_rcp_f32_e32 v149, v149
	v_fma_f32 v146, v146, 2.0, -1.0
	v_fma_f32 v147, v147, 2.0, -1.0
	v_fma_f32 v150, v150, 2.0, -1.0
	v_fma_f32 v151, v151, 2.0, -1.0
	v_fma_f32 v152, v152, 2.0, -1.0
	v_fma_f32 v153, v153, 2.0, -1.0
	v_fma_f32 v148, v148, 2.0, -1.0
	v_fma_f32 v149, v149, 2.0, -1.0

; __device__ __forceinline__ float fsigmoid(float x) { return frcp(1.f + fexp2(-x * LOG2E)); }
;     __device__ __forceinline__ void operator()(const Acc& acc, const Unit& u, int wr, int wc, int fr, int fq) const {
;     ...
;                         const int c = colb + 128 * bj;
;                         f32x4 v0 = acc[ai][bj][m][0], v1 = acc[ai][bj][m][1];
;                         if (c < 64) {
; #pragma unroll
;                             for (int j = 0; j < 4; ++j) { v0[j] = 2.f * fsigmoid(2.f * v0[j]) - 1.f; v1[j] = 2.f * fsigmoid(2.f * v1[j]) - 1.f; }
.LBB0_863:
	s_andn2_saveexec_b64 s[50:51], s[50:51]
	s_cbranch_execz .LBB0_865
	v_add_f32_e32 v145, v96, v96
	v_mul_f32_e32 v145, 0xbfb8aa3b, v145
	v_add_f32_e32 v146, v101, v101
	v_exp_f32_e32 v145, v145
	v_mul_f32_e32 v146, 0xbfb8aa3b, v146
	v_exp_f32_e32 v146, v146
	v_add_f32_e32 v147, v102, v102
	v_add_f32_e32 v145, 1.0, v145
	v_rcp_f32_e32 v148, v145
	v_add_f32_e32 v145, 1.0, v146
	v_add_f32_e32 v146, v97, v97
	v_add_f32_e32 v149, v98, v98
	v_mul_f32_e32 v146, 0xbfb8aa3b, v146
	v_mul_f32_e32 v147, 0xbfb8aa3b, v147
	v_mul_f32_e32 v149, 0xbfb8aa3b, v149
	v_exp_f32_e32 v146, v146
	v_exp_f32_e32 v147, v147
	v_exp_f32_e32 v149, v149
	v_add_f32_e32 v144, v100, v100
	v_add_f32_e32 v150, 1.0, v146
	v_add_f32_e32 v146, 1.0, v147
	v_add_f32_e32 v147, 1.0, v149
	v_add_f32_e32 v149, v103, v103
	v_add_f32_e32 v151, v99, v99
	v_mul_f32_e32 v144, 0xbfb8aa3b, v144
	v_mul_f32_e32 v149, 0xbfb8aa3b, v149
	v_mul_f32_e32 v151, 0xbfb8aa3b, v151
	v_exp_f32_e32 v144, v144
	v_exp_f32_e32 v149, v149
	v_exp_f32_e32 v151, v151
	v_rcp_f32_e32 v152, v147
	v_add_f32_e32 v144, 1.0, v144
	v_add_f32_e32 v147, 1.0, v149
	v_add_f32_e32 v149, 1.0, v151
	v_rcp_f32_e32 v144, v144
	v_rcp_f32_e32 v145, v145
	v_rcp_f32_e32 v146, v146
	v_rcp_f32_e32 v147, v147
	v_rcp_f32_e32 v153, v149
	v_rcp_f32_e32 v149, v150
	v_fma_f32 v150, v146, 2.0, -1.0
	v_fma_f32 v151, v147, 2.0, -1.0
	v_fma_f32 v146, v144, 2.0, -1.0
	v_fma_f32 v147, v145, 2.0, -1.0
	v_fma_f32 v152, v152, 2.0, -1.0
	v_fma_f32 v153, v153, 2.0, -1.0
	v_fma_f32 v148, v148, 2.0, -1.0
	v_fma_f32 v149, v149, 2.0, -1.0

; __device__ __forceinline__ float fsigmoid(float x) { return frcp(1.f + fexp2(-x * LOG2E)); }
;     __device__ __forceinline__ void operator()(const Acc& acc, const Unit& u, int wr, int wc, int fr, int fq) const {
;     ...
;                         const int c = colb + 128 * bj;
;                         f32x4 v0 = acc[ai][bj][m][0], v1 = acc[ai][bj][m][1];
;                         if (c < 64) {
; #pragma unroll
;                             for (int j = 0; j < 4; ++j) { v0[j] = 2.f * fsigmoid(2.f * v0[j]) - 1.f; v1[j] = 2.f * fsigmoid(2.f * v1[j]) - 1.f; }
.LBB0_869:
	s_andn2_saveexec_b64 s[50:51], s[50:51]
	s_cbranch_execz .LBB0_871
	v_add_f32_e32 v147, v72, v72
	v_mul_f32_e32 v147, 0xbfb8aa3b, v147
	v_add_f32_e32 v148, v77, v77
	v_exp_f32_e32 v147, v147
	v_mul_f32_e32 v148, 0xbfb8aa3b, v148
	v_exp_f32_e32 v149, v148
	v_add_f32_e32 v152, v79, v79
	v_add_f32_e32 v147, 1.0, v147
	v_add_f32_e32 v151, v74, v74
	v_mul_f32_e32 v152, 0xbfb8aa3b, v152
	v_add_f32_e32 v146, v76, v76
	v_rcp_f32_e32 v148, v147
	v_add_f32_e32 v147, 1.0, v149
	v_add_f32_e32 v149, v73, v73
	v_add_f32_e32 v150, v78, v78
	v_mul_f32_e32 v151, 0xbfb8aa3b, v151
	v_exp_f32_e32 v153, v152
	v_add_f32_e32 v152, v75, v75
	v_mul_f32_e32 v146, 0xbfb8aa3b, v146
	v_mul_f32_e32 v149, 0xbfb8aa3b, v149
	v_mul_f32_e32 v150, 0xbfb8aa3b, v150
	v_exp_f32_e32 v151, v151
	v_mul_f32_e32 v152, 0xbfb8aa3b, v152
	v_exp_f32_e32 v146, v146
	v_exp_f32_e32 v149, v149
	v_exp_f32_e32 v150, v150
	v_exp_f32_e32 v162, v152
	v_add_f32_e32 v151, 1.0, v151
	v_add_f32_e32 v146, 1.0, v146
	v_add_f32_e32 v149, 1.0, v149
	v_add_f32_e32 v150, 1.0, v150
	v_rcp_f32_e32 v152, v151
	v_add_f32_e32 v151, 1.0, v153
	v_add_f32_e32 v153, 1.0, v162
	v_rcp_f32_e32 v146, v146
	v_rcp_f32_e32 v147, v147
	v_rcp_f32_e32 v150, v150
	v_rcp_f32_e32 v151, v151
	v_rcp_f32_e32 v153, v153
	v_rcp_f32_e32 v149, v149
	v_fma_f32 v146, v146, 2.0, -1.0
	v_fma_f32 v147, v147, 2.0, -1.0
	v_fma_f32 v150, v150, 2.0, -1.0
	v_fma_f32 v151, v151, 2.0, -1.0
	v_fma_f32 v152, v152, 2.0, -1.0
	v_fma_f32 v153, v153, 2.0, -1.0
	v_fma_f32 v148, v148, 2.0, -1.0
	v_fma_f32 v149, v149, 2.0, -1.0

; __device__ __forceinline__ float fsigmoid(float x) { return frcp(1.f + fexp2(-x * LOG2E)); }
;     __device__ __forceinline__ void operator()(const Acc& acc, const Unit& u, int wr, int wc, int fr, int fq) const {
;     ...
;                         const int c = colb + 128 * bj;
;                         f32x4 v0 = acc[ai][bj][m][0], v1 = acc[ai][bj][m][1];
;                         if (c < 64) {
; #pragma unroll
;                             for (int j = 0; j < 4; ++j) { v0[j] = 2.f * fsigmoid(2.f * v0[j]) - 1.f; v1[j] = 2.f * fsigmoid(2.f * v1[j]) - 1.f; }
.LBB0_875:
	s_andn2_saveexec_b64 s[50:51], s[50:51]
	s_cbranch_execz .LBB0_877
	v_add_f32_e32 v145, v80, v80
	v_mul_f32_e32 v145, 0xbfb8aa3b, v145
	v_add_f32_e32 v146, v85, v85
	v_exp_f32_e32 v145, v145
	v_mul_f32_e32 v146, 0xbfb8aa3b, v146
	v_exp_f32_e32 v146, v146
	v_add_f32_e32 v147, v86, v86
	v_add_f32_e32 v145, 1.0, v145
	v_rcp_f32_e32 v148, v145
	v_add_f32_e32 v145, 1.0, v146
	v_add_f32_e32 v146, v81, v81
	v_add_f32_e32 v149, v82, v82
	v_mul_f32_e32 v146, 0xbfb8aa3b, v146
	v_mul_f32_e32 v147, 0xbfb8aa3b, v147
	v_mul_f32_e32 v149, 0xbfb8aa3b, v149
	v_exp_f32_e32 v146, v146
	v_exp_f32_e32 v147, v147
	v_exp_f32_e32 v149, v149
	v_add_f32_e32 v144, v84, v84
	v_add_f32_e32 v150, 1.0, v146
	v_add_f32_e32 v146, 1.0, v147
	v_add_f32_e32 v147, 1.0, v149
	v_add_f32_e32 v149, v87, v87
	v_add_f32_e32 v151, v83, v83
	v_mul_f32_e32 v144, 0xbfb8aa3b, v144
	v_mul_f32_e32 v149, 0xbfb8aa3b, v149
	v_mul_f32_e32 v151, 0xbfb8aa3b, v151
	v_exp_f32_e32 v144, v144
	v_exp_f32_e32 v149, v149
	v_exp_f32_e32 v151, v151
	v_rcp_f32_e32 v152, v147
	v_add_f32_e32 v144, 1.0, v144
	v_add_f32_e32 v147, 1.0, v149
	v_add_f32_e32 v149, 1.0, v151
	v_rcp_f32_e32 v144, v144
	v_rcp_f32_e32 v145, v145
	v_rcp_f32_e32 v146, v146
	v_rcp_f32_e32 v147, v147
	v_rcp_f32_e32 v153, v149
	v_rcp_f32_e32 v149, v150
	v_fma_f32 v150, v146, 2.0, -1.0
	v_fma_f32 v151, v147, 2.0, -1.0
	v_fma_f32 v146, v144, 2.0, -1.0
	v_fma_f32 v147, v145, 2.0, -1.0
	v_fma_f32 v152, v152, 2.0, -1.0
	v_fma_f32 v153, v153, 2.0, -1.0
	v_fma_f32 v148, v148, 2.0, -1.0
	v_fma_f32 v149, v149, 2.0, -1.0

; __device__ __forceinline__ float fsigmoid(float x) { return frcp(1.f + fexp2(-x * LOG2E)); }
;     __device__ __forceinline__ void operator()(const Acc& acc, const Unit& u, int wr, int wc, int fr, int fq) const {
;     ...
;                         const int c = colb + 128 * bj;
;                         f32x4 v0 = acc[ai][bj][m][0], v1 = acc[ai][bj][m][1];
;                         if (c < 64) {
; #pragma unroll
;                             for (int j = 0; j < 4; ++j) { v0[j] = 2.f * fsigmoid(2.f * v0[j]) - 1.f; v1[j] = 2.f * fsigmoid(2.f * v1[j]) - 1.f; }
.LBB0_881:
	s_andn2_saveexec_b64 s[50:51], s[50:51]
	s_cbranch_execz .LBB0_883
	v_add_f32_e32 v147, v64, v64
	v_mul_f32_e32 v147, 0xbfb8aa3b, v147
	v_add_f32_e32 v148, v69, v69
	v_exp_f32_e32 v147, v147
	v_mul_f32_e32 v148, 0xbfb8aa3b, v148
	v_exp_f32_e32 v149, v148
	v_add_f32_e32 v152, v71, v71
	v_add_f32_e32 v147, 1.0, v147
	v_add_f32_e32 v151, v66, v66
	v_mul_f32_e32 v152, 0xbfb8aa3b, v152
	v_add_f32_e32 v146, v68, v68
	v_rcp_f32_e32 v148, v147
	v_add_f32_e32 v147, 1.0, v149
	v_add_f32_e32 v149, v65, v65
	v_add_f32_e32 v150, v70, v70
	v_mul_f32_e32 v151, 0xbfb8aa3b, v151
	v_exp_f32_e32 v153, v152
	v_add_f32_e32 v152, v67, v67
	v_mul_f32_e32 v146, 0xbfb8aa3b, v146
	v_mul_f32_e32 v149, 0xbfb8aa3b, v149
	v_mul_f32_e32 v150, 0xbfb8aa3b, v150
	v_exp_f32_e32 v151, v151
	v_mul_f32_e32 v152, 0xbfb8aa3b, v152
	v_exp_f32_e32 v146, v146
	v_exp_f32_e32 v149, v149
	v_exp_f32_e32 v150, v150
	v_exp_f32_e32 v162, v152
	v_add_f32_e32 v151, 1.0, v151
	v_add_f32_e32 v146, 1.0, v146
	v_add_f32_e32 v149, 1.0, v149
	v_add_f32_e32 v150, 1.0, v150
	v_rcp_f32_e32 v152, v151
	v_add_f32_e32 v151, 1.0, v153
	v_add_f32_e32 v153, 1.0, v162
	v_rcp_f32_e32 v146, v146
	v_rcp_f32_e32 v147, v147
	v_rcp_f32_e32 v150, v150
	v_rcp_f32_e32 v151, v151
	v_rcp_f32_e32 v153, v153
	v_rcp_f32_e32 v149, v149
	v_fma_f32 v146, v146, 2.0, -1.0
	v_fma_f32 v147, v147, 2.0, -1.0
	v_fma_f32 v150, v150, 2.0, -1.0
	v_fma_f32 v151, v151, 2.0, -1.0
	v_fma_f32 v152, v152, 2.0, -1.0
	v_fma_f32 v153, v153, 2.0, -1.0
	v_fma_f32 v148, v148, 2.0, -1.0
	v_fma_f32 v149, v149, 2.0, -1.0

; __device__ __forceinline__ float fsigmoid(float x) { return frcp(1.f + fexp2(-x * LOG2E)); }
;     __device__ __forceinline__ void operator()(const Acc& acc, const Unit& u, int wr, int wc, int fr, int fq) const {
;     ...
;                         const int c = colb + 128 * bj;
;                         f32x4 v0 = acc[ai][bj][m][0], v1 = acc[ai][bj][m][1];
;                         if (c < 64) {
; #pragma unroll
;                             for (int j = 0; j < 4; ++j) { v0[j] = 2.f * fsigmoid(2.f * v0[j]) - 1.f; v1[j] = 2.f * fsigmoid(2.f * v1[j]) - 1.f; }
.LBB0_887:
	s_andn2_saveexec_b64 s[50:51], s[50:51]
	s_cbranch_execz .LBB0_889
	v_add_f32_e32 v145, v56, v56
	v_mul_f32_e32 v145, 0xbfb8aa3b, v145
	v_add_f32_e32 v146, v61, v61
	v_exp_f32_e32 v145, v145
	v_mul_f32_e32 v146, 0xbfb8aa3b, v146
	v_exp_f32_e32 v146, v146
	v_add_f32_e32 v147, v62, v62
	v_add_f32_e32 v145, 1.0, v145
	v_rcp_f32_e32 v148, v145
	v_add_f32_e32 v145, 1.0, v146
	v_add_f32_e32 v146, v57, v57
	v_add_f32_e32 v149, v58, v58
	v_mul_f32_e32 v146, 0xbfb8aa3b, v146
	v_mul_f32_e32 v147, 0xbfb8aa3b, v147
	v_mul_f32_e32 v149, 0xbfb8aa3b, v149
	v_exp_f32_e32 v146, v146
	v_exp_f32_e32 v147, v147
	v_exp_f32_e32 v149, v149
	v_add_f32_e32 v144, v60, v60
	v_add_f32_e32 v150, 1.0, v146
	v_add_f32_e32 v146, 1.0, v147
	v_add_f32_e32 v147, 1.0, v149
	v_add_f32_e32 v149, v63, v63
	v_add_f32_e32 v151, v59, v59
	v_mul_f32_e32 v144, 0xbfb8aa3b, v144
	v_mul_f32_e32 v149, 0xbfb8aa3b, v149
	v_mul_f32_e32 v151, 0xbfb8aa3b, v151
	v_exp_f32_e32 v144, v144
	v_exp_f32_e32 v149, v149
	v_exp_f32_e32 v151, v151
	v_rcp_f32_e32 v152, v147
	v_add_f32_e32 v144, 1.0, v144
	v_add_f32_e32 v147, 1.0, v149
	v_add_f32_e32 v149, 1.0, v151
	v_rcp_f32_e32 v144, v144
	v_rcp_f32_e32 v145, v145
	v_rcp_f32_e32 v146, v146
	v_rcp_f32_e32 v147, v147
	v_rcp_f32_e32 v153, v149
	v_rcp_f32_e32 v149, v150
	v_fma_f32 v150, v146, 2.0, -1.0
	v_fma_f32 v151, v147, 2.0, -1.0
	v_fma_f32 v146, v144, 2.0, -1.0
	v_fma_f32 v147, v145, 2.0, -1.0
	v_fma_f32 v152, v152, 2.0, -1.0
	v_fma_f32 v153, v153, 2.0, -1.0
	v_fma_f32 v148, v148, 2.0, -1.0
	v_fma_f32 v149, v149, 2.0, -1.0

; __device__ __forceinline__ float fsigmoid(float x) { return frcp(1.f + fexp2(-x * LOG2E)); }
;     __device__ __forceinline__ void operator()(const Acc& acc, const Unit& u, int wr, int wc, int fr, int fq) const {
;     ...
;                         const int c = colb + 128 * bj;
;                         f32x4 v0 = acc[ai][bj][m][0], v1 = acc[ai][bj][m][1];
;                         if (c < 64) {
; #pragma unroll
;                             for (int j = 0; j < 4; ++j) { v0[j] = 2.f * fsigmoid(2.f * v0[j]) - 1.f; v1[j] = 2.f * fsigmoid(2.f * v1[j]) - 1.f; }
.LBB0_893:
	s_andn2_saveexec_b64 s[50:51], s[50:51]
	s_cbranch_execz .LBB0_895
	v_add_f32_e32 v147, v40, v40
	v_mul_f32_e32 v147, 0xbfb8aa3b, v147
	v_add_f32_e32 v148, v45, v45
	v_exp_f32_e32 v147, v147
	v_mul_f32_e32 v148, 0xbfb8aa3b, v148
	v_exp_f32_e32 v149, v148
	v_add_f32_e32 v152, v47, v47
	v_add_f32_e32 v147, 1.0, v147
	v_add_f32_e32 v151, v42, v42
	v_mul_f32_e32 v152, 0xbfb8aa3b, v152
	v_add_f32_e32 v146, v44, v44
	v_rcp_f32_e32 v148, v147
	v_add_f32_e32 v147, 1.0, v149
	v_add_f32_e32 v149, v41, v41
	v_add_f32_e32 v150, v46, v46
	v_mul_f32_e32 v151, 0xbfb8aa3b, v151
	v_exp_f32_e32 v153, v152
	v_add_f32_e32 v152, v43, v43
	v_mul_f32_e32 v146, 0xbfb8aa3b, v146
	v_mul_f32_e32 v149, 0xbfb8aa3b, v149
	v_mul_f32_e32 v150, 0xbfb8aa3b, v150
	v_exp_f32_e32 v151, v151
	v_mul_f32_e32 v152, 0xbfb8aa3b, v152
	v_exp_f32_e32 v146, v146
	v_exp_f32_e32 v149, v149
	v_exp_f32_e32 v150, v150
	v_exp_f32_e32 v162, v152
	v_add_f32_e32 v151, 1.0, v151
	v_add_f32_e32 v146, 1.0, v146
	v_add_f32_e32 v149, 1.0, v149
	v_add_f32_e32 v150, 1.0, v150
	v_rcp_f32_e32 v152, v151
	v_add_f32_e32 v151, 1.0, v153
	v_add_f32_e32 v153, 1.0, v162
	v_rcp_f32_e32 v146, v146
	v_rcp_f32_e32 v147, v147
	v_rcp_f32_e32 v150, v150
	v_rcp_f32_e32 v151, v151
	v_rcp_f32_e32 v153, v153
	v_rcp_f32_e32 v149, v149
	v_fma_f32 v146, v146, 2.0, -1.0
	v_fma_f32 v147, v147, 2.0, -1.0
	v_fma_f32 v150, v150, 2.0, -1.0
	v_fma_f32 v151, v151, 2.0, -1.0
	v_fma_f32 v152, v152, 2.0, -1.0
	v_fma_f32 v153, v153, 2.0, -1.0
	v_fma_f32 v148, v148, 2.0, -1.0
	v_fma_f32 v149, v149, 2.0, -1.0

; __device__ __forceinline__ float fsigmoid(float x) { return frcp(1.f + fexp2(-x * LOG2E)); }
;     __device__ __forceinline__ void operator()(const Acc& acc, const Unit& u, int wr, int wc, int fr, int fq) const {
;     ...
;                         const int c = colb + 128 * bj;
;                         f32x4 v0 = acc[ai][bj][m][0], v1 = acc[ai][bj][m][1];
;                         if (c < 64) {
; #pragma unroll
;                             for (int j = 0; j < 4; ++j) { v0[j] = 2.f * fsigmoid(2.f * v0[j]) - 1.f; v1[j] = 2.f * fsigmoid(2.f * v1[j]) - 1.f; }
.LBB0_899:
	s_andn2_saveexec_b64 s[50:51], s[50:51]
	s_cbranch_execz .LBB0_901
	v_add_f32_e32 v145, v48, v48
	v_mul_f32_e32 v145, 0xbfb8aa3b, v145
	v_add_f32_e32 v146, v53, v53
	v_exp_f32_e32 v145, v145
	v_mul_f32_e32 v146, 0xbfb8aa3b, v146
	v_exp_f32_e32 v146, v146
	v_add_f32_e32 v147, v54, v54
	v_add_f32_e32 v145, 1.0, v145
	v_rcp_f32_e32 v148, v145
	v_add_f32_e32 v145, 1.0, v146
	v_add_f32_e32 v146, v49, v49
	v_add_f32_e32 v149, v50, v50
	v_mul_f32_e32 v146, 0xbfb8aa3b, v146
	v_mul_f32_e32 v147, 0xbfb8aa3b, v147
	v_mul_f32_e32 v149, 0xbfb8aa3b, v149
	v_exp_f32_e32 v146, v146
	v_exp_f32_e32 v147, v147
	v_exp_f32_e32 v149, v149
	v_add_f32_e32 v144, v52, v52
	v_add_f32_e32 v150, 1.0, v146
	v_add_f32_e32 v146, 1.0, v147
	v_add_f32_e32 v147, 1.0, v149
	v_add_f32_e32 v149, v55, v55
	v_add_f32_e32 v151, v51, v51
	v_mul_f32_e32 v144, 0xbfb8aa3b, v144
	v_mul_f32_e32 v149, 0xbfb8aa3b, v149
	v_mul_f32_e32 v151, 0xbfb8aa3b, v151
	v_exp_f32_e32 v144, v144
	v_exp_f32_e32 v149, v149
	v_exp_f32_e32 v151, v151
	v_rcp_f32_e32 v152, v147
	v_add_f32_e32 v144, 1.0, v144
	v_add_f32_e32 v147, 1.0, v149
	v_add_f32_e32 v149, 1.0, v151
	v_rcp_f32_e32 v144, v144
	v_rcp_f32_e32 v145, v145
	v_rcp_f32_e32 v146, v146
	v_rcp_f32_e32 v147, v147
	v_rcp_f32_e32 v153, v149
	v_rcp_f32_e32 v149, v150
	v_fma_f32 v150, v146, 2.0, -1.0
	v_fma_f32 v151, v147, 2.0, -1.0
	v_fma_f32 v146, v144, 2.0, -1.0
	v_fma_f32 v147, v145, 2.0, -1.0
	v_fma_f32 v152, v152, 2.0, -1.0
	v_fma_f32 v153, v153, 2.0, -1.0
	v_fma_f32 v148, v148, 2.0, -1.0
	v_fma_f32 v149, v149, 2.0, -1.0

; __device__ __forceinline__ float fsigmoid(float x) { return frcp(1.f + fexp2(-x * LOG2E)); }
;     __device__ __forceinline__ void operator()(const Acc& acc, const Unit& u, int wr, int wc, int fr, int fq) const {
;     ...
;                         const int c = colb + 128 * bj;
;                         f32x4 v0 = acc[ai][bj][m][0], v1 = acc[ai][bj][m][1];
;                         if (c < 64) {
; #pragma unroll
;                             for (int j = 0; j < 4; ++j) { v0[j] = 2.f * fsigmoid(2.f * v0[j]) - 1.f; v1[j] = 2.f * fsigmoid(2.f * v1[j]) - 1.f; }
.LBB0_905:
	s_andn2_saveexec_b64 s[50:51], s[50:51]
	s_cbranch_execz .LBB0_907
	v_add_f32_e32 v147, v24, v24
	v_mul_f32_e32 v147, 0xbfb8aa3b, v147
	v_add_f32_e32 v148, v29, v29
	v_exp_f32_e32 v147, v147
	v_mul_f32_e32 v148, 0xbfb8aa3b, v148
	v_exp_f32_e32 v149, v148
	v_add_f32_e32 v152, v31, v31
	v_add_f32_e32 v147, 1.0, v147
	v_add_f32_e32 v151, v26, v26
	v_mul_f32_e32 v152, 0xbfb8aa3b, v152
	v_add_f32_e32 v146, v28, v28
	v_rcp_f32_e32 v148, v147
	v_add_f32_e32 v147, 1.0, v149
	v_add_f32_e32 v149, v25, v25
	v_add_f32_e32 v150, v30, v30
	v_mul_f32_e32 v151, 0xbfb8aa3b, v151
	v_exp_f32_e32 v153, v152
	v_add_f32_e32 v152, v27, v27
	v_mul_f32_e32 v146, 0xbfb8aa3b, v146
	v_mul_f32_e32 v149, 0xbfb8aa3b, v149
	v_mul_f32_e32 v150, 0xbfb8aa3b, v150
	v_exp_f32_e32 v151, v151
	v_mul_f32_e32 v152, 0xbfb8aa3b, v152
	v_exp_f32_e32 v146, v146
	v_exp_f32_e32 v149, v149
	v_exp_f32_e32 v150, v150
	v_exp_f32_e32 v162, v152
	v_add_f32_e32 v151, 1.0, v151
	v_add_f32_e32 v146, 1.0, v146
	v_add_f32_e32 v149, 1.0, v149
	v_add_f32_e32 v150, 1.0, v150
	v_rcp_f32_e32 v152, v151
	v_add_f32_e32 v151, 1.0, v153
	v_add_f32_e32 v153, 1.0, v162
	v_rcp_f32_e32 v146, v146
	v_rcp_f32_e32 v147, v147
	v_rcp_f32_e32 v150, v150
	v_rcp_f32_e32 v151, v151
	v_rcp_f32_e32 v153, v153
	v_rcp_f32_e32 v149, v149
	v_fma_f32 v146, v146, 2.0, -1.0
	v_fma_f32 v147, v147, 2.0, -1.0
	v_fma_f32 v150, v150, 2.0, -1.0
	v_fma_f32 v151, v151, 2.0, -1.0
	v_fma_f32 v152, v152, 2.0, -1.0
	v_fma_f32 v153, v153, 2.0, -1.0
	v_fma_f32 v148, v148, 2.0, -1.0
	v_fma_f32 v149, v149, 2.0, -1.0

; __device__ __forceinline__ float fsigmoid(float x) { return frcp(1.f + fexp2(-x * LOG2E)); }
;     __device__ __forceinline__ void operator()(const Acc& acc, const Unit& u, int wr, int wc, int fr, int fq) const {
;     ...
;                         const int c = colb + 128 * bj;
;                         f32x4 v0 = acc[ai][bj][m][0], v1 = acc[ai][bj][m][1];
;                         if (c < 64) {
; #pragma unroll
;                             for (int j = 0; j < 4; ++j) { v0[j] = 2.f * fsigmoid(2.f * v0[j]) - 1.f; v1[j] = 2.f * fsigmoid(2.f * v1[j]) - 1.f; }
.LBB0_911:
	s_andn2_saveexec_b64 s[50:51], s[50:51]
	s_cbranch_execz .LBB0_913
	v_add_f32_e32 v145, v32, v32
	v_mul_f32_e32 v145, 0xbfb8aa3b, v145
	v_add_f32_e32 v146, v37, v37
	v_exp_f32_e32 v145, v145
	v_mul_f32_e32 v146, 0xbfb8aa3b, v146
	v_exp_f32_e32 v146, v146
	v_add_f32_e32 v147, v38, v38
	v_add_f32_e32 v145, 1.0, v145
	v_rcp_f32_e32 v148, v145
	v_add_f32_e32 v145, 1.0, v146
	v_add_f32_e32 v146, v33, v33
	v_add_f32_e32 v149, v34, v34
	v_mul_f32_e32 v146, 0xbfb8aa3b, v146
	v_mul_f32_e32 v147, 0xbfb8aa3b, v147
	v_mul_f32_e32 v149, 0xbfb8aa3b, v149
	v_exp_f32_e32 v146, v146
	v_exp_f32_e32 v147, v147
	v_exp_f32_e32 v149, v149
	v_add_f32_e32 v144, v36, v36
	v_add_f32_e32 v150, 1.0, v146
	v_add_f32_e32 v146, 1.0, v147
	v_add_f32_e32 v147, 1.0, v149
	v_add_f32_e32 v149, v39, v39
	v_add_f32_e32 v151, v35, v35
	v_mul_f32_e32 v144, 0xbfb8aa3b, v144
	v_mul_f32_e32 v149, 0xbfb8aa3b, v149
	v_mul_f32_e32 v151, 0xbfb8aa3b, v151
	v_exp_f32_e32 v144, v144
	v_exp_f32_e32 v149, v149
	v_exp_f32_e32 v151, v151
	v_rcp_f32_e32 v152, v147
	v_add_f32_e32 v144, 1.0, v144
	v_add_f32_e32 v147, 1.0, v149
	v_add_f32_e32 v149, 1.0, v151
	v_rcp_f32_e32 v144, v144
	v_rcp_f32_e32 v145, v145
	v_rcp_f32_e32 v146, v146
	v_rcp_f32_e32 v147, v147
	v_rcp_f32_e32 v153, v149
	v_rcp_f32_e32 v149, v150
	v_fma_f32 v150, v146, 2.0, -1.0
	v_fma_f32 v151, v147, 2.0, -1.0
	v_fma_f32 v146, v144, 2.0, -1.0
	v_fma_f32 v147, v145, 2.0, -1.0
	v_fma_f32 v152, v152, 2.0, -1.0
	v_fma_f32 v153, v153, 2.0, -1.0
	v_fma_f32 v148, v148, 2.0, -1.0
	v_fma_f32 v149, v149, 2.0, -1.0

; __device__ __forceinline__ float fsigmoid(float x) { return frcp(1.f + fexp2(-x * LOG2E)); }
;     __device__ __forceinline__ void operator()(const Acc& acc, const Unit& u, int wr, int wc, int fr, int fq) const {
;     ...
;                         const int c = colb + 128 * bj;
;                         f32x4 v0 = acc[ai][bj][m][0], v1 = acc[ai][bj][m][1];
;                         if (c < 64) {
; #pragma unroll
;                             for (int j = 0; j < 4; ++j) { v0[j] = 2.f * fsigmoid(2.f * v0[j]) - 1.f; v1[j] = 2.f * fsigmoid(2.f * v1[j]) - 1.f; }
.LBB0_917:
	s_andn2_saveexec_b64 s[50:51], s[50:51]
	s_cbranch_execz .LBB0_919
	v_add_f32_e32 v147, v8, v8
	v_mul_f32_e32 v147, 0xbfb8aa3b, v147
	v_add_f32_e32 v148, v13, v13
	v_exp_f32_e32 v147, v147
	v_mul_f32_e32 v148, 0xbfb8aa3b, v148
	v_exp_f32_e32 v149, v148
	v_add_f32_e32 v152, v15, v15
	v_add_f32_e32 v147, 1.0, v147
	v_add_f32_e32 v151, v10, v10
	v_mul_f32_e32 v152, 0xbfb8aa3b, v152
	v_add_f32_e32 v146, v12, v12
	v_rcp_f32_e32 v148, v147
	v_add_f32_e32 v147, 1.0, v149
	v_add_f32_e32 v149, v9, v9
	v_add_f32_e32 v150, v14, v14
	v_mul_f32_e32 v151, 0xbfb8aa3b, v151
	v_exp_f32_e32 v153, v152
	v_add_f32_e32 v152, v11, v11
	v_mul_f32_e32 v146, 0xbfb8aa3b, v146
	v_mul_f32_e32 v149, 0xbfb8aa3b, v149
	v_mul_f32_e32 v150, 0xbfb8aa3b, v150
	v_exp_f32_e32 v151, v151
	v_mul_f32_e32 v152, 0xbfb8aa3b, v152
	v_exp_f32_e32 v146, v146
	v_exp_f32_e32 v149, v149
	v_exp_f32_e32 v150, v150
	v_exp_f32_e32 v162, v152
	v_add_f32_e32 v151, 1.0, v151
	v_add_f32_e32 v146, 1.0, v146
	v_add_f32_e32 v149, 1.0, v149
	v_add_f32_e32 v150, 1.0, v150
	v_rcp_f32_e32 v152, v151
	v_add_f32_e32 v151, 1.0, v153
	v_add_f32_e32 v153, 1.0, v162
	v_rcp_f32_e32 v146, v146
	v_rcp_f32_e32 v147, v147
	v_rcp_f32_e32 v150, v150
	v_rcp_f32_e32 v151, v151
	v_rcp_f32_e32 v153, v153
	v_rcp_f32_e32 v149, v149
	v_fma_f32 v146, v146, 2.0, -1.0
	v_fma_f32 v147, v147, 2.0, -1.0
	v_fma_f32 v150, v150, 2.0, -1.0
	v_fma_f32 v151, v151, 2.0, -1.0
	v_fma_f32 v152, v152, 2.0, -1.0
	v_fma_f32 v153, v153, 2.0, -1.0
	v_fma_f32 v148, v148, 2.0, -1.0
	v_fma_f32 v149, v149, 2.0, -1.0

; __device__ __forceinline__ float fsigmoid(float x) { return frcp(1.f + fexp2(-x * LOG2E)); }
;     __device__ __forceinline__ void operator()(const Acc& acc, const Unit& u, int wr, int wc, int fr, int fq) const {
;     ...
;                         const int c = colb + 128 * bj;
;                         f32x4 v0 = acc[ai][bj][m][0], v1 = acc[ai][bj][m][1];
;                         if (c < 64) {
; #pragma unroll
;                             for (int j = 0; j < 4; ++j) { v0[j] = 2.f * fsigmoid(2.f * v0[j]) - 1.f; v1[j] = 2.f * fsigmoid(2.f * v1[j]) - 1.f; }
.LBB0_923:
	s_andn2_saveexec_b64 s[8:9], s[8:9]
	s_cbranch_execz .LBB0_925
	v_add_f32_e32 v145, v16, v16
	v_mul_f32_e32 v145, 0xbfb8aa3b, v145
	v_add_f32_e32 v146, v21, v21
	v_exp_f32_e32 v145, v145
	v_mul_f32_e32 v146, 0xbfb8aa3b, v146
	v_exp_f32_e32 v146, v146
	v_add_f32_e32 v147, v22, v22
	v_add_f32_e32 v145, 1.0, v145
	v_rcp_f32_e32 v148, v145
	v_add_f32_e32 v145, 1.0, v146
	v_add_f32_e32 v146, v17, v17
	v_add_f32_e32 v149, v18, v18
	v_mul_f32_e32 v146, 0xbfb8aa3b, v146
	v_mul_f32_e32 v147, 0xbfb8aa3b, v147
	v_mul_f32_e32 v149, 0xbfb8aa3b, v149
	v_exp_f32_e32 v146, v146
	v_exp_f32_e32 v147, v147
	v_exp_f32_e32 v149, v149
	v_add_f32_e32 v144, v20, v20
	v_add_f32_e32 v150, 1.0, v146
	v_add_f32_e32 v146, 1.0, v147
	v_add_f32_e32 v147, 1.0, v149
	v_add_f32_e32 v149, v23, v23
	v_add_f32_e32 v151, v19, v19
	v_mul_f32_e32 v144, 0xbfb8aa3b, v144
	v_mul_f32_e32 v149, 0xbfb8aa3b, v149
	v_mul_f32_e32 v151, 0xbfb8aa3b, v151
	v_exp_f32_e32 v144, v144
	v_exp_f32_e32 v149, v149
	v_exp_f32_e32 v151, v151
	v_rcp_f32_e32 v152, v147
	v_add_f32_e32 v144, 1.0, v144
	v_add_f32_e32 v147, 1.0, v149
	v_add_f32_e32 v149, 1.0, v151
	v_rcp_f32_e32 v144, v144
	v_rcp_f32_e32 v145, v145
	v_rcp_f32_e32 v146, v146
	v_rcp_f32_e32 v147, v147
	v_rcp_f32_e32 v153, v149
	v_rcp_f32_e32 v149, v150
	v_fma_f32 v150, v146, 2.0, -1.0
	v_fma_f32 v151, v147, 2.0, -1.0
	v_fma_f32 v146, v144, 2.0, -1.0
	v_fma_f32 v147, v145, 2.0, -1.0
	v_fma_f32 v152, v152, 2.0, -1.0
	v_fma_f32 v153, v153, 2.0, -1.0
	v_fma_f32 v148, v148, 2.0, -1.0
	v_fma_f32 v149, v149, 2.0, -1.0

; __device__ __forceinline__ float fsigmoid(float x) { return frcp(1.f + fexp2(-x * LOG2E)); }
;     __device__ __forceinline__ void operator()(const Acc& acc, const Unit& u, int wr, int wc, int fr, int fq) const {
;     ...
;                         const int c = colb + 128 * bj;
;                         f32x4 v0 = acc[ai][bj][m][0], v1 = acc[ai][bj][m][1];
;                         if (c < 64) {
; #pragma unroll
;                             for (int j = 0; j < 4; ++j) { v0[j] = 2.f * fsigmoid(2.f * v0[j]) - 1.f; v1[j] = 2.f * fsigmoid(2.f * v1[j]) - 1.f; }
.LBB0_929:
	s_andn2_saveexec_b64 s[6:7], s[6:7]
	s_cbranch_execz .LBB0_931
	v_add_f32_e32 v141, v4, v4
	v_add_f32_e32 v142, v0, v0
	v_mul_f32_e32 v141, 0xbfb8aa3b, v141
	v_mul_f32_e32 v142, 0xbfb8aa3b, v142
	v_exp_f32_e32 v141, v141
	v_exp_f32_e32 v143, v142
	v_add_f32_e32 v142, v5, v5
	v_mul_f32_e32 v142, 0xbfb8aa3b, v142
	v_exp_f32_e32 v147, v142
	v_add_f32_e32 v141, 1.0, v141
	v_rcp_f32_e32 v142, v141
	v_add_f32_e32 v141, 1.0, v143
	v_rcp_f32_e32 v146, v141
	v_add_f32_e32 v141, 1.0, v147
	v_add_f32_e32 v147, v6, v6
	v_mul_f32_e32 v147, 0xbfb8aa3b, v147
	v_add_f32_e32 v148, v2, v2
	v_exp_f32_e32 v147, v147
	v_mul_f32_e32 v148, 0xbfb8aa3b, v148
	v_exp_f32_e32 v149, v148
	v_rcp_f32_e32 v143, v141
	v_add_f32_e32 v147, 1.0, v147
	v_rcp_f32_e32 v148, v147
	v_add_f32_e32 v147, 1.0, v149
	v_add_f32_e32 v149, v7, v7
	v_add_f32_e32 v141, v1, v1
	v_mul_f32_e32 v149, 0xbfb8aa3b, v149
	v_add_f32_e32 v150, v3, v3
	v_mul_f32_e32 v141, 0xbfb8aa3b, v141
	v_exp_f32_e32 v149, v149
	v_mul_f32_e32 v150, 0xbfb8aa3b, v150
	v_exp_f32_e32 v141, v141
	v_exp_f32_e32 v151, v150
	v_rcp_f32_e32 v150, v147
	v_add_f32_e32 v147, 1.0, v149
	v_add_f32_e32 v141, 1.0, v141
	v_rcp_f32_e32 v149, v147
	v_add_f32_e32 v147, 1.0, v151
	v_rcp_f32_e32 v151, v147
	v_rcp_f32_e32 v147, v141
	v_fma_f32 v148, v148, 2.0, -1.0
	v_fma_f32 v149, v149, 2.0, -1.0
	v_fma_f32 v142, v142, 2.0, -1.0
	v_fma_f32 v143, v143, 2.0, -1.0
	v_fma_f32 v150, v150, 2.0, -1.0
	v_fma_f32 v151, v151, 2.0, -1.0
	v_fma_f32 v146, v146, 2.0, -1.0
	v_fma_f32 v147, v147, 2.0, -1.0

; #define GAS __attribute__((address_space(1)))
; __device__ __forceinline__ float fsigmoid(float x) { return frcp(1.f + fexp2(-x * LOG2E)); }
;     __device__ __forceinline__ void operator()(const Acc& acc, const Unit& u, int wr, int wc, int fr, int fq) const {
;     ...
;         const float* bias = ldp(PL, t4 == 0 ? 17 : (t4 == 1 ? 20 : 31)) + (t4 < 2 ? idx * D : 0);
;         bf16_t* dst = W + (t4 == 0 ? 0L : (t4 == 1 ? (long)(32u << 20) : -(long)(32u << 20)));
;         const bf16_t* V = W - (long)(32u << 20);
;         const float osc = t4 == 0 ? 0.60653065971f : 1.f;
; #pragma unroll
;         for (int bj = 0; bj < 2; ++bj) {
;             const f32x4 b0 = *(const GAS f32x4*)(bias + colb + 128 * bj), b1 = *(const GAS f32x4*)(bias + colb + 128 * bj + 4);
; #pragma unroll
;             for (int ai = 0; ai < 2; ++ai)
; #pragma unroll
;                 for (int m = 0; m < 4; ++m) {
;                     const size_t off = (size_t)(row0 + ai * HALF + m * 16) * D + colb + 128 * bj;
;                     f32x4 v0_ = acc[ai][bj][m][0] + b0, v1_ = acc[ai][bj][m][1] + b1;
; #pragma unroll
;                     for (int j = 0; j < 4; ++j) { v0_[j] = fsigmoid(v0_[j]) * osc; v1_[j] = fsigmoid(v1_[j]) * osc; }
;                     if (t4 == 2) {
;                         f32x4 x0, x1, f0, f1; unpack8(*(const GAS u32x4*)(V + off), x0, x1); unpack8(*(const GAS u32x4*)(VF + off), f0, f1);
;                         v0_ = x0 + (f0 - x0) * v0_; v1_ = x1 + (f1 - x1) * v1_;
;                     }
;                     *(GAS u32x4*)(dst + off) = pack8(v0_, v1_);
.LBB0_1128:
	s_lshl_b32 s4, s69, 8
	s_lshl_b32 s1, s38, 8
	s_and_b32 s4, s4, 0x300
	s_ashr_i32 s0, s69, 2
	s_add_i32 s1, s1, s57
	s_or_b32 s29, s4, s58
	s_cmp_eq_u32 s0, 1
	s_cselect_b64 s[4:5], -1, 0
	s_and_b64 s[38:39], s[4:5], exec
	s_cselect_b32 s40, s66, 0xf8
	s_cmp_lt_u32 s69, 4
	s_cselect_b64 vcc, -1, 0
	s_and_b64 s[38:39], vcc, exec
	s_cselect_b32 s38, 0x88, s40
	s_add_i32 s38, s38, 0
	s_add_i32 s38, s38, 0x20000
	v_mov_b32_e32 v149, v161
	v_mov_b32_e32 v104, s38
	ds_read_b64 v[104:105], v104
	v_ashrrev_i32_e32 v106, 1, v149
	v_and_b32_e32 v106, -8, v106
	v_add_u32_e32 v152, s29, v106
	v_ashrrev_i32_e32 v153, 31, v152
	s_waitcnt lgkmcnt(0)
	v_readfirstlane_b32 s29, v104
	v_readfirstlane_b32 s38, v105
	v_and_or_b32 v156, v149, 15, s1
	v_mov_b32_e32 v104, s29
	v_mov_b32_e32 v105, s38
	v_lshl_add_u64 v[154:155], v[152:153], 2, v[104:105]
	global_load_dwordx4 v[108:111], v[154:155], off
	global_load_dwordx4 v[104:107], v[154:155], off offset:16
	v_ashrrev_i32_e32 v157, 31, v156
	v_cndmask_b32_e32 v148, 1.0, v166, vcc
	v_lshlrev_b64 v[150:151], 10, v[156:157]
	s_cmp_eq_u32 s0, 2
	s_cselect_b64 s[40:41], -1, 0
	s_cmp_lg_u32 s0, 2
	s_waitcnt vmcnt(0)
	v_add_f32_e32 v134, v134, v110
	v_add_f32_e32 v135, v135, v111
	v_add_f32_e32 v132, v132, v108
	v_add_f32_e32 v133, v133, v109
	v_add_f32_e32 v130, v130, v106
	v_add_f32_e32 v131, v131, v107
	v_add_f32_e32 v128, v128, v104
	v_add_f32_e32 v129, v129, v105
	v_mul_f32_e32 v132, 0xbfb8aa3b, v132
	v_mul_f32_e32 v128, 0xbfb8aa3b, v128
	v_mul_f32_e32 v133, 0xbfb8aa3b, v133
	v_mul_f32_e32 v129, 0xbfb8aa3b, v129
	v_mul_f32_e32 v134, 0xbfb8aa3b, v134
	v_mul_f32_e32 v130, 0xbfb8aa3b, v130
	v_mul_f32_e32 v135, 0xbfb8aa3b, v135
	v_mul_f32_e32 v131, 0xbfb8aa3b, v131
	v_exp_f32_e32 v132, v132
	v_exp_f32_e32 v128, v128
	v_exp_f32_e32 v133, v133
	v_exp_f32_e32 v129, v129
	v_exp_f32_e32 v134, v134
	v_exp_f32_e32 v130, v130
	v_exp_f32_e32 v135, v135
	v_exp_f32_e32 v131, v131
	v_add_f32_e32 v132, 1.0, v132
	v_add_f32_e32 v128, 1.0, v128
	v_add_f32_e32 v133, 1.0, v133
	v_add_f32_e32 v149, 1.0, v129
	v_add_f32_e32 v129, 1.0, v134
	v_add_f32_e32 v134, 1.0, v130
	v_add_f32_e32 v135, 1.0, v135
	v_add_f32_e32 v159, 1.0, v131
	v_rcp_f32_e32 v130, v132
	v_rcp_f32_e32 v158, v128
	v_rcp_f32_e32 v131, v133
	v_rcp_f32_e32 v128, v129
	v_rcp_f32_e32 v129, v135
	v_rcp_f32_e32 v132, v134
	v_rcp_f32_e32 v133, v159
	v_rcp_f32_e32 v159, v149
	v_mul_f32_e32 v128, v148, v128
	v_mul_f32_e32 v129, v148, v129
	v_mul_f32_e32 v134, v148, v130
	v_mul_f32_e32 v135, v148, v131
	v_mul_f32_e32 v132, v148, v132
	v_mul_f32_e32 v133, v148, v133
	v_mul_f32_e32 v158, v148, v158
	v_mul_f32_e32 v159, v148, v159
	v_lshl_add_u64 v[130:131], v[150:151], 0, v[152:153]
	s_cbranch_scc1 .LBB0_1130
	v_lshlrev_b64 v[172:173], 1, v[130:131]
	v_lshl_add_u64 v[168:169], s[18:19], 0, v[172:173]
	v_lshl_add_u64 v[172:173], s[8:9], 0, v[172:173]
	global_load_dwordx4 v[168:171], v[168:169], off
	s_waitcnt vmcnt(0)
	v_lshlrev_b32_e32 v176, 16, v168
	global_load_dwordx4 v[172:175], v[172:173], off
	v_and_b32_e32 v177, 0xffff0000, v168
	v_lshlrev_b32_e32 v168, 16, v169
	v_and_b32_e32 v169, 0xffff0000, v169
	v_lshlrev_b32_e32 v178, 16, v170
	v_and_b32_e32 v179, 0xffff0000, v170
	v_lshlrev_b32_e32 v170, 16, v171
	v_and_b32_e32 v171, 0xffff0000, v171
	s_waitcnt vmcnt(0)
	v_lshlrev_b32_e32 v149, 16, v172
	v_and_b32_e32 v167, 0xffff0000, v172
	v_lshlrev_b32_e32 v180, 16, v173
	v_and_b32_e32 v181, 0xffff0000, v173
	v_lshlrev_b32_e32 v182, 16, v174
	v_and_b32_e32 v183, 0xffff0000, v174
	v_lshlrev_b32_e32 v184, 16, v175
	v_and_b32_e32 v185, 0xffff0000, v175
	v_sub_f32_e32 v173, v167, v177
	v_sub_f32_e32 v172, v149, v176
	v_sub_f32_e32 v175, v181, v169
	v_sub_f32_e32 v174, v180, v168
	v_sub_f32_e32 v181, v183, v179
	v_sub_f32_e32 v180, v182, v178
	v_sub_f32_e32 v183, v185, v171
	v_sub_f32_e32 v182, v184, v170
	v_fma_f32 v128, v128, v174, v168
	v_fma_f32 v129, v129, v175, v169
	v_fma_f32 v134, v134, v172, v176
	v_fma_f32 v135, v135, v173, v177
	v_fma_f32 v132, v132, v182, v170
	v_fma_f32 v133, v133, v183, v171
	v_fma_f32 v158, v158, v180, v178
	v_fma_f32 v159, v159, v181, v179
.LBB0_1130:
	v_add_f32_e32 v120, v120, v104
	v_add_f32_e32 v121, v121, v105
	v_add_f32_e32 v124, v124, v108
	v_add_f32_e32 v125, v125, v109
	v_mul_f32_e32 v120, 0xbfb8aa3b, v120
	v_exp_f32_e32 v120, v120
	v_mul_f32_e32 v125, 0xbfb8aa3b, v125
	v_exp_f32_e32 v125, v125
	v_mul_f32_e32 v121, 0xbfb8aa3b, v121
	v_exp_f32_e32 v121, v121
	v_add_f32_e32 v120, 1.0, v120
	v_cvt_pk_bf16_f32 v170, v158, v159
	v_add_f32_e32 v126, v126, v110
	v_add_f32_e32 v127, v127, v111
	v_add_f32_e32 v122, v122, v106
	v_add_f32_e32 v123, v123, v107
	v_rcp_f32_e32 v158, v120
	v_add_f32_e32 v120, 1.0, v125
	v_rcp_f32_e32 v125, v120
	v_add_f32_e32 v120, 1.0, v121
	v_mul_f32_e32 v121, 0xbfb8aa3b, v126
	v_mul_f32_e32 v122, 0xbfb8aa3b, v122
	v_exp_f32_e32 v121, v121
	v_exp_f32_e32 v122, v122
	s_and_b64 s[38:39], s[4:5], exec
	v_rcp_f32_e32 v159, v120
	v_add_f32_e32 v120, 1.0, v121
	v_add_f32_e32 v121, 1.0, v122
	v_mul_f32_e32 v122, 0xbfb8aa3b, v127
	s_cselect_b32 s0, s67, 0xfe000000
	s_and_b64 s[38:39], vcc, exec
	v_mul_f32_e32 v124, 0xbfb8aa3b, v124
	v_exp_f32_e32 v126, v122
	v_rcp_f32_e32 v122, v121
	v_mul_f32_e32 v121, 0xbfb8aa3b, v123
	s_cselect_b32 s38, 0, s0
	s_or_b64 s[4:5], vcc, s[4:5]
	v_exp_f32_e32 v124, v124
	v_exp_f32_e32 v123, v121
	s_and_b64 s[4:5], s[4:5], exec
	s_cselect_b32 s39, 0, -1
	s_lshl_b64 s[4:5], s[38:39], 1
	s_add_u32 s38, s59, s4
	v_add_f32_e32 v124, 1.0, v124
	v_add_f32_e32 v123, 1.0, v123
	s_addc_u32 s39, s60, s5
	v_rcp_f32_e32 v124, v124
	v_add_f32_e32 v121, 1.0, v126
	v_rcp_f32_e32 v123, v123
	v_cvt_pk_bf16_f32 v168, v134, v135
	v_cvt_pk_bf16_f32 v169, v128, v129
	v_cvt_pk_bf16_f32 v171, v132, v133
	v_lshl_add_u64 v[132:133], v[130:131], 1, s[38:39]
	v_rcp_f32_e32 v120, v120
	v_rcp_f32_e32 v121, v121
	global_store_dwordx4 v[132:133], v[168:171], off
	v_or_b32_e32 v128, 16, v156
	v_mov_b32_e32 v149, v148
	v_ashrrev_i32_e32 v129, 31, v128
	v_mov_b32_e32 v126, v148
	v_mov_b32_e32 v127, v148
	v_lshlrev_b64 v[128:129], 10, v[128:129]
	v_mul_f32_e32 v134, v148, v124
	v_mul_f32_e32 v135, v149, v125
	v_mul_f32_e32 v124, v126, v122
	v_mul_f32_e32 v125, v127, v123
	v_cndmask_b32_e64 v122, 0, 1, s[40:41]
	v_mul_f32_e32 v120, v126, v120
	v_mul_f32_e32 v121, v127, v121
	v_mul_f32_e32 v158, v148, v158
	v_mul_f32_e32 v159, v149, v159
	v_cmp_ne_u32_e64 s[4:5], 1, v122
	s_andn2_b64 vcc, exec, s[40:41]
	v_lshl_add_u64 v[122:123], v[128:129], 0, v[152:153]
	s_cbranch_vccnz .LBB0_1132
; #define GAS __attribute__((address_space(1)))
; __device__ __forceinline__ float fsigmoid(float x) { return frcp(1.f + fexp2(-x * LOG2E)); }
;     __device__ __forceinline__ void operator()(const Acc& acc, const Unit& u, int wr, int wc, int fr, int fq) const {
;     ...
;             for (int ai = 0; ai < 2; ++ai)
; #pragma unroll
;                 for (int m = 0; m < 4; ++m) {
;                     const size_t off = (size_t)(row0 + ai * HALF + m * 16) * D + colb + 128 * bj;
;                     f32x4 v0_ = acc[ai][bj][m][0] + b0, v1_ = acc[ai][bj][m][1] + b1;
; #pragma unroll
;                     for (int j = 0; j < 4; ++j) { v0_[j] = fsigmoid(v0_[j]) * osc; v1_[j] = fsigmoid(v1_[j]) * osc; }
;                     if (t4 == 2) {
;                         f32x4 x0, x1, f0, f1; unpack8(*(const GAS u32x4*)(V + off), x0, x1); unpack8(*(const GAS u32x4*)(VF + off), f0, f1);
;                         v0_ = x0 + (f0 - x0) * v0_; v1_ = x1 + (f1 - x1) * v1_;
;                     }
;                     *(GAS u32x4*)(dst + off) = pack8(v0_, v1_);
	v_lshlrev_b64 v[172:173], 1, v[122:123]
	v_lshl_add_u64 v[168:169], s[18:19], 0, v[172:173]
	v_lshl_add_u64 v[172:173], s[8:9], 0, v[172:173]
	global_load_dwordx4 v[168:171], v[168:169], off
	s_waitcnt vmcnt(0)
	v_lshlrev_b32_e32 v176, 16, v168
	global_load_dwordx4 v[172:175], v[172:173], off
	v_and_b32_e32 v177, 0xffff0000, v168
	v_lshlrev_b32_e32 v168, 16, v169
	v_and_b32_e32 v169, 0xffff0000, v169
	v_lshlrev_b32_e32 v178, 16, v170
	v_and_b32_e32 v179, 0xffff0000, v170
	v_lshlrev_b32_e32 v170, 16, v171
	v_and_b32_e32 v171, 0xffff0000, v171
	s_waitcnt vmcnt(0)
	v_lshlrev_b32_e32 v167, 16, v172
	v_and_b32_e32 v172, 0xffff0000, v172
	v_lshlrev_b32_e32 v180, 16, v173
	v_and_b32_e32 v181, 0xffff0000, v173
	v_lshlrev_b32_e32 v182, 16, v174
	v_and_b32_e32 v183, 0xffff0000, v174
	v_lshlrev_b32_e32 v184, 16, v175
	v_and_b32_e32 v185, 0xffff0000, v175
	v_sub_f32_e32 v173, v172, v177
	v_sub_f32_e32 v172, v167, v176
	v_sub_f32_e32 v175, v181, v169
	v_sub_f32_e32 v174, v180, v168
	v_sub_f32_e32 v181, v183, v179
	v_sub_f32_e32 v180, v182, v178
	v_sub_f32_e32 v183, v185, v171
	v_sub_f32_e32 v182, v184, v170
	v_fma_f32 v120, v120, v174, v168
	v_fma_f32 v121, v121, v175, v169
	v_fma_f32 v134, v134, v172, v176
	v_fma_f32 v135, v135, v173, v177
	v_fma_f32 v124, v124, v182, v170
	v_fma_f32 v125, v125, v183, v171
	v_fma_f32 v158, v158, v180, v178
	v_fma_f32 v159, v159, v181, v179
.LBB0_1132:
	v_add_f32_e32 v112, v112, v104
	v_add_f32_e32 v113, v113, v105
	v_add_f32_e32 v116, v116, v108
	v_add_f32_e32 v117, v117, v109
	v_mul_f32_e32 v112, 0xbfb8aa3b, v112
	v_exp_f32_e32 v112, v112
	v_mul_f32_e32 v117, 0xbfb8aa3b, v117
	v_exp_f32_e32 v117, v117
	v_cvt_pk_bf16_f32 v168, v134, v135
	v_add_f32_e32 v112, 1.0, v112
	v_add_f32_e32 v118, v118, v110
	v_add_f32_e32 v119, v119, v111
	v_add_f32_e32 v114, v114, v106
	v_add_f32_e32 v115, v115, v107
	v_rcp_f32_e32 v134, v112
	v_add_f32_e32 v112, 1.0, v117
	v_rcp_f32_e32 v117, v112
	v_mul_f32_e32 v112, 0xbfb8aa3b, v113
	v_mul_f32_e32 v113, 0xbfb8aa3b, v118
	v_mul_f32_e32 v114, 0xbfb8aa3b, v114
	v_exp_f32_e32 v112, v112
	v_exp_f32_e32 v113, v113
	v_exp_f32_e32 v114, v114
	v_mul_f32_e32 v116, 0xbfb8aa3b, v116
	v_add_f32_e32 v118, 1.0, v112
	v_add_f32_e32 v112, 1.0, v113
	v_add_f32_e32 v113, 1.0, v114
	v_mul_f32_e32 v114, 0xbfb8aa3b, v119
	v_exp_f32_e32 v119, v114
	v_mul_f32_e32 v114, 0xbfb8aa3b, v115
	v_exp_f32_e32 v116, v116
	v_exp_f32_e32 v115, v114
	v_rcp_f32_e32 v114, v113
	v_add_f32_e32 v113, 1.0, v119
	v_add_f32_e32 v116, 1.0, v116
	v_add_f32_e32 v115, 1.0, v115
	v_cvt_pk_bf16_f32 v169, v120, v121
	v_cvt_pk_bf16_f32 v170, v158, v159
	v_cvt_pk_bf16_f32 v171, v124, v125
	v_lshl_add_u64 v[124:125], v[122:123], 1, s[38:39]
	v_rcp_f32_e32 v116, v116
	v_rcp_f32_e32 v112, v112
	v_rcp_f32_e32 v113, v113
	v_rcp_f32_e32 v115, v115
	v_rcp_f32_e32 v135, v118
	global_store_dwordx4 v[124:125], v[168:171], off
	v_or_b32_e32 v120, 32, v156
	v_ashrrev_i32_e32 v121, 31, v120
	v_lshlrev_b64 v[120:121], 10, v[120:121]
	v_mul_f32_e32 v112, v126, v112
	v_mul_f32_e32 v113, v127, v113
	v_mul_f32_e32 v118, v148, v116
	v_mul_f32_e32 v119, v149, v117
	v_mul_f32_e32 v116, v126, v114
	v_mul_f32_e32 v117, v127, v115
	v_mul_f32_e32 v126, v148, v134
	v_mul_f32_e32 v127, v149, v135
	s_and_b64 vcc, exec, s[4:5]
	v_lshl_add_u64 v[114:115], v[120:121], 0, v[152:153]
	s_cbranch_vccnz .LBB0_1134
	v_lshlrev_b64 v[134:135], 1, v[114:115]
	v_lshl_add_u64 v[158:159], s[18:19], 0, v[134:135]
	v_lshl_add_u64 v[134:135], s[8:9], 0, v[134:135]
	global_load_dwordx4 v[168:171], v[158:159], off
	global_load_dwordx4 v[172:175], v[134:135], off
	s_waitcnt vmcnt(1)
	v_lshlrev_b32_e32 v134, 16, v168
	v_and_b32_e32 v135, 0xffff0000, v168
	v_lshlrev_b32_e32 v158, 16, v169
	v_and_b32_e32 v159, 0xffff0000, v169
	v_lshlrev_b32_e32 v168, 16, v170
	v_and_b32_e32 v169, 0xffff0000, v170
	v_lshlrev_b32_e32 v170, 16, v171
	v_and_b32_e32 v171, 0xffff0000, v171
	s_waitcnt vmcnt(0)
	v_lshlrev_b32_e32 v167, 16, v172
	v_and_b32_e32 v172, 0xffff0000, v172
	v_lshlrev_b32_e32 v176, 16, v173
	v_and_b32_e32 v177, 0xffff0000, v173
	v_lshlrev_b32_e32 v178, 16, v174
	v_and_b32_e32 v179, 0xffff0000, v174
	v_lshlrev_b32_e32 v180, 16, v175
	v_and_b32_e32 v181, 0xffff0000, v175
	v_sub_f32_e32 v173, v172, v135
	v_sub_f32_e32 v172, v167, v134
	v_sub_f32_e32 v175, v177, v159
	v_sub_f32_e32 v174, v176, v158
	v_sub_f32_e32 v177, v179, v169
	v_sub_f32_e32 v176, v178, v168
	v_sub_f32_e32 v179, v181, v171
	v_sub_f32_e32 v178, v180, v170
	v_fma_f32 v112, v112, v174, v158
	v_fma_f32 v113, v113, v175, v159
	v_fma_f32 v118, v118, v172, v134
	v_fma_f32 v119, v119, v173, v135
	v_fma_f32 v116, v116, v178, v170
	v_fma_f32 v117, v117, v179, v171
	v_fma_f32 v126, v126, v176, v168
	v_fma_f32 v127, v127, v177, v169
; #define GAS __attribute__((address_space(1)))
; __device__ __forceinline__ float fsigmoid(float x) { return frcp(1.f + fexp2(-x * LOG2E)); }
;     __device__ __forceinline__ void operator()(const Acc& acc, const Unit& u, int wr, int wc, int fr, int fq) const {
;     ...
;             for (int ai = 0; ai < 2; ++ai)
; #pragma unroll
;                 for (int m = 0; m < 4; ++m) {
;                     const size_t off = (size_t)(row0 + ai * HALF + m * 16) * D + colb + 128 * bj;
;                     f32x4 v0_ = acc[ai][bj][m][0] + b0, v1_ = acc[ai][bj][m][1] + b1;
; #pragma unroll
;                     for (int j = 0; j < 4; ++j) { v0_[j] = fsigmoid(v0_[j]) * osc; v1_[j] = fsigmoid(v1_[j]) * osc; }
;                     if (t4 == 2) {
;                         f32x4 x0, x1, f0, f1; unpack8(*(const GAS u32x4*)(V + off), x0, x1); unpack8(*(const GAS u32x4*)(VF + off), f0, f1);
;                         v0_ = x0 + (f0 - x0) * v0_; v1_ = x1 + (f1 - x1) * v1_;
;                     }
;                     *(GAS u32x4*)(dst + off) = pack8(v0_, v1_);
.LBB0_1134:
	v_add_f32_e32 v96, v96, v104
	v_add_f32_e32 v97, v97, v105
	v_add_f32_e32 v100, v100, v108
	v_add_f32_e32 v101, v101, v109
	v_mul_f32_e32 v96, 0xbfb8aa3b, v96
	v_exp_f32_e32 v96, v96
	v_mul_f32_e32 v101, 0xbfb8aa3b, v101
	v_exp_f32_e32 v101, v101
	v_mul_f32_e32 v97, 0xbfb8aa3b, v97
	v_exp_f32_e32 v97, v97
	v_add_f32_e32 v96, 1.0, v96
	v_cvt_pk_bf16_f32 v170, v126, v127
	v_add_f32_e32 v102, v102, v110
	v_add_f32_e32 v103, v103, v111
	v_add_f32_e32 v98, v98, v106
	v_add_f32_e32 v99, v99, v107
	v_rcp_f32_e32 v126, v96
	v_add_f32_e32 v96, 1.0, v101
	v_rcp_f32_e32 v101, v96
	v_add_f32_e32 v96, 1.0, v97
	v_mul_f32_e32 v97, 0xbfb8aa3b, v102
	v_mul_f32_e32 v98, 0xbfb8aa3b, v98
	v_exp_f32_e32 v97, v97
	v_exp_f32_e32 v98, v98
	v_rcp_f32_e32 v127, v96
	v_mul_f32_e32 v100, 0xbfb8aa3b, v100
	v_add_f32_e32 v96, 1.0, v97
	v_add_f32_e32 v97, 1.0, v98
	v_mul_f32_e32 v98, 0xbfb8aa3b, v103
	v_exp_f32_e32 v102, v98
	v_rcp_f32_e32 v98, v97
	v_mul_f32_e32 v97, 0xbfb8aa3b, v99
	v_exp_f32_e32 v100, v100
	v_exp_f32_e32 v99, v97
	v_add_f32_e32 v97, 1.0, v102
	v_cvt_pk_bf16_f32 v168, v118, v119
	v_add_f32_e32 v100, 1.0, v100
	v_add_f32_e32 v99, 1.0, v99
	v_cvt_pk_bf16_f32 v169, v112, v113
	v_cvt_pk_bf16_f32 v171, v116, v117
	v_lshl_add_u64 v[116:117], v[114:115], 1, s[38:39]
	v_rcp_f32_e32 v100, v100
	v_rcp_f32_e32 v96, v96
	v_rcp_f32_e32 v97, v97
	v_rcp_f32_e32 v99, v99
	global_store_dwordx4 v[116:117], v[168:171], off
	v_or_b32_e32 v112, 48, v156
	v_ashrrev_i32_e32 v113, 31, v112
	v_lshlrev_b64 v[112:113], 10, v[112:113]
	v_mov_b32_e32 v102, v148
	v_mov_b32_e32 v103, v148
	v_mul_f32_e32 v96, v102, v96
	v_mul_f32_e32 v97, v103, v97
	v_mul_f32_e32 v118, v148, v100
	v_mul_f32_e32 v119, v149, v101
	v_mul_f32_e32 v100, v102, v98
	v_mul_f32_e32 v101, v103, v99
	v_mul_f32_e32 v126, v148, v126
	v_mul_f32_e32 v127, v149, v127
	s_and_b64 vcc, exec, s[4:5]
	v_lshl_add_u64 v[98:99], v[112:113], 0, v[152:153]
	s_cbranch_vccnz .LBB0_1136
	v_lshlrev_b64 v[134:135], 1, v[98:99]
	v_lshl_add_u64 v[158:159], s[18:19], 0, v[134:135]
	v_lshl_add_u64 v[134:135], s[8:9], 0, v[134:135]
	global_load_dwordx4 v[168:171], v[158:159], off
	global_load_dwordx4 v[172:175], v[134:135], off
	s_waitcnt vmcnt(1)
	v_lshlrev_b32_e32 v134, 16, v168
	v_and_b32_e32 v135, 0xffff0000, v168
	v_lshlrev_b32_e32 v158, 16, v169
	v_and_b32_e32 v159, 0xffff0000, v169
	v_lshlrev_b32_e32 v168, 16, v170
	v_and_b32_e32 v169, 0xffff0000, v170
	v_lshlrev_b32_e32 v170, 16, v171
	v_and_b32_e32 v171, 0xffff0000, v171
	s_waitcnt vmcnt(0)
	v_lshlrev_b32_e32 v167, 16, v172
	v_and_b32_e32 v172, 0xffff0000, v172
	v_lshlrev_b32_e32 v176, 16, v173
	v_and_b32_e32 v177, 0xffff0000, v173
	v_lshlrev_b32_e32 v178, 16, v174
	v_and_b32_e32 v179, 0xffff0000, v174
	v_lshlrev_b32_e32 v180, 16, v175
	v_and_b32_e32 v181, 0xffff0000, v175
	v_sub_f32_e32 v173, v172, v135
	v_sub_f32_e32 v172, v167, v134
	v_sub_f32_e32 v175, v177, v159
	v_sub_f32_e32 v174, v176, v158
	v_sub_f32_e32 v177, v179, v169
	v_sub_f32_e32 v176, v178, v168
	v_sub_f32_e32 v179, v181, v171
	v_sub_f32_e32 v178, v180, v170
	v_fma_f32 v96, v96, v174, v158
	v_fma_f32 v97, v97, v175, v159
	v_fma_f32 v118, v118, v172, v134
	v_fma_f32 v119, v119, v173, v135
	v_fma_f32 v100, v100, v178, v170
	v_fma_f32 v101, v101, v179, v171
	v_fma_f32 v126, v126, v176, v168
	v_fma_f32 v127, v127, v177, v169
.LBB0_1136:
	v_add_f32_e32 v88, v88, v104
	v_add_f32_e32 v89, v89, v105
	v_add_f32_e32 v92, v92, v108
	v_add_f32_e32 v93, v93, v109
	v_mul_f32_e32 v88, 0xbfb8aa3b, v88
	v_exp_f32_e32 v88, v88
	v_mul_f32_e32 v93, 0xbfb8aa3b, v93
	v_exp_f32_e32 v93, v93
	v_cvt_pk_bf16_f32 v170, v126, v127
	v_add_f32_e32 v88, 1.0, v88
	v_add_f32_e32 v94, v94, v110
	v_add_f32_e32 v95, v95, v111
	v_add_f32_e32 v90, v90, v106
	v_add_f32_e32 v91, v91, v107
	v_rcp_f32_e32 v126, v88
	v_add_f32_e32 v88, 1.0, v93
	v_rcp_f32_e32 v93, v88
	v_mul_f32_e32 v88, 0xbfb8aa3b, v89
	v_mul_f32_e32 v89, 0xbfb8aa3b, v94
	v_mul_f32_e32 v90, 0xbfb8aa3b, v90
	v_exp_f32_e32 v88, v88
	v_exp_f32_e32 v89, v89
	v_exp_f32_e32 v90, v90
	v_mul_f32_e32 v92, 0xbfb8aa3b, v92
	v_add_f32_e32 v94, 1.0, v88
	v_add_f32_e32 v88, 1.0, v89
	v_add_f32_e32 v89, 1.0, v90
	v_mul_f32_e32 v90, 0xbfb8aa3b, v95
	v_exp_f32_e32 v95, v90
	v_mul_f32_e32 v90, 0xbfb8aa3b, v91
	v_exp_f32_e32 v92, v92
	v_exp_f32_e32 v91, v90
	v_rcp_f32_e32 v90, v89
	v_add_f32_e32 v89, 1.0, v95
	v_add_f32_e32 v92, 1.0, v92
	v_add_f32_e32 v91, 1.0, v91
	v_cvt_pk_bf16_f32 v168, v118, v119
	v_cvt_pk_bf16_f32 v169, v96, v97
	v_cvt_pk_bf16_f32 v171, v100, v101
	v_lshl_add_u64 v[100:101], v[98:99], 1, s[38:39]
	v_rcp_f32_e32 v92, v92
	v_rcp_f32_e32 v88, v88
	v_rcp_f32_e32 v89, v89
	v_rcp_f32_e32 v91, v91
	v_rcp_f32_e32 v127, v94
	global_store_dwordx4 v[100:101], v[168:171], off
	v_lshlrev_b64 v[118:119], 10, v[156:157]
	v_lshl_add_u64 v[96:97], v[118:119], 0, s[12:13]
	v_mul_f32_e32 v88, v102, v88
	v_mul_f32_e32 v89, v103, v89
	v_mul_f32_e32 v94, v148, v92
	v_mul_f32_e32 v95, v149, v93
	v_mul_f32_e32 v92, v102, v90
	v_mul_f32_e32 v93, v103, v91
	v_mul_f32_e32 v102, v148, v126
	v_mul_f32_e32 v103, v149, v127
	s_and_b64 vcc, exec, s[4:5]
	v_lshl_add_u64 v[90:91], v[96:97], 0, v[152:153]
	s_cbranch_vccnz .LBB0_1138
	v_lshlrev_b64 v[126:127], 1, v[90:91]
	v_lshl_add_u64 v[134:135], s[18:19], 0, v[126:127]
	v_lshl_add_u64 v[126:127], s[8:9], 0, v[126:127]
	global_load_dwordx4 v[168:171], v[134:135], off
	global_load_dwordx4 v[172:175], v[126:127], off
	s_waitcnt vmcnt(1)
	v_lshlrev_b32_e32 v126, 16, v168
	v_and_b32_e32 v127, 0xffff0000, v168
	v_lshlrev_b32_e32 v134, 16, v169
	v_and_b32_e32 v135, 0xffff0000, v169
	v_lshlrev_b32_e32 v158, 16, v170
	v_and_b32_e32 v159, 0xffff0000, v170
	v_lshlrev_b32_e32 v168, 16, v171
	v_and_b32_e32 v169, 0xffff0000, v171
	s_waitcnt vmcnt(0)
	v_lshlrev_b32_e32 v167, 16, v172
	v_and_b32_e32 v170, 0xffff0000, v172
	v_lshlrev_b32_e32 v172, 16, v173
	v_and_b32_e32 v173, 0xffff0000, v173
	v_lshlrev_b32_e32 v176, 16, v174
	v_and_b32_e32 v174, 0xffff0000, v174
	v_lshlrev_b32_e32 v178, 16, v175
	v_and_b32_e32 v177, 0xffff0000, v175
	v_sub_f32_e32 v171, v170, v127
	v_sub_f32_e32 v170, v167, v126
	v_sub_f32_e32 v173, v173, v135
	v_sub_f32_e32 v172, v172, v134
	v_sub_f32_e32 v175, v174, v159
	v_sub_f32_e32 v174, v176, v158
	v_sub_f32_e32 v177, v177, v169
	v_sub_f32_e32 v176, v178, v168
	v_fma_f32 v88, v88, v172, v134
	v_fma_f32 v89, v89, v173, v135
	v_fma_f32 v94, v94, v170, v126
	v_fma_f32 v95, v95, v171, v127
	v_fma_f32 v92, v92, v176, v168
	v_fma_f32 v93, v93, v177, v169
	v_fma_f32 v102, v102, v174, v158
	v_fma_f32 v103, v103, v175, v159
; #define GAS __attribute__((address_space(1)))
; __device__ __forceinline__ float fsigmoid(float x) { return frcp(1.f + fexp2(-x * LOG2E)); }
;     __device__ __forceinline__ void operator()(const Acc& acc, const Unit& u, int wr, int wc, int fr, int fq) const {
;     ...
;             for (int ai = 0; ai < 2; ++ai)
; #pragma unroll
;                 for (int m = 0; m < 4; ++m) {
;                     const size_t off = (size_t)(row0 + ai * HALF + m * 16) * D + colb + 128 * bj;
;                     f32x4 v0_ = acc[ai][bj][m][0] + b0, v1_ = acc[ai][bj][m][1] + b1;
; #pragma unroll
;                     for (int j = 0; j < 4; ++j) { v0_[j] = fsigmoid(v0_[j]) * osc; v1_[j] = fsigmoid(v1_[j]) * osc; }
;                     if (t4 == 2) {
;                         f32x4 x0, x1, f0, f1; unpack8(*(const GAS u32x4*)(V + off), x0, x1); unpack8(*(const GAS u32x4*)(VF + off), f0, f1);
;                         v0_ = x0 + (f0 - x0) * v0_; v1_ = x1 + (f1 - x1) * v1_;
;                     }
;                     *(GAS u32x4*)(dst + off) = pack8(v0_, v1_);
.LBB0_1138:
	v_add_f32_e32 v80, v80, v104
	v_add_f32_e32 v81, v81, v105
	v_add_f32_e32 v84, v84, v108
	v_add_f32_e32 v85, v85, v109
	v_mul_f32_e32 v80, 0xbfb8aa3b, v80
	v_exp_f32_e32 v80, v80
	v_mul_f32_e32 v85, 0xbfb8aa3b, v85
	v_exp_f32_e32 v85, v85
	v_mul_f32_e32 v81, 0xbfb8aa3b, v81
	v_exp_f32_e32 v81, v81
	v_add_f32_e32 v80, 1.0, v80
	v_cvt_pk_bf16_f32 v170, v102, v103
	v_add_f32_e32 v86, v86, v110
	v_add_f32_e32 v87, v87, v111
	v_add_f32_e32 v82, v82, v106
	v_add_f32_e32 v83, v83, v107
	v_rcp_f32_e32 v102, v80
	v_add_f32_e32 v80, 1.0, v85
	v_rcp_f32_e32 v85, v80
	v_add_f32_e32 v80, 1.0, v81
	v_mul_f32_e32 v81, 0xbfb8aa3b, v86
	v_mul_f32_e32 v82, 0xbfb8aa3b, v82
	v_exp_f32_e32 v81, v81
	v_exp_f32_e32 v82, v82
	v_rcp_f32_e32 v103, v80
	v_mul_f32_e32 v84, 0xbfb8aa3b, v84
	v_add_f32_e32 v80, 1.0, v81
	v_add_f32_e32 v81, 1.0, v82
	v_mul_f32_e32 v82, 0xbfb8aa3b, v87
	v_exp_f32_e32 v86, v82
	v_rcp_f32_e32 v82, v81
	v_mul_f32_e32 v81, 0xbfb8aa3b, v83
	v_exp_f32_e32 v84, v84
	v_exp_f32_e32 v83, v81
	v_add_f32_e32 v81, 1.0, v86
	v_cvt_pk_bf16_f32 v168, v94, v95
	v_add_f32_e32 v84, 1.0, v84
	v_add_f32_e32 v83, 1.0, v83
	v_cvt_pk_bf16_f32 v169, v88, v89
	v_cvt_pk_bf16_f32 v171, v92, v93
	v_lshl_add_u64 v[92:93], v[90:91], 1, s[38:39]
	v_rcp_f32_e32 v84, v84
	v_rcp_f32_e32 v80, v80
	v_rcp_f32_e32 v81, v81
	v_rcp_f32_e32 v83, v83
	global_store_dwordx4 v[92:93], v[168:171], off
	v_lshl_add_u64 v[88:89], v[118:119], 0, s[20:21]
	v_mov_b32_e32 v86, v148
	v_mov_b32_e32 v87, v148
	v_mul_f32_e32 v80, v86, v80
	v_mul_f32_e32 v81, v87, v81
	v_mul_f32_e32 v94, v148, v84
	v_mul_f32_e32 v95, v149, v85
	v_mul_f32_e32 v84, v86, v82
	v_mul_f32_e32 v85, v87, v83
	v_mul_f32_e32 v102, v148, v102
	v_mul_f32_e32 v103, v149, v103
	s_and_b64 vcc, exec, s[4:5]
	v_lshl_add_u64 v[82:83], v[88:89], 0, v[152:153]
	s_cbranch_vccnz .LBB0_1140
	v_lshlrev_b64 v[118:119], 1, v[82:83]
	v_lshl_add_u64 v[126:127], s[18:19], 0, v[118:119]
	v_lshl_add_u64 v[118:119], s[8:9], 0, v[118:119]
	global_load_dwordx4 v[168:171], v[126:127], off
	global_load_dwordx4 v[172:175], v[118:119], off
	s_waitcnt vmcnt(1)
	v_lshlrev_b32_e32 v118, 16, v168
	v_and_b32_e32 v119, 0xffff0000, v168
	v_lshlrev_b32_e32 v126, 16, v169
	v_and_b32_e32 v127, 0xffff0000, v169
	v_lshlrev_b32_e32 v134, 16, v170
	v_and_b32_e32 v135, 0xffff0000, v170
	v_lshlrev_b32_e32 v158, 16, v171
	v_and_b32_e32 v159, 0xffff0000, v171
	s_waitcnt vmcnt(0)
	v_lshlrev_b32_e32 v167, 16, v172
	v_and_b32_e32 v168, 0xffff0000, v172
	v_lshlrev_b32_e32 v170, 16, v173
	v_and_b32_e32 v171, 0xffff0000, v173
	v_lshlrev_b32_e32 v172, 16, v174
	v_and_b32_e32 v173, 0xffff0000, v174
	v_lshlrev_b32_e32 v174, 16, v175
	v_and_b32_e32 v175, 0xffff0000, v175
	v_sub_f32_e32 v169, v168, v119
	v_sub_f32_e32 v168, v167, v118
	v_sub_f32_e32 v171, v171, v127
	v_sub_f32_e32 v170, v170, v126
	v_sub_f32_e32 v173, v173, v135
	v_sub_f32_e32 v172, v172, v134
	v_sub_f32_e32 v175, v175, v159
	v_sub_f32_e32 v174, v174, v158
	v_fma_f32 v80, v80, v170, v126
	v_fma_f32 v81, v81, v171, v127
	v_fma_f32 v94, v94, v168, v118
	v_fma_f32 v95, v95, v169, v119
	v_fma_f32 v84, v84, v174, v158
	v_fma_f32 v85, v85, v175, v159
	v_fma_f32 v102, v102, v172, v134
	v_fma_f32 v103, v103, v173, v135
.LBB0_1140:
	v_add_f32_e32 v72, v72, v104
	v_add_f32_e32 v73, v73, v105
	v_add_f32_e32 v76, v76, v108
	v_add_f32_e32 v77, v77, v109
	v_mul_f32_e32 v72, 0xbfb8aa3b, v72
	v_exp_f32_e32 v72, v72
	v_mul_f32_e32 v77, 0xbfb8aa3b, v77
	v_exp_f32_e32 v77, v77
	v_cvt_pk_bf16_f32 v170, v102, v103
	v_add_f32_e32 v72, 1.0, v72
	v_add_f32_e32 v78, v78, v110
	v_add_f32_e32 v79, v79, v111
	v_add_f32_e32 v74, v74, v106
	v_add_f32_e32 v75, v75, v107
	v_rcp_f32_e32 v102, v72
	v_add_f32_e32 v72, 1.0, v77
	v_rcp_f32_e32 v77, v72
	v_mul_f32_e32 v72, 0xbfb8aa3b, v73
	v_mul_f32_e32 v73, 0xbfb8aa3b, v78
	v_mul_f32_e32 v74, 0xbfb8aa3b, v74
	v_exp_f32_e32 v72, v72
	v_exp_f32_e32 v73, v73
	v_exp_f32_e32 v74, v74
	v_mul_f32_e32 v76, 0xbfb8aa3b, v76
	v_add_f32_e32 v78, 1.0, v72
	v_add_f32_e32 v72, 1.0, v73
	v_add_f32_e32 v73, 1.0, v74
	v_mul_f32_e32 v74, 0xbfb8aa3b, v79
	v_exp_f32_e32 v79, v74
	v_mul_f32_e32 v74, 0xbfb8aa3b, v75
	v_exp_f32_e32 v76, v76
	v_exp_f32_e32 v75, v74
	v_rcp_f32_e32 v74, v73
	v_add_f32_e32 v73, 1.0, v79
	v_add_f32_e32 v76, 1.0, v76
	v_add_f32_e32 v75, 1.0, v75
	v_cvt_pk_bf16_f32 v168, v94, v95
	v_cvt_pk_bf16_f32 v169, v80, v81
	v_cvt_pk_bf16_f32 v171, v84, v85
	v_lshl_add_u64 v[84:85], v[82:83], 1, s[38:39]
	v_rcp_f32_e32 v76, v76
	v_rcp_f32_e32 v72, v72
	v_rcp_f32_e32 v73, v73
	v_rcp_f32_e32 v75, v75
	v_rcp_f32_e32 v103, v78
	global_store_dwordx4 v[84:85], v[168:171], off
	v_lshlrev_b64 v[94:95], 10, v[156:157]
	v_lshl_add_u64 v[80:81], v[94:95], 0, s[24:25]
	v_mul_f32_e32 v72, v86, v72
	v_mul_f32_e32 v73, v87, v73
	v_mul_f32_e32 v78, v148, v76
	v_mul_f32_e32 v79, v149, v77
	v_mul_f32_e32 v76, v86, v74
	v_mul_f32_e32 v77, v87, v75
	v_mul_f32_e32 v86, v148, v102
	v_mul_f32_e32 v87, v149, v103
	s_and_b64 vcc, exec, s[4:5]
	v_lshl_add_u64 v[74:75], v[80:81], 0, v[152:153]
	s_cbranch_vccnz .LBB0_1142
	v_lshlrev_b64 v[102:103], 1, v[74:75]
	v_lshl_add_u64 v[118:119], s[18:19], 0, v[102:103]
	v_lshl_add_u64 v[102:103], s[8:9], 0, v[102:103]
	global_load_dwordx4 v[156:159], v[118:119], off
	global_load_dwordx4 v[168:171], v[102:103], off
	s_waitcnt vmcnt(1)
	v_lshlrev_b32_e32 v102, 16, v156
	v_and_b32_e32 v103, 0xffff0000, v156
	v_lshlrev_b32_e32 v118, 16, v157
	v_and_b32_e32 v119, 0xffff0000, v157
	v_lshlrev_b32_e32 v126, 16, v158
	v_and_b32_e32 v127, 0xffff0000, v158
	v_lshlrev_b32_e32 v134, 16, v159
	v_and_b32_e32 v135, 0xffff0000, v159
	s_waitcnt vmcnt(0)
	v_lshlrev_b32_e32 v156, 16, v168
	v_and_b32_e32 v157, 0xffff0000, v168
	v_lshlrev_b32_e32 v158, 16, v169
	v_and_b32_e32 v159, 0xffff0000, v169
	v_lshlrev_b32_e32 v167, 16, v170
	v_and_b32_e32 v168, 0xffff0000, v170
	v_lshlrev_b32_e32 v170, 16, v171
	v_and_b32_e32 v171, 0xffff0000, v171
	v_sub_f32_e32 v157, v157, v103
	v_sub_f32_e32 v156, v156, v102
	v_sub_f32_e32 v159, v159, v119
	v_sub_f32_e32 v158, v158, v118
	v_sub_f32_e32 v169, v168, v127
	v_sub_f32_e32 v168, v167, v126
	v_sub_f32_e32 v171, v171, v135
	v_sub_f32_e32 v170, v170, v134
	v_fma_f32 v72, v72, v158, v118
	v_fma_f32 v73, v73, v159, v119
	v_fma_f32 v78, v78, v156, v102
	v_fma_f32 v79, v79, v157, v103
	v_fma_f32 v76, v76, v170, v134
	v_fma_f32 v77, v77, v171, v135
	v_fma_f32 v86, v86, v168, v126
	v_fma_f32 v87, v87, v169, v127
; #define GAS __attribute__((address_space(1)))
; __device__ __forceinline__ float fsigmoid(float x) { return frcp(1.f + fexp2(-x * LOG2E)); }
;     __device__ __forceinline__ void operator()(const Acc& acc, const Unit& u, int wr, int wc, int fr, int fq) const {
;     ...
;         for (int bj = 0; bj < 2; ++bj) {
;             const f32x4 b0 = *(const GAS f32x4*)(bias + colb + 128 * bj), b1 = *(const GAS f32x4*)(bias + colb + 128 * bj + 4);
; #pragma unroll
;             for (int ai = 0; ai < 2; ++ai)
; #pragma unroll
;                 for (int m = 0; m < 4; ++m) {
;                     const size_t off = (size_t)(row0 + ai * HALF + m * 16) * D + colb + 128 * bj;
;                     f32x4 v0_ = acc[ai][bj][m][0] + b0, v1_ = acc[ai][bj][m][1] + b1;
; #pragma unroll
;                     for (int j = 0; j < 4; ++j) { v0_[j] = fsigmoid(v0_[j]) * osc; v1_[j] = fsigmoid(v1_[j]) * osc; }
;                     if (t4 == 2) {
;                         f32x4 x0, x1, f0, f1; unpack8(*(const GAS u32x4*)(V + off), x0, x1); unpack8(*(const GAS u32x4*)(VF + off), f0, f1);
;                         v0_ = x0 + (f0 - x0) * v0_; v1_ = x1 + (f1 - x1) * v1_;
;                     }
;                     *(GAS u32x4*)(dst + off) = pack8(v0_, v1_);
.LBB0_1142:
	v_add_f32_e32 v64, v64, v104
	v_add_f32_e32 v65, v65, v105
	v_add_f32_e32 v68, v68, v108
	v_add_f32_e32 v69, v69, v109
	v_mul_f32_e32 v64, 0xbfb8aa3b, v64
	v_exp_f32_e32 v64, v64
	v_mul_f32_e32 v69, 0xbfb8aa3b, v69
	v_exp_f32_e32 v69, v69
	v_mul_f32_e32 v65, 0xbfb8aa3b, v65
	v_exp_f32_e32 v65, v65
	v_add_f32_e32 v64, 1.0, v64
	v_cvt_pk_bf16_f32 v159, v76, v77
	v_add_f32_e32 v70, v70, v110
	v_add_f32_e32 v71, v71, v111
	v_add_f32_e32 v66, v66, v106
	v_add_f32_e32 v67, v67, v107
	v_rcp_f32_e32 v76, v64
	v_add_f32_e32 v64, 1.0, v69
	v_rcp_f32_e32 v69, v64
	v_add_f32_e32 v64, 1.0, v65
	v_mul_f32_e32 v65, 0xbfb8aa3b, v70
	v_mul_f32_e32 v66, 0xbfb8aa3b, v66
	v_exp_f32_e32 v65, v65
	v_exp_f32_e32 v66, v66
	v_rcp_f32_e32 v77, v64
	v_mul_f32_e32 v68, 0xbfb8aa3b, v68
	v_add_f32_e32 v64, 1.0, v65
	v_add_f32_e32 v65, 1.0, v66
	v_mul_f32_e32 v66, 0xbfb8aa3b, v71
	v_exp_f32_e32 v70, v66
	v_rcp_f32_e32 v66, v65
	v_mul_f32_e32 v65, 0xbfb8aa3b, v67
	v_exp_f32_e32 v68, v68
	v_exp_f32_e32 v67, v65
	v_add_f32_e32 v65, 1.0, v70
	v_cvt_pk_bf16_f32 v156, v78, v79
	v_add_f32_e32 v68, 1.0, v68
	v_add_f32_e32 v67, 1.0, v67
	v_cvt_pk_bf16_f32 v157, v72, v73
	v_cvt_pk_bf16_f32 v158, v86, v87
	v_lshl_add_u64 v[78:79], v[74:75], 1, s[38:39]
	v_rcp_f32_e32 v68, v68
	v_rcp_f32_e32 v64, v64
	v_rcp_f32_e32 v65, v65
	v_rcp_f32_e32 v67, v67
	global_store_dwordx4 v[78:79], v[156:159], off
	v_lshl_add_u64 v[72:73], v[94:95], 0, s[26:27]
	v_mov_b32_e32 v102, v148
	v_mov_b32_e32 v103, v148
	v_mul_f32_e32 v64, v102, v64
	v_mul_f32_e32 v65, v103, v65
	v_mul_f32_e32 v68, v148, v68
	v_mul_f32_e32 v69, v149, v69
	v_mul_f32_e32 v66, v102, v66
	v_mul_f32_e32 v67, v103, v67
	v_mul_f32_e32 v70, v148, v76
	v_mul_f32_e32 v71, v149, v77
	s_and_b64 vcc, exec, s[4:5]
	v_lshl_add_u64 v[76:77], v[72:73], 0, v[152:153]
	s_cbranch_vccnz .LBB0_1144
	v_lshlrev_b64 v[86:87], 1, v[76:77]
	v_lshl_add_u64 v[94:95], s[18:19], 0, v[86:87]
	v_lshl_add_u64 v[86:87], s[8:9], 0, v[86:87]
	global_load_dwordx4 v[104:107], v[94:95], off
	global_load_dwordx4 v[108:111], v[86:87], off
	s_waitcnt vmcnt(1)
	v_lshlrev_b32_e32 v86, 16, v104
	v_and_b32_e32 v87, 0xffff0000, v104
	v_lshlrev_b32_e32 v94, 16, v105
	v_and_b32_e32 v95, 0xffff0000, v105
	v_lshlrev_b32_e32 v104, 16, v106
	v_and_b32_e32 v105, 0xffff0000, v106
	v_lshlrev_b32_e32 v106, 16, v107
	v_and_b32_e32 v107, 0xffff0000, v107
	s_waitcnt vmcnt(0)
	v_lshlrev_b32_e32 v118, 16, v108
	v_and_b32_e32 v108, 0xffff0000, v108
	v_lshlrev_b32_e32 v119, 16, v109
	v_and_b32_e32 v126, 0xffff0000, v109
	v_lshlrev_b32_e32 v127, 16, v110
	v_and_b32_e32 v134, 0xffff0000, v110
	v_lshlrev_b32_e32 v135, 16, v111
	v_and_b32_e32 v156, 0xffff0000, v111
	v_sub_f32_e32 v109, v108, v87
	v_sub_f32_e32 v108, v118, v86
	v_sub_f32_e32 v111, v126, v95
	v_sub_f32_e32 v110, v119, v94
	v_sub_f32_e32 v119, v134, v105
	v_sub_f32_e32 v118, v127, v104
	v_sub_f32_e32 v127, v156, v107
	v_sub_f32_e32 v126, v135, v106
	v_fma_f32 v64, v64, v110, v94
	v_fma_f32 v65, v65, v111, v95
	v_fma_f32 v68, v68, v108, v86
	v_fma_f32 v69, v69, v109, v87
	v_fma_f32 v66, v66, v126, v106
	v_fma_f32 v67, v67, v127, v107
	v_fma_f32 v70, v70, v118, v104
	v_fma_f32 v71, v71, v119, v105
.LBB0_1144:
	v_cvt_pk_bf16_f32 v68, v68, v69
	v_cvt_pk_bf16_f32 v69, v64, v65
	v_cvt_pk_bf16_f32 v70, v70, v71
	v_cvt_pk_bf16_f32 v71, v66, v67
	v_lshl_add_u64 v[86:87], v[76:77], 1, s[38:39]
	global_store_dwordx4 v[86:87], v[68:71], off
	global_load_dwordx4 v[68:71], v[154:155], off offset:512
	global_load_dwordx4 v[64:67], v[154:155], off offset:528
	v_lshl_add_u64 v[94:95], v[152:153], 0, s[16:17]
	s_and_b64 vcc, exec, s[4:5]
	s_waitcnt vmcnt(1)
	v_add_f32_e32 v62, v62, v70
	v_add_f32_e32 v63, v63, v71
	v_add_f32_e32 v60, v60, v68
	v_add_f32_e32 v61, v61, v69
	s_waitcnt vmcnt(0)
	v_add_f32_e32 v58, v58, v66
	v_add_f32_e32 v59, v59, v67
	v_add_f32_e32 v56, v56, v64
	v_add_f32_e32 v57, v57, v65
	v_mul_f32_e32 v60, 0xbfb8aa3b, v60
	v_mul_f32_e32 v56, 0xbfb8aa3b, v56
	v_mul_f32_e32 v61, 0xbfb8aa3b, v61
	v_mul_f32_e32 v57, 0xbfb8aa3b, v57
	v_mul_f32_e32 v62, 0xbfb8aa3b, v62
	v_mul_f32_e32 v58, 0xbfb8aa3b, v58
	v_mul_f32_e32 v63, 0xbfb8aa3b, v63
	v_mul_f32_e32 v59, 0xbfb8aa3b, v59
	v_exp_f32_e32 v60, v60
	v_exp_f32_e32 v56, v56
	v_exp_f32_e32 v61, v61
	v_exp_f32_e32 v57, v57
	v_exp_f32_e32 v62, v62
	v_exp_f32_e32 v58, v58
	v_exp_f32_e32 v63, v63
	v_exp_f32_e32 v59, v59
	v_add_f32_e32 v60, 1.0, v60
	v_add_f32_e32 v104, 1.0, v56
	v_add_f32_e32 v61, 1.0, v61
	v_add_f32_e32 v106, 1.0, v57
	v_add_f32_e32 v62, 1.0, v62
	v_add_f32_e32 v105, 1.0, v58
	v_add_f32_e32 v63, 1.0, v63
	v_add_f32_e32 v107, 1.0, v59
	v_rcp_f32_e32 v56, v60
	v_rcp_f32_e32 v60, v104
	v_rcp_f32_e32 v57, v61
	v_rcp_f32_e32 v58, v62
	v_rcp_f32_e32 v59, v63
	v_rcp_f32_e32 v104, v105
	v_rcp_f32_e32 v105, v107
	v_rcp_f32_e32 v61, v106
	v_mul_f32_e32 v58, v102, v58
	v_mul_f32_e32 v59, v103, v59
	v_mul_f32_e32 v62, v148, v56
	v_mul_f32_e32 v63, v149, v57
	v_mul_f32_e32 v56, v102, v104
	v_mul_f32_e32 v57, v103, v105
	v_mul_f32_e32 v60, v148, v60
	v_mul_f32_e32 v61, v149, v61
	s_cbranch_vccnz .LBB0_1146
	v_lshl_add_u64 v[106:107], v[94:95], 0, v[150:151]
	v_lshl_add_u64 v[102:103], v[130:131], 1, s[8:9]
	v_lshl_add_u64 v[106:107], v[106:107], 1, s[18:19]
	global_load_dwordx4 v[102:105], v[102:103], off offset:256
	s_waitcnt vmcnt(0)
	v_lshlrev_b32_e32 v110, 16, v102
	global_load_dwordx4 v[106:109], v[106:107], off
	v_and_b32_e32 v111, 0xffff0000, v102
	v_lshlrev_b32_e32 v118, 16, v103
	v_and_b32_e32 v119, 0xffff0000, v103
	v_lshlrev_b32_e32 v126, 16, v104
	v_and_b32_e32 v127, 0xffff0000, v104
	v_lshlrev_b32_e32 v130, 16, v105
	v_and_b32_e32 v131, 0xffff0000, v105
	s_waitcnt vmcnt(0)
	v_lshlrev_b32_e32 v102, 16, v106
	v_and_b32_e32 v103, 0xffff0000, v106
	v_lshlrev_b32_e32 v104, 16, v107
	v_and_b32_e32 v105, 0xffff0000, v107
	v_lshlrev_b32_e32 v106, 16, v108
	v_and_b32_e32 v107, 0xffff0000, v108
	v_lshlrev_b32_e32 v108, 16, v109
	v_and_b32_e32 v109, 0xffff0000, v109
	v_sub_f32_e32 v111, v111, v103
	v_sub_f32_e32 v110, v110, v102
	v_sub_f32_e32 v119, v119, v105
	v_sub_f32_e32 v118, v118, v104
	v_sub_f32_e32 v127, v127, v107
	v_sub_f32_e32 v126, v126, v106
	v_sub_f32_e32 v131, v131, v109
	v_sub_f32_e32 v130, v130, v108
	v_fma_f32 v58, v58, v118, v104
	v_fma_f32 v59, v59, v119, v105
	v_fma_f32 v62, v62, v110, v102
	v_fma_f32 v63, v63, v111, v103
	v_fma_f32 v56, v56, v130, v108
	v_fma_f32 v57, v57, v131, v109
	v_fma_f32 v60, v60, v126, v106
	v_fma_f32 v61, v61, v127, v107
; #define GAS __attribute__((address_space(1)))
; __device__ __forceinline__ float fsigmoid(float x) { return frcp(1.f + fexp2(-x * LOG2E)); }
;     __device__ __forceinline__ void operator()(const Acc& acc, const Unit& u, int wr, int wc, int fr, int fq) const {
;     ...
;             for (int ai = 0; ai < 2; ++ai)
; #pragma unroll
;                 for (int m = 0; m < 4; ++m) {
;                     const size_t off = (size_t)(row0 + ai * HALF + m * 16) * D + colb + 128 * bj;
;                     f32x4 v0_ = acc[ai][bj][m][0] + b0, v1_ = acc[ai][bj][m][1] + b1;
; #pragma unroll
;                     for (int j = 0; j < 4; ++j) { v0_[j] = fsigmoid(v0_[j]) * osc; v1_[j] = fsigmoid(v1_[j]) * osc; }
;                     if (t4 == 2) {
;                         f32x4 x0, x1, f0, f1; unpack8(*(const GAS u32x4*)(V + off), x0, x1); unpack8(*(const GAS u32x4*)(VF + off), f0, f1);
;                         v0_ = x0 + (f0 - x0) * v0_; v1_ = x1 + (f1 - x1) * v1_;
;                     }
;                     *(GAS u32x4*)(dst + off) = pack8(v0_, v1_);
.LBB0_1146:
	v_add_f32_e32 v48, v48, v64
	v_add_f32_e32 v49, v49, v65
	v_add_f32_e32 v52, v52, v68
	v_add_f32_e32 v53, v53, v69
	v_mul_f32_e32 v48, 0xbfb8aa3b, v48
	v_exp_f32_e32 v48, v48
	v_mul_f32_e32 v53, 0xbfb8aa3b, v53
	v_exp_f32_e32 v53, v53
	v_mul_f32_e32 v49, 0xbfb8aa3b, v49
	v_exp_f32_e32 v49, v49
	v_add_f32_e32 v48, 1.0, v48
	v_cvt_pk_bf16_f32 v105, v56, v57
	v_add_f32_e32 v54, v54, v70
	v_add_f32_e32 v55, v55, v71
	v_rcp_f32_e32 v56, v48
	v_add_f32_e32 v48, 1.0, v53
	v_add_f32_e32 v50, v50, v66
	v_add_f32_e32 v51, v51, v67
	v_rcp_f32_e32 v53, v48
	v_add_f32_e32 v48, 1.0, v49
	v_mul_f32_e32 v49, 0xbfb8aa3b, v54
	v_exp_f32_e32 v49, v49
	v_mul_f32_e32 v50, 0xbfb8aa3b, v50
	v_exp_f32_e32 v54, v50
	v_rcp_f32_e32 v57, v48
	v_add_f32_e32 v48, 1.0, v49
	v_rcp_f32_e32 v50, v48
	v_add_f32_e32 v48, 1.0, v54
	v_cvt_pk_bf16_f32 v103, v58, v59
	v_mul_f32_e32 v52, 0xbfb8aa3b, v52
	v_mul_f32_e32 v49, 0xbfb8aa3b, v55
	v_rcp_f32_e32 v58, v48
	v_mul_f32_e32 v48, 0xbfb8aa3b, v51
	v_exp_f32_e32 v52, v52
	v_exp_f32_e32 v49, v49
	v_exp_f32_e32 v54, v48
	v_cvt_pk_bf16_f32 v102, v62, v63
	v_add_f32_e32 v52, 1.0, v52
	v_add_f32_e32 v48, 1.0, v49
	v_add_f32_e32 v49, 1.0, v54
	v_cvt_pk_bf16_f32 v104, v60, v61
	v_rcp_f32_e32 v52, v52
	v_rcp_f32_e32 v51, v48
	v_rcp_f32_e32 v59, v49
	global_store_dwordx4 v[132:133], v[102:105], off offset:256
	v_mov_b32_e32 v48, v148
	v_mov_b32_e32 v49, v148
	v_mul_f32_e32 v50, v48, v50
	v_mul_f32_e32 v51, v49, v51
	v_mul_f32_e32 v54, v148, v52
	v_mul_f32_e32 v55, v149, v53
	v_mul_f32_e32 v52, v48, v58
	v_mul_f32_e32 v53, v49, v59
	s_and_b64 vcc, exec, s[4:5]
	v_mul_f32_e32 v56, v148, v56
	v_mul_f32_e32 v57, v149, v57
	s_cbranch_vccnz .LBB0_1148
	v_lshl_add_u64 v[62:63], v[94:95], 0, v[128:129]
	v_lshl_add_u64 v[58:59], v[122:123], 1, s[8:9]
	v_lshl_add_u64 v[62:63], v[62:63], 1, s[18:19]
	global_load_dwordx4 v[58:61], v[58:59], off offset:256
	s_waitcnt vmcnt(0)
	v_lshlrev_b32_e32 v106, 16, v58
	global_load_dwordx4 v[102:105], v[62:63], off
	v_and_b32_e32 v107, 0xffff0000, v58
	v_lshlrev_b32_e32 v108, 16, v59
	v_and_b32_e32 v109, 0xffff0000, v59
	v_lshlrev_b32_e32 v110, 16, v60
	v_and_b32_e32 v111, 0xffff0000, v60
	v_lshlrev_b32_e32 v118, 16, v61
	v_and_b32_e32 v119, 0xffff0000, v61
	s_waitcnt vmcnt(0)
	v_lshlrev_b32_e32 v58, 16, v102
	v_and_b32_e32 v59, 0xffff0000, v102
	v_lshlrev_b32_e32 v60, 16, v103
	v_and_b32_e32 v61, 0xffff0000, v103
	v_lshlrev_b32_e32 v62, 16, v104
	v_and_b32_e32 v63, 0xffff0000, v104
	v_lshlrev_b32_e32 v102, 16, v105
	v_and_b32_e32 v103, 0xffff0000, v105
	v_sub_f32_e32 v105, v107, v59
	v_sub_f32_e32 v104, v106, v58
	v_sub_f32_e32 v107, v109, v61
	v_sub_f32_e32 v106, v108, v60
	v_sub_f32_e32 v109, v111, v63
	v_sub_f32_e32 v108, v110, v62
	v_sub_f32_e32 v111, v119, v103
	v_sub_f32_e32 v110, v118, v102
	v_fma_f32 v50, v50, v106, v60
	v_fma_f32 v51, v51, v107, v61
	v_fma_f32 v54, v54, v104, v58
	v_fma_f32 v55, v55, v105, v59
	v_fma_f32 v52, v52, v110, v102
	v_fma_f32 v53, v53, v111, v103
	v_fma_f32 v56, v56, v108, v62
	v_fma_f32 v57, v57, v109, v63
.LBB0_1148:
	v_add_f32_e32 v40, v40, v64
	v_add_f32_e32 v41, v41, v65
	v_add_f32_e32 v44, v44, v68
	v_add_f32_e32 v45, v45, v69
	v_mul_f32_e32 v40, 0xbfb8aa3b, v40
	v_exp_f32_e32 v40, v40
	v_mul_f32_e32 v45, 0xbfb8aa3b, v45
	v_exp_f32_e32 v45, v45
	v_cvt_pk_bf16_f32 v54, v54, v55
	v_add_f32_e32 v40, 1.0, v40
	v_cvt_pk_bf16_f32 v55, v50, v51
	v_add_f32_e32 v46, v46, v70
	v_add_f32_e32 v47, v47, v71
	v_add_f32_e32 v42, v42, v66
	v_add_f32_e32 v43, v43, v67
	v_rcp_f32_e32 v50, v40
	v_add_f32_e32 v40, 1.0, v45
	v_rcp_f32_e32 v45, v40
	v_mul_f32_e32 v40, 0xbfb8aa3b, v41
	v_mul_f32_e32 v41, 0xbfb8aa3b, v46
	v_mul_f32_e32 v42, 0xbfb8aa3b, v42
	v_exp_f32_e32 v40, v40
	v_exp_f32_e32 v41, v41
	v_exp_f32_e32 v42, v42
	v_mul_f32_e32 v44, 0xbfb8aa3b, v44
	v_add_f32_e32 v46, 1.0, v40
	v_add_f32_e32 v40, 1.0, v41
	v_add_f32_e32 v41, 1.0, v42
	v_mul_f32_e32 v42, 0xbfb8aa3b, v47
	v_exp_f32_e32 v47, v42
	v_mul_f32_e32 v42, 0xbfb8aa3b, v43
	v_exp_f32_e32 v44, v44
	v_exp_f32_e32 v43, v42
	v_rcp_f32_e32 v42, v41
	v_add_f32_e32 v41, 1.0, v47
	v_add_f32_e32 v44, 1.0, v44
	v_add_f32_e32 v43, 1.0, v43
	v_cvt_pk_bf16_f32 v56, v56, v57
	v_cvt_pk_bf16_f32 v57, v52, v53
	v_rcp_f32_e32 v44, v44
	v_rcp_f32_e32 v40, v40
	v_rcp_f32_e32 v41, v41
	v_rcp_f32_e32 v43, v43
	v_rcp_f32_e32 v51, v46
	global_store_dwordx4 v[124:125], v[54:57], off offset:256
	v_mul_f32_e32 v40, v48, v40
	v_mul_f32_e32 v41, v49, v41
	v_mul_f32_e32 v44, v148, v44
	v_mul_f32_e32 v45, v149, v45
	v_mul_f32_e32 v42, v48, v42
	v_mul_f32_e32 v43, v49, v43
	s_and_b64 vcc, exec, s[4:5]
	v_mul_f32_e32 v46, v148, v50
	v_mul_f32_e32 v47, v149, v51
	s_cbranch_vccnz .LBB0_1150
	v_lshl_add_u64 v[52:53], v[94:95], 0, v[120:121]
	v_lshl_add_u64 v[48:49], v[114:115], 1, s[8:9]
	v_lshl_add_u64 v[52:53], v[52:53], 1, s[18:19]
	global_load_dwordx4 v[48:51], v[48:49], off offset:256
	s_waitcnt vmcnt(0)
	v_lshlrev_b32_e32 v56, 16, v48
	global_load_dwordx4 v[52:55], v[52:53], off
	v_and_b32_e32 v57, 0xffff0000, v48
	v_lshlrev_b32_e32 v58, 16, v49
	v_and_b32_e32 v59, 0xffff0000, v49
	v_lshlrev_b32_e32 v60, 16, v50
	v_and_b32_e32 v61, 0xffff0000, v50
	v_lshlrev_b32_e32 v62, 16, v51
	v_and_b32_e32 v63, 0xffff0000, v51
	s_waitcnt vmcnt(0)
	v_lshlrev_b32_e32 v48, 16, v52
	v_and_b32_e32 v49, 0xffff0000, v52
	v_lshlrev_b32_e32 v50, 16, v53
	v_and_b32_e32 v51, 0xffff0000, v53
	v_lshlrev_b32_e32 v52, 16, v54
	v_and_b32_e32 v53, 0xffff0000, v54
	v_lshlrev_b32_e32 v54, 16, v55
	v_and_b32_e32 v55, 0xffff0000, v55
	v_sub_f32_e32 v57, v57, v49
	v_sub_f32_e32 v56, v56, v48
	v_sub_f32_e32 v59, v59, v51
	v_sub_f32_e32 v58, v58, v50
	v_sub_f32_e32 v61, v61, v53
	v_sub_f32_e32 v60, v60, v52
	v_sub_f32_e32 v63, v63, v55
	v_sub_f32_e32 v62, v62, v54
	v_fma_f32 v40, v40, v58, v50
	v_fma_f32 v41, v41, v59, v51
	v_fma_f32 v44, v44, v56, v48
	v_fma_f32 v45, v45, v57, v49
	v_fma_f32 v42, v42, v62, v54
	v_fma_f32 v43, v43, v63, v55
	v_fma_f32 v46, v46, v60, v52
	v_fma_f32 v47, v47, v61, v53
; #define GAS __attribute__((address_space(1)))
; __device__ __forceinline__ float fsigmoid(float x) { return frcp(1.f + fexp2(-x * LOG2E)); }
;     __device__ __forceinline__ void operator()(const Acc& acc, const Unit& u, int wr, int wc, int fr, int fq) const {
;     ...
;             for (int ai = 0; ai < 2; ++ai)
; #pragma unroll
;                 for (int m = 0; m < 4; ++m) {
;                     const size_t off = (size_t)(row0 + ai * HALF + m * 16) * D + colb + 128 * bj;
;                     f32x4 v0_ = acc[ai][bj][m][0] + b0, v1_ = acc[ai][bj][m][1] + b1;
; #pragma unroll
;                     for (int j = 0; j < 4; ++j) { v0_[j] = fsigmoid(v0_[j]) * osc; v1_[j] = fsigmoid(v1_[j]) * osc; }
;                     if (t4 == 2) {
;                         f32x4 x0, x1, f0, f1; unpack8(*(const GAS u32x4*)(V + off), x0, x1); unpack8(*(const GAS u32x4*)(VF + off), f0, f1);
;                         v0_ = x0 + (f0 - x0) * v0_; v1_ = x1 + (f1 - x1) * v1_;
;                     }
;                     *(GAS u32x4*)(dst + off) = pack8(v0_, v1_);
.LBB0_1150:
	v_add_f32_e32 v32, v32, v64
	v_add_f32_e32 v33, v33, v65
	v_add_f32_e32 v36, v36, v68
	v_add_f32_e32 v37, v37, v69
	v_mul_f32_e32 v32, 0xbfb8aa3b, v32
	v_exp_f32_e32 v32, v32
	v_mul_f32_e32 v37, 0xbfb8aa3b, v37
	v_exp_f32_e32 v37, v37
	v_mul_f32_e32 v33, 0xbfb8aa3b, v33
	v_exp_f32_e32 v33, v33
	v_add_f32_e32 v32, 1.0, v32
	v_cvt_pk_bf16_f32 v44, v44, v45
	v_cvt_pk_bf16_f32 v45, v40, v41
	v_add_f32_e32 v38, v38, v70
	v_add_f32_e32 v39, v39, v71
	v_rcp_f32_e32 v40, v32
	v_add_f32_e32 v32, 1.0, v37
	v_add_f32_e32 v34, v34, v66
	v_add_f32_e32 v35, v35, v67
	v_rcp_f32_e32 v37, v32
	v_add_f32_e32 v32, 1.0, v33
	v_mul_f32_e32 v33, 0xbfb8aa3b, v38
	v_exp_f32_e32 v33, v33
	v_mul_f32_e32 v34, 0xbfb8aa3b, v34
	v_exp_f32_e32 v38, v34
	v_rcp_f32_e32 v41, v32
	v_add_f32_e32 v32, 1.0, v33
	v_rcp_f32_e32 v34, v32
	v_add_f32_e32 v32, 1.0, v38
	v_cvt_pk_bf16_f32 v46, v46, v47
	v_cvt_pk_bf16_f32 v47, v42, v43
	v_mul_f32_e32 v36, 0xbfb8aa3b, v36
	v_mul_f32_e32 v33, 0xbfb8aa3b, v39
	v_rcp_f32_e32 v42, v32
	v_mul_f32_e32 v32, 0xbfb8aa3b, v35
	v_exp_f32_e32 v36, v36
	v_exp_f32_e32 v33, v33
	v_exp_f32_e32 v38, v32
	global_store_dwordx4 v[116:117], v[44:47], off offset:256
	v_add_f32_e32 v36, 1.0, v36
	v_add_f32_e32 v32, 1.0, v33
	v_add_f32_e32 v33, 1.0, v38
	v_rcp_f32_e32 v36, v36
	v_rcp_f32_e32 v35, v32
	v_rcp_f32_e32 v43, v33
	v_mov_b32_e32 v32, v148
	v_mov_b32_e32 v33, v148
	v_mul_f32_e32 v34, v32, v34
	v_mul_f32_e32 v35, v33, v35
	v_mul_f32_e32 v38, v148, v36
	v_mul_f32_e32 v39, v149, v37
	v_mul_f32_e32 v36, v32, v42
	v_mul_f32_e32 v37, v33, v43
	s_and_b64 vcc, exec, s[4:5]
	v_mul_f32_e32 v40, v148, v40
	v_mul_f32_e32 v41, v149, v41
	s_cbranch_vccnz .LBB0_1152
	v_lshl_add_u64 v[46:47], v[94:95], 0, v[112:113]
	v_lshl_add_u64 v[42:43], v[98:99], 1, s[8:9]
	v_lshl_add_u64 v[46:47], v[46:47], 1, s[18:19]
	global_load_dwordx4 v[42:45], v[42:43], off offset:256
	s_waitcnt vmcnt(0)
	v_lshlrev_b32_e32 v50, 16, v42
	global_load_dwordx4 v[46:49], v[46:47], off
	v_and_b32_e32 v51, 0xffff0000, v42
	v_lshlrev_b32_e32 v52, 16, v43
	v_and_b32_e32 v53, 0xffff0000, v43
	v_lshlrev_b32_e32 v54, 16, v44
	v_and_b32_e32 v55, 0xffff0000, v44
	v_lshlrev_b32_e32 v56, 16, v45
	v_and_b32_e32 v57, 0xffff0000, v45
	s_waitcnt vmcnt(0)
	v_lshlrev_b32_e32 v42, 16, v46
	v_and_b32_e32 v43, 0xffff0000, v46
	v_lshlrev_b32_e32 v44, 16, v47
	v_and_b32_e32 v45, 0xffff0000, v47
	v_lshlrev_b32_e32 v46, 16, v48
	v_and_b32_e32 v47, 0xffff0000, v48
	v_lshlrev_b32_e32 v48, 16, v49
	v_and_b32_e32 v49, 0xffff0000, v49
	v_sub_f32_e32 v51, v51, v43
	v_sub_f32_e32 v50, v50, v42
	v_sub_f32_e32 v53, v53, v45
	v_sub_f32_e32 v52, v52, v44
	v_sub_f32_e32 v55, v55, v47
	v_sub_f32_e32 v54, v54, v46
	v_sub_f32_e32 v57, v57, v49
	v_sub_f32_e32 v56, v56, v48
	v_fma_f32 v34, v34, v52, v44
	v_fma_f32 v35, v35, v53, v45
	v_fma_f32 v38, v38, v50, v42
	v_fma_f32 v39, v39, v51, v43
	v_fma_f32 v36, v36, v56, v48
	v_fma_f32 v37, v37, v57, v49
	v_fma_f32 v40, v40, v54, v46
	v_fma_f32 v41, v41, v55, v47
.LBB0_1152:
	v_add_f32_e32 v24, v24, v64
	v_add_f32_e32 v25, v25, v65
	v_add_f32_e32 v28, v28, v68
	v_add_f32_e32 v29, v29, v69
	v_mul_f32_e32 v24, 0xbfb8aa3b, v24
	v_exp_f32_e32 v24, v24
	v_mul_f32_e32 v29, 0xbfb8aa3b, v29
	v_exp_f32_e32 v29, v29
	v_cvt_pk_bf16_f32 v38, v38, v39
	v_add_f32_e32 v24, 1.0, v24
	v_cvt_pk_bf16_f32 v39, v34, v35
	v_add_f32_e32 v30, v30, v70
	v_add_f32_e32 v31, v31, v71
	v_add_f32_e32 v26, v26, v66
	v_add_f32_e32 v27, v27, v67
	v_rcp_f32_e32 v34, v24
	v_add_f32_e32 v24, 1.0, v29
	v_rcp_f32_e32 v29, v24
	v_mul_f32_e32 v24, 0xbfb8aa3b, v25
	v_mul_f32_e32 v25, 0xbfb8aa3b, v30
	v_mul_f32_e32 v26, 0xbfb8aa3b, v26
	v_exp_f32_e32 v24, v24
	v_exp_f32_e32 v25, v25
	v_exp_f32_e32 v26, v26
	v_mul_f32_e32 v28, 0xbfb8aa3b, v28
	v_add_f32_e32 v30, 1.0, v24
	v_add_f32_e32 v24, 1.0, v25
	v_add_f32_e32 v25, 1.0, v26
	v_mul_f32_e32 v26, 0xbfb8aa3b, v31
	v_exp_f32_e32 v31, v26
	v_mul_f32_e32 v26, 0xbfb8aa3b, v27
	v_exp_f32_e32 v28, v28
	v_exp_f32_e32 v27, v26
	v_rcp_f32_e32 v26, v25
	v_add_f32_e32 v25, 1.0, v31
	v_add_f32_e32 v28, 1.0, v28
	v_add_f32_e32 v27, 1.0, v27
	v_cvt_pk_bf16_f32 v40, v40, v41
	v_cvt_pk_bf16_f32 v41, v36, v37
	v_rcp_f32_e32 v28, v28
	v_rcp_f32_e32 v24, v24
	v_rcp_f32_e32 v25, v25
	v_rcp_f32_e32 v27, v27
	v_rcp_f32_e32 v35, v30
	global_store_dwordx4 v[100:101], v[38:41], off offset:256
	v_mul_f32_e32 v24, v32, v24
	v_mul_f32_e32 v25, v33, v25
	v_mul_f32_e32 v28, v148, v28
	v_mul_f32_e32 v29, v149, v29
	v_mul_f32_e32 v26, v32, v26
	v_mul_f32_e32 v27, v33, v27
	s_and_b64 vcc, exec, s[4:5]
	v_mul_f32_e32 v30, v148, v34
	v_mul_f32_e32 v31, v149, v35
	s_cbranch_vccnz .LBB0_1154
	v_lshl_add_u64 v[36:37], v[94:95], 0, v[96:97]
	v_lshl_add_u64 v[32:33], v[90:91], 1, s[8:9]
	v_lshl_add_u64 v[36:37], v[36:37], 1, s[18:19]
	global_load_dwordx4 v[32:35], v[32:33], off offset:256
	s_waitcnt vmcnt(0)
	v_lshlrev_b32_e32 v40, 16, v32
	global_load_dwordx4 v[36:39], v[36:37], off
	v_and_b32_e32 v41, 0xffff0000, v32
	v_lshlrev_b32_e32 v42, 16, v33
	v_and_b32_e32 v43, 0xffff0000, v33
	v_lshlrev_b32_e32 v44, 16, v34
	v_and_b32_e32 v45, 0xffff0000, v34
	v_lshlrev_b32_e32 v46, 16, v35
	v_and_b32_e32 v47, 0xffff0000, v35
	s_waitcnt vmcnt(0)
	v_lshlrev_b32_e32 v32, 16, v36
	v_and_b32_e32 v33, 0xffff0000, v36
	v_lshlrev_b32_e32 v34, 16, v37
	v_and_b32_e32 v35, 0xffff0000, v37
	v_lshlrev_b32_e32 v36, 16, v38
	v_and_b32_e32 v37, 0xffff0000, v38
	v_lshlrev_b32_e32 v38, 16, v39
	v_and_b32_e32 v39, 0xffff0000, v39
	v_sub_f32_e32 v41, v41, v33
	v_sub_f32_e32 v40, v40, v32
	v_sub_f32_e32 v43, v43, v35
	v_sub_f32_e32 v42, v42, v34
	v_sub_f32_e32 v45, v45, v37
	v_sub_f32_e32 v44, v44, v36
	v_sub_f32_e32 v47, v47, v39
	v_sub_f32_e32 v46, v46, v38
	v_fma_f32 v24, v24, v42, v34
	v_fma_f32 v25, v25, v43, v35
	v_fma_f32 v28, v28, v40, v32
	v_fma_f32 v29, v29, v41, v33
	v_fma_f32 v26, v26, v46, v38
	v_fma_f32 v27, v27, v47, v39
	v_fma_f32 v30, v30, v44, v36
	v_fma_f32 v31, v31, v45, v37
; #define GAS __attribute__((address_space(1)))
; __device__ __forceinline__ float fsigmoid(float x) { return frcp(1.f + fexp2(-x * LOG2E)); }
;     __device__ __forceinline__ void operator()(const Acc& acc, const Unit& u, int wr, int wc, int fr, int fq) const {
;     ...
;             for (int ai = 0; ai < 2; ++ai)
; #pragma unroll
;                 for (int m = 0; m < 4; ++m) {
;                     const size_t off = (size_t)(row0 + ai * HALF + m * 16) * D + colb + 128 * bj;
;                     f32x4 v0_ = acc[ai][bj][m][0] + b0, v1_ = acc[ai][bj][m][1] + b1;
; #pragma unroll
;                     for (int j = 0; j < 4; ++j) { v0_[j] = fsigmoid(v0_[j]) * osc; v1_[j] = fsigmoid(v1_[j]) * osc; }
;                     if (t4 == 2) {
;                         f32x4 x0, x1, f0, f1; unpack8(*(const GAS u32x4*)(V + off), x0, x1); unpack8(*(const GAS u32x4*)(VF + off), f0, f1);
;                         v0_ = x0 + (f0 - x0) * v0_; v1_ = x1 + (f1 - x1) * v1_;
;                     }
;                     *(GAS u32x4*)(dst + off) = pack8(v0_, v1_);
.LBB0_1154:
	v_add_f32_e32 v16, v16, v64
	v_add_f32_e32 v17, v17, v65
	v_add_f32_e32 v20, v20, v68
	v_add_f32_e32 v21, v21, v69
	v_mul_f32_e32 v16, 0xbfb8aa3b, v16
	v_exp_f32_e32 v16, v16
	v_mul_f32_e32 v21, 0xbfb8aa3b, v21
	v_exp_f32_e32 v21, v21
	v_mul_f32_e32 v17, 0xbfb8aa3b, v17
	v_exp_f32_e32 v17, v17
	v_add_f32_e32 v16, 1.0, v16
	v_cvt_pk_bf16_f32 v28, v28, v29
	v_cvt_pk_bf16_f32 v29, v24, v25
	v_add_f32_e32 v22, v22, v70
	v_add_f32_e32 v23, v23, v71
	v_rcp_f32_e32 v24, v16
	v_add_f32_e32 v16, 1.0, v21
	v_add_f32_e32 v18, v18, v66
	v_add_f32_e32 v19, v19, v67
	v_rcp_f32_e32 v21, v16
	v_add_f32_e32 v16, 1.0, v17
	v_mul_f32_e32 v17, 0xbfb8aa3b, v22
	v_exp_f32_e32 v17, v17
	v_mul_f32_e32 v18, 0xbfb8aa3b, v18
	v_exp_f32_e32 v22, v18
	v_rcp_f32_e32 v25, v16
	v_add_f32_e32 v16, 1.0, v17
	v_rcp_f32_e32 v18, v16
	v_add_f32_e32 v16, 1.0, v22
	v_cvt_pk_bf16_f32 v30, v30, v31
	v_cvt_pk_bf16_f32 v31, v26, v27
	v_mul_f32_e32 v20, 0xbfb8aa3b, v20
	v_mul_f32_e32 v17, 0xbfb8aa3b, v23
	v_rcp_f32_e32 v26, v16
	v_mul_f32_e32 v16, 0xbfb8aa3b, v19
	v_exp_f32_e32 v20, v20
	v_exp_f32_e32 v17, v17
	v_exp_f32_e32 v22, v16
	global_store_dwordx4 v[92:93], v[28:31], off offset:256
	v_add_f32_e32 v20, 1.0, v20
	v_add_f32_e32 v16, 1.0, v17
	v_add_f32_e32 v17, 1.0, v22
	v_rcp_f32_e32 v20, v20
	v_rcp_f32_e32 v19, v16
	v_rcp_f32_e32 v27, v17
	v_mov_b32_e32 v16, v148
	v_mov_b32_e32 v17, v148
	v_mul_f32_e32 v18, v16, v18
	v_mul_f32_e32 v19, v17, v19
	v_mul_f32_e32 v22, v148, v20
	v_mul_f32_e32 v23, v149, v21
	v_mul_f32_e32 v20, v16, v26
	v_mul_f32_e32 v21, v17, v27
	s_and_b64 vcc, exec, s[4:5]
	v_mul_f32_e32 v24, v148, v24
	v_mul_f32_e32 v25, v149, v25
	s_cbranch_vccnz .LBB0_1156
	v_lshl_add_u64 v[30:31], v[94:95], 0, v[88:89]
	v_lshl_add_u64 v[26:27], v[82:83], 1, s[8:9]
	v_lshl_add_u64 v[30:31], v[30:31], 1, s[18:19]
	global_load_dwordx4 v[26:29], v[26:27], off offset:256
	s_waitcnt vmcnt(0)
	v_lshlrev_b32_e32 v34, 16, v26
	global_load_dwordx4 v[30:33], v[30:31], off
	v_and_b32_e32 v35, 0xffff0000, v26
	v_lshlrev_b32_e32 v36, 16, v27
	v_and_b32_e32 v37, 0xffff0000, v27
	v_lshlrev_b32_e32 v38, 16, v28
	v_and_b32_e32 v39, 0xffff0000, v28
	v_lshlrev_b32_e32 v40, 16, v29
	v_and_b32_e32 v41, 0xffff0000, v29
	s_waitcnt vmcnt(0)
	v_lshlrev_b32_e32 v26, 16, v30
	v_and_b32_e32 v27, 0xffff0000, v30
	v_lshlrev_b32_e32 v28, 16, v31
	v_and_b32_e32 v29, 0xffff0000, v31
	v_lshlrev_b32_e32 v30, 16, v32
	v_and_b32_e32 v31, 0xffff0000, v32
	v_lshlrev_b32_e32 v32, 16, v33
	v_and_b32_e32 v33, 0xffff0000, v33
	v_sub_f32_e32 v35, v35, v27
	v_sub_f32_e32 v34, v34, v26
	v_sub_f32_e32 v37, v37, v29
	v_sub_f32_e32 v36, v36, v28
	v_sub_f32_e32 v39, v39, v31
	v_sub_f32_e32 v38, v38, v30
	v_sub_f32_e32 v41, v41, v33
	v_sub_f32_e32 v40, v40, v32
	v_fma_f32 v18, v18, v36, v28
	v_fma_f32 v19, v19, v37, v29
	v_fma_f32 v22, v22, v34, v26
	v_fma_f32 v23, v23, v35, v27
	v_fma_f32 v20, v20, v40, v32
	v_fma_f32 v21, v21, v41, v33
	v_fma_f32 v24, v24, v38, v30
	v_fma_f32 v25, v25, v39, v31
; #define GAS __attribute__((address_space(1)))
; __device__ __forceinline__ float fsigmoid(float x) { return frcp(1.f + fexp2(-x * LOG2E)); }
;     __device__ __forceinline__ void operator()(const Acc& acc, const Unit& u, int wr, int wc, int fr, int fq) const {
;     ...
;             for (int ai = 0; ai < 2; ++ai)
; #pragma unroll
;                 for (int m = 0; m < 4; ++m) {
;                     const size_t off = (size_t)(row0 + ai * HALF + m * 16) * D + colb + 128 * bj;
;                     f32x4 v0_ = acc[ai][bj][m][0] + b0, v1_ = acc[ai][bj][m][1] + b1;
; #pragma unroll
;                     for (int j = 0; j < 4; ++j) { v0_[j] = fsigmoid(v0_[j]) * osc; v1_[j] = fsigmoid(v1_[j]) * osc; }
;                     if (t4 == 2) {
;                         f32x4 x0, x1, f0, f1; unpack8(*(const GAS u32x4*)(V + off), x0, x1); unpack8(*(const GAS u32x4*)(VF + off), f0, f1);
;                         v0_ = x0 + (f0 - x0) * v0_; v1_ = x1 + (f1 - x1) * v1_;
;                     }
;                     *(GAS u32x4*)(dst + off) = pack8(v0_, v1_);
.LBB0_1156:
	v_add_f32_e32 v8, v8, v64
	v_add_f32_e32 v9, v9, v65
	v_add_f32_e32 v12, v12, v68
	v_add_f32_e32 v13, v13, v69
	v_mul_f32_e32 v8, 0xbfb8aa3b, v8
	v_exp_f32_e32 v8, v8
	v_mul_f32_e32 v13, 0xbfb8aa3b, v13
	v_exp_f32_e32 v13, v13
	v_cvt_pk_bf16_f32 v22, v22, v23
	v_add_f32_e32 v8, 1.0, v8
	v_cvt_pk_bf16_f32 v23, v18, v19
	v_add_f32_e32 v14, v14, v70
	v_add_f32_e32 v15, v15, v71
	v_add_f32_e32 v10, v10, v66
	v_add_f32_e32 v11, v11, v67
	v_rcp_f32_e32 v18, v8
	v_add_f32_e32 v8, 1.0, v13
	v_rcp_f32_e32 v13, v8
	v_mul_f32_e32 v8, 0xbfb8aa3b, v9
	v_mul_f32_e32 v9, 0xbfb8aa3b, v14
	v_mul_f32_e32 v10, 0xbfb8aa3b, v10
	v_exp_f32_e32 v8, v8
	v_exp_f32_e32 v9, v9
	v_exp_f32_e32 v10, v10
	v_mul_f32_e32 v12, 0xbfb8aa3b, v12
	v_add_f32_e32 v14, 1.0, v8
	v_add_f32_e32 v8, 1.0, v9
	v_add_f32_e32 v9, 1.0, v10
	v_mul_f32_e32 v10, 0xbfb8aa3b, v15
	v_exp_f32_e32 v15, v10
	v_mul_f32_e32 v10, 0xbfb8aa3b, v11
	v_exp_f32_e32 v12, v12
	v_exp_f32_e32 v11, v10
	v_rcp_f32_e32 v10, v9
	v_add_f32_e32 v9, 1.0, v15
	v_add_f32_e32 v12, 1.0, v12
	v_add_f32_e32 v11, 1.0, v11
	v_cvt_pk_bf16_f32 v24, v24, v25
	v_cvt_pk_bf16_f32 v25, v20, v21
	v_rcp_f32_e32 v12, v12
	v_rcp_f32_e32 v8, v8
	v_rcp_f32_e32 v9, v9
	v_rcp_f32_e32 v11, v11
	v_rcp_f32_e32 v19, v14
	global_store_dwordx4 v[84:85], v[22:25], off offset:256
	v_mul_f32_e32 v8, v16, v8
	v_mul_f32_e32 v9, v17, v9
	v_mul_f32_e32 v12, v148, v12
	v_mul_f32_e32 v13, v149, v13
	v_mul_f32_e32 v10, v16, v10
	v_mul_f32_e32 v11, v17, v11
	s_and_b64 vcc, exec, s[4:5]
	v_mul_f32_e32 v14, v148, v18
	v_mul_f32_e32 v15, v149, v19
	s_cbranch_vccnz .LBB0_1158
	v_lshl_add_u64 v[20:21], v[94:95], 0, v[80:81]
	v_lshl_add_u64 v[16:17], v[74:75], 1, s[8:9]
	v_lshl_add_u64 v[20:21], v[20:21], 1, s[18:19]
	global_load_dwordx4 v[16:19], v[16:17], off offset:256
	s_waitcnt vmcnt(0)
	v_lshlrev_b32_e32 v24, 16, v16
	global_load_dwordx4 v[20:23], v[20:21], off
	v_and_b32_e32 v25, 0xffff0000, v16
	v_lshlrev_b32_e32 v26, 16, v17
	v_and_b32_e32 v27, 0xffff0000, v17
	v_lshlrev_b32_e32 v28, 16, v18
	v_and_b32_e32 v29, 0xffff0000, v18
	v_lshlrev_b32_e32 v30, 16, v19
	v_and_b32_e32 v31, 0xffff0000, v19
	s_waitcnt vmcnt(0)
	v_lshlrev_b32_e32 v16, 16, v20
	v_and_b32_e32 v17, 0xffff0000, v20
	v_lshlrev_b32_e32 v18, 16, v21
	v_and_b32_e32 v19, 0xffff0000, v21
	v_lshlrev_b32_e32 v20, 16, v22
	v_and_b32_e32 v21, 0xffff0000, v22
	v_lshlrev_b32_e32 v22, 16, v23
	v_and_b32_e32 v23, 0xffff0000, v23
	v_sub_f32_e32 v25, v25, v17
	v_sub_f32_e32 v24, v24, v16
	v_sub_f32_e32 v27, v27, v19
	v_sub_f32_e32 v26, v26, v18
	v_sub_f32_e32 v29, v29, v21
	v_sub_f32_e32 v28, v28, v20
	v_sub_f32_e32 v31, v31, v23
	v_sub_f32_e32 v30, v30, v22
	v_fma_f32 v8, v8, v26, v18
	v_fma_f32 v9, v9, v27, v19
	v_fma_f32 v12, v12, v24, v16
	v_fma_f32 v13, v13, v25, v17
	v_fma_f32 v10, v10, v30, v22
	v_fma_f32 v11, v11, v31, v23
	v_fma_f32 v14, v14, v28, v20
	v_fma_f32 v15, v15, v29, v21
.LBB0_1158:
	v_add_f32_e32 v0, v0, v64
	v_add_f32_e32 v1, v1, v65
	v_add_f32_e32 v4, v4, v68
	v_add_f32_e32 v5, v5, v69
	v_mul_f32_e32 v0, 0xbfb8aa3b, v0
	v_exp_f32_e32 v0, v0
	v_mul_f32_e32 v5, 0xbfb8aa3b, v5
	v_exp_f32_e32 v5, v5
	v_mul_f32_e32 v1, 0xbfb8aa3b, v1
	v_exp_f32_e32 v1, v1
	v_add_f32_e32 v0, 1.0, v0
	v_cvt_pk_bf16_f32 v12, v12, v13
	v_cvt_pk_bf16_f32 v13, v8, v9
	v_add_f32_e32 v6, v6, v70
	v_add_f32_e32 v7, v7, v71
	v_add_f32_e32 v2, v2, v66
	v_add_f32_e32 v3, v3, v67
	v_rcp_f32_e32 v8, v0
	v_add_f32_e32 v0, 1.0, v5
	v_rcp_f32_e32 v5, v0
	v_add_f32_e32 v0, 1.0, v1
	v_mul_f32_e32 v1, 0xbfb8aa3b, v6
	v_mul_f32_e32 v2, 0xbfb8aa3b, v2
	v_exp_f32_e32 v1, v1
	v_exp_f32_e32 v2, v2
	v_rcp_f32_e32 v9, v0
	v_mul_f32_e32 v4, 0xbfb8aa3b, v4
	v_add_f32_e32 v0, 1.0, v1
	v_add_f32_e32 v1, 1.0, v2
	v_mul_f32_e32 v2, 0xbfb8aa3b, v7
	v_exp_f32_e32 v6, v2
	v_rcp_f32_e32 v2, v1
	v_mul_f32_e32 v1, 0xbfb8aa3b, v3
	v_exp_f32_e32 v4, v4
	v_exp_f32_e32 v3, v1
	v_add_f32_e32 v1, 1.0, v6
	v_cvt_pk_bf16_f32 v14, v14, v15
	v_add_f32_e32 v4, 1.0, v4
	v_add_f32_e32 v3, 1.0, v3
	v_cvt_pk_bf16_f32 v15, v10, v11
	v_rcp_f32_e32 v4, v4
	v_rcp_f32_e32 v0, v0
	v_rcp_f32_e32 v1, v1
	v_rcp_f32_e32 v3, v3
	global_store_dwordx4 v[78:79], v[12:15], off offset:256
	v_mov_b32_e32 v6, v148
	v_mov_b32_e32 v7, v148
	v_mul_f32_e32 v0, v6, v0
	v_mul_f32_e32 v1, v7, v1
	v_mul_f32_e32 v4, v148, v4
	v_mul_f32_e32 v5, v149, v5
	v_mul_f32_e32 v2, v6, v2
	v_mul_f32_e32 v3, v7, v3
	s_and_b64 vcc, exec, s[4:5]
	v_mul_f32_e32 v6, v148, v8
	v_mul_f32_e32 v7, v149, v9
	s_cbranch_vccnz .LBB0_1160
	v_lshl_add_u64 v[12:13], v[94:95], 0, v[72:73]
	v_lshl_add_u64 v[8:9], v[76:77], 1, s[8:9]
	v_lshl_add_u64 v[12:13], v[12:13], 1, s[18:19]
	global_load_dwordx4 v[8:11], v[8:9], off offset:256
	s_waitcnt vmcnt(0)
	v_lshlrev_b32_e32 v16, 16, v8
	global_load_dwordx4 v[12:15], v[12:13], off
	v_and_b32_e32 v17, 0xffff0000, v8
	v_lshlrev_b32_e32 v18, 16, v9
	v_and_b32_e32 v19, 0xffff0000, v9
	v_lshlrev_b32_e32 v20, 16, v10
	v_and_b32_e32 v21, 0xffff0000, v10
	v_lshlrev_b32_e32 v22, 16, v11
	v_and_b32_e32 v23, 0xffff0000, v11
	s_waitcnt vmcnt(0)
	v_lshlrev_b32_e32 v8, 16, v12
	v_and_b32_e32 v9, 0xffff0000, v12
	v_lshlrev_b32_e32 v10, 16, v13
	v_and_b32_e32 v11, 0xffff0000, v13
	v_lshlrev_b32_e32 v12, 16, v14
	v_and_b32_e32 v13, 0xffff0000, v14
	v_lshlrev_b32_e32 v14, 16, v15
	v_and_b32_e32 v15, 0xffff0000, v15
	v_sub_f32_e32 v17, v17, v9
	v_sub_f32_e32 v16, v16, v8
	v_sub_f32_e32 v19, v19, v11
	v_sub_f32_e32 v18, v18, v10
	v_sub_f32_e32 v21, v21, v13
	v_sub_f32_e32 v20, v20, v12
	v_sub_f32_e32 v23, v23, v15
	v_sub_f32_e32 v22, v22, v14
	v_fma_f32 v0, v0, v18, v10
	v_fma_f32 v1, v1, v19, v11
	v_fma_f32 v4, v4, v16, v8
	v_fma_f32 v5, v5, v17, v9
	v_fma_f32 v2, v2, v22, v14
	v_fma_f32 v3, v3, v23, v15
	v_fma_f32 v6, v6, v20, v12
	v_fma_f32 v7, v7, v21, v13

; __device__ __forceinline__ void scan_phase2(LAS unsigned char* lds, const int wid, const bf16_t* R, const bf16_t* K, const bf16_t* V, const bf16_t* W, const bf16_t* A,
;                                             const float* k_k, const float* k_a, const float* r_k, bf16_t* Y, float* BON) {
;     ...
;                     const int c = it - 2;
;                     const LAS unsigned char* Pb = lds + L_P + (c % 3) * P_SIZE;
;                     const LAS unsigned char* Qb = lds + L_Q + (c & 1) * Q_SIZE;
;                     bf16x8 sa[2];
; #pragma unroll
;                     for (int ks = 0; ks < 2; ++ks) sa[ks] = *(const LAS bf16x8*)(S16 + (l15 * 72 + 32 * ks + 8 * q) * 2);
;                     const s16x4 va = *(const LAS s16x4*)(Pb + P_VT + ((16 * wid + l15) * 20 + 4 * q) * 2);
;                     f32x4 X = {0.f, 0.f, 0.f, 0.f}, Yc = X;
; #pragma unroll
;                     for (int ks = 0; ks < 2; ++ks) {
;                         X = mfma32(sa[ks], *(const LAS bf16x8*)(Pb + P_AR + (l15 * 72 + 32 * ks + 8 * q) * 2), X);
;                         Yc = mfma32(sa[ks], *(const LAS bf16x8*)(Pb + P_AR + ((16 + l15) * 72 + 32 * ks + 8 * q) * 2), Yc);
;                     }
;                     X = mfma16(va, *(const LAS s16x4*)(Qb + Q_MKB + (l15 * 16 + 4 * q) * 2), X);
;                     Yc = mfma16(va, *(const LAS s16x4*)(Qb + Q_NKR + (l15 * 16 + 4 * q) * 2), Yc);
;                     MF_SETTLE(X);
; #pragma unroll
;                     for (int i = 0; i < 4; ++i) *(LAS bf16_t*)(XU + ((4 * q + i) * 20 + l15) * 2) = f2bf(X[i]);
;                     LDS_WAIT(); asm volatile("" ::: "memory");
;                     const s16x4 xa = *(const LAS s16x4*)(XU + (l15 * 20 + 4 * q) * 2);
;                     f32x4 U = mfma16(xa, *(const LAS s16x4*)(Qb + Q_TT + (l15 * 16 + 4 * q) * 2), (f32x4){0.f, 0.f, 0.f, 0.f});
;                     LDS_WAIT(); asm volatile("" ::: "memory");
;                     MF_SETTLE(U);
; #pragma unroll
;                     for (int i = 0; i < 4; ++i) *(LAS bf16_t*)(XU + ((4 * q + i) * 20 + l15) * 2) = f2bf(U[i]);
;                     LDS_WAIT(); asm volatile("" ::: "memory");
;                     const s16x4 ua = *(const LAS s16x4*)(XU + (l15 * 20 + 4 * q) * 2);
;                     Yc = mfma16(ua, *(const LAS s16x4*)(Qb + Q_NBR + (l15 * 16 + 4 * q) * 2), Yc);
;                     MF_SETTLE(Yc);
.LBB0_1231:
	s_add_i32 s0, s30, 2
	s_cmp_lt_u32 s0, 2
	s_cbranch_scc1 .LBB0_1230
	s_and_b32 s0, s30, 0xff
	s_mulk_i32 s0, 0xab
	s_lshr_b32 s0, s0, 9
	s_mul_i32 s0, s0, 3
	s_sub_i32 s0, s30, s0
	s_and_b32 s0, s0, 0xff
	s_mulk_i32 s0, 0x3e00
	s_add_i32 s0, s0, 0
	v_add_u32_e32 v24, s0, v83
	ds_read_b128 v[48:51], v118 offset:52736
	ds_read_b128 v[52:55], v118 offset:52800
	ds_read_b128 v[56:59], v24 offset:4608
	v_add_u32_e32 v45, s0, v72
	ds_read_b64 v[146:147], v45 offset:14336
	ds_read_b128 v[60:63], v24 offset:4672
	s_and_b32 s1, s54, 0x800
	s_waitcnt lgkmcnt(2)
	v_mfma_f32_16x16x32_bf16 v[56:59], v[48:51], v[56:59], 0
	v_add_u32_e32 v45, s1, v113
	ds_read2st64_b64 v[64:67], v45 offset0:93 offset1:95
	s_lshl_b64 s[56:57], s[30:31], 15
	s_waitcnt lgkmcnt(1)
	v_mfma_f32_16x16x32_bf16 v[56:59], v[52:55], v[60:63], v[56:59]
	ds_read_b128 v[60:63], v24 offset:6912
	ds_read_b128 v[142:145], v24 offset:6976
	v_add_u32_e32 v24, s66, v84
	s_waitcnt lgkmcnt(2)
	v_mfma_f32_16x16x16_bf16 v[56:59], v[146:147], v[64:65], v[56:59]
	s_waitcnt lgkmcnt(1)
	v_mfma_f32_16x16x32_bf16 v[48:51], v[48:51], v[60:63], 0
	v_add_u32_e32 v60, s0, v89
	s_nop 4
	v_cvt_pk_bf16_f32 v56, v56, s0
	v_cvt_pk_bf16_f32 v57, v57, s0
	ds_write_b16 v119, v56 offset:57344
	ds_write_b16 v24, v57 offset:57344
	v_cvt_pk_bf16_f32 v56, v58, s0
	ds_write_b16 v120, v56 offset:57344
	v_cvt_pk_bf16_f32 v56, v59, s0
	ds_write_b16 v121, v56 offset:57344
	s_waitcnt lgkmcnt(0)
	ds_read_b64 v[56:57], v122 offset:57344
	s_waitcnt lgkmcnt(5)
	v_mfma_f32_16x16x32_bf16 v[48:51], v[52:55], v[142:145], v[48:51]
	ds_read_b64 v[52:53], v45 offset:49152
	s_waitcnt lgkmcnt(0)
	s_waitcnt lgkmcnt(0)
	v_mfma_f32_16x16x16_bf16 v[52:55], v[56:57], v[52:53], 0
	v_mfma_f32_16x16x16_bf16 v[48:51], v[146:147], v[66:67], v[48:51]
	s_nop 6
	v_cvt_pk_bf16_f32 v52, v52, s0
	v_cvt_pk_bf16_f32 v53, v53, s0
	ds_write_b16 v119, v52 offset:57344
	ds_write_b16 v24, v53 offset:57344
	v_cvt_pk_bf16_f32 v24, v54, s0
	ds_write_b16 v120, v24 offset:57344
	v_cvt_pk_bf16_f32 v24, v55, s0
	ds_write_b16 v121, v24 offset:57344
	s_waitcnt lgkmcnt(0)
	ds_read_b64 v[52:53], v122 offset:57344
	v_add_u32_e32 v24, s0, v69
	v_add_u32_e32 v54, s0, v85
	ds_read_b32 v24, v24 offset:15616
	ds_read_b64 v[54:55], v54 offset:9216
	ds_read_b64 v[56:57], v45 offset:48128
	s_waitcnt lgkmcnt(0)
	v_mfma_f32_16x16x16_bf16 v[48:51], v[52:53], v[56:57], v[48:51]
	v_add_u32_e32 v45, s0, v86
	v_add_u32_e32 v57, s0, v88
	s_nop 5
	v_cvt_pk_bf16_f32 v48, v48, v49
	v_mfma_f32_16x16x16_bf16 v[8:11], v[52:53], v[54:55], v[8:11]
	ds_read_b64 v[54:55], v45 offset:9216
	v_add_u32_e32 v45, s0, v87
	v_cvt_pk_bf16_f32 v49, v50, v51
	v_lshl_add_u64 v[50:51], v[46:47], 0, s[56:57]
	ds_read_b32 v56, v45 offset:15616
	ds_read_b64 v[58:59], v57 offset:9216
	ds_read_b64 v[60:61], v60 offset:9216
	global_store_dwordx2 v[50:51], v[48:49], off
	v_add_u32_e32 v48, s0, v91
	ds_read_b64 v[48:49], v48 offset:9216
	s_waitcnt lgkmcnt(4)
	v_mfma_f32_16x16x16_bf16 v[8:11], v[146:147], v[54:55], v[8:11]
	v_add_u32_e32 v45, s0, v90
	v_add_u32_e32 v51, s0, v92
	v_add_u32_e32 v57, s0, v93
	s_waitcnt lgkmcnt(2)
	v_mfma_f32_16x16x16_bf16 v[12:15], v[52:53], v[58:59], v[12:15]
	ds_read_b32 v50, v45 offset:15616
	ds_read_b64 v[54:55], v51 offset:9216
	ds_read_b32 v58, v57 offset:15616
	v_mul_f32_e32 v10, v24, v10
	v_mul_f32_e32 v11, v24, v11
	v_mul_f32_e32 v8, v24, v8
	v_mul_f32_e32 v9, v24, v9
	s_waitcnt lgkmcnt(3)
	v_mfma_f32_16x16x16_bf16 v[4:7], v[52:53], v[48:49], v[4:7]
	v_add_u32_e32 v24, s0, v94
	ds_read_b64 v[48:49], v24 offset:9216
	v_add_u32_e32 v24, s0, v95
	v_mfma_f32_16x16x16_bf16 v[12:15], v[146:147], v[60:61], v[12:15]
	s_waitcnt lgkmcnt(2)
	v_mfma_f32_16x16x16_bf16 v[4:7], v[146:147], v[54:55], v[4:7]
	ds_read_b64 v[54:55], v24 offset:9216
	v_cvt_pk_bf16_f32 v24, v8, s0
	ds_write_b16 v123, v24 offset:52736
	v_cvt_pk_bf16_f32 v24, v9, s0
	ds_write_b16 v124, v24 offset:52736
	v_cvt_pk_bf16_f32 v24, v10, s0
	s_waitcnt lgkmcnt(3)
	v_mfma_f32_16x16x16_bf16 v[0:3], v[52:53], v[48:49], v[0:3]
	v_mul_f32_e64 v12, v56, v12
	v_mul_f32_e64 v13, v56, v13
	ds_write_b16 v125, v24 offset:52736
	v_cvt_pk_bf16_f32 v24, v11, s0
	ds_write_b16 v126, v24 offset:52736
	v_cvt_pk_bf16_f32 v24, v12, s0
	v_mul_f32_e32 v14, v56, v14
	v_mul_f32_e32 v15, v56, v15
	ds_write_b16 v127, v24 offset:52736
	v_cvt_pk_bf16_f32 v24, v13, s0
	ds_write_b16 v128, v24 offset:52736
	v_cvt_pk_bf16_f32 v24, v14, s0
	v_mul_f32_e32 v4, v50, v4
	v_mul_f32_e32 v5, v50, v5
	s_waitcnt lgkmcnt(6)
	v_mfma_f32_16x16x16_bf16 v[0:3], v[146:147], v[54:55], v[0:3]
	ds_write_b16 v129, v24 offset:52736
	v_cvt_pk_bf16_f32 v24, v15, s0
	ds_write_b16 v130, v24 offset:52736
	v_cvt_pk_bf16_f32 v24, v4, s0
	v_mul_f32_e32 v6, v50, v6
	v_mul_f32_e32 v7, v50, v7
	ds_write_b16 v131, v24 offset:52736
	v_cvt_pk_bf16_f32 v24, v5, s0
	ds_write_b16 v132, v24 offset:52736
	v_cvt_pk_bf16_f32 v24, v6, s0
	v_mul_f32_e32 v0, v58, v0
	v_mul_f32_e32 v1, v58, v1
	ds_write_b16 v133, v24 offset:52736
	v_cvt_pk_bf16_f32 v24, v7, s0
	ds_write_b16 v134, v24 offset:52736
	v_cvt_pk_bf16_f32 v24, v0, s0
	v_mul_f32_e32 v2, v58, v2
	v_mul_f32_e32 v3, v58, v3
	ds_write_b16 v135, v24 offset:52736
	v_cvt_pk_bf16_f32 v24, v1, s0
	ds_write_b16 v136, v24 offset:52736
	v_cvt_pk_bf16_f32 v24, v2, s0
	ds_write_b16 v137, v24 offset:52736
	v_cvt_pk_bf16_f32 v24, v3, s0
	ds_write_b16 v138, v24 offset:52736
	s_waitcnt lgkmcnt(0)
	s_branch .LBB0_1230

; #define LAS __attribute__((address_space(3)))
; __device__ __forceinline__ float fexp2(float x) { return __builtin_amdgcn_exp2f(x); }
; __device__ __forceinline__ void scan_phase2(LAS unsigned char* lds, const int wid, const bf16_t* R, const bf16_t* K, const bf16_t* V, const bf16_t* W, const bf16_t* A,
;                                             const float* k_k, const float* k_a, const float* r_k, bf16_t* Y, float* BON) {
;     ...
;                     const f32x4 kx = unpack4(kr), ax = unpack4(ar), rx = unpack4(rr);
;                     f32x4 kk = kx * kkp;
;                     float ss = (kk[0] * kk[0] + kk[1] * kk[1]) + (kk[2] * kk[2] + kk[3] * kk[3]);
;                     ss = reduce16(ss);
;                     kk = kk * (1.f / fmaxf(sqrtf(ss), 1e-12f));
;                     const f32x4 km = kx * (1.f + (ax - 1.f) * kap);
;                     const f32x4 rkm = rx * km * rkp;
;                     float bs = (rkm[0] + rkm[1]) + (rkm[2] + rkm[3]);
;                     bs = reduce16(bs);
;                     if (half == 0 && kq == 0) BON[(tokb + (size_t)it * CL + s) * 16 + h] = bs;
;                     const f32x4 cum = *(const LAS f32x4*)(lds + L_CE + (it & 1) * 4096 + (s * 64 + kq * 4) * 4);
;                     const f32x4 ews = unpack4(wr_);
;                     f32x4 e1, e2, ed;
; #pragma unroll
;                     for (int i = 0; i < 4; ++i) { e1[i] = fexp2(cum[i] * LOG2E); e2[i] = frcp(e1[i]); ed[i] = fexp2(ews[i] * LOG2E); }
;                     const f32x4 av = -kk, bv = kk * ax;
;                     const f32x4 bbar = bv * e1, kbar = km * e1, abar = av * (e2 * ed), rbar = rx * e2;
;                     *(LAS u32x2*)(Pb + P_BK + (s * 72 + kq * 4) * 2) = pack4(bbar);
;                     *(LAS u32x2*)(Pb + P_BK + ((16 + s) * 72 + kq * 4) * 2) = pack4(kbar);
;                     *(LAS u32x2*)(Pb + P_AR + (s * 72 + kq * 4) * 2) = pack4(abar);
;                     *(LAS u32x2*)(Pb + P_AR + ((16 + s) * 72 + kq * 4) * 2) = pack4(rbar);
; #pragma unroll
;                     for (int i = 0; i < 4; ++i) {
;                         *(LAS bf16_t*)(Pb + P_BKT + ((kq * 4 + i) * 40 + s) * 2) = f2bf(bbar[i]);
;                         *(LAS bf16_t*)(Pb + P_BKT + ((kq * 4 + i) * 40 + 16 + s) * 2) = f2bf(kbar[i]);
;                     }
;                     if (s == 15) *(LAS f32x4*)(Pb + P_LAM + kq * 16) = e2;
.LBB0_1257:
	s_cmpk_gt_u32 s89, 0xff
	s_cbranch_scc1 .LBB0_1263
	s_waitcnt vmcnt(2)
	v_lshlrev_b32_e32 v66, 16, v50
	v_and_b32_e32 v67, 0xffff0000, v50
	v_lshlrev_b32_e32 v64, 16, v51
	v_and_b32_e32 v65, 0xffff0000, v51
	v_mul_f32_e32 v12, v2, v64
	v_mul_f32_e32 v13, v3, v65
	v_mul_f32_e32 v14, v0, v66
	v_mul_f32_e32 v15, v1, v67
	v_mul_f32_e32 v142, v12, v12
	v_mul_f32_e32 v143, v13, v13
	v_mul_f32_e32 v144, v14, v14
	v_mul_f32_e32 v145, v15, v15
	s_waitcnt vmcnt(1)
	v_lshlrev_b32_e32 v60, 16, v52
	v_pk_mov_b32 v[146:147], v[144:145], v[142:143] op_sel:[1,0]
	v_mov_b32_e32 v145, v143
	v_and_b32_e32 v61, 0xffff0000, v52
	v_lshlrev_b32_e32 v62, 16, v53
	v_and_b32_e32 v63, 0xffff0000, v53
	v_add_f32_e32 v142, v146, v144
	v_add_f32_e32 v143, v147, v145
	v_add_f32_e32 v144, -1.0, v60
	v_add_f32_e32 v145, -1.0, v61
	v_add_f32_e32 v24, v142, v143
	v_add_f32_e32 v142, -1.0, v62
	v_add_f32_e32 v143, -1.0, v63
	v_fma_f32 v144, v4, v144, 1.0
	v_fma_f32 v145, v5, v145, 1.0
	v_fma_f32 v142, v6, v142, 1.0
	v_fma_f32 v143, v7, v143, 1.0
	v_lshlrev_b32_e32 v56, 16, v48
	v_and_b32_e32 v57, 0xffff0000, v48
	v_lshlrev_b32_e32 v58, 16, v49
	v_and_b32_e32 v59, 0xffff0000, v49
	v_mul_f32_e32 v64, v142, v64
	v_mul_f32_e32 v65, v143, v65
	v_mul_f32_e32 v66, v144, v66
	v_mul_f32_e32 v67, v145, v67
	v_mul_f32_e32 v144, v64, v58
	v_mul_f32_e32 v145, v65, v59
	v_mul_f32_e32 v142, v66, v56
	v_mul_f32_e32 v143, v67, v57
	v_mul_f32_e32 v144, v10, v144
	v_mul_f32_e32 v145, v11, v145
	v_mul_f32_e32 v142, v8, v142
	v_mul_f32_e32 v143, v9, v143
	v_add_f32_e32 v141, v144, v145
	v_add_f32_e32 v45, v142, v143
	v_add_f32_e32 v141, v45, v141
	v_add_f32_dpp v24, v24, v24 quad_perm:[1,0,3,2] row_mask:0xf bank_mask:0xf bound_ctrl:1
	s_nop 0
	v_add_f32_dpp v141, v141, v141 quad_perm:[1,0,3,2] row_mask:0xf bank_mask:0xf bound_ctrl:1
	v_add_f32_dpp v24, v24, v24 quad_perm:[2,3,0,1] row_mask:0xf bank_mask:0xf bound_ctrl:1
	s_nop 0
	v_add_f32_dpp v141, v141, v141 quad_perm:[2,3,0,1] row_mask:0xf bank_mask:0xf bound_ctrl:1
	v_add_f32_dpp v24, v24, v24 row_half_mirror row_mask:0xf bank_mask:0xf bound_ctrl:1
	s_nop 0
	v_add_f32_dpp v141, v141, v141 row_half_mirror row_mask:0xf bank_mask:0xf bound_ctrl:1
	v_mov_b32_dpp v45, v24 row_mirror row_mask:0xf bank_mask:0xf bound_ctrl:1
	s_nop 0
	v_mov_b32_dpp v142, v141 row_mirror row_mask:0xf bank_mask:0xf bound_ctrl:1
	s_and_saveexec_b64 s[24:25], s[20:21]
	s_cbranch_execz .LBB0_1260
	v_add_f32_e32 v141, v141, v142
	flat_store_dword v[46:47], v141
.LBB0_1260:
	s_or_b64 exec, exec, s[24:25]
	v_add_f32_e32 v24, v24, v45
	v_mul_f32_e32 v45, 0x4f800000, v24
	v_cmp_gt_f32_e32 vcc, s83, v24
	s_mul_i32 s0, s89, 0xab
	s_bfe_u32 s0, s0, 0x70009
	v_cndmask_b32_e32 v24, v24, v45, vcc
	v_sqrt_f32_e32 v45, v24
	s_mul_i32 s0, s0, 3
	s_sub_i32 s0, s89, s0
	s_and_b32 s0, s0, 0xff
	v_add_u32_e32 v142, -1, v45
	v_fma_f32 v143, -v142, v45, v24
	v_cmp_ge_f32_e64 s[24:25], 0, v143
	v_add_u32_e32 v143, 1, v45
	s_mulk_i32 s0, 0x3e00
	v_cndmask_b32_e64 v142, v45, v142, s[24:25]
	v_fma_f32 v45, -v143, v45, v24
	v_cmp_lt_f32_e64 s[24:25], 0, v45
	s_add_i32 s90, s0, 0
	s_and_b32 s0, s30, 0x1000
	v_cndmask_b32_e64 v45, v142, v143, s[24:25]
	v_mul_f32_e32 v142, 0x37800000, v45
	v_cndmask_b32_e32 v45, v45, v142, vcc
	v_cmp_class_f32_e32 vcc, v24, v140
	s_waitcnt vmcnt(0)
	v_and_b32_e32 v151, 0xffff0000, v54
	v_lshlrev_b32_e32 v141, 16, v54
	v_cndmask_b32_e32 v24, v45, v24, vcc
	v_max_f32_e32 v24, 0x2b8cbccc, v24
	v_div_scale_f32 v45, s[24:25], v24, v24, 1.0
	v_rcp_f32_e32 v146, v45
	v_lshlrev_b32_e32 v152, 16, v55
	v_and_b32_e32 v153, 0xffff0000, v55
	v_fma_f32 v142, -v45, v146, 1.0
	v_fmac_f32_e32 v146, v142, v146
	v_div_scale_f32 v142, vcc, 1.0, v24, 1.0
	v_mul_f32_e32 v147, v142, v146
	v_fma_f32 v143, -v45, v147, v142
	v_fmac_f32_e32 v147, v143, v146
	v_fma_f32 v45, -v45, v147, v142
	v_add_u32_e32 v142, s0, v23
	ds_read_b128 v[142:145], v142 offset:58624
	v_div_fmas_f32 v45, v45, v146, v147
	v_div_fixup_f32 v24, v45, v24, 1.0
	v_mul_f32_e32 v146, v12, v24
	v_mul_f32_e32 v147, v13, v24
	v_mul_f32_e32 v148, v14, v24
	v_mul_f32_e32 v149, v15, v24
	s_waitcnt lgkmcnt(0)
	v_mul_f32_e32 v12, 0x3fb8aa3b, v142
	v_mul_f32_e32 v14, 0x3fb8aa3b, v151
	v_exp_f32_e32 v142, v12
	v_mul_f32_e32 v12, 0x3fb8aa3b, v143
	v_mul_f32_e32 v15, 0x3fb8aa3b, v144
	v_exp_f32_e32 v151, v14
	v_mul_f32_e32 v14, 0x3fb8aa3b, v145
	v_exp_f32_e32 v143, v12
	v_exp_f32_e32 v144, v15
	v_exp_f32_e32 v145, v14
	v_mul_f32_e32 v13, 0x3fb8aa3b, v141
	v_mul_f32_e32 v15, 0x3fb8aa3b, v152
	v_mul_f32_e32 v24, 0x3fb8aa3b, v153
	v_rcp_f32_e32 v12, v142
	v_exp_f32_e32 v150, v13
	v_rcp_f32_e32 v13, v143
	v_rcp_f32_e32 v14, v144
	v_exp_f32_e32 v152, v15
	v_rcp_f32_e32 v15, v145
	v_exp_f32_e32 v153, v24
	v_mul_f32_e32 v60, v148, v60
	v_mul_f32_e32 v61, v149, v61
	v_mul_f32_e32 v62, v146, v62
	v_mul_f32_e32 v63, v147, v63
	v_mul_f32_e32 v60, v60, v142
	v_mul_f32_e32 v61, v61, v143
	v_mul_f32_e32 v62, v62, v144
	v_mul_f32_e32 v63, v63, v145
	v_mul_f32_e32 v64, v64, v144
	v_mul_f32_e32 v65, v65, v145
	v_mul_f32_e32 v66, v66, v142
	v_mul_f32_e32 v67, v67, v143
	v_mul_f32_e32 v142, v150, v12
	v_mul_f32_e32 v143, v151, v13
	v_mul_f32_e32 v144, v152, v14
	v_mul_f32_e32 v145, v153, v15
	v_mul_f32_e64 v142, v142, -v148
	v_mul_f32_e64 v143, v143, -v149
	v_mul_f32_e64 v144, v144, -v146
	v_mul_f32_e64 v145, v145, -v147
	v_mul_f32_e32 v58, v14, v58
	v_mul_f32_e32 v59, v15, v59
	v_mul_f32_e32 v56, v12, v56
	v_mul_f32_e32 v57, v13, v57
	v_cvt_pk_bf16_f32 v146, v60, v61
	v_cvt_pk_bf16_f32 v147, v62, v63
	v_add_u32_e32 v24, s90, v70
	ds_write_b64 v24, v[146:147]
	v_cvt_pk_bf16_f32 v146, v66, v67
	v_cvt_pk_bf16_f32 v147, v64, v65
	v_add_u32_e32 v45, s90, v71
	v_cvt_pk_bf16_f32 v142, v142, v143
	v_cvt_pk_bf16_f32 v143, v144, v145
	v_cvt_pk_bf16_f32 v56, v56, v57
	v_cvt_pk_bf16_f32 v57, v58, v59
	ds_write_b64 v45, v[146:147]
	ds_write_b64 v24, v[142:143] offset:4608
	ds_write_b64 v45, v[56:57] offset:4608
	v_cvt_pk_bf16_f32 v24, v60, s0
	v_add_u32_e32 v45, s90, v75
	ds_write_b16 v45, v24 offset:9216
	v_cvt_pk_bf16_f32 v24, v66, s0
	v_add_u32_e32 v45, s90, v76
	ds_write_b16 v45, v24 offset:9216
	v_cvt_pk_bf16_f32 v24, v61, s0
	v_add_u32_e32 v45, s90, v77
	ds_write_b16 v45, v24 offset:9216
	v_cvt_pk_bf16_f32 v24, v67, s0
	v_add_u32_e32 v45, s90, v78
	ds_write_b16 v45, v24 offset:9216
	v_cvt_pk_bf16_f32 v24, v62, s0
	v_add_u32_e32 v45, s90, v79
	ds_write_b16 v45, v24 offset:9216
	v_cvt_pk_bf16_f32 v24, v64, s0
	v_add_u32_e32 v45, s90, v80
	ds_write_b16 v45, v24 offset:9216
	v_cvt_pk_bf16_f32 v24, v63, s0
	v_add_u32_e32 v45, s90, v81
	ds_write_b16 v45, v24 offset:9216
	v_cvt_pk_bf16_f32 v24, v65, s0
	v_add_u32_e32 v45, s90, v82
	ds_write_b16 v45, v24 offset:9216
	s_and_saveexec_b64 s[24:25], s[2:3]
	v_add_u32_e32 v24, s90, v22
	ds_write_b128 v24, v[12:15] offset:15616
	s_or_b64 exec, exec, s[24:25]

; #define GAS __attribute__((address_space(1)))
;     __device__ __forceinline__ void operator()(const Acc& acc, const Unit& u, int wr, int wc, int fr, int fq) const {
;     ...
;         const int row0 = u.pm * BM + wr * 64 + fr;
;         const int colb = head * 64 + 8 * fq;
; #pragma unroll
;         for (int ai = 0; ai < 2; ++ai)
; #pragma unroll
;             for (int m = 0; m < 4; ++m) {
;                 const int row = row0 + ai * HALF + m * 16;
;                 const size_t off = (size_t)row * D + colb;
;                 f32x4 y[2][2], v[2][2];
; #pragma unroll
;                 for (int bj = 0; bj < 2; ++bj) { unpack8(*(const GAS u32x4*)(Y + off + 32 * bj), y[bj][0], y[bj][1]); unpack8(*(const GAS u32x4*)(V + off + 32 * bj), v[bj][0], v[bj][1]); }
;                 const float bs = BON[(size_t)row * 16 + head];
;                 float s = 0.f;
; #pragma unroll
;                 for (int bj = 0; bj < 2; ++bj)
; #pragma unroll
;                     for (int n = 0; n < 2; ++n) s += (y[bj][n][0] + y[bj][n][1]) + (y[bj][n][2] + y[bj][n][3]);
;                 s += __shfl_xor(s, 16); s += __shfl_xor(s, 32);
;                 const float mean = s * (1.f / 64.f);
;                 float q = 0.f;
; #pragma unroll
;                 for (int bj = 0; bj < 2; ++bj)
; #pragma unroll
;                     for (int n = 0; n < 2; ++n) { y[bj][n] = y[bj][n] - mean; q += (y[bj][n][0] * y[bj][n][0] + y[bj][n][1] * y[bj][n][1]) + (y[bj][n][2] * y[bj][n][2] + y[bj][n][3] * y[bj][n][3]); }
;                 q += __shfl_xor(q, 16); q += __shfl_xor(q, 32);
;                 const float rs = rsqrtf(q * (1.f / 64.f) + 64e-5f);
.LBB0_1331:
	s_lshl_b32 s0, s35, 2
	v_mov_b32_e32 v140, v153
	s_or_b32 s38, s0, s70
	s_lshl_b32 s0, s34, 8
	s_add_i32 s0, s0, s71
	v_and_or_b32 v146, v140, 15, s0
	v_ashrrev_i32_e32 v140, 1, v140
	v_and_b32_e32 v140, -8, v140
	v_lshl_add_u32 v144, s38, 6, v140
	v_ashrrev_i32_e32 v147, 31, v146
	v_ashrrev_i32_e32 v145, 31, v144
	v_lshlrev_b64 v[140:141], 10, v[146:147]
	v_lshl_add_u64 v[140:141], v[140:141], 0, v[144:145]
	v_lshlrev_b64 v[148:149], 1, v[140:141]
	v_lshl_add_u64 v[140:141], s[16:17], 0, v[148:149]
	global_load_dwordx4 v[162:165], v[140:141], off offset:64
	global_load_dwordx4 v[166:169], v[140:141], off
	v_lshlrev_b64 v[140:141], 6, v[146:147]
	s_ashr_i32 s39, s38, 31
	v_lshlrev_b64 v[142:143], 2, v[144:145]
	s_lshl_b64 s[34:35], s[38:39], 2
	v_lshl_add_u64 v[150:151], s[18:19], 0, v[140:141]
	v_lshl_add_u64 v[140:141], s[8:9], 0, v[142:143]
	v_lshl_add_u64 v[182:183], s[6:7], 0, v[148:149]
	v_lshl_add_u64 v[142:143], s[10:11], 0, v[142:143]
	global_load_dwordx4 v[170:173], v[182:183], off
	v_lshl_add_u64 v[150:151], v[150:151], 0, s[34:35]
	s_waitcnt vmcnt(0)
	v_lshlrev_b32_e32 v186, 16, v162
	v_lshlrev_b32_e32 v199, 16, v167
	v_lshlrev_b32_e32 v198, 16, v166
	v_and_b32_e32 v185, 0xffff0000, v167
	v_and_b32_e32 v184, 0xffff0000, v166
	v_lshlrev_b32_e32 v201, 16, v169
	v_lshlrev_b32_e32 v200, 16, v168
	v_and_b32_e32 v203, 0xffff0000, v169
	v_and_b32_e32 v202, 0xffff0000, v168
	v_and_b32_e32 v187, 0xffff0000, v162
	v_lshlrev_b32_e32 v188, 16, v163
	v_and_b32_e32 v189, 0xffff0000, v163
	v_lshlrev_b32_e32 v190, 16, v164
	v_and_b32_e32 v192, 0xffff0000, v164
	v_lshlrev_b32_e32 v194, 16, v165
	v_and_b32_e32 v196, 0xffff0000, v165
	v_add_f32_e32 v162, v198, v184
	v_add_f32_e32 v163, v199, v185
	v_add_f32_e32 v164, v200, v202
	v_add_f32_e32 v165, v201, v203
	v_add_f32_e32 v147, v162, v163
	v_add_f32_e32 v162, v164, v164
	v_add_f32_e32 v163, v164, v165
	v_add_f32_e32 v195, v186, v187
	v_add_f32_e32 v197, v188, v189
	v_add_f32_e32 v193, 0, v147
	v_mov_b32_e32 v191, v163
	v_add_f32_e32 v164, v194, v196
	v_add_f32_e32 v165, v195, v197
	v_add_f32_e32 v162, v190, v192
	v_add_f32_e32 v163, v191, v193
	s_nop 0
	v_add_f32_e32 v162, v162, v164
	v_add_f32_e32 v163, v163, v165
	s_nop 0
	v_add_f32_e32 v147, v162, v163
	global_load_dwordx4 v[162:165], v[140:141], off offset:16
	global_load_dwordx4 v[166:169], v[140:141], off
	global_load_dwordx4 v[174:177], v[142:143], off offset:16
	global_load_dwordx4 v[178:181], v[142:143], off
	ds_bpermute_b32 v161, v154, v147
	flat_load_dword v150, v[150:151]
	s_waitcnt lgkmcnt(0)
	v_add_f32_e32 v147, v147, v161
	ds_bpermute_b32 v161, v155, v147
	s_waitcnt lgkmcnt(0)
	v_add_f32_e32 v147, v147, v161
	v_fmac_f32_e32 v184, 0xbc800000, v147
	v_fmac_f32_e32 v185, 0xbc800000, v147
	v_fmac_f32_e32 v199, 0xbc800000, v147
	v_fmac_f32_e32 v202, 0xbc800000, v147
	v_fmac_f32_e32 v203, 0xbc800000, v147
	v_fmac_f32_e32 v201, 0xbc800000, v147
	v_fmac_f32_e32 v198, 0xbc800000, v147
	v_fmac_f32_e32 v200, 0xbc800000, v147
	v_fmac_f32_e32 v186, 0xbc800000, v147
	v_fmac_f32_e32 v188, 0xbc800000, v147
	v_mov_b32_e32 v204, v199
	v_mov_b32_e32 v205, v185
	v_mov_b32_e32 v199, v184
	v_mov_b32_e32 v206, v201
	v_mov_b32_e32 v207, v203
	v_mov_b32_e32 v201, v202
	v_fmac_f32_e32 v187, 0xbc800000, v147
	v_fmac_f32_e32 v189, 0xbc800000, v147
	v_mul_f32_e32 v184, v186, v186
	v_mul_f32_e32 v202, v188, v188
	v_mul_f32_e32 v208, v204, v204
	v_mul_f32_e32 v209, v205, v205
	v_mul_f32_e32 v210, v198, v198
	v_mul_f32_e32 v211, v199, v199
	v_mul_f32_e32 v212, v206, v206
	v_mul_f32_e32 v213, v207, v207
	v_mul_f32_e32 v214, v200, v200
	v_mul_f32_e32 v215, v201, v201
	v_fmac_f32_e32 v192, 0xbc800000, v147
	v_fmac_f32_e32 v190, 0xbc800000, v147
	v_fma_f32 v185, v187, v187, v184
	v_fma_f32 v184, v186, v186, v184
	v_fma_f32 v203, v189, v189, v202
	v_fma_f32 v202, v188, v188, v202
	v_pk_mov_b32 v[216:217], v[210:211], v[208:209] op_sel:[1,0]
	v_mov_b32_e32 v211, v209
	v_pk_mov_b32 v[208:209], v[214:215], v[212:213] op_sel:[1,0]
	v_mov_b32_e32 v215, v213
	v_mul_f32_e32 v184, v190, v190
	v_mul_f32_e32 v202, v192, v192
	v_add_f32_e32 v210, v216, v210
	v_add_f32_e32 v211, v217, v211
	v_add_f32_e32 v208, v208, v214
	v_add_f32_e32 v209, v209, v215
	v_fmac_f32_e32 v196, 0xbc800000, v147
	v_fmac_f32_e32 v194, 0xbc800000, v147
	v_add_f32_e32 v184, v184, v202
	v_add_f32_e32 v185, v185, v203
	v_add_f32_e32 v202, v210, v210
	v_add_f32_e32 v203, v210, v211
	v_add_f32_e32 v209, v208, v209
	v_add_f32_e32 v208, v208, v208
	v_mul_f32_e32 v202, v194, v194
	v_mul_f32_e32 v208, v196, v196
	v_add_f32_e32 v202, v202, v208
	v_add_f32_e32 v203, v203, v209
	v_lshlrev_b32_e32 v208, 16, v172
	v_add_f32_e32 v184, v184, v202
	v_add_f32_e32 v185, v185, v203
	v_lshlrev_b32_e32 v202, 16, v170
	v_add_f32_e32 v147, v184, v185
	ds_bpermute_b32 v151, v154, v147
	v_and_b32_e32 v203, 0xffff0000, v170
	v_lshlrev_b32_e32 v170, 16, v171
	v_and_b32_e32 v171, 0xffff0000, v171
	v_and_b32_e32 v209, 0xffff0000, v172
	s_waitcnt lgkmcnt(0)
	v_add_f32_e32 v147, v147, v151
	ds_bpermute_b32 v151, v155, v147
	v_lshlrev_b32_e32 v172, 16, v173
	v_and_b32_e32 v173, 0xffff0000, v173
	global_load_dwordx4 v[182:185], v[182:183], off offset:64
	v_mov_b32_e32 v191, v192
	s_waitcnt lgkmcnt(0)
	v_add_f32_e32 v147, v147, v151
	v_fmamk_f32 v147, v147, 0x3c800000, v160
	v_mul_f32_e32 v151, 0x4b800000, v147
	v_cmp_gt_f32_e32 vcc, s78, v147
	v_mov_b32_e32 v195, v196
	s_nop 0
	v_cndmask_b32_e32 v147, v147, v151, vcc
	v_rsq_f32_e32 v147, v147
	s_nop 0
	v_mul_f32_e32 v151, 0x45800000, v147
	v_cndmask_b32_e32 v210, v147, v151, vcc
	v_mul_f32_e32 v198, v198, v210
	v_mul_f32_e32 v199, v199, v210
	v_mul_f32_e32 v204, v204, v210
	v_mul_f32_e32 v205, v205, v210
	v_mul_f32_e32 v200, v200, v210
	v_mul_f32_e32 v201, v201, v210
	v_mul_f32_e32 v206, v206, v210
	v_mul_f32_e32 v207, v207, v210
	s_waitcnt vmcnt(0)
; #define GAS __attribute__((address_space(1)))
;     __device__ __forceinline__ void operator()(const Acc& acc, const Unit& u, int wr, int wc, int fr, int fq) const {
;     ...
;                 const int row = row0 + ai * HALF + m * 16;
;                 const size_t off = (size_t)row * D + colb;
;                 f32x4 y[2][2], v[2][2];
; #pragma unroll
;                 for (int bj = 0; bj < 2; ++bj) { unpack8(*(const GAS u32x4*)(Y + off + 32 * bj), y[bj][0], y[bj][1]); unpack8(*(const GAS u32x4*)(V + off + 32 * bj), v[bj][0], v[bj][1]); }
;                 const float bs = BON[(size_t)row * 16 + head];
;                 float s = 0.f;
; #pragma unroll
;                 for (int bj = 0; bj < 2; ++bj)
; #pragma unroll
;                     for (int n = 0; n < 2; ++n) s += (y[bj][n][0] + y[bj][n][1]) + (y[bj][n][2] + y[bj][n][3]);
;                 s += __shfl_xor(s, 16); s += __shfl_xor(s, 32);
;                 const float mean = s * (1.f / 64.f);
;                 float q = 0.f;
; #pragma unroll
;                 for (int bj = 0; bj < 2; ++bj)
; #pragma unroll
;                     for (int n = 0; n < 2; ++n) { y[bj][n] = y[bj][n] - mean; q += (y[bj][n][0] * y[bj][n][0] + y[bj][n][1] * y[bj][n][1]) + (y[bj][n][2] * y[bj][n][2] + y[bj][n][3] * y[bj][n][3]); }
;                 q += __shfl_xor(q, 16); q += __shfl_xor(q, 32);
;                 const float rs = rsqrtf(q * (1.f / 64.f) + 64e-5f);
; #pragma unroll
;                 for (int bj = 0; bj < 2; ++bj) {
;                     f32x4 o[2];
; #pragma unroll
;                     for (int n = 0; n < 2; ++n) {
;                         const f32x4 lw = *(const GAS f32x4*)(ln_w + colb + 32 * bj + 4 * n), lb = *(const GAS f32x4*)(ln_b + colb + 32 * bj + 4 * n);
;                         o[n] = (y[bj][n] * rs * lw + lb + v[bj][n] * bs) * acc[ai][bj][m][n];
;                     }
;                     *(GAS u32x4*)(YG + off + 32 * bj) = pack8(o[0], o[1]);
	v_fma_f32 v168, v168, v204, v180
	v_fma_f32 v169, v169, v205, v181
	v_fma_f32 v166, v166, v198, v178
	v_fma_f32 v167, v167, v199, v179
	v_fma_f32 v164, v164, v206, v176
	v_fma_f32 v165, v165, v207, v177
	v_fma_f32 v162, v162, v200, v174
	v_fma_f32 v163, v163, v201, v175
	v_fma_f32 v166, v150, v202, v166
	v_fma_f32 v167, v150, v203, v167
	v_fma_f32 v168, v150, v170, v168
	v_fma_f32 v169, v150, v171, v169
	v_fma_f32 v162, v150, v208, v162
	v_fma_f32 v163, v150, v209, v163
	v_fma_f32 v164, v150, v172, v164
	v_fma_f32 v165, v150, v173, v165
	v_mul_f32_e32 v126, v126, v168
	v_mul_f32_e32 v127, v127, v169
	v_mul_f32_e32 v124, v124, v166
	v_mul_f32_e32 v125, v125, v167
	v_mul_f32_e32 v164, v122, v164
	v_mul_f32_e32 v165, v123, v165
	v_mul_f32_e32 v122, v120, v162
	v_mul_f32_e32 v123, v121, v163
	v_cvt_pk_bf16_f32 v120, v124, v125
	v_cvt_pk_bf16_f32 v121, v126, v127
	v_cvt_pk_bf16_f32 v122, v122, v123
	v_cvt_pk_bf16_f32 v123, v164, v165
	v_lshl_add_u64 v[170:171], s[20:21], 0, v[148:149]
	global_store_dwordx4 v[170:171], v[120:123], off
	global_load_dwordx4 v[120:123], v[142:143], off offset:128
	s_nop 0
	global_load_dwordx4 v[124:127], v[140:141], off offset:128
	global_load_dwordx4 v[162:165], v[140:141], off offset:144
	global_load_dwordx4 v[166:169], v[142:143], off offset:144
	v_or_b32_e32 v172, 16, v146
	v_ashrrev_i32_e32 v173, 31, v172
	v_lshlrev_b64 v[148:149], 10, v[172:173]
	v_lshl_add_u64 v[148:149], v[148:149], 0, v[144:145]
	v_lshlrev_b64 v[148:149], 1, v[148:149]
	v_lshl_add_u64 v[174:175], s[16:17], 0, v[148:149]
	v_lshlrev_b32_e32 v176, 16, v182
	v_and_b32_e32 v177, 0xffff0000, v182
	v_lshlrev_b32_e32 v178, 16, v183
	v_and_b32_e32 v179, 0xffff0000, v183
	v_lshlrev_b32_e32 v180, 16, v184
	v_and_b32_e32 v181, 0xffff0000, v184
	v_lshlrev_b32_e32 v182, 16, v185
	v_and_b32_e32 v183, 0xffff0000, v185
	v_mul_f32_e32 v184, v186, v210
	v_mul_f32_e32 v185, v187, v210
	v_mul_f32_e32 v186, v188, v210
	v_mul_f32_e32 v187, v189, v210
	v_mul_f32_e32 v188, v190, v210
	v_mul_f32_e32 v189, v191, v210
	v_mul_f32_e32 v190, v194, v210
	v_mul_f32_e32 v191, v195, v210
	s_waitcnt vmcnt(2)
	v_fma_f32 v122, v126, v186, v122
	v_fma_f32 v123, v127, v187, v123
	v_fma_f32 v120, v124, v184, v120
	v_fma_f32 v121, v125, v185, v121
	s_waitcnt vmcnt(0)
	v_fma_f32 v124, v164, v190, v168
	v_fma_f32 v125, v165, v191, v169
	v_fma_f32 v126, v162, v188, v166
	v_fma_f32 v127, v163, v189, v167
	v_fma_f32 v120, v150, v176, v120
	v_fma_f32 v121, v150, v177, v121
	v_fma_f32 v122, v150, v178, v122
	v_fma_f32 v123, v150, v179, v123
	v_fma_f32 v126, v150, v180, v126
	v_fma_f32 v127, v150, v181, v127
	v_fma_f32 v124, v150, v182, v124
	v_fma_f32 v125, v150, v183, v125
	v_mul_f32_e32 v118, v118, v122
	v_mul_f32_e32 v119, v119, v123
	v_mul_f32_e32 v116, v116, v120
	v_mul_f32_e32 v117, v117, v121
	v_mul_f32_e32 v120, v114, v124
	v_mul_f32_e32 v121, v115, v125
	v_mul_f32_e32 v114, v112, v126
	v_mul_f32_e32 v115, v113, v127
	v_cvt_pk_bf16_f32 v112, v116, v117
	v_cvt_pk_bf16_f32 v113, v118, v119
	v_cvt_pk_bf16_f32 v114, v114, v115
	v_cvt_pk_bf16_f32 v115, v120, v121
	global_store_dwordx4 v[170:171], v[112:115], off offset:64
	global_load_dwordx4 v[120:123], v[174:175], off offset:64
	global_load_dwordx4 v[162:165], v[174:175], off
	v_lshlrev_b64 v[112:113], 6, v[172:173]
	v_lshl_add_u64 v[178:179], s[18:19], 0, v[112:113]
	v_lshl_add_u64 v[180:181], s[6:7], 0, v[148:149]
	global_load_dwordx4 v[112:115], v[180:181], off
	v_lshl_add_u64 v[178:179], v[178:179], 0, s[34:35]
	s_waitcnt vmcnt(2)
	v_lshlrev_b32_e32 v116, 16, v120
	s_waitcnt vmcnt(1)
	v_lshlrev_b32_e32 v151, 16, v163
	v_lshlrev_b32_e32 v150, 16, v162
	v_and_b32_e32 v183, 0xffff0000, v163
	v_and_b32_e32 v182, 0xffff0000, v162
	v_lshlrev_b32_e32 v185, 16, v165
	v_lshlrev_b32_e32 v184, 16, v164
	v_and_b32_e32 v187, 0xffff0000, v165
	v_and_b32_e32 v186, 0xffff0000, v164
	v_add_f32_e32 v162, v150, v182
	v_add_f32_e32 v163, v151, v183
	v_add_f32_e32 v164, v184, v186
	v_add_f32_e32 v165, v185, v187
	v_and_b32_e32 v117, 0xffff0000, v120
	v_lshlrev_b32_e32 v118, 16, v121
	v_and_b32_e32 v119, 0xffff0000, v121
	v_add_f32_e32 v121, v162, v163
	v_add_f32_e32 v162, v164, v164
	v_add_f32_e32 v163, v164, v165
	v_lshlrev_b32_e32 v120, 16, v122
	v_and_b32_e32 v124, 0xffff0000, v122
	v_lshlrev_b32_e32 v122, 16, v123
	v_and_b32_e32 v126, 0xffff0000, v123
	v_add_f32_e32 v123, v116, v117
	v_add_f32_e32 v127, v118, v119
	v_add_f32_e32 v125, 0, v121
	v_mov_b32_e32 v121, v163
	v_add_f32_e32 v164, v122, v126
	v_add_f32_e32 v165, v123, v127
	v_add_f32_e32 v162, v120, v124
	v_add_f32_e32 v163, v121, v125
	s_nop 0
	v_add_f32_e32 v162, v162, v164
	v_add_f32_e32 v163, v163, v165
	s_nop 0
	v_add_f32_e32 v121, v162, v163
	global_load_dwordx4 v[162:165], v[140:141], off offset:16
	global_load_dwordx4 v[166:169], v[140:141], off
	global_load_dwordx4 v[170:173], v[142:143], off offset:16
	global_load_dwordx4 v[174:177], v[142:143], off
	flat_load_dword v188, v[178:179]
	ds_bpermute_b32 v123, v154, v121
	s_waitcnt lgkmcnt(0)
	v_add_f32_e32 v121, v121, v123
	ds_bpermute_b32 v123, v155, v121
	s_waitcnt lgkmcnt(0)
; #define GAS __attribute__((address_space(1)))
;     __device__ __forceinline__ void operator()(const Acc& acc, const Unit& u, int wr, int wc, int fr, int fq) const {
;     ...
;                 const int row = row0 + ai * HALF + m * 16;
;                 const size_t off = (size_t)row * D + colb;
;                 f32x4 y[2][2], v[2][2];
; #pragma unroll
;                 for (int bj = 0; bj < 2; ++bj) { unpack8(*(const GAS u32x4*)(Y + off + 32 * bj), y[bj][0], y[bj][1]); unpack8(*(const GAS u32x4*)(V + off + 32 * bj), v[bj][0], v[bj][1]); }
;                 const float bs = BON[(size_t)row * 16 + head];
;                 float s = 0.f;
; #pragma unroll
;                 for (int bj = 0; bj < 2; ++bj)
; #pragma unroll
;                     for (int n = 0; n < 2; ++n) s += (y[bj][n][0] + y[bj][n][1]) + (y[bj][n][2] + y[bj][n][3]);
;                 s += __shfl_xor(s, 16); s += __shfl_xor(s, 32);
;                 const float mean = s * (1.f / 64.f);
;                 float q = 0.f;
; #pragma unroll
;                 for (int bj = 0; bj < 2; ++bj)
; #pragma unroll
;                     for (int n = 0; n < 2; ++n) { y[bj][n] = y[bj][n] - mean; q += (y[bj][n][0] * y[bj][n][0] + y[bj][n][1] * y[bj][n][1]) + (y[bj][n][2] * y[bj][n][2] + y[bj][n][3] * y[bj][n][3]); }
;                 q += __shfl_xor(q, 16); q += __shfl_xor(q, 32);
;                 const float rs = rsqrtf(q * (1.f / 64.f) + 64e-5f);
; #pragma unroll
;                 for (int bj = 0; bj < 2; ++bj) {
;                     f32x4 o[2];
; #pragma unroll
;                     for (int n = 0; n < 2; ++n) {
;                         const f32x4 lw = *(const GAS f32x4*)(ln_w + colb + 32 * bj + 4 * n), lb = *(const GAS f32x4*)(ln_b + colb + 32 * bj + 4 * n);
;                         o[n] = (y[bj][n] * rs * lw + lb + v[bj][n] * bs) * acc[ai][bj][m][n];
;                     }
;                     *(GAS u32x4*)(YG + off + 32 * bj) = pack8(o[0], o[1]);
	v_add_f32_e32 v121, v121, v123
	v_fmac_f32_e32 v182, 0xbc800000, v121
	v_fmac_f32_e32 v183, 0xbc800000, v121
	v_fmac_f32_e32 v151, 0xbc800000, v121
	v_fmac_f32_e32 v186, 0xbc800000, v121
	v_fmac_f32_e32 v187, 0xbc800000, v121
	v_fmac_f32_e32 v185, 0xbc800000, v121
	v_fmac_f32_e32 v150, 0xbc800000, v121
	v_fmac_f32_e32 v184, 0xbc800000, v121
	v_fmac_f32_e32 v116, 0xbc800000, v121
	v_fmac_f32_e32 v118, 0xbc800000, v121
	v_mov_b32_e32 v190, v151
	v_mov_b32_e32 v191, v183
	v_mov_b32_e32 v151, v182
	v_mov_b32_e32 v182, v185
	v_mov_b32_e32 v183, v187
	v_mov_b32_e32 v185, v186
	v_fmac_f32_e32 v117, 0xbc800000, v121
	v_fmac_f32_e32 v119, 0xbc800000, v121
	v_mul_f32_e32 v178, v116, v116
	v_mul_f32_e32 v186, v118, v118
	v_mul_f32_e32 v192, v190, v190
	v_mul_f32_e32 v193, v191, v191
	v_mul_f32_e32 v194, v150, v150
	v_mul_f32_e32 v195, v151, v151
	v_mul_f32_e32 v196, v182, v182
	v_mul_f32_e32 v197, v183, v183
	v_mul_f32_e32 v198, v184, v184
	v_mul_f32_e32 v199, v185, v185
	v_fmac_f32_e32 v124, 0xbc800000, v121
	v_fmac_f32_e32 v120, 0xbc800000, v121
	v_fma_f32 v179, v117, v117, v178
	v_fma_f32 v178, v116, v116, v178
	v_fma_f32 v187, v119, v119, v186
	v_fma_f32 v186, v118, v118, v186
	v_pk_mov_b32 v[200:201], v[194:195], v[192:193] op_sel:[1,0]
	v_mov_b32_e32 v195, v193
	v_pk_mov_b32 v[192:193], v[198:199], v[196:197] op_sel:[1,0]
	v_mov_b32_e32 v199, v197
	v_mul_f32_e32 v178, v120, v120
	v_mul_f32_e32 v186, v124, v124
	v_add_f32_e32 v194, v200, v194
	v_add_f32_e32 v195, v201, v195
	v_add_f32_e32 v192, v192, v198
	v_add_f32_e32 v193, v193, v199
	v_fmac_f32_e32 v126, 0xbc800000, v121
	v_fmac_f32_e32 v122, 0xbc800000, v121
	v_add_f32_e32 v178, v178, v186
	v_add_f32_e32 v179, v179, v187
	v_add_f32_e32 v186, v194, v194
	v_add_f32_e32 v187, v194, v195
	v_add_f32_e32 v193, v192, v193
	v_add_f32_e32 v192, v192, v192
	v_mul_f32_e32 v186, v122, v122
	v_mul_f32_e32 v192, v126, v126
	v_add_f32_e32 v186, v186, v192
	v_add_f32_e32 v187, v187, v193
	s_waitcnt vmcnt(0)
	v_lshlrev_b32_e32 v192, 16, v114
	v_add_f32_e32 v178, v178, v186
	v_add_f32_e32 v179, v179, v187
	v_lshl_add_u64 v[186:187], s[20:21], 0, v[148:149]
	v_add_f32_e32 v121, v178, v179
	ds_bpermute_b32 v123, v154, v121
	v_lshlrev_b32_e32 v148, 16, v112
	v_and_b32_e32 v149, 0xffff0000, v112
	v_lshlrev_b32_e32 v112, 16, v113
	v_and_b32_e32 v113, 0xffff0000, v113
	s_waitcnt lgkmcnt(0)
	v_add_f32_e32 v121, v121, v123
	ds_bpermute_b32 v123, v155, v121
	v_and_b32_e32 v193, 0xffff0000, v114
	v_lshlrev_b32_e32 v114, 16, v115
	v_and_b32_e32 v115, 0xffff0000, v115
	global_load_dwordx4 v[178:181], v[180:181], off offset:64
	s_waitcnt lgkmcnt(0)
	v_add_f32_e32 v121, v121, v123
	v_fmamk_f32 v121, v121, 0x3c800000, v160
	v_mul_f32_e32 v123, 0x4b800000, v121
	v_cmp_gt_f32_e32 vcc, s78, v121
	s_nop 1
	v_cndmask_b32_e32 v121, v121, v123, vcc
	v_rsq_f32_e32 v121, v121
	s_nop 0
	v_mul_f32_e32 v123, 0x45800000, v121
	v_cndmask_b32_e32 v194, v121, v123, vcc
	v_mul_f32_e32 v150, v150, v194
	v_mul_f32_e32 v151, v151, v194
	v_mul_f32_e32 v190, v190, v194
	v_mul_f32_e32 v191, v191, v194
	v_mul_f32_e32 v184, v184, v194
	v_mul_f32_e32 v185, v185, v194
	v_mul_f32_e32 v182, v182, v194
	v_mul_f32_e32 v183, v183, v194
	v_fma_f32 v168, v168, v190, v176
	v_fma_f32 v169, v169, v191, v177
	v_fma_f32 v150, v166, v150, v174
	v_fma_f32 v151, v167, v151, v175
	v_fma_f32 v164, v164, v182, v172
	v_fma_f32 v165, v165, v183, v173
	v_fma_f32 v162, v162, v184, v170
	v_fma_f32 v163, v163, v185, v171
	v_fma_f32 v148, v188, v148, v150
	v_fma_f32 v149, v188, v149, v151
	v_fma_f32 v112, v188, v112, v168
	v_fma_f32 v113, v188, v113, v169
	v_fma_f32 v150, v188, v192, v162
	v_fma_f32 v151, v188, v193, v163
	v_fma_f32 v114, v188, v114, v164
	v_fma_f32 v115, v188, v115, v165
	v_mul_f32_e32 v110, v110, v112
	v_mul_f32_e32 v111, v111, v113
	v_mul_f32_e32 v108, v108, v148
	v_mul_f32_e32 v109, v109, v149
	v_mul_f32_e32 v112, v106, v114
	v_mul_f32_e32 v113, v107, v115
	v_mul_f32_e32 v106, v104, v150
	v_mul_f32_e32 v107, v105, v151
	v_cvt_pk_bf16_f32 v104, v108, v109
	v_cvt_pk_bf16_f32 v105, v110, v111
	v_cvt_pk_bf16_f32 v106, v106, v107
	v_cvt_pk_bf16_f32 v107, v112, v113
	global_store_dwordx4 v[186:187], v[104:107], off
	global_load_dwordx4 v[104:107], v[142:143], off offset:128
	s_nop 0
	global_load_dwordx4 v[108:111], v[140:141], off offset:128
	global_load_dwordx4 v[148:151], v[140:141], off offset:144
	global_load_dwordx4 v[162:165], v[142:143], off offset:144
	v_mov_b32_e32 v121, v124
	v_mov_b32_e32 v123, v126
	v_mul_f32_e32 v116, v116, v194
	v_mul_f32_e32 v117, v117, v194
	v_mul_f32_e32 v118, v118, v194
	v_mul_f32_e32 v119, v119, v194
	v_mul_f32_e32 v120, v120, v194
	v_mul_f32_e32 v121, v121, v194
	v_mul_f32_e32 v122, v122, v194
	v_mul_f32_e32 v123, v123, v194
	v_or_b32_e32 v114, 32, v146
	v_ashrrev_i32_e32 v115, 31, v114
	v_lshlrev_b64 v[112:113], 10, v[114:115]
	v_lshl_add_u64 v[112:113], v[112:113], 0, v[144:145]
	v_lshlrev_b64 v[112:113], 1, v[112:113]
	v_lshl_add_u64 v[166:167], s[16:17], 0, v[112:113]
	s_waitcnt vmcnt(5)
	v_lshlrev_b32_e32 v168, 16, v178
	v_and_b32_e32 v169, 0xffff0000, v178
	v_lshlrev_b32_e32 v170, 16, v179
	v_and_b32_e32 v171, 0xffff0000, v179
	v_lshlrev_b32_e32 v172, 16, v180
	v_and_b32_e32 v173, 0xffff0000, v180
	v_lshlrev_b32_e32 v174, 16, v181
	v_and_b32_e32 v175, 0xffff0000, v181
	s_waitcnt vmcnt(2)
	v_fma_f32 v106, v110, v118, v106
	v_fma_f32 v107, v111, v119, v107
	v_fma_f32 v104, v108, v116, v104
	v_fma_f32 v105, v109, v117, v105
	s_waitcnt vmcnt(0)
; #define GAS __attribute__((address_space(1)))
;     __device__ __forceinline__ void operator()(const Acc& acc, const Unit& u, int wr, int wc, int fr, int fq) const {
;     ...
;                 const int row = row0 + ai * HALF + m * 16;
;                 const size_t off = (size_t)row * D + colb;
;                 f32x4 y[2][2], v[2][2];
; #pragma unroll
;                 for (int bj = 0; bj < 2; ++bj) { unpack8(*(const GAS u32x4*)(Y + off + 32 * bj), y[bj][0], y[bj][1]); unpack8(*(const GAS u32x4*)(V + off + 32 * bj), v[bj][0], v[bj][1]); }
;                 const float bs = BON[(size_t)row * 16 + head];
;                 float s = 0.f;
; #pragma unroll
;                 for (int bj = 0; bj < 2; ++bj)
; #pragma unroll
;                     for (int n = 0; n < 2; ++n) s += (y[bj][n][0] + y[bj][n][1]) + (y[bj][n][2] + y[bj][n][3]);
;                 s += __shfl_xor(s, 16); s += __shfl_xor(s, 32);
;                 const float mean = s * (1.f / 64.f);
;                 float q = 0.f;
; #pragma unroll
;                 for (int bj = 0; bj < 2; ++bj)
; #pragma unroll
;                     for (int n = 0; n < 2; ++n) { y[bj][n] = y[bj][n] - mean; q += (y[bj][n][0] * y[bj][n][0] + y[bj][n][1] * y[bj][n][1]) + (y[bj][n][2] * y[bj][n][2] + y[bj][n][3] * y[bj][n][3]); }
;                 q += __shfl_xor(q, 16); q += __shfl_xor(q, 32);
;                 const float rs = rsqrtf(q * (1.f / 64.f) + 64e-5f);
; #pragma unroll
;                 for (int bj = 0; bj < 2; ++bj) {
;                     f32x4 o[2];
; #pragma unroll
;                     for (int n = 0; n < 2; ++n) {
;                         const f32x4 lw = *(const GAS f32x4*)(ln_w + colb + 32 * bj + 4 * n), lb = *(const GAS f32x4*)(ln_b + colb + 32 * bj + 4 * n);
;                         o[n] = (y[bj][n] * rs * lw + lb + v[bj][n] * bs) * acc[ai][bj][m][n];
;                     }
;                     *(GAS u32x4*)(YG + off + 32 * bj) = pack8(o[0], o[1]);
	v_fma_f32 v108, v150, v122, v164
	v_fma_f32 v109, v151, v123, v165
	v_fma_f32 v110, v148, v120, v162
	v_fma_f32 v111, v149, v121, v163
	v_fma_f32 v104, v188, v168, v104
	v_fma_f32 v105, v188, v169, v105
	v_fma_f32 v106, v188, v170, v106
	v_fma_f32 v107, v188, v171, v107
	v_fma_f32 v110, v188, v172, v110
	v_fma_f32 v111, v188, v173, v111
	v_fma_f32 v108, v188, v174, v108
	v_fma_f32 v109, v188, v175, v109
	v_mul_f32_e32 v102, v102, v106
	v_mul_f32_e32 v103, v103, v107
	v_mul_f32_e32 v100, v100, v104
	v_mul_f32_e32 v101, v101, v105
	v_mul_f32_e32 v104, v98, v108
	v_mul_f32_e32 v105, v99, v109
	v_mul_f32_e32 v98, v96, v110
	v_mul_f32_e32 v99, v97, v111
	v_cvt_pk_bf16_f32 v96, v100, v101
	v_cvt_pk_bf16_f32 v97, v102, v103
	v_cvt_pk_bf16_f32 v98, v98, v99
	v_cvt_pk_bf16_f32 v99, v104, v105
	global_store_dwordx4 v[186:187], v[96:99], off offset:64
	global_load_dwordx4 v[104:107], v[166:167], off offset:64
	global_load_dwordx4 v[116:119], v[166:167], off
	v_lshlrev_b64 v[96:97], 6, v[114:115]
	v_lshl_add_u64 v[162:163], s[18:19], 0, v[96:97]
	v_lshl_add_u64 v[164:165], s[6:7], 0, v[112:113]
	global_load_dwordx4 v[96:99], v[164:165], off
	v_lshl_add_u64 v[162:163], v[162:163], 0, s[34:35]
	s_waitcnt vmcnt(2)
	v_lshlrev_b32_e32 v100, 16, v104
	s_waitcnt vmcnt(1)
	v_lshlrev_b32_e32 v115, 16, v117
	v_lshlrev_b32_e32 v114, 16, v116
	v_and_b32_e32 v167, 0xffff0000, v117
	v_and_b32_e32 v166, 0xffff0000, v116
	v_lshlrev_b32_e32 v169, 16, v119
	v_lshlrev_b32_e32 v168, 16, v118
	v_and_b32_e32 v171, 0xffff0000, v119
	v_and_b32_e32 v170, 0xffff0000, v118
	v_add_f32_e32 v116, v114, v166
	v_add_f32_e32 v117, v115, v167
	v_add_f32_e32 v118, v168, v170
	v_add_f32_e32 v119, v169, v171
	v_and_b32_e32 v101, 0xffff0000, v104
	v_lshlrev_b32_e32 v102, 16, v105
	v_and_b32_e32 v103, 0xffff0000, v105
	v_add_f32_e32 v105, v116, v117
	v_add_f32_e32 v116, v118, v118
	v_add_f32_e32 v117, v118, v119
	v_lshlrev_b32_e32 v104, 16, v106
	v_and_b32_e32 v108, 0xffff0000, v106
	v_lshlrev_b32_e32 v106, 16, v107
	v_and_b32_e32 v110, 0xffff0000, v107
	v_add_f32_e32 v107, v100, v101
	v_add_f32_e32 v111, v102, v103
	v_add_f32_e32 v109, 0, v105
	v_mov_b32_e32 v105, v117
	v_add_f32_e32 v118, v106, v110
	v_add_f32_e32 v119, v107, v111
	v_add_f32_e32 v116, v104, v108
	v_add_f32_e32 v117, v105, v109
	s_nop 0
	v_add_f32_e32 v116, v116, v118
	v_add_f32_e32 v117, v117, v119
	s_nop 0
	v_add_f32_e32 v105, v116, v117
	global_load_dwordx4 v[116:119], v[140:141], off offset:16
	global_load_dwordx4 v[120:123], v[140:141], off
	global_load_dwordx4 v[124:127], v[142:143], off offset:16
	global_load_dwordx4 v[148:151], v[142:143], off
	flat_load_dword v172, v[162:163]
	ds_bpermute_b32 v107, v154, v105
	s_waitcnt lgkmcnt(0)
	v_add_f32_e32 v105, v105, v107
	ds_bpermute_b32 v107, v155, v105
	s_waitcnt lgkmcnt(0)
	v_add_f32_e32 v105, v105, v107
	v_fmac_f32_e32 v166, 0xbc800000, v105
	v_fmac_f32_e32 v167, 0xbc800000, v105
	v_fmac_f32_e32 v115, 0xbc800000, v105
	v_fmac_f32_e32 v170, 0xbc800000, v105
	v_fmac_f32_e32 v171, 0xbc800000, v105
	v_fmac_f32_e32 v169, 0xbc800000, v105
	v_fmac_f32_e32 v114, 0xbc800000, v105
	v_fmac_f32_e32 v168, 0xbc800000, v105
	v_fmac_f32_e32 v100, 0xbc800000, v105
	v_fmac_f32_e32 v102, 0xbc800000, v105
	v_mov_b32_e32 v174, v115
	v_mov_b32_e32 v175, v167
	v_mov_b32_e32 v115, v166
	v_mov_b32_e32 v166, v169
	v_mov_b32_e32 v167, v171
	v_mov_b32_e32 v169, v170
	v_fmac_f32_e32 v101, 0xbc800000, v105
	v_fmac_f32_e32 v103, 0xbc800000, v105
	v_mul_f32_e32 v162, v100, v100
	v_mul_f32_e32 v170, v102, v102
	v_mul_f32_e32 v176, v174, v174
	v_mul_f32_e32 v177, v175, v175
	v_mul_f32_e32 v178, v114, v114
	v_mul_f32_e32 v179, v115, v115
	v_mul_f32_e32 v180, v166, v166
	v_mul_f32_e32 v181, v167, v167
	v_mul_f32_e32 v182, v168, v168
	v_mul_f32_e32 v183, v169, v169
	v_fmac_f32_e32 v108, 0xbc800000, v105
	v_fmac_f32_e32 v104, 0xbc800000, v105
	v_fma_f32 v163, v101, v101, v162
	v_fma_f32 v162, v100, v100, v162
	v_fma_f32 v171, v103, v103, v170
	v_fma_f32 v170, v102, v102, v170
	v_pk_mov_b32 v[184:185], v[178:179], v[176:177] op_sel:[1,0]
	v_mov_b32_e32 v179, v177
	v_pk_mov_b32 v[176:177], v[182:183], v[180:181] op_sel:[1,0]
	v_mov_b32_e32 v183, v181
	v_mul_f32_e32 v162, v104, v104
	v_mul_f32_e32 v170, v108, v108
	v_add_f32_e32 v178, v184, v178
	v_add_f32_e32 v179, v185, v179
	v_add_f32_e32 v176, v176, v182
	v_add_f32_e32 v177, v177, v183
	v_fmac_f32_e32 v110, 0xbc800000, v105
	v_fmac_f32_e32 v106, 0xbc800000, v105
	v_add_f32_e32 v162, v162, v170
	v_add_f32_e32 v163, v163, v171
	v_add_f32_e32 v170, v178, v178
	v_add_f32_e32 v171, v178, v179
	v_add_f32_e32 v177, v176, v177
	v_add_f32_e32 v176, v176, v176
	v_mul_f32_e32 v170, v106, v106
	v_mul_f32_e32 v176, v110, v110
	v_add_f32_e32 v170, v170, v176
	v_add_f32_e32 v171, v171, v177
	s_waitcnt vmcnt(0)
	v_lshlrev_b32_e32 v176, 16, v98
	v_add_f32_e32 v162, v162, v170
	v_add_f32_e32 v163, v163, v171
	v_lshl_add_u64 v[170:171], s[20:21], 0, v[112:113]
	v_add_f32_e32 v105, v162, v163
	ds_bpermute_b32 v107, v154, v105
	v_lshlrev_b32_e32 v112, 16, v96
	v_and_b32_e32 v113, 0xffff0000, v96
	v_lshlrev_b32_e32 v96, 16, v97
	v_and_b32_e32 v97, 0xffff0000, v97
	s_waitcnt lgkmcnt(0)
	v_add_f32_e32 v105, v105, v107
	ds_bpermute_b32 v107, v155, v105
	v_and_b32_e32 v177, 0xffff0000, v98
	v_lshlrev_b32_e32 v98, 16, v99
	v_and_b32_e32 v99, 0xffff0000, v99
	global_load_dwordx4 v[162:165], v[164:165], off offset:64
	s_waitcnt lgkmcnt(0)
; #define GAS __attribute__((address_space(1)))
;     __device__ __forceinline__ void operator()(const Acc& acc, const Unit& u, int wr, int wc, int fr, int fq) const {
;     ...
;                 const int row = row0 + ai * HALF + m * 16;
;                 const size_t off = (size_t)row * D + colb;
;                 f32x4 y[2][2], v[2][2];
; #pragma unroll
;                 for (int bj = 0; bj < 2; ++bj) { unpack8(*(const GAS u32x4*)(Y + off + 32 * bj), y[bj][0], y[bj][1]); unpack8(*(const GAS u32x4*)(V + off + 32 * bj), v[bj][0], v[bj][1]); }
;                 const float bs = BON[(size_t)row * 16 + head];
;                 float s = 0.f;
; #pragma unroll
;                 for (int bj = 0; bj < 2; ++bj)
; #pragma unroll
;                     for (int n = 0; n < 2; ++n) s += (y[bj][n][0] + y[bj][n][1]) + (y[bj][n][2] + y[bj][n][3]);
;                 s += __shfl_xor(s, 16); s += __shfl_xor(s, 32);
;                 const float mean = s * (1.f / 64.f);
;                 float q = 0.f;
; #pragma unroll
;                 for (int bj = 0; bj < 2; ++bj)
; #pragma unroll
;                     for (int n = 0; n < 2; ++n) { y[bj][n] = y[bj][n] - mean; q += (y[bj][n][0] * y[bj][n][0] + y[bj][n][1] * y[bj][n][1]) + (y[bj][n][2] * y[bj][n][2] + y[bj][n][3] * y[bj][n][3]); }
;                 q += __shfl_xor(q, 16); q += __shfl_xor(q, 32);
;                 const float rs = rsqrtf(q * (1.f / 64.f) + 64e-5f);
; #pragma unroll
;                 for (int bj = 0; bj < 2; ++bj) {
;                     f32x4 o[2];
; #pragma unroll
;                     for (int n = 0; n < 2; ++n) {
;                         const f32x4 lw = *(const GAS f32x4*)(ln_w + colb + 32 * bj + 4 * n), lb = *(const GAS f32x4*)(ln_b + colb + 32 * bj + 4 * n);
;                         o[n] = (y[bj][n] * rs * lw + lb + v[bj][n] * bs) * acc[ai][bj][m][n];
;                     }
;                     *(GAS u32x4*)(YG + off + 32 * bj) = pack8(o[0], o[1]);
	v_add_f32_e32 v105, v105, v107
	v_fmamk_f32 v105, v105, 0x3c800000, v160
	v_mul_f32_e32 v107, 0x4b800000, v105
	v_cmp_gt_f32_e32 vcc, s78, v105
	s_nop 1
	v_cndmask_b32_e32 v105, v105, v107, vcc
	v_rsq_f32_e32 v105, v105
	s_nop 0
	v_mul_f32_e32 v107, 0x45800000, v105
	v_cndmask_b32_e32 v178, v105, v107, vcc
	v_mul_f32_e32 v114, v114, v178
	v_mul_f32_e32 v115, v115, v178
	v_mul_f32_e32 v174, v174, v178
	v_mul_f32_e32 v175, v175, v178
	v_mul_f32_e32 v168, v168, v178
	v_mul_f32_e32 v169, v169, v178
	v_mul_f32_e32 v166, v166, v178
	v_mul_f32_e32 v167, v167, v178
	v_fma_f32 v122, v122, v174, v150
	v_fma_f32 v123, v123, v175, v151
	v_fma_f32 v114, v120, v114, v148
	v_fma_f32 v115, v121, v115, v149
	v_fma_f32 v118, v118, v166, v126
	v_fma_f32 v119, v119, v167, v127
	v_fma_f32 v116, v116, v168, v124
	v_fma_f32 v117, v117, v169, v125
	v_fma_f32 v112, v172, v112, v114
	v_fma_f32 v113, v172, v113, v115
	v_fma_f32 v96, v172, v96, v122
	v_fma_f32 v97, v172, v97, v123
	v_fma_f32 v114, v172, v176, v116
	v_fma_f32 v115, v172, v177, v117
	v_fma_f32 v98, v172, v98, v118
	v_fma_f32 v99, v172, v99, v119
	v_mul_f32_e32 v94, v94, v96
	v_mul_f32_e32 v95, v95, v97
	v_mul_f32_e32 v92, v92, v112
	v_mul_f32_e32 v93, v93, v113
	v_mul_f32_e32 v96, v90, v98
	v_mul_f32_e32 v97, v91, v99
	v_mul_f32_e32 v90, v88, v114
	v_mul_f32_e32 v91, v89, v115
	v_cvt_pk_bf16_f32 v88, v92, v93
	v_cvt_pk_bf16_f32 v89, v94, v95
	v_cvt_pk_bf16_f32 v90, v90, v91
	v_cvt_pk_bf16_f32 v91, v96, v97
	global_store_dwordx4 v[170:171], v[88:91], off
	global_load_dwordx4 v[88:91], v[142:143], off offset:128
	s_nop 0
	global_load_dwordx4 v[92:95], v[140:141], off offset:128
	global_load_dwordx4 v[112:115], v[140:141], off offset:144
	global_load_dwordx4 v[116:119], v[142:143], off offset:144
	v_mov_b32_e32 v105, v108
	v_mov_b32_e32 v107, v110
	v_mul_f32_e32 v100, v100, v178
	v_mul_f32_e32 v101, v101, v178
	v_mul_f32_e32 v102, v102, v178
	v_mul_f32_e32 v103, v103, v178
	v_mul_f32_e32 v104, v104, v178
	v_mul_f32_e32 v105, v105, v178
	v_mul_f32_e32 v106, v106, v178
	v_mul_f32_e32 v107, v107, v178
	v_or_b32_e32 v98, 48, v146
	v_ashrrev_i32_e32 v99, 31, v98
	v_lshlrev_b64 v[96:97], 10, v[98:99]
	v_lshl_add_u64 v[96:97], v[96:97], 0, v[144:145]
	v_lshlrev_b64 v[96:97], 1, v[96:97]
	v_lshl_add_u64 v[120:121], s[16:17], 0, v[96:97]
	s_waitcnt vmcnt(5)
	v_lshlrev_b32_e32 v122, 16, v162
	v_and_b32_e32 v123, 0xffff0000, v162
	v_lshlrev_b32_e32 v124, 16, v163
	v_and_b32_e32 v125, 0xffff0000, v163
	v_lshlrev_b32_e32 v126, 16, v164
	v_and_b32_e32 v127, 0xffff0000, v164
	v_lshlrev_b32_e32 v148, 16, v165
	v_and_b32_e32 v149, 0xffff0000, v165
	s_waitcnt vmcnt(2)
	v_fma_f32 v90, v94, v102, v90
	v_fma_f32 v91, v95, v103, v91
	v_fma_f32 v88, v92, v100, v88
	v_fma_f32 v89, v93, v101, v89
	s_waitcnt vmcnt(0)
	v_fma_f32 v92, v114, v106, v118
	v_fma_f32 v93, v115, v107, v119
	v_fma_f32 v94, v112, v104, v116
	v_fma_f32 v95, v113, v105, v117
	v_fma_f32 v88, v172, v122, v88
	v_fma_f32 v89, v172, v123, v89
	v_fma_f32 v90, v172, v124, v90
	v_fma_f32 v91, v172, v125, v91
	v_fma_f32 v94, v172, v126, v94
	v_fma_f32 v95, v172, v127, v95
	v_fma_f32 v92, v172, v148, v92
	v_fma_f32 v93, v172, v149, v93
	v_mul_f32_e32 v86, v86, v90
	v_mul_f32_e32 v87, v87, v91
	v_mul_f32_e32 v84, v84, v88
	v_mul_f32_e32 v85, v85, v89
	v_mul_f32_e32 v88, v82, v92
	v_mul_f32_e32 v89, v83, v93
	v_mul_f32_e32 v82, v80, v94
	v_mul_f32_e32 v83, v81, v95
	v_cvt_pk_bf16_f32 v80, v84, v85
	v_cvt_pk_bf16_f32 v81, v86, v87
	v_cvt_pk_bf16_f32 v82, v82, v83
	v_cvt_pk_bf16_f32 v83, v88, v89
	global_store_dwordx4 v[170:171], v[80:83], off offset:64
	global_load_dwordx4 v[88:91], v[120:121], off offset:64
	global_load_dwordx4 v[100:103], v[120:121], off
	v_lshlrev_b64 v[80:81], 6, v[98:99]
	v_lshl_add_u64 v[116:117], s[18:19], 0, v[80:81]
	v_lshl_add_u64 v[118:119], s[6:7], 0, v[96:97]
	global_load_dwordx4 v[80:83], v[118:119], off
	v_lshl_add_u64 v[116:117], v[116:117], 0, s[34:35]
	s_waitcnt vmcnt(2)
	v_lshlrev_b32_e32 v84, 16, v88
	s_waitcnt vmcnt(1)
	v_lshlrev_b32_e32 v99, 16, v101
	v_lshlrev_b32_e32 v98, 16, v100
	v_and_b32_e32 v121, 0xffff0000, v101
	v_and_b32_e32 v120, 0xffff0000, v100
	v_lshlrev_b32_e32 v123, 16, v103
	v_lshlrev_b32_e32 v122, 16, v102
	v_and_b32_e32 v125, 0xffff0000, v103
	v_and_b32_e32 v124, 0xffff0000, v102
	v_add_f32_e32 v100, v98, v120
	v_add_f32_e32 v101, v99, v121
	v_add_f32_e32 v102, v122, v124
	v_add_f32_e32 v103, v123, v125
	v_and_b32_e32 v85, 0xffff0000, v88
	v_lshlrev_b32_e32 v86, 16, v89
	v_and_b32_e32 v87, 0xffff0000, v89
	v_add_f32_e32 v89, v100, v101
	v_add_f32_e32 v100, v102, v102
	v_add_f32_e32 v101, v102, v103
	v_lshlrev_b32_e32 v88, 16, v90
	v_and_b32_e32 v92, 0xffff0000, v90
	v_lshlrev_b32_e32 v90, 16, v91
	v_and_b32_e32 v94, 0xffff0000, v91
	v_add_f32_e32 v91, v84, v85
	v_add_f32_e32 v95, v86, v87
	v_add_f32_e32 v93, 0, v89
	v_mov_b32_e32 v89, v101
	v_add_f32_e32 v102, v90, v94
	v_add_f32_e32 v103, v91, v95
	v_add_f32_e32 v100, v88, v92
	v_add_f32_e32 v101, v89, v93
	s_nop 0
	v_add_f32_e32 v100, v100, v102
	v_add_f32_e32 v101, v101, v103
	s_nop 0
	v_add_f32_e32 v89, v100, v101
	global_load_dwordx4 v[100:103], v[140:141], off offset:16
	global_load_dwordx4 v[104:107], v[140:141], off
	global_load_dwordx4 v[108:111], v[142:143], off offset:16
	global_load_dwordx4 v[112:115], v[142:143], off
	flat_load_dword v126, v[116:117]
	ds_bpermute_b32 v91, v154, v89
	s_waitcnt lgkmcnt(0)
	v_add_f32_e32 v89, v89, v91
	ds_bpermute_b32 v91, v155, v89
	s_waitcnt lgkmcnt(0)
; #define GAS __attribute__((address_space(1)))
;     __device__ __forceinline__ void operator()(const Acc& acc, const Unit& u, int wr, int wc, int fr, int fq) const {
;     ...
;                 const int row = row0 + ai * HALF + m * 16;
;                 const size_t off = (size_t)row * D + colb;
;                 f32x4 y[2][2], v[2][2];
; #pragma unroll
;                 for (int bj = 0; bj < 2; ++bj) { unpack8(*(const GAS u32x4*)(Y + off + 32 * bj), y[bj][0], y[bj][1]); unpack8(*(const GAS u32x4*)(V + off + 32 * bj), v[bj][0], v[bj][1]); }
;                 const float bs = BON[(size_t)row * 16 + head];
;                 float s = 0.f;
; #pragma unroll
;                 for (int bj = 0; bj < 2; ++bj)
; #pragma unroll
;                     for (int n = 0; n < 2; ++n) s += (y[bj][n][0] + y[bj][n][1]) + (y[bj][n][2] + y[bj][n][3]);
;                 s += __shfl_xor(s, 16); s += __shfl_xor(s, 32);
;                 const float mean = s * (1.f / 64.f);
;                 float q = 0.f;
; #pragma unroll
;                 for (int bj = 0; bj < 2; ++bj)
; #pragma unroll
;                     for (int n = 0; n < 2; ++n) { y[bj][n] = y[bj][n] - mean; q += (y[bj][n][0] * y[bj][n][0] + y[bj][n][1] * y[bj][n][1]) + (y[bj][n][2] * y[bj][n][2] + y[bj][n][3] * y[bj][n][3]); }
;                 q += __shfl_xor(q, 16); q += __shfl_xor(q, 32);
;                 const float rs = rsqrtf(q * (1.f / 64.f) + 64e-5f);
; #pragma unroll
;                 for (int bj = 0; bj < 2; ++bj) {
;                     f32x4 o[2];
; #pragma unroll
;                     for (int n = 0; n < 2; ++n) {
;                         const f32x4 lw = *(const GAS f32x4*)(ln_w + colb + 32 * bj + 4 * n), lb = *(const GAS f32x4*)(ln_b + colb + 32 * bj + 4 * n);
;                         o[n] = (y[bj][n] * rs * lw + lb + v[bj][n] * bs) * acc[ai][bj][m][n];
;                     }
;                     *(GAS u32x4*)(YG + off + 32 * bj) = pack8(o[0], o[1]);
	v_add_f32_e32 v89, v89, v91
	v_fmac_f32_e32 v120, 0xbc800000, v89
	v_fmac_f32_e32 v121, 0xbc800000, v89
	v_fmac_f32_e32 v99, 0xbc800000, v89
	v_fmac_f32_e32 v124, 0xbc800000, v89
	v_fmac_f32_e32 v125, 0xbc800000, v89
	v_fmac_f32_e32 v123, 0xbc800000, v89
	v_fmac_f32_e32 v98, 0xbc800000, v89
	v_fmac_f32_e32 v122, 0xbc800000, v89
	v_fmac_f32_e32 v84, 0xbc800000, v89
	v_fmac_f32_e32 v86, 0xbc800000, v89
	v_mov_b32_e32 v148, v99
	v_mov_b32_e32 v149, v121
	v_mov_b32_e32 v99, v120
	v_mov_b32_e32 v120, v123
	v_mov_b32_e32 v121, v125
	v_mov_b32_e32 v123, v124
	v_fmac_f32_e32 v85, 0xbc800000, v89
	v_fmac_f32_e32 v87, 0xbc800000, v89
	v_mul_f32_e32 v116, v84, v84
	v_mul_f32_e32 v124, v86, v86
	v_mul_f32_e32 v150, v148, v148
	v_mul_f32_e32 v151, v149, v149
	v_mul_f32_e32 v162, v98, v98
	v_mul_f32_e32 v163, v99, v99
	v_mul_f32_e32 v164, v120, v120
	v_mul_f32_e32 v165, v121, v121
	v_mul_f32_e32 v166, v122, v122
	v_mul_f32_e32 v167, v123, v123
	v_fmac_f32_e32 v92, 0xbc800000, v89
	v_fmac_f32_e32 v88, 0xbc800000, v89
	v_fma_f32 v117, v85, v85, v116
	v_fma_f32 v116, v84, v84, v116
	v_fma_f32 v125, v87, v87, v124
	v_fma_f32 v124, v86, v86, v124
	v_pk_mov_b32 v[168:169], v[162:163], v[150:151] op_sel:[1,0]
	v_mov_b32_e32 v163, v151
	v_pk_mov_b32 v[150:151], v[166:167], v[164:165] op_sel:[1,0]
	v_mov_b32_e32 v167, v165
	v_mul_f32_e32 v116, v88, v88
	v_mul_f32_e32 v124, v92, v92
	v_add_f32_e32 v162, v168, v162
	v_add_f32_e32 v163, v169, v163
	v_add_f32_e32 v150, v150, v166
	v_add_f32_e32 v151, v151, v167
	v_fmac_f32_e32 v94, 0xbc800000, v89
	v_fmac_f32_e32 v90, 0xbc800000, v89
	v_add_f32_e32 v116, v116, v124
	v_add_f32_e32 v117, v117, v125
	v_add_f32_e32 v124, v162, v162
	v_add_f32_e32 v125, v162, v163
	v_add_f32_e32 v151, v150, v151
	v_add_f32_e32 v150, v150, v150
	v_mul_f32_e32 v124, v90, v90
	v_mul_f32_e32 v150, v94, v94
	v_add_f32_e32 v124, v124, v150
	v_add_f32_e32 v125, v125, v151
	s_waitcnt vmcnt(0)
	v_lshlrev_b32_e32 v150, 16, v82
	v_add_f32_e32 v116, v116, v124
	v_add_f32_e32 v117, v117, v125
	v_lshl_add_u64 v[124:125], s[20:21], 0, v[96:97]
	v_add_f32_e32 v89, v116, v117
	ds_bpermute_b32 v91, v154, v89
	v_lshlrev_b32_e32 v96, 16, v80
	v_and_b32_e32 v97, 0xffff0000, v80
	v_lshlrev_b32_e32 v80, 16, v81
	v_and_b32_e32 v81, 0xffff0000, v81
	s_waitcnt lgkmcnt(0)
	v_add_f32_e32 v89, v89, v91
	ds_bpermute_b32 v91, v155, v89
	v_and_b32_e32 v151, 0xffff0000, v82
	v_lshlrev_b32_e32 v82, 16, v83
	v_and_b32_e32 v83, 0xffff0000, v83
	global_load_dwordx4 v[116:119], v[118:119], off offset:64
	s_waitcnt lgkmcnt(0)
	v_add_f32_e32 v89, v89, v91
	v_fmamk_f32 v89, v89, 0x3c800000, v160
	v_mul_f32_e32 v91, 0x4b800000, v89
	v_cmp_gt_f32_e32 vcc, s78, v89
	s_nop 1
	v_cndmask_b32_e32 v89, v89, v91, vcc
	v_rsq_f32_e32 v89, v89
	s_nop 0
	v_mul_f32_e32 v91, 0x45800000, v89
	v_cndmask_b32_e32 v162, v89, v91, vcc
	v_mul_f32_e32 v98, v98, v162
	v_mul_f32_e32 v99, v99, v162
	v_mul_f32_e32 v148, v148, v162
	v_mul_f32_e32 v149, v149, v162
	v_mul_f32_e32 v122, v122, v162
	v_mul_f32_e32 v123, v123, v162
	v_mul_f32_e32 v120, v120, v162
	v_mul_f32_e32 v121, v121, v162
	v_fma_f32 v106, v106, v148, v114
	v_fma_f32 v107, v107, v149, v115
	v_fma_f32 v98, v104, v98, v112
	v_fma_f32 v99, v105, v99, v113
	v_fma_f32 v102, v102, v120, v110
	v_fma_f32 v103, v103, v121, v111
	v_fma_f32 v100, v100, v122, v108
	v_fma_f32 v101, v101, v123, v109
	v_fma_f32 v96, v126, v96, v98
	v_fma_f32 v97, v126, v97, v99
	v_fma_f32 v80, v126, v80, v106
	v_fma_f32 v81, v126, v81, v107
	v_fma_f32 v98, v126, v150, v100
	v_fma_f32 v99, v126, v151, v101
	v_fma_f32 v82, v126, v82, v102
	v_fma_f32 v83, v126, v83, v103
	v_mul_f32_e32 v78, v78, v80
	v_mul_f32_e32 v79, v79, v81
	v_mul_f32_e32 v76, v76, v96
	v_mul_f32_e32 v77, v77, v97
	v_mul_f32_e32 v80, v74, v82
	v_mul_f32_e32 v81, v75, v83
	v_mul_f32_e32 v74, v72, v98
	v_mul_f32_e32 v75, v73, v99
	v_cvt_pk_bf16_f32 v72, v76, v77
	v_cvt_pk_bf16_f32 v73, v78, v79
	v_cvt_pk_bf16_f32 v74, v74, v75
	v_cvt_pk_bf16_f32 v75, v80, v81
	global_store_dwordx4 v[124:125], v[72:75], off
	global_load_dwordx4 v[72:75], v[142:143], off offset:128
	s_nop 0
	global_load_dwordx4 v[76:79], v[140:141], off offset:128
	global_load_dwordx4 v[96:99], v[140:141], off offset:144
	global_load_dwordx4 v[100:103], v[142:143], off offset:144
	v_mov_b32_e32 v89, v92
	v_mov_b32_e32 v91, v94
	v_mul_f32_e32 v84, v84, v162
	v_mul_f32_e32 v85, v85, v162
	v_mul_f32_e32 v86, v86, v162
	v_mul_f32_e32 v87, v87, v162
	v_mul_f32_e32 v88, v88, v162
	v_mul_f32_e32 v89, v89, v162
	v_mul_f32_e32 v90, v90, v162
	v_mul_f32_e32 v91, v91, v162
	v_add_u32_e32 v82, 0x80, v146
	v_ashrrev_i32_e32 v83, 31, v82
	v_lshlrev_b64 v[80:81], 10, v[82:83]
	v_lshl_add_u64 v[80:81], v[80:81], 0, v[144:145]
	v_lshlrev_b64 v[80:81], 1, v[80:81]
	v_lshl_add_u64 v[104:105], s[16:17], 0, v[80:81]
	s_waitcnt vmcnt(5)
	v_lshlrev_b32_e32 v106, 16, v116
	v_and_b32_e32 v107, 0xffff0000, v116
	v_lshlrev_b32_e32 v108, 16, v117
	v_and_b32_e32 v109, 0xffff0000, v117
	v_lshlrev_b32_e32 v110, 16, v118
	v_and_b32_e32 v111, 0xffff0000, v118
	v_lshlrev_b32_e32 v112, 16, v119
	v_and_b32_e32 v113, 0xffff0000, v119
	s_waitcnt vmcnt(2)
	v_fma_f32 v74, v78, v86, v74
	v_fma_f32 v75, v79, v87, v75
	v_fma_f32 v72, v76, v84, v72
	v_fma_f32 v73, v77, v85, v73
	s_waitcnt vmcnt(0)
; #define GAS __attribute__((address_space(1)))
;     __device__ __forceinline__ void operator()(const Acc& acc, const Unit& u, int wr, int wc, int fr, int fq) const {
;     ...
;                 const int row = row0 + ai * HALF + m * 16;
;                 const size_t off = (size_t)row * D + colb;
;                 f32x4 y[2][2], v[2][2];
; #pragma unroll
;                 for (int bj = 0; bj < 2; ++bj) { unpack8(*(const GAS u32x4*)(Y + off + 32 * bj), y[bj][0], y[bj][1]); unpack8(*(const GAS u32x4*)(V + off + 32 * bj), v[bj][0], v[bj][1]); }
;                 const float bs = BON[(size_t)row * 16 + head];
;                 float s = 0.f;
; #pragma unroll
;                 for (int bj = 0; bj < 2; ++bj)
; #pragma unroll
;                     for (int n = 0; n < 2; ++n) s += (y[bj][n][0] + y[bj][n][1]) + (y[bj][n][2] + y[bj][n][3]);
;                 s += __shfl_xor(s, 16); s += __shfl_xor(s, 32);
;                 const float mean = s * (1.f / 64.f);
;                 float q = 0.f;
; #pragma unroll
;                 for (int bj = 0; bj < 2; ++bj)
; #pragma unroll
;                     for (int n = 0; n < 2; ++n) { y[bj][n] = y[bj][n] - mean; q += (y[bj][n][0] * y[bj][n][0] + y[bj][n][1] * y[bj][n][1]) + (y[bj][n][2] * y[bj][n][2] + y[bj][n][3] * y[bj][n][3]); }
;                 q += __shfl_xor(q, 16); q += __shfl_xor(q, 32);
;                 const float rs = rsqrtf(q * (1.f / 64.f) + 64e-5f);
; #pragma unroll
;                 for (int bj = 0; bj < 2; ++bj) {
;                     f32x4 o[2];
; #pragma unroll
;                     for (int n = 0; n < 2; ++n) {
;                         const f32x4 lw = *(const GAS f32x4*)(ln_w + colb + 32 * bj + 4 * n), lb = *(const GAS f32x4*)(ln_b + colb + 32 * bj + 4 * n);
;                         o[n] = (y[bj][n] * rs * lw + lb + v[bj][n] * bs) * acc[ai][bj][m][n];
;                     }
;                     *(GAS u32x4*)(YG + off + 32 * bj) = pack8(o[0], o[1]);
	v_fma_f32 v76, v98, v90, v102
	v_fma_f32 v77, v99, v91, v103
	v_fma_f32 v78, v96, v88, v100
	v_fma_f32 v79, v97, v89, v101
	v_fma_f32 v72, v126, v106, v72
	v_fma_f32 v73, v126, v107, v73
	v_fma_f32 v74, v126, v108, v74
	v_fma_f32 v75, v126, v109, v75
	v_fma_f32 v78, v126, v110, v78
	v_fma_f32 v79, v126, v111, v79
	v_fma_f32 v76, v126, v112, v76
	v_fma_f32 v77, v126, v113, v77
	v_mul_f32_e32 v70, v70, v74
	v_mul_f32_e32 v71, v71, v75
	v_mul_f32_e32 v68, v68, v72
	v_mul_f32_e32 v69, v69, v73
	v_mul_f32_e32 v72, v66, v76
	v_mul_f32_e32 v73, v67, v77
	v_mul_f32_e32 v66, v64, v78
	v_mul_f32_e32 v67, v65, v79
	v_cvt_pk_bf16_f32 v64, v68, v69
	v_cvt_pk_bf16_f32 v65, v70, v71
	v_cvt_pk_bf16_f32 v66, v66, v67
	v_cvt_pk_bf16_f32 v67, v72, v73
	global_store_dwordx4 v[124:125], v[64:67], off offset:64
	global_load_dwordx4 v[72:75], v[104:105], off offset:64
	global_load_dwordx4 v[84:87], v[104:105], off
	v_lshlrev_b64 v[64:65], 6, v[82:83]
	v_lshl_add_u64 v[100:101], s[18:19], 0, v[64:65]
	v_lshl_add_u64 v[102:103], s[6:7], 0, v[80:81]
	global_load_dwordx4 v[64:67], v[102:103], off
	v_lshl_add_u64 v[100:101], v[100:101], 0, s[34:35]
	s_waitcnt vmcnt(2)
	v_lshlrev_b32_e32 v68, 16, v72
	s_waitcnt vmcnt(1)
	v_lshlrev_b32_e32 v83, 16, v85
	v_lshlrev_b32_e32 v82, 16, v84
	v_and_b32_e32 v105, 0xffff0000, v85
	v_and_b32_e32 v104, 0xffff0000, v84
	v_lshlrev_b32_e32 v107, 16, v87
	v_lshlrev_b32_e32 v106, 16, v86
	v_and_b32_e32 v109, 0xffff0000, v87
	v_and_b32_e32 v108, 0xffff0000, v86
	v_add_f32_e32 v84, v82, v104
	v_add_f32_e32 v85, v83, v105
	v_add_f32_e32 v86, v106, v108
	v_add_f32_e32 v87, v107, v109
	v_and_b32_e32 v69, 0xffff0000, v72
	v_lshlrev_b32_e32 v70, 16, v73
	v_and_b32_e32 v71, 0xffff0000, v73
	v_add_f32_e32 v73, v84, v85
	v_add_f32_e32 v84, v86, v86
	v_add_f32_e32 v85, v86, v87
	v_lshlrev_b32_e32 v72, 16, v74
	v_and_b32_e32 v76, 0xffff0000, v74
	v_lshlrev_b32_e32 v74, 16, v75
	v_and_b32_e32 v78, 0xffff0000, v75
	v_add_f32_e32 v75, v68, v69
	v_add_f32_e32 v79, v70, v71
	v_add_f32_e32 v77, 0, v73
	v_mov_b32_e32 v73, v85
	v_add_f32_e32 v86, v74, v78
	v_add_f32_e32 v87, v75, v79
	v_add_f32_e32 v84, v72, v76
	v_add_f32_e32 v85, v73, v77
	s_nop 0
	v_add_f32_e32 v84, v84, v86
	v_add_f32_e32 v85, v85, v87
	s_nop 0
	v_add_f32_e32 v73, v84, v85
	global_load_dwordx4 v[84:87], v[140:141], off offset:16
	global_load_dwordx4 v[88:91], v[140:141], off
	global_load_dwordx4 v[92:95], v[142:143], off offset:16
	global_load_dwordx4 v[96:99], v[142:143], off
	flat_load_dword v110, v[100:101]
	ds_bpermute_b32 v75, v154, v73
	s_waitcnt lgkmcnt(0)
	v_add_f32_e32 v73, v73, v75
	ds_bpermute_b32 v75, v155, v73
	s_waitcnt lgkmcnt(0)
	v_add_f32_e32 v73, v73, v75
	v_fmac_f32_e32 v104, 0xbc800000, v73
	v_fmac_f32_e32 v105, 0xbc800000, v73
	v_fmac_f32_e32 v83, 0xbc800000, v73
	v_fmac_f32_e32 v108, 0xbc800000, v73
	v_fmac_f32_e32 v109, 0xbc800000, v73
	v_fmac_f32_e32 v107, 0xbc800000, v73
	v_fmac_f32_e32 v82, 0xbc800000, v73
	v_fmac_f32_e32 v106, 0xbc800000, v73
	v_fmac_f32_e32 v68, 0xbc800000, v73
	v_fmac_f32_e32 v70, 0xbc800000, v73
	v_mov_b32_e32 v112, v83
	v_mov_b32_e32 v113, v105
	v_mov_b32_e32 v83, v104
	v_mov_b32_e32 v104, v107
	v_mov_b32_e32 v105, v109
	v_mov_b32_e32 v107, v108
	v_fmac_f32_e32 v69, 0xbc800000, v73
	v_fmac_f32_e32 v71, 0xbc800000, v73
	v_mul_f32_e32 v100, v68, v68
	v_mul_f32_e32 v108, v70, v70
	v_mul_f32_e32 v114, v112, v112
	v_mul_f32_e32 v115, v113, v113
	v_mul_f32_e32 v116, v82, v82
	v_mul_f32_e32 v117, v83, v83
	v_mul_f32_e32 v118, v104, v104
	v_mul_f32_e32 v119, v105, v105
	v_mul_f32_e32 v120, v106, v106
	v_mul_f32_e32 v121, v107, v107
	v_fmac_f32_e32 v76, 0xbc800000, v73
	v_fmac_f32_e32 v72, 0xbc800000, v73
	v_fma_f32 v101, v69, v69, v100
	v_fma_f32 v100, v68, v68, v100
	v_fma_f32 v109, v71, v71, v108
	v_fma_f32 v108, v70, v70, v108
	v_pk_mov_b32 v[122:123], v[116:117], v[114:115] op_sel:[1,0]
	v_mov_b32_e32 v117, v115
	v_pk_mov_b32 v[114:115], v[120:121], v[118:119] op_sel:[1,0]
	v_mov_b32_e32 v121, v119
	v_mul_f32_e32 v100, v72, v72
	v_mul_f32_e32 v108, v76, v76
	v_add_f32_e32 v116, v122, v116
	v_add_f32_e32 v117, v123, v117
	v_add_f32_e32 v114, v114, v120
	v_add_f32_e32 v115, v115, v121
	v_fmac_f32_e32 v78, 0xbc800000, v73
	v_fmac_f32_e32 v74, 0xbc800000, v73
	v_add_f32_e32 v100, v100, v108
	v_add_f32_e32 v101, v101, v109
	v_add_f32_e32 v108, v116, v116
	v_add_f32_e32 v109, v116, v117
	v_add_f32_e32 v115, v114, v115
	v_add_f32_e32 v114, v114, v114
	v_mul_f32_e32 v108, v74, v74
	v_mul_f32_e32 v114, v78, v78
	v_add_f32_e32 v108, v108, v114
	v_add_f32_e32 v109, v109, v115
	s_waitcnt vmcnt(0)
	v_lshlrev_b32_e32 v114, 16, v66
	v_add_f32_e32 v100, v100, v108
	v_add_f32_e32 v101, v101, v109
	v_lshl_add_u64 v[108:109], s[20:21], 0, v[80:81]
	v_add_f32_e32 v73, v100, v101
	ds_bpermute_b32 v75, v154, v73
	v_lshlrev_b32_e32 v80, 16, v64
	v_and_b32_e32 v81, 0xffff0000, v64
	v_lshlrev_b32_e32 v64, 16, v65
	v_and_b32_e32 v65, 0xffff0000, v65
	s_waitcnt lgkmcnt(0)
	v_add_f32_e32 v73, v73, v75
	ds_bpermute_b32 v75, v155, v73
	v_and_b32_e32 v115, 0xffff0000, v66
	v_lshlrev_b32_e32 v66, 16, v67
	v_and_b32_e32 v67, 0xffff0000, v67
	global_load_dwordx4 v[100:103], v[102:103], off offset:64
	s_waitcnt lgkmcnt(0)
; #define GAS __attribute__((address_space(1)))
;     __device__ __forceinline__ void operator()(const Acc& acc, const Unit& u, int wr, int wc, int fr, int fq) const {
;     ...
;                 const int row = row0 + ai * HALF + m * 16;
;                 const size_t off = (size_t)row * D + colb;
;                 f32x4 y[2][2], v[2][2];
; #pragma unroll
;                 for (int bj = 0; bj < 2; ++bj) { unpack8(*(const GAS u32x4*)(Y + off + 32 * bj), y[bj][0], y[bj][1]); unpack8(*(const GAS u32x4*)(V + off + 32 * bj), v[bj][0], v[bj][1]); }
;                 const float bs = BON[(size_t)row * 16 + head];
;                 float s = 0.f;
; #pragma unroll
;                 for (int bj = 0; bj < 2; ++bj)
; #pragma unroll
;                     for (int n = 0; n < 2; ++n) s += (y[bj][n][0] + y[bj][n][1]) + (y[bj][n][2] + y[bj][n][3]);
;                 s += __shfl_xor(s, 16); s += __shfl_xor(s, 32);
;                 const float mean = s * (1.f / 64.f);
;                 float q = 0.f;
; #pragma unroll
;                 for (int bj = 0; bj < 2; ++bj)
; #pragma unroll
;                     for (int n = 0; n < 2; ++n) { y[bj][n] = y[bj][n] - mean; q += (y[bj][n][0] * y[bj][n][0] + y[bj][n][1] * y[bj][n][1]) + (y[bj][n][2] * y[bj][n][2] + y[bj][n][3] * y[bj][n][3]); }
;                 q += __shfl_xor(q, 16); q += __shfl_xor(q, 32);
;                 const float rs = rsqrtf(q * (1.f / 64.f) + 64e-5f);
; #pragma unroll
;                 for (int bj = 0; bj < 2; ++bj) {
;                     f32x4 o[2];
; #pragma unroll
;                     for (int n = 0; n < 2; ++n) {
;                         const f32x4 lw = *(const GAS f32x4*)(ln_w + colb + 32 * bj + 4 * n), lb = *(const GAS f32x4*)(ln_b + colb + 32 * bj + 4 * n);
;                         o[n] = (y[bj][n] * rs * lw + lb + v[bj][n] * bs) * acc[ai][bj][m][n];
;                     }
;                     *(GAS u32x4*)(YG + off + 32 * bj) = pack8(o[0], o[1]);
	v_add_f32_e32 v73, v73, v75
	v_fmamk_f32 v73, v73, 0x3c800000, v160
	v_mul_f32_e32 v75, 0x4b800000, v73
	v_cmp_gt_f32_e32 vcc, s78, v73
	s_nop 1
	v_cndmask_b32_e32 v73, v73, v75, vcc
	v_rsq_f32_e32 v73, v73
	s_nop 0
	v_mul_f32_e32 v75, 0x45800000, v73
	v_cndmask_b32_e32 v116, v73, v75, vcc
	v_mul_f32_e32 v82, v82, v116
	v_mul_f32_e32 v83, v83, v116
	v_mul_f32_e32 v112, v112, v116
	v_mul_f32_e32 v113, v113, v116
	v_mul_f32_e32 v106, v106, v116
	v_mul_f32_e32 v107, v107, v116
	v_mul_f32_e32 v104, v104, v116
	v_mul_f32_e32 v105, v105, v116
	v_fma_f32 v90, v90, v112, v98
	v_fma_f32 v91, v91, v113, v99
	v_fma_f32 v82, v88, v82, v96
	v_fma_f32 v83, v89, v83, v97
	v_fma_f32 v86, v86, v104, v94
	v_fma_f32 v87, v87, v105, v95
	v_fma_f32 v84, v84, v106, v92
	v_fma_f32 v85, v85, v107, v93
	v_fma_f32 v80, v110, v80, v82
	v_fma_f32 v81, v110, v81, v83
	v_fma_f32 v64, v110, v64, v90
	v_fma_f32 v65, v110, v65, v91
	v_fma_f32 v82, v110, v114, v84
	v_fma_f32 v83, v110, v115, v85
	v_fma_f32 v66, v110, v66, v86
	v_fma_f32 v67, v110, v67, v87
	v_mul_f32_e32 v62, v62, v64
	v_mul_f32_e32 v63, v63, v65
	v_mul_f32_e32 v60, v60, v80
	v_mul_f32_e32 v61, v61, v81
	v_mul_f32_e32 v64, v58, v66
	v_mul_f32_e32 v65, v59, v67
	v_mul_f32_e32 v58, v56, v82
	v_mul_f32_e32 v59, v57, v83
	v_cvt_pk_bf16_f32 v56, v60, v61
	v_cvt_pk_bf16_f32 v57, v62, v63
	v_cvt_pk_bf16_f32 v58, v58, v59
	v_cvt_pk_bf16_f32 v59, v64, v65
	global_store_dwordx4 v[108:109], v[56:59], off
	global_load_dwordx4 v[56:59], v[142:143], off offset:128
	s_nop 0
	global_load_dwordx4 v[60:63], v[140:141], off offset:128
	global_load_dwordx4 v[80:83], v[140:141], off offset:144
	global_load_dwordx4 v[84:87], v[142:143], off offset:144
	v_mov_b32_e32 v73, v76
	v_mov_b32_e32 v75, v78
	v_mul_f32_e32 v68, v68, v116
	v_mul_f32_e32 v69, v69, v116
	v_mul_f32_e32 v70, v70, v116
	v_mul_f32_e32 v71, v71, v116
	v_mul_f32_e32 v72, v72, v116
	v_mul_f32_e32 v73, v73, v116
	v_mul_f32_e32 v74, v74, v116
	v_mul_f32_e32 v75, v75, v116
	v_add_u32_e32 v66, 0x90, v146
	v_ashrrev_i32_e32 v67, 31, v66
	v_lshlrev_b64 v[64:65], 10, v[66:67]
	v_lshl_add_u64 v[64:65], v[64:65], 0, v[144:145]
	v_lshlrev_b64 v[64:65], 1, v[64:65]
	v_lshl_add_u64 v[88:89], s[16:17], 0, v[64:65]
	s_waitcnt vmcnt(5)
	v_lshlrev_b32_e32 v90, 16, v100
	v_and_b32_e32 v91, 0xffff0000, v100
	v_lshlrev_b32_e32 v92, 16, v101
	v_and_b32_e32 v93, 0xffff0000, v101
	v_lshlrev_b32_e32 v94, 16, v102
	v_and_b32_e32 v95, 0xffff0000, v102
	v_lshlrev_b32_e32 v96, 16, v103
	v_and_b32_e32 v97, 0xffff0000, v103
	s_waitcnt vmcnt(2)
	v_fma_f32 v58, v62, v70, v58
	v_fma_f32 v59, v63, v71, v59
	v_fma_f32 v56, v60, v68, v56
	v_fma_f32 v57, v61, v69, v57
	s_waitcnt vmcnt(0)
	v_fma_f32 v60, v82, v74, v86
	v_fma_f32 v61, v83, v75, v87
	v_fma_f32 v62, v80, v72, v84
	v_fma_f32 v63, v81, v73, v85
	v_fma_f32 v56, v110, v90, v56
	v_fma_f32 v57, v110, v91, v57
	v_fma_f32 v58, v110, v92, v58
	v_fma_f32 v59, v110, v93, v59
	v_fma_f32 v62, v110, v94, v62
	v_fma_f32 v63, v110, v95, v63
	v_fma_f32 v60, v110, v96, v60
	v_fma_f32 v61, v110, v97, v61
	v_mul_f32_e32 v54, v54, v58
	v_mul_f32_e32 v55, v55, v59
	v_mul_f32_e32 v52, v52, v56
	v_mul_f32_e32 v53, v53, v57
	v_mul_f32_e32 v56, v50, v60
	v_mul_f32_e32 v57, v51, v61
	v_mul_f32_e32 v50, v48, v62
	v_mul_f32_e32 v51, v49, v63
	v_cvt_pk_bf16_f32 v48, v52, v53
	v_cvt_pk_bf16_f32 v49, v54, v55
	v_cvt_pk_bf16_f32 v50, v50, v51
	v_cvt_pk_bf16_f32 v51, v56, v57
	global_store_dwordx4 v[108:109], v[48:51], off offset:64
	global_load_dwordx4 v[56:59], v[88:89], off offset:64
	global_load_dwordx4 v[68:71], v[88:89], off
	v_lshlrev_b64 v[48:49], 6, v[66:67]
	v_lshl_add_u64 v[84:85], s[18:19], 0, v[48:49]
	v_lshl_add_u64 v[86:87], s[6:7], 0, v[64:65]
	global_load_dwordx4 v[48:51], v[86:87], off
	v_lshl_add_u64 v[84:85], v[84:85], 0, s[34:35]
	s_waitcnt vmcnt(2)
	v_lshlrev_b32_e32 v52, 16, v56
	s_waitcnt vmcnt(1)
	v_lshlrev_b32_e32 v67, 16, v69
	v_lshlrev_b32_e32 v66, 16, v68
	v_and_b32_e32 v89, 0xffff0000, v69
	v_and_b32_e32 v88, 0xffff0000, v68
	v_lshlrev_b32_e32 v91, 16, v71
	v_lshlrev_b32_e32 v90, 16, v70
	v_and_b32_e32 v93, 0xffff0000, v71
	v_and_b32_e32 v92, 0xffff0000, v70
	v_add_f32_e32 v68, v66, v88
	v_add_f32_e32 v69, v67, v89
	v_add_f32_e32 v70, v90, v92
	v_add_f32_e32 v71, v91, v93
	v_and_b32_e32 v53, 0xffff0000, v56
	v_lshlrev_b32_e32 v54, 16, v57
	v_and_b32_e32 v55, 0xffff0000, v57
	v_add_f32_e32 v57, v68, v69
	v_add_f32_e32 v68, v70, v70
	v_add_f32_e32 v69, v70, v71
	v_lshlrev_b32_e32 v56, 16, v58
	v_and_b32_e32 v60, 0xffff0000, v58
	v_lshlrev_b32_e32 v58, 16, v59
	v_and_b32_e32 v62, 0xffff0000, v59
	v_add_f32_e32 v59, v52, v53
	v_add_f32_e32 v63, v54, v55
	v_add_f32_e32 v61, 0, v57
	v_mov_b32_e32 v57, v69
	v_add_f32_e32 v70, v58, v62
	v_add_f32_e32 v71, v59, v63
	v_add_f32_e32 v68, v56, v60
	v_add_f32_e32 v69, v57, v61
	s_nop 0
	v_add_f32_e32 v68, v68, v70
	v_add_f32_e32 v69, v69, v71
	s_nop 0
	v_add_f32_e32 v57, v68, v69
	global_load_dwordx4 v[68:71], v[140:141], off offset:16
	global_load_dwordx4 v[72:75], v[140:141], off
	global_load_dwordx4 v[76:79], v[142:143], off offset:16
	global_load_dwordx4 v[80:83], v[142:143], off
	flat_load_dword v94, v[84:85]
	ds_bpermute_b32 v59, v154, v57
	s_waitcnt lgkmcnt(0)
	v_add_f32_e32 v57, v57, v59
	ds_bpermute_b32 v59, v155, v57
	s_waitcnt lgkmcnt(0)
; #define GAS __attribute__((address_space(1)))
;     __device__ __forceinline__ void operator()(const Acc& acc, const Unit& u, int wr, int wc, int fr, int fq) const {
;     ...
;                 const int row = row0 + ai * HALF + m * 16;
;                 const size_t off = (size_t)row * D + colb;
;                 f32x4 y[2][2], v[2][2];
; #pragma unroll
;                 for (int bj = 0; bj < 2; ++bj) { unpack8(*(const GAS u32x4*)(Y + off + 32 * bj), y[bj][0], y[bj][1]); unpack8(*(const GAS u32x4*)(V + off + 32 * bj), v[bj][0], v[bj][1]); }
;                 const float bs = BON[(size_t)row * 16 + head];
;                 float s = 0.f;
; #pragma unroll
;                 for (int bj = 0; bj < 2; ++bj)
; #pragma unroll
;                     for (int n = 0; n < 2; ++n) s += (y[bj][n][0] + y[bj][n][1]) + (y[bj][n][2] + y[bj][n][3]);
;                 s += __shfl_xor(s, 16); s += __shfl_xor(s, 32);
;                 const float mean = s * (1.f / 64.f);
;                 float q = 0.f;
; #pragma unroll
;                 for (int bj = 0; bj < 2; ++bj)
; #pragma unroll
;                     for (int n = 0; n < 2; ++n) { y[bj][n] = y[bj][n] - mean; q += (y[bj][n][0] * y[bj][n][0] + y[bj][n][1] * y[bj][n][1]) + (y[bj][n][2] * y[bj][n][2] + y[bj][n][3] * y[bj][n][3]); }
;                 q += __shfl_xor(q, 16); q += __shfl_xor(q, 32);
;                 const float rs = rsqrtf(q * (1.f / 64.f) + 64e-5f);
; #pragma unroll
;                 for (int bj = 0; bj < 2; ++bj) {
;                     f32x4 o[2];
; #pragma unroll
;                     for (int n = 0; n < 2; ++n) {
;                         const f32x4 lw = *(const GAS f32x4*)(ln_w + colb + 32 * bj + 4 * n), lb = *(const GAS f32x4*)(ln_b + colb + 32 * bj + 4 * n);
;                         o[n] = (y[bj][n] * rs * lw + lb + v[bj][n] * bs) * acc[ai][bj][m][n];
;                     }
;                     *(GAS u32x4*)(YG + off + 32 * bj) = pack8(o[0], o[1]);
	v_add_f32_e32 v57, v57, v59
	v_fmac_f32_e32 v88, 0xbc800000, v57
	v_fmac_f32_e32 v89, 0xbc800000, v57
	v_fmac_f32_e32 v67, 0xbc800000, v57
	v_fmac_f32_e32 v92, 0xbc800000, v57
	v_fmac_f32_e32 v93, 0xbc800000, v57
	v_fmac_f32_e32 v91, 0xbc800000, v57
	v_fmac_f32_e32 v66, 0xbc800000, v57
	v_fmac_f32_e32 v90, 0xbc800000, v57
	v_fmac_f32_e32 v52, 0xbc800000, v57
	v_fmac_f32_e32 v54, 0xbc800000, v57
	v_mov_b32_e32 v96, v67
	v_mov_b32_e32 v97, v89
	v_mov_b32_e32 v67, v88
	v_mov_b32_e32 v88, v91
	v_mov_b32_e32 v89, v93
	v_mov_b32_e32 v91, v92
	v_fmac_f32_e32 v53, 0xbc800000, v57
	v_fmac_f32_e32 v55, 0xbc800000, v57
	v_mul_f32_e32 v84, v52, v52
	v_mul_f32_e32 v92, v54, v54
	v_mul_f32_e32 v98, v96, v96
	v_mul_f32_e32 v99, v97, v97
	v_mul_f32_e32 v100, v66, v66
	v_mul_f32_e32 v101, v67, v67
	v_mul_f32_e32 v102, v88, v88
	v_mul_f32_e32 v103, v89, v89
	v_mul_f32_e32 v104, v90, v90
	v_mul_f32_e32 v105, v91, v91
	v_fmac_f32_e32 v60, 0xbc800000, v57
	v_fmac_f32_e32 v56, 0xbc800000, v57
	v_fma_f32 v85, v53, v53, v84
	v_fma_f32 v84, v52, v52, v84
	v_fma_f32 v93, v55, v55, v92
	v_fma_f32 v92, v54, v54, v92
	v_pk_mov_b32 v[106:107], v[100:101], v[98:99] op_sel:[1,0]
	v_mov_b32_e32 v101, v99
	v_pk_mov_b32 v[98:99], v[104:105], v[102:103] op_sel:[1,0]
	v_mov_b32_e32 v105, v103
	v_mul_f32_e32 v84, v56, v56
	v_mul_f32_e32 v92, v60, v60
	v_add_f32_e32 v100, v106, v100
	v_add_f32_e32 v101, v107, v101
	v_add_f32_e32 v98, v98, v104
	v_add_f32_e32 v99, v99, v105
	v_fmac_f32_e32 v62, 0xbc800000, v57
	v_fmac_f32_e32 v58, 0xbc800000, v57
	v_add_f32_e32 v84, v84, v92
	v_add_f32_e32 v85, v85, v93
	v_add_f32_e32 v92, v100, v100
	v_add_f32_e32 v93, v100, v101
	v_add_f32_e32 v99, v98, v99
	v_add_f32_e32 v98, v98, v98
	v_mul_f32_e32 v92, v58, v58
	v_mul_f32_e32 v98, v62, v62
	v_add_f32_e32 v92, v92, v98
	v_add_f32_e32 v93, v93, v99
	s_waitcnt vmcnt(0)
	v_lshlrev_b32_e32 v98, 16, v50
	v_add_f32_e32 v84, v84, v92
	v_add_f32_e32 v85, v85, v93
	v_lshl_add_u64 v[92:93], s[20:21], 0, v[64:65]
	v_add_f32_e32 v57, v84, v85
	ds_bpermute_b32 v59, v154, v57
	v_lshlrev_b32_e32 v64, 16, v48
	v_and_b32_e32 v65, 0xffff0000, v48
	v_lshlrev_b32_e32 v48, 16, v49
	v_and_b32_e32 v49, 0xffff0000, v49
	s_waitcnt lgkmcnt(0)
	v_add_f32_e32 v57, v57, v59
	ds_bpermute_b32 v59, v155, v57
	v_and_b32_e32 v99, 0xffff0000, v50
	v_lshlrev_b32_e32 v50, 16, v51
	v_and_b32_e32 v51, 0xffff0000, v51
	global_load_dwordx4 v[84:87], v[86:87], off offset:64
	s_waitcnt lgkmcnt(0)
	v_add_f32_e32 v57, v57, v59
	v_fmamk_f32 v57, v57, 0x3c800000, v160
	v_mul_f32_e32 v59, 0x4b800000, v57
	v_cmp_gt_f32_e32 vcc, s78, v57
	s_nop 1
	v_cndmask_b32_e32 v57, v57, v59, vcc
	v_rsq_f32_e32 v57, v57
	s_nop 0
	v_mul_f32_e32 v59, 0x45800000, v57
	v_cndmask_b32_e32 v100, v57, v59, vcc
	v_mul_f32_e32 v66, v66, v100
	v_mul_f32_e32 v67, v67, v100
	v_mul_f32_e32 v96, v96, v100
	v_mul_f32_e32 v97, v97, v100
	v_mul_f32_e32 v90, v90, v100
	v_mul_f32_e32 v91, v91, v100
	v_mul_f32_e32 v88, v88, v100
	v_mul_f32_e32 v89, v89, v100
	v_fma_f32 v74, v74, v96, v82
	v_fma_f32 v75, v75, v97, v83
	v_fma_f32 v66, v72, v66, v80
	v_fma_f32 v67, v73, v67, v81
	v_fma_f32 v70, v70, v88, v78
	v_fma_f32 v71, v71, v89, v79
	v_fma_f32 v68, v68, v90, v76
	v_fma_f32 v69, v69, v91, v77
	v_fma_f32 v64, v94, v64, v66
	v_fma_f32 v65, v94, v65, v67
	v_fma_f32 v48, v94, v48, v74
	v_fma_f32 v49, v94, v49, v75
	v_fma_f32 v66, v94, v98, v68
	v_fma_f32 v67, v94, v99, v69
	v_fma_f32 v50, v94, v50, v70
	v_fma_f32 v51, v94, v51, v71
	v_mul_f32_e32 v46, v46, v48
	v_mul_f32_e32 v47, v47, v49
	v_mul_f32_e32 v44, v44, v64
	v_mul_f32_e32 v45, v45, v65
	v_mul_f32_e32 v48, v42, v50
	v_mul_f32_e32 v49, v43, v51
	v_mul_f32_e32 v42, v40, v66
	v_mul_f32_e32 v43, v41, v67
	v_cvt_pk_bf16_f32 v40, v44, v45
	v_cvt_pk_bf16_f32 v41, v46, v47
	v_cvt_pk_bf16_f32 v42, v42, v43
	v_cvt_pk_bf16_f32 v43, v48, v49
	global_store_dwordx4 v[92:93], v[40:43], off
	global_load_dwordx4 v[40:43], v[142:143], off offset:128
	s_nop 0
	global_load_dwordx4 v[44:47], v[140:141], off offset:128
	global_load_dwordx4 v[64:67], v[140:141], off offset:144
	global_load_dwordx4 v[68:71], v[142:143], off offset:144
	v_mov_b32_e32 v57, v60
	v_mov_b32_e32 v59, v62
	v_mul_f32_e32 v52, v52, v100
	v_mul_f32_e32 v53, v53, v100
	v_mul_f32_e32 v54, v54, v100
	v_mul_f32_e32 v55, v55, v100
	v_mul_f32_e32 v56, v56, v100
	v_mul_f32_e32 v57, v57, v100
	v_mul_f32_e32 v58, v58, v100
	v_mul_f32_e32 v59, v59, v100
	v_add_u32_e32 v50, 0xa0, v146
	v_ashrrev_i32_e32 v51, 31, v50
	v_lshlrev_b64 v[48:49], 10, v[50:51]
	v_lshl_add_u64 v[48:49], v[48:49], 0, v[144:145]
	v_lshlrev_b64 v[48:49], 1, v[48:49]
	v_lshl_add_u64 v[72:73], s[16:17], 0, v[48:49]
	s_waitcnt vmcnt(5)
	v_lshlrev_b32_e32 v74, 16, v84
	v_and_b32_e32 v75, 0xffff0000, v84
	v_lshlrev_b32_e32 v76, 16, v85
	v_and_b32_e32 v77, 0xffff0000, v85
	v_lshlrev_b32_e32 v78, 16, v86
	v_and_b32_e32 v79, 0xffff0000, v86
	v_lshlrev_b32_e32 v80, 16, v87
	v_and_b32_e32 v81, 0xffff0000, v87
	s_waitcnt vmcnt(2)
	v_fma_f32 v42, v46, v54, v42
	v_fma_f32 v43, v47, v55, v43
	v_fma_f32 v40, v44, v52, v40
	v_fma_f32 v41, v45, v53, v41
	s_waitcnt vmcnt(0)
; #define GAS __attribute__((address_space(1)))
;     __device__ __forceinline__ void operator()(const Acc& acc, const Unit& u, int wr, int wc, int fr, int fq) const {
;     ...
;                 const int row = row0 + ai * HALF + m * 16;
;                 const size_t off = (size_t)row * D + colb;
;                 f32x4 y[2][2], v[2][2];
; #pragma unroll
;                 for (int bj = 0; bj < 2; ++bj) { unpack8(*(const GAS u32x4*)(Y + off + 32 * bj), y[bj][0], y[bj][1]); unpack8(*(const GAS u32x4*)(V + off + 32 * bj), v[bj][0], v[bj][1]); }
;                 const float bs = BON[(size_t)row * 16 + head];
;                 float s = 0.f;
; #pragma unroll
;                 for (int bj = 0; bj < 2; ++bj)
; #pragma unroll
;                     for (int n = 0; n < 2; ++n) s += (y[bj][n][0] + y[bj][n][1]) + (y[bj][n][2] + y[bj][n][3]);
;                 s += __shfl_xor(s, 16); s += __shfl_xor(s, 32);
;                 const float mean = s * (1.f / 64.f);
;                 float q = 0.f;
; #pragma unroll
;                 for (int bj = 0; bj < 2; ++bj)
; #pragma unroll
;                     for (int n = 0; n < 2; ++n) { y[bj][n] = y[bj][n] - mean; q += (y[bj][n][0] * y[bj][n][0] + y[bj][n][1] * y[bj][n][1]) + (y[bj][n][2] * y[bj][n][2] + y[bj][n][3] * y[bj][n][3]); }
;                 q += __shfl_xor(q, 16); q += __shfl_xor(q, 32);
;                 const float rs = rsqrtf(q * (1.f / 64.f) + 64e-5f);
; #pragma unroll
;                 for (int bj = 0; bj < 2; ++bj) {
;                     f32x4 o[2];
; #pragma unroll
;                     for (int n = 0; n < 2; ++n) {
;                         const f32x4 lw = *(const GAS f32x4*)(ln_w + colb + 32 * bj + 4 * n), lb = *(const GAS f32x4*)(ln_b + colb + 32 * bj + 4 * n);
;                         o[n] = (y[bj][n] * rs * lw + lb + v[bj][n] * bs) * acc[ai][bj][m][n];
;                     }
;                     *(GAS u32x4*)(YG + off + 32 * bj) = pack8(o[0], o[1]);
	v_fma_f32 v44, v66, v58, v70
	v_fma_f32 v45, v67, v59, v71
	v_fma_f32 v46, v64, v56, v68
	v_fma_f32 v47, v65, v57, v69
	v_fma_f32 v40, v94, v74, v40
	v_fma_f32 v41, v94, v75, v41
	v_fma_f32 v42, v94, v76, v42
	v_fma_f32 v43, v94, v77, v43
	v_fma_f32 v46, v94, v78, v46
	v_fma_f32 v47, v94, v79, v47
	v_fma_f32 v44, v94, v80, v44
	v_fma_f32 v45, v94, v81, v45
	v_mul_f32_e32 v38, v38, v42
	v_mul_f32_e32 v39, v39, v43
	v_mul_f32_e32 v36, v36, v40
	v_mul_f32_e32 v37, v37, v41
	v_mul_f32_e32 v40, v34, v44
	v_mul_f32_e32 v41, v35, v45
	v_mul_f32_e32 v34, v32, v46
	v_mul_f32_e32 v35, v33, v47
	v_cvt_pk_bf16_f32 v32, v36, v37
	v_cvt_pk_bf16_f32 v33, v38, v39
	v_cvt_pk_bf16_f32 v34, v34, v35
	v_cvt_pk_bf16_f32 v35, v40, v41
	global_store_dwordx4 v[92:93], v[32:35], off offset:64
	global_load_dwordx4 v[40:43], v[72:73], off offset:64
	global_load_dwordx4 v[52:55], v[72:73], off
	v_lshlrev_b64 v[32:33], 6, v[50:51]
	v_lshl_add_u64 v[68:69], s[18:19], 0, v[32:33]
	v_lshl_add_u64 v[70:71], s[6:7], 0, v[48:49]
	global_load_dwordx4 v[32:35], v[70:71], off
	v_lshl_add_u64 v[68:69], v[68:69], 0, s[34:35]
	s_waitcnt vmcnt(2)
	v_lshlrev_b32_e32 v36, 16, v40
	s_waitcnt vmcnt(1)
	v_lshlrev_b32_e32 v51, 16, v53
	v_lshlrev_b32_e32 v50, 16, v52
	v_and_b32_e32 v73, 0xffff0000, v53
	v_and_b32_e32 v72, 0xffff0000, v52
	v_lshlrev_b32_e32 v75, 16, v55
	v_lshlrev_b32_e32 v74, 16, v54
	v_and_b32_e32 v77, 0xffff0000, v55
	v_and_b32_e32 v76, 0xffff0000, v54
	v_add_f32_e32 v52, v50, v72
	v_add_f32_e32 v53, v51, v73
	v_add_f32_e32 v54, v74, v76
	v_add_f32_e32 v55, v75, v77
	v_and_b32_e32 v37, 0xffff0000, v40
	v_lshlrev_b32_e32 v38, 16, v41
	v_and_b32_e32 v39, 0xffff0000, v41
	v_add_f32_e32 v41, v52, v53
	v_add_f32_e32 v52, v54, v54
	v_add_f32_e32 v53, v54, v55
	v_lshlrev_b32_e32 v40, 16, v42
	v_and_b32_e32 v44, 0xffff0000, v42
	v_lshlrev_b32_e32 v42, 16, v43
	v_and_b32_e32 v46, 0xffff0000, v43
	v_add_f32_e32 v43, v36, v37
	v_add_f32_e32 v47, v38, v39
	v_add_f32_e32 v45, 0, v41
	v_mov_b32_e32 v41, v53
	v_add_f32_e32 v54, v42, v46
	v_add_f32_e32 v55, v43, v47
	v_add_f32_e32 v52, v40, v44
	v_add_f32_e32 v53, v41, v45
	s_nop 0
	v_add_f32_e32 v52, v52, v54
	v_add_f32_e32 v53, v53, v55
	s_nop 0
	v_add_f32_e32 v41, v52, v53
	global_load_dwordx4 v[52:55], v[140:141], off offset:16
	global_load_dwordx4 v[56:59], v[140:141], off
	global_load_dwordx4 v[60:63], v[142:143], off offset:16
	global_load_dwordx4 v[64:67], v[142:143], off
	flat_load_dword v78, v[68:69]
	ds_bpermute_b32 v43, v154, v41
	s_waitcnt lgkmcnt(0)
	v_add_f32_e32 v41, v41, v43
	ds_bpermute_b32 v43, v155, v41
	s_waitcnt lgkmcnt(0)
	v_add_f32_e32 v41, v41, v43
	v_fmac_f32_e32 v72, 0xbc800000, v41
	v_fmac_f32_e32 v73, 0xbc800000, v41
	v_fmac_f32_e32 v51, 0xbc800000, v41
	v_fmac_f32_e32 v76, 0xbc800000, v41
	v_fmac_f32_e32 v77, 0xbc800000, v41
	v_fmac_f32_e32 v75, 0xbc800000, v41
	v_fmac_f32_e32 v50, 0xbc800000, v41
	v_fmac_f32_e32 v74, 0xbc800000, v41
	v_fmac_f32_e32 v36, 0xbc800000, v41
	v_fmac_f32_e32 v38, 0xbc800000, v41
	v_mov_b32_e32 v80, v51
	v_mov_b32_e32 v81, v73
	v_mov_b32_e32 v51, v72
	v_mov_b32_e32 v72, v75
	v_mov_b32_e32 v73, v77
	v_mov_b32_e32 v75, v76
	v_fmac_f32_e32 v37, 0xbc800000, v41
	v_fmac_f32_e32 v39, 0xbc800000, v41
	v_mul_f32_e32 v68, v36, v36
	v_mul_f32_e32 v76, v38, v38
	v_mul_f32_e32 v82, v80, v80
	v_mul_f32_e32 v83, v81, v81
	v_mul_f32_e32 v84, v50, v50
	v_mul_f32_e32 v85, v51, v51
	v_mul_f32_e32 v86, v72, v72
	v_mul_f32_e32 v87, v73, v73
	v_mul_f32_e32 v88, v74, v74
	v_mul_f32_e32 v89, v75, v75
	v_fmac_f32_e32 v44, 0xbc800000, v41
	v_fmac_f32_e32 v40, 0xbc800000, v41
	v_fma_f32 v69, v37, v37, v68
	v_fma_f32 v68, v36, v36, v68
	v_fma_f32 v77, v39, v39, v76
	v_fma_f32 v76, v38, v38, v76
	v_pk_mov_b32 v[90:91], v[84:85], v[82:83] op_sel:[1,0]
	v_mov_b32_e32 v85, v83
	v_pk_mov_b32 v[82:83], v[88:89], v[86:87] op_sel:[1,0]
	v_mov_b32_e32 v89, v87
	v_mul_f32_e32 v68, v40, v40
	v_mul_f32_e32 v76, v44, v44
	v_add_f32_e32 v84, v90, v84
	v_add_f32_e32 v85, v91, v85
	v_add_f32_e32 v82, v82, v88
	v_add_f32_e32 v83, v83, v89
	v_fmac_f32_e32 v46, 0xbc800000, v41
	v_fmac_f32_e32 v42, 0xbc800000, v41
	v_add_f32_e32 v68, v68, v76
	v_add_f32_e32 v69, v69, v77
	v_add_f32_e32 v76, v84, v84
	v_add_f32_e32 v77, v84, v85
	v_add_f32_e32 v83, v82, v83
	v_add_f32_e32 v82, v82, v82
	v_mul_f32_e32 v76, v42, v42
	v_mul_f32_e32 v82, v46, v46
	v_add_f32_e32 v76, v76, v82
	v_add_f32_e32 v77, v77, v83
	s_waitcnt vmcnt(0)
	v_lshlrev_b32_e32 v82, 16, v34
	v_add_f32_e32 v68, v68, v76
	v_add_f32_e32 v69, v69, v77
	v_lshl_add_u64 v[76:77], s[20:21], 0, v[48:49]
	v_add_f32_e32 v41, v68, v69
	ds_bpermute_b32 v43, v154, v41
	v_lshlrev_b32_e32 v48, 16, v32
	v_and_b32_e32 v49, 0xffff0000, v32
	v_lshlrev_b32_e32 v32, 16, v33
	v_and_b32_e32 v33, 0xffff0000, v33
	s_waitcnt lgkmcnt(0)
	v_add_f32_e32 v41, v41, v43
	ds_bpermute_b32 v43, v155, v41
	v_and_b32_e32 v83, 0xffff0000, v34
	v_lshlrev_b32_e32 v34, 16, v35
	v_and_b32_e32 v35, 0xffff0000, v35
	global_load_dwordx4 v[68:71], v[70:71], off offset:64
	s_waitcnt lgkmcnt(0)
; #define GAS __attribute__((address_space(1)))
;     __device__ __forceinline__ void operator()(const Acc& acc, const Unit& u, int wr, int wc, int fr, int fq) const {
;     ...
;                 const int row = row0 + ai * HALF + m * 16;
;                 const size_t off = (size_t)row * D + colb;
;                 f32x4 y[2][2], v[2][2];
; #pragma unroll
;                 for (int bj = 0; bj < 2; ++bj) { unpack8(*(const GAS u32x4*)(Y + off + 32 * bj), y[bj][0], y[bj][1]); unpack8(*(const GAS u32x4*)(V + off + 32 * bj), v[bj][0], v[bj][1]); }
;                 const float bs = BON[(size_t)row * 16 + head];
;                 float s = 0.f;
; #pragma unroll
;                 for (int bj = 0; bj < 2; ++bj)
; #pragma unroll
;                     for (int n = 0; n < 2; ++n) s += (y[bj][n][0] + y[bj][n][1]) + (y[bj][n][2] + y[bj][n][3]);
;                 s += __shfl_xor(s, 16); s += __shfl_xor(s, 32);
;                 const float mean = s * (1.f / 64.f);
;                 float q = 0.f;
; #pragma unroll
;                 for (int bj = 0; bj < 2; ++bj)
; #pragma unroll
;                     for (int n = 0; n < 2; ++n) { y[bj][n] = y[bj][n] - mean; q += (y[bj][n][0] * y[bj][n][0] + y[bj][n][1] * y[bj][n][1]) + (y[bj][n][2] * y[bj][n][2] + y[bj][n][3] * y[bj][n][3]); }
;                 q += __shfl_xor(q, 16); q += __shfl_xor(q, 32);
;                 const float rs = rsqrtf(q * (1.f / 64.f) + 64e-5f);
; #pragma unroll
;                 for (int bj = 0; bj < 2; ++bj) {
;                     f32x4 o[2];
; #pragma unroll
;                     for (int n = 0; n < 2; ++n) {
;                         const f32x4 lw = *(const GAS f32x4*)(ln_w + colb + 32 * bj + 4 * n), lb = *(const GAS f32x4*)(ln_b + colb + 32 * bj + 4 * n);
;                         o[n] = (y[bj][n] * rs * lw + lb + v[bj][n] * bs) * acc[ai][bj][m][n];
;                     }
;                     *(GAS u32x4*)(YG + off + 32 * bj) = pack8(o[0], o[1]);
	v_add_f32_e32 v41, v41, v43
	v_fmamk_f32 v41, v41, 0x3c800000, v160
	v_mul_f32_e32 v43, 0x4b800000, v41
	v_cmp_gt_f32_e32 vcc, s78, v41
	s_nop 1
	v_cndmask_b32_e32 v41, v41, v43, vcc
	v_rsq_f32_e32 v41, v41
	s_nop 0
	v_mul_f32_e32 v43, 0x45800000, v41
	v_cndmask_b32_e32 v84, v41, v43, vcc
	v_mul_f32_e32 v50, v50, v84
	v_mul_f32_e32 v51, v51, v84
	v_mul_f32_e32 v80, v80, v84
	v_mul_f32_e32 v81, v81, v84
	v_mul_f32_e32 v74, v74, v84
	v_mul_f32_e32 v75, v75, v84
	v_mul_f32_e32 v72, v72, v84
	v_mul_f32_e32 v73, v73, v84
	v_fma_f32 v58, v58, v80, v66
	v_fma_f32 v59, v59, v81, v67
	v_fma_f32 v50, v56, v50, v64
	v_fma_f32 v51, v57, v51, v65
	v_fma_f32 v54, v54, v72, v62
	v_fma_f32 v55, v55, v73, v63
	v_fma_f32 v52, v52, v74, v60
	v_fma_f32 v53, v53, v75, v61
	v_fma_f32 v48, v78, v48, v50
	v_fma_f32 v49, v78, v49, v51
	v_fma_f32 v32, v78, v32, v58
	v_fma_f32 v33, v78, v33, v59
	v_fma_f32 v50, v78, v82, v52
	v_fma_f32 v51, v78, v83, v53
	v_fma_f32 v34, v78, v34, v54
	v_fma_f32 v35, v78, v35, v55
	v_mul_f32_e32 v30, v30, v32
	v_mul_f32_e32 v31, v31, v33
	v_mul_f32_e32 v28, v28, v48
	v_mul_f32_e32 v29, v29, v49
	v_mul_f32_e32 v32, v26, v34
	v_mul_f32_e32 v33, v27, v35
	v_mul_f32_e32 v26, v24, v50
	v_mul_f32_e32 v27, v25, v51
	v_cvt_pk_bf16_f32 v24, v28, v29
	v_cvt_pk_bf16_f32 v25, v30, v31
	v_cvt_pk_bf16_f32 v26, v26, v27
	v_cvt_pk_bf16_f32 v27, v32, v33
	global_store_dwordx4 v[76:77], v[24:27], off
	global_load_dwordx4 v[24:27], v[142:143], off offset:128
	s_nop 0
	global_load_dwordx4 v[28:31], v[140:141], off offset:128
	global_load_dwordx4 v[48:51], v[140:141], off offset:144
	global_load_dwordx4 v[52:55], v[142:143], off offset:144
	v_mov_b32_e32 v41, v44
	v_mov_b32_e32 v43, v46
	v_mul_f32_e32 v36, v36, v84
	v_mul_f32_e32 v37, v37, v84
	v_mul_f32_e32 v38, v38, v84
	v_mul_f32_e32 v39, v39, v84
	v_mul_f32_e32 v40, v40, v84
	v_mul_f32_e32 v41, v41, v84
	v_mul_f32_e32 v42, v42, v84
	v_mul_f32_e32 v43, v43, v84
	v_add_u32_e32 v34, 0xb0, v146
	v_ashrrev_i32_e32 v35, 31, v34
	v_lshlrev_b64 v[32:33], 10, v[34:35]
	v_lshl_add_u64 v[32:33], v[32:33], 0, v[144:145]
	v_lshlrev_b64 v[32:33], 1, v[32:33]
	v_lshl_add_u64 v[56:57], s[16:17], 0, v[32:33]
	s_waitcnt vmcnt(5)
	v_lshlrev_b32_e32 v58, 16, v68
	v_and_b32_e32 v59, 0xffff0000, v68
	v_lshlrev_b32_e32 v60, 16, v69
	v_and_b32_e32 v61, 0xffff0000, v69
	v_lshlrev_b32_e32 v62, 16, v70
	v_and_b32_e32 v63, 0xffff0000, v70
	v_lshlrev_b32_e32 v64, 16, v71
	v_and_b32_e32 v65, 0xffff0000, v71
	s_waitcnt vmcnt(2)
	v_fma_f32 v26, v30, v38, v26
	v_fma_f32 v27, v31, v39, v27
	v_fma_f32 v24, v28, v36, v24
	v_fma_f32 v25, v29, v37, v25
	s_waitcnt vmcnt(0)
	v_fma_f32 v28, v50, v42, v54
	v_fma_f32 v29, v51, v43, v55
	v_fma_f32 v30, v48, v40, v52
	v_fma_f32 v31, v49, v41, v53
	v_fma_f32 v24, v78, v58, v24
	v_fma_f32 v25, v78, v59, v25
	v_fma_f32 v26, v78, v60, v26
	v_fma_f32 v27, v78, v61, v27
	v_fma_f32 v30, v78, v62, v30
	v_fma_f32 v31, v78, v63, v31
	v_fma_f32 v28, v78, v64, v28
	v_fma_f32 v29, v78, v65, v29
	v_mul_f32_e32 v22, v22, v26
	v_mul_f32_e32 v23, v23, v27
	v_mul_f32_e32 v20, v20, v24
	v_mul_f32_e32 v21, v21, v25
	v_mul_f32_e32 v24, v18, v28
	v_mul_f32_e32 v25, v19, v29
	v_mul_f32_e32 v18, v16, v30
	v_mul_f32_e32 v19, v17, v31
	v_cvt_pk_bf16_f32 v16, v20, v21
	v_cvt_pk_bf16_f32 v17, v22, v23
	v_cvt_pk_bf16_f32 v18, v18, v19
	v_cvt_pk_bf16_f32 v19, v24, v25
	global_store_dwordx4 v[76:77], v[16:19], off offset:64
	global_load_dwordx4 v[24:27], v[56:57], off offset:64
	global_load_dwordx4 v[36:39], v[56:57], off
	v_lshlrev_b64 v[16:17], 6, v[34:35]
	v_lshl_add_u64 v[52:53], s[18:19], 0, v[16:17]
	v_lshl_add_u64 v[54:55], s[6:7], 0, v[32:33]
	global_load_dwordx4 v[16:19], v[54:55], off
	v_lshl_add_u64 v[52:53], v[52:53], 0, s[34:35]
	s_waitcnt vmcnt(2)
	v_lshlrev_b32_e32 v20, 16, v24
	s_waitcnt vmcnt(1)
	v_lshlrev_b32_e32 v35, 16, v37
	v_lshlrev_b32_e32 v34, 16, v36
	v_and_b32_e32 v57, 0xffff0000, v37
	v_and_b32_e32 v56, 0xffff0000, v36
	v_lshlrev_b32_e32 v59, 16, v39
	v_lshlrev_b32_e32 v58, 16, v38
	v_and_b32_e32 v61, 0xffff0000, v39
	v_and_b32_e32 v60, 0xffff0000, v38
	v_add_f32_e32 v36, v34, v56
	v_add_f32_e32 v37, v35, v57
	v_add_f32_e32 v38, v58, v60
	v_add_f32_e32 v39, v59, v61
	v_and_b32_e32 v21, 0xffff0000, v24
	v_lshlrev_b32_e32 v22, 16, v25
	v_and_b32_e32 v23, 0xffff0000, v25
	v_add_f32_e32 v25, v36, v37
	v_add_f32_e32 v36, v38, v38
	v_add_f32_e32 v37, v38, v39
	v_lshlrev_b32_e32 v24, 16, v26
	v_and_b32_e32 v30, 0xffff0000, v26
	v_lshlrev_b32_e32 v26, 16, v27
	v_and_b32_e32 v28, 0xffff0000, v27
	v_add_f32_e32 v27, v20, v21
	v_add_f32_e32 v29, v22, v23
	v_add_f32_e32 v31, 0, v25
	v_mov_b32_e32 v25, v37
	v_add_f32_e32 v38, v26, v28
	v_add_f32_e32 v39, v27, v29
	v_add_f32_e32 v36, v24, v30
	v_add_f32_e32 v37, v25, v31
	s_nop 0
	v_add_f32_e32 v36, v36, v38
	v_add_f32_e32 v37, v37, v39
	s_nop 0
	v_add_f32_e32 v25, v36, v37
	global_load_dwordx4 v[36:39], v[140:141], off offset:16
	global_load_dwordx4 v[40:43], v[140:141], off
	global_load_dwordx4 v[44:47], v[142:143], off offset:16
	global_load_dwordx4 v[48:51], v[142:143], off
	flat_load_dword v62, v[52:53]
	ds_bpermute_b32 v27, v154, v25
	s_waitcnt lgkmcnt(0)
	v_add_f32_e32 v25, v25, v27
	ds_bpermute_b32 v27, v155, v25
	s_waitcnt lgkmcnt(0)
; template <class Epi>
; __device__ __forceinline__ void gemm_phase(LAS unsigned char* lds, const int wid, const Gemm g, const Epi& E) {
;     ...
;         if (wr == 0) PG8_BAR;
;         { int le = lane; asm volatile("" : "+v"(le)); E(acc, cur, wr, wc, le & 15, le >> 4); }
;         if (!has_next) break;
; #pragma unroll
;         for (int a = 0; a < 2; ++a)
; #pragma unroll
;             for (int b = 0; b < 2; ++b)
;     __device__ __forceinline__ void operator()(const Acc& acc, const Unit& u, int wr, int wc, int fr, int fq) const {
;     ...
;                 const int row = row0 + ai * HALF + m * 16;
;                 const size_t off = (size_t)row * D + colb;
;                 f32x4 y[2][2], v[2][2];
; #pragma unroll
;                 for (int bj = 0; bj < 2; ++bj) { unpack8(*(const GAS u32x4*)(Y + off + 32 * bj), y[bj][0], y[bj][1]); unpack8(*(const GAS u32x4*)(V + off + 32 * bj), v[bj][0], v[bj][1]); }
;                 const float bs = BON[(size_t)row * 16 + head];
;                 float s = 0.f;
; #pragma unroll
;                 for (int bj = 0; bj < 2; ++bj)
; #pragma unroll
;                     for (int n = 0; n < 2; ++n) s += (y[bj][n][0] + y[bj][n][1]) + (y[bj][n][2] + y[bj][n][3]);
;                 s += __shfl_xor(s, 16); s += __shfl_xor(s, 32);
;                 const float mean = s * (1.f / 64.f);
;                 float q = 0.f;
; #pragma unroll
;                 for (int bj = 0; bj < 2; ++bj)
; #pragma unroll
;                     for (int n = 0; n < 2; ++n) { y[bj][n] = y[bj][n] - mean; q += (y[bj][n][0] * y[bj][n][0] + y[bj][n][1] * y[bj][n][1]) + (y[bj][n][2] * y[bj][n][2] + y[bj][n][3] * y[bj][n][3]); }
;                 q += __shfl_xor(q, 16); q += __shfl_xor(q, 32);
;                 const float rs = rsqrtf(q * (1.f / 64.f) + 64e-5f);
; #pragma unroll
;                 for (int bj = 0; bj < 2; ++bj) {
;                     f32x4 o[2];
; #pragma unroll
;                     for (int n = 0; n < 2; ++n) {
;                         const f32x4 lw = *(const GAS f32x4*)(ln_w + colb + 32 * bj + 4 * n), lb = *(const GAS f32x4*)(ln_b + colb + 32 * bj + 4 * n);
;                         o[n] = (y[bj][n] * rs * lw + lb + v[bj][n] * bs) * acc[ai][bj][m][n];
;                     }
;                     *(GAS u32x4*)(YG + off + 32 * bj) = pack8(o[0], o[1]);
;                 }
;                 asm volatile("" ::: "memory");
;             }
;     }
	v_add_f32_e32 v25, v25, v27
	v_fmac_f32_e32 v56, 0xbc800000, v25
	v_fmac_f32_e32 v57, 0xbc800000, v25
	v_fmac_f32_e32 v35, 0xbc800000, v25
	v_fmac_f32_e32 v60, 0xbc800000, v25
	v_fmac_f32_e32 v61, 0xbc800000, v25
	v_fmac_f32_e32 v59, 0xbc800000, v25
	v_fmac_f32_e32 v34, 0xbc800000, v25
	v_fmac_f32_e32 v58, 0xbc800000, v25
	v_fmac_f32_e32 v20, 0xbc800000, v25
	v_fmac_f32_e32 v22, 0xbc800000, v25
	v_mov_b32_e32 v64, v35
	v_mov_b32_e32 v65, v57
	v_mov_b32_e32 v35, v56
	v_mov_b32_e32 v56, v59
	v_mov_b32_e32 v57, v61
	v_mov_b32_e32 v59, v60
	v_fmac_f32_e32 v21, 0xbc800000, v25
	v_fmac_f32_e32 v23, 0xbc800000, v25
	v_mul_f32_e32 v52, v20, v20
	v_mul_f32_e32 v60, v22, v22
	v_mul_f32_e32 v66, v64, v64
	v_mul_f32_e32 v67, v65, v65
	v_mul_f32_e32 v68, v34, v34
	v_mul_f32_e32 v69, v35, v35
	v_mul_f32_e32 v70, v56, v56
	v_mul_f32_e32 v71, v57, v57
	v_mul_f32_e32 v72, v58, v58
	v_mul_f32_e32 v73, v59, v59
	v_fmac_f32_e32 v30, 0xbc800000, v25
	v_fmac_f32_e32 v24, 0xbc800000, v25
	v_fma_f32 v53, v21, v21, v52
	v_fma_f32 v52, v20, v20, v52
	v_fma_f32 v61, v23, v23, v60
	v_fma_f32 v60, v22, v22, v60
	v_pk_mov_b32 v[74:75], v[68:69], v[66:67] op_sel:[1,0]
	v_mov_b32_e32 v69, v67
	v_pk_mov_b32 v[66:67], v[72:73], v[70:71] op_sel:[1,0]
	v_mov_b32_e32 v73, v71
	v_mul_f32_e32 v52, v24, v24
	v_mul_f32_e32 v60, v30, v30
	v_add_f32_e32 v68, v74, v68
	v_add_f32_e32 v69, v75, v69
	v_add_f32_e32 v66, v66, v72
	v_add_f32_e32 v67, v67, v73
	v_fmac_f32_e32 v28, 0xbc800000, v25
	v_fmac_f32_e32 v26, 0xbc800000, v25
	v_add_f32_e32 v52, v52, v60
	v_add_f32_e32 v53, v53, v61
	v_add_f32_e32 v60, v68, v68
	v_add_f32_e32 v61, v68, v69
	v_add_f32_e32 v67, v66, v67
	v_add_f32_e32 v66, v66, v66
	v_mul_f32_e32 v60, v26, v26
	v_mul_f32_e32 v66, v28, v28
	v_add_f32_e32 v60, v60, v66
	v_add_f32_e32 v61, v61, v67
	s_waitcnt vmcnt(0)
	v_lshlrev_b32_e32 v66, 16, v18
	v_add_f32_e32 v52, v52, v60
	v_add_f32_e32 v53, v53, v61
	v_lshl_add_u64 v[60:61], s[20:21], 0, v[32:33]
	v_add_f32_e32 v25, v52, v53
	ds_bpermute_b32 v27, v154, v25
	v_lshlrev_b32_e32 v32, 16, v16
	v_and_b32_e32 v33, 0xffff0000, v16
	v_lshlrev_b32_e32 v16, 16, v17
	v_and_b32_e32 v17, 0xffff0000, v17
	s_waitcnt lgkmcnt(0)
	v_add_f32_e32 v25, v25, v27
	ds_bpermute_b32 v27, v155, v25
	v_and_b32_e32 v67, 0xffff0000, v18
	v_lshlrev_b32_e32 v18, 16, v19
	v_and_b32_e32 v19, 0xffff0000, v19
	global_load_dwordx4 v[52:55], v[54:55], off offset:64
	s_waitcnt lgkmcnt(0)
	v_add_f32_e32 v25, v25, v27
	v_fmamk_f32 v25, v25, 0x3c800000, v160
	v_mul_f32_e32 v27, 0x4b800000, v25
	v_cmp_gt_f32_e32 vcc, s78, v25
	s_nop 1
	v_cndmask_b32_e32 v25, v25, v27, vcc
	v_rsq_f32_e32 v25, v25
	s_nop 0
	v_mul_f32_e32 v27, 0x45800000, v25
	v_cndmask_b32_e32 v68, v25, v27, vcc
	v_mul_f32_e32 v34, v34, v68
	v_mul_f32_e32 v35, v35, v68
	v_mul_f32_e32 v64, v64, v68
	v_mul_f32_e32 v65, v65, v68
	v_mul_f32_e32 v58, v58, v68
	v_mul_f32_e32 v59, v59, v68
	v_mul_f32_e32 v56, v56, v68
	v_mul_f32_e32 v57, v57, v68
	v_fma_f32 v42, v42, v64, v50
	v_fma_f32 v43, v43, v65, v51
	v_fma_f32 v34, v40, v34, v48
	v_fma_f32 v35, v41, v35, v49
	v_fma_f32 v38, v38, v56, v46
	v_fma_f32 v39, v39, v57, v47
	v_fma_f32 v36, v36, v58, v44
	v_fma_f32 v37, v37, v59, v45
	v_fma_f32 v32, v62, v32, v34
	v_fma_f32 v33, v62, v33, v35
	v_fma_f32 v16, v62, v16, v42
	v_fma_f32 v17, v62, v17, v43
	v_fma_f32 v34, v62, v66, v36
	v_fma_f32 v35, v62, v67, v37
	v_fma_f32 v18, v62, v18, v38
	v_fma_f32 v19, v62, v19, v39
	v_mul_f32_e32 v14, v14, v16
	v_mul_f32_e32 v15, v15, v17
	v_mul_f32_e32 v12, v12, v32
	v_mul_f32_e32 v13, v13, v33
	v_mul_f32_e32 v16, v10, v18
	v_mul_f32_e32 v17, v11, v19
	v_mul_f32_e32 v10, v8, v34
	v_mul_f32_e32 v11, v9, v35
	v_cvt_pk_bf16_f32 v8, v12, v13
	v_cvt_pk_bf16_f32 v9, v14, v15
	v_cvt_pk_bf16_f32 v10, v10, v11
	v_cvt_pk_bf16_f32 v11, v16, v17
	global_store_dwordx4 v[60:61], v[8:11], off
	global_load_dwordx4 v[8:11], v[142:143], off offset:128
	s_nop 0
	global_load_dwordx4 v[12:15], v[140:141], off offset:128
	global_load_dwordx4 v[16:19], v[140:141], off offset:144
	global_load_dwordx4 v[32:35], v[142:143], off offset:144
	v_mov_b32_e32 v25, v30
	v_mov_b32_e32 v27, v28
	v_mul_f32_e32 v20, v20, v68
	v_mul_f32_e32 v21, v21, v68
	v_mul_f32_e32 v22, v22, v68
	v_mul_f32_e32 v23, v23, v68
	v_mul_f32_e32 v24, v24, v68
	v_mul_f32_e32 v25, v25, v68
	v_mul_f32_e32 v26, v26, v68
	v_mul_f32_e32 v27, v27, v68
	s_andn2_b64 vcc, exec, s[2:3]
	s_mov_b64 s[2:3], -1
	s_waitcnt vmcnt(5)
	v_lshlrev_b32_e32 v36, 16, v52
	v_and_b32_e32 v37, 0xffff0000, v52
	v_lshlrev_b32_e32 v38, 16, v53
	v_and_b32_e32 v39, 0xffff0000, v53
	v_lshlrev_b32_e32 v40, 16, v54
	v_and_b32_e32 v41, 0xffff0000, v54
	v_lshlrev_b32_e32 v42, 16, v55
	v_and_b32_e32 v43, 0xffff0000, v55
	s_waitcnt vmcnt(2)
	v_fma_f32 v10, v14, v22, v10
	v_fma_f32 v11, v15, v23, v11
	v_fma_f32 v8, v12, v20, v8
	v_fma_f32 v9, v13, v21, v9
	s_waitcnt vmcnt(0)
	v_fma_f32 v12, v18, v26, v34
	v_fma_f32 v13, v19, v27, v35
	v_fma_f32 v14, v16, v24, v32
	v_fma_f32 v15, v17, v25, v33
	v_fma_f32 v8, v62, v36, v8
	v_fma_f32 v9, v62, v37, v9
	v_fma_f32 v10, v62, v38, v10
	v_fma_f32 v11, v62, v39, v11
	v_fma_f32 v14, v62, v40, v14
	v_fma_f32 v15, v62, v41, v15
	v_fma_f32 v12, v62, v42, v12
	v_fma_f32 v13, v62, v43, v13
	v_mul_f32_e32 v6, v6, v10
	v_mul_f32_e32 v7, v7, v11
	v_mul_f32_e32 v4, v4, v8
	v_mul_f32_e32 v5, v5, v9
	v_mul_f32_e32 v8, v2, v12
	v_mul_f32_e32 v9, v3, v13
	v_mul_f32_e32 v2, v0, v14
	v_mul_f32_e32 v3, v1, v15
	v_cvt_pk_bf16_f32 v0, v4, v5
	v_cvt_pk_bf16_f32 v1, v6, v7
	v_cvt_pk_bf16_f32 v2, v2, v3
	v_cvt_pk_bf16_f32 v3, v8, v9
	global_store_dwordx4 v[60:61], v[0:3], off offset:64
	s_cbranch_vccnz .LBB0_1320
	s_andn2_b64 vcc, exec, s[12:13]
	s_cbranch_vccnz .LBB0_1319
	s_barrier
	s_branch .LBB0_1319

; #define GAS __attribute__((address_space(1)))
;     __device__ __forceinline__ void operator()(const Acc& acc, const Unit& u, int wr, int wc, int fr, int fq) const {
;         const int row0 = u.pm * BM + wr * 64 + fr, col0 = u.pn * BM + wc * 32 + 8 * fq;
; #pragma unroll
;         for (int ai = 0; ai < 2; ++ai)
; #pragma unroll
;             for (int m = 0; m < 4; ++m) {
;                 const size_t off = (size_t)(row0 + ai * HALF + m * 16) * D + col0;
; #pragma unroll
;                 for (int bj = 0; bj < 2; ++bj) {
;                     const size_t p = off + bj * HALF;
;                     f32x4 b0, b1;
;                     if (BASE_F32) { b0 = *(const GAS f32x4*)((const float*)base + p); b1 = *(const GAS f32x4*)((const float*)base + p + 4); }
;                     else unpack8h(*(const GAS u32x4*)((const bf16_t*)base + p), b0, b1);
;                     b0 += acc[ai][bj][m][0]; b1 += acc[ai][bj][m][1];
;                     if (OUT_F32) { *(GAS f32x4*)((float*)out + p) = b0; *(GAS f32x4*)((float*)out + p + 4) = b1; }
;                     else *(GAS u32x4*)((bf16_t*)out + p) = pack8h(b0, b1);
;                 }
;                 asm volatile("" ::: "memory");
;             }
;     }
.LBB0_1401:
	v_mov_b32_e32 v140, v147
	s_lshl_b32 s0, s34, 8
	s_add_i32 s0, s0, s55
	v_and_or_b32 v144, v140, 15, s0
	s_lshl_b32 s0, s63, 8
	v_ashrrev_i32_e32 v140, 1, v140
	s_or_b32 s0, s0, s56
	v_and_b32_e32 v140, -8, v140
	v_add_u32_e32 v142, s0, v140
	v_ashrrev_i32_e32 v145, 31, v144
	v_ashrrev_i32_e32 v143, 31, v142
	v_lshlrev_b64 v[140:141], 10, v[144:145]
	v_lshl_add_u64 v[140:141], v[140:141], 0, v[142:143]
	v_lshlrev_b64 v[140:141], 1, v[140:141]
	v_lshl_add_u64 v[156:157], s[12:13], 0, v[140:141]
	global_load_dwordx4 v[152:155], v[156:157], off
	v_lshl_add_u64 v[158:159], s[14:15], 0, v[140:141]
	s_andn2_b64 vcc, exec, s[2:3]
	s_mov_b64 s[2:3], -1
	s_waitcnt vmcnt(0)
	v_cvt_f32_f16_e32 v160, v153
	v_cvt_f32_f16_sdwa v161, v153 dst_sel:DWORD dst_unused:UNUSED_PAD src0_sel:WORD_1
	v_cvt_f32_f16_e32 v162, v152
	v_cvt_f32_f16_sdwa v163, v152 dst_sel:DWORD dst_unused:UNUSED_PAD src0_sel:WORD_1
	v_cvt_f32_f16_e32 v152, v155
	v_cvt_f32_f16_e32 v164, v154
	v_cvt_f32_f16_sdwa v165, v154 dst_sel:DWORD dst_unused:UNUSED_PAD src0_sel:WORD_1
	v_cvt_f32_f16_sdwa v153, v155 dst_sel:DWORD dst_unused:UNUSED_PAD src0_sel:WORD_1
	v_add_f32_e32 v124, v124, v162
	v_add_f32_e32 v125, v125, v163
	v_add_f32_e32 v126, v126, v160
	v_add_f32_e32 v127, v127, v161
	v_add_f32_e32 v120, v120, v164
	v_add_f32_e32 v121, v121, v165
	v_add_f32_e32 v122, v122, v152
	v_add_f32_e32 v123, v123, v153
	s_nop 0
	v_cvt_pk_f16_f32 v123, v122, v123
	v_cvt_pk_f16_f32 v122, v120, v121
	v_cvt_pk_f16_f32 v121, v126, v127
	v_cvt_pk_f16_f32 v120, v124, v125
	global_store_dwordx4 v[158:159], v[120:123], off
	global_load_dwordx4 v[120:123], v[156:157], off offset:256
	v_or_b32_e32 v124, 16, v144
	v_ashrrev_i32_e32 v125, 31, v124
	v_lshlrev_b64 v[124:125], 10, v[124:125]
	v_lshl_add_u64 v[124:125], v[124:125], 0, v[142:143]
	v_lshlrev_b64 v[124:125], 1, v[124:125]
	v_lshl_add_u64 v[126:127], s[12:13], 0, v[124:125]
	s_waitcnt vmcnt(0)
	v_cvt_f32_f16_e32 v152, v121
	v_cvt_f32_f16_sdwa v153, v121 dst_sel:DWORD dst_unused:UNUSED_PAD src0_sel:WORD_1
	v_cvt_f32_f16_e32 v154, v120
	v_cvt_f32_f16_sdwa v155, v120 dst_sel:DWORD dst_unused:UNUSED_PAD src0_sel:WORD_1
	v_cvt_f32_f16_e32 v120, v123
	v_cvt_f32_f16_e32 v156, v122
	v_cvt_f32_f16_sdwa v157, v122 dst_sel:DWORD dst_unused:UNUSED_PAD src0_sel:WORD_1
	v_cvt_f32_f16_sdwa v121, v123 dst_sel:DWORD dst_unused:UNUSED_PAD src0_sel:WORD_1
	v_add_f32_e32 v116, v116, v154
	v_add_f32_e32 v117, v117, v155
	v_add_f32_e32 v118, v118, v152
	v_add_f32_e32 v119, v119, v153
	v_add_f32_e32 v112, v112, v156
	v_add_f32_e32 v113, v113, v157
	v_add_f32_e32 v114, v114, v120
	v_add_f32_e32 v115, v115, v121
	s_nop 0
	v_cvt_pk_f16_f32 v115, v114, v115
	v_cvt_pk_f16_f32 v114, v112, v113
	v_cvt_pk_f16_f32 v113, v118, v119
	v_cvt_pk_f16_f32 v112, v116, v117
	global_store_dwordx4 v[158:159], v[112:115], off offset:256
	global_load_dwordx4 v[112:115], v[126:127], off
	v_lshl_add_u64 v[116:117], s[14:15], 0, v[124:125]
	s_waitcnt vmcnt(0)
	v_cvt_f32_f16_e32 v118, v113
	v_cvt_f32_f16_sdwa v119, v113 dst_sel:DWORD dst_unused:UNUSED_PAD src0_sel:WORD_1
	v_cvt_f32_f16_e32 v120, v112
	v_cvt_f32_f16_sdwa v121, v112 dst_sel:DWORD dst_unused:UNUSED_PAD src0_sel:WORD_1
	v_cvt_f32_f16_e32 v112, v115
	v_cvt_f32_f16_e32 v122, v114
	v_cvt_f32_f16_sdwa v123, v114 dst_sel:DWORD dst_unused:UNUSED_PAD src0_sel:WORD_1
	v_cvt_f32_f16_sdwa v113, v115 dst_sel:DWORD dst_unused:UNUSED_PAD src0_sel:WORD_1
	v_add_f32_e32 v108, v108, v120
	v_add_f32_e32 v109, v109, v121
	v_add_f32_e32 v110, v110, v118
	v_add_f32_e32 v111, v111, v119
	v_add_f32_e32 v104, v104, v122
	v_add_f32_e32 v105, v105, v123
	v_add_f32_e32 v106, v106, v112
	v_add_f32_e32 v107, v107, v113
	s_nop 0
	v_cvt_pk_f16_f32 v107, v106, v107
	v_cvt_pk_f16_f32 v106, v104, v105
	v_cvt_pk_f16_f32 v105, v110, v111
	v_cvt_pk_f16_f32 v104, v108, v109
	global_store_dwordx4 v[116:117], v[104:107], off
	global_load_dwordx4 v[104:107], v[126:127], off offset:256
	v_or_b32_e32 v108, 32, v144
	v_ashrrev_i32_e32 v109, 31, v108
	v_lshlrev_b64 v[108:109], 10, v[108:109]
	v_lshl_add_u64 v[108:109], v[108:109], 0, v[142:143]
	v_lshlrev_b64 v[108:109], 1, v[108:109]
	v_lshl_add_u64 v[110:111], s[12:13], 0, v[108:109]
	s_waitcnt vmcnt(0)
	v_cvt_f32_f16_e32 v112, v105
	v_cvt_f32_f16_sdwa v113, v105 dst_sel:DWORD dst_unused:UNUSED_PAD src0_sel:WORD_1
	v_cvt_f32_f16_e32 v114, v104
	v_cvt_f32_f16_sdwa v115, v104 dst_sel:DWORD dst_unused:UNUSED_PAD src0_sel:WORD_1
	v_cvt_f32_f16_e32 v104, v107
	v_cvt_f32_f16_e32 v118, v106
	v_cvt_f32_f16_sdwa v119, v106 dst_sel:DWORD dst_unused:UNUSED_PAD src0_sel:WORD_1
	v_cvt_f32_f16_sdwa v105, v107 dst_sel:DWORD dst_unused:UNUSED_PAD src0_sel:WORD_1
	v_add_f32_e32 v100, v100, v114
	v_add_f32_e32 v101, v101, v115
	v_add_f32_e32 v102, v102, v112
	v_add_f32_e32 v103, v103, v113
	v_add_f32_e32 v96, v96, v118
	v_add_f32_e32 v97, v97, v119
	v_add_f32_e32 v98, v98, v104
	v_add_f32_e32 v99, v99, v105
	s_nop 0
	v_cvt_pk_f16_f32 v99, v98, v99
	v_cvt_pk_f16_f32 v98, v96, v97
	v_cvt_pk_f16_f32 v97, v102, v103
	v_cvt_pk_f16_f32 v96, v100, v101
	global_store_dwordx4 v[116:117], v[96:99], off offset:256
	global_load_dwordx4 v[96:99], v[110:111], off
	v_lshl_add_u64 v[100:101], s[14:15], 0, v[108:109]
	s_waitcnt vmcnt(0)
; #define GAS __attribute__((address_space(1)))
;     __device__ __forceinline__ void operator()(const Acc& acc, const Unit& u, int wr, int wc, int fr, int fq) const {
;         const int row0 = u.pm * BM + wr * 64 + fr, col0 = u.pn * BM + wc * 32 + 8 * fq;
; #pragma unroll
;         for (int ai = 0; ai < 2; ++ai)
; #pragma unroll
;             for (int m = 0; m < 4; ++m) {
;                 const size_t off = (size_t)(row0 + ai * HALF + m * 16) * D + col0;
; #pragma unroll
;                 for (int bj = 0; bj < 2; ++bj) {
;                     const size_t p = off + bj * HALF;
;                     f32x4 b0, b1;
;                     if (BASE_F32) { b0 = *(const GAS f32x4*)((const float*)base + p); b1 = *(const GAS f32x4*)((const float*)base + p + 4); }
;                     else unpack8h(*(const GAS u32x4*)((const bf16_t*)base + p), b0, b1);
;                     b0 += acc[ai][bj][m][0]; b1 += acc[ai][bj][m][1];
;                     if (OUT_F32) { *(GAS f32x4*)((float*)out + p) = b0; *(GAS f32x4*)((float*)out + p + 4) = b1; }
;                     else *(GAS u32x4*)((bf16_t*)out + p) = pack8h(b0, b1);
;                 }
;                 asm volatile("" ::: "memory");
;             }
;     }
	v_cvt_f32_f16_e32 v102, v97
	v_cvt_f32_f16_sdwa v103, v97 dst_sel:DWORD dst_unused:UNUSED_PAD src0_sel:WORD_1
	v_cvt_f32_f16_e32 v104, v96
	v_cvt_f32_f16_sdwa v105, v96 dst_sel:DWORD dst_unused:UNUSED_PAD src0_sel:WORD_1
	v_cvt_f32_f16_e32 v96, v99
	v_cvt_f32_f16_e32 v106, v98
	v_cvt_f32_f16_sdwa v107, v98 dst_sel:DWORD dst_unused:UNUSED_PAD src0_sel:WORD_1
	v_cvt_f32_f16_sdwa v97, v99 dst_sel:DWORD dst_unused:UNUSED_PAD src0_sel:WORD_1
	v_add_f32_e32 v92, v92, v104
	v_add_f32_e32 v93, v93, v105
	v_add_f32_e32 v94, v94, v102
	v_add_f32_e32 v95, v95, v103
	v_add_f32_e32 v88, v88, v106
	v_add_f32_e32 v89, v89, v107
	v_add_f32_e32 v90, v90, v96
	v_add_f32_e32 v91, v91, v97
	s_nop 0
	v_cvt_pk_f16_f32 v91, v90, v91
	v_cvt_pk_f16_f32 v90, v88, v89
	v_cvt_pk_f16_f32 v89, v94, v95
	v_cvt_pk_f16_f32 v88, v92, v93
	global_store_dwordx4 v[100:101], v[88:91], off
	global_load_dwordx4 v[88:91], v[110:111], off offset:256
	v_or_b32_e32 v92, 48, v144
	v_ashrrev_i32_e32 v93, 31, v92
	v_lshlrev_b64 v[92:93], 10, v[92:93]
	v_lshl_add_u64 v[92:93], v[92:93], 0, v[142:143]
	v_lshlrev_b64 v[92:93], 1, v[92:93]
	v_lshl_add_u64 v[94:95], s[12:13], 0, v[92:93]
	s_waitcnt vmcnt(0)
	v_cvt_f32_f16_e32 v96, v89
	v_cvt_f32_f16_sdwa v97, v89 dst_sel:DWORD dst_unused:UNUSED_PAD src0_sel:WORD_1
	v_cvt_f32_f16_e32 v98, v88
	v_cvt_f32_f16_sdwa v99, v88 dst_sel:DWORD dst_unused:UNUSED_PAD src0_sel:WORD_1
	v_cvt_f32_f16_e32 v88, v91
	v_cvt_f32_f16_e32 v102, v90
	v_cvt_f32_f16_sdwa v103, v90 dst_sel:DWORD dst_unused:UNUSED_PAD src0_sel:WORD_1
	v_cvt_f32_f16_sdwa v89, v91 dst_sel:DWORD dst_unused:UNUSED_PAD src0_sel:WORD_1
	v_add_f32_e32 v84, v84, v98
	v_add_f32_e32 v85, v85, v99
	v_add_f32_e32 v86, v86, v96
	v_add_f32_e32 v87, v87, v97
	v_add_f32_e32 v80, v80, v102
	v_add_f32_e32 v81, v81, v103
	v_add_f32_e32 v82, v82, v88
	v_add_f32_e32 v83, v83, v89
	s_nop 0
	v_cvt_pk_f16_f32 v83, v82, v83
	v_cvt_pk_f16_f32 v82, v80, v81
	v_cvt_pk_f16_f32 v81, v86, v87
	v_cvt_pk_f16_f32 v80, v84, v85
	global_store_dwordx4 v[100:101], v[80:83], off offset:256
	global_load_dwordx4 v[80:83], v[94:95], off
	v_lshl_add_u64 v[84:85], s[14:15], 0, v[92:93]
	s_waitcnt vmcnt(0)
	v_cvt_f32_f16_e32 v86, v81
	v_cvt_f32_f16_sdwa v87, v81 dst_sel:DWORD dst_unused:UNUSED_PAD src0_sel:WORD_1
	v_cvt_f32_f16_e32 v88, v80
	v_cvt_f32_f16_sdwa v89, v80 dst_sel:DWORD dst_unused:UNUSED_PAD src0_sel:WORD_1
	v_cvt_f32_f16_e32 v80, v83
	v_cvt_f32_f16_e32 v90, v82
	v_cvt_f32_f16_sdwa v91, v82 dst_sel:DWORD dst_unused:UNUSED_PAD src0_sel:WORD_1
	v_cvt_f32_f16_sdwa v81, v83 dst_sel:DWORD dst_unused:UNUSED_PAD src0_sel:WORD_1
	v_add_f32_e32 v76, v76, v88
	v_add_f32_e32 v77, v77, v89
	v_add_f32_e32 v78, v78, v86
	v_add_f32_e32 v79, v79, v87
	v_add_f32_e32 v72, v72, v90
	v_add_f32_e32 v73, v73, v91
	v_add_f32_e32 v74, v74, v80
	v_add_f32_e32 v75, v75, v81
	s_nop 0
	v_cvt_pk_f16_f32 v75, v74, v75
	v_cvt_pk_f16_f32 v74, v72, v73
	v_cvt_pk_f16_f32 v73, v78, v79
	v_cvt_pk_f16_f32 v72, v76, v77
	global_store_dwordx4 v[84:85], v[72:75], off
	global_load_dwordx4 v[72:75], v[94:95], off offset:256
	v_lshl_add_u64 v[76:77], v[140:141], 0, s[8:9]
	v_lshl_add_u64 v[78:79], s[12:13], 0, v[76:77]
	s_waitcnt vmcnt(0)
	v_cvt_f32_f16_e32 v80, v73
	v_cvt_f32_f16_sdwa v81, v73 dst_sel:DWORD dst_unused:UNUSED_PAD src0_sel:WORD_1
	v_cvt_f32_f16_e32 v82, v72
	v_cvt_f32_f16_sdwa v83, v72 dst_sel:DWORD dst_unused:UNUSED_PAD src0_sel:WORD_1
	v_cvt_f32_f16_e32 v72, v75
	v_cvt_f32_f16_e32 v86, v74
	v_cvt_f32_f16_sdwa v87, v74 dst_sel:DWORD dst_unused:UNUSED_PAD src0_sel:WORD_1
	v_cvt_f32_f16_sdwa v73, v75 dst_sel:DWORD dst_unused:UNUSED_PAD src0_sel:WORD_1
	v_add_f32_e32 v68, v68, v82
	v_add_f32_e32 v69, v69, v83
	v_add_f32_e32 v70, v70, v80
	v_add_f32_e32 v71, v71, v81
	v_add_f32_e32 v64, v64, v86
	v_add_f32_e32 v65, v65, v87
	v_add_f32_e32 v66, v66, v72
	v_add_f32_e32 v67, v67, v73
	s_nop 0
	v_cvt_pk_f16_f32 v67, v66, v67
	v_cvt_pk_f16_f32 v66, v64, v65
	v_cvt_pk_f16_f32 v65, v70, v71
	v_cvt_pk_f16_f32 v64, v68, v69
	global_store_dwordx4 v[84:85], v[64:67], off offset:256
	global_load_dwordx4 v[64:67], v[78:79], off
	v_lshl_add_u64 v[68:69], s[14:15], 0, v[76:77]
	s_waitcnt vmcnt(0)
	v_cvt_f32_f16_e32 v70, v65
	v_cvt_f32_f16_sdwa v71, v65 dst_sel:DWORD dst_unused:UNUSED_PAD src0_sel:WORD_1
	v_cvt_f32_f16_e32 v72, v64
	v_cvt_f32_f16_sdwa v73, v64 dst_sel:DWORD dst_unused:UNUSED_PAD src0_sel:WORD_1
	v_cvt_f32_f16_e32 v64, v67
	v_cvt_f32_f16_e32 v74, v66
	v_cvt_f32_f16_sdwa v75, v66 dst_sel:DWORD dst_unused:UNUSED_PAD src0_sel:WORD_1
	v_cvt_f32_f16_sdwa v65, v67 dst_sel:DWORD dst_unused:UNUSED_PAD src0_sel:WORD_1
	v_add_f32_e32 v60, v60, v72
	v_add_f32_e32 v61, v61, v73
	v_add_f32_e32 v62, v62, v70
	v_add_f32_e32 v63, v63, v71
	v_add_f32_e32 v56, v56, v74
	v_add_f32_e32 v57, v57, v75
	v_add_f32_e32 v58, v58, v64
	v_add_f32_e32 v59, v59, v65
	s_nop 0
	v_cvt_pk_f16_f32 v59, v58, v59
	v_cvt_pk_f16_f32 v58, v56, v57
	v_cvt_pk_f16_f32 v57, v62, v63
	v_cvt_pk_f16_f32 v56, v60, v61
	global_store_dwordx4 v[68:69], v[56:59], off
	global_load_dwordx4 v[56:59], v[78:79], off offset:256
	v_lshl_add_u64 v[60:61], v[140:141], 0, s[16:17]
	v_lshl_add_u64 v[62:63], s[12:13], 0, v[60:61]
	s_waitcnt vmcnt(0)
; #define GAS __attribute__((address_space(1)))
;     __device__ __forceinline__ void operator()(const Acc& acc, const Unit& u, int wr, int wc, int fr, int fq) const {
;         const int row0 = u.pm * BM + wr * 64 + fr, col0 = u.pn * BM + wc * 32 + 8 * fq;
; #pragma unroll
;         for (int ai = 0; ai < 2; ++ai)
; #pragma unroll
;             for (int m = 0; m < 4; ++m) {
;                 const size_t off = (size_t)(row0 + ai * HALF + m * 16) * D + col0;
; #pragma unroll
;                 for (int bj = 0; bj < 2; ++bj) {
;                     const size_t p = off + bj * HALF;
;                     f32x4 b0, b1;
;                     if (BASE_F32) { b0 = *(const GAS f32x4*)((const float*)base + p); b1 = *(const GAS f32x4*)((const float*)base + p + 4); }
;                     else unpack8h(*(const GAS u32x4*)((const bf16_t*)base + p), b0, b1);
;                     b0 += acc[ai][bj][m][0]; b1 += acc[ai][bj][m][1];
;                     if (OUT_F32) { *(GAS f32x4*)((float*)out + p) = b0; *(GAS f32x4*)((float*)out + p + 4) = b1; }
;                     else *(GAS u32x4*)((bf16_t*)out + p) = pack8h(b0, b1);
;                 }
;                 asm volatile("" ::: "memory");
;             }
;     }
	v_cvt_f32_f16_e32 v64, v57
	v_cvt_f32_f16_sdwa v65, v57 dst_sel:DWORD dst_unused:UNUSED_PAD src0_sel:WORD_1
	v_cvt_f32_f16_e32 v66, v56
	v_cvt_f32_f16_sdwa v67, v56 dst_sel:DWORD dst_unused:UNUSED_PAD src0_sel:WORD_1
	v_cvt_f32_f16_e32 v56, v59
	v_cvt_f32_f16_e32 v70, v58
	v_cvt_f32_f16_sdwa v71, v58 dst_sel:DWORD dst_unused:UNUSED_PAD src0_sel:WORD_1
	v_cvt_f32_f16_sdwa v57, v59 dst_sel:DWORD dst_unused:UNUSED_PAD src0_sel:WORD_1
	v_add_f32_e32 v52, v52, v66
	v_add_f32_e32 v53, v53, v67
	v_add_f32_e32 v54, v54, v64
	v_add_f32_e32 v55, v55, v65
	v_add_f32_e32 v48, v48, v70
	v_add_f32_e32 v49, v49, v71
	v_add_f32_e32 v50, v50, v56
	v_add_f32_e32 v51, v51, v57
	s_nop 0
	v_cvt_pk_f16_f32 v51, v50, v51
	v_cvt_pk_f16_f32 v50, v48, v49
	v_cvt_pk_f16_f32 v49, v54, v55
	v_cvt_pk_f16_f32 v48, v52, v53
	global_store_dwordx4 v[68:69], v[48:51], off offset:256
	global_load_dwordx4 v[48:51], v[62:63], off
	v_lshl_add_u64 v[52:53], s[14:15], 0, v[60:61]
	s_waitcnt vmcnt(0)
	v_cvt_f32_f16_e32 v54, v49
	v_cvt_f32_f16_sdwa v55, v49 dst_sel:DWORD dst_unused:UNUSED_PAD src0_sel:WORD_1
	v_cvt_f32_f16_e32 v56, v48
	v_cvt_f32_f16_sdwa v57, v48 dst_sel:DWORD dst_unused:UNUSED_PAD src0_sel:WORD_1
	v_cvt_f32_f16_e32 v48, v51
	v_cvt_f32_f16_e32 v58, v50
	v_cvt_f32_f16_sdwa v59, v50 dst_sel:DWORD dst_unused:UNUSED_PAD src0_sel:WORD_1
	v_cvt_f32_f16_sdwa v49, v51 dst_sel:DWORD dst_unused:UNUSED_PAD src0_sel:WORD_1
	v_add_f32_e32 v44, v44, v56
	v_add_f32_e32 v45, v45, v57
	v_add_f32_e32 v46, v46, v54
	v_add_f32_e32 v47, v47, v55
	v_add_f32_e32 v40, v40, v58
	v_add_f32_e32 v41, v41, v59
	v_add_f32_e32 v42, v42, v48
	v_add_f32_e32 v43, v43, v49
	s_nop 0
	v_cvt_pk_f16_f32 v43, v42, v43
	v_cvt_pk_f16_f32 v42, v40, v41
	v_cvt_pk_f16_f32 v41, v46, v47
	v_cvt_pk_f16_f32 v40, v44, v45
	global_store_dwordx4 v[52:53], v[40:43], off
	global_load_dwordx4 v[40:43], v[62:63], off offset:256
	v_lshl_add_u64 v[44:45], v[140:141], 0, s[18:19]
	v_lshl_add_u64 v[46:47], s[12:13], 0, v[44:45]
	s_waitcnt vmcnt(0)
	v_cvt_f32_f16_e32 v48, v41
	v_cvt_f32_f16_sdwa v49, v41 dst_sel:DWORD dst_unused:UNUSED_PAD src0_sel:WORD_1
	v_cvt_f32_f16_e32 v50, v40
	v_cvt_f32_f16_sdwa v51, v40 dst_sel:DWORD dst_unused:UNUSED_PAD src0_sel:WORD_1
	v_cvt_f32_f16_e32 v40, v43
	v_cvt_f32_f16_e32 v54, v42
	v_cvt_f32_f16_sdwa v55, v42 dst_sel:DWORD dst_unused:UNUSED_PAD src0_sel:WORD_1
	v_cvt_f32_f16_sdwa v41, v43 dst_sel:DWORD dst_unused:UNUSED_PAD src0_sel:WORD_1
	v_add_f32_e32 v36, v36, v50
	v_add_f32_e32 v37, v37, v51
	v_add_f32_e32 v38, v38, v48
	v_add_f32_e32 v39, v39, v49
	v_add_f32_e32 v32, v32, v54
	v_add_f32_e32 v33, v33, v55
	v_add_f32_e32 v34, v34, v40
	v_add_f32_e32 v35, v35, v41
	s_nop 0
	v_cvt_pk_f16_f32 v35, v34, v35
	v_cvt_pk_f16_f32 v34, v32, v33
	v_cvt_pk_f16_f32 v33, v38, v39
	v_cvt_pk_f16_f32 v32, v36, v37
	global_store_dwordx4 v[52:53], v[32:35], off offset:256
	global_load_dwordx4 v[32:35], v[46:47], off
	v_lshl_add_u64 v[36:37], s[14:15], 0, v[44:45]
	s_waitcnt vmcnt(0)
	v_cvt_f32_f16_e32 v38, v33
	v_cvt_f32_f16_sdwa v39, v33 dst_sel:DWORD dst_unused:UNUSED_PAD src0_sel:WORD_1
	v_cvt_f32_f16_e32 v40, v32
	v_cvt_f32_f16_sdwa v41, v32 dst_sel:DWORD dst_unused:UNUSED_PAD src0_sel:WORD_1
	v_cvt_f32_f16_e32 v32, v35
	v_cvt_f32_f16_e32 v42, v34
	v_cvt_f32_f16_sdwa v43, v34 dst_sel:DWORD dst_unused:UNUSED_PAD src0_sel:WORD_1
	v_cvt_f32_f16_sdwa v33, v35 dst_sel:DWORD dst_unused:UNUSED_PAD src0_sel:WORD_1
	v_add_f32_e32 v28, v28, v40
	v_add_f32_e32 v29, v29, v41
	v_add_f32_e32 v30, v30, v38
	v_add_f32_e32 v31, v31, v39
	v_add_f32_e32 v24, v24, v42
	v_add_f32_e32 v25, v25, v43
	v_add_f32_e32 v26, v26, v32
	v_add_f32_e32 v27, v27, v33
	s_nop 0
	v_cvt_pk_f16_f32 v27, v26, v27
	v_cvt_pk_f16_f32 v26, v24, v25
	v_cvt_pk_f16_f32 v25, v30, v31
	v_cvt_pk_f16_f32 v24, v28, v29
	global_store_dwordx4 v[36:37], v[24:27], off
	global_load_dwordx4 v[24:27], v[46:47], off offset:256
	v_lshl_add_u64 v[28:29], v[140:141], 0, s[20:21]
	v_lshl_add_u64 v[30:31], s[12:13], 0, v[28:29]
	s_waitcnt vmcnt(0)
	v_cvt_f32_f16_e32 v32, v25
	v_cvt_f32_f16_sdwa v33, v25 dst_sel:DWORD dst_unused:UNUSED_PAD src0_sel:WORD_1
	v_cvt_f32_f16_e32 v34, v24
	v_cvt_f32_f16_sdwa v35, v24 dst_sel:DWORD dst_unused:UNUSED_PAD src0_sel:WORD_1
	v_cvt_f32_f16_e32 v24, v27
	v_cvt_f32_f16_e32 v38, v26
	v_cvt_f32_f16_sdwa v39, v26 dst_sel:DWORD dst_unused:UNUSED_PAD src0_sel:WORD_1
	v_cvt_f32_f16_sdwa v25, v27 dst_sel:DWORD dst_unused:UNUSED_PAD src0_sel:WORD_1
	v_add_f32_e32 v20, v20, v34
	v_add_f32_e32 v21, v21, v35
	v_add_f32_e32 v22, v22, v32
	v_add_f32_e32 v23, v23, v33
	v_add_f32_e32 v16, v16, v38
	v_add_f32_e32 v17, v17, v39
	v_add_f32_e32 v18, v18, v24
	v_add_f32_e32 v19, v19, v25
	s_nop 0
	v_cvt_pk_f16_f32 v19, v18, v19
	v_cvt_pk_f16_f32 v18, v16, v17
	v_cvt_pk_f16_f32 v17, v22, v23
	v_cvt_pk_f16_f32 v16, v20, v21
	global_store_dwordx4 v[36:37], v[16:19], off offset:256
	global_load_dwordx4 v[16:19], v[30:31], off
	v_lshl_add_u64 v[20:21], s[14:15], 0, v[28:29]
	s_waitcnt vmcnt(0)
	v_cvt_f32_f16_e32 v22, v17
	v_cvt_f32_f16_sdwa v23, v17 dst_sel:DWORD dst_unused:UNUSED_PAD src0_sel:WORD_1
	v_cvt_f32_f16_e32 v24, v16
	v_cvt_f32_f16_sdwa v25, v16 dst_sel:DWORD dst_unused:UNUSED_PAD src0_sel:WORD_1
	v_cvt_f32_f16_e32 v16, v19
	v_cvt_f32_f16_e32 v26, v18
	v_cvt_f32_f16_sdwa v27, v18 dst_sel:DWORD dst_unused:UNUSED_PAD src0_sel:WORD_1
	v_cvt_f32_f16_sdwa v17, v19 dst_sel:DWORD dst_unused:UNUSED_PAD src0_sel:WORD_1
	v_add_f32_e32 v12, v12, v24
	v_add_f32_e32 v13, v13, v25
	v_add_f32_e32 v14, v14, v22
	v_add_f32_e32 v15, v15, v23
	v_add_f32_e32 v8, v8, v26
	v_add_f32_e32 v9, v9, v27
	v_add_f32_e32 v10, v10, v16
	v_add_f32_e32 v11, v11, v17
	s_nop 0
	v_cvt_pk_f16_f32 v11, v10, v11
	v_cvt_pk_f16_f32 v10, v8, v9
	v_cvt_pk_f16_f32 v9, v14, v15
	v_cvt_pk_f16_f32 v8, v12, v13
	global_store_dwordx4 v[20:21], v[8:11], off
	global_load_dwordx4 v[8:11], v[30:31], off offset:256
	s_waitcnt vmcnt(0)
	v_cvt_f32_f16_e32 v12, v9
	v_cvt_f32_f16_sdwa v13, v9 dst_sel:DWORD dst_unused:UNUSED_PAD src0_sel:WORD_1
	v_cvt_f32_f16_e32 v14, v8
	v_cvt_f32_f16_sdwa v15, v8 dst_sel:DWORD dst_unused:UNUSED_PAD src0_sel:WORD_1
	v_cvt_f32_f16_e32 v8, v11
	v_cvt_f32_f16_e32 v16, v10
	v_cvt_f32_f16_sdwa v17, v10 dst_sel:DWORD dst_unused:UNUSED_PAD src0_sel:WORD_1
	v_cvt_f32_f16_sdwa v9, v11 dst_sel:DWORD dst_unused:UNUSED_PAD src0_sel:WORD_1
	v_add_f32_e32 v4, v4, v14
	v_add_f32_e32 v5, v5, v15
	v_add_f32_e32 v6, v6, v12
	v_add_f32_e32 v7, v7, v13
	v_add_f32_e32 v0, v0, v16
	v_add_f32_e32 v1, v1, v17
	v_add_f32_e32 v2, v2, v8
	v_add_f32_e32 v3, v3, v9
	s_nop 0
	v_cvt_pk_f16_f32 v3, v2, v3
	v_cvt_pk_f16_f32 v2, v0, v1
	v_cvt_pk_f16_f32 v1, v6, v7
	v_cvt_pk_f16_f32 v0, v4, v5
	global_store_dwordx4 v[20:21], v[0:3], off offset:256
	s_cbranch_vccnz .LBB0_1390
	s_andn2_b64 vcc, exec, s[6:7]
	s_cbranch_vccnz .LBB0_1389
	s_barrier
	s_branch .LBB0_1389

; #define GAS __attribute__((address_space(1)))
; template <int MODE, bool XBF>
; __device__ __forceinline__ void rmsnorm_rows(const void* x, const float* gain, bf16_t* H, int gw, int NGW, int lane, const LAS float* WF, const float* fbias, float* LF) {
;     ...
;     for (int row0 = gw * RB; row0 < T; row0 += NGW * RB) {
;         f32x4 v[RB][2][2]; float s[RB];
; #pragma unroll
;         for (int r = 0; r < RB; ++r)
; #pragma unroll
;             for (int j = 0; j < 2; ++j) { const size_t xo = (size_t)(row0 + r) * D + 512 * j + lane * 8;
;                 if (XBF) unpack8h(*(const GAS u32x4*)((const bf16_t*)x + xo), v[r][j][0], v[r][j][1]);
;                 else { v[r][j][0] = *(const GAS f32x4*)((const float*)x + xo); v[r][j][1] = *(const GAS f32x4*)((const float*)x + xo + 4); } }
.LBB0_1470:
	v_lshl_add_u64 v[18:19], s[28:29], 0, v[16:17]
	v_add_co_u32_e64 v36, s[2:3], s19, v18
	v_add_co_u32_e32 v30, vcc, 0x5800000, v18
	s_nop 0
	v_addc_co_u32_e64 v37, s[2:3], 0, v19, s[2:3]
	v_add_co_u32_e64 v38, s[2:3], s21, v18
	v_addc_co_u32_e32 v31, vcc, 0, v19, vcc
	s_nop 0
	v_addc_co_u32_e64 v39, s[2:3], 0, v19, s[2:3]
	v_add_co_u32_e64 v44, s[2:3], s23, v18
	v_lshl_add_u64 v[26:27], s[24:25], 0, v[16:17]
	s_nop 0
	v_addc_co_u32_e64 v45, s[2:3], 0, v19, s[2:3]
	global_load_dwordx4 v[32:35], v[38:39], off offset:-4096
	global_load_dwordx4 v[40:43], v[36:37], off offset:1024
	global_load_dwordx4 v[48:51], v[36:37], off offset:2048
	global_load_dwordx4 v[56:59], v[36:37], off offset:3072
	global_load_dwordx4 v[64:67], v[38:39], off
	global_load_dwordx4 v[72:75], v[38:39], off offset:1024
	global_load_dwordx4 v[80:83], v[38:39], off offset:2048
	global_load_dwordx4 v[88:91], v[38:39], off offset:3072
	global_load_dwordx4 v[96:99], v[44:45], off
	global_load_dwordx4 v[104:107], v[44:45], off offset:1024
	global_load_dwordx4 v[112:115], v[44:45], off offset:2048
	global_load_dwordx4 v[120:123], v[44:45], off offset:3072
	global_load_dwordx4 v[128:131], v[30:31], off
	global_load_dwordx4 v[136:139], v[30:31], off offset:1024
	global_load_dwordx4 v[144:147], v[30:31], off offset:2048
	global_load_dwordx4 v[152:155], v[30:31], off offset:3072
	v_add_co_u32_e64 v22, s[2:3], s35, v26
	v_mov_b64_e32 v[20:21], s[34:35]
	s_nop 0
	v_addc_co_u32_e64 v23, s[2:3], 0, v27, s[2:3]
	v_add_co_u32_e64 v24, s[2:3], s38, v26
	s_add_i32 s18, s18, s20
	s_nop 0
	v_addc_co_u32_e64 v25, s[2:3], 0, v27, s[2:3]
	v_add_co_u32_e64 v28, s[2:3], s39, v26
	s_add_u32 s24, s24, s26
	s_nop 0
	v_addc_co_u32_e64 v29, s[2:3], 0, v27, s[2:3]
	v_add_co_u32_e64 v26, s[2:3], s40, v26
	s_addc_u32 s25, s25, s27
	s_nop 0
	v_addc_co_u32_e64 v27, s[2:3], 0, v27, s[2:3]
	s_add_u32 s28, s28, s26
	s_addc_u32 s29, s29, s27
	s_cmp_lt_i32 s18, 0x8000
	s_waitcnt vmcnt(15)
	v_cvt_f32_f16_e32 v18, v32
	v_cvt_f32_f16_sdwa v19, v32 dst_sel:DWORD dst_unused:UNUSED_PAD src0_sel:WORD_1
	v_cvt_f32_f16_e32 v30, v33
	v_cvt_f32_f16_sdwa v31, v33 dst_sel:DWORD dst_unused:UNUSED_PAD src0_sel:WORD_1
	v_cvt_f32_f16_e32 v32, v34
	v_cvt_f32_f16_sdwa v33, v34 dst_sel:DWORD dst_unused:UNUSED_PAD src0_sel:WORD_1
	v_cvt_f32_f16_e32 v34, v35
	v_cvt_f32_f16_sdwa v35, v35 dst_sel:DWORD dst_unused:UNUSED_PAD src0_sel:WORD_1
	s_waitcnt vmcnt(14)
	v_cvt_f32_f16_e32 v36, v40
	v_cvt_f32_f16_sdwa v37, v40 dst_sel:DWORD dst_unused:UNUSED_PAD src0_sel:WORD_1
	v_cvt_f32_f16_e32 v40, v41
	s_waitcnt vmcnt(13)
	v_cvt_f32_f16_e32 v44, v48
	v_cvt_f32_f16_sdwa v45, v48 dst_sel:DWORD dst_unused:UNUSED_PAD src0_sel:WORD_1
	v_cvt_f32_f16_e32 v46, v49
	v_cvt_f32_f16_sdwa v47, v49 dst_sel:DWORD dst_unused:UNUSED_PAD src0_sel:WORD_1
	v_cvt_f32_f16_e32 v48, v50
	v_cvt_f32_f16_sdwa v49, v50 dst_sel:DWORD dst_unused:UNUSED_PAD src0_sel:WORD_1
	v_cvt_f32_f16_e32 v50, v51
	v_cvt_f32_f16_sdwa v51, v51 dst_sel:DWORD dst_unused:UNUSED_PAD src0_sel:WORD_1
	v_cvt_f32_f16_sdwa v41, v41 dst_sel:DWORD dst_unused:UNUSED_PAD src0_sel:WORD_1
	s_waitcnt vmcnt(12)
	v_cvt_f32_f16_e32 v52, v56
	v_cvt_f32_f16_sdwa v53, v56 dst_sel:DWORD dst_unused:UNUSED_PAD src0_sel:WORD_1
	v_cvt_f32_f16_e32 v56, v57
	s_waitcnt vmcnt(11)
	v_cvt_f32_f16_e32 v60, v64
	v_cvt_f32_f16_sdwa v61, v64 dst_sel:DWORD dst_unused:UNUSED_PAD src0_sel:WORD_1
	v_cvt_f32_f16_e32 v62, v65
	v_cvt_f32_f16_sdwa v63, v65 dst_sel:DWORD dst_unused:UNUSED_PAD src0_sel:WORD_1
	v_cvt_f32_f16_e32 v64, v66
	v_cvt_f32_f16_sdwa v65, v66 dst_sel:DWORD dst_unused:UNUSED_PAD src0_sel:WORD_1
	v_cvt_f32_f16_e32 v66, v67
	v_cvt_f32_f16_sdwa v67, v67 dst_sel:DWORD dst_unused:UNUSED_PAD src0_sel:WORD_1
	s_waitcnt vmcnt(10)
	v_cvt_f32_f16_e32 v68, v72
	v_cvt_f32_f16_sdwa v69, v72 dst_sel:DWORD dst_unused:UNUSED_PAD src0_sel:WORD_1
	v_cvt_f32_f16_e32 v72, v73
	s_waitcnt vmcnt(9)
	v_cvt_f32_f16_e32 v76, v80
	v_cvt_f32_f16_sdwa v77, v80 dst_sel:DWORD dst_unused:UNUSED_PAD src0_sel:WORD_1
	v_cvt_f32_f16_e32 v78, v81
	v_cvt_f32_f16_sdwa v79, v81 dst_sel:DWORD dst_unused:UNUSED_PAD src0_sel:WORD_1
	v_cvt_f32_f16_e32 v80, v82
	v_cvt_f32_f16_sdwa v81, v82 dst_sel:DWORD dst_unused:UNUSED_PAD src0_sel:WORD_1
	v_cvt_f32_f16_e32 v82, v83
	v_cvt_f32_f16_sdwa v83, v83 dst_sel:DWORD dst_unused:UNUSED_PAD src0_sel:WORD_1
	s_waitcnt vmcnt(8)
	v_cvt_f32_f16_e32 v84, v88
	v_cvt_f32_f16_sdwa v85, v88 dst_sel:DWORD dst_unused:UNUSED_PAD src0_sel:WORD_1
	v_cvt_f32_f16_e32 v88, v89
	s_waitcnt vmcnt(7)
	v_cvt_f32_f16_e32 v92, v96
	v_cvt_f32_f16_sdwa v93, v96 dst_sel:DWORD dst_unused:UNUSED_PAD src0_sel:WORD_1
	v_cvt_f32_f16_e32 v94, v97
	v_cvt_f32_f16_sdwa v95, v97 dst_sel:DWORD dst_unused:UNUSED_PAD src0_sel:WORD_1
	v_cvt_f32_f16_e32 v96, v98
	v_cvt_f32_f16_sdwa v97, v98 dst_sel:DWORD dst_unused:UNUSED_PAD src0_sel:WORD_1
	v_cvt_f32_f16_e32 v98, v99
	v_cvt_f32_f16_sdwa v99, v99 dst_sel:DWORD dst_unused:UNUSED_PAD src0_sel:WORD_1
	s_waitcnt vmcnt(5)
	v_cvt_f32_f16_e32 v108, v112
	v_cvt_f32_f16_sdwa v109, v112 dst_sel:DWORD dst_unused:UNUSED_PAD src0_sel:WORD_1
	v_cvt_f32_f16_e32 v110, v113
	v_cvt_f32_f16_sdwa v111, v113 dst_sel:DWORD dst_unused:UNUSED_PAD src0_sel:WORD_1
	v_cvt_f32_f16_e32 v112, v114
	v_cvt_f32_f16_sdwa v113, v114 dst_sel:DWORD dst_unused:UNUSED_PAD src0_sel:WORD_1
	v_cvt_f32_f16_e32 v114, v115
	v_cvt_f32_f16_sdwa v115, v115 dst_sel:DWORD dst_unused:UNUSED_PAD src0_sel:WORD_1
	s_waitcnt vmcnt(3)
; #define GAS __attribute__((address_space(1)))
; template <int MODE, bool XBF>
; __device__ __forceinline__ void rmsnorm_rows(const void* x, const float* gain, bf16_t* H, int gw, int NGW, int lane, const LAS float* WF, const float* fbias, float* LF) {
;     ...
;             for (int j = 0; j < 2; ++j) { const size_t xo = (size_t)(row0 + r) * D + 512 * j + lane * 8;
;                 if (XBF) unpack8h(*(const GAS u32x4*)((const bf16_t*)x + xo), v[r][j][0], v[r][j][1]);
;                 else { v[r][j][0] = *(const GAS f32x4*)((const float*)x + xo); v[r][j][1] = *(const GAS f32x4*)((const float*)x + xo + 4); } }
; #pragma unroll
;         for (int r = 0; r < RB; ++r) { s[r] = 0.f;
; #pragma unroll
;             for (int j = 0; j < 2; ++j)
; #pragma unroll
;                 for (int e = 0; e < 2; ++e) s[r] += (v[r][j][e][0] * v[r][j][e][0] + v[r][j][e][1] * v[r][j][e][1]) + (v[r][j][e][2] * v[r][j][e][2] + v[r][j][e][3] * v[r][j][e][3]); }
	v_cvt_f32_f16_e32 v124, v128
	v_cvt_f32_f16_sdwa v125, v128 dst_sel:DWORD dst_unused:UNUSED_PAD src0_sel:WORD_1
	v_cvt_f32_f16_e32 v126, v129
	v_cvt_f32_f16_sdwa v127, v129 dst_sel:DWORD dst_unused:UNUSED_PAD src0_sel:WORD_1
	v_cvt_f32_f16_e32 v128, v130
	v_cvt_f32_f16_sdwa v129, v130 dst_sel:DWORD dst_unused:UNUSED_PAD src0_sel:WORD_1
	v_cvt_f32_f16_e32 v130, v131
	v_cvt_f32_f16_sdwa v131, v131 dst_sel:DWORD dst_unused:UNUSED_PAD src0_sel:WORD_1
	s_waitcnt vmcnt(1)
	v_cvt_f32_f16_e32 v140, v144
	v_cvt_f32_f16_sdwa v141, v144 dst_sel:DWORD dst_unused:UNUSED_PAD src0_sel:WORD_1
	v_cvt_f32_f16_e32 v142, v145
	v_cvt_f32_f16_sdwa v143, v145 dst_sel:DWORD dst_unused:UNUSED_PAD src0_sel:WORD_1
	v_cvt_f32_f16_e32 v144, v146
	v_cvt_f32_f16_sdwa v145, v146 dst_sel:DWORD dst_unused:UNUSED_PAD src0_sel:WORD_1
	v_cvt_f32_f16_e32 v146, v147
	v_cvt_f32_f16_sdwa v147, v147 dst_sel:DWORD dst_unused:UNUSED_PAD src0_sel:WORD_1
	v_cvt_f32_f16_sdwa v39, v43 dst_sel:DWORD dst_unused:UNUSED_PAD src0_sel:WORD_1
	v_cvt_f32_f16_e32 v38, v43
	v_cvt_f32_f16_sdwa v57, v57 dst_sel:DWORD dst_unused:UNUSED_PAD src0_sel:WORD_1
	v_cvt_f32_f16_sdwa v73, v73 dst_sel:DWORD dst_unused:UNUSED_PAD src0_sel:WORD_1
	v_cvt_f32_f16_sdwa v89, v89 dst_sel:DWORD dst_unused:UNUSED_PAD src0_sel:WORD_1
	v_cvt_f32_f16_sdwa v55, v59 dst_sel:DWORD dst_unused:UNUSED_PAD src0_sel:WORD_1
	v_cvt_f32_f16_e32 v54, v59
	v_cvt_f32_f16_sdwa v71, v75 dst_sel:DWORD dst_unused:UNUSED_PAD src0_sel:WORD_1
	v_cvt_f32_f16_e32 v70, v75
	v_cvt_f32_f16_sdwa v87, v91 dst_sel:DWORD dst_unused:UNUSED_PAD src0_sel:WORD_1
	v_cvt_f32_f16_e32 v86, v91
	v_cvt_f32_f16_e32 v100, v104
	v_cvt_f32_f16_sdwa v101, v104 dst_sel:DWORD dst_unused:UNUSED_PAD src0_sel:WORD_1
	v_cvt_f32_f16_e32 v104, v105
	v_cvt_f32_f16_e32 v116, v120
	v_cvt_f32_f16_sdwa v117, v120 dst_sel:DWORD dst_unused:UNUSED_PAD src0_sel:WORD_1
	v_cvt_f32_f16_e32 v120, v121
	v_cvt_f32_f16_e32 v132, v136
	v_cvt_f32_f16_sdwa v133, v136 dst_sel:DWORD dst_unused:UNUSED_PAD src0_sel:WORD_1
	v_cvt_f32_f16_e32 v136, v137
	s_waitcnt vmcnt(0)
	v_cvt_f32_f16_e32 v148, v152
	v_cvt_f32_f16_sdwa v149, v152 dst_sel:DWORD dst_unused:UNUSED_PAD src0_sel:WORD_1
	v_cvt_f32_f16_e32 v152, v153
	v_cvt_f32_f16_sdwa v43, v42 dst_sel:DWORD dst_unused:UNUSED_PAD src0_sel:WORD_1
	v_cvt_f32_f16_e32 v42, v42
	v_cvt_f32_f16_sdwa v59, v58 dst_sel:DWORD dst_unused:UNUSED_PAD src0_sel:WORD_1
	v_cvt_f32_f16_e32 v58, v58
	v_cvt_f32_f16_sdwa v105, v105 dst_sel:DWORD dst_unused:UNUSED_PAD src0_sel:WORD_1
	v_cvt_f32_f16_sdwa v121, v121 dst_sel:DWORD dst_unused:UNUSED_PAD src0_sel:WORD_1
	v_cvt_f32_f16_sdwa v137, v137 dst_sel:DWORD dst_unused:UNUSED_PAD src0_sel:WORD_1
	v_cvt_f32_f16_sdwa v153, v153 dst_sel:DWORD dst_unused:UNUSED_PAD src0_sel:WORD_1
	v_mul_f32_e32 v164, v30, v30
	v_mul_f32_e32 v165, v31, v31
	v_mul_f32_e32 v166, v18, v18
	v_mul_f32_e32 v167, v19, v19
	v_mul_f32_e32 v168, v34, v34
	v_mul_f32_e32 v169, v35, v35
	v_mul_f32_e32 v170, v32, v32
	v_mul_f32_e32 v171, v33, v33
	v_mul_f32_e32 v172, v36, v36
	v_mul_f32_e32 v174, v40, v40
	v_mul_f32_e32 v176, v46, v46
	v_mul_f32_e32 v177, v47, v47
	v_mul_f32_e32 v178, v44, v44
	v_mul_f32_e32 v179, v45, v45
	v_mul_f32_e32 v180, v50, v50
	v_mul_f32_e32 v181, v51, v51
	v_mul_f32_e32 v182, v48, v48
	v_mul_f32_e32 v183, v49, v49
	v_cvt_f32_f16_sdwa v75, v74 dst_sel:DWORD dst_unused:UNUSED_PAD src0_sel:WORD_1
	v_cvt_f32_f16_e32 v74, v74
	v_cvt_f32_f16_sdwa v91, v90 dst_sel:DWORD dst_unused:UNUSED_PAD src0_sel:WORD_1
	v_cvt_f32_f16_e32 v90, v90
	v_cvt_f32_f16_sdwa v103, v107 dst_sel:DWORD dst_unused:UNUSED_PAD src0_sel:WORD_1
	v_cvt_f32_f16_e32 v102, v107
	v_cvt_f32_f16_sdwa v107, v106 dst_sel:DWORD dst_unused:UNUSED_PAD src0_sel:WORD_1
	v_cvt_f32_f16_e32 v106, v106
	v_cvt_f32_f16_sdwa v119, v123 dst_sel:DWORD dst_unused:UNUSED_PAD src0_sel:WORD_1
	v_cvt_f32_f16_e32 v118, v123
	v_cvt_f32_f16_sdwa v123, v122 dst_sel:DWORD dst_unused:UNUSED_PAD src0_sel:WORD_1
	v_cvt_f32_f16_e32 v122, v122
	v_cvt_f32_f16_sdwa v135, v139 dst_sel:DWORD dst_unused:UNUSED_PAD src0_sel:WORD_1
	v_cvt_f32_f16_e32 v134, v139
	v_cvt_f32_f16_sdwa v139, v138 dst_sel:DWORD dst_unused:UNUSED_PAD src0_sel:WORD_1
	v_cvt_f32_f16_e32 v138, v138
	v_cvt_f32_f16_sdwa v151, v155 dst_sel:DWORD dst_unused:UNUSED_PAD src0_sel:WORD_1
	v_cvt_f32_f16_e32 v150, v155
	v_cvt_f32_f16_sdwa v155, v154 dst_sel:DWORD dst_unused:UNUSED_PAD src0_sel:WORD_1
	v_cvt_f32_f16_e32 v154, v154
	v_mul_f32_e32 v184, v52, v52
	v_mul_f32_e32 v186, v56, v56
	v_mul_f32_e32 v188, v62, v62
	v_mul_f32_e32 v189, v63, v63
	v_mul_f32_e32 v190, v60, v60
	v_mul_f32_e32 v191, v61, v61
	v_mul_f32_e32 v192, v66, v66
	v_mul_f32_e32 v193, v67, v67
	v_mul_f32_e32 v194, v64, v64
	v_mul_f32_e32 v195, v65, v65
	v_mul_f32_e32 v196, v68, v68
	v_mul_f32_e32 v198, v72, v72
	v_mul_f32_e32 v200, v78, v78
	v_mul_f32_e32 v201, v79, v79
	v_mul_f32_e32 v202, v76, v76
	v_mul_f32_e32 v203, v77, v77
	v_mul_f32_e32 v204, v82, v82
	v_mul_f32_e32 v205, v83, v83
	v_mul_f32_e32 v206, v80, v80
	v_mul_f32_e32 v207, v81, v81
	v_mul_f32_e32 v208, v84, v84
	v_mul_f32_e32 v210, v88, v88
	v_mul_f32_e32 v212, v94, v94
	v_mul_f32_e32 v213, v95, v95
	v_mul_f32_e32 v214, v92, v92
	v_mul_f32_e32 v215, v93, v93
	v_mul_f32_e32 v216, v98, v98
	v_mul_f32_e32 v217, v99, v99
	v_mul_f32_e32 v218, v96, v96
	v_mul_f32_e32 v219, v97, v97
	v_mul_f32_e32 v224, v110, v110
	v_mul_f32_e32 v225, v111, v111
	v_mul_f32_e32 v226, v108, v108
	v_mul_f32_e32 v227, v109, v109
	v_mul_f32_e32 v228, v114, v114
	v_mul_f32_e32 v229, v115, v115
	v_mul_f32_e32 v230, v112, v112
	v_mul_f32_e32 v231, v113, v113
	v_mul_f32_e32 v236, v126, v126
	v_mul_f32_e32 v237, v127, v127
; template <int MODE, bool XBF>
; __device__ __forceinline__ void rmsnorm_rows(const void* x, const float* gain, bf16_t* H, int gw, int NGW, int lane, const LAS float* WF, const float* fbias, float* LF) {
;     ...
;         for (int r = 0; r < RB; ++r) { s[r] = 0.f;
; #pragma unroll
;             for (int j = 0; j < 2; ++j)
; #pragma unroll
;                 for (int e = 0; e < 2; ++e) s[r] += (v[r][j][e][0] * v[r][j][e][0] + v[r][j][e][1] * v[r][j][e][1]) + (v[r][j][e][2] * v[r][j][e][2] + v[r][j][e][3] * v[r][j][e][3]); }
	v_mul_f32_e32 v238, v124, v124
	v_mul_f32_e32 v239, v125, v125
	v_mul_f32_e32 v240, v130, v130
	v_mul_f32_e32 v241, v131, v131
	v_mul_f32_e32 v242, v128, v128
	v_mul_f32_e32 v243, v129, v129
	v_mul_f32_e32 v244, v142, v142
	v_mul_f32_e32 v245, v143, v143
	v_mul_f32_e32 v246, v140, v140
	v_mul_f32_e32 v247, v141, v141
	v_mul_f32_e32 v248, v146, v146
	v_mul_f32_e32 v249, v147, v147
	v_mul_f32_e32 v250, v144, v144
	v_mul_f32_e32 v251, v145, v145
	v_pk_mov_b32 v[252:253], v[166:167], v[164:165] op_sel:[1,0]
	v_mov_b32_e32 v167, v165
	v_pk_mov_b32 v[164:165], v[170:171], v[168:169] op_sel:[1,0]
	v_mov_b32_e32 v171, v169
	v_pk_mov_b32 v[168:169], v[178:179], v[176:177] op_sel:[1,0]
	v_mov_b32_e32 v179, v177
	v_pk_mov_b32 v[176:177], v[182:183], v[180:181] op_sel:[1,0]
	v_mov_b32_e32 v183, v181
	v_fma_f32 v173, v37, v37, v172
	v_fma_f32 v172, v36, v36, v172
	v_fma_f32 v175, v41, v41, v174
	v_fma_f32 v174, v40, v40, v174
	v_pk_mov_b32 v[180:181], v[190:191], v[188:189] op_sel:[1,0]
	v_mov_b32_e32 v191, v189
	v_pk_mov_b32 v[188:189], v[194:195], v[192:193] op_sel:[1,0]
	v_mov_b32_e32 v195, v193
	v_pk_mov_b32 v[192:193], v[202:203], v[200:201] op_sel:[1,0]
	v_mov_b32_e32 v203, v201
	v_pk_mov_b32 v[200:201], v[206:207], v[204:205] op_sel:[1,0]
	v_mov_b32_e32 v207, v205
	v_pk_mov_b32 v[204:205], v[214:215], v[212:213] op_sel:[1,0]
	v_mov_b32_e32 v215, v213
	v_pk_mov_b32 v[212:213], v[218:219], v[216:217] op_sel:[1,0]
	v_mov_b32_e32 v219, v217
	v_pk_mov_b32 v[216:217], v[226:227], v[224:225] op_sel:[1,0]
	v_mov_b32_e32 v227, v225
	v_pk_mov_b32 v[224:225], v[230:231], v[228:229] op_sel:[1,0]
	v_mov_b32_e32 v231, v229
	v_pk_mov_b32 v[228:229], v[238:239], v[236:237] op_sel:[1,0]
	v_mov_b32_e32 v239, v237
	v_pk_mov_b32 v[236:237], v[242:243], v[240:241] op_sel:[1,0]
	v_mov_b32_e32 v243, v241
	v_pk_mov_b32 v[240:241], v[246:247], v[244:245] op_sel:[1,0]
	v_mov_b32_e32 v247, v245
	v_pk_mov_b32 v[244:245], v[250:251], v[248:249] op_sel:[1,0]
	v_mov_b32_e32 v251, v249
	v_add_f32_e32 v166, v252, v166
	v_add_f32_e32 v167, v253, v167
	v_add_f32_e32 v164, v164, v170
	v_add_f32_e32 v165, v165, v171
	v_add_f32_e32 v168, v168, v178
	v_add_f32_e32 v169, v169, v179
	v_fma_f32 v185, v53, v53, v184
	v_fma_f32 v184, v52, v52, v184
	v_fma_f32 v187, v57, v57, v186
	v_fma_f32 v186, v56, v56, v186
	v_fma_f32 v197, v69, v69, v196
	v_fma_f32 v196, v68, v68, v196
	v_fma_f32 v199, v73, v73, v198
	v_fma_f32 v198, v72, v72, v198
	v_fma_f32 v209, v85, v85, v208
	v_fma_f32 v208, v84, v84, v208
	v_fma_f32 v211, v89, v89, v210
	v_fma_f32 v210, v88, v88, v210
	v_mul_f32_e32 v172, v38, v38
	v_mul_f32_e32 v174, v39, v39
	v_add_f32_e32 v176, v176, v182
	v_add_f32_e32 v177, v177, v183
	v_mul_f32_e32 v220, v100, v100
	v_mul_f32_e32 v222, v104, v104
	v_mul_f32_e32 v232, v116, v116
	v_mul_f32_e32 v234, v120, v120
	v_mul_f32_e32 v248, v132, v132
	v_mul_f32_e32 v252, v136, v136
	v_mul_f32_e32 v170, v148, v148
	v_mul_f32_e32 v178, v152, v152
	v_mul_f32_e32 v184, v54, v54
	v_mul_f32_e32 v186, v55, v55
	v_add_f32_e32 v180, v180, v190
	v_add_f32_e32 v181, v181, v191
	v_add_f32_e32 v182, v188, v194
	v_add_f32_e32 v183, v189, v195
	v_mul_f32_e32 v196, v70, v70
	v_mul_f32_e32 v198, v71, v71
	v_add_f32_e32 v188, v192, v202
	v_add_f32_e32 v189, v193, v203
	v_add_f32_e32 v190, v200, v206
	v_add_f32_e32 v191, v201, v207
	v_mul_f32_e32 v208, v86, v86
	v_mul_f32_e32 v210, v87, v87
	v_add_f32_e32 v192, v204, v214
	v_add_f32_e32 v193, v205, v215
	v_add_f32_e32 v194, v212, v218
	v_add_f32_e32 v195, v213, v219
	v_add_f32_e32 v200, v216, v226
	v_add_f32_e32 v201, v217, v227
	v_add_f32_e32 v202, v224, v230
	v_add_f32_e32 v203, v225, v231
	v_add_f32_e32 v204, v228, v238
	v_add_f32_e32 v205, v229, v239
	v_add_f32_e32 v206, v236, v242
	v_add_f32_e32 v207, v237, v243
	v_add_f32_e32 v212, v240, v246
	v_add_f32_e32 v213, v241, v247
	v_add_f32_e32 v214, v244, v250
	v_add_f32_e32 v215, v245, v251
	v_add_f32_e32 v167, v166, v167
	v_add_f32_e32 v166, v166, v166
	v_add_f32_e32 v165, v164, v165
	v_add_f32_e32 v164, v164, v164
	v_add_f32_e32 v172, v172, v174
	v_add_f32_e32 v173, v173, v175
	v_add_f32_e32 v169, v168, v169
	v_add_f32_e32 v168, v168, v168
	v_add_f32_e32 v174, v176, v176
	v_add_f32_e32 v175, v176, v177
	v_fma_f32 v221, v101, v101, v220
	v_fma_f32 v220, v100, v100, v220
	v_fma_f32 v223, v105, v105, v222
	v_fma_f32 v222, v104, v104, v222
	v_fma_f32 v233, v117, v117, v232
	v_fma_f32 v232, v116, v116, v232
	v_fma_f32 v235, v121, v121, v234
	v_fma_f32 v234, v120, v120, v234
	v_fma_f32 v249, v133, v133, v248
	v_fma_f32 v248, v132, v132, v248
	v_fma_f32 v253, v137, v137, v252
	v_fma_f32 v252, v136, v136, v252
	v_fma_f32 v171, v149, v149, v170
	v_fma_f32 v170, v148, v148, v170
	v_fma_f32 v179, v153, v153, v178
	v_fma_f32 v178, v152, v152, v178
	v_add_f32_e32 v176, v184, v186
	v_add_f32_e32 v177, v185, v187
	v_add_f32_e32 v181, v180, v181
	v_add_f32_e32 v180, v180, v180
	v_add_f32_e32 v183, v182, v183
	v_add_f32_e32 v182, v182, v182
	v_add_f32_e32 v184, v196, v198
	v_add_f32_e32 v185, v197, v199
	v_add_f32_e32 v186, v188, v188
	v_add_f32_e32 v187, v188, v189
	v_add_f32_e32 v188, v190, v190
	v_add_f32_e32 v189, v190, v191
	v_add_f32_e32 v190, v208, v210
	v_add_f32_e32 v191, v209, v211
	v_add_f32_e32 v193, v192, v193
	v_add_f32_e32 v192, v192, v192
	v_add_f32_e32 v195, v194, v195
	v_add_f32_e32 v194, v194, v194
	v_add_f32_e32 v198, v200, v200
	v_add_f32_e32 v199, v200, v201
	v_add_f32_e32 v200, v202, v202
	v_add_f32_e32 v201, v202, v203
	v_add_f32_e32 v205, v204, v205
	v_add_f32_e32 v204, v204, v204
	v_add_f32_e32 v207, v206, v207
	v_add_f32_e32 v206, v206, v206
	v_add_f32_e32 v210, v212, v212
	v_add_f32_e32 v211, v212, v213
; template <int MODE, bool XBF>
; __device__ __forceinline__ void rmsnorm_rows(const void* x, const float* gain, bf16_t* H, int gw, int NGW, int lane, const LAS float* WF, const float* fbias, float* LF) {
;     ...
;         for (int r = 0; r < RB; ++r) { s[r] = 0.f;
; #pragma unroll
;             for (int j = 0; j < 2; ++j)
; #pragma unroll
;                 for (int e = 0; e < 2; ++e) s[r] += (v[r][j][e][0] * v[r][j][e][0] + v[r][j][e][1] * v[r][j][e][1]) + (v[r][j][e][2] * v[r][j][e][2] + v[r][j][e][3] * v[r][j][e][3]); }
; #pragma unroll
;         for (int o = 1; o < 64; o <<= 1)
; #pragma unroll
;             for (int r = 0; r < RB; ++r) s[r] += __shfl_xor(s[r], o);
	v_add_f32_e32 v212, v214, v214
	v_add_f32_e32 v213, v214, v215
	v_mul_f32_e32 v166, v42, v42
	v_mul_f32_e32 v164, v43, v43
	v_mul_f32_e32 v168, v58, v58
	v_mul_f32_e32 v174, v59, v59
	v_mul_f32_e32 v220, v102, v102
	v_mul_f32_e32 v222, v103, v103
	v_mul_f32_e32 v232, v118, v118
	v_mul_f32_e32 v234, v119, v119
	v_mul_f32_e32 v248, v134, v134
	v_mul_f32_e32 v252, v135, v135
	v_mul_f32_e32 v170, v150, v150
	v_mul_f32_e32 v178, v151, v151
	v_mul_f32_e32 v180, v74, v74
	v_mul_f32_e32 v182, v75, v75
	v_mul_f32_e32 v186, v90, v90
	v_mul_f32_e32 v188, v91, v91
	v_mul_f32_e32 v192, v106, v106
	v_mul_f32_e32 v194, v107, v107
	v_mul_f32_e32 v198, v122, v122
	v_mul_f32_e32 v200, v123, v123
	v_mul_f32_e32 v204, v138, v138
	v_mul_f32_e32 v206, v139, v139
	v_mul_f32_e32 v210, v154, v154
	v_mul_f32_e32 v212, v155, v155
	v_add_f32_e32 v164, v166, v164
	v_add_f32_e32 v165, v167, v165
	v_add_f32_e32 v166, v168, v174
	v_add_f32_e32 v167, v169, v175
	v_add_f32_e32 v196, v220, v222
	v_add_f32_e32 v197, v221, v223
	v_add_f32_e32 v202, v232, v234
	v_add_f32_e32 v203, v233, v235
	v_add_f32_e32 v208, v248, v252
	v_add_f32_e32 v209, v249, v253
	v_add_f32_e32 v170, v170, v178
	v_add_f32_e32 v171, v171, v179
	v_add_f32_e32 v168, v180, v182
	v_add_f32_e32 v169, v181, v183
	v_add_f32_e32 v174, v186, v188
	v_add_f32_e32 v175, v187, v189
	v_add_f32_e32 v178, v192, v194
	v_add_f32_e32 v179, v193, v195
	v_add_f32_e32 v180, v198, v200
	v_add_f32_e32 v181, v199, v201
	v_add_f32_e32 v182, v204, v206
	v_add_f32_e32 v183, v205, v207
	v_add_f32_e32 v186, v210, v212
	v_add_f32_e32 v187, v211, v213
	v_add_f32_e32 v164, v164, v172
	v_add_f32_e32 v165, v165, v173
	v_add_f32_e32 v166, v166, v176
	v_add_f32_e32 v167, v167, v177
	v_add_f32_e32 v168, v168, v184
	v_add_f32_e32 v169, v169, v185
	v_add_f32_e32 v172, v174, v190
	v_add_f32_e32 v173, v175, v191
	v_add_f32_e32 v174, v178, v196
	v_add_f32_e32 v175, v179, v197
	v_add_f32_e32 v176, v180, v202
	v_add_f32_e32 v177, v181, v203
	v_add_f32_e32 v178, v182, v208
	v_add_f32_e32 v179, v183, v209
	v_add_f32_e32 v170, v186, v170
	v_add_f32_e32 v171, v187, v171
	v_mov_b32_e32 v180, v166
	v_mov_b32_e32 v181, v164
	v_mov_b32_e32 v164, v167
	v_mov_b32_e32 v166, v172
	v_mov_b32_e32 v167, v168
	v_mov_b32_e32 v168, v173
	v_mov_b32_e32 v172, v176
	v_mov_b32_e32 v173, v174
	v_mov_b32_e32 v174, v177
	v_mov_b32_e32 v176, v170
	v_mov_b32_e32 v177, v178
	v_mov_b32_e32 v178, v171
	v_add_f32_e32 v164, v180, v164
	v_add_f32_e32 v165, v181, v165
	v_add_f32_e32 v166, v166, v168
	v_add_f32_e32 v167, v167, v169
	v_add_f32_e32 v168, v172, v174
	v_add_f32_e32 v169, v173, v175
	v_add_f32_e32 v170, v176, v178
	v_add_f32_e32 v171, v177, v179
	ds_bpermute_b32 v173, v157, v165
	ds_bpermute_b32 v172, v157, v164
	ds_bpermute_b32 v175, v157, v167
	ds_bpermute_b32 v174, v157, v166
	ds_bpermute_b32 v177, v157, v169
	ds_bpermute_b32 v176, v157, v168
	ds_bpermute_b32 v179, v157, v171
	ds_bpermute_b32 v178, v157, v170
	s_waitcnt lgkmcnt(6)
	v_add_f32_e32 v164, v164, v172
	v_add_f32_e32 v165, v165, v173
	s_waitcnt lgkmcnt(4)
	v_add_f32_e32 v166, v166, v174
	v_add_f32_e32 v167, v167, v175
	s_waitcnt lgkmcnt(2)
	v_add_f32_e32 v168, v168, v176
	v_add_f32_e32 v169, v169, v177
	ds_bpermute_b32 v173, v158, v165
	s_waitcnt lgkmcnt(1)
	v_add_f32_e32 v170, v170, v178
	v_add_f32_e32 v171, v171, v179
	ds_bpermute_b32 v172, v158, v164
	ds_bpermute_b32 v175, v158, v167
	ds_bpermute_b32 v174, v158, v166
	ds_bpermute_b32 v177, v158, v169
	ds_bpermute_b32 v176, v158, v168
	ds_bpermute_b32 v179, v158, v171
	ds_bpermute_b32 v178, v158, v170
	s_waitcnt lgkmcnt(6)
	v_add_f32_e32 v164, v164, v172
	v_add_f32_e32 v165, v165, v173
	s_waitcnt lgkmcnt(4)
	v_add_f32_e32 v166, v166, v174
	v_add_f32_e32 v167, v167, v175
	s_waitcnt lgkmcnt(2)
	v_add_f32_e32 v168, v168, v176
	v_add_f32_e32 v169, v169, v177
	ds_bpermute_b32 v173, v159, v165
	s_waitcnt lgkmcnt(1)
	v_add_f32_e32 v170, v170, v178
	v_add_f32_e32 v171, v171, v179
	ds_bpermute_b32 v172, v159, v164
	ds_bpermute_b32 v175, v159, v167
	ds_bpermute_b32 v174, v159, v166
	ds_bpermute_b32 v177, v159, v169
	ds_bpermute_b32 v176, v159, v168
	ds_bpermute_b32 v179, v159, v171
	ds_bpermute_b32 v178, v159, v170
	s_waitcnt lgkmcnt(6)
	v_add_f32_e32 v164, v164, v172
	v_add_f32_e32 v165, v165, v173
	s_waitcnt lgkmcnt(4)
	v_add_f32_e32 v166, v166, v174
	v_add_f32_e32 v167, v167, v175
	s_waitcnt lgkmcnt(2)
	v_add_f32_e32 v168, v168, v176
	v_add_f32_e32 v169, v169, v177
	ds_bpermute_b32 v173, v160, v165
	s_waitcnt lgkmcnt(1)
	v_add_f32_e32 v170, v170, v178
	v_add_f32_e32 v171, v171, v179
	ds_bpermute_b32 v172, v160, v164
	ds_bpermute_b32 v175, v160, v167
	ds_bpermute_b32 v174, v160, v166
	ds_bpermute_b32 v177, v160, v169
	ds_bpermute_b32 v176, v160, v168
	ds_bpermute_b32 v179, v160, v171
	ds_bpermute_b32 v178, v160, v170
	s_waitcnt lgkmcnt(6)
	v_add_f32_e32 v164, v164, v172
	v_add_f32_e32 v165, v165, v173
	s_waitcnt lgkmcnt(4)
	v_add_f32_e32 v166, v166, v174
	v_add_f32_e32 v167, v167, v175
	s_waitcnt lgkmcnt(2)
	v_add_f32_e32 v168, v168, v176
	v_add_f32_e32 v169, v169, v177
	ds_bpermute_b32 v173, v161, v165
	s_waitcnt lgkmcnt(1)
	v_add_f32_e32 v170, v170, v178
	v_add_f32_e32 v171, v171, v179
	ds_bpermute_b32 v172, v161, v164
	ds_bpermute_b32 v175, v161, v167
	ds_bpermute_b32 v174, v161, v166
	ds_bpermute_b32 v177, v161, v169
	ds_bpermute_b32 v176, v161, v168
	ds_bpermute_b32 v179, v161, v171
	ds_bpermute_b32 v178, v161, v170
	s_waitcnt lgkmcnt(6)
	v_add_f32_e32 v164, v164, v172
	v_add_f32_e32 v165, v165, v173
	s_waitcnt lgkmcnt(4)
	v_add_f32_e32 v166, v166, v174
	v_add_f32_e32 v167, v167, v175
	s_waitcnt lgkmcnt(2)
; template <int MODE, bool XBF>
; __device__ __forceinline__ void rmsnorm_rows(const void* x, const float* gain, bf16_t* H, int gw, int NGW, int lane, const LAS float* WF, const float* fbias, float* LF) {
;     ...
;         for (int o = 1; o < 64; o <<= 1)
; #pragma unroll
;             for (int r = 0; r < RB; ++r) s[r] += __shfl_xor(s[r], o);
; #pragma unroll
;         for (int r = 0; r < RB; ++r) {
;             const int row = row0 + r;
;             const float rstd = rsqrtf(s[r] * (1.f / D) + 1e-6f);
;             const size_t hrow = MODE == 2 ? (size_t)row + (row >> 12) + 1 : (size_t)row;
; #pragma unroll
;             for (int j = 0; j < 2; ++j) { v[r][j][0] = v[r][j][0] * rstd * g[j][0]; v[r][j][1] = v[r][j][1] * rstd * g[j][1];
	v_add_f32_e32 v168, v168, v176
	v_add_f32_e32 v169, v169, v177
	ds_bpermute_b32 v173, v162, v165
	s_waitcnt lgkmcnt(1)
	v_add_f32_e32 v170, v170, v178
	v_add_f32_e32 v171, v171, v179
	ds_bpermute_b32 v172, v162, v164
	ds_bpermute_b32 v175, v162, v167
	ds_bpermute_b32 v174, v162, v166
	ds_bpermute_b32 v177, v162, v169
	ds_bpermute_b32 v176, v162, v168
	ds_bpermute_b32 v179, v162, v171
	ds_bpermute_b32 v178, v162, v170
	s_waitcnt lgkmcnt(6)
	v_add_f32_e32 v164, v164, v172
	v_add_f32_e32 v165, v165, v173
	s_waitcnt lgkmcnt(4)
	v_add_f32_e32 v166, v166, v174
	v_add_f32_e32 v167, v167, v175
	s_waitcnt lgkmcnt(2)
	v_add_f32_e32 v168, v168, v176
	v_add_f32_e32 v169, v169, v177
	v_fma_f32 v164, v164, s30, v20
	v_fma_f32 v165, v165, s30, v20
	s_waitcnt lgkmcnt(0)
	v_add_f32_e32 v170, v170, v178
	v_add_f32_e32 v171, v171, v179
	v_fma_f32 v166, v166, s30, v20
	v_fma_f32 v167, v167, s30, v20
	v_fma_f32 v168, v168, s30, v20
	v_fma_f32 v169, v169, s30, v20
	v_fma_f32 v21, v171, s30, v20
	v_fma_f32 v20, v170, s30, v20
	v_mul_f32_e32 v163, 0x4b800000, v165
	v_cmp_gt_f32_e64 s[2:3], s31, v165
	v_mul_f32_e32 v170, 0x4b800000, v164
	v_cmp_gt_f32_e32 vcc, s31, v164
	v_mul_f32_e32 v171, 0x4b800000, v167
	v_mul_f32_e32 v172, 0x4b800000, v166
	v_cmp_gt_f32_e64 s[4:5], s31, v166
	v_cmp_gt_f32_e64 s[6:7], s31, v167
	v_mul_f32_e32 v173, 0x4b800000, v169
	v_mul_f32_e32 v174, 0x4b800000, v168
	v_cmp_gt_f32_e64 s[8:9], s31, v168
	v_cmp_gt_f32_e64 s[10:11], s31, v169
	v_mul_f32_e32 v175, 0x4b800000, v21
	v_mul_f32_e32 v176, 0x4b800000, v20
	v_cmp_gt_f32_e64 s[12:13], s31, v20
	v_cndmask_b32_e64 v163, v165, v163, s[2:3]
	v_cmp_gt_f32_e64 s[14:15], s31, v21
	v_cndmask_b32_e32 v164, v164, v170, vcc
	v_cndmask_b32_e64 v165, v167, v171, s[6:7]
	v_cndmask_b32_e64 v166, v166, v172, s[4:5]
	v_cndmask_b32_e64 v167, v169, v173, s[10:11]
	v_cndmask_b32_e64 v168, v168, v174, s[8:9]
	v_cndmask_b32_e64 v21, v21, v175, s[14:15]
	v_cndmask_b32_e64 v20, v20, v176, s[12:13]
	v_rsq_f32_e32 v163, v163
	v_rsq_f32_e32 v164, v164
	v_rsq_f32_e32 v165, v165
	v_rsq_f32_e32 v169, v166
	v_rsq_f32_e32 v167, v167
	v_rsq_f32_e32 v171, v168
	v_rsq_f32_e32 v21, v21
	v_rsq_f32_e32 v173, v20
	v_mul_f32_e32 v20, 0x45800000, v163
	v_mul_f32_e32 v166, 0x45800000, v164
	v_mul_f32_e32 v168, 0x45800000, v165
	v_mul_f32_e32 v170, 0x45800000, v169
	v_mul_f32_e32 v172, 0x45800000, v167
	v_mul_f32_e32 v174, 0x45800000, v171
	v_mul_f32_e32 v175, 0x45800000, v21
	v_mul_f32_e32 v176, 0x45800000, v173
	v_cndmask_b32_e64 v20, v163, v20, s[2:3]
	v_cndmask_b32_e32 v164, v164, v166, vcc
	v_cndmask_b32_e64 v166, v165, v168, s[6:7]
	v_cndmask_b32_e64 v168, v169, v170, s[4:5]
	v_cndmask_b32_e64 v170, v167, v172, s[10:11]
	v_cndmask_b32_e64 v172, v171, v174, s[8:9]
	v_cndmask_b32_e64 v174, v21, v175, s[14:15]
	v_cndmask_b32_e64 v176, v173, v176, s[12:13]
	v_mul_f32_e32 v18, v20, v18
	v_mul_f32_e32 v19, v20, v19
	v_mul_f32_e32 v30, v20, v30
	v_mul_f32_e32 v31, v20, v31
	v_mul_f32_e32 v32, v20, v32
	v_mul_f32_e32 v33, v20, v33
	v_mul_f32_e32 v34, v20, v34
	v_mul_f32_e32 v35, v20, v35
	v_mul_f32_e32 v36, v20, v36
	v_mul_f32_e32 v37, v20, v37
	v_mul_f32_e32 v40, v20, v40
	v_mul_f32_e32 v41, v20, v41
	v_mul_f32_e32 v42, v20, v42
	v_mul_f32_e32 v43, v20, v43
	v_mul_f32_e32 v21, v20, v39
	v_mul_f32_e32 v20, v20, v38
	v_mul_f32_e32 v38, v164, v44
	v_mul_f32_e32 v39, v164, v45
	v_mul_f32_e32 v44, v164, v46
	v_mul_f32_e32 v45, v164, v47
	v_mul_f32_e32 v46, v164, v48
	v_mul_f32_e32 v47, v164, v49
	v_mul_f32_e32 v48, v164, v50
	v_mul_f32_e32 v49, v164, v51
	v_mul_f32_e32 v50, v164, v52
	v_mul_f32_e32 v51, v164, v53
	v_mul_f32_e32 v52, v164, v56
	v_mul_f32_e32 v53, v164, v57
	v_mul_f32_e32 v56, v164, v58
	v_mul_f32_e32 v57, v164, v59
	v_mul_f32_e32 v54, v164, v54
	v_mul_f32_e32 v55, v164, v55
	v_mul_f32_e32 v58, v166, v60
	v_mul_f32_e32 v59, v166, v61
	v_mul_f32_e32 v60, v166, v62
	v_mul_f32_e32 v61, v166, v63
	v_mul_f32_e32 v62, v166, v64
	v_mul_f32_e32 v63, v166, v65
	v_mul_f32_e32 v64, v166, v66
	v_mul_f32_e32 v65, v166, v67
	v_mul_f32_e32 v66, v166, v68
	v_mul_f32_e32 v67, v166, v69
	v_mul_f32_e32 v68, v166, v72
	v_mul_f32_e32 v69, v166, v73
	v_mul_f32_e32 v72, v166, v74
	v_mul_f32_e32 v73, v166, v75
	v_mul_f32_e32 v70, v166, v70
	v_mul_f32_e32 v71, v166, v71
	v_mul_f32_e32 v74, v168, v76
	v_mul_f32_e32 v75, v168, v77
	v_mul_f32_e32 v76, v168, v78
	v_mul_f32_e32 v77, v168, v79
	v_mul_f32_e32 v78, v168, v80
	v_mul_f32_e32 v79, v168, v81
	v_mul_f32_e32 v80, v168, v82
	v_mul_f32_e32 v81, v168, v83
	v_mul_f32_e32 v82, v168, v84
	v_mul_f32_e32 v83, v168, v85
	v_mul_f32_e32 v84, v168, v88
	v_mul_f32_e32 v85, v168, v89
	v_mul_f32_e32 v88, v168, v90
	v_mul_f32_e32 v89, v168, v91
	v_mul_f32_e32 v86, v168, v86
	v_mul_f32_e32 v87, v168, v87
	v_mul_f32_e32 v90, v170, v92
	v_mul_f32_e32 v91, v170, v93
	v_mul_f32_e32 v92, v170, v94
	v_mul_f32_e32 v93, v170, v95
	v_mul_f32_e32 v94, v170, v96
	v_mul_f32_e32 v95, v170, v97
	v_mul_f32_e32 v96, v170, v98
	v_mul_f32_e32 v97, v170, v99
	v_mul_f32_e32 v98, v170, v100
	v_mul_f32_e32 v99, v170, v101
	v_mul_f32_e32 v100, v170, v104
	v_mul_f32_e32 v101, v170, v105
	v_mul_f32_e32 v104, v170, v106
	v_mul_f32_e32 v105, v170, v107
	v_mul_f32_e32 v102, v170, v102
	v_mul_f32_e32 v103, v170, v103
	v_mul_f32_e32 v106, v172, v108
	v_mul_f32_e32 v107, v172, v109
	v_mul_f32_e32 v108, v172, v110
	v_mul_f32_e32 v109, v172, v111
	v_mul_f32_e32 v110, v172, v112
	v_mul_f32_e32 v111, v172, v113
	v_mul_f32_e32 v112, v172, v114
	v_mul_f32_e32 v113, v172, v115
	v_mul_f32_e32 v114, v172, v116
	v_mul_f32_e32 v115, v172, v117
	v_mul_f32_e32 v116, v172, v120
	v_mul_f32_e32 v117, v172, v121
	v_mul_f32_e32 v120, v172, v122
; #define GAS __attribute__((address_space(1)))
; template <int MODE, bool XBF>
; __device__ __forceinline__ void rmsnorm_rows(const void* x, const float* gain, bf16_t* H, int gw, int NGW, int lane, const LAS float* WF, const float* fbias, float* LF) {
;     ...
;             const float rstd = rsqrtf(s[r] * (1.f / D) + 1e-6f);
;             const size_t hrow = MODE == 2 ? (size_t)row + (row >> 12) + 1 : (size_t)row;
; #pragma unroll
;             for (int j = 0; j < 2; ++j) { v[r][j][0] = v[r][j][0] * rstd * g[j][0]; v[r][j][1] = v[r][j][1] * rstd * g[j][1];
;                 *(GAS u32x4*)(H + hrow * D + 512 * j + lane * 8) = pack8(v[r][j][0], v[r][j][1]); }
	v_mul_f32_e32 v121, v172, v123
	v_mul_f32_e32 v118, v172, v118
	v_mul_f32_e32 v119, v172, v119
	v_mul_f32_e32 v122, v174, v124
	v_mul_f32_e32 v123, v174, v125
	v_mul_f32_e32 v124, v174, v126
	v_mul_f32_e32 v125, v174, v127
	v_mul_f32_e32 v126, v174, v128
	v_mul_f32_e32 v127, v174, v129
	v_mul_f32_e32 v128, v174, v130
	v_mul_f32_e32 v129, v174, v131
	v_mul_f32_e32 v130, v174, v132
	v_mul_f32_e32 v131, v174, v133
	v_mul_f32_e32 v132, v174, v136
	v_mul_f32_e32 v133, v174, v137
	v_mul_f32_e32 v136, v174, v138
	v_mul_f32_e32 v137, v174, v139
	v_mul_f32_e32 v134, v174, v134
	v_mul_f32_e32 v135, v174, v135
	v_mul_f32_e32 v138, v176, v140
	v_mul_f32_e32 v139, v176, v141
	v_mul_f32_e32 v140, v176, v142
	v_mul_f32_e32 v141, v176, v143
	v_mul_f32_e32 v142, v176, v144
	v_mul_f32_e32 v143, v176, v145
	v_mul_f32_e32 v144, v176, v146
	v_mul_f32_e32 v145, v176, v147
	v_mul_f32_e32 v146, v176, v148
	v_mul_f32_e32 v147, v176, v149
	v_mul_f32_e32 v148, v176, v152
	v_mul_f32_e32 v149, v176, v153
	v_mul_f32_e32 v152, v176, v154
	v_mul_f32_e32 v153, v176, v155
	v_mul_f32_e32 v150, v176, v150
	v_mul_f32_e32 v151, v176, v151
	v_mul_f32_e32 v30, v2, v30
	v_mul_f32_e32 v31, v3, v31
	v_mul_f32_e32 v18, v0, v18
	v_mul_f32_e32 v19, v1, v19
	v_mul_f32_e32 v34, v10, v34
	v_mul_f32_e32 v35, v11, v35
	v_mul_f32_e32 v32, v8, v32
	v_mul_f32_e32 v33, v9, v33
	v_mul_f32_e32 v40, v14, v40
	v_mul_f32_e32 v41, v15, v41
	v_mul_f32_e32 v36, v12, v36
	v_mul_f32_e32 v37, v13, v37
	v_mul_f32_e32 v154, v6, v20
	v_mul_f32_e32 v155, v7, v21
	v_mul_f32_e32 v42, v4, v42
	v_mul_f32_e32 v43, v5, v43
	v_mul_f32_e32 v44, v2, v44
	v_mul_f32_e32 v45, v3, v45
	v_mul_f32_e32 v38, v0, v38
	v_mul_f32_e32 v39, v1, v39
	v_mul_f32_e32 v48, v10, v48
	v_mul_f32_e32 v49, v11, v49
	v_mul_f32_e32 v46, v8, v46
	v_mul_f32_e32 v47, v9, v47
	v_mul_f32_e32 v52, v14, v52
	v_mul_f32_e32 v53, v15, v53
	v_mul_f32_e32 v50, v12, v50
	v_mul_f32_e32 v51, v13, v51
	v_mul_f32_e32 v54, v6, v54
	v_mul_f32_e32 v55, v7, v55
	v_mul_f32_e32 v56, v4, v56
	v_mul_f32_e32 v57, v5, v57
	v_mul_f32_e32 v60, v2, v60
	v_mul_f32_e32 v61, v3, v61
	v_mul_f32_e32 v58, v0, v58
	v_mul_f32_e32 v59, v1, v59
	v_mul_f32_e32 v64, v10, v64
	v_mul_f32_e32 v65, v11, v65
	v_mul_f32_e32 v62, v8, v62
	v_mul_f32_e32 v63, v9, v63
	v_mul_f32_e32 v68, v14, v68
	v_mul_f32_e32 v69, v15, v69
	v_mul_f32_e32 v66, v12, v66
	v_mul_f32_e32 v67, v13, v67
	v_mul_f32_e32 v70, v6, v70
	v_mul_f32_e32 v71, v7, v71
	v_mul_f32_e32 v72, v4, v72
	v_mul_f32_e32 v73, v5, v73
	v_mul_f32_e32 v76, v2, v76
	v_mul_f32_e32 v77, v3, v77
	v_mul_f32_e32 v74, v0, v74
	v_mul_f32_e32 v75, v1, v75
	v_mul_f32_e32 v80, v10, v80
	v_mul_f32_e32 v81, v11, v81
	v_mul_f32_e32 v78, v8, v78
	v_mul_f32_e32 v79, v9, v79
	v_mul_f32_e32 v84, v14, v84
	v_mul_f32_e32 v85, v15, v85
	v_mul_f32_e32 v82, v12, v82
	v_mul_f32_e32 v83, v13, v83
	v_mul_f32_e32 v86, v6, v86
	v_mul_f32_e32 v87, v7, v87
	v_mul_f32_e32 v88, v4, v88
	v_mul_f32_e32 v89, v5, v89
	v_mul_f32_e32 v92, v2, v92
	v_mul_f32_e32 v93, v3, v93
	v_mul_f32_e32 v90, v0, v90
	v_mul_f32_e32 v91, v1, v91
	v_mul_f32_e32 v96, v10, v96
	v_mul_f32_e32 v97, v11, v97
	v_mul_f32_e32 v94, v8, v94
	v_mul_f32_e32 v95, v9, v95
	v_mul_f32_e32 v100, v14, v100
	v_mul_f32_e32 v101, v15, v101
	v_mul_f32_e32 v98, v12, v98
	v_mul_f32_e32 v99, v13, v99
	v_mul_f32_e32 v102, v6, v102
	v_mul_f32_e32 v103, v7, v103
	v_mul_f32_e32 v104, v4, v104
	v_mul_f32_e32 v105, v5, v105
	v_mul_f32_e32 v108, v2, v108
	v_mul_f32_e32 v109, v3, v109
	v_mul_f32_e32 v106, v0, v106
	v_mul_f32_e32 v107, v1, v107
	v_mul_f32_e32 v112, v10, v112
	v_mul_f32_e32 v113, v11, v113
	v_mul_f32_e32 v110, v8, v110
	v_mul_f32_e32 v111, v9, v111
	v_mul_f32_e32 v116, v14, v116
	v_mul_f32_e32 v117, v15, v117
	v_mul_f32_e32 v114, v12, v114
	v_mul_f32_e32 v115, v13, v115
	v_mul_f32_e32 v118, v6, v118
	v_mul_f32_e32 v119, v7, v119
	v_mul_f32_e32 v120, v4, v120
	v_mul_f32_e32 v121, v5, v121
	v_mul_f32_e32 v124, v2, v124
	v_mul_f32_e32 v125, v3, v125
	v_mul_f32_e32 v122, v0, v122
; #define GAS __attribute__((address_space(1)))
; template <int MODE, bool XBF>
; __device__ __forceinline__ void rmsnorm_rows(const void* x, const float* gain, bf16_t* H, int gw, int NGW, int lane, const LAS float* WF, const float* fbias, float* LF) {
;     ...
;         for (int r = 0; r < RB; ++r) {
;             const int row = row0 + r;
;             const float rstd = rsqrtf(s[r] * (1.f / D) + 1e-6f);
;             const size_t hrow = MODE == 2 ? (size_t)row + (row >> 12) + 1 : (size_t)row;
; #pragma unroll
;             for (int j = 0; j < 2; ++j) { v[r][j][0] = v[r][j][0] * rstd * g[j][0]; v[r][j][1] = v[r][j][1] * rstd * g[j][1];
;                 *(GAS u32x4*)(H + hrow * D + 512 * j + lane * 8) = pack8(v[r][j][0], v[r][j][1]); }
	v_mul_f32_e32 v123, v1, v123
	v_mul_f32_e32 v128, v10, v128
	v_mul_f32_e32 v129, v11, v129
	v_mul_f32_e32 v126, v8, v126
	v_mul_f32_e32 v127, v9, v127
	v_mul_f32_e32 v132, v14, v132
	v_mul_f32_e32 v133, v15, v133
	v_mul_f32_e32 v130, v12, v130
	v_mul_f32_e32 v131, v13, v131
	v_mul_f32_e32 v134, v6, v134
	v_mul_f32_e32 v135, v7, v135
	v_mul_f32_e32 v136, v4, v136
	v_mul_f32_e32 v137, v5, v137
	v_mul_f32_e32 v140, v2, v140
	v_mul_f32_e32 v141, v3, v141
	v_mul_f32_e32 v138, v0, v138
	v_mul_f32_e32 v139, v1, v139
	v_mul_f32_e32 v144, v10, v144
	v_mul_f32_e32 v145, v11, v145
	v_mul_f32_e32 v142, v8, v142
	v_mul_f32_e32 v143, v9, v143
	v_mul_f32_e32 v148, v14, v148
	v_mul_f32_e32 v149, v15, v149
	v_mul_f32_e32 v146, v12, v146
	v_mul_f32_e32 v147, v13, v147
	v_mul_f32_e32 v150, v6, v150
	v_mul_f32_e32 v151, v7, v151
	v_mul_f32_e32 v152, v4, v152
	v_mul_f32_e32 v153, v5, v153
	v_cvt_pk_bf16_f32 v18, v18, v19
	v_cvt_pk_bf16_f32 v19, v30, v31
	v_cvt_pk_bf16_f32 v20, v32, v33
	v_cvt_pk_bf16_f32 v21, v34, v35
	v_cvt_pk_bf16_f32 v30, v36, v37
	v_cvt_pk_bf16_f32 v31, v40, v41
	v_cvt_pk_bf16_f32 v32, v42, v43
	v_cvt_pk_bf16_f32 v33, v154, v155
	v_cvt_pk_bf16_f32 v34, v38, v39
	v_cvt_pk_bf16_f32 v35, v44, v45
	v_cvt_pk_bf16_f32 v36, v46, v47
	v_cvt_pk_bf16_f32 v37, v48, v49
	v_cvt_pk_bf16_f32 v38, v50, v51
	v_cvt_pk_bf16_f32 v39, v52, v53
	v_cvt_pk_bf16_f32 v40, v56, v57
	v_cvt_pk_bf16_f32 v41, v54, v55
	v_cvt_pk_bf16_f32 v42, v58, v59
	v_cvt_pk_bf16_f32 v43, v60, v61
	v_cvt_pk_bf16_f32 v44, v62, v63
	v_cvt_pk_bf16_f32 v45, v64, v65
	v_cvt_pk_bf16_f32 v46, v66, v67
	v_cvt_pk_bf16_f32 v47, v68, v69
	v_cvt_pk_bf16_f32 v48, v72, v73
	v_cvt_pk_bf16_f32 v49, v70, v71
	v_cvt_pk_bf16_f32 v50, v74, v75
	v_cvt_pk_bf16_f32 v51, v76, v77
	v_cvt_pk_bf16_f32 v52, v78, v79
	v_cvt_pk_bf16_f32 v53, v80, v81
	v_cvt_pk_bf16_f32 v54, v82, v83
	v_cvt_pk_bf16_f32 v55, v84, v85
	v_cvt_pk_bf16_f32 v56, v88, v89
	v_cvt_pk_bf16_f32 v57, v86, v87
	v_cvt_pk_bf16_f32 v58, v90, v91
	v_cvt_pk_bf16_f32 v59, v92, v93
	v_cvt_pk_bf16_f32 v60, v94, v95
	v_cvt_pk_bf16_f32 v61, v96, v97
	v_cvt_pk_bf16_f32 v62, v98, v99
	v_cvt_pk_bf16_f32 v63, v100, v101
	v_cvt_pk_bf16_f32 v64, v104, v105
	v_cvt_pk_bf16_f32 v65, v102, v103
	v_cvt_pk_bf16_f32 v66, v106, v107
	v_cvt_pk_bf16_f32 v67, v108, v109
	v_cvt_pk_bf16_f32 v68, v110, v111
	v_cvt_pk_bf16_f32 v69, v112, v113
	v_cvt_pk_bf16_f32 v70, v114, v115
	v_cvt_pk_bf16_f32 v71, v116, v117
	v_cvt_pk_bf16_f32 v72, v120, v121
	v_cvt_pk_bf16_f32 v73, v118, v119
	v_cvt_pk_bf16_f32 v74, v122, v123
	v_cvt_pk_bf16_f32 v75, v124, v125
	v_cvt_pk_bf16_f32 v76, v126, v127
	v_cvt_pk_bf16_f32 v77, v128, v129
	v_cvt_pk_bf16_f32 v78, v130, v131
	v_cvt_pk_bf16_f32 v79, v132, v133
	v_cvt_pk_bf16_f32 v80, v136, v137
	v_cvt_pk_bf16_f32 v81, v134, v135
	v_cvt_pk_bf16_f32 v82, v138, v139
	v_cvt_pk_bf16_f32 v83, v140, v141
	v_cvt_pk_bf16_f32 v84, v142, v143
	v_cvt_pk_bf16_f32 v85, v144, v145
	v_cvt_pk_bf16_f32 v86, v146, v147
	v_cvt_pk_bf16_f32 v87, v148, v149
	v_cvt_pk_bf16_f32 v88, v152, v153
	v_cvt_pk_bf16_f32 v89, v150, v151
	global_store_dwordx4 v[24:25], v[18:21], off
	global_store_dwordx4 v[24:25], v[30:33], off offset:1024
	global_store_dwordx4 v[24:25], v[34:37], off offset:2048
	global_store_dwordx4 v[24:25], v[38:41], off offset:3072
	global_store_dwordx4 v[26:27], v[42:45], off offset:-4096
	global_store_dwordx4 v[28:29], v[46:49], off offset:1024
	global_store_dwordx4 v[28:29], v[50:53], off offset:2048
	global_store_dwordx4 v[28:29], v[54:57], off offset:3072
	global_store_dwordx4 v[26:27], v[58:61], off
	global_store_dwordx4 v[26:27], v[62:65], off offset:1024
	global_store_dwordx4 v[26:27], v[66:69], off offset:2048
	global_store_dwordx4 v[26:27], v[70:73], off offset:3072
	global_store_dwordx4 v[24:25], v[74:77], off offset:-4096
	global_store_dwordx4 v[22:23], v[78:81], off offset:1024
	global_store_dwordx4 v[22:23], v[82:85], off offset:2048
	global_store_dwordx4 v[22:23], v[86:89], off offset:3072
	s_cbranch_scc1 .LBB0_1470

; #define GAS __attribute__((address_space(1)))
; __device__ __forceinline__ float fsigmoid(float x) { return frcp(1.f + fexp2(-x * LOG2E)); }
;     __device__ __forceinline__ void operator()(const Acc& acc, const Unit& u, int wr, int wc, int fr, int fq) const {
;         const int row0 = u.pm * BM + wr * 64 + fr, col0 = u.pn * HALF + wc * 32 + 8 * fq;
; #pragma unroll
;         for (int ai = 0; ai < 2; ++ai)
; #pragma unroll
;             for (int m = 0; m < 4; ++m) {
;                 f32x4 o[2];
; #pragma unroll
;                 for (int n = 0; n < 2; ++n)
; #pragma unroll
;                     for (int j = 0; j < 4; ++j) { const float gx = acc[ai][0][m][n][j]; o[n][j] = gx * fsigmoid(gx) * acc[ai][1][m][n][j]; }
;                 *(GAS u32x4*)(ACT + (size_t)(row0 + ai * HALF + m * 16) * F + col0) = pack8(o[0], o[1]);
;             }
.LBB0_1533:
	v_mul_f32_e32 v148, 0xbfb8aa3b, v124
	v_mul_f32_e32 v149, 0xbfb8aa3b, v125
	v_exp_f32_e32 v148, v148
	v_exp_f32_e32 v149, v149
	v_mov_b32_e32 v147, v141
	s_lshl_b32 s0, s20, 8
	v_add_f32_e32 v148, 1.0, v148
	v_add_f32_e32 v149, 1.0, v149
	v_rcp_f32_e32 v148, v148
	v_rcp_f32_e32 v149, v149
	s_add_i32 s0, s0, s46
	v_and_or_b32 v146, v147, 15, s0
	s_lshl_b32 s0, s55, 7
	v_ashrrev_i32_e32 v147, 1, v147
	s_or_b32 s0, s0, s47
	v_and_b32_e32 v147, -8, v147
	v_add_u32_e32 v150, s0, v147
	v_mul_f32_e32 v124, v124, v148
	v_mul_f32_e32 v125, v125, v149
	v_mul_f32_e32 v147, 0xbfb8aa3b, v126
	v_mul_f32_e32 v148, 0xbfb8aa3b, v127
	v_exp_f32_e32 v147, v147
	v_exp_f32_e32 v148, v148
	v_mul_f32_e32 v116, v124, v116
	v_mul_f32_e32 v117, v125, v117
	v_ashrrev_i32_e32 v151, 31, v150
	v_add_f32_e32 v124, 1.0, v147
	v_add_f32_e32 v125, 1.0, v148
	v_mul_f32_e32 v147, 0xbfb8aa3b, v120
	v_rcp_f32_e32 v124, v124
	v_rcp_f32_e32 v125, v125
	v_exp_f32_e32 v147, v147
	v_mul_f32_e32 v148, 0xbfb8aa3b, v121
	v_exp_f32_e32 v148, v148
	v_mul_f32_e32 v124, v126, v124
	v_mul_f32_e32 v125, v127, v125
	v_add_f32_e32 v126, 1.0, v147
	v_mul_f32_e32 v147, 0xbfb8aa3b, v122
	v_add_f32_e32 v127, 1.0, v148
	v_exp_f32_e32 v147, v147
	v_mul_f32_e32 v148, 0xbfb8aa3b, v123
	v_exp_f32_e32 v149, v148
	v_rcp_f32_e32 v126, v126
	v_add_f32_e32 v147, 1.0, v147
	v_rcp_f32_e32 v127, v127
	v_rcp_f32_e32 v148, v147
	v_add_f32_e32 v147, 1.0, v149
	v_rcp_f32_e32 v149, v147
	v_mul_f32_e32 v120, v120, v126
	v_mul_f32_e32 v121, v121, v127
	v_mul_f32_e32 v118, v124, v118
	v_mul_f32_e32 v119, v125, v119
	v_mul_f32_e32 v112, v120, v112
	v_mul_f32_e32 v113, v121, v113
	v_mul_f32_e32 v120, v122, v148
	v_mul_f32_e32 v121, v123, v149
	v_cvt_pk_bf16_f32 v116, v116, v117
	v_mul_f32_e32 v114, v120, v114
	v_mul_f32_e32 v115, v121, v115
	v_cvt_pk_bf16_f32 v117, v118, v119
	v_cvt_pk_bf16_f32 v119, v114, v115
	v_mul_f32_e32 v114, 0xbfb8aa3b, v108
	v_exp_f32_e32 v114, v114
	v_mul_f32_e32 v115, 0xbfb8aa3b, v109
	v_exp_f32_e32 v115, v115
	v_cvt_pk_bf16_f32 v118, v112, v113
	v_add_f32_e32 v114, 1.0, v114
	v_mov_b64_e32 v[112:113], s[10:11]
	v_rcp_f32_e32 v122, v114
	v_add_f32_e32 v114, 1.0, v115
	v_mad_i64_i32 v[120:121], s[24:25], v146, s54, v[112:113]
	v_rcp_f32_e32 v123, v114
	v_lshlrev_b64 v[114:115], 1, v[150:151]
	v_lshl_add_u64 v[120:121], v[120:121], 0, v[114:115]
	global_store_dwordx4 v[120:121], v[116:119], off
	v_mul_f32_e32 v108, v108, v122
	v_mul_f32_e32 v109, v109, v123
	s_andn2_b64 vcc, exec, s[2:3]
	v_mul_f32_e32 v116, 0xbfb8aa3b, v110
	v_mul_f32_e32 v117, 0xbfb8aa3b, v111
	v_exp_f32_e32 v116, v116
	v_exp_f32_e32 v117, v117
	v_mul_f32_e32 v100, v108, v100
	v_mul_f32_e32 v101, v109, v101
	s_mov_b64 s[2:3], -1
	v_add_f32_e32 v108, 1.0, v116
	v_add_f32_e32 v109, 1.0, v117
	v_mul_f32_e32 v116, 0xbfb8aa3b, v104
	v_mul_f32_e32 v117, 0xbfb8aa3b, v105
	v_rcp_f32_e32 v108, v108
	v_rcp_f32_e32 v109, v109
	v_exp_f32_e32 v116, v116
	v_exp_f32_e32 v117, v117
	v_mul_f32_e32 v108, v110, v108
	v_mul_f32_e32 v109, v111, v109
	v_add_f32_e32 v110, 1.0, v116
	v_add_f32_e32 v111, 1.0, v117
	v_mul_f32_e32 v116, 0xbfb8aa3b, v106
	v_mul_f32_e32 v117, 0xbfb8aa3b, v107
	v_exp_f32_e32 v116, v116
	v_exp_f32_e32 v117, v117
	v_rcp_f32_e32 v110, v110
	v_rcp_f32_e32 v111, v111
	v_add_f32_e32 v116, 1.0, v116
	v_add_f32_e32 v117, 1.0, v117
	v_rcp_f32_e32 v116, v116
	v_rcp_f32_e32 v117, v117
	v_mul_f32_e32 v104, v104, v110
	v_mul_f32_e32 v105, v105, v111
	v_mul_f32_e32 v102, v108, v102
	v_mul_f32_e32 v103, v109, v103
	v_mul_f32_e32 v104, v104, v96
	v_mul_f32_e32 v105, v105, v97
	v_mul_f32_e32 v96, v106, v116
	v_mul_f32_e32 v97, v107, v117
	s_nop 0
	v_mul_f32_e32 v106, v96, v98
	v_mul_f32_e32 v107, v97, v99
	v_cvt_pk_bf16_f32 v96, v100, v101
	v_mul_f32_e32 v100, 0xbfb8aa3b, v92
	v_mul_f32_e32 v101, 0xbfb8aa3b, v93
	v_exp_f32_e32 v100, v100
	v_exp_f32_e32 v101, v101
	v_cvt_pk_bf16_f32 v97, v102, v103
	v_or_b32_e32 v102, 16, v146
	v_mad_i64_i32 v[102:103], s[24:25], v102, s54, v[112:113]
	v_cvt_pk_bf16_f32 v98, v104, v105
	v_cvt_pk_bf16_f32 v99, v106, v107
	v_add_f32_e32 v100, 1.0, v100
	v_add_f32_e32 v101, 1.0, v101
	v_lshl_add_u64 v[102:103], v[102:103], 0, v[114:115]
	v_rcp_f32_e32 v100, v100
	v_rcp_f32_e32 v101, v101
	global_store_dwordx4 v[102:103], v[96:99], off
	v_mul_f32_e32 v92, v92, v100
	v_mul_f32_e32 v93, v93, v101
	s_nop 0
	v_mul_f32_e32 v96, 0xbfb8aa3b, v94
	v_mul_f32_e32 v97, 0xbfb8aa3b, v95
	v_exp_f32_e32 v96, v96
	v_exp_f32_e32 v97, v97
	v_mul_f32_e32 v84, v92, v84
	v_mul_f32_e32 v85, v93, v85
	v_add_f32_e32 v92, 1.0, v96
	v_add_f32_e32 v93, 1.0, v97
	v_mul_f32_e32 v96, 0xbfb8aa3b, v88
	v_mul_f32_e32 v97, 0xbfb8aa3b, v89
	v_rcp_f32_e32 v92, v92
	v_rcp_f32_e32 v93, v93
	v_exp_f32_e32 v96, v96
	v_exp_f32_e32 v97, v97
	v_mul_f32_e32 v92, v94, v92
	v_mul_f32_e32 v93, v95, v93
	v_add_f32_e32 v94, 1.0, v96
	v_add_f32_e32 v95, 1.0, v97
	v_mul_f32_e32 v96, 0xbfb8aa3b, v90
	v_mul_f32_e32 v97, 0xbfb8aa3b, v91
	v_exp_f32_e32 v96, v96
	v_exp_f32_e32 v97, v97
	v_rcp_f32_e32 v94, v94
	v_rcp_f32_e32 v95, v95
	v_add_f32_e32 v96, 1.0, v96
	v_add_f32_e32 v97, 1.0, v97
	v_rcp_f32_e32 v96, v96
	v_rcp_f32_e32 v97, v97
	v_mul_f32_e32 v88, v88, v94
	v_mul_f32_e32 v89, v89, v95
	v_mul_f32_e32 v86, v92, v86
	v_mul_f32_e32 v87, v93, v87
	v_mul_f32_e32 v88, v88, v80
	v_mul_f32_e32 v89, v89, v81
	v_mul_f32_e32 v80, v90, v96
	v_mul_f32_e32 v81, v91, v97
	s_nop 0
	v_mul_f32_e32 v90, v80, v82
	v_mul_f32_e32 v91, v81, v83
	v_cvt_pk_bf16_f32 v80, v84, v85
	v_mul_f32_e32 v84, 0xbfb8aa3b, v76
	v_mul_f32_e32 v85, 0xbfb8aa3b, v77
	v_exp_f32_e32 v84, v84
	v_exp_f32_e32 v85, v85
	v_cvt_pk_bf16_f32 v81, v86, v87
	v_or_b32_e32 v86, 32, v146
; #define GAS __attribute__((address_space(1)))
; __device__ __forceinline__ float fsigmoid(float x) { return frcp(1.f + fexp2(-x * LOG2E)); }
;     __device__ __forceinline__ void operator()(const Acc& acc, const Unit& u, int wr, int wc, int fr, int fq) const {
;         const int row0 = u.pm * BM + wr * 64 + fr, col0 = u.pn * HALF + wc * 32 + 8 * fq;
; #pragma unroll
;         for (int ai = 0; ai < 2; ++ai)
; #pragma unroll
;             for (int m = 0; m < 4; ++m) {
;                 f32x4 o[2];
; #pragma unroll
;                 for (int n = 0; n < 2; ++n)
; #pragma unroll
;                     for (int j = 0; j < 4; ++j) { const float gx = acc[ai][0][m][n][j]; o[n][j] = gx * fsigmoid(gx) * acc[ai][1][m][n][j]; }
;                 *(GAS u32x4*)(ACT + (size_t)(row0 + ai * HALF + m * 16) * F + col0) = pack8(o[0], o[1]);
;             }
	v_mad_i64_i32 v[86:87], s[24:25], v86, s54, v[112:113]
	v_cvt_pk_bf16_f32 v82, v88, v89
	v_cvt_pk_bf16_f32 v83, v90, v91
	v_add_f32_e32 v84, 1.0, v84
	v_add_f32_e32 v85, 1.0, v85
	v_lshl_add_u64 v[86:87], v[86:87], 0, v[114:115]
	v_rcp_f32_e32 v84, v84
	v_rcp_f32_e32 v85, v85
	global_store_dwordx4 v[86:87], v[80:83], off
	v_mul_f32_e32 v76, v76, v84
	v_mul_f32_e32 v77, v77, v85
	s_nop 0
	v_mul_f32_e32 v80, 0xbfb8aa3b, v78
	v_mul_f32_e32 v81, 0xbfb8aa3b, v79
	v_exp_f32_e32 v80, v80
	v_exp_f32_e32 v81, v81
	v_mul_f32_e32 v68, v76, v68
	v_mul_f32_e32 v69, v77, v69
	v_add_f32_e32 v76, 1.0, v80
	v_add_f32_e32 v77, 1.0, v81
	v_mul_f32_e32 v80, 0xbfb8aa3b, v72
	v_mul_f32_e32 v81, 0xbfb8aa3b, v73
	v_rcp_f32_e32 v76, v76
	v_rcp_f32_e32 v77, v77
	v_exp_f32_e32 v80, v80
	v_exp_f32_e32 v81, v81
	v_mul_f32_e32 v76, v78, v76
	v_mul_f32_e32 v77, v79, v77
	v_add_f32_e32 v78, 1.0, v80
	v_add_f32_e32 v79, 1.0, v81
	v_mul_f32_e32 v80, 0xbfb8aa3b, v74
	v_mul_f32_e32 v81, 0xbfb8aa3b, v75
	v_exp_f32_e32 v80, v80
	v_exp_f32_e32 v81, v81
	v_rcp_f32_e32 v78, v78
	v_rcp_f32_e32 v79, v79
	v_add_f32_e32 v80, 1.0, v80
	v_add_f32_e32 v81, 1.0, v81
	v_rcp_f32_e32 v80, v80
	v_rcp_f32_e32 v81, v81
	v_mul_f32_e32 v72, v72, v78
	v_mul_f32_e32 v73, v73, v79
	v_mul_f32_e32 v70, v76, v70
	v_mul_f32_e32 v71, v77, v71
	v_mul_f32_e32 v72, v72, v64
	v_mul_f32_e32 v73, v73, v65
	v_mul_f32_e32 v64, v74, v80
	v_mul_f32_e32 v65, v75, v81
	s_nop 0
	v_mul_f32_e32 v74, v64, v66
	v_mul_f32_e32 v75, v65, v67
	v_cvt_pk_bf16_f32 v64, v68, v69
	v_mul_f32_e32 v69, 0xbfb8aa3b, v60
	v_cvt_pk_bf16_f32 v65, v70, v71
	v_exp_f32_e32 v70, v69
	v_mul_f32_e32 v69, 0xbfb8aa3b, v61
	v_exp_f32_e32 v71, v69
	v_or_b32_e32 v68, 48, v146
	v_mad_i64_i32 v[68:69], s[24:25], v68, s54, v[112:113]
	v_cvt_pk_bf16_f32 v66, v72, v73
	v_cvt_pk_bf16_f32 v67, v74, v75
	v_add_f32_e32 v70, 1.0, v70
	v_add_f32_e32 v71, 1.0, v71
	v_lshl_add_u64 v[68:69], v[68:69], 0, v[114:115]
	v_rcp_f32_e32 v70, v70
	v_rcp_f32_e32 v71, v71
	global_store_dwordx4 v[68:69], v[64:67], off
	v_mul_f32_e32 v60, v60, v70
	v_mul_f32_e32 v61, v61, v71
	s_nop 0
	v_mul_f32_e32 v64, 0xbfb8aa3b, v62
	v_mul_f32_e32 v65, 0xbfb8aa3b, v63
	v_exp_f32_e32 v64, v64
	v_exp_f32_e32 v65, v65
	v_mul_f32_e32 v52, v60, v52
	v_mul_f32_e32 v53, v61, v53
	v_add_u32_e32 v66, 0x80, v146
	v_add_f32_e32 v60, 1.0, v64
	v_add_f32_e32 v61, 1.0, v65
	v_mul_f32_e32 v64, 0xbfb8aa3b, v56
	v_mul_f32_e32 v65, 0xbfb8aa3b, v57
	v_rcp_f32_e32 v60, v60
	v_rcp_f32_e32 v61, v61
	v_exp_f32_e32 v64, v64
	v_exp_f32_e32 v65, v65
	v_mul_f32_e32 v60, v62, v60
	v_mul_f32_e32 v61, v63, v61
	v_add_f32_e32 v62, 1.0, v64
	v_add_f32_e32 v63, 1.0, v65
	v_mul_f32_e32 v64, 0xbfb8aa3b, v58
	v_mul_f32_e32 v65, 0xbfb8aa3b, v59
	v_exp_f32_e32 v64, v64
	v_exp_f32_e32 v65, v65
	v_rcp_f32_e32 v62, v62
	v_rcp_f32_e32 v63, v63
	v_add_f32_e32 v64, 1.0, v64
	v_add_f32_e32 v65, 1.0, v65
	v_rcp_f32_e32 v64, v64
	v_rcp_f32_e32 v65, v65
	v_mul_f32_e32 v56, v56, v62
	v_mul_f32_e32 v57, v57, v63
	v_mul_f32_e32 v54, v60, v54
	v_mul_f32_e32 v55, v61, v55
	v_mul_f32_e32 v56, v56, v48
	v_mul_f32_e32 v57, v57, v49
	v_mul_f32_e32 v48, v58, v64
	v_mul_f32_e32 v49, v59, v65
	s_nop 0
	v_mul_f32_e32 v58, v48, v50
	v_mul_f32_e32 v59, v49, v51
	v_mul_f32_e32 v51, 0xbfb8aa3b, v44
	v_cvt_pk_bf16_f32 v48, v52, v53
	v_exp_f32_e32 v52, v51
	v_mul_f32_e32 v51, 0xbfb8aa3b, v45
	v_exp_f32_e32 v53, v51
	v_cvt_pk_bf16_f32 v49, v54, v55
	v_mad_i64_i32 v[54:55], s[24:25], v66, s54, v[112:113]
	v_cvt_pk_bf16_f32 v50, v56, v57
	v_cvt_pk_bf16_f32 v51, v58, v59
	v_add_f32_e32 v52, 1.0, v52
	v_add_f32_e32 v53, 1.0, v53
	v_lshl_add_u64 v[54:55], v[54:55], 0, v[114:115]
	v_rcp_f32_e32 v52, v52
	v_rcp_f32_e32 v53, v53
	global_store_dwordx4 v[54:55], v[48:51], off
	v_mul_f32_e32 v44, v44, v52
	v_mul_f32_e32 v45, v45, v53
	s_nop 0
	v_mul_f32_e32 v48, 0xbfb8aa3b, v46
	v_mul_f32_e32 v49, 0xbfb8aa3b, v47
	v_exp_f32_e32 v48, v48
	v_exp_f32_e32 v49, v49
	v_mul_f32_e32 v36, v44, v36
	v_mul_f32_e32 v37, v45, v37
	v_add_f32_e32 v44, 1.0, v48
	v_add_f32_e32 v45, 1.0, v49
	v_mul_f32_e32 v48, 0xbfb8aa3b, v40
	v_mul_f32_e32 v49, 0xbfb8aa3b, v41
	v_rcp_f32_e32 v44, v44
	v_rcp_f32_e32 v45, v45
	v_exp_f32_e32 v48, v48
	v_exp_f32_e32 v49, v49
	v_mul_f32_e32 v44, v46, v44
	v_mul_f32_e32 v45, v47, v45
	v_add_f32_e32 v46, 1.0, v48
	v_add_f32_e32 v47, 1.0, v49
	v_mul_f32_e32 v48, 0xbfb8aa3b, v42
; #define GAS __attribute__((address_space(1)))
; __device__ __forceinline__ float fsigmoid(float x) { return frcp(1.f + fexp2(-x * LOG2E)); }
;     __device__ __forceinline__ void operator()(const Acc& acc, const Unit& u, int wr, int wc, int fr, int fq) const {
;         const int row0 = u.pm * BM + wr * 64 + fr, col0 = u.pn * HALF + wc * 32 + 8 * fq;
; #pragma unroll
;         for (int ai = 0; ai < 2; ++ai)
; #pragma unroll
;             for (int m = 0; m < 4; ++m) {
;                 f32x4 o[2];
; #pragma unroll
;                 for (int n = 0; n < 2; ++n)
; #pragma unroll
;                     for (int j = 0; j < 4; ++j) { const float gx = acc[ai][0][m][n][j]; o[n][j] = gx * fsigmoid(gx) * acc[ai][1][m][n][j]; }
;                 *(GAS u32x4*)(ACT + (size_t)(row0 + ai * HALF + m * 16) * F + col0) = pack8(o[0], o[1]);
;             }
	v_mul_f32_e32 v49, 0xbfb8aa3b, v43
	v_exp_f32_e32 v48, v48
	v_exp_f32_e32 v49, v49
	v_rcp_f32_e32 v46, v46
	v_rcp_f32_e32 v47, v47
	v_add_f32_e32 v48, 1.0, v48
	v_add_f32_e32 v49, 1.0, v49
	v_rcp_f32_e32 v48, v48
	v_rcp_f32_e32 v49, v49
	v_mul_f32_e32 v40, v40, v46
	v_mul_f32_e32 v41, v41, v47
	v_mul_f32_e32 v38, v44, v38
	v_mul_f32_e32 v39, v45, v39
	v_mul_f32_e32 v40, v40, v32
	v_mul_f32_e32 v41, v41, v33
	v_mul_f32_e32 v32, v42, v48
	v_mul_f32_e32 v33, v43, v49
	s_nop 0
	v_mul_f32_e32 v42, v32, v34
	v_mul_f32_e32 v43, v33, v35
	v_cvt_pk_bf16_f32 v32, v36, v37
	v_mul_f32_e32 v36, 0xbfb8aa3b, v28
	v_mul_f32_e32 v37, 0xbfb8aa3b, v29
	v_exp_f32_e32 v36, v36
	v_exp_f32_e32 v37, v37
	v_cvt_pk_bf16_f32 v33, v38, v39
	v_add_u32_e32 v38, 0x90, v146
	v_mad_i64_i32 v[38:39], s[24:25], v38, s54, v[112:113]
	v_cvt_pk_bf16_f32 v34, v40, v41
	v_cvt_pk_bf16_f32 v35, v42, v43
	v_add_f32_e32 v36, 1.0, v36
	v_add_f32_e32 v37, 1.0, v37
	v_lshl_add_u64 v[38:39], v[38:39], 0, v[114:115]
	v_rcp_f32_e32 v36, v36
	v_rcp_f32_e32 v37, v37
	global_store_dwordx4 v[38:39], v[32:35], off
	v_mul_f32_e32 v28, v28, v36
	v_mul_f32_e32 v29, v29, v37
	s_nop 0
	v_mul_f32_e32 v32, 0xbfb8aa3b, v30
	v_mul_f32_e32 v33, 0xbfb8aa3b, v31
	v_exp_f32_e32 v32, v32
	v_exp_f32_e32 v33, v33
	v_mul_f32_e32 v20, v28, v20
	v_mul_f32_e32 v21, v29, v21
	v_add_f32_e32 v28, 1.0, v32
	v_add_f32_e32 v29, 1.0, v33
	v_mul_f32_e32 v32, 0xbfb8aa3b, v24
	v_mul_f32_e32 v33, 0xbfb8aa3b, v25
	v_rcp_f32_e32 v28, v28
	v_rcp_f32_e32 v29, v29
	v_exp_f32_e32 v32, v32
	v_exp_f32_e32 v33, v33
	v_mul_f32_e32 v28, v30, v28
	v_mul_f32_e32 v29, v31, v29
	v_add_f32_e32 v30, 1.0, v32
	v_add_f32_e32 v31, 1.0, v33
	v_mul_f32_e32 v32, 0xbfb8aa3b, v26
	v_mul_f32_e32 v33, 0xbfb8aa3b, v27
	v_exp_f32_e32 v32, v32
	v_exp_f32_e32 v33, v33
	v_rcp_f32_e32 v30, v30
	v_rcp_f32_e32 v31, v31
	v_add_f32_e32 v32, 1.0, v32
	v_add_f32_e32 v33, 1.0, v33
	v_rcp_f32_e32 v32, v32
	v_rcp_f32_e32 v33, v33
	v_mul_f32_e32 v24, v24, v30
	v_mul_f32_e32 v25, v25, v31
	v_mul_f32_e32 v22, v28, v22
	v_mul_f32_e32 v23, v29, v23
	v_mul_f32_e32 v24, v24, v16
	v_mul_f32_e32 v25, v25, v17
	v_mul_f32_e32 v16, v26, v32
	v_mul_f32_e32 v17, v27, v33
	s_nop 0
	v_mul_f32_e32 v26, v16, v18
	v_mul_f32_e32 v27, v17, v19
	v_cvt_pk_bf16_f32 v16, v20, v21
	v_mul_f32_e32 v20, 0xbfb8aa3b, v12
	v_mul_f32_e32 v21, 0xbfb8aa3b, v13
	v_exp_f32_e32 v20, v20
	v_exp_f32_e32 v21, v21
	v_cvt_pk_bf16_f32 v17, v22, v23
	v_add_u32_e32 v22, 0xa0, v146
	v_mad_i64_i32 v[22:23], s[24:25], v22, s54, v[112:113]
	v_cvt_pk_bf16_f32 v18, v24, v25
	v_cvt_pk_bf16_f32 v19, v26, v27
	v_add_f32_e32 v20, 1.0, v20
	v_add_f32_e32 v21, 1.0, v21
	v_lshl_add_u64 v[22:23], v[22:23], 0, v[114:115]
	v_rcp_f32_e32 v20, v20
	v_rcp_f32_e32 v21, v21
	global_store_dwordx4 v[22:23], v[16:19], off
	v_mul_f32_e32 v12, v12, v20
	v_mul_f32_e32 v13, v13, v21
	s_nop 0
	v_mul_f32_e32 v16, 0xbfb8aa3b, v14
	v_mul_f32_e32 v17, 0xbfb8aa3b, v15
	v_exp_f32_e32 v16, v16
	v_exp_f32_e32 v17, v17
	v_mul_f32_e32 v4, v12, v4
	v_mul_f32_e32 v5, v13, v5
	v_add_f32_e32 v12, 1.0, v16
	v_add_f32_e32 v13, 1.0, v17
	v_mul_f32_e32 v16, 0xbfb8aa3b, v8
	v_mul_f32_e32 v17, 0xbfb8aa3b, v9
	v_rcp_f32_e32 v12, v12
	v_rcp_f32_e32 v13, v13
	v_exp_f32_e32 v16, v16
	v_exp_f32_e32 v17, v17
	v_mul_f32_e32 v12, v14, v12
	v_mul_f32_e32 v13, v15, v13
	v_add_f32_e32 v14, 1.0, v16
	v_add_f32_e32 v15, 1.0, v17
	v_mul_f32_e32 v16, 0xbfb8aa3b, v10
	v_mul_f32_e32 v17, 0xbfb8aa3b, v11
	v_exp_f32_e32 v16, v16
	v_exp_f32_e32 v17, v17
	v_rcp_f32_e32 v14, v14
	v_rcp_f32_e32 v15, v15
	v_add_f32_e32 v16, 1.0, v16
	v_add_f32_e32 v17, 1.0, v17
	v_rcp_f32_e32 v16, v16
	v_rcp_f32_e32 v17, v17
	v_mul_f32_e32 v8, v8, v14
	v_mul_f32_e32 v9, v9, v15
	v_mul_f32_e32 v6, v12, v6
	v_mul_f32_e32 v7, v13, v7
	v_mul_f32_e32 v8, v8, v0
	v_mul_f32_e32 v9, v9, v1
	v_mul_f32_e32 v0, v10, v16
	v_mul_f32_e32 v1, v11, v17
	s_nop 0
	v_mul_f32_e32 v10, v0, v2
	v_mul_f32_e32 v11, v1, v3
	v_cvt_pk_bf16_f32 v0, v4, v5
	v_add_u32_e32 v4, 0xb0, v146
	v_mad_i64_i32 v[4:5], s[24:25], v4, s54, v[112:113]
	v_cvt_pk_bf16_f32 v1, v6, v7
	v_cvt_pk_bf16_f32 v2, v8, v9
	v_cvt_pk_bf16_f32 v3, v10, v11
	v_lshl_add_u64 v[4:5], v[4:5], 0, v[114:115]
	global_store_dwordx4 v[4:5], v[0:3], off
	s_cbranch_vccnz .LBB0_1526
	s_andn2_b64 vcc, exec, s[6:7]
	s_cbranch_vccnz .LBB0_1525
	s_barrier
	s_branch .LBB0_1525

; #define GAS __attribute__((address_space(1)))
;     __device__ __forceinline__ void operator()(const Acc& acc, const Unit& u, int wr, int wc, int fr, int fq) const {
;     ...
;         for (int ai = 0; ai < 2; ++ai)
; #pragma unroll
;             for (int m = 0; m < 4; ++m) {
;                 const size_t off = (size_t)(row0 + ai * HALF + m * 16) * D + col0;
; #pragma unroll
;                 for (int bj = 0; bj < 2; ++bj) {
;                     const size_t p = off + bj * HALF;
;                     f32x4 b0, b1;
;                     if (BASE_F32) { b0 = *(const GAS f32x4*)((const float*)base + p); b1 = *(const GAS f32x4*)((const float*)base + p + 4); }
;                     else unpack8h(*(const GAS u32x4*)((const bf16_t*)base + p), b0, b1);
;                     b0 += acc[ai][bj][m][0]; b1 += acc[ai][bj][m][1];
;                     if (OUT_F32) { *(GAS f32x4*)((float*)out + p) = b0; *(GAS f32x4*)((float*)out + p + 4) = b1; }
;                     else *(GAS u32x4*)((bf16_t*)out + p) = pack8h(b0, b1);
;                 }
;                 asm volatile("" ::: "memory");
.LBB0_1607:
	v_mov_b32_e32 v140, v147
	s_lshl_b32 s0, s60, 8
	s_add_i32 s0, s0, s50
	v_and_or_b32 v144, v140, 15, s0
	s_lshl_b32 s0, s61, 8
	v_ashrrev_i32_e32 v140, 1, v140
	s_or_b32 s0, s0, s51
	v_and_b32_e32 v140, -8, v140
	v_add_u32_e32 v142, s0, v140
	v_ashrrev_i32_e32 v145, 31, v144
	v_ashrrev_i32_e32 v143, 31, v142
	v_lshlrev_b64 v[140:141], 10, v[144:145]
	v_lshl_add_u64 v[140:141], v[140:141], 0, v[142:143]
	v_lshlrev_b64 v[140:141], 1, v[140:141]
	v_lshl_add_u64 v[156:157], s[12:13], 0, v[140:141]
	global_load_dwordx4 v[152:155], v[156:157], off
	v_lshl_add_u64 v[158:159], s[14:15], 0, v[140:141]
	s_and_b64 vcc, exec, s[2:3]
	s_mov_b64 s[2:3], -1
	s_waitcnt vmcnt(0)
	v_cvt_f32_f16_e32 v160, v153
	v_cvt_f32_f16_sdwa v161, v153 dst_sel:DWORD dst_unused:UNUSED_PAD src0_sel:WORD_1
	v_cvt_f32_f16_e32 v162, v152
	v_cvt_f32_f16_sdwa v163, v152 dst_sel:DWORD dst_unused:UNUSED_PAD src0_sel:WORD_1
	v_cvt_f32_f16_e32 v152, v155
	v_cvt_f32_f16_e32 v164, v154
	v_cvt_f32_f16_sdwa v165, v154 dst_sel:DWORD dst_unused:UNUSED_PAD src0_sel:WORD_1
	v_cvt_f32_f16_sdwa v153, v155 dst_sel:DWORD dst_unused:UNUSED_PAD src0_sel:WORD_1
	v_add_f32_e32 v124, v124, v162
	v_add_f32_e32 v125, v125, v163
	v_add_f32_e32 v126, v126, v160
	v_add_f32_e32 v127, v127, v161
	v_add_f32_e32 v120, v120, v164
	v_add_f32_e32 v121, v121, v165
	v_add_f32_e32 v122, v122, v152
	v_add_f32_e32 v123, v123, v153
	s_nop 0
	v_cvt_pk_f16_f32 v123, v122, v123
	v_cvt_pk_f16_f32 v122, v120, v121
	v_cvt_pk_f16_f32 v121, v126, v127
	v_cvt_pk_f16_f32 v120, v124, v125
	global_store_dwordx4 v[158:159], v[120:123], off
	global_load_dwordx4 v[120:123], v[156:157], off offset:256
	v_or_b32_e32 v124, 16, v144
	v_ashrrev_i32_e32 v125, 31, v124
	v_lshlrev_b64 v[124:125], 10, v[124:125]
	v_lshl_add_u64 v[124:125], v[124:125], 0, v[142:143]
	v_lshlrev_b64 v[124:125], 1, v[124:125]
	v_lshl_add_u64 v[126:127], s[12:13], 0, v[124:125]
	s_waitcnt vmcnt(0)
	v_cvt_f32_f16_e32 v152, v121
	v_cvt_f32_f16_sdwa v153, v121 dst_sel:DWORD dst_unused:UNUSED_PAD src0_sel:WORD_1
	v_cvt_f32_f16_e32 v154, v120
	v_cvt_f32_f16_sdwa v155, v120 dst_sel:DWORD dst_unused:UNUSED_PAD src0_sel:WORD_1
	v_cvt_f32_f16_e32 v120, v123
	v_cvt_f32_f16_e32 v156, v122
	v_cvt_f32_f16_sdwa v157, v122 dst_sel:DWORD dst_unused:UNUSED_PAD src0_sel:WORD_1
	v_cvt_f32_f16_sdwa v121, v123 dst_sel:DWORD dst_unused:UNUSED_PAD src0_sel:WORD_1
	v_add_f32_e32 v116, v116, v154
	v_add_f32_e32 v117, v117, v155
	v_add_f32_e32 v118, v118, v152
	v_add_f32_e32 v119, v119, v153
	v_add_f32_e32 v112, v112, v156
	v_add_f32_e32 v113, v113, v157
	v_add_f32_e32 v114, v114, v120
	v_add_f32_e32 v115, v115, v121
	s_nop 0
	v_cvt_pk_f16_f32 v115, v114, v115
	v_cvt_pk_f16_f32 v114, v112, v113
	v_cvt_pk_f16_f32 v113, v118, v119
	v_cvt_pk_f16_f32 v112, v116, v117
	global_store_dwordx4 v[158:159], v[112:115], off offset:256
	global_load_dwordx4 v[112:115], v[126:127], off
	v_lshl_add_u64 v[116:117], s[14:15], 0, v[124:125]
	s_waitcnt vmcnt(0)
	v_cvt_f32_f16_e32 v118, v113
	v_cvt_f32_f16_sdwa v119, v113 dst_sel:DWORD dst_unused:UNUSED_PAD src0_sel:WORD_1
	v_cvt_f32_f16_e32 v120, v112
	v_cvt_f32_f16_sdwa v121, v112 dst_sel:DWORD dst_unused:UNUSED_PAD src0_sel:WORD_1
	v_cvt_f32_f16_e32 v112, v115
	v_cvt_f32_f16_e32 v122, v114
	v_cvt_f32_f16_sdwa v123, v114 dst_sel:DWORD dst_unused:UNUSED_PAD src0_sel:WORD_1
	v_cvt_f32_f16_sdwa v113, v115 dst_sel:DWORD dst_unused:UNUSED_PAD src0_sel:WORD_1
	v_add_f32_e32 v108, v108, v120
	v_add_f32_e32 v109, v109, v121
	v_add_f32_e32 v110, v110, v118
	v_add_f32_e32 v111, v111, v119
	v_add_f32_e32 v104, v104, v122
	v_add_f32_e32 v105, v105, v123
	v_add_f32_e32 v106, v106, v112
	v_add_f32_e32 v107, v107, v113
	s_nop 0
	v_cvt_pk_f16_f32 v107, v106, v107
	v_cvt_pk_f16_f32 v106, v104, v105
	v_cvt_pk_f16_f32 v105, v110, v111
	v_cvt_pk_f16_f32 v104, v108, v109
	global_store_dwordx4 v[116:117], v[104:107], off
	global_load_dwordx4 v[104:107], v[126:127], off offset:256
	v_or_b32_e32 v108, 32, v144
	v_ashrrev_i32_e32 v109, 31, v108
	v_lshlrev_b64 v[108:109], 10, v[108:109]
	v_lshl_add_u64 v[108:109], v[108:109], 0, v[142:143]
	v_lshlrev_b64 v[108:109], 1, v[108:109]
	v_lshl_add_u64 v[110:111], s[12:13], 0, v[108:109]
	s_waitcnt vmcnt(0)
	v_cvt_f32_f16_e32 v112, v105
	v_cvt_f32_f16_sdwa v113, v105 dst_sel:DWORD dst_unused:UNUSED_PAD src0_sel:WORD_1
	v_cvt_f32_f16_e32 v114, v104
	v_cvt_f32_f16_sdwa v115, v104 dst_sel:DWORD dst_unused:UNUSED_PAD src0_sel:WORD_1
	v_cvt_f32_f16_e32 v104, v107
	v_cvt_f32_f16_e32 v118, v106
	v_cvt_f32_f16_sdwa v119, v106 dst_sel:DWORD dst_unused:UNUSED_PAD src0_sel:WORD_1
	v_cvt_f32_f16_sdwa v105, v107 dst_sel:DWORD dst_unused:UNUSED_PAD src0_sel:WORD_1
	v_add_f32_e32 v100, v100, v114
	v_add_f32_e32 v101, v101, v115
	v_add_f32_e32 v102, v102, v112
	v_add_f32_e32 v103, v103, v113
	v_add_f32_e32 v96, v96, v118
	v_add_f32_e32 v97, v97, v119
	v_add_f32_e32 v98, v98, v104
	v_add_f32_e32 v99, v99, v105
	s_nop 0
	v_cvt_pk_f16_f32 v99, v98, v99
	v_cvt_pk_f16_f32 v98, v96, v97
	v_cvt_pk_f16_f32 v97, v102, v103
	v_cvt_pk_f16_f32 v96, v100, v101
	global_store_dwordx4 v[116:117], v[96:99], off offset:256
	global_load_dwordx4 v[96:99], v[110:111], off
	v_lshl_add_u64 v[100:101], s[14:15], 0, v[108:109]
	s_waitcnt vmcnt(0)
; #define GAS __attribute__((address_space(1)))
;     __device__ __forceinline__ void operator()(const Acc& acc, const Unit& u, int wr, int wc, int fr, int fq) const {
;     ...
;         for (int ai = 0; ai < 2; ++ai)
; #pragma unroll
;             for (int m = 0; m < 4; ++m) {
;                 const size_t off = (size_t)(row0 + ai * HALF + m * 16) * D + col0;
; #pragma unroll
;                 for (int bj = 0; bj < 2; ++bj) {
;                     const size_t p = off + bj * HALF;
;                     f32x4 b0, b1;
;                     if (BASE_F32) { b0 = *(const GAS f32x4*)((const float*)base + p); b1 = *(const GAS f32x4*)((const float*)base + p + 4); }
;                     else unpack8h(*(const GAS u32x4*)((const bf16_t*)base + p), b0, b1);
;                     b0 += acc[ai][bj][m][0]; b1 += acc[ai][bj][m][1];
;                     if (OUT_F32) { *(GAS f32x4*)((float*)out + p) = b0; *(GAS f32x4*)((float*)out + p + 4) = b1; }
;                     else *(GAS u32x4*)((bf16_t*)out + p) = pack8h(b0, b1);
;                 }
;                 asm volatile("" ::: "memory");
	v_cvt_f32_f16_e32 v102, v97
	v_cvt_f32_f16_sdwa v103, v97 dst_sel:DWORD dst_unused:UNUSED_PAD src0_sel:WORD_1
	v_cvt_f32_f16_e32 v104, v96
	v_cvt_f32_f16_sdwa v105, v96 dst_sel:DWORD dst_unused:UNUSED_PAD src0_sel:WORD_1
	v_cvt_f32_f16_e32 v96, v99
	v_cvt_f32_f16_e32 v106, v98
	v_cvt_f32_f16_sdwa v107, v98 dst_sel:DWORD dst_unused:UNUSED_PAD src0_sel:WORD_1
	v_cvt_f32_f16_sdwa v97, v99 dst_sel:DWORD dst_unused:UNUSED_PAD src0_sel:WORD_1
	v_add_f32_e32 v92, v92, v104
	v_add_f32_e32 v93, v93, v105
	v_add_f32_e32 v94, v94, v102
	v_add_f32_e32 v95, v95, v103
	v_add_f32_e32 v88, v88, v106
	v_add_f32_e32 v89, v89, v107
	v_add_f32_e32 v90, v90, v96
	v_add_f32_e32 v91, v91, v97
	s_nop 0
	v_cvt_pk_f16_f32 v91, v90, v91
	v_cvt_pk_f16_f32 v90, v88, v89
	v_cvt_pk_f16_f32 v89, v94, v95
	v_cvt_pk_f16_f32 v88, v92, v93
	global_store_dwordx4 v[100:101], v[88:91], off
	global_load_dwordx4 v[88:91], v[110:111], off offset:256
	v_or_b32_e32 v92, 48, v144
	v_ashrrev_i32_e32 v93, 31, v92
	v_lshlrev_b64 v[92:93], 10, v[92:93]
	v_lshl_add_u64 v[92:93], v[92:93], 0, v[142:143]
	v_lshlrev_b64 v[92:93], 1, v[92:93]
	v_lshl_add_u64 v[94:95], s[12:13], 0, v[92:93]
	s_waitcnt vmcnt(0)
	v_cvt_f32_f16_e32 v96, v89
	v_cvt_f32_f16_sdwa v97, v89 dst_sel:DWORD dst_unused:UNUSED_PAD src0_sel:WORD_1
	v_cvt_f32_f16_e32 v98, v88
	v_cvt_f32_f16_sdwa v99, v88 dst_sel:DWORD dst_unused:UNUSED_PAD src0_sel:WORD_1
	v_cvt_f32_f16_e32 v88, v91
	v_cvt_f32_f16_e32 v102, v90
	v_cvt_f32_f16_sdwa v103, v90 dst_sel:DWORD dst_unused:UNUSED_PAD src0_sel:WORD_1
	v_cvt_f32_f16_sdwa v89, v91 dst_sel:DWORD dst_unused:UNUSED_PAD src0_sel:WORD_1
	v_add_f32_e32 v84, v84, v98
	v_add_f32_e32 v85, v85, v99
	v_add_f32_e32 v86, v86, v96
	v_add_f32_e32 v87, v87, v97
	v_add_f32_e32 v80, v80, v102
	v_add_f32_e32 v81, v81, v103
	v_add_f32_e32 v82, v82, v88
	v_add_f32_e32 v83, v83, v89
	s_nop 0
	v_cvt_pk_f16_f32 v83, v82, v83
	v_cvt_pk_f16_f32 v82, v80, v81
	v_cvt_pk_f16_f32 v81, v86, v87
	v_cvt_pk_f16_f32 v80, v84, v85
	global_store_dwordx4 v[100:101], v[80:83], off offset:256
	global_load_dwordx4 v[80:83], v[94:95], off
	v_lshl_add_u64 v[84:85], s[14:15], 0, v[92:93]
	s_waitcnt vmcnt(0)
	v_cvt_f32_f16_e32 v86, v81
	v_cvt_f32_f16_sdwa v87, v81 dst_sel:DWORD dst_unused:UNUSED_PAD src0_sel:WORD_1
	v_cvt_f32_f16_e32 v88, v80
	v_cvt_f32_f16_sdwa v89, v80 dst_sel:DWORD dst_unused:UNUSED_PAD src0_sel:WORD_1
	v_cvt_f32_f16_e32 v80, v83
	v_cvt_f32_f16_e32 v90, v82
	v_cvt_f32_f16_sdwa v91, v82 dst_sel:DWORD dst_unused:UNUSED_PAD src0_sel:WORD_1
	v_cvt_f32_f16_sdwa v81, v83 dst_sel:DWORD dst_unused:UNUSED_PAD src0_sel:WORD_1
	v_add_f32_e32 v76, v76, v88
	v_add_f32_e32 v77, v77, v89
	v_add_f32_e32 v78, v78, v86
	v_add_f32_e32 v79, v79, v87
	v_add_f32_e32 v72, v72, v90
	v_add_f32_e32 v73, v73, v91
	v_add_f32_e32 v74, v74, v80
	v_add_f32_e32 v75, v75, v81
	s_nop 0
	v_cvt_pk_f16_f32 v75, v74, v75
	v_cvt_pk_f16_f32 v74, v72, v73
	v_cvt_pk_f16_f32 v73, v78, v79
	v_cvt_pk_f16_f32 v72, v76, v77
	global_store_dwordx4 v[84:85], v[72:75], off
	global_load_dwordx4 v[72:75], v[94:95], off offset:256
	v_lshl_add_u64 v[76:77], v[140:141], 0, s[16:17]
	v_lshl_add_u64 v[78:79], s[12:13], 0, v[76:77]
	s_waitcnt vmcnt(0)
	v_cvt_f32_f16_e32 v80, v73
	v_cvt_f32_f16_sdwa v81, v73 dst_sel:DWORD dst_unused:UNUSED_PAD src0_sel:WORD_1
	v_cvt_f32_f16_e32 v82, v72
	v_cvt_f32_f16_sdwa v83, v72 dst_sel:DWORD dst_unused:UNUSED_PAD src0_sel:WORD_1
	v_cvt_f32_f16_e32 v72, v75
	v_cvt_f32_f16_e32 v86, v74
	v_cvt_f32_f16_sdwa v87, v74 dst_sel:DWORD dst_unused:UNUSED_PAD src0_sel:WORD_1
	v_cvt_f32_f16_sdwa v73, v75 dst_sel:DWORD dst_unused:UNUSED_PAD src0_sel:WORD_1
	v_add_f32_e32 v68, v68, v82
	v_add_f32_e32 v69, v69, v83
	v_add_f32_e32 v70, v70, v80
	v_add_f32_e32 v71, v71, v81
	v_add_f32_e32 v64, v64, v86
	v_add_f32_e32 v65, v65, v87
	v_add_f32_e32 v66, v66, v72
	v_add_f32_e32 v67, v67, v73
	s_nop 0
	v_cvt_pk_f16_f32 v67, v66, v67
	v_cvt_pk_f16_f32 v66, v64, v65
	v_cvt_pk_f16_f32 v65, v70, v71
	v_cvt_pk_f16_f32 v64, v68, v69
	global_store_dwordx4 v[84:85], v[64:67], off offset:256
	global_load_dwordx4 v[64:67], v[78:79], off
	v_lshl_add_u64 v[68:69], s[14:15], 0, v[76:77]
	s_waitcnt vmcnt(0)
	v_cvt_f32_f16_e32 v70, v65
	v_cvt_f32_f16_sdwa v71, v65 dst_sel:DWORD dst_unused:UNUSED_PAD src0_sel:WORD_1
	v_cvt_f32_f16_e32 v72, v64
	v_cvt_f32_f16_sdwa v73, v64 dst_sel:DWORD dst_unused:UNUSED_PAD src0_sel:WORD_1
	v_cvt_f32_f16_e32 v64, v67
	v_cvt_f32_f16_e32 v74, v66
	v_cvt_f32_f16_sdwa v75, v66 dst_sel:DWORD dst_unused:UNUSED_PAD src0_sel:WORD_1
	v_cvt_f32_f16_sdwa v65, v67 dst_sel:DWORD dst_unused:UNUSED_PAD src0_sel:WORD_1
	v_add_f32_e32 v60, v60, v72
	v_add_f32_e32 v61, v61, v73
	v_add_f32_e32 v62, v62, v70
	v_add_f32_e32 v63, v63, v71
	v_add_f32_e32 v56, v56, v74
	v_add_f32_e32 v57, v57, v75
	v_add_f32_e32 v58, v58, v64
	v_add_f32_e32 v59, v59, v65
	s_nop 0
	v_cvt_pk_f16_f32 v59, v58, v59
	v_cvt_pk_f16_f32 v58, v56, v57
	v_cvt_pk_f16_f32 v57, v62, v63
	v_cvt_pk_f16_f32 v56, v60, v61
	global_store_dwordx4 v[68:69], v[56:59], off
	global_load_dwordx4 v[56:59], v[78:79], off offset:256
	v_lshl_add_u64 v[60:61], v[140:141], 0, s[18:19]
	v_lshl_add_u64 v[62:63], s[12:13], 0, v[60:61]
	s_waitcnt vmcnt(0)
; #define GAS __attribute__((address_space(1)))
;     __device__ __forceinline__ void operator()(const Acc& acc, const Unit& u, int wr, int wc, int fr, int fq) const {
;     ...
;         for (int ai = 0; ai < 2; ++ai)
; #pragma unroll
;             for (int m = 0; m < 4; ++m) {
;                 const size_t off = (size_t)(row0 + ai * HALF + m * 16) * D + col0;
; #pragma unroll
;                 for (int bj = 0; bj < 2; ++bj) {
;                     const size_t p = off + bj * HALF;
;                     f32x4 b0, b1;
;                     if (BASE_F32) { b0 = *(const GAS f32x4*)((const float*)base + p); b1 = *(const GAS f32x4*)((const float*)base + p + 4); }
;                     else unpack8h(*(const GAS u32x4*)((const bf16_t*)base + p), b0, b1);
;                     b0 += acc[ai][bj][m][0]; b1 += acc[ai][bj][m][1];
;                     if (OUT_F32) { *(GAS f32x4*)((float*)out + p) = b0; *(GAS f32x4*)((float*)out + p + 4) = b1; }
;                     else *(GAS u32x4*)((bf16_t*)out + p) = pack8h(b0, b1);
;                 }
;                 asm volatile("" ::: "memory");
	v_cvt_f32_f16_e32 v64, v57
	v_cvt_f32_f16_sdwa v65, v57 dst_sel:DWORD dst_unused:UNUSED_PAD src0_sel:WORD_1
	v_cvt_f32_f16_e32 v66, v56
	v_cvt_f32_f16_sdwa v67, v56 dst_sel:DWORD dst_unused:UNUSED_PAD src0_sel:WORD_1
	v_cvt_f32_f16_e32 v56, v59
	v_cvt_f32_f16_e32 v70, v58
	v_cvt_f32_f16_sdwa v71, v58 dst_sel:DWORD dst_unused:UNUSED_PAD src0_sel:WORD_1
	v_cvt_f32_f16_sdwa v57, v59 dst_sel:DWORD dst_unused:UNUSED_PAD src0_sel:WORD_1
	v_add_f32_e32 v52, v52, v66
	v_add_f32_e32 v53, v53, v67
	v_add_f32_e32 v54, v54, v64
	v_add_f32_e32 v55, v55, v65
	v_add_f32_e32 v48, v48, v70
	v_add_f32_e32 v49, v49, v71
	v_add_f32_e32 v50, v50, v56
	v_add_f32_e32 v51, v51, v57
	s_nop 0
	v_cvt_pk_f16_f32 v51, v50, v51
	v_cvt_pk_f16_f32 v50, v48, v49
	v_cvt_pk_f16_f32 v49, v54, v55
	v_cvt_pk_f16_f32 v48, v52, v53
	global_store_dwordx4 v[68:69], v[48:51], off offset:256
	global_load_dwordx4 v[48:51], v[62:63], off
	v_lshl_add_u64 v[52:53], s[14:15], 0, v[60:61]
	s_waitcnt vmcnt(0)
	v_cvt_f32_f16_e32 v54, v49
	v_cvt_f32_f16_sdwa v55, v49 dst_sel:DWORD dst_unused:UNUSED_PAD src0_sel:WORD_1
	v_cvt_f32_f16_e32 v56, v48
	v_cvt_f32_f16_sdwa v57, v48 dst_sel:DWORD dst_unused:UNUSED_PAD src0_sel:WORD_1
	v_cvt_f32_f16_e32 v48, v51
	v_cvt_f32_f16_e32 v58, v50
	v_cvt_f32_f16_sdwa v59, v50 dst_sel:DWORD dst_unused:UNUSED_PAD src0_sel:WORD_1
	v_cvt_f32_f16_sdwa v49, v51 dst_sel:DWORD dst_unused:UNUSED_PAD src0_sel:WORD_1
	v_add_f32_e32 v44, v44, v56
	v_add_f32_e32 v45, v45, v57
	v_add_f32_e32 v46, v46, v54
	v_add_f32_e32 v47, v47, v55
	v_add_f32_e32 v40, v40, v58
	v_add_f32_e32 v41, v41, v59
	v_add_f32_e32 v42, v42, v48
	v_add_f32_e32 v43, v43, v49
	s_nop 0
	v_cvt_pk_f16_f32 v43, v42, v43
	v_cvt_pk_f16_f32 v42, v40, v41
	v_cvt_pk_f16_f32 v41, v46, v47
	v_cvt_pk_f16_f32 v40, v44, v45
	global_store_dwordx4 v[52:53], v[40:43], off
	global_load_dwordx4 v[40:43], v[62:63], off offset:256
	v_lshl_add_u64 v[44:45], v[140:141], 0, s[20:21]
	v_lshl_add_u64 v[46:47], s[12:13], 0, v[44:45]
	s_waitcnt vmcnt(0)
	v_cvt_f32_f16_e32 v48, v41
	v_cvt_f32_f16_sdwa v49, v41 dst_sel:DWORD dst_unused:UNUSED_PAD src0_sel:WORD_1
	v_cvt_f32_f16_e32 v50, v40
	v_cvt_f32_f16_sdwa v51, v40 dst_sel:DWORD dst_unused:UNUSED_PAD src0_sel:WORD_1
	v_cvt_f32_f16_e32 v40, v43
	v_cvt_f32_f16_e32 v54, v42
	v_cvt_f32_f16_sdwa v55, v42 dst_sel:DWORD dst_unused:UNUSED_PAD src0_sel:WORD_1
	v_cvt_f32_f16_sdwa v41, v43 dst_sel:DWORD dst_unused:UNUSED_PAD src0_sel:WORD_1
	v_add_f32_e32 v36, v36, v50
	v_add_f32_e32 v37, v37, v51
	v_add_f32_e32 v38, v38, v48
	v_add_f32_e32 v39, v39, v49
	v_add_f32_e32 v32, v32, v54
	v_add_f32_e32 v33, v33, v55
	v_add_f32_e32 v34, v34, v40
	v_add_f32_e32 v35, v35, v41
	s_nop 0
	v_cvt_pk_f16_f32 v35, v34, v35
	v_cvt_pk_f16_f32 v34, v32, v33
	v_cvt_pk_f16_f32 v33, v38, v39
	v_cvt_pk_f16_f32 v32, v36, v37
	global_store_dwordx4 v[52:53], v[32:35], off offset:256
	global_load_dwordx4 v[32:35], v[46:47], off
	v_lshl_add_u64 v[36:37], s[14:15], 0, v[44:45]
	s_waitcnt vmcnt(0)
	v_cvt_f32_f16_e32 v38, v33
	v_cvt_f32_f16_sdwa v39, v33 dst_sel:DWORD dst_unused:UNUSED_PAD src0_sel:WORD_1
	v_cvt_f32_f16_e32 v40, v32
	v_cvt_f32_f16_sdwa v41, v32 dst_sel:DWORD dst_unused:UNUSED_PAD src0_sel:WORD_1
	v_cvt_f32_f16_e32 v32, v35
	v_cvt_f32_f16_e32 v42, v34
	v_cvt_f32_f16_sdwa v43, v34 dst_sel:DWORD dst_unused:UNUSED_PAD src0_sel:WORD_1
	v_cvt_f32_f16_sdwa v33, v35 dst_sel:DWORD dst_unused:UNUSED_PAD src0_sel:WORD_1
	v_add_f32_e32 v28, v28, v40
	v_add_f32_e32 v29, v29, v41
	v_add_f32_e32 v30, v30, v38
	v_add_f32_e32 v31, v31, v39
	v_add_f32_e32 v24, v24, v42
	v_add_f32_e32 v25, v25, v43
	v_add_f32_e32 v26, v26, v32
	v_add_f32_e32 v27, v27, v33
	s_nop 0
	v_cvt_pk_f16_f32 v27, v26, v27
	v_cvt_pk_f16_f32 v26, v24, v25
	v_cvt_pk_f16_f32 v25, v30, v31
	v_cvt_pk_f16_f32 v24, v28, v29
	global_store_dwordx4 v[36:37], v[24:27], off
	global_load_dwordx4 v[24:27], v[46:47], off offset:256
	v_lshl_add_u64 v[28:29], v[140:141], 0, s[24:25]
	v_lshl_add_u64 v[30:31], s[12:13], 0, v[28:29]
	s_waitcnt vmcnt(0)
	v_cvt_f32_f16_e32 v32, v25
	v_cvt_f32_f16_sdwa v33, v25 dst_sel:DWORD dst_unused:UNUSED_PAD src0_sel:WORD_1
	v_cvt_f32_f16_e32 v34, v24
	v_cvt_f32_f16_sdwa v35, v24 dst_sel:DWORD dst_unused:UNUSED_PAD src0_sel:WORD_1
	v_cvt_f32_f16_e32 v24, v27
	v_cvt_f32_f16_e32 v38, v26
	v_cvt_f32_f16_sdwa v39, v26 dst_sel:DWORD dst_unused:UNUSED_PAD src0_sel:WORD_1
	v_cvt_f32_f16_sdwa v25, v27 dst_sel:DWORD dst_unused:UNUSED_PAD src0_sel:WORD_1
	v_add_f32_e32 v20, v20, v34
	v_add_f32_e32 v21, v21, v35
	v_add_f32_e32 v22, v22, v32
	v_add_f32_e32 v23, v23, v33
	v_add_f32_e32 v16, v16, v38
	v_add_f32_e32 v17, v17, v39
	v_add_f32_e32 v18, v18, v24
	v_add_f32_e32 v19, v19, v25
	s_nop 0
	v_cvt_pk_f16_f32 v19, v18, v19
	v_cvt_pk_f16_f32 v18, v16, v17
	v_cvt_pk_f16_f32 v17, v22, v23
	v_cvt_pk_f16_f32 v16, v20, v21
	global_store_dwordx4 v[36:37], v[16:19], off offset:256
	global_load_dwordx4 v[16:19], v[30:31], off
	v_lshl_add_u64 v[20:21], s[14:15], 0, v[28:29]
	s_waitcnt vmcnt(0)
	v_cvt_f32_f16_e32 v22, v17
	v_cvt_f32_f16_sdwa v23, v17 dst_sel:DWORD dst_unused:UNUSED_PAD src0_sel:WORD_1
	v_cvt_f32_f16_e32 v24, v16
	v_cvt_f32_f16_sdwa v25, v16 dst_sel:DWORD dst_unused:UNUSED_PAD src0_sel:WORD_1
	v_cvt_f32_f16_e32 v16, v19
	v_cvt_f32_f16_e32 v26, v18
	v_cvt_f32_f16_sdwa v27, v18 dst_sel:DWORD dst_unused:UNUSED_PAD src0_sel:WORD_1
	v_cvt_f32_f16_sdwa v17, v19 dst_sel:DWORD dst_unused:UNUSED_PAD src0_sel:WORD_1
	v_add_f32_e32 v12, v12, v24
	v_add_f32_e32 v13, v13, v25
	v_add_f32_e32 v14, v14, v22
	v_add_f32_e32 v15, v15, v23
	v_add_f32_e32 v8, v8, v26
	v_add_f32_e32 v9, v9, v27
	v_add_f32_e32 v10, v10, v16
	v_add_f32_e32 v11, v11, v17
	s_nop 0
	v_cvt_pk_f16_f32 v11, v10, v11
	v_cvt_pk_f16_f32 v10, v8, v9
	v_cvt_pk_f16_f32 v9, v14, v15
	v_cvt_pk_f16_f32 v8, v12, v13
	global_store_dwordx4 v[20:21], v[8:11], off
	global_load_dwordx4 v[8:11], v[30:31], off offset:256
	s_waitcnt vmcnt(0)
	v_cvt_f32_f16_e32 v12, v9
	v_cvt_f32_f16_sdwa v13, v9 dst_sel:DWORD dst_unused:UNUSED_PAD src0_sel:WORD_1
	v_cvt_f32_f16_e32 v14, v8
	v_cvt_f32_f16_sdwa v15, v8 dst_sel:DWORD dst_unused:UNUSED_PAD src0_sel:WORD_1
	v_cvt_f32_f16_e32 v8, v11
	v_cvt_f32_f16_e32 v16, v10
	v_cvt_f32_f16_sdwa v17, v10 dst_sel:DWORD dst_unused:UNUSED_PAD src0_sel:WORD_1
	v_cvt_f32_f16_sdwa v9, v11 dst_sel:DWORD dst_unused:UNUSED_PAD src0_sel:WORD_1
	v_add_f32_e32 v4, v4, v14
	v_add_f32_e32 v5, v5, v15
	v_add_f32_e32 v6, v6, v12
	v_add_f32_e32 v7, v7, v13
	v_add_f32_e32 v0, v0, v16
	v_add_f32_e32 v1, v1, v17
	v_add_f32_e32 v2, v2, v8
	v_add_f32_e32 v3, v3, v9
	s_nop 0
	v_cvt_pk_f16_f32 v3, v2, v3
	v_cvt_pk_f16_f32 v2, v0, v1
	v_cvt_pk_f16_f32 v1, v6, v7
	v_cvt_pk_f16_f32 v0, v4, v5
	global_store_dwordx4 v[20:21], v[0:3], off offset:256
	s_cbranch_vccnz .LBB0_1592
	s_andn2_b64 vcc, exec, s[8:9]
	s_cbranch_vccnz .LBB0_1591
	s_barrier
	s_branch .LBB0_1591

; #define GAS __attribute__((address_space(1)))
; template <int MODE, bool XBF>
; __device__ __forceinline__ void rmsnorm_rows(const void* x, const float* gain, bf16_t* H, int gw, int NGW, int lane, const LAS float* WF, const float* fbias, float* LF) {
;     ...
; #pragma unroll
;         for (int r = 0; r < RB; ++r)
; #pragma unroll
;             for (int j = 0; j < 2; ++j) { const size_t xo = (size_t)(row0 + r) * D + 512 * j + lane * 8;
;                 if (XBF) unpack8h(*(const GAS u32x4*)((const bf16_t*)x + xo), v[r][j][0], v[r][j][1]);
;                 else { v[r][j][0] = *(const GAS f32x4*)((const float*)x + xo); v[r][j][1] = *(const GAS f32x4*)((const float*)x + xo + 4); } }
; #pragma unroll
;         for (int r = 0; r < RB; ++r) { s[r] = 0.f;
; #pragma unroll
;             for (int j = 0; j < 2; ++j)
; #pragma unroll
;                 for (int e = 0; e < 2; ++e) s[r] += (v[r][j][e][0] * v[r][j][e][0] + v[r][j][e][1] * v[r][j][e][1]) + (v[r][j][e][2] * v[r][j][e][2] + v[r][j][e][3] * v[r][j][e][3]); }
; #pragma unroll
;         for (int o = 1; o < 64; o <<= 1)
; #pragma unroll
;             for (int r = 0; r < RB; ++r) s[r] += __shfl_xor(s[r], o);
; #pragma unroll
;         for (int r = 0; r < RB; ++r) {
;             const int row = row0 + r;
;             const float rstd = rsqrtf(s[r] * (1.f / D) + 1e-6f);
;             const size_t hrow = MODE == 2 ? (size_t)row + (row >> 12) + 1 : (size_t)row;
; #pragma unroll
;             for (int j = 0; j < 2; ++j) { v[r][j][0] = v[r][j][0] * rstd * g[j][0]; v[r][j][1] = v[r][j][1] * rstd * g[j][1];
.LBB0_1682:
	v_lshl_add_u64 v[24:25], s[24:25], 0, v[148:149]
	v_add_co_u32_e32 v26, vcc, s15, v24
	s_ashr_i32 s30, s14, 12
	s_nop 0
	v_addc_co_u32_e32 v27, vcc, 0, v25, vcc
	v_add_co_u32_e32 v24, vcc, 0x5800000, v24
	s_waitcnt lgkmcnt(0)
	global_load_dwordx4 v[16:19], v[26:27], off
	global_load_dwordx4 v[20:23], v[26:27], off offset:1024
	global_load_dwordx4 v[48:51], v[26:27], off offset:2048
	global_load_dwordx4 v[52:55], v[26:27], off offset:3072
	v_addc_co_u32_e32 v25, vcc, 0, v25, vcc
	global_load_dwordx4 v[56:59], v[24:25], off
	global_load_dwordx4 v[60:63], v[24:25], off offset:1024
	global_load_dwordx4 v[80:83], v[24:25], off offset:2048
	global_load_dwordx4 v[84:87], v[24:25], off offset:3072
	s_ashr_i32 s31, s30, 31
	s_lshl_b64 s[30:31], s[30:31], 17
	s_and_b32 s40, s14, 0xffc
	s_waitcnt vmcnt(0)
	v_cvt_f32_f16_e32 v42, v16
	v_cvt_f32_f16_sdwa v43, v16 dst_sel:DWORD dst_unused:UNUSED_PAD src0_sel:WORD_1
	v_cvt_f32_f16_e32 v46, v17
	s_waitcnt vmcnt(3)
	v_cvt_f32_f16_e32 v66, v56
	v_cvt_f32_f16_sdwa v67, v56 dst_sel:DWORD dst_unused:UNUSED_PAD src0_sel:WORD_1
	v_cvt_f32_f16_e32 v78, v57
	v_cvt_f32_f16_sdwa v79, v57 dst_sel:DWORD dst_unused:UNUSED_PAD src0_sel:WORD_1
	v_cvt_f32_f16_e32 v64, v58
	v_cvt_f32_f16_sdwa v65, v58 dst_sel:DWORD dst_unused:UNUSED_PAD src0_sel:WORD_1
	v_cvt_f32_f16_e32 v76, v59
	v_cvt_f32_f16_sdwa v77, v59 dst_sel:DWORD dst_unused:UNUSED_PAD src0_sel:WORD_1
	v_cvt_f32_f16_sdwa v47, v17 dst_sel:DWORD dst_unused:UNUSED_PAD src0_sel:WORD_1
	v_cvt_f32_f16_e32 v40, v18
	v_cvt_f32_f16_sdwa v41, v18 dst_sel:DWORD dst_unused:UNUSED_PAD src0_sel:WORD_1
	v_cvt_f32_f16_e32 v44, v19
	v_cvt_f32_f16_sdwa v45, v19 dst_sel:DWORD dst_unused:UNUSED_PAD src0_sel:WORD_1
	v_cvt_f32_f16_e32 v36, v20
	v_cvt_f32_f16_sdwa v37, v20 dst_sel:DWORD dst_unused:UNUSED_PAD src0_sel:WORD_1
	v_cvt_f32_f16_e32 v38, v21
	v_cvt_f32_f16_sdwa v39, v21 dst_sel:DWORD dst_unused:UNUSED_PAD src0_sel:WORD_1
	v_cvt_f32_f16_sdwa v33, v23 dst_sel:DWORD dst_unused:UNUSED_PAD src0_sel:WORD_1
	v_cvt_f32_f16_e32 v32, v23
	v_cvt_f32_f16_sdwa v35, v22 dst_sel:DWORD dst_unused:UNUSED_PAD src0_sel:WORD_1
	v_cvt_f32_f16_e32 v34, v22
	v_cvt_f32_f16_e32 v26, v48
	v_cvt_f32_f16_sdwa v27, v48 dst_sel:DWORD dst_unused:UNUSED_PAD src0_sel:WORD_1
	v_cvt_f32_f16_e32 v30, v49
	v_cvt_f32_f16_sdwa v31, v49 dst_sel:DWORD dst_unused:UNUSED_PAD src0_sel:WORD_1
	v_cvt_f32_f16_e32 v24, v50
	v_cvt_f32_f16_sdwa v25, v50 dst_sel:DWORD dst_unused:UNUSED_PAD src0_sel:WORD_1
	v_cvt_f32_f16_e32 v28, v51
	v_cvt_f32_f16_sdwa v29, v51 dst_sel:DWORD dst_unused:UNUSED_PAD src0_sel:WORD_1
	v_cvt_f32_f16_e32 v20, v52
	v_cvt_f32_f16_sdwa v21, v52 dst_sel:DWORD dst_unused:UNUSED_PAD src0_sel:WORD_1
	v_cvt_f32_f16_e32 v22, v53
	v_cvt_f32_f16_sdwa v23, v53 dst_sel:DWORD dst_unused:UNUSED_PAD src0_sel:WORD_1
	v_cvt_f32_f16_sdwa v17, v55 dst_sel:DWORD dst_unused:UNUSED_PAD src0_sel:WORD_1
	v_cvt_f32_f16_e32 v16, v55
	v_cvt_f32_f16_sdwa v19, v54 dst_sel:DWORD dst_unused:UNUSED_PAD src0_sel:WORD_1
	v_cvt_f32_f16_e32 v18, v54
	s_waitcnt vmcnt(2)
	v_cvt_f32_f16_e32 v72, v60
	v_cvt_f32_f16_sdwa v73, v60 dst_sel:DWORD dst_unused:UNUSED_PAD src0_sel:WORD_1
	v_cvt_f32_f16_e32 v74, v61
	v_cvt_f32_f16_sdwa v75, v61 dst_sel:DWORD dst_unused:UNUSED_PAD src0_sel:WORD_1
	v_cvt_f32_f16_sdwa v69, v63 dst_sel:DWORD dst_unused:UNUSED_PAD src0_sel:WORD_1
	v_cvt_f32_f16_e32 v68, v63
	v_cvt_f32_f16_sdwa v71, v62 dst_sel:DWORD dst_unused:UNUSED_PAD src0_sel:WORD_1
	v_cvt_f32_f16_e32 v70, v62
	s_waitcnt vmcnt(1)
	v_cvt_f32_f16_e32 v60, v80
	v_cvt_f32_f16_sdwa v61, v80 dst_sel:DWORD dst_unused:UNUSED_PAD src0_sel:WORD_1
	v_cvt_f32_f16_e32 v62, v81
	v_cvt_f32_f16_sdwa v63, v81 dst_sel:DWORD dst_unused:UNUSED_PAD src0_sel:WORD_1
	v_cvt_f32_f16_e32 v56, v82
	v_cvt_f32_f16_sdwa v57, v82 dst_sel:DWORD dst_unused:UNUSED_PAD src0_sel:WORD_1
	v_cvt_f32_f16_e32 v58, v83
	v_cvt_f32_f16_sdwa v59, v83 dst_sel:DWORD dst_unused:UNUSED_PAD src0_sel:WORD_1
	s_waitcnt vmcnt(0)
	v_cvt_f32_f16_e32 v52, v84
	v_cvt_f32_f16_sdwa v53, v84 dst_sel:DWORD dst_unused:UNUSED_PAD src0_sel:WORD_1
	v_cvt_f32_f16_e32 v54, v85
	v_cvt_f32_f16_sdwa v55, v85 dst_sel:DWORD dst_unused:UNUSED_PAD src0_sel:WORD_1
	v_cvt_f32_f16_sdwa v49, v87 dst_sel:DWORD dst_unused:UNUSED_PAD src0_sel:WORD_1
	v_cvt_f32_f16_e32 v48, v87
	v_cvt_f32_f16_sdwa v51, v86 dst_sel:DWORD dst_unused:UNUSED_PAD src0_sel:WORD_1
	v_cvt_f32_f16_e32 v50, v86
	v_mul_f32_e32 v80, v78, v78
	v_mul_f32_e32 v81, v79, v79
	v_mul_f32_e32 v82, v66, v66
	v_mul_f32_e32 v83, v67, v67
	v_mul_f32_e32 v84, v76, v76
	v_mul_f32_e32 v85, v77, v77
	v_mul_f32_e32 v86, v64, v64
	v_mul_f32_e32 v87, v65, v65
	v_pk_mov_b32 v[88:89], v[82:83], v[80:81] op_sel:[1,0]
	v_mov_b32_e32 v83, v81
	v_pk_mov_b32 v[80:81], v[86:87], v[84:85] op_sel:[1,0]
	v_mov_b32_e32 v87, v85
	v_add_f32_e32 v80, v80, v86
	v_add_f32_e32 v81, v81, v87
	v_add_f32_e32 v82, v88, v82
	v_add_f32_e32 v83, v89, v83
	v_add_f32_e32 v81, v80, v81
	v_add_f32_e32 v80, v80, v80
	v_mul_f32_e32 v80, v72, v72
	v_fma_f32 v84, v72, v72, v80
	v_fma_f32 v85, v73, v73, v80
	v_mul_f32_e32 v80, v74, v74
	v_add_f32_e32 v83, v82, v83
	v_add_f32_e32 v82, v82, v82
	v_fma_f32 v86, v74, v74, v80
	v_fma_f32 v87, v75, v75, v80
	v_mul_f32_e32 v82, v70, v70
	v_mul_f32_e32 v80, v71, v71
	v_mul_f32_e32 v84, v68, v68
	v_mul_f32_e32 v86, v69, v69
	v_add_f32_e32 v80, v82, v80
	v_add_f32_e32 v81, v83, v81
	v_add_f32_e32 v82, v84, v86
	v_add_f32_e32 v83, v85, v87
	v_mul_f32_e32 v84, v60, v60
	v_mul_f32_e32 v85, v61, v61
	v_add_f32_e32 v80, v80, v82
	v_add_f32_e32 v81, v81, v83
	v_mul_f32_e32 v82, v62, v62
	v_mul_f32_e32 v83, v63, v63
	v_mov_b32_e32 v93, v80
; #define GAS __attribute__((address_space(1)))
; template <int MODE, bool XBF>
; __device__ __forceinline__ void rmsnorm_rows(const void* x, const float* gain, bf16_t* H, int gw, int NGW, int lane, const LAS float* WF, const float* fbias, float* LF) {
;     ...
;         for (int r = 0; r < RB; ++r) { s[r] = 0.f;
; #pragma unroll
;             for (int j = 0; j < 2; ++j)
; #pragma unroll
;                 for (int e = 0; e < 2; ++e) s[r] += (v[r][j][e][0] * v[r][j][e][0] + v[r][j][e][1] * v[r][j][e][1]) + (v[r][j][e][2] * v[r][j][e][2] + v[r][j][e][3] * v[r][j][e][3]); }
; #pragma unroll
;         for (int o = 1; o < 64; o <<= 1)
; #pragma unroll
;             for (int r = 0; r < RB; ++r) s[r] += __shfl_xor(s[r], o);
; #pragma unroll
;         for (int r = 0; r < RB; ++r) {
;             const int row = row0 + r;
;             const float rstd = rsqrtf(s[r] * (1.f / D) + 1e-6f);
;             const size_t hrow = MODE == 2 ? (size_t)row + (row >> 12) + 1 : (size_t)row;
; #pragma unroll
;             for (int j = 0; j < 2; ++j) { v[r][j][0] = v[r][j][0] * rstd * g[j][0]; v[r][j][1] = v[r][j][1] * rstd * g[j][1];
;                 *(GAS u32x4*)(H + hrow * D + 512 * j + lane * 8) = pack8(v[r][j][0], v[r][j][1]); }
	v_pk_mov_b32 v[86:87], v[84:85], v[82:83] op_sel:[1,0]
	v_mov_b32_e32 v85, v83
	v_add_f32_e32 v82, v86, v84
	v_add_f32_e32 v83, v87, v85
	v_mul_f32_e32 v84, v58, v58
	v_mul_f32_e32 v85, v59, v59
	v_add_f32_e32 v83, v82, v83
	v_add_f32_e32 v82, v82, v82
	v_mul_f32_e32 v86, v56, v56
	v_mul_f32_e32 v87, v57, v57
	v_mul_f32_e32 v82, v52, v52
	v_pk_mov_b32 v[88:89], v[86:87], v[84:85] op_sel:[1,0]
	v_mov_b32_e32 v87, v85
	v_add_f32_e32 v84, v88, v86
	v_add_f32_e32 v85, v89, v87
	v_fma_f32 v86, v52, v52, v82
	v_fma_f32 v87, v53, v53, v82
	v_mul_f32_e32 v82, v54, v54
	v_add_f32_e32 v85, v84, v85
	v_add_f32_e32 v84, v84, v84
	v_fma_f32 v88, v54, v54, v82
	v_fma_f32 v89, v55, v55, v82
	v_mul_f32_e32 v82, v50, v50
	v_mul_f32_e32 v84, v51, v51
	v_mul_f32_e32 v86, v48, v48
	v_mul_f32_e32 v88, v49, v49
	v_add_f32_e32 v82, v82, v84
	v_add_f32_e32 v83, v83, v85
	v_add_f32_e32 v84, v86, v88
	v_add_f32_e32 v85, v87, v89
	v_mul_f32_e32 v86, v42, v42
	v_mul_f32_e32 v87, v43, v43
	v_add_f32_e32 v82, v82, v84
	v_add_f32_e32 v83, v83, v85
	v_mul_f32_e32 v84, v46, v46
	v_mul_f32_e32 v85, v47, v47
	v_mov_b32_e32 v92, v82
	v_mov_b32_e32 v80, v83
	v_add_f32_e32 v80, v92, v80
	v_add_f32_e32 v81, v93, v81
	ds_bpermute_b32 v83, v209, v81
	ds_bpermute_b32 v82, v209, v80
	v_pk_mov_b32 v[88:89], v[86:87], v[84:85] op_sel:[1,0]
	v_mov_b32_e32 v87, v85
	v_add_f32_e32 v84, v88, v86
	v_add_f32_e32 v85, v89, v87
	v_mul_f32_e32 v86, v44, v44
	v_mul_f32_e32 v87, v45, v45
	s_waitcnt lgkmcnt(0)
	v_add_f32_e32 v80, v80, v82
	v_add_f32_e32 v81, v81, v83
	ds_bpermute_b32 v83, v208, v81
	ds_bpermute_b32 v82, v208, v80
	v_add_f32_e32 v85, v84, v85
	v_add_f32_e32 v84, v84, v84
	v_mul_f32_e32 v88, v40, v40
	v_mul_f32_e32 v89, v41, v41
	v_mul_f32_e32 v84, v36, v36
	v_pk_mov_b32 v[90:91], v[88:89], v[86:87] op_sel:[1,0]
	s_waitcnt lgkmcnt(0)
	v_add_f32_e32 v80, v80, v82
	v_add_f32_e32 v81, v81, v83
	ds_bpermute_b32 v83, v207, v81
	ds_bpermute_b32 v82, v207, v80
	v_mov_b32_e32 v89, v87
	v_add_f32_e32 v86, v90, v88
	v_add_f32_e32 v87, v91, v89
	v_fma_f32 v88, v36, v36, v84
	v_fma_f32 v89, v37, v37, v84
	v_mul_f32_e32 v84, v38, v38
	s_waitcnt lgkmcnt(0)
	v_add_f32_e32 v80, v80, v82
	v_add_f32_e32 v81, v81, v83
	ds_bpermute_b32 v83, v206, v81
	ds_bpermute_b32 v82, v206, v80
	v_add_f32_e32 v87, v86, v87
	v_add_f32_e32 v86, v86, v86
	v_fma_f32 v90, v38, v38, v84
	v_fma_f32 v91, v39, v39, v84
	v_mul_f32_e32 v84, v34, v34
	v_mul_f32_e32 v86, v35, v35
	s_waitcnt lgkmcnt(0)
	v_add_f32_e32 v80, v80, v82
	v_add_f32_e32 v81, v81, v83
	ds_bpermute_b32 v83, v205, v81
	ds_bpermute_b32 v82, v205, v80
	v_mul_f32_e32 v88, v32, v32
	v_mul_f32_e32 v90, v33, v33
	v_add_f32_e32 v84, v84, v86
	v_add_f32_e32 v85, v85, v87
	v_add_f32_e32 v86, v88, v90
	v_add_f32_e32 v87, v89, v91
	v_mul_f32_e32 v88, v26, v26
	v_mul_f32_e32 v89, v27, v27
	v_add_f32_e32 v86, v84, v86
	v_add_f32_e32 v87, v85, v87
	v_mul_f32_e32 v84, v30, v30
	v_mul_f32_e32 v85, v31, v31
	s_waitcnt lgkmcnt(0)
	v_add_f32_e32 v80, v80, v82
	v_add_f32_e32 v81, v81, v83
	v_pk_mov_b32 v[90:91], v[88:89], v[84:85] op_sel:[1,0]
	v_mov_b32_e32 v89, v85
	v_add_f32_e32 v84, v90, v88
	v_add_f32_e32 v85, v91, v89
	v_mul_f32_e32 v88, v28, v28
	v_mul_f32_e32 v89, v29, v29
	v_mul_f32_e32 v90, v24, v24
	v_mul_f32_e32 v91, v25, v25
	ds_bpermute_b32 v83, v203, v81
	ds_bpermute_b32 v82, v203, v80
	v_add_f32_e32 v85, v84, v85
	v_add_f32_e32 v84, v84, v84
	v_pk_mov_b32 v[92:93], v[90:91], v[88:89] op_sel:[1,0]
	v_mov_b32_e32 v91, v89
	v_add_f32_e32 v88, v92, v90
	v_add_f32_e32 v89, v93, v91
	v_mul_f32_e32 v84, v20, v20
	v_add_f32_e32 v89, v88, v89
	v_add_f32_e32 v88, v88, v88
	v_fma_f32 v90, v20, v20, v84
	v_fma_f32 v91, v21, v21, v84
	v_mul_f32_e32 v84, v22, v22
	v_fma_f32 v92, v22, v22, v84
	v_fma_f32 v93, v23, v23, v84
	v_mul_f32_e32 v84, v18, v18
	v_mul_f32_e32 v88, v19, v19
	v_add_f32_e32 v84, v84, v88
	v_add_f32_e32 v85, v85, v89
	s_waitcnt lgkmcnt(0)
	v_add_f32_e32 v80, v80, v82
	v_add_f32_e32 v81, v81, v83
	v_mov_b64_e32 v[88:89], s[28:29]
	v_fma_f32 v94, v80, s26, v88
	v_fma_f32 v95, v81, s26, v88
	v_mul_f32_e32 v90, v16, v16
	v_mul_f32_e32 v80, 0x4b800000, v95
	v_cmp_gt_f32_e32 vcc, s17, v95
	v_mul_f32_e32 v92, v17, v17
	s_nop 0
	v_cndmask_b32_e32 v80, v95, v80, vcc
	v_rsq_f32_e32 v82, v80
	v_add_f32_e32 v80, v90, v92
	v_add_f32_e32 v81, v91, v93
	v_lshl_add_u64 v[92:93], s[18:19], 0, v[148:149]
	v_add_f32_e32 v90, v84, v80
	v_add_f32_e32 v91, v85, v81
	v_mul_f32_e32 v80, 0x45800000, v82
	v_cndmask_b32_e32 v98, v82, v80, vcc
	v_mul_f32_e32 v80, v98, v66
	v_mul_f32_e32 v81, v98, v67
	v_mul_f32_e32 v76, v98, v76
	v_mul_f32_e32 v77, v98, v77
	v_mul_f32_e32 v66, v98, v78
	v_mul_f32_e32 v67, v98, v79
	v_mul_f32_e32 v78, v0, v80
	v_mul_f32_e32 v79, v1, v81
	v_mul_f32_e32 v80, v10, v76
	v_mul_f32_e32 v81, v11, v77
	v_add_co_u32_e32 v76, vcc, s23, v92
	v_mul_f32_e32 v70, v98, v70
	v_mul_f32_e32 v71, v98, v71
	s_nop 0
	v_addc_co_u32_e32 v77, vcc, 0, v93, vcc
	v_add_co_u32_e32 v92, vcc, s27, v92
	v_mul_f32_e32 v72, v98, v72
	v_mul_f32_e32 v73, v98, v73
	s_nop 0
	v_addc_co_u32_e32 v93, vcc, 0, v93, vcc
	v_mul_f32_e32 v74, v98, v74
	v_mul_f32_e32 v75, v98, v75
	v_mul_f32_e32 v68, v98, v68
	v_mul_f32_e32 v69, v98, v69
	v_mul_f32_e32 v124, v4, v70
	v_mul_f32_e32 v125, v5, v71
	v_mul_f32_e32 v70, 0x4b800000, v94
	v_cmp_gt_f32_e32 vcc, s17, v94
	v_mul_f32_e32 v112, v14, v74
	v_mul_f32_e32 v113, v15, v75
	v_mul_f32_e32 v96, v12, v72
	v_mul_f32_e32 v97, v13, v73
	v_mul_f32_e32 v166, v6, v68
	v_mul_f32_e32 v167, v7, v69
	v_cndmask_b32_e32 v70, v94, v70, vcc
	v_cvt_pk_bf16_f32 v68, v96, v97
	v_cvt_pk_bf16_f32 v69, v112, v113
	v_rsq_f32_e32 v72, v70
	v_cvt_pk_bf16_f32 v70, v124, v125
	v_cvt_pk_bf16_f32 v71, v166, v167
	global_store_dwordx4 v[76:77], v[68:71], off offset:1024
	v_mul_f32_e32 v73, 0x45800000, v72
	v_cndmask_b32_e32 v72, v72, v73, vcc
	v_mov_b32_e32 v68, v90
	v_mov_b32_e32 v69, v86
	v_mov_b32_e32 v86, v91
	v_add_f32_e32 v68, v68, v86
	v_add_f32_e32 v69, v69, v87
	ds_bpermute_b32 v71, v209, v69
	ds_bpermute_b32 v70, v209, v68
	v_mul_f32_e32 v62, v72, v62
	v_mul_f32_e32 v63, v72, v63
	v_mul_f32_e32 v198, v2, v62
	v_mul_f32_e32 v199, v3, v63
	v_mul_f32_e32 v60, v72, v60
	v_mul_f32_e32 v61, v72, v61
	v_mul_f32_e32 v200, v0, v60
	v_mul_f32_e32 v201, v1, v61
	s_waitcnt lgkmcnt(0)
; #define LAS __attribute__((address_space(3)))
; #define GAS __attribute__((address_space(1)))
; template <int MODE, bool XBF>
; __device__ __forceinline__ void rmsnorm_rows(const void* x, const float* gain, bf16_t* H, int gw, int NGW, int lane, const LAS float* WF, const float* fbias, float* LF) {
;     ...
;         for (int r = 0; r < RB; ++r) {
;             const int row = row0 + r;
;             const float rstd = rsqrtf(s[r] * (1.f / D) + 1e-6f);
;             const size_t hrow = MODE == 2 ? (size_t)row + (row >> 12) + 1 : (size_t)row;
; #pragma unroll
;             for (int j = 0; j < 2; ++j) { v[r][j][0] = v[r][j][0] * rstd * g[j][0]; v[r][j][1] = v[r][j][1] * rstd * g[j][1];
;                 *(GAS u32x4*)(H + hrow * D + 512 * j + lane * 8) = pack8(v[r][j][0], v[r][j][1]); }
;         }
;         if (MODE == 1) {
;             float dt[RB][8];
; #pragma unroll
;             for (int r = 0; r < RB; ++r)
; #pragma unroll
;                 for (int h = 0; h < 8; ++h) dt[r][h] = 0.f;
; #pragma unroll
;             for (int j = 0; j < 2; ++j)
; #pragma unroll
;                 for (int e = 0; e < 2; ++e)
; #pragma unroll
;                     for (int c = 0; c < 4; ++c) {
;                         const LAS float* wp = WF + (512 * j + lane * 8 + 4 * e + c) * 8;
;                         const f32x4 w0 = *(const LAS f32x4*)wp, w1 = *(const LAS f32x4*)(wp + 4);
	v_add_f32_e32 v62, v68, v70
	v_add_f32_e32 v63, v69, v71
	ds_bpermute_b32 v69, v208, v63
	ds_bpermute_b32 v68, v208, v62
	v_mul_f32_e32 v56, v72, v56
	v_mul_f32_e32 v57, v72, v57
	v_mul_f32_e32 v58, v72, v58
	v_mul_f32_e32 v59, v72, v59
	v_mul_f32_e32 v194, v10, v58
	v_mul_f32_e32 v195, v11, v59
	v_mul_f32_e32 v196, v8, v56
	v_mul_f32_e32 v197, v9, v57
	s_waitcnt lgkmcnt(0)
	v_add_f32_e32 v60, v62, v68
	v_add_f32_e32 v61, v63, v69
	ds_bpermute_b32 v63, v207, v61
	ds_bpermute_b32 v62, v207, v60
	v_cvt_pk_bf16_f32 v56, v200, v201
	v_cvt_pk_bf16_f32 v57, v198, v199
	v_cvt_pk_bf16_f32 v58, v196, v197
	v_cvt_pk_bf16_f32 v59, v194, v195
	s_waitcnt lgkmcnt(0)
	v_add_f32_e32 v60, v60, v62
	v_add_f32_e32 v61, v61, v63
	ds_bpermute_b32 v63, v206, v61
	ds_bpermute_b32 v62, v206, v60
	global_store_dwordx4 v[76:77], v[56:59], off offset:2048
	v_mul_f32_e32 v52, v72, v52
	v_mul_f32_e32 v53, v72, v53
	v_mul_f32_e32 v54, v72, v54
	v_mul_f32_e32 v55, v72, v55
	v_mul_f32_e32 v192, v12, v52
	v_mul_f32_e32 v193, v13, v53
	s_waitcnt lgkmcnt(0)
	v_add_f32_e32 v56, v60, v62
	v_add_f32_e32 v57, v61, v63
	ds_bpermute_b32 v59, v205, v57
	ds_bpermute_b32 v58, v205, v56
	v_mul_f32_e32 v190, v14, v54
	v_mul_f32_e32 v191, v15, v55
	v_mul_f32_e32 v50, v72, v50
	v_mul_f32_e32 v51, v72, v51
	v_mul_f32_e32 v188, v4, v50
	v_mul_f32_e32 v189, v5, v51
	v_mul_f32_e32 v48, v72, v48
	v_mul_f32_e32 v49, v72, v49
	s_waitcnt lgkmcnt(0)
	v_add_f32_e32 v52, v56, v58
	v_add_f32_e32 v53, v57, v59
	ds_bpermute_b32 v55, v203, v53
	ds_bpermute_b32 v54, v203, v52
	v_mul_f32_e32 v186, v6, v48
	v_mul_f32_e32 v187, v7, v49
	v_cvt_pk_bf16_f32 v48, v192, v193
	v_cvt_pk_bf16_f32 v49, v190, v191
	v_mul_f32_e32 v64, v98, v64
	v_mul_f32_e32 v65, v98, v65
	s_waitcnt lgkmcnt(0)
	v_add_f32_e32 v50, v52, v54
	v_add_f32_e32 v51, v53, v55
	v_mul_f32_e32 v66, v2, v66
	v_mul_f32_e32 v67, v3, v67
	v_fma_f32 v52, v50, s26, v88
	v_fma_f32 v53, v51, s26, v88
	v_cvt_pk_bf16_f32 v51, v186, v187
	v_mul_f32_e32 v50, 0x4b800000, v53
	v_cmp_gt_f32_e32 vcc, s17, v53
	v_mul_f32_e32 v64, v8, v64
	v_mul_f32_e32 v65, v9, v65
	v_cvt_pk_bf16_f32 v82, v78, v79
	v_cndmask_b32_e32 v50, v53, v50, vcc
	v_rsq_f32_e32 v53, v50
	v_cvt_pk_bf16_f32 v50, v188, v189
	global_store_dwordx4 v[76:77], v[48:51], off offset:3072
	v_cvt_pk_bf16_f32 v83, v66, v67
	v_cvt_pk_bf16_f32 v84, v64, v65
	v_mul_f32_e32 v48, 0x45800000, v53
	v_cndmask_b32_e32 v48, v53, v48, vcc
	v_mul_f32_e32 v34, v48, v34
	v_mul_f32_e32 v35, v48, v35
	v_mul_f32_e32 v172, v4, v34
	v_mul_f32_e32 v173, v5, v35
	v_mul_f32_e32 v34, 0x4b800000, v52
	v_cmp_gt_f32_e32 vcc, s17, v52
	v_mul_f32_e32 v36, v48, v36
	v_mul_f32_e32 v37, v48, v37
	v_mul_f32_e32 v176, v12, v36
	v_mul_f32_e32 v177, v13, v37
	v_cndmask_b32_e32 v34, v52, v34, vcc
	v_rsq_f32_e32 v36, v34
	v_mul_f32_e32 v38, v48, v38
	v_mul_f32_e32 v39, v48, v39
	v_mul_f32_e32 v32, v48, v32
	v_mul_f32_e32 v33, v48, v33
	v_mul_f32_e32 v174, v14, v38
	v_mul_f32_e32 v175, v15, v39
	v_mul_f32_e32 v170, v6, v32
	v_mul_f32_e32 v171, v7, v33
	v_cvt_pk_bf16_f32 v32, v176, v177
	v_cvt_pk_bf16_f32 v33, v174, v175
	v_cvt_pk_bf16_f32 v34, v172, v173
	v_cvt_pk_bf16_f32 v35, v170, v171
	global_store_dwordx4 v[92:93], v[32:35], off offset:1024
	v_mul_f32_e32 v42, v48, v42
	v_mul_f32_e32 v43, v48, v43
	v_mul_f32_e32 v46, v48, v46
	v_mul_f32_e32 v47, v48, v47
	v_mul_f32_e32 v32, 0x45800000, v36
	v_cndmask_b32_e32 v32, v36, v32, vcc
	v_mul_f32_e32 v26, v32, v26
	v_mul_f32_e32 v27, v32, v27
	v_mul_f32_e32 v184, v0, v42
	v_mul_f32_e32 v185, v1, v43
	v_mul_f32_e32 v40, v48, v40
	v_mul_f32_e32 v41, v48, v41
	v_mul_f32_e32 v42, v48, v44
	v_mul_f32_e32 v43, v48, v45
	v_mul_f32_e32 v30, v32, v30
	v_mul_f32_e32 v31, v32, v31
	v_mul_f32_e32 v168, v0, v26
	v_mul_f32_e32 v169, v1, v27
	v_mul_f32_e32 v24, v32, v24
	v_mul_f32_e32 v25, v32, v25
	v_mul_f32_e32 v26, v32, v28
	v_mul_f32_e32 v27, v32, v29
	v_mul_f32_e32 v20, v32, v20
	v_mul_f32_e32 v21, v32, v21
	v_mul_f32_e32 v22, v32, v22
	v_mul_f32_e32 v23, v32, v23
	v_mul_f32_e32 v18, v32, v18
	v_mul_f32_e32 v19, v32, v19
	v_mul_f32_e32 v16, v32, v16
	v_mul_f32_e32 v17, v32, v17
	v_mul_f32_e32 v182, v2, v46
	v_mul_f32_e32 v183, v3, v47
	v_mul_f32_e32 v178, v10, v42
	v_mul_f32_e32 v179, v11, v43
	v_mul_f32_e32 v180, v8, v40
	v_mul_f32_e32 v181, v9, v41
	v_mul_f32_e32 v164, v2, v30
	v_mul_f32_e32 v165, v3, v31
	v_mul_f32_e32 v160, v10, v26
	v_mul_f32_e32 v161, v11, v27
	v_mul_f32_e32 v162, v8, v24
	v_mul_f32_e32 v163, v9, v25
	v_mul_f32_e32 v156, v14, v22
	v_mul_f32_e32 v157, v15, v23
	v_mul_f32_e32 v158, v12, v20
	v_mul_f32_e32 v159, v13, v21
	v_mul_f32_e32 v152, v6, v16
	v_mul_f32_e32 v153, v7, v17
	v_mul_f32_e32 v154, v4, v18
	v_mul_f32_e32 v155, v5, v19
	v_cvt_pk_bf16_f32 v85, v80, v81
	v_cvt_pk_bf16_f32 v40, v184, v185
	v_cvt_pk_bf16_f32 v41, v182, v183
	v_cvt_pk_bf16_f32 v42, v180, v181
	v_cvt_pk_bf16_f32 v43, v178, v179
	v_cvt_pk_bf16_f32 v24, v168, v169
	v_cvt_pk_bf16_f32 v25, v164, v165
	v_cvt_pk_bf16_f32 v26, v162, v163
	v_cvt_pk_bf16_f32 v27, v160, v161
	v_cvt_pk_bf16_f32 v16, v158, v159
	v_cvt_pk_bf16_f32 v17, v156, v157
	v_cvt_pk_bf16_f32 v18, v154, v155
	v_cvt_pk_bf16_f32 v19, v152, v153
	global_store_dwordx4 v[92:93], v[82:85], off offset:-4096
	global_store_dwordx4 v[92:93], v[40:43], off
	global_store_dwordx4 v[92:93], v[24:27], off offset:2048
	ds_read_b128 v[32:35], v210
	global_store_dwordx4 v[92:93], v[16:19], off offset:3072
	ds_read_b128 v[28:31], v210 offset:16
	ds_read_b128 v[20:23], v210 offset:32
	ds_read_b128 v[16:19], v210 offset:48
	ds_read_b128 v[36:39], v210 offset:64
	ds_read_b128 v[24:27], v210 offset:80
	ds_read_b128 v[44:47], v210 offset:96
	ds_read_b128 v[40:43], v210 offset:112
	ds_read_b128 v[52:55], v210 offset:128
	ds_read_b128 v[48:51], v210 offset:144
	s_waitcnt lgkmcnt(9)
; #define LAS __attribute__((address_space(3)))
; template <int MODE, bool XBF>
; __device__ __forceinline__ void rmsnorm_rows(const void* x, const float* gain, bf16_t* H, int gw, int NGW, int lane, const LAS float* WF, const float* fbias, float* LF) {
;     ...
;             for (int j = 0; j < 2; ++j)
; #pragma unroll
;                 for (int e = 0; e < 2; ++e)
; #pragma unroll
;                     for (int c = 0; c < 4; ++c) {
;                         const LAS float* wp = WF + (512 * j + lane * 8 + 4 * e + c) * 8;
;                         const f32x4 w0 = *(const LAS f32x4*)wp, w1 = *(const LAS f32x4*)(wp + 4);
; #pragma unroll
;                         for (int r = 0; r < RB; ++r) {
;                             const float hv = v[r][j][e][c];
;                             dt[r][0] += hv * w0[0]; dt[r][1] += hv * w0[1]; dt[r][2] += hv * w0[2]; dt[r][3] += hv * w0[3];
;                             dt[r][4] += hv * w1[0]; dt[r][5] += hv * w1[1]; dt[r][6] += hv * w1[2]; dt[r][7] += hv * w1[3];
;                         }
;                     }
;             const bool hi32 = (lane & 32) != 0, hi16 = (lane & 16) != 0, hi8 = (lane & 8) != 0;
;             const int hsel = (hi32 ? 4 : 0) + (hi16 ? 2 : 0) + (hi8 ? 1 : 0);
;             const float fb = fbias[hsel];
; #pragma unroll
;             for (int r = 0; r < RB; ++r) {
;                 float d4[4], d2[2], d1;
; #pragma unroll
;                 for (int k = 0; k < 4; ++k) { const float send = hi32 ? dt[r][k] : dt[r][k + 4], keep = hi32 ? dt[r][k + 4] : dt[r][k]; d4[k] = keep + __shfl_xor(send, 32); }
; #pragma unroll
;                 for (int k = 0; k < 2; ++k) { const float send = hi16 ? d4[k] : d4[k + 2], keep = hi16 ? d4[k + 2] : d4[k]; d2[k] = keep + __shfl_xor(send, 16); }
;                 { const float send = hi8 ? d2[0] : d2[1], keep = hi8 ? d2[1] : d2[0]; d1 = keep + __shfl_xor(send, 8); }
;                 d1 += __shfl_xor(d1, 4); d1 += __shfl_xor(d1, 2); d1 += __shfl_xor(d1, 1);
	v_fma_f32 v151, v32, v78, 0
	v_fma_f32 v204, v33, v78, 0
	v_fma_f32 v216, v34, v78, 0
	v_fma_f32 v217, v35, v78, 0
	s_waitcnt lgkmcnt(8)
	v_fma_f32 v218, v28, v78, 0
	v_fma_f32 v219, v29, v78, 0
	v_fma_f32 v220, v30, v78, 0
	v_fma_f32 v221, v31, v78, 0
	ds_read_b128 v[60:63], v210 offset:160
	ds_read_b128 v[56:59], v210 offset:176
	s_waitcnt lgkmcnt(9)
	v_fmac_f32_e32 v151, v79, v20
	v_fmac_f32_e32 v204, v79, v21
	v_fmac_f32_e32 v216, v79, v22
	v_fmac_f32_e32 v217, v79, v23
	s_waitcnt lgkmcnt(8)
	v_fmac_f32_e32 v218, v79, v16
	v_fmac_f32_e32 v219, v79, v17
	v_fmac_f32_e32 v220, v79, v18
	v_fmac_f32_e32 v221, v79, v19
	flat_load_dword v215, v[144:145] offset:32
	s_waitcnt lgkmcnt(0)
	v_fmac_f32_e32 v151, v66, v36
	v_fmac_f32_e32 v204, v66, v37
	v_fmac_f32_e32 v216, v66, v38
	v_fmac_f32_e32 v217, v66, v39
	v_fmac_f32_e32 v218, v66, v24
	v_fmac_f32_e32 v219, v66, v25
	v_fmac_f32_e32 v220, v66, v26
	v_fmac_f32_e32 v221, v66, v27
	v_fmac_f32_e32 v151, v67, v44
	v_fmac_f32_e32 v204, v67, v45
	v_fmac_f32_e32 v216, v67, v46
	v_fmac_f32_e32 v217, v67, v47
	v_fmac_f32_e32 v218, v67, v40
	v_fmac_f32_e32 v219, v67, v41
	v_fmac_f32_e32 v220, v67, v42
	v_fmac_f32_e32 v221, v67, v43
	v_fmac_f32_e32 v151, v64, v52
	v_fmac_f32_e32 v204, v64, v53
	v_fmac_f32_e32 v216, v64, v54
	v_fmac_f32_e32 v217, v64, v55
	v_fmac_f32_e32 v218, v64, v48
	v_fmac_f32_e32 v219, v64, v49
	v_fmac_f32_e32 v220, v64, v50
	v_fmac_f32_e32 v221, v64, v51
	v_fmac_f32_e32 v151, v65, v60
	v_fmac_f32_e32 v204, v65, v61
	v_fmac_f32_e32 v216, v65, v62
	v_fmac_f32_e32 v217, v65, v63
	v_fmac_f32_e32 v218, v65, v56
	ds_read_b128 v[68:71], v210 offset:192
	v_fmac_f32_e32 v219, v65, v57
	v_fmac_f32_e32 v220, v65, v58
	v_fmac_f32_e32 v221, v65, v59
	ds_read_b128 v[64:67], v210 offset:208
	ds_read_b128 v[76:79], v210 offset:224
	ds_read_b128 v[72:75], v210 offset:240
	s_waitcnt lgkmcnt(0)
	v_fmac_f32_e32 v151, v80, v68
	v_fmac_f32_e32 v204, v80, v69
	v_fmac_f32_e32 v216, v80, v70
	v_fmac_f32_e32 v217, v80, v71
	v_fmac_f32_e32 v218, v80, v64
	v_fmac_f32_e32 v219, v80, v65
	v_fmac_f32_e32 v220, v80, v66
	v_fmac_f32_e32 v221, v80, v67
	v_fmac_f32_e32 v151, v81, v76
	v_fmac_f32_e32 v204, v81, v77
	v_fmac_f32_e32 v216, v81, v78
	v_fmac_f32_e32 v217, v81, v79
	v_fmac_f32_e32 v218, v81, v72
	ds_read_b128 v[84:87], v210 offset:17408
	v_fmac_f32_e32 v219, v81, v73
	v_fmac_f32_e32 v220, v81, v74
	v_fmac_f32_e32 v221, v81, v75
	ds_read_b128 v[80:83], v210 offset:17424
	ds_read_b128 v[92:95], v210 offset:17440
	ds_read_b128 v[88:91], v210 offset:17456
	s_waitcnt lgkmcnt(0)
	v_fmac_f32_e32 v151, v96, v84
	v_fmac_f32_e32 v204, v96, v85
	v_fmac_f32_e32 v216, v96, v86
	v_fmac_f32_e32 v217, v96, v87
	v_fmac_f32_e32 v218, v96, v80
	v_fmac_f32_e32 v219, v96, v81
	v_fmac_f32_e32 v220, v96, v82
	v_fmac_f32_e32 v221, v96, v83
	v_fmac_f32_e32 v151, v97, v92
	v_fmac_f32_e32 v204, v97, v93
	v_fmac_f32_e32 v216, v97, v94
	v_fmac_f32_e32 v217, v97, v95
	v_fmac_f32_e32 v218, v97, v88
	ds_read_b128 v[100:103], v210 offset:17472
	v_fmac_f32_e32 v219, v97, v89
	v_fmac_f32_e32 v220, v97, v90
	v_fmac_f32_e32 v221, v97, v91
	ds_read_b128 v[96:99], v210 offset:17488
	ds_read_b128 v[108:111], v210 offset:17504
	ds_read_b128 v[104:107], v210 offset:17520
	s_waitcnt lgkmcnt(0)
	v_fmac_f32_e32 v151, v112, v100
	v_fmac_f32_e32 v204, v112, v101
	v_fmac_f32_e32 v216, v112, v102
	v_fmac_f32_e32 v217, v112, v103
	v_fmac_f32_e32 v218, v112, v96
	v_fmac_f32_e32 v219, v112, v97
	v_fmac_f32_e32 v220, v112, v98
	v_fmac_f32_e32 v221, v112, v99
	v_fmac_f32_e32 v151, v113, v108
	v_fmac_f32_e32 v204, v113, v109
	v_fmac_f32_e32 v216, v113, v110
	v_fmac_f32_e32 v217, v113, v111
	v_fmac_f32_e32 v218, v113, v104
	ds_read_b128 v[116:119], v210 offset:17536
	v_fmac_f32_e32 v219, v113, v105
	v_fmac_f32_e32 v220, v113, v106
	v_fmac_f32_e32 v221, v113, v107
	ds_read_b128 v[112:115], v210 offset:17552
	ds_read_b128 v[120:123], v210 offset:17568
	ds_read_b128 v[140:143], v210 offset:17584
	s_waitcnt lgkmcnt(0)
	v_fmac_f32_e32 v151, v124, v116
	v_fmac_f32_e32 v204, v124, v117
	v_fmac_f32_e32 v216, v124, v118
	v_fmac_f32_e32 v217, v124, v119
	v_fmac_f32_e32 v218, v124, v112
	v_fmac_f32_e32 v219, v124, v113
	v_fmac_f32_e32 v220, v124, v114
	v_fmac_f32_e32 v221, v124, v115
	ds_read_b128 v[136:139], v210 offset:17600
	ds_read_b128 v[132:135], v210 offset:17616
	v_fmac_f32_e32 v151, v125, v120
	v_fmac_f32_e32 v204, v125, v121
	v_fmac_f32_e32 v216, v125, v122
	v_fmac_f32_e32 v217, v125, v123
	v_fmac_f32_e32 v218, v125, v140
	v_fmac_f32_e32 v219, v125, v141
	v_fmac_f32_e32 v220, v125, v142
	v_fmac_f32_e32 v221, v125, v143
	ds_read_b128 v[128:131], v210 offset:17632
	ds_read_b128 v[124:127], v210 offset:17648
	s_waitcnt lgkmcnt(0)
	v_fmac_f32_e32 v151, v166, v136
	v_fmac_f32_e32 v218, v166, v132
	v_fmac_f32_e32 v204, v166, v137
	v_fmac_f32_e32 v151, v167, v128
	v_fmac_f32_e32 v218, v167, v124
	v_fmac_f32_e32 v216, v166, v138
	v_fmac_f32_e32 v217, v166, v139
	v_fmac_f32_e32 v219, v166, v133
	v_fmac_f32_e32 v220, v166, v134
	v_fmac_f32_e32 v221, v166, v135
	v_cndmask_b32_e64 v166, v151, v218, s[2:3]
	ds_bpermute_b32 v166, v203, v166
	v_fmac_f32_e32 v204, v167, v129
	v_fmac_f32_e32 v219, v167, v125
	v_cndmask_b32_e64 v151, v218, v151, s[2:3]
	v_fmac_f32_e32 v216, v167, v130
	v_fmac_f32_e32 v220, v167, v126
	s_waitcnt lgkmcnt(0)
	v_add_f32_e32 v151, v151, v166
	v_cndmask_b32_e64 v166, v204, v219, s[2:3]
	v_fmac_f32_e32 v217, v167, v131
	v_fmac_f32_e32 v221, v167, v127
	v_cndmask_b32_e64 v167, v219, v204, s[2:3]
	ds_bpermute_b32 v166, v203, v166
	v_cndmask_b32_e64 v204, v216, v220, s[2:3]
	ds_bpermute_b32 v204, v203, v204
	v_cndmask_b32_e64 v218, v217, v221, s[2:3]
	ds_bpermute_b32 v218, v203, v218
	s_waitcnt lgkmcnt(0)
	v_add_f32_e32 v166, v167, v166
	v_cndmask_b32_e64 v167, v220, v216, s[2:3]
	v_add_f32_e32 v167, v167, v204
	v_cndmask_b32_e64 v204, v221, v217, s[2:3]
	v_add_f32_e32 v204, v204, v218
	v_cndmask_b32_e64 v216, v151, v167, s[4:5]
	v_cndmask_b32_e64 v217, v166, v204, s[4:5]
	ds_bpermute_b32 v216, v205, v216
	ds_bpermute_b32 v217, v205, v217
	v_cndmask_b32_e64 v151, v167, v151, s[4:5]
	v_cndmask_b32_e64 v166, v204, v166, s[4:5]
	s_waitcnt lgkmcnt(0)
	v_add_f32_e32 v151, v151, v216
	v_add_f32_e32 v166, v166, v217
	v_cndmask_b32_e64 v167, v151, v166, s[6:7]
	ds_bpermute_b32 v167, v206, v167
	v_cndmask_b32_e64 v151, v166, v151, s[6:7]
	s_waitcnt lgkmcnt(0)
	v_add_f32_e32 v151, v151, v167
	ds_bpermute_b32 v166, v207, v151
	s_waitcnt lgkmcnt(0)
	v_add_f32_e32 v151, v151, v166
	ds_bpermute_b32 v166, v208, v151
	s_waitcnt lgkmcnt(0)
	v_add_f32_e32 v151, v151, v166
	ds_bpermute_b32 v216, v209, v151
	v_lshl_add_u64 v[166:167], v[146:147], 0, s[30:31]
	s_and_saveexec_b64 s[30:31], s[8:9]
	s_cbranch_execz .LBB0_1684
; template <int MODE, bool XBF>
; __device__ __forceinline__ void rmsnorm_rows(const void* x, const float* gain, bf16_t* H, int gw, int NGW, int lane, const LAS float* WF, const float* fbias, float* LF) {
;     ...
;                 if ((lane & 7) == 0) {
;                     const int row = row0 + r;
;                     const float z = d1 + fb;
;                     LF[((size_t)(row >> 12) * 8 + hsel) * S + (row & 4095)] = fminf(z, 0.f) - log1pf(__expf(-fabsf(z)));
;                 }
	s_waitcnt lgkmcnt(0)
	v_add_f32_e32 v151, v151, v216
	s_waitcnt vmcnt(0)
	v_add_f32_e32 v151, v215, v151
	v_mul_f32_e64 v204, |v151|, s29
	v_exp_f32_e32 v204, v204
	v_min_f32_e32 v230, 0, v151
	s_lshl_b32 s12, s40, 2
	v_add_f32_e32 v151, 1.0, v204
	v_add_f32_e32 v216, -1.0, v151
	v_sub_f32_e32 v217, v216, v151
	v_sub_f32_e32 v216, v204, v216
	v_add_f32_e32 v217, 1.0, v217
	v_frexp_mant_f32_e32 v218, v151
	v_add_f32_e32 v219, v216, v217
	v_cvt_f64_f32_e32 v[216:217], v151
	v_frexp_exp_i32_f64_e32 v216, v[216:217]
	v_cmp_gt_f32_e32 vcc, s34, v218
	s_nop 1
	v_subbrev_co_u32_e32 v224, vcc, 0, v216, vcc
	v_sub_u32_e32 v216, 0, v224
	v_ldexp_f32 v151, v151, v216
	v_add_f32_e32 v218, -1.0, v151
	v_add_f32_e32 v217, 1.0, v218
	v_ldexp_f32 v216, v219, v216
	v_sub_f32_e32 v217, v151, v217
	v_add_f32_e32 v219, v216, v217
	v_add_f32_e32 v217, 1.0, v151
	v_add_f32_e32 v220, -1.0, v217
	v_sub_f32_e32 v151, v151, v220
	v_add_f32_e32 v151, v216, v151
	v_add_f32_e32 v225, v217, v151
	v_rcp_f32_e32 v226, v225
	v_sub_f32_e32 v216, v225, v217
	v_add_f32_e32 v217, v218, v219
	v_sub_f32_e32 v151, v151, v216
	v_mul_f32_e32 v228, v217, v226
	v_sub_f32_e32 v216, v217, v218
	v_mul_f32_e32 v218, v225, v228
	v_fma_f32 v220, v228, v225, -v218
	v_fmac_f32_e32 v220, v228, v151
	v_sub_f32_e32 v227, v219, v216
	v_add_f32_e32 v216, v218, v220
	v_sub_f32_e32 v219, v217, v216
	v_add_f32_e64 v222, v216, -v218
	v_add_f32_e64 v223, v217, -v219
	v_mov_b32_e32 v221, v216
	v_add_f32_e64 v216, v222, -v220
	v_add_f32_e64 v217, v223, -v221
	v_cmp_neq_f32_e32 vcc, s38, v204
	v_add_f32_e32 v217, v227, v217
	v_add_f32_e32 v216, v216, v217
	v_add_f32_e32 v217, v219, v216
	v_mul_f32_e32 v227, v226, v217
	v_mul_f32_e32 v218, v225, v227
	v_fma_f32 v220, v227, v225, -v218
	v_fmac_f32_e32 v220, v227, v151
	v_sub_f32_e32 v151, v219, v217
	v_add_f32_e32 v151, v216, v151
	v_add_f32_e32 v216, v218, v220
	v_sub_f32_e32 v219, v217, v216
	v_add_f32_e64 v222, v216, -v218
	v_add_f32_e64 v223, v217, -v219
	v_mov_b32_e32 v221, v216
	v_add_f32_e64 v216, v222, -v220
	v_add_f32_e64 v217, v223, -v221
	s_nop 0
	v_add_f32_e32 v151, v151, v217
	v_add_f32_e32 v151, v216, v151
	v_add_f32_e32 v217, v228, v227
	v_add_f32_e32 v151, v219, v151
	v_sub_f32_e32 v216, v217, v228
	v_mul_f32_e32 v151, v226, v151
	v_sub_f32_e32 v216, v227, v216
	v_add_f32_e32 v218, v216, v151
	v_add_f32_e32 v220, v217, v218
	v_cvt_f32_i32_e32 v216, v224
	v_mul_f32_e32 v221, v220, v220
	v_sub_f32_e32 v217, v220, v217
	v_fmamk_f32 v151, v221, 0x3e9b6dac, v211
	v_sub_f32_e32 v217, v218, v217
	v_fmaak_f32 v151, v221, v151, 0x3f2aaada
	v_ldexp_f32 v222, v217, 1
	v_mul_f32_e32 v217, v220, v221
	v_ldexp_f32 v219, v220, 1
	v_mul_f32_e32 v220, v216, v150
	v_mul_f32_e32 v221, v217, v151
	s_nop 0
	v_fma_f32 v218, v216, s35, -v220
	v_fmac_f32_e32 v218, 0xb102e308, v216
	v_add_f32_e32 v216, v220, v218
	v_add_f32_e32 v217, v221, v219
	s_nop 0
	v_sub_f32_e32 v151, v217, v219
	v_sub_f32_e32 v151, v221, v151
	v_add_f32_e32 v223, v222, v151
	v_mov_b32_e32 v222, v220
	v_add_f32_e64 v220, v216, -v220
	v_add_f32_e64 v221, v217, -v221
	v_add_f32_e32 v224, v216, v222
	v_add_f32_e32 v225, v217, v223
	v_mov_b32_e32 v219, v216
	v_mov_b32_e32 v221, v225
	v_add_f32_e64 v226, v218, -v220
	v_add_f32_e64 v227, v219, -v221
	v_add_f32_e32 v218, v218, v220
	v_add_f32_e32 v219, v219, v221
	v_mov_b32_e32 v222, v223
	v_add_f32_e64 v220, v219, -v216
	v_add_f32_e64 v221, v218, -v217
	v_add_f32_e64 v228, v224, -v220
	v_add_f32_e64 v229, v225, -v220
	v_mov_b32_e32 v224, v225
	v_mov_b32_e32 v225, v219
	v_pk_mov_b32 v[220:221], v[216:217], v[220:221] op_sel:[1,0]
	v_mov_b32_e32 v223, v216
	v_add_f32_e64 v220, v224, -v220
	v_add_f32_e64 v221, v225, -v221
	v_mov_b32_e32 v228, v226
	v_add_f32_e64 v216, v222, -v220
	v_add_f32_e64 v217, v223, -v221
	v_mov_b32_e32 v227, v219
	v_add_f32_e32 v220, v228, v216
	v_add_f32_e32 v221, v229, v217
	s_nop 0
	v_add_f32_e32 v222, v220, v221
	v_add_f32_e32 v223, v221, v220
	s_nop 0
	v_pk_add_f32 v[218:219], v[218:219], v[222:223] op_sel:[1,0] op_sel_hi:[0,1]
	v_mov_b32_e32 v221, v218
	v_add_f32_e64 v224, v220, -v226
	v_add_f32_e64 v225, v221, -v227
	v_mov_b32_e32 v217, v222
	v_sub_f32_e32 v151, v220, v224
	v_add_f32_e64 v216, v216, -v224
	v_add_f32_e64 v217, v217, -v225
	v_sub_f32_e32 v151, v226, v151
	v_add_f32_e32 v151, v216, v151
	v_add_f32_e32 v151, v151, v217
	v_add_f32_e32 v151, v218, v151
	v_cndmask_b32_e32 v151, v212, v151, vcc
	v_cmp_ngt_f32_e32 vcc, -1.0, v204
	v_lshl_add_u64 v[216:217], v[166:167], 0, s[12:13]
	s_nop 0
	v_cndmask_b32_e32 v151, v213, v151, vcc
	v_cmp_neq_f32_e32 vcc, -1.0, v204
	s_nop 1
	v_cndmask_b32_e32 v151, v214, v151, vcc
	v_cmp_lt_f32_e64 vcc, |v204|, s39
	s_nop 1
	v_cndmask_b32_e32 v151, v151, v204, vcc
	v_sub_f32_e32 v151, v230, v151
	flat_store_dword v[216:217], v151
; #define LAS __attribute__((address_space(3)))
; template <int MODE, bool XBF>
; __device__ __forceinline__ void rmsnorm_rows(const void* x, const float* gain, bf16_t* H, int gw, int NGW, int lane, const LAS float* WF, const float* fbias, float* LF) {
;     ...
;             for (int j = 0; j < 2; ++j)
; #pragma unroll
;                 for (int e = 0; e < 2; ++e)
; #pragma unroll
;                     for (int c = 0; c < 4; ++c) {
;                         const LAS float* wp = WF + (512 * j + lane * 8 + 4 * e + c) * 8;
;                         const f32x4 w0 = *(const LAS f32x4*)wp, w1 = *(const LAS f32x4*)(wp + 4);
; #pragma unroll
;                         for (int r = 0; r < RB; ++r) {
;                             const float hv = v[r][j][e][c];
;                             dt[r][0] += hv * w0[0]; dt[r][1] += hv * w0[1]; dt[r][2] += hv * w0[2]; dt[r][3] += hv * w0[3];
;                             dt[r][4] += hv * w1[0]; dt[r][5] += hv * w1[1]; dt[r][6] += hv * w1[2]; dt[r][7] += hv * w1[3];
;                         }
;                     }
;             const bool hi32 = (lane & 32) != 0, hi16 = (lane & 16) != 0, hi8 = (lane & 8) != 0;
;             const int hsel = (hi32 ? 4 : 0) + (hi16 ? 2 : 0) + (hi8 ? 1 : 0);
;             const float fb = fbias[hsel];
; #pragma unroll
;             for (int r = 0; r < RB; ++r) {
;                 float d4[4], d2[2], d1;
; #pragma unroll
;                 for (int k = 0; k < 4; ++k) { const float send = hi32 ? dt[r][k] : dt[r][k + 4], keep = hi32 ? dt[r][k + 4] : dt[r][k]; d4[k] = keep + __shfl_xor(send, 32); }
; #pragma unroll
;                 for (int k = 0; k < 2; ++k) { const float send = hi16 ? d4[k] : d4[k + 2], keep = hi16 ? d4[k + 2] : d4[k]; d2[k] = keep + __shfl_xor(send, 16); }
;                 { const float send = hi8 ? d2[0] : d2[1], keep = hi8 ? d2[1] : d2[0]; d1 = keep + __shfl_xor(send, 8); }
;                 d1 += __shfl_xor(d1, 4); d1 += __shfl_xor(d1, 2); d1 += __shfl_xor(d1, 1);
.LBB0_1684:
	s_or_b64 exec, exec, s[30:31]
	v_fma_f32 v151, v32, v200, 0
	v_fma_f32 v218, v28, v200, 0
	v_fmac_f32_e32 v151, v20, v201
	v_fmac_f32_e32 v218, v201, v16
	v_fma_f32 v204, v33, v200, 0
	s_waitcnt lgkmcnt(0)
	v_fma_f32 v216, v34, v200, 0
	v_fma_f32 v217, v35, v200, 0
	v_fma_f32 v219, v29, v200, 0
	v_fma_f32 v220, v30, v200, 0
	v_fma_f32 v200, v31, v200, 0
	v_fmac_f32_e32 v151, v198, v36
	v_fmac_f32_e32 v218, v198, v24
	v_fmac_f32_e32 v204, v21, v201
	v_fmac_f32_e32 v216, v22, v201
	v_fmac_f32_e32 v217, v23, v201
	v_fmac_f32_e32 v219, v201, v17
	v_fmac_f32_e32 v220, v201, v18
	v_fmac_f32_e32 v200, v201, v19
	v_fmac_f32_e32 v151, v199, v44
	v_fmac_f32_e32 v218, v199, v40
	v_fmac_f32_e32 v204, v198, v37
	v_fmac_f32_e32 v216, v198, v38
	v_fmac_f32_e32 v217, v198, v39
	v_fmac_f32_e32 v219, v198, v25
	v_fmac_f32_e32 v220, v198, v26
	v_fmac_f32_e32 v200, v198, v27
	v_fmac_f32_e32 v151, v196, v52
	v_fmac_f32_e32 v218, v196, v48
	v_fmac_f32_e32 v204, v199, v45
	v_fmac_f32_e32 v216, v199, v46
	v_fmac_f32_e32 v217, v199, v47
	v_fmac_f32_e32 v219, v199, v41
	v_fmac_f32_e32 v220, v199, v42
	v_fmac_f32_e32 v200, v199, v43
	v_fmac_f32_e32 v151, v197, v60
	v_fmac_f32_e32 v218, v197, v56
	v_fmac_f32_e32 v204, v196, v53
	v_fmac_f32_e32 v216, v196, v54
	v_fmac_f32_e32 v217, v196, v55
	v_fmac_f32_e32 v219, v196, v49
	v_fmac_f32_e32 v220, v196, v50
	v_fmac_f32_e32 v200, v196, v51
	v_fmac_f32_e32 v151, v194, v68
	v_fmac_f32_e32 v218, v194, v64
	v_fmac_f32_e32 v204, v197, v61
	v_fmac_f32_e32 v216, v197, v62
	v_fmac_f32_e32 v217, v197, v63
	v_fmac_f32_e32 v219, v197, v57
	v_fmac_f32_e32 v220, v197, v58
	v_fmac_f32_e32 v200, v197, v59
	v_fmac_f32_e32 v151, v195, v76
	v_fmac_f32_e32 v218, v195, v72
	v_fmac_f32_e32 v204, v194, v69
	v_fmac_f32_e32 v216, v194, v70
	v_fmac_f32_e32 v217, v194, v71
	v_fmac_f32_e32 v219, v194, v65
	v_fmac_f32_e32 v220, v194, v66
	v_fmac_f32_e32 v200, v194, v67
	v_fmac_f32_e32 v151, v192, v84
	v_fmac_f32_e32 v218, v192, v80
	v_fmac_f32_e32 v204, v195, v77
	v_fmac_f32_e32 v216, v195, v78
	v_fmac_f32_e32 v217, v195, v79
	v_fmac_f32_e32 v219, v195, v73
	v_fmac_f32_e32 v220, v195, v74
	v_fmac_f32_e32 v200, v195, v75
	v_fmac_f32_e32 v151, v193, v92
	v_fmac_f32_e32 v218, v193, v88
	v_fmac_f32_e32 v204, v192, v85
	v_fmac_f32_e32 v216, v192, v86
	v_fmac_f32_e32 v217, v192, v87
	v_fmac_f32_e32 v219, v192, v81
	v_fmac_f32_e32 v220, v192, v82
	v_fmac_f32_e32 v200, v192, v83
	v_fmac_f32_e32 v151, v190, v100
	v_fmac_f32_e32 v218, v190, v96
	v_fmac_f32_e32 v204, v193, v93
	v_fmac_f32_e32 v216, v193, v94
	v_fmac_f32_e32 v217, v193, v95
	v_fmac_f32_e32 v219, v193, v89
	v_fmac_f32_e32 v220, v193, v90
	v_fmac_f32_e32 v200, v193, v91
	v_fmac_f32_e32 v151, v191, v108
	v_fmac_f32_e32 v218, v191, v104
	v_fmac_f32_e32 v204, v190, v101
	v_fmac_f32_e32 v216, v190, v102
	v_fmac_f32_e32 v217, v190, v103
	v_fmac_f32_e32 v219, v190, v97
	v_fmac_f32_e32 v220, v190, v98
	v_fmac_f32_e32 v200, v190, v99
	v_fmac_f32_e32 v151, v188, v116
	v_fmac_f32_e32 v218, v188, v112
	v_fmac_f32_e32 v204, v191, v109
	v_fmac_f32_e32 v216, v191, v110
	v_fmac_f32_e32 v217, v191, v111
	v_fmac_f32_e32 v219, v191, v105
	v_fmac_f32_e32 v220, v191, v106
	v_fmac_f32_e32 v200, v191, v107
	v_fmac_f32_e32 v151, v189, v120
	v_fmac_f32_e32 v218, v189, v140
	v_fmac_f32_e32 v204, v188, v117
	v_fmac_f32_e32 v216, v188, v118
	v_fmac_f32_e32 v217, v188, v119
	v_fmac_f32_e32 v219, v188, v113
	v_fmac_f32_e32 v220, v188, v114
	v_fmac_f32_e32 v200, v188, v115
	v_fmac_f32_e32 v151, v186, v136
	v_fmac_f32_e32 v218, v186, v132
	v_fmac_f32_e32 v204, v189, v121
	v_fmac_f32_e32 v216, v189, v122
	v_fmac_f32_e32 v217, v189, v123
	v_fmac_f32_e32 v219, v189, v141
	v_fmac_f32_e32 v220, v189, v142
	v_fmac_f32_e32 v200, v189, v143
	v_fmac_f32_e32 v151, v187, v128
	v_fmac_f32_e32 v218, v187, v124
	v_fmac_f32_e32 v204, v186, v137
	v_fmac_f32_e32 v216, v186, v138
	v_fmac_f32_e32 v217, v186, v139
	v_fmac_f32_e32 v219, v186, v133
	v_fmac_f32_e32 v220, v186, v134
	v_fmac_f32_e32 v200, v186, v135
	v_cndmask_b32_e64 v186, v151, v218, s[2:3]
	ds_bpermute_b32 v186, v203, v186
	v_fmac_f32_e32 v204, v187, v129
	v_fmac_f32_e32 v219, v187, v125
	v_cndmask_b32_e64 v151, v218, v151, s[2:3]
	v_fmac_f32_e32 v216, v187, v130
	v_fmac_f32_e32 v220, v187, v126
	s_waitcnt lgkmcnt(0)
	v_add_f32_e32 v151, v151, v186
	v_cndmask_b32_e64 v186, v204, v219, s[2:3]
	v_fmac_f32_e32 v217, v187, v131
	v_fmac_f32_e32 v200, v187, v127
	ds_bpermute_b32 v186, v203, v186
	v_cndmask_b32_e64 v188, v216, v220, s[2:3]
	ds_bpermute_b32 v188, v203, v188
	v_cndmask_b32_e64 v189, v217, v200, s[2:3]
	ds_bpermute_b32 v189, v203, v189
	v_cndmask_b32_e64 v187, v219, v204, s[2:3]
	s_waitcnt lgkmcnt(0)
	v_add_f32_e32 v186, v187, v186
	v_cndmask_b32_e64 v187, v220, v216, s[2:3]
	v_add_f32_e32 v187, v187, v188
	v_cndmask_b32_e64 v188, v200, v217, s[2:3]
	v_add_f32_e32 v188, v188, v189
	v_cndmask_b32_e64 v189, v151, v187, s[4:5]
	v_cndmask_b32_e64 v190, v186, v188, s[4:5]
	ds_bpermute_b32 v189, v205, v189
	ds_bpermute_b32 v190, v205, v190
	v_cndmask_b32_e64 v151, v187, v151, s[4:5]
	v_cndmask_b32_e64 v186, v188, v186, s[4:5]
	s_waitcnt lgkmcnt(0)
	v_add_f32_e32 v151, v151, v189
	v_add_f32_e32 v186, v186, v190
	v_cndmask_b32_e64 v187, v151, v186, s[6:7]
	ds_bpermute_b32 v187, v206, v187
	v_cndmask_b32_e64 v151, v186, v151, s[6:7]
	s_waitcnt lgkmcnt(0)
	v_add_f32_e32 v151, v151, v187
	ds_bpermute_b32 v186, v207, v151
	s_waitcnt lgkmcnt(0)
	v_add_f32_e32 v151, v151, v186
	ds_bpermute_b32 v186, v208, v151
	s_waitcnt lgkmcnt(0)
	v_add_f32_e32 v151, v151, v186
	ds_bpermute_b32 v186, v209, v151
	s_and_saveexec_b64 s[30:31], s[8:9]
	s_cbranch_execz .LBB0_1686
; template <int MODE, bool XBF>
; __device__ __forceinline__ void rmsnorm_rows(const void* x, const float* gain, bf16_t* H, int gw, int NGW, int lane, const LAS float* WF, const float* fbias, float* LF) {
;     ...
;             for (int r = 0; r < RB; ++r) {
;                 float d4[4], d2[2], d1;
; #pragma unroll
;                 for (int k = 0; k < 4; ++k) { const float send = hi32 ? dt[r][k] : dt[r][k + 4], keep = hi32 ? dt[r][k + 4] : dt[r][k]; d4[k] = keep + __shfl_xor(send, 32); }
; #pragma unroll
;                 for (int k = 0; k < 2; ++k) { const float send = hi16 ? d4[k] : d4[k + 2], keep = hi16 ? d4[k + 2] : d4[k]; d2[k] = keep + __shfl_xor(send, 16); }
;                 { const float send = hi8 ? d2[0] : d2[1], keep = hi8 ? d2[1] : d2[0]; d1 = keep + __shfl_xor(send, 8); }
;                 d1 += __shfl_xor(d1, 4); d1 += __shfl_xor(d1, 2); d1 += __shfl_xor(d1, 1);
;                 if ((lane & 7) == 0) {
;                     const int row = row0 + r;
;                     const float z = d1 + fb;
;                     LF[((size_t)(row >> 12) * 8 + hsel) * S + (row & 4095)] = fminf(z, 0.f) - log1pf(__expf(-fabsf(z)));
	s_waitcnt lgkmcnt(0)
	v_add_f32_e32 v151, v151, v186
	s_waitcnt vmcnt(0)
	v_add_f32_e32 v151, v215, v151
	v_mul_f32_e64 v186, |v151|, s29
	v_exp_f32_e32 v200, v186
	v_min_f32_e32 v201, 0, v151
	s_lshl_b32 s12, s40, 2
	v_add_f32_e32 v151, 1.0, v200
	v_add_f32_e32 v186, -1.0, v151
	v_sub_f32_e32 v187, v186, v151
	v_sub_f32_e32 v186, v200, v186
	v_add_f32_e32 v187, 1.0, v187
	v_frexp_mant_f32_e32 v188, v151
	v_add_f32_e32 v189, v186, v187
	v_cvt_f64_f32_e32 v[186:187], v151
	v_frexp_exp_i32_f64_e32 v186, v[186:187]
	v_cmp_gt_f32_e32 vcc, s34, v188
	s_nop 1
	v_subbrev_co_u32_e32 v194, vcc, 0, v186, vcc
	v_sub_u32_e32 v186, 0, v194
	v_ldexp_f32 v151, v151, v186
	v_add_f32_e32 v188, -1.0, v151
	v_add_f32_e32 v187, 1.0, v188
	v_ldexp_f32 v186, v189, v186
	v_sub_f32_e32 v187, v151, v187
	v_add_f32_e32 v189, v186, v187
	v_add_f32_e32 v187, 1.0, v151
	v_add_f32_e32 v190, -1.0, v187
	v_sub_f32_e32 v151, v151, v190
	v_add_f32_e32 v151, v186, v151
	v_add_f32_e32 v195, v187, v151
	v_rcp_f32_e32 v196, v195
	v_sub_f32_e32 v186, v195, v187
	v_add_f32_e32 v187, v188, v189
	v_sub_f32_e32 v151, v151, v186
	v_mul_f32_e32 v198, v187, v196
	v_sub_f32_e32 v186, v187, v188
	v_mul_f32_e32 v188, v195, v198
	v_fma_f32 v190, v198, v195, -v188
	v_fmac_f32_e32 v190, v198, v151
	v_sub_f32_e32 v197, v189, v186
	v_add_f32_e32 v186, v188, v190
	v_sub_f32_e32 v189, v187, v186
	v_add_f32_e64 v192, v186, -v188
	v_add_f32_e64 v193, v187, -v189
	v_mov_b32_e32 v191, v186
	v_add_f32_e64 v186, v192, -v190
	v_add_f32_e64 v187, v193, -v191
	v_cmp_neq_f32_e32 vcc, s38, v200
	v_add_f32_e32 v187, v197, v187
	v_add_f32_e32 v186, v186, v187
	v_add_f32_e32 v187, v189, v186
	v_mul_f32_e32 v197, v196, v187
	v_mul_f32_e32 v188, v195, v197
	v_fma_f32 v190, v197, v195, -v188
	v_fmac_f32_e32 v190, v197, v151
	v_sub_f32_e32 v151, v189, v187
	v_add_f32_e32 v151, v186, v151
	v_add_f32_e32 v186, v188, v190
	v_sub_f32_e32 v189, v187, v186
	v_add_f32_e64 v192, v186, -v188
	v_add_f32_e64 v193, v187, -v189
	v_mov_b32_e32 v191, v186
	v_add_f32_e64 v186, v192, -v190
	v_add_f32_e64 v187, v193, -v191
	s_nop 0
	v_add_f32_e32 v151, v151, v187
	v_add_f32_e32 v151, v186, v151
	v_add_f32_e32 v187, v198, v197
	v_add_f32_e32 v151, v189, v151
	v_sub_f32_e32 v186, v187, v198
	v_mul_f32_e32 v151, v196, v151
	v_sub_f32_e32 v186, v197, v186
	v_add_f32_e32 v188, v186, v151
	v_add_f32_e32 v190, v187, v188
	v_cvt_f32_i32_e32 v186, v194
	v_mul_f32_e32 v191, v190, v190
	v_sub_f32_e32 v187, v190, v187
	v_fmamk_f32 v151, v191, 0x3e9b6dac, v211
	v_sub_f32_e32 v187, v188, v187
	v_fmaak_f32 v151, v191, v151, 0x3f2aaada
	v_ldexp_f32 v192, v187, 1
	v_mul_f32_e32 v187, v190, v191
	v_ldexp_f32 v189, v190, 1
	v_mul_f32_e32 v190, v186, v150
	v_mul_f32_e32 v191, v187, v151
	s_nop 0
	v_fma_f32 v188, v186, s35, -v190
	v_fmac_f32_e32 v188, 0xb102e308, v186
	v_add_f32_e32 v186, v190, v188
	v_add_f32_e32 v187, v191, v189
	s_nop 0
	v_sub_f32_e32 v151, v187, v189
	v_sub_f32_e32 v151, v191, v151
	v_add_f32_e32 v193, v192, v151
	v_mov_b32_e32 v192, v190
	v_add_f32_e64 v190, v186, -v190
	v_add_f32_e64 v191, v187, -v191
	v_add_f32_e32 v194, v186, v192
	v_add_f32_e32 v195, v187, v193
	v_mov_b32_e32 v189, v186
	v_mov_b32_e32 v191, v195
	v_add_f32_e64 v196, v188, -v190
	v_add_f32_e64 v197, v189, -v191
	v_add_f32_e32 v188, v188, v190
	v_add_f32_e32 v189, v189, v191
	v_mov_b32_e32 v192, v193
	v_add_f32_e64 v190, v189, -v186
	v_add_f32_e64 v191, v188, -v187
	v_add_f32_e64 v198, v194, -v190
	v_add_f32_e64 v199, v195, -v190
	v_mov_b32_e32 v194, v195
	v_mov_b32_e32 v195, v189
	v_pk_mov_b32 v[190:191], v[186:187], v[190:191] op_sel:[1,0]
	v_mov_b32_e32 v193, v186
	v_add_f32_e64 v190, v194, -v190
	v_add_f32_e64 v191, v195, -v191
	v_mov_b32_e32 v198, v196
	v_add_f32_e64 v186, v192, -v190
	v_add_f32_e64 v187, v193, -v191
	v_mov_b32_e32 v197, v189
	v_add_f32_e32 v190, v198, v186
	v_add_f32_e32 v191, v199, v187
	s_nop 0
	v_add_f32_e32 v192, v190, v191
	v_add_f32_e32 v193, v191, v190
	s_nop 0
	v_pk_add_f32 v[188:189], v[188:189], v[192:193] op_sel:[1,0] op_sel_hi:[0,1]
	v_mov_b32_e32 v191, v188
	v_add_f32_e64 v194, v190, -v196
	v_add_f32_e64 v195, v191, -v197
	v_mov_b32_e32 v187, v192
	v_sub_f32_e32 v151, v190, v194
	v_add_f32_e64 v186, v186, -v194
	v_add_f32_e64 v187, v187, -v195
	v_sub_f32_e32 v151, v196, v151
	v_add_f32_e32 v151, v186, v151
	v_add_f32_e32 v151, v151, v187
	v_add_f32_e32 v151, v188, v151
	v_cndmask_b32_e32 v151, v212, v151, vcc
	v_cmp_ngt_f32_e32 vcc, -1.0, v200
	v_lshl_add_u64 v[186:187], v[166:167], 0, s[12:13]
	s_nop 0
	v_cndmask_b32_e32 v151, v213, v151, vcc
	v_cmp_neq_f32_e32 vcc, -1.0, v200
	s_nop 1
	v_cndmask_b32_e32 v151, v214, v151, vcc
	v_cmp_lt_f32_e64 vcc, |v200|, s39
	s_nop 1
	v_cndmask_b32_e32 v151, v151, v200, vcc
	v_sub_f32_e32 v151, v201, v151
	flat_store_dword v[186:187], v151 offset:4
; #define LAS __attribute__((address_space(3)))
; template <int MODE, bool XBF>
; __device__ __forceinline__ void rmsnorm_rows(const void* x, const float* gain, bf16_t* H, int gw, int NGW, int lane, const LAS float* WF, const float* fbias, float* LF) {
;     ...
;             for (int j = 0; j < 2; ++j)
; #pragma unroll
;                 for (int e = 0; e < 2; ++e)
; #pragma unroll
;                     for (int c = 0; c < 4; ++c) {
;                         const LAS float* wp = WF + (512 * j + lane * 8 + 4 * e + c) * 8;
;                         const f32x4 w0 = *(const LAS f32x4*)wp, w1 = *(const LAS f32x4*)(wp + 4);
; #pragma unroll
;                         for (int r = 0; r < RB; ++r) {
;                             const float hv = v[r][j][e][c];
;                             dt[r][0] += hv * w0[0]; dt[r][1] += hv * w0[1]; dt[r][2] += hv * w0[2]; dt[r][3] += hv * w0[3];
;                             dt[r][4] += hv * w1[0]; dt[r][5] += hv * w1[1]; dt[r][6] += hv * w1[2]; dt[r][7] += hv * w1[3];
;                         }
;                     }
;             const bool hi32 = (lane & 32) != 0, hi16 = (lane & 16) != 0, hi8 = (lane & 8) != 0;
;             const int hsel = (hi32 ? 4 : 0) + (hi16 ? 2 : 0) + (hi8 ? 1 : 0);
;             const float fb = fbias[hsel];
; #pragma unroll
;             for (int r = 0; r < RB; ++r) {
;                 float d4[4], d2[2], d1;
; #pragma unroll
;                 for (int k = 0; k < 4; ++k) { const float send = hi32 ? dt[r][k] : dt[r][k + 4], keep = hi32 ? dt[r][k + 4] : dt[r][k]; d4[k] = keep + __shfl_xor(send, 32); }
; #pragma unroll
;                 for (int k = 0; k < 2; ++k) { const float send = hi16 ? d4[k] : d4[k + 2], keep = hi16 ? d4[k + 2] : d4[k]; d2[k] = keep + __shfl_xor(send, 16); }
;                 { const float send = hi8 ? d2[0] : d2[1], keep = hi8 ? d2[1] : d2[0]; d1 = keep + __shfl_xor(send, 8); }
;                 d1 += __shfl_xor(d1, 4); d1 += __shfl_xor(d1, 2); d1 += __shfl_xor(d1, 1);
.LBB0_1686:
	s_or_b64 exec, exec, s[30:31]
	v_fma_f32 v151, v32, v184, 0
	v_fma_f32 v189, v28, v184, 0
	v_fmac_f32_e32 v151, v20, v185
	v_fmac_f32_e32 v189, v16, v185
	s_waitcnt lgkmcnt(0)
	v_fma_f32 v186, v33, v184, 0
	v_fma_f32 v187, v34, v184, 0
	v_fma_f32 v188, v35, v184, 0
	v_fma_f32 v190, v29, v184, 0
	v_fma_f32 v191, v30, v184, 0
	v_fma_f32 v184, v31, v184, 0
	v_fmac_f32_e32 v151, v182, v36
	v_fmac_f32_e32 v189, v182, v24
	v_fmac_f32_e32 v186, v21, v185
	v_fmac_f32_e32 v187, v22, v185
	v_fmac_f32_e32 v188, v23, v185
	v_fmac_f32_e32 v190, v17, v185
	v_fmac_f32_e32 v191, v18, v185
	v_fmac_f32_e32 v184, v19, v185
	v_fmac_f32_e32 v151, v183, v44
	v_fmac_f32_e32 v189, v183, v40
	v_fmac_f32_e32 v186, v182, v37
	v_fmac_f32_e32 v187, v182, v38
	v_fmac_f32_e32 v188, v182, v39
	v_fmac_f32_e32 v190, v182, v25
	v_fmac_f32_e32 v191, v182, v26
	v_fmac_f32_e32 v184, v182, v27
	v_fmac_f32_e32 v151, v180, v52
	v_fmac_f32_e32 v189, v180, v48
	v_fmac_f32_e32 v186, v183, v45
	v_fmac_f32_e32 v187, v183, v46
	v_fmac_f32_e32 v188, v183, v47
	v_fmac_f32_e32 v190, v183, v41
	v_fmac_f32_e32 v191, v183, v42
	v_fmac_f32_e32 v184, v183, v43
	v_fmac_f32_e32 v151, v181, v60
	v_fmac_f32_e32 v189, v181, v56
	v_fmac_f32_e32 v186, v180, v53
	v_fmac_f32_e32 v187, v180, v54
	v_fmac_f32_e32 v188, v180, v55
	v_fmac_f32_e32 v190, v180, v49
	v_fmac_f32_e32 v191, v180, v50
	v_fmac_f32_e32 v184, v180, v51
	v_fmac_f32_e32 v151, v178, v68
	v_fmac_f32_e32 v189, v178, v64
	v_fmac_f32_e32 v186, v181, v61
	v_fmac_f32_e32 v187, v181, v62
	v_fmac_f32_e32 v188, v181, v63
	v_fmac_f32_e32 v190, v181, v57
	v_fmac_f32_e32 v191, v181, v58
	v_fmac_f32_e32 v184, v181, v59
	v_fmac_f32_e32 v151, v179, v76
	v_fmac_f32_e32 v189, v179, v72
	v_fmac_f32_e32 v186, v178, v69
	v_fmac_f32_e32 v187, v178, v70
	v_fmac_f32_e32 v188, v178, v71
	v_fmac_f32_e32 v190, v178, v65
	v_fmac_f32_e32 v191, v178, v66
	v_fmac_f32_e32 v184, v178, v67
	v_fmac_f32_e32 v151, v176, v84
	v_fmac_f32_e32 v189, v176, v80
	v_fmac_f32_e32 v186, v179, v77
	v_fmac_f32_e32 v187, v179, v78
	v_fmac_f32_e32 v188, v179, v79
	v_fmac_f32_e32 v190, v179, v73
	v_fmac_f32_e32 v191, v179, v74
	v_fmac_f32_e32 v184, v179, v75
	v_fmac_f32_e32 v151, v177, v92
	v_fmac_f32_e32 v189, v177, v88
	v_fmac_f32_e32 v186, v176, v85
	v_fmac_f32_e32 v187, v176, v86
	v_fmac_f32_e32 v188, v176, v87
	v_fmac_f32_e32 v190, v176, v81
	v_fmac_f32_e32 v191, v176, v82
	v_fmac_f32_e32 v184, v176, v83
	v_fmac_f32_e32 v151, v174, v100
	v_fmac_f32_e32 v189, v174, v96
	v_fmac_f32_e32 v186, v177, v93
	v_fmac_f32_e32 v187, v177, v94
	v_fmac_f32_e32 v188, v177, v95
	v_fmac_f32_e32 v190, v177, v89
	v_fmac_f32_e32 v191, v177, v90
	v_fmac_f32_e32 v184, v177, v91
	v_fmac_f32_e32 v151, v175, v108
	v_fmac_f32_e32 v189, v175, v104
	v_fmac_f32_e32 v186, v174, v101
	v_fmac_f32_e32 v187, v174, v102
	v_fmac_f32_e32 v188, v174, v103
	v_fmac_f32_e32 v190, v174, v97
	v_fmac_f32_e32 v191, v174, v98
	v_fmac_f32_e32 v184, v174, v99
	v_fmac_f32_e32 v151, v172, v116
	v_fmac_f32_e32 v189, v172, v112
	v_fmac_f32_e32 v186, v175, v109
	v_fmac_f32_e32 v187, v175, v110
	v_fmac_f32_e32 v188, v175, v111
	v_fmac_f32_e32 v190, v175, v105
	v_fmac_f32_e32 v191, v175, v106
	v_fmac_f32_e32 v184, v175, v107
	v_fmac_f32_e32 v151, v173, v120
	v_fmac_f32_e32 v189, v173, v140
	v_fmac_f32_e32 v186, v172, v117
	v_fmac_f32_e32 v187, v172, v118
	v_fmac_f32_e32 v188, v172, v119
	v_fmac_f32_e32 v190, v172, v113
	v_fmac_f32_e32 v191, v172, v114
	v_fmac_f32_e32 v184, v172, v115
	v_fmac_f32_e32 v151, v170, v136
	v_fmac_f32_e32 v189, v170, v132
	v_fmac_f32_e32 v186, v173, v121
	v_fmac_f32_e32 v187, v173, v122
	v_fmac_f32_e32 v188, v173, v123
	v_fmac_f32_e32 v190, v173, v141
	v_fmac_f32_e32 v191, v173, v142
	v_fmac_f32_e32 v184, v173, v143
	v_fmac_f32_e32 v151, v171, v128
	v_fmac_f32_e32 v189, v171, v124
	v_fmac_f32_e32 v186, v170, v137
	v_fmac_f32_e32 v187, v170, v138
	v_fmac_f32_e32 v188, v170, v139
	v_fmac_f32_e32 v190, v170, v133
	v_fmac_f32_e32 v191, v170, v134
	v_fmac_f32_e32 v184, v170, v135
	v_cndmask_b32_e64 v170, v151, v189, s[2:3]
	ds_bpermute_b32 v170, v203, v170
	v_fmac_f32_e32 v186, v171, v129
	v_fmac_f32_e32 v190, v171, v125
	v_cndmask_b32_e64 v151, v189, v151, s[2:3]
	v_fmac_f32_e32 v187, v171, v130
	v_fmac_f32_e32 v191, v171, v126
	s_waitcnt lgkmcnt(0)
	v_add_f32_e32 v151, v151, v170
	v_cndmask_b32_e64 v170, v186, v190, s[2:3]
	v_fmac_f32_e32 v188, v171, v131
	v_fmac_f32_e32 v184, v171, v127
	ds_bpermute_b32 v170, v203, v170
	v_cndmask_b32_e64 v172, v187, v191, s[2:3]
	ds_bpermute_b32 v172, v203, v172
	v_cndmask_b32_e64 v173, v188, v184, s[2:3]
	ds_bpermute_b32 v173, v203, v173
	v_cndmask_b32_e64 v171, v190, v186, s[2:3]
	s_waitcnt lgkmcnt(0)
	v_add_f32_e32 v170, v171, v170
	v_cndmask_b32_e64 v171, v191, v187, s[2:3]
	v_add_f32_e32 v171, v171, v172
	v_cndmask_b32_e64 v172, v184, v188, s[2:3]
	v_add_f32_e32 v172, v172, v173
	v_cndmask_b32_e64 v173, v151, v171, s[4:5]
	v_cndmask_b32_e64 v174, v170, v172, s[4:5]
	ds_bpermute_b32 v173, v205, v173
	ds_bpermute_b32 v174, v205, v174
	v_cndmask_b32_e64 v151, v171, v151, s[4:5]
	v_cndmask_b32_e64 v170, v172, v170, s[4:5]
	s_waitcnt lgkmcnt(0)
	v_add_f32_e32 v151, v151, v173
	v_add_f32_e32 v170, v170, v174
	v_cndmask_b32_e64 v171, v151, v170, s[6:7]
	ds_bpermute_b32 v171, v206, v171
	v_cndmask_b32_e64 v151, v170, v151, s[6:7]
	s_waitcnt lgkmcnt(0)
	v_add_f32_e32 v151, v151, v171
	ds_bpermute_b32 v170, v207, v151
	s_waitcnt lgkmcnt(0)
	v_add_f32_e32 v151, v151, v170
	ds_bpermute_b32 v170, v208, v151
	s_waitcnt lgkmcnt(0)
	v_add_f32_e32 v151, v151, v170
	ds_bpermute_b32 v170, v209, v151
	s_and_saveexec_b64 s[30:31], s[8:9]
	s_cbranch_execz .LBB0_1688
; template <int MODE, bool XBF>
; __device__ __forceinline__ void rmsnorm_rows(const void* x, const float* gain, bf16_t* H, int gw, int NGW, int lane, const LAS float* WF, const float* fbias, float* LF) {
;     ...
;                 if ((lane & 7) == 0) {
;                     const int row = row0 + r;
;                     const float z = d1 + fb;
;                     LF[((size_t)(row >> 12) * 8 + hsel) * S + (row & 4095)] = fminf(z, 0.f) - log1pf(__expf(-fabsf(z)));
	s_waitcnt lgkmcnt(0)
	v_add_f32_e32 v151, v151, v170
	s_waitcnt vmcnt(0)
	v_add_f32_e32 v151, v215, v151
	v_mul_f32_e64 v170, |v151|, s29
	v_exp_f32_e32 v184, v170
	v_min_f32_e32 v185, 0, v151
	s_lshl_b32 s12, s40, 2
	v_add_f32_e32 v151, 1.0, v184
	v_add_f32_e32 v170, -1.0, v151
	v_sub_f32_e32 v171, v170, v151
	v_sub_f32_e32 v170, v184, v170
	v_add_f32_e32 v171, 1.0, v171
	v_frexp_mant_f32_e32 v172, v151
	v_add_f32_e32 v173, v170, v171
	v_cvt_f64_f32_e32 v[170:171], v151
	v_frexp_exp_i32_f64_e32 v170, v[170:171]
	v_cmp_gt_f32_e32 vcc, s34, v172
	s_nop 1
	v_subbrev_co_u32_e32 v178, vcc, 0, v170, vcc
	v_sub_u32_e32 v170, 0, v178
	v_ldexp_f32 v151, v151, v170
	v_add_f32_e32 v172, -1.0, v151
	v_add_f32_e32 v171, 1.0, v172
	v_ldexp_f32 v170, v173, v170
	v_sub_f32_e32 v171, v151, v171
	v_add_f32_e32 v173, v170, v171
	v_add_f32_e32 v171, 1.0, v151
	v_add_f32_e32 v174, -1.0, v171
	v_sub_f32_e32 v151, v151, v174
	v_add_f32_e32 v151, v170, v151
	v_add_f32_e32 v179, v171, v151
	v_rcp_f32_e32 v180, v179
	v_sub_f32_e32 v170, v179, v171
	v_add_f32_e32 v171, v172, v173
	v_sub_f32_e32 v151, v151, v170
	v_mul_f32_e32 v182, v171, v180
	v_sub_f32_e32 v170, v171, v172
	v_mul_f32_e32 v172, v179, v182
	v_fma_f32 v174, v182, v179, -v172
	v_fmac_f32_e32 v174, v182, v151
	v_sub_f32_e32 v181, v173, v170
	v_add_f32_e32 v170, v172, v174
	v_sub_f32_e32 v173, v171, v170
	v_add_f32_e64 v176, v170, -v172
	v_add_f32_e64 v177, v171, -v173
	v_mov_b32_e32 v175, v170
	v_add_f32_e64 v170, v176, -v174
	v_add_f32_e64 v171, v177, -v175
	v_cmp_neq_f32_e32 vcc, s38, v184
	v_add_f32_e32 v171, v181, v171
	v_add_f32_e32 v170, v170, v171
	v_add_f32_e32 v171, v173, v170
	v_mul_f32_e32 v181, v180, v171
	v_mul_f32_e32 v172, v179, v181
	v_fma_f32 v174, v181, v179, -v172
	v_fmac_f32_e32 v174, v181, v151
	v_sub_f32_e32 v151, v173, v171
	v_add_f32_e32 v151, v170, v151
	v_add_f32_e32 v170, v172, v174
	v_sub_f32_e32 v173, v171, v170
	v_add_f32_e64 v176, v170, -v172
	v_add_f32_e64 v177, v171, -v173
	v_mov_b32_e32 v175, v170
	v_add_f32_e64 v170, v176, -v174
	v_add_f32_e64 v171, v177, -v175
	s_nop 0
	v_add_f32_e32 v151, v151, v171
	v_add_f32_e32 v151, v170, v151
	v_add_f32_e32 v171, v182, v181
	v_add_f32_e32 v151, v173, v151
	v_sub_f32_e32 v170, v171, v182
	v_mul_f32_e32 v151, v180, v151
	v_sub_f32_e32 v170, v181, v170
	v_add_f32_e32 v172, v170, v151
	v_add_f32_e32 v174, v171, v172
	v_cvt_f32_i32_e32 v170, v178
	v_mul_f32_e32 v175, v174, v174
	v_sub_f32_e32 v171, v174, v171
	v_fmamk_f32 v151, v175, 0x3e9b6dac, v211
	v_sub_f32_e32 v171, v172, v171
	v_fmaak_f32 v151, v175, v151, 0x3f2aaada
	v_ldexp_f32 v176, v171, 1
	v_mul_f32_e32 v171, v174, v175
	v_ldexp_f32 v173, v174, 1
	v_mul_f32_e32 v174, v170, v150
	v_mul_f32_e32 v175, v171, v151
	s_nop 0
	v_fma_f32 v172, v170, s35, -v174
	v_fmac_f32_e32 v172, 0xb102e308, v170
	v_add_f32_e32 v170, v174, v172
	v_add_f32_e32 v171, v175, v173
	s_nop 0
	v_sub_f32_e32 v151, v171, v173
	v_sub_f32_e32 v151, v175, v151
	v_add_f32_e32 v177, v176, v151
	v_mov_b32_e32 v176, v174
	v_add_f32_e64 v174, v170, -v174
	v_add_f32_e64 v175, v171, -v175
	v_add_f32_e32 v178, v170, v176
	v_add_f32_e32 v179, v171, v177
	v_mov_b32_e32 v173, v170
	v_mov_b32_e32 v175, v179
	v_add_f32_e64 v180, v172, -v174
	v_add_f32_e64 v181, v173, -v175
	v_add_f32_e32 v172, v172, v174
	v_add_f32_e32 v173, v173, v175
	v_mov_b32_e32 v176, v177
	v_add_f32_e64 v174, v173, -v170
	v_add_f32_e64 v175, v172, -v171
	v_add_f32_e64 v182, v178, -v174
	v_add_f32_e64 v183, v179, -v174
	v_mov_b32_e32 v178, v179
	v_mov_b32_e32 v179, v173
	v_pk_mov_b32 v[174:175], v[170:171], v[174:175] op_sel:[1,0]
	v_mov_b32_e32 v177, v170
	v_add_f32_e64 v174, v178, -v174
	v_add_f32_e64 v175, v179, -v175
	v_mov_b32_e32 v182, v180
	v_add_f32_e64 v170, v176, -v174
	v_add_f32_e64 v171, v177, -v175
	v_mov_b32_e32 v181, v173
	v_add_f32_e32 v174, v182, v170
	v_add_f32_e32 v175, v183, v171
	s_nop 0
	v_add_f32_e32 v176, v174, v175
	v_add_f32_e32 v177, v175, v174
	s_nop 0
	v_pk_add_f32 v[172:173], v[172:173], v[176:177] op_sel:[1,0] op_sel_hi:[0,1]
	v_mov_b32_e32 v175, v172
	v_add_f32_e64 v178, v174, -v180
	v_add_f32_e64 v179, v175, -v181
	v_mov_b32_e32 v171, v176
	v_sub_f32_e32 v151, v174, v178
	v_add_f32_e64 v170, v170, -v178
	v_add_f32_e64 v171, v171, -v179
	v_sub_f32_e32 v151, v180, v151
	v_add_f32_e32 v151, v170, v151
	v_add_f32_e32 v151, v151, v171
	v_add_f32_e32 v151, v172, v151
	v_cndmask_b32_e32 v151, v212, v151, vcc
	v_cmp_ngt_f32_e32 vcc, -1.0, v184
	v_lshl_add_u64 v[170:171], v[166:167], 0, s[12:13]
	s_nop 0
	v_cndmask_b32_e32 v151, v213, v151, vcc
	v_cmp_neq_f32_e32 vcc, -1.0, v184
	s_nop 1
	v_cndmask_b32_e32 v151, v214, v151, vcc
	v_cmp_lt_f32_e64 vcc, |v184|, s39
	s_nop 1
	v_cndmask_b32_e32 v151, v151, v184, vcc
	v_sub_f32_e32 v151, v185, v151
	flat_store_dword v[170:171], v151 offset:8
; #define LAS __attribute__((address_space(3)))
; template <int MODE, bool XBF>
; __device__ __forceinline__ void rmsnorm_rows(const void* x, const float* gain, bf16_t* H, int gw, int NGW, int lane, const LAS float* WF, const float* fbias, float* LF) {
;     ...
;             for (int j = 0; j < 2; ++j)
; #pragma unroll
;                 for (int e = 0; e < 2; ++e)
; #pragma unroll
;                     for (int c = 0; c < 4; ++c) {
;                         const LAS float* wp = WF + (512 * j + lane * 8 + 4 * e + c) * 8;
;                         const f32x4 w0 = *(const LAS f32x4*)wp, w1 = *(const LAS f32x4*)(wp + 4);
; #pragma unroll
;                         for (int r = 0; r < RB; ++r) {
;                             const float hv = v[r][j][e][c];
;                             dt[r][0] += hv * w0[0]; dt[r][1] += hv * w0[1]; dt[r][2] += hv * w0[2]; dt[r][3] += hv * w0[3];
;                             dt[r][4] += hv * w1[0]; dt[r][5] += hv * w1[1]; dt[r][6] += hv * w1[2]; dt[r][7] += hv * w1[3];
;                         }
;                     }
;             const bool hi32 = (lane & 32) != 0, hi16 = (lane & 16) != 0, hi8 = (lane & 8) != 0;
;             const int hsel = (hi32 ? 4 : 0) + (hi16 ? 2 : 0) + (hi8 ? 1 : 0);
;             const float fb = fbias[hsel];
; #pragma unroll
;             for (int r = 0; r < RB; ++r) {
;                 float d4[4], d2[2], d1;
; #pragma unroll
;                 for (int k = 0; k < 4; ++k) { const float send = hi32 ? dt[r][k] : dt[r][k + 4], keep = hi32 ? dt[r][k + 4] : dt[r][k]; d4[k] = keep + __shfl_xor(send, 32); }
; #pragma unroll
;                 for (int k = 0; k < 2; ++k) { const float send = hi16 ? d4[k] : d4[k + 2], keep = hi16 ? d4[k + 2] : d4[k]; d2[k] = keep + __shfl_xor(send, 16); }
;                 { const float send = hi8 ? d2[0] : d2[1], keep = hi8 ? d2[1] : d2[0]; d1 = keep + __shfl_xor(send, 8); }
;                 d1 += __shfl_xor(d1, 4); d1 += __shfl_xor(d1, 2); d1 += __shfl_xor(d1, 1);
.LBB0_1688:
	s_or_b64 exec, exec, s[30:31]
	v_fma_f32 v32, v32, v168, 0
	v_fma_f32 v28, v28, v168, 0
	v_fmac_f32_e32 v32, v20, v169
	v_fmac_f32_e32 v28, v16, v169
	v_fmac_f32_e32 v32, v36, v164
	v_fmac_f32_e32 v28, v164, v24
	v_fmac_f32_e32 v32, v165, v44
	v_fmac_f32_e32 v28, v165, v40
	v_fmac_f32_e32 v32, v162, v52
	v_fmac_f32_e32 v28, v162, v48
	v_fmac_f32_e32 v32, v163, v60
	v_fmac_f32_e32 v28, v163, v56
	v_fma_f32 v33, v33, v168, 0
	v_fma_f32 v29, v29, v168, 0
	v_fmac_f32_e32 v32, v160, v68
	v_fmac_f32_e32 v28, v160, v64
	v_fma_f32 v34, v34, v168, 0
	v_fma_f32 v30, v30, v168, 0
	v_fmac_f32_e32 v33, v21, v169
	v_fmac_f32_e32 v29, v17, v169
	v_fmac_f32_e32 v32, v161, v76
	v_fmac_f32_e32 v28, v161, v72
	v_fma_f32 v35, v35, v168, 0
	v_fma_f32 v31, v31, v168, 0
	v_fmac_f32_e32 v34, v22, v169
	v_fmac_f32_e32 v30, v18, v169
	v_fmac_f32_e32 v33, v37, v164
	v_fmac_f32_e32 v29, v164, v25
	v_fmac_f32_e32 v32, v158, v84
	v_fmac_f32_e32 v28, v158, v80
	v_fmac_f32_e32 v35, v23, v169
	v_fmac_f32_e32 v31, v19, v169
	v_fmac_f32_e32 v34, v38, v164
	v_fmac_f32_e32 v30, v164, v26
	v_fmac_f32_e32 v33, v165, v45
	v_fmac_f32_e32 v29, v165, v41
	v_fmac_f32_e32 v32, v159, v92
	v_fmac_f32_e32 v28, v159, v88
	v_fmac_f32_e32 v35, v39, v164
	v_fmac_f32_e32 v31, v164, v27
	v_fmac_f32_e32 v34, v165, v46
	v_fmac_f32_e32 v30, v165, v42
	v_fmac_f32_e32 v33, v162, v53
	v_fmac_f32_e32 v29, v162, v49
	v_fmac_f32_e32 v32, v156, v100
	v_fmac_f32_e32 v28, v156, v96
	v_fmac_f32_e32 v35, v165, v47
	v_fmac_f32_e32 v31, v165, v43
	v_fmac_f32_e32 v34, v162, v54
	v_fmac_f32_e32 v30, v162, v50
	v_fmac_f32_e32 v33, v163, v61
	v_fmac_f32_e32 v29, v163, v57
	v_fmac_f32_e32 v32, v157, v108
	v_fmac_f32_e32 v28, v157, v104
	v_fmac_f32_e32 v35, v162, v55
	v_fmac_f32_e32 v31, v162, v51
	v_fmac_f32_e32 v34, v163, v62
	v_fmac_f32_e32 v30, v163, v58
	v_fmac_f32_e32 v33, v160, v69
	v_fmac_f32_e32 v29, v160, v65
	v_fmac_f32_e32 v32, v154, v116
	v_fmac_f32_e32 v28, v154, v112
	v_fmac_f32_e32 v35, v163, v63
	v_fmac_f32_e32 v31, v163, v59
	v_fmac_f32_e32 v34, v160, v70
	v_fmac_f32_e32 v30, v160, v66
	v_fmac_f32_e32 v33, v161, v77
	v_fmac_f32_e32 v29, v161, v73
	v_fmac_f32_e32 v32, v155, v120
	v_fmac_f32_e32 v28, v155, v140
	v_fmac_f32_e32 v35, v160, v71
	v_fmac_f32_e32 v31, v160, v67
	v_fmac_f32_e32 v34, v161, v78
	v_fmac_f32_e32 v30, v161, v74
	v_fmac_f32_e32 v33, v158, v85
	v_fmac_f32_e32 v29, v158, v81
	v_fmac_f32_e32 v32, v152, v136
	v_fmac_f32_e32 v28, v152, v132
	v_fmac_f32_e32 v35, v161, v79
	v_fmac_f32_e32 v31, v161, v75
	v_fmac_f32_e32 v34, v158, v86
	v_fmac_f32_e32 v30, v158, v82
	v_fmac_f32_e32 v33, v159, v93
	v_fmac_f32_e32 v29, v159, v89
	v_fmac_f32_e32 v32, v153, v128
	v_fmac_f32_e32 v28, v153, v124
	v_fmac_f32_e32 v35, v158, v87
	v_fmac_f32_e32 v31, v158, v83
	v_fmac_f32_e32 v34, v159, v94
	v_fmac_f32_e32 v30, v159, v90
	v_fmac_f32_e32 v33, v156, v101
	v_fmac_f32_e32 v29, v156, v97
	v_cndmask_b32_e64 v16, v32, v28, s[2:3]
	v_fmac_f32_e32 v35, v159, v95
	v_fmac_f32_e32 v31, v159, v91
	v_fmac_f32_e32 v34, v156, v102
	v_fmac_f32_e32 v30, v156, v98
	v_fmac_f32_e32 v33, v157, v109
	v_fmac_f32_e32 v29, v157, v105
	ds_bpermute_b32 v16, v203, v16
	v_fmac_f32_e32 v35, v156, v103
	v_fmac_f32_e32 v31, v156, v99
	v_fmac_f32_e32 v34, v157, v110
	v_fmac_f32_e32 v30, v157, v106
	v_fmac_f32_e32 v33, v154, v117
	v_fmac_f32_e32 v29, v154, v113
	v_fmac_f32_e32 v35, v157, v111
	v_fmac_f32_e32 v31, v157, v107
	v_fmac_f32_e32 v34, v154, v118
	v_fmac_f32_e32 v30, v154, v114
	v_fmac_f32_e32 v33, v155, v121
	v_fmac_f32_e32 v29, v155, v141
	v_fmac_f32_e32 v35, v154, v119
	v_fmac_f32_e32 v31, v154, v115
	v_fmac_f32_e32 v34, v155, v122
	v_fmac_f32_e32 v30, v155, v142
	v_fmac_f32_e32 v33, v152, v137
	v_fmac_f32_e32 v29, v152, v133
	v_fmac_f32_e32 v35, v155, v123
	v_fmac_f32_e32 v31, v155, v143
	v_fmac_f32_e32 v34, v152, v138
	v_fmac_f32_e32 v30, v152, v134
	v_fmac_f32_e32 v33, v153, v129
	v_fmac_f32_e32 v29, v153, v125
	v_cndmask_b32_e64 v17, v28, v32, s[2:3]
	v_fmac_f32_e32 v35, v152, v139
	v_fmac_f32_e32 v31, v152, v135
	v_fmac_f32_e32 v34, v153, v130
	v_fmac_f32_e32 v30, v153, v126
	s_waitcnt lgkmcnt(0)
	v_add_f32_e32 v16, v17, v16
	v_cndmask_b32_e64 v17, v33, v29, s[2:3]
	v_fmac_f32_e32 v35, v153, v131
	v_fmac_f32_e32 v31, v153, v127
	ds_bpermute_b32 v17, v203, v17
	v_cndmask_b32_e64 v19, v34, v30, s[2:3]
	ds_bpermute_b32 v19, v203, v19
	v_cndmask_b32_e64 v20, v35, v31, s[2:3]
	ds_bpermute_b32 v20, v203, v20
	v_cndmask_b32_e64 v18, v29, v33, s[2:3]
	s_waitcnt lgkmcnt(0)
	v_add_f32_e32 v17, v18, v17
	v_cndmask_b32_e64 v18, v30, v34, s[2:3]
	v_add_f32_e32 v18, v18, v19
	v_cndmask_b32_e64 v19, v31, v35, s[2:3]
	v_add_f32_e32 v19, v19, v20
	v_cndmask_b32_e64 v20, v16, v18, s[4:5]
	v_cndmask_b32_e64 v21, v17, v19, s[4:5]
	ds_bpermute_b32 v20, v205, v20
	ds_bpermute_b32 v21, v205, v21
	v_cndmask_b32_e64 v16, v18, v16, s[4:5]
	v_cndmask_b32_e64 v17, v19, v17, s[4:5]
	s_waitcnt lgkmcnt(0)
	v_add_f32_e32 v16, v16, v20
	v_add_f32_e32 v17, v17, v21
	v_cndmask_b32_e64 v18, v16, v17, s[6:7]
	ds_bpermute_b32 v18, v206, v18
	v_cndmask_b32_e64 v16, v17, v16, s[6:7]
	s_waitcnt lgkmcnt(0)
	v_add_f32_e32 v16, v16, v18
	ds_bpermute_b32 v17, v207, v16
	s_waitcnt lgkmcnt(0)
	v_add_f32_e32 v16, v16, v17
	ds_bpermute_b32 v17, v208, v16
	s_waitcnt lgkmcnt(0)
	v_add_f32_e32 v16, v16, v17
	ds_bpermute_b32 v17, v209, v16
	s_and_saveexec_b64 s[30:31], s[8:9]
	s_cbranch_execz .LBB0_1681
; template <int MODE, bool XBF>
; __device__ __forceinline__ void rmsnorm_rows(const void* x, const float* gain, bf16_t* H, int gw, int NGW, int lane, const LAS float* WF, const float* fbias, float* LF) {
;     ...
;                 if ((lane & 7) == 0) {
;                     const int row = row0 + r;
;                     const float z = d1 + fb;
;                     LF[((size_t)(row >> 12) * 8 + hsel) * S + (row & 4095)] = fminf(z, 0.f) - log1pf(__expf(-fabsf(z)));
	s_waitcnt lgkmcnt(0)
	v_add_f32_e32 v16, v16, v17
	s_waitcnt vmcnt(0)
	v_add_f32_e32 v16, v215, v16
	v_mul_f32_e64 v17, |v16|, s29
	v_exp_f32_e32 v30, v17
	v_min_f32_e32 v31, 0, v16
	s_lshl_b32 s12, s40, 2
	v_add_f32_e32 v18, 1.0, v30
	v_add_f32_e32 v16, -1.0, v18
	v_sub_f32_e32 v17, v16, v18
	v_sub_f32_e32 v16, v30, v16
	v_add_f32_e32 v17, 1.0, v17
	v_frexp_mant_f32_e32 v19, v18
	v_add_f32_e32 v20, v16, v17
	v_cvt_f64_f32_e32 v[16:17], v18
	v_frexp_exp_i32_f64_e32 v16, v[16:17]
	v_cmp_gt_f32_e32 vcc, s34, v19
	s_nop 1
	v_subbrev_co_u32_e32 v24, vcc, 0, v16, vcc
	v_sub_u32_e32 v16, 0, v24
	v_ldexp_f32 v17, v18, v16
	v_ldexp_f32 v16, v20, v16
	v_add_f32_e32 v18, -1.0, v17
	v_add_f32_e32 v20, 1.0, v17
	v_add_f32_e32 v19, 1.0, v18
	v_add_f32_e32 v21, -1.0, v20
	v_sub_f32_e32 v19, v17, v19
	v_sub_f32_e32 v17, v17, v21
	v_add_f32_e32 v19, v16, v19
	v_add_f32_e32 v16, v16, v17
	v_add_f32_e32 v25, v20, v16
	v_rcp_f32_e32 v27, v25
	v_sub_f32_e32 v17, v25, v20
	v_sub_f32_e32 v26, v16, v17
	v_add_f32_e32 v17, v18, v19
	v_mul_f32_e32 v29, v17, v27
	v_sub_f32_e32 v16, v17, v18
	v_mul_f32_e32 v18, v25, v29
	v_fma_f32 v20, v29, v25, -v18
	v_fmac_f32_e32 v20, v29, v26
	v_sub_f32_e32 v28, v19, v16
	v_add_f32_e32 v16, v18, v20
	v_sub_f32_e32 v19, v17, v16
	v_add_f32_e64 v22, v16, -v18
	v_add_f32_e64 v23, v17, -v19
	v_mov_b32_e32 v21, v16
	v_add_f32_e64 v16, v22, -v20
	v_add_f32_e64 v17, v23, -v21
	v_cmp_neq_f32_e32 vcc, s38, v30
	v_add_f32_e32 v17, v28, v17
	v_add_f32_e32 v16, v16, v17
	v_add_f32_e32 v17, v19, v16
	v_mul_f32_e32 v28, v27, v17
	v_mul_f32_e32 v18, v25, v28
	v_fma_f32 v20, v28, v25, -v18
	v_fmac_f32_e32 v20, v28, v26
	v_sub_f32_e32 v19, v19, v17
	v_add_f32_e32 v25, v16, v19
	v_add_f32_e32 v16, v18, v20
	v_sub_f32_e32 v19, v17, v16
	v_add_f32_e64 v22, v16, -v18
	v_add_f32_e64 v23, v17, -v19
	v_mov_b32_e32 v21, v16
	v_add_f32_e64 v16, v22, -v20
	v_add_f32_e64 v17, v23, -v21
	s_nop 0
	v_add_f32_e32 v17, v25, v17
	v_add_f32_e32 v16, v16, v17
	v_add_f32_e32 v17, v29, v28
	v_add_f32_e32 v16, v19, v16
	v_sub_f32_e32 v18, v17, v29
	v_mul_f32_e32 v16, v27, v16
	v_sub_f32_e32 v18, v28, v18
	v_add_f32_e32 v18, v18, v16
	v_add_f32_e32 v20, v17, v18
	v_mul_f32_e32 v21, v20, v20
	v_fmamk_f32 v16, v21, 0x3e9b6dac, v211
	v_fmaak_f32 v151, v21, v16, 0x3f2aaada
	v_cvt_f32_i32_e32 v16, v24
	v_sub_f32_e32 v17, v20, v17
	v_sub_f32_e32 v17, v18, v17
	v_ldexp_f32 v22, v17, 1
	v_mul_f32_e32 v17, v20, v21
	v_ldexp_f32 v19, v20, 1
	v_mul_f32_e32 v20, v16, v150
	v_mul_f32_e32 v21, v17, v151
	s_nop 0
	v_fma_f32 v18, v16, s35, -v20
	v_fmac_f32_e32 v18, 0xb102e308, v16
	v_add_f32_e32 v16, v20, v18
	v_add_f32_e32 v17, v21, v19
	s_nop 0
	v_sub_f32_e32 v19, v17, v19
	v_sub_f32_e32 v19, v21, v19
	v_add_f32_e32 v23, v22, v19
	v_mov_b32_e32 v22, v20
	v_add_f32_e64 v20, v16, -v20
	v_add_f32_e64 v21, v17, -v21
	v_add_f32_e32 v24, v16, v22
	v_add_f32_e32 v25, v17, v23
	v_mov_b32_e32 v19, v16
	v_mov_b32_e32 v21, v25
	v_add_f32_e64 v26, v18, -v20
	v_add_f32_e64 v27, v19, -v21
	v_add_f32_e32 v18, v18, v20
	v_add_f32_e32 v19, v19, v21
	v_mov_b32_e32 v22, v23
	v_add_f32_e64 v20, v19, -v16
	v_add_f32_e64 v21, v18, -v17
	v_add_f32_e64 v28, v24, -v20
	v_add_f32_e64 v29, v25, -v20
	v_mov_b32_e32 v24, v25
	v_mov_b32_e32 v25, v19
	v_pk_mov_b32 v[20:21], v[16:17], v[20:21] op_sel:[1,0]
	v_mov_b32_e32 v23, v16
	v_add_f32_e64 v20, v24, -v20
	v_add_f32_e64 v21, v25, -v21
	v_mov_b32_e32 v28, v26
	v_add_f32_e64 v16, v22, -v20
	v_add_f32_e64 v17, v23, -v21
	v_mov_b32_e32 v27, v19
	v_add_f32_e32 v20, v28, v16
	v_add_f32_e32 v21, v29, v17
	s_nop 0
	v_add_f32_e32 v22, v20, v21
	v_add_f32_e32 v23, v21, v20
	s_nop 0
	v_pk_add_f32 v[18:19], v[18:19], v[22:23] op_sel:[1,0] op_sel_hi:[0,1]
	v_mov_b32_e32 v21, v18
	v_add_f32_e64 v24, v20, -v26
	v_add_f32_e64 v25, v21, -v27
	v_mov_b32_e32 v17, v22
	v_sub_f32_e32 v19, v20, v24
	v_add_f32_e64 v16, v16, -v24
	v_add_f32_e64 v17, v17, -v25
	v_sub_f32_e32 v19, v26, v19
	v_add_f32_e32 v16, v16, v19
	v_add_f32_e32 v16, v16, v17
	v_add_f32_e32 v16, v18, v16
	v_cndmask_b32_e32 v16, v212, v16, vcc
	v_cmp_ngt_f32_e32 vcc, -1.0, v30
	s_nop 1
	v_cndmask_b32_e32 v16, v213, v16, vcc
	v_cmp_neq_f32_e32 vcc, -1.0, v30
	s_nop 1
	v_cndmask_b32_e32 v16, v214, v16, vcc
	v_cmp_lt_f32_e64 vcc, |v30|, s39
	s_nop 1
	v_cndmask_b32_e32 v16, v16, v30, vcc
	v_sub_f32_e32 v18, v31, v16
	v_lshl_add_u64 v[16:17], v[166:167], 0, s[12:13]
	flat_store_dword v[16:17], v18 offset:12
	s_branch .LBB0_1681

; #define GAS __attribute__((address_space(1)))
;     __device__ __forceinline__ void operator()(const Acc& acc, const Unit& u, int wr, int wc, int fr, int fq) const {
;     ...
;         if (kind < 2) {
;             const float* gn = kind == 0 ? qg : kg; const float sc = kind == 0 ? QSCALE : 1.f;
;             f32x4 gv[2][2];
; #pragma unroll
;             for (int bj = 0; bj < 2; ++bj)
; #pragma unroll
;                 for (int n = 0; n < 2; ++n) gv[bj][n] = *(const GAS f32x4*)(gn + 32 * bj + 8 * fq + 4 * n);
;             const int colb = kind * 512 + half * 256 + wc * 64 + 8 * fq;
; #pragma unroll
;             for (int ai = 0; ai < 2; ++ai)
; #pragma unroll
;                 for (int m = 0; m < 4; ++m) {
;                     float ss = 0.f;
; #pragma unroll
;                     for (int bj = 0; bj < 2; ++bj)
; #pragma unroll
;                         for (int n = 0; n < 2; ++n) { const f32x4 x = acc[ai][bj][m][n]; ss += (x[0] * x[0] + x[1] * x[1]) + (x[2] * x[2] + x[3] * x[3]); }
;                     ss += __shfl_xor(ss, 16); ss += __shfl_xor(ss, 32);
;                     const float rs = rsqrtf(ss * (1.f / 64.f) + 1e-6f) * sc;
;                     bf16_t* rowp = P + (size_t)(row0 + ai * HALF + m * 16) * NPROJ + colb;
; #pragma unroll
;                     for (int bj = 0; bj < 2; ++bj) *(GAS u32x4*)(rowp + 32 * bj) = pack8(acc[ai][bj][m][0] * rs * gv[bj][0], acc[ai][bj][m][1] * rs * gv[bj][1]);
.LBB0_1822:
	s_cmp_lt_u32 s30, 2
	s_cselect_b64 vcc, -1, 0
	s_and_b64 s[4:5], vcc, exec
	s_cselect_b32 s0, s23, s45
	s_cselect_b32 s1, s19, s44
	v_lshlrev_b32_e32 v156, 3, v140
	v_mov_b32_e32 v128, s1
	v_mov_b32_e32 v129, s0
	v_ashrrev_i32_e32 v157, 31, v156
	v_lshl_add_u64 v[132:133], v[156:157], 2, v[128:129]
	global_load_dwordx4 v[136:139], v[132:133], off offset:272
	global_load_dwordx4 v[140:143], v[132:133], off offset:256
	global_load_dwordx4 v[128:131], v[132:133], off offset:400
	s_nop 0
	global_load_dwordx4 v[132:135], v[132:133], off offset:384
	v_mul_f32_e32 v158, v126, v126
	v_mul_f32_e32 v159, v127, v127
	v_mul_f32_e32 v160, v124, v124
	v_mul_f32_e32 v161, v125, v125
	v_mul_f32_e32 v157, v112, v112
	v_pk_mov_b32 v[174:175], v[160:161], v[158:159] op_sel:[1,0]
	v_mov_b32_e32 v161, v159
	v_add_f32_e32 v158, v174, v160
	v_add_f32_e32 v159, v175, v161
	v_mul_f32_e32 v160, v122, v122
	v_mul_f32_e32 v161, v123, v123
	v_mul_f32_e32 v174, v120, v120
	v_mul_f32_e32 v175, v121, v121
	v_mul_f32_e32 v173, v113, v113
	v_pk_mov_b32 v[176:177], v[174:175], v[160:161] op_sel:[1,0]
	v_mov_b32_e32 v175, v161
	v_add_f32_e32 v160, v176, v174
	v_add_f32_e32 v161, v177, v175
	v_add_f32_e32 v158, v158, v159
	v_mov_b32_e32 v159, v158
	v_add_f32_e32 v160, v160, v161
	v_mov_b32_e32 v161, v160
	v_mov_b32_e32 v159, v157
	v_mov_b32_e32 v161, v173
	v_add_f32_e32 v158, v158, v160
	v_add_f32_e32 v159, v159, v161
	v_mul_f32_e32 v160, v117, v117
	v_mul_f32_e32 v174, v114, v114
	v_fma_f32 v161, v117, v117, v160
	v_fma_f32 v160, v116, v116, v160
	v_mul_f32_e32 v176, v115, v115
	v_mov_b32_e32 v161, v174
	v_mul_f32_e32 v174, v119, v119
	v_fma_f32 v175, v119, v119, v174
	v_fma_f32 v174, v118, v118, v174
	v_mul_f32_e32 v157, v96, v96
	v_mov_b32_e32 v175, v176
	v_add_f32_e32 v160, v160, v174
	v_add_f32_e32 v161, v161, v175
	v_mul_f32_e32 v174, v108, v108
	v_mul_f32_e32 v175, v109, v109
	v_add_f32_e32 v158, v158, v160
	v_add_f32_e32 v159, v159, v161
	v_mul_f32_e32 v160, v110, v110
	v_mul_f32_e32 v161, v111, v111
	v_mul_f32_e32 v173, v97, v97
	v_pk_mov_b32 v[176:177], v[174:175], v[160:161] op_sel:[1,0]
	v_mov_b32_e32 v175, v161
	v_add_f32_e32 v160, v176, v174
	v_add_f32_e32 v161, v177, v175
	v_mul_f32_e32 v174, v106, v106
	v_mul_f32_e32 v175, v107, v107
	v_mul_f32_e32 v176, v104, v104
	v_mul_f32_e32 v177, v105, v105
	v_add_f32_e32 v160, v160, v161
	v_mov_b32_e32 v161, v160
	v_pk_mov_b32 v[178:179], v[176:177], v[174:175] op_sel:[1,0]
	v_mov_b32_e32 v177, v175
	v_add_f32_e32 v174, v178, v176
	v_add_f32_e32 v175, v179, v177
	v_mov_b32_e32 v161, v157
	v_add_f32_e32 v174, v174, v175
	v_mov_b32_e32 v175, v174
	v_mul_f32_e32 v176, v98, v98
	v_mov_b32_e32 v175, v173
	v_add_f32_e32 v160, v160, v174
	v_add_f32_e32 v161, v161, v175
	v_mul_f32_e32 v174, v101, v101
	v_fma_f32 v175, v101, v101, v174
	v_fma_f32 v174, v100, v100, v174
	v_mul_f32_e32 v178, v99, v99
	v_mov_b32_e32 v175, v176
	v_mul_f32_e32 v176, v103, v103
	v_fma_f32 v177, v103, v103, v176
	v_fma_f32 v176, v102, v102, v176
	v_cndmask_b32_e32 v172, 1.0, v170, vcc
	v_mov_b32_e32 v177, v178
	v_add_f32_e32 v174, v174, v176
	v_add_f32_e32 v175, v175, v177
	s_lshl_b32 s1, s25, 8
	v_add_f32_e32 v160, v160, v174
	v_add_f32_e32 v161, v161, v175
	v_mov_b32_e32 v175, v158
	v_mov_b32_e32 v174, v160
	v_mov_b32_e32 v158, v161
	v_add_f32_e32 v158, v174, v158
	v_add_f32_e32 v159, v175, v159
	ds_bpermute_b32 v161, v164, v159
	ds_bpermute_b32 v160, v164, v158
	s_lshl_b32 s0, s21, 9
	s_or_b32 s1, s1, s58
	s_or_b32 s0, s1, s0
	v_add_u32_e32 v174, s0, v156
	s_waitcnt lgkmcnt(0)
	v_add_f32_e32 v158, v158, v160
	v_add_f32_e32 v159, v159, v161
	ds_bpermute_b32 v161, v165, v159
	ds_bpermute_b32 v160, v165, v158
	v_ashrrev_i32_e32 v175, 31, v174
	v_mov_b64_e32 v[156:157], s[12:13]
	v_mad_i64_i32 v[178:179], s[4:5], v171, s65, v[156:157]
	s_waitcnt lgkmcnt(0)
	v_add_f32_e32 v158, v158, v160
	v_add_f32_e32 v159, v159, v161
	v_mov_b64_e32 v[160:161], s[18:19]
	v_fma_f32 v176, v158, s16, v160
	v_fma_f32 v177, v159, s16, v160
	s_nop 0
	v_mul_f32_e32 v158, 0x4b800000, v177
	v_cmp_gt_f32_e32 vcc, s66, v177
	s_nop 1
	v_cndmask_b32_e32 v158, v177, v158, vcc
	v_rsq_f32_e32 v173, v158
	v_lshlrev_b64 v[158:159], 1, v[174:175]
	v_lshl_add_u64 v[174:175], v[178:179], 0, v[158:159]
	v_mul_f32_e32 v177, 0x45800000, v173
	v_cndmask_b32_e32 v173, v173, v177, vcc
	v_mul_f32_e32 v178, v172, v173
	v_mul_f32_e32 v124, v124, v178
	v_mul_f32_e32 v125, v125, v178
	v_mul_f32_e32 v126, v126, v178
	v_mul_f32_e32 v127, v127, v178
	v_mul_f32_e32 v120, v120, v178
	v_mul_f32_e32 v121, v121, v178
	v_mul_f32_e32 v122, v122, v178
	v_mul_f32_e32 v123, v123, v178
	s_waitcnt vmcnt(0)
; #define GAS __attribute__((address_space(1)))
;     __device__ __forceinline__ void operator()(const Acc& acc, const Unit& u, int wr, int wc, int fr, int fq) const {
;     ...
;                         for (int n = 0; n < 2; ++n) { const f32x4 x = acc[ai][bj][m][n]; ss += (x[0] * x[0] + x[1] * x[1]) + (x[2] * x[2] + x[3] * x[3]); }
;                     ss += __shfl_xor(ss, 16); ss += __shfl_xor(ss, 32);
;                     const float rs = rsqrtf(ss * (1.f / 64.f) + 1e-6f) * sc;
;                     bf16_t* rowp = P + (size_t)(row0 + ai * HALF + m * 16) * NPROJ + colb;
; #pragma unroll
;                     for (int bj = 0; bj < 2; ++bj) *(GAS u32x4*)(rowp + 32 * bj) = pack8(acc[ai][bj][m][0] * rs * gv[bj][0], acc[ai][bj][m][1] * rs * gv[bj][1]);
	v_mul_f32_e32 v126, v142, v126
	v_mul_f32_e32 v127, v143, v127
	v_mul_f32_e32 v124, v140, v124
	v_mul_f32_e32 v125, v141, v125
	v_mul_f32_e32 v180, v138, v122
	v_mul_f32_e32 v181, v139, v123
	v_mul_f32_e32 v122, v136, v120
	v_mul_f32_e32 v123, v137, v121
	v_mul_f32_e32 v116, v116, v178
	v_mul_f32_e32 v117, v117, v178
	v_cvt_pk_bf16_f32 v120, v124, v125
	v_cvt_pk_bf16_f32 v121, v126, v127
	v_cvt_pk_bf16_f32 v122, v122, v123
	v_cvt_pk_bf16_f32 v123, v180, v181
	v_mul_f32_e32 v116, v132, v116
	v_mul_f32_e32 v117, v133, v117
	v_mul_f32_e32 v112, v112, v178
	v_mul_f32_e32 v113, v113, v178
	v_mul_f32_e32 v114, v114, v178
	v_mul_f32_e32 v115, v115, v178
	global_store_dwordx4 v[174:175], v[120:123], off
	v_cmp_gt_f32_e32 vcc, s66, v176
	v_mul_f32_e32 v118, v118, v178
	v_mul_f32_e32 v119, v119, v178
	v_mul_f32_e32 v120, v130, v114
	v_mul_f32_e32 v121, v131, v115
	v_mul_f32_e32 v114, v128, v112
	v_mul_f32_e32 v115, v129, v113
	v_cvt_pk_bf16_f32 v112, v116, v117
	v_mul_f32_e32 v116, 0x4b800000, v176
	v_cndmask_b32_e32 v116, v176, v116, vcc
	v_rsq_f32_e32 v116, v116
	v_mul_f32_e32 v118, v134, v118
	v_mul_f32_e32 v119, v135, v119
	v_cvt_pk_bf16_f32 v114, v114, v115
	v_cvt_pk_bf16_f32 v113, v118, v119
	v_cvt_pk_bf16_f32 v115, v120, v121
	global_store_dwordx4 v[174:175], v[112:115], off offset:64
	s_nop 1
	v_mul_f32_e32 v112, 0x45800000, v116
	v_cndmask_b32_e32 v112, v116, v112, vcc
	v_mul_f32_e32 v112, v172, v112
	v_or_b32_e32 v113, 16, v171
	v_mul_f32_e32 v108, v108, v112
	v_mul_f32_e32 v109, v109, v112
	v_mul_f32_e32 v110, v110, v112
	v_mul_f32_e32 v111, v111, v112
	v_mul_f32_e32 v104, v104, v112
	v_mul_f32_e32 v105, v105, v112
	v_mul_f32_e32 v106, v106, v112
	v_mul_f32_e32 v107, v107, v112
	v_mad_i64_i32 v[114:115], s[4:5], v113, s65, v[156:157]
	v_mul_f32_e32 v110, v142, v110
	v_mul_f32_e32 v111, v143, v111
	v_mul_f32_e32 v108, v140, v108
	v_mul_f32_e32 v109, v141, v109
	v_mul_f32_e32 v116, v138, v106
	v_mul_f32_e32 v117, v139, v107
	v_mul_f32_e32 v106, v136, v104
	v_mul_f32_e32 v107, v137, v105
	v_lshl_add_u64 v[114:115], v[114:115], 0, v[158:159]
	v_cvt_pk_bf16_f32 v104, v108, v109
	v_cvt_pk_bf16_f32 v105, v110, v111
	v_cvt_pk_bf16_f32 v106, v106, v107
	v_cvt_pk_bf16_f32 v107, v116, v117
	global_store_dwordx4 v[114:115], v[104:107], off
	v_mul_f32_e32 v100, v100, v112
	v_mul_f32_e32 v101, v101, v112
	v_mul_f32_e32 v102, v102, v112
	v_mul_f32_e32 v103, v103, v112
	v_mul_f32_e32 v104, v94, v94
	v_mul_f32_e32 v105, v95, v95
	v_mul_f32_e32 v106, v92, v92
	v_mul_f32_e32 v107, v93, v93
	v_mul_f32_e32 v96, v96, v112
	v_mul_f32_e32 v97, v97, v112
	v_pk_mov_b32 v[108:109], v[106:107], v[104:105] op_sel:[1,0]
	v_mov_b32_e32 v107, v105
	v_add_f32_e32 v104, v108, v106
	v_add_f32_e32 v105, v109, v107
	v_mul_f32_e32 v106, v90, v90
	v_mul_f32_e32 v107, v91, v91
	v_mul_f32_e32 v108, v88, v88
	v_mul_f32_e32 v109, v89, v89
	v_add_f32_e32 v104, v104, v105
	v_mov_b32_e32 v105, v104
	v_pk_mov_b32 v[110:111], v[108:109], v[106:107] op_sel:[1,0]
	v_mov_b32_e32 v109, v107
	v_add_f32_e32 v106, v110, v108
	v_add_f32_e32 v107, v111, v109
	v_mul_f32_e32 v108, v76, v76
	v_mul_f32_e32 v109, v77, v77
	v_add_f32_e32 v106, v106, v107
	v_mov_b32_e32 v107, v106
	v_mov_b32_e32 v105, v108
	v_mov_b32_e32 v107, v109
	v_add_f32_e32 v104, v104, v106
	v_add_f32_e32 v105, v105, v107
	v_mul_f32_e32 v106, v85, v85
	v_mul_f32_e32 v108, v87, v87
	v_mul_f32_e32 v110, v78, v78
	v_mul_f32_e32 v111, v79, v79
	v_fma_f32 v107, v85, v85, v106
	v_fma_f32 v106, v84, v84, v106
	v_fma_f32 v109, v87, v87, v108
	v_fma_f32 v108, v86, v86, v108
	v_mov_b32_e32 v107, v110
	v_mov_b32_e32 v109, v111
	v_add_f32_e32 v106, v106, v108
	v_add_f32_e32 v107, v107, v109
	v_mul_f32_e32 v108, v80, v80
	v_mul_f32_e32 v109, v81, v81
	v_add_f32_e32 v104, v104, v106
	v_add_f32_e32 v105, v105, v107
	v_mul_f32_e32 v106, v82, v82
	v_mul_f32_e32 v107, v83, v83
	v_mul_f32_e32 v98, v98, v112
	v_mul_f32_e32 v99, v99, v112
	v_pk_mov_b32 v[110:111], v[108:109], v[106:107] op_sel:[1,0]
	v_mov_b32_e32 v109, v107
	v_add_f32_e32 v106, v110, v108
	v_add_f32_e32 v107, v111, v109
	v_mul_f32_e32 v108, v74, v74
	v_mul_f32_e32 v109, v75, v75
	v_mul_f32_e32 v110, v72, v72
	v_mul_f32_e32 v111, v73, v73
	v_add_f32_e32 v106, v106, v107
	v_mov_b32_e32 v107, v106
	v_pk_mov_b32 v[112:113], v[110:111], v[108:109] op_sel:[1,0]
	v_mov_b32_e32 v111, v109
	v_add_f32_e32 v108, v112, v110
	v_add_f32_e32 v109, v113, v111
	v_mul_f32_e32 v110, v64, v64
	v_mul_f32_e32 v111, v65, v65
	v_add_f32_e32 v108, v108, v109
	v_mov_b32_e32 v109, v108
	v_mov_b32_e32 v107, v110
	v_mov_b32_e32 v109, v111
	v_add_f32_e32 v106, v106, v108
	v_add_f32_e32 v107, v107, v109
	v_mul_f32_e32 v108, v69, v69
	v_mul_f32_e32 v110, v71, v71
	v_mul_f32_e32 v112, v66, v66
	v_mul_f32_e32 v113, v67, v67
	v_fma_f32 v109, v69, v69, v108
	v_fma_f32 v108, v68, v68, v108
	v_fma_f32 v111, v71, v71, v110
	v_fma_f32 v110, v70, v70, v110
	v_mov_b32_e32 v109, v112
	v_mov_b32_e32 v111, v113
	v_add_f32_e32 v108, v108, v110
	v_add_f32_e32 v109, v109, v111
	v_mul_f32_e32 v100, v132, v100
	v_mul_f32_e32 v101, v133, v101
	v_add_f32_e32 v106, v106, v108
	v_add_f32_e32 v107, v107, v109
	v_mov_b32_e32 v109, v104
	v_mov_b32_e32 v108, v106
	v_mov_b32_e32 v104, v107
	v_add_f32_e32 v104, v108, v104
	v_add_f32_e32 v105, v109, v105
	ds_bpermute_b32 v107, v164, v105
	ds_bpermute_b32 v106, v164, v104
	v_mul_f32_e32 v102, v134, v102
	v_mul_f32_e32 v103, v135, v103
	v_mul_f32_e32 v108, v130, v98
	v_mul_f32_e32 v109, v131, v99
	v_mul_f32_e32 v98, v128, v96
	v_mul_f32_e32 v99, v129, v97
	v_cvt_pk_bf16_f32 v96, v100, v101
	s_waitcnt lgkmcnt(0)
; #define GAS __attribute__((address_space(1)))
;     __device__ __forceinline__ void operator()(const Acc& acc, const Unit& u, int wr, int wc, int fr, int fq) const {
;     ...
;                         for (int n = 0; n < 2; ++n) { const f32x4 x = acc[ai][bj][m][n]; ss += (x[0] * x[0] + x[1] * x[1]) + (x[2] * x[2] + x[3] * x[3]); }
;                     ss += __shfl_xor(ss, 16); ss += __shfl_xor(ss, 32);
;                     const float rs = rsqrtf(ss * (1.f / 64.f) + 1e-6f) * sc;
;                     bf16_t* rowp = P + (size_t)(row0 + ai * HALF + m * 16) * NPROJ + colb;
; #pragma unroll
;                     for (int bj = 0; bj < 2; ++bj) *(GAS u32x4*)(rowp + 32 * bj) = pack8(acc[ai][bj][m][0] * rs * gv[bj][0], acc[ai][bj][m][1] * rs * gv[bj][1]);
	v_add_f32_e32 v100, v104, v106
	v_add_f32_e32 v101, v105, v107
	v_cvt_pk_bf16_f32 v97, v102, v103
	ds_bpermute_b32 v103, v165, v101
	ds_bpermute_b32 v102, v165, v100
	v_cvt_pk_bf16_f32 v98, v98, v99
	v_cvt_pk_bf16_f32 v99, v108, v109
	global_store_dwordx4 v[114:115], v[96:99], off offset:64
	s_waitcnt lgkmcnt(0)
	s_nop 0
	v_add_f32_e32 v96, v100, v102
	v_add_f32_e32 v97, v101, v103
	v_or_b32_e32 v98, 32, v171
	v_fma_f32 v96, v96, s16, v160
	v_fma_f32 v97, v97, s16, v160
	s_nop 0
	v_mul_f32_e32 v99, 0x4b800000, v97
	v_cmp_gt_f32_e32 vcc, s66, v97
	s_nop 1
	v_cndmask_b32_e32 v97, v97, v99, vcc
	v_rsq_f32_e32 v97, v97
	v_mad_i64_i32 v[98:99], s[4:5], v98, s65, v[156:157]
	v_lshl_add_u64 v[98:99], v[98:99], 0, v[158:159]
	v_mul_f32_e32 v100, 0x45800000, v97
	v_cndmask_b32_e32 v97, v97, v100, vcc
	v_mul_f32_e32 v100, v172, v97
	v_mul_f32_e32 v92, v92, v100
	v_mul_f32_e32 v93, v93, v100
	v_mul_f32_e32 v94, v94, v100
	v_mul_f32_e32 v95, v95, v100
	v_mul_f32_e32 v88, v88, v100
	v_mul_f32_e32 v89, v89, v100
	v_mul_f32_e32 v90, v90, v100
	v_mul_f32_e32 v91, v91, v100
	v_mul_f32_e32 v94, v142, v94
	v_mul_f32_e32 v95, v143, v95
	v_mul_f32_e32 v92, v140, v92
	v_mul_f32_e32 v93, v141, v93
	v_mul_f32_e32 v102, v138, v90
	v_mul_f32_e32 v103, v139, v91
	v_mul_f32_e32 v90, v136, v88
	v_mul_f32_e32 v91, v137, v89
	v_mul_f32_e32 v84, v84, v100
	v_mul_f32_e32 v85, v85, v100
	v_cvt_pk_bf16_f32 v88, v92, v93
	v_cvt_pk_bf16_f32 v89, v94, v95
	v_cvt_pk_bf16_f32 v90, v90, v91
	v_cvt_pk_bf16_f32 v91, v102, v103
	v_mul_f32_e32 v84, v132, v84
	v_mul_f32_e32 v85, v133, v85
	v_mul_f32_e32 v76, v76, v100
	v_mul_f32_e32 v77, v77, v100
	v_mul_f32_e32 v78, v78, v100
	v_mul_f32_e32 v79, v79, v100
	global_store_dwordx4 v[98:99], v[88:91], off
	v_cmp_gt_f32_e32 vcc, s66, v96
	v_mul_f32_e32 v86, v86, v100
	v_mul_f32_e32 v87, v87, v100
	v_mul_f32_e32 v88, v130, v78
	v_mul_f32_e32 v89, v131, v79
	v_mul_f32_e32 v78, v128, v76
	v_mul_f32_e32 v79, v129, v77
	v_cvt_pk_bf16_f32 v76, v84, v85
	v_mul_f32_e32 v84, 0x4b800000, v96
	v_cndmask_b32_e32 v84, v96, v84, vcc
	v_rsq_f32_e32 v84, v84
	v_mul_f32_e32 v86, v134, v86
	v_mul_f32_e32 v87, v135, v87
	v_cvt_pk_bf16_f32 v78, v78, v79
	v_cvt_pk_bf16_f32 v77, v86, v87
	v_cvt_pk_bf16_f32 v79, v88, v89
	global_store_dwordx4 v[98:99], v[76:79], off offset:64
	s_nop 1
	v_mul_f32_e32 v76, 0x45800000, v84
	v_cndmask_b32_e32 v76, v84, v76, vcc
	v_mul_f32_e32 v76, v172, v76
	v_or_b32_e32 v77, 48, v171
	v_mul_f32_e32 v80, v80, v76
	v_mul_f32_e32 v81, v81, v76
	v_mul_f32_e32 v82, v82, v76
	v_mul_f32_e32 v83, v83, v76
	v_mul_f32_e32 v72, v72, v76
	v_mul_f32_e32 v73, v73, v76
	v_mul_f32_e32 v74, v74, v76
	v_mul_f32_e32 v75, v75, v76
	v_mad_i64_i32 v[78:79], s[4:5], v77, s65, v[156:157]
	v_mul_f32_e32 v82, v142, v82
	v_mul_f32_e32 v83, v143, v83
	v_mul_f32_e32 v80, v140, v80
	v_mul_f32_e32 v81, v141, v81
	v_mul_f32_e32 v84, v138, v74
	v_mul_f32_e32 v85, v139, v75
	v_mul_f32_e32 v74, v136, v72
	v_mul_f32_e32 v75, v137, v73
	v_lshl_add_u64 v[78:79], v[78:79], 0, v[158:159]
	v_cvt_pk_bf16_f32 v72, v80, v81
	v_cvt_pk_bf16_f32 v73, v82, v83
	v_cvt_pk_bf16_f32 v74, v74, v75
	v_cvt_pk_bf16_f32 v75, v84, v85
	global_store_dwordx4 v[78:79], v[72:75], off
	v_mul_f32_e32 v68, v68, v76
	v_mul_f32_e32 v69, v69, v76
	v_mul_f32_e32 v70, v70, v76
	v_mul_f32_e32 v71, v71, v76
	v_mul_f32_e32 v72, v62, v62
	v_mul_f32_e32 v73, v63, v63
	v_mul_f32_e32 v74, v60, v60
	v_mul_f32_e32 v75, v61, v61
	v_mul_f32_e32 v64, v64, v76
	v_mul_f32_e32 v65, v65, v76
	v_mul_f32_e32 v66, v66, v76
	v_mul_f32_e32 v67, v67, v76
	v_pk_mov_b32 v[76:77], v[74:75], v[72:73] op_sel:[1,0]
	v_mov_b32_e32 v75, v73
	v_add_f32_e32 v72, v76, v74
	v_add_f32_e32 v73, v77, v75
	v_mul_f32_e32 v74, v58, v58
	v_mul_f32_e32 v75, v59, v59
	v_mul_f32_e32 v76, v56, v56
	v_mul_f32_e32 v77, v57, v57
	v_add_f32_e32 v72, v72, v73
	v_mov_b32_e32 v73, v72
	v_pk_mov_b32 v[80:81], v[76:77], v[74:75] op_sel:[1,0]
	v_mov_b32_e32 v77, v75
	v_add_f32_e32 v74, v80, v76
	v_add_f32_e32 v75, v81, v77
	v_mul_f32_e32 v76, v44, v44
	v_mul_f32_e32 v77, v45, v45
	v_add_f32_e32 v74, v74, v75
	v_mov_b32_e32 v75, v74
	v_mov_b32_e32 v73, v76
	v_mov_b32_e32 v75, v77
	v_add_f32_e32 v72, v72, v74
	v_add_f32_e32 v73, v73, v75
	v_mul_f32_e32 v74, v53, v53
	v_mul_f32_e32 v76, v55, v55
	v_mul_f32_e32 v80, v46, v46
	v_mul_f32_e32 v81, v47, v47
	v_fma_f32 v75, v53, v53, v74
	v_fma_f32 v74, v52, v52, v74
	v_fma_f32 v77, v55, v55, v76
	v_fma_f32 v76, v54, v54, v76
	v_mov_b32_e32 v75, v80
	v_mov_b32_e32 v77, v81
	v_add_f32_e32 v74, v74, v76
	v_add_f32_e32 v75, v75, v77
	v_mul_f32_e32 v76, v48, v48
	v_mul_f32_e32 v77, v49, v49
	v_add_f32_e32 v72, v72, v74
	v_add_f32_e32 v73, v73, v75
	v_mul_f32_e32 v74, v50, v50
	v_mul_f32_e32 v75, v51, v51
	v_mul_f32_e32 v68, v132, v68
	v_mul_f32_e32 v69, v133, v69
	v_pk_mov_b32 v[80:81], v[76:77], v[74:75] op_sel:[1,0]
	v_mov_b32_e32 v77, v75
	v_add_f32_e32 v74, v80, v76
	v_add_f32_e32 v75, v81, v77
	v_mul_f32_e32 v76, v42, v42
	v_mul_f32_e32 v77, v43, v43
	v_mul_f32_e32 v80, v40, v40
	v_mul_f32_e32 v81, v41, v41
	v_add_f32_e32 v74, v74, v75
	v_mov_b32_e32 v75, v74
	v_pk_mov_b32 v[82:83], v[80:81], v[76:77] op_sel:[1,0]
	v_mov_b32_e32 v81, v77
	v_add_f32_e32 v76, v82, v80
	v_add_f32_e32 v77, v83, v81
	v_mul_f32_e32 v80, v32, v32
	v_mul_f32_e32 v81, v33, v33
	v_add_f32_e32 v76, v76, v77
	v_mov_b32_e32 v77, v76
	v_mov_b32_e32 v75, v80
	v_mov_b32_e32 v77, v81
	v_add_f32_e32 v74, v74, v76
	v_add_f32_e32 v75, v75, v77
	v_mul_f32_e32 v76, v37, v37
	v_mul_f32_e32 v80, v39, v39
	v_mul_f32_e32 v82, v34, v34
	v_mul_f32_e32 v83, v35, v35
	v_fma_f32 v77, v37, v37, v76
	v_fma_f32 v76, v36, v36, v76
	v_fma_f32 v81, v39, v39, v80
	v_fma_f32 v80, v38, v38, v80
	v_mov_b32_e32 v77, v82
	v_mov_b32_e32 v81, v83
	v_add_f32_e32 v76, v76, v80
	v_add_f32_e32 v77, v77, v81
	v_mul_f32_e32 v70, v134, v70
	v_mul_f32_e32 v71, v135, v71
	v_add_f32_e32 v74, v74, v76
	v_add_f32_e32 v75, v75, v77
	v_mov_b32_e32 v77, v72
	v_mov_b32_e32 v76, v74
	v_mov_b32_e32 v72, v75
	v_add_f32_e32 v72, v76, v72
	v_add_f32_e32 v73, v77, v73
	ds_bpermute_b32 v75, v164, v73
	ds_bpermute_b32 v74, v164, v72
	v_mul_f32_e32 v76, v130, v66
	v_mul_f32_e32 v77, v131, v67
	v_mul_f32_e32 v66, v128, v64
	v_mul_f32_e32 v67, v129, v65
	v_cvt_pk_bf16_f32 v64, v68, v69
	v_cvt_pk_bf16_f32 v65, v70, v71
	s_waitcnt lgkmcnt(0)
; #define GAS __attribute__((address_space(1)))
;     __device__ __forceinline__ void operator()(const Acc& acc, const Unit& u, int wr, int wc, int fr, int fq) const {
;     ...
;                         for (int n = 0; n < 2; ++n) { const f32x4 x = acc[ai][bj][m][n]; ss += (x[0] * x[0] + x[1] * x[1]) + (x[2] * x[2] + x[3] * x[3]); }
;                     ss += __shfl_xor(ss, 16); ss += __shfl_xor(ss, 32);
;                     const float rs = rsqrtf(ss * (1.f / 64.f) + 1e-6f) * sc;
;                     bf16_t* rowp = P + (size_t)(row0 + ai * HALF + m * 16) * NPROJ + colb;
; #pragma unroll
;                     for (int bj = 0; bj < 2; ++bj) *(GAS u32x4*)(rowp + 32 * bj) = pack8(acc[ai][bj][m][0] * rs * gv[bj][0], acc[ai][bj][m][1] * rs * gv[bj][1]);
	v_add_f32_e32 v68, v72, v74
	v_add_f32_e32 v69, v73, v75
	ds_bpermute_b32 v71, v165, v69
	ds_bpermute_b32 v70, v165, v68
	v_cvt_pk_bf16_f32 v66, v66, v67
	v_cvt_pk_bf16_f32 v67, v76, v77
	global_store_dwordx4 v[78:79], v[64:67], off offset:64
	s_waitcnt lgkmcnt(0)
	s_nop 0
	v_add_f32_e32 v64, v68, v70
	v_add_f32_e32 v65, v69, v71
	v_add_u32_e32 v66, 0x80, v171
	v_fma_f32 v64, v64, s16, v160
	v_fma_f32 v65, v65, s16, v160
	s_nop 0
	v_mul_f32_e32 v67, 0x4b800000, v65
	v_cmp_gt_f32_e32 vcc, s66, v65
	s_nop 1
	v_cndmask_b32_e32 v65, v65, v67, vcc
	v_rsq_f32_e32 v65, v65
	v_mad_i64_i32 v[66:67], s[4:5], v66, s65, v[156:157]
	v_lshl_add_u64 v[66:67], v[66:67], 0, v[158:159]
	v_mul_f32_e32 v68, 0x45800000, v65
	v_cndmask_b32_e32 v65, v65, v68, vcc
	v_mul_f32_e32 v68, v172, v65
	v_mul_f32_e32 v60, v60, v68
	v_mul_f32_e32 v61, v61, v68
	v_mul_f32_e32 v62, v62, v68
	v_mul_f32_e32 v63, v63, v68
	v_mul_f32_e32 v56, v56, v68
	v_mul_f32_e32 v57, v57, v68
	v_mul_f32_e32 v58, v58, v68
	v_mul_f32_e32 v59, v59, v68
	v_mul_f32_e32 v62, v142, v62
	v_mul_f32_e32 v63, v143, v63
	v_mul_f32_e32 v60, v140, v60
	v_mul_f32_e32 v61, v141, v61
	v_mul_f32_e32 v70, v138, v58
	v_mul_f32_e32 v71, v139, v59
	v_mul_f32_e32 v58, v136, v56
	v_mul_f32_e32 v59, v137, v57
	v_mul_f32_e32 v52, v52, v68
	v_mul_f32_e32 v53, v53, v68
	v_cvt_pk_bf16_f32 v56, v60, v61
	v_cvt_pk_bf16_f32 v57, v62, v63
	v_cvt_pk_bf16_f32 v58, v58, v59
	v_cvt_pk_bf16_f32 v59, v70, v71
	v_mul_f32_e32 v52, v132, v52
	v_mul_f32_e32 v53, v133, v53
	v_mul_f32_e32 v44, v44, v68
	v_mul_f32_e32 v45, v45, v68
	v_mul_f32_e32 v46, v46, v68
	v_mul_f32_e32 v47, v47, v68
	global_store_dwordx4 v[66:67], v[56:59], off
	v_cmp_gt_f32_e32 vcc, s66, v64
	v_mul_f32_e32 v54, v54, v68
	v_mul_f32_e32 v55, v55, v68
	v_mul_f32_e32 v56, v130, v46
	v_mul_f32_e32 v57, v131, v47
	v_mul_f32_e32 v46, v128, v44
	v_mul_f32_e32 v47, v129, v45
	v_cvt_pk_bf16_f32 v44, v52, v53
	v_mul_f32_e32 v52, 0x4b800000, v64
	v_cndmask_b32_e32 v52, v64, v52, vcc
	v_rsq_f32_e32 v52, v52
	v_mul_f32_e32 v54, v134, v54
	v_mul_f32_e32 v55, v135, v55
	v_cvt_pk_bf16_f32 v46, v46, v47
	v_cvt_pk_bf16_f32 v45, v54, v55
	v_cvt_pk_bf16_f32 v47, v56, v57
	global_store_dwordx4 v[66:67], v[44:47], off offset:64
	s_nop 1
	v_mul_f32_e32 v44, 0x45800000, v52
	v_cndmask_b32_e32 v44, v52, v44, vcc
	v_mul_f32_e32 v44, v172, v44
	v_add_u32_e32 v45, 0x90, v171
	v_mul_f32_e32 v48, v48, v44
	v_mul_f32_e32 v49, v49, v44
	v_mul_f32_e32 v50, v50, v44
	v_mul_f32_e32 v51, v51, v44
	v_mul_f32_e32 v40, v40, v44
	v_mul_f32_e32 v41, v41, v44
	v_mul_f32_e32 v42, v42, v44
	v_mul_f32_e32 v43, v43, v44
	v_mad_i64_i32 v[46:47], s[4:5], v45, s65, v[156:157]
	v_mul_f32_e32 v50, v142, v50
	v_mul_f32_e32 v51, v143, v51
	v_mul_f32_e32 v48, v140, v48
	v_mul_f32_e32 v49, v141, v49
	v_mul_f32_e32 v52, v138, v42
	v_mul_f32_e32 v53, v139, v43
	v_mul_f32_e32 v42, v136, v40
	v_mul_f32_e32 v43, v137, v41
	v_lshl_add_u64 v[46:47], v[46:47], 0, v[158:159]
	v_cvt_pk_bf16_f32 v40, v48, v49
	v_cvt_pk_bf16_f32 v41, v50, v51
	v_cvt_pk_bf16_f32 v42, v42, v43
	v_cvt_pk_bf16_f32 v43, v52, v53
	global_store_dwordx4 v[46:47], v[40:43], off
	v_mul_f32_e32 v36, v36, v44
	v_mul_f32_e32 v37, v37, v44
	v_mul_f32_e32 v38, v38, v44
	v_mul_f32_e32 v39, v39, v44
	v_mul_f32_e32 v40, v30, v30
	v_mul_f32_e32 v41, v31, v31
	v_mul_f32_e32 v42, v28, v28
	v_mul_f32_e32 v43, v29, v29
	v_mul_f32_e32 v32, v32, v44
	v_mul_f32_e32 v33, v33, v44
	v_mul_f32_e32 v34, v34, v44
	v_mul_f32_e32 v35, v35, v44
	v_pk_mov_b32 v[44:45], v[42:43], v[40:41] op_sel:[1,0]
	v_mov_b32_e32 v43, v41
	v_add_f32_e32 v40, v44, v42
	v_add_f32_e32 v41, v45, v43
	v_mul_f32_e32 v42, v26, v26
	v_mul_f32_e32 v43, v27, v27
	v_mul_f32_e32 v44, v24, v24
	v_mul_f32_e32 v45, v25, v25
	v_add_f32_e32 v40, v40, v41
	v_mov_b32_e32 v41, v40
	v_pk_mov_b32 v[48:49], v[44:45], v[42:43] op_sel:[1,0]
	v_mov_b32_e32 v45, v43
	v_add_f32_e32 v42, v48, v44
	v_add_f32_e32 v43, v49, v45
	v_mul_f32_e32 v44, v12, v12
	v_mul_f32_e32 v45, v13, v13
	v_add_f32_e32 v42, v42, v43
	v_mov_b32_e32 v43, v42
	v_mov_b32_e32 v41, v44
	v_mov_b32_e32 v43, v45
	v_add_f32_e32 v40, v40, v42
	v_add_f32_e32 v41, v41, v43
	v_mul_f32_e32 v42, v21, v21
	v_mul_f32_e32 v44, v23, v23
	v_mul_f32_e32 v48, v14, v14
	v_mul_f32_e32 v49, v15, v15
	v_fma_f32 v43, v21, v21, v42
	v_fma_f32 v42, v20, v20, v42
	v_fma_f32 v45, v23, v23, v44
	v_fma_f32 v44, v22, v22, v44
	v_mov_b32_e32 v43, v48
	v_mov_b32_e32 v45, v49
	v_add_f32_e32 v42, v42, v44
	v_add_f32_e32 v43, v43, v45
	v_mul_f32_e32 v44, v16, v16
	v_mul_f32_e32 v45, v17, v17
	v_add_f32_e32 v40, v40, v42
	v_add_f32_e32 v41, v41, v43
	v_mul_f32_e32 v42, v18, v18
	v_mul_f32_e32 v43, v19, v19
	v_mul_f32_e32 v36, v132, v36
	v_mul_f32_e32 v37, v133, v37
	v_pk_mov_b32 v[48:49], v[44:45], v[42:43] op_sel:[1,0]
	v_mov_b32_e32 v45, v43
	v_add_f32_e32 v42, v48, v44
	v_add_f32_e32 v43, v49, v45
	v_mul_f32_e32 v44, v10, v10
	v_mul_f32_e32 v45, v11, v11
	v_mul_f32_e32 v48, v8, v8
	v_mul_f32_e32 v49, v9, v9
	v_add_f32_e32 v42, v42, v43
	v_mov_b32_e32 v43, v42
	v_pk_mov_b32 v[50:51], v[48:49], v[44:45] op_sel:[1,0]
	v_mov_b32_e32 v49, v45
	v_add_f32_e32 v44, v50, v48
	v_add_f32_e32 v45, v51, v49
	v_mul_f32_e32 v48, v0, v0
	v_mul_f32_e32 v49, v1, v1
	v_add_f32_e32 v44, v44, v45
	v_mov_b32_e32 v45, v44
	v_mov_b32_e32 v43, v48
	v_mov_b32_e32 v45, v49
	v_add_f32_e32 v42, v42, v44
	v_add_f32_e32 v43, v43, v45
	v_mul_f32_e32 v44, v5, v5
	v_mul_f32_e32 v48, v7, v7
	v_mul_f32_e32 v50, v2, v2
	v_mul_f32_e32 v51, v3, v3
	v_fma_f32 v45, v5, v5, v44
	v_fma_f32 v44, v4, v4, v44
	v_fma_f32 v49, v7, v7, v48
	v_fma_f32 v48, v6, v6, v48
	v_mov_b32_e32 v45, v50
	v_mov_b32_e32 v49, v51
	v_add_f32_e32 v44, v44, v48
	v_add_f32_e32 v45, v45, v49
	v_mul_f32_e32 v38, v134, v38
	v_mul_f32_e32 v39, v135, v39
	v_add_f32_e32 v42, v42, v44
	v_add_f32_e32 v43, v43, v45
	v_mov_b32_e32 v45, v40
	v_mov_b32_e32 v44, v42
	v_mov_b32_e32 v40, v43
	v_add_f32_e32 v40, v44, v40
	v_add_f32_e32 v41, v45, v41
	ds_bpermute_b32 v43, v164, v41
	ds_bpermute_b32 v42, v164, v40
	v_mul_f32_e32 v44, v130, v34
	v_mul_f32_e32 v45, v131, v35
	v_mul_f32_e32 v34, v128, v32
	v_mul_f32_e32 v35, v129, v33
	v_cvt_pk_bf16_f32 v32, v36, v37
	v_cvt_pk_bf16_f32 v33, v38, v39
	s_waitcnt lgkmcnt(0)
; #define GAS __attribute__((address_space(1)))
;     __device__ __forceinline__ void operator()(const Acc& acc, const Unit& u, int wr, int wc, int fr, int fq) const {
;     ...
;                         for (int n = 0; n < 2; ++n) { const f32x4 x = acc[ai][bj][m][n]; ss += (x[0] * x[0] + x[1] * x[1]) + (x[2] * x[2] + x[3] * x[3]); }
;                     ss += __shfl_xor(ss, 16); ss += __shfl_xor(ss, 32);
;                     const float rs = rsqrtf(ss * (1.f / 64.f) + 1e-6f) * sc;
;                     bf16_t* rowp = P + (size_t)(row0 + ai * HALF + m * 16) * NPROJ + colb;
; #pragma unroll
;                     for (int bj = 0; bj < 2; ++bj) *(GAS u32x4*)(rowp + 32 * bj) = pack8(acc[ai][bj][m][0] * rs * gv[bj][0], acc[ai][bj][m][1] * rs * gv[bj][1]);
	v_add_f32_e32 v36, v40, v42
	v_add_f32_e32 v37, v41, v43
	ds_bpermute_b32 v39, v165, v37
	ds_bpermute_b32 v38, v165, v36
	v_cvt_pk_bf16_f32 v34, v34, v35
	v_cvt_pk_bf16_f32 v35, v44, v45
	global_store_dwordx4 v[46:47], v[32:35], off offset:64
	s_waitcnt lgkmcnt(0)
	s_nop 0
	v_add_f32_e32 v32, v36, v38
	v_add_f32_e32 v33, v37, v39
	v_add_u32_e32 v34, 0xa0, v171
	v_fma_f32 v32, v32, s16, v160
	v_fma_f32 v33, v33, s16, v160
	s_nop 0
	v_mul_f32_e32 v35, 0x4b800000, v33
	v_cmp_gt_f32_e32 vcc, s66, v33
	s_nop 1
	v_cndmask_b32_e32 v33, v33, v35, vcc
	v_rsq_f32_e32 v33, v33
	v_mad_i64_i32 v[34:35], s[4:5], v34, s65, v[156:157]
	v_lshl_add_u64 v[34:35], v[34:35], 0, v[158:159]
	v_mul_f32_e32 v36, 0x45800000, v33
	v_cndmask_b32_e32 v33, v33, v36, vcc
	v_mul_f32_e32 v36, v172, v33
	v_mul_f32_e32 v28, v28, v36
	v_mul_f32_e32 v29, v29, v36
	v_mul_f32_e32 v30, v30, v36
	v_mul_f32_e32 v31, v31, v36
	v_mul_f32_e32 v24, v24, v36
	v_mul_f32_e32 v25, v25, v36
	v_mul_f32_e32 v26, v26, v36
	v_mul_f32_e32 v27, v27, v36
	v_mul_f32_e32 v30, v142, v30
	v_mul_f32_e32 v31, v143, v31
	v_mul_f32_e32 v28, v140, v28
	v_mul_f32_e32 v29, v141, v29
	v_mul_f32_e32 v38, v138, v26
	v_mul_f32_e32 v39, v139, v27
	v_mul_f32_e32 v26, v136, v24
	v_mul_f32_e32 v27, v137, v25
	v_mul_f32_e32 v20, v20, v36
	v_mul_f32_e32 v21, v21, v36
	v_cvt_pk_bf16_f32 v24, v28, v29
	v_cvt_pk_bf16_f32 v25, v30, v31
	v_cvt_pk_bf16_f32 v26, v26, v27
	v_cvt_pk_bf16_f32 v27, v38, v39
	v_mul_f32_e32 v20, v132, v20
	v_mul_f32_e32 v21, v133, v21
	v_mul_f32_e32 v12, v12, v36
	v_mul_f32_e32 v13, v13, v36
	v_mul_f32_e32 v14, v14, v36
	v_mul_f32_e32 v15, v15, v36
	global_store_dwordx4 v[34:35], v[24:27], off
	v_cmp_gt_f32_e32 vcc, s66, v32
	v_mul_f32_e32 v22, v22, v36
	v_mul_f32_e32 v23, v23, v36
	v_mul_f32_e32 v24, v130, v14
	v_mul_f32_e32 v25, v131, v15
	v_mul_f32_e32 v14, v128, v12
	v_mul_f32_e32 v15, v129, v13
	v_cvt_pk_bf16_f32 v12, v20, v21
	v_mul_f32_e32 v20, 0x4b800000, v32
	v_cndmask_b32_e32 v20, v32, v20, vcc
	v_rsq_f32_e32 v20, v20
	v_mul_f32_e32 v22, v134, v22
	v_mul_f32_e32 v23, v135, v23
	v_cvt_pk_bf16_f32 v14, v14, v15
	v_cvt_pk_bf16_f32 v13, v22, v23
	v_cvt_pk_bf16_f32 v15, v24, v25
	global_store_dwordx4 v[34:35], v[12:15], off offset:64
	s_nop 1
	v_mul_f32_e32 v12, 0x45800000, v20
	v_cndmask_b32_e32 v12, v20, v12, vcc
	v_mul_f32_e32 v12, v172, v12
	v_add_u32_e32 v13, 0xb0, v171
	v_mad_i64_i32 v[14:15], s[4:5], v13, s65, v[156:157]
	v_mul_f32_e32 v16, v16, v12
	v_mul_f32_e32 v17, v17, v12
	v_mul_f32_e32 v18, v18, v12
	v_mul_f32_e32 v19, v19, v12
	v_mul_f32_e32 v8, v8, v12
	v_mul_f32_e32 v9, v9, v12
	v_mul_f32_e32 v10, v10, v12
	v_mul_f32_e32 v11, v11, v12
	v_mul_f32_e32 v4, v4, v12
	v_mul_f32_e32 v5, v5, v12
	v_mul_f32_e32 v6, v6, v12
	v_mul_f32_e32 v7, v7, v12
	v_mul_f32_e32 v0, v0, v12
	v_mul_f32_e32 v1, v1, v12
	v_mul_f32_e32 v2, v2, v12
	v_mul_f32_e32 v3, v3, v12
	v_lshl_add_u64 v[14:15], v[14:15], 0, v[158:159]
	v_mul_f32_e32 v18, v142, v18
	v_mul_f32_e32 v19, v143, v19
	v_mul_f32_e32 v16, v140, v16
	v_mul_f32_e32 v17, v141, v17
	v_mul_f32_e32 v20, v138, v10
	v_mul_f32_e32 v21, v139, v11
	v_mul_f32_e32 v10, v136, v8
	v_mul_f32_e32 v11, v137, v9
	v_mul_f32_e32 v6, v134, v6
	v_mul_f32_e32 v7, v135, v7
	v_mul_f32_e32 v4, v132, v4
	v_mul_f32_e32 v5, v133, v5
	v_mul_f32_e32 v2, v130, v2
	v_mul_f32_e32 v3, v131, v3
	v_mul_f32_e32 v0, v128, v0
	v_mul_f32_e32 v1, v129, v1
	v_cvt_pk_bf16_f32 v8, v16, v17
	v_cvt_pk_bf16_f32 v9, v18, v19
	v_cvt_pk_bf16_f32 v10, v10, v11
	v_cvt_pk_bf16_f32 v11, v20, v21
	v_cvt_pk_bf16_f32 v128, v4, v5
	v_cvt_pk_bf16_f32 v129, v6, v7
	v_cvt_pk_bf16_f32 v130, v0, v1
	v_cvt_pk_bf16_f32 v131, v2, v3
	v_lshl_add_u64 v[132:133], v[14:15], 0, 64
	global_store_dwordx4 v[14:15], v[8:11], off
	s_andn2_b64 vcc, exec, s[2:3]
	s_mov_b64 s[2:3], -1
	global_store_dwordx4 v[132:133], v[128:131], off
	s_cbranch_vccnz .LBB0_1747

; __device__ __forceinline__ void attn_phase(LAS unsigned char* lds, const int wid, const bf16_t* P, const float* LF, bf16_t* CAT, const float* qgain, const float* kgain) {
;     ...
;             float base = inc - c[7];
;             for (int i = 0; i < wid; ++i) base += red[i];
; #pragma unroll
;             for (int i = 0; i < 8; ++i) CB[tid * 8 + i] = -(base + c[i]) * LOG2E;
;         }
;         __syncthreads();
;     ...
;             const int qb = ui == 0 ? jq : (ui == 1 ? 15 - jq : (ui == 2 ? 7 - jq : 8 + jq));
.LBB0_1889:
	s_ashr_i32 s20, s68, 5
	v_add_f32_e32 v2, v2, v10
	v_add_f32_e32 v3, v3, v10
	s_lshl_b32 s0, s18, 7
	s_lshl_b32 s1, s68, 5
	v_mul_f32_e32 v12, s48, v2
	v_mul_f32_e32 v13, s48, v3
	v_add_f32_e32 v2, v8, v10
	v_add_f32_e32 v3, v9, v10
	s_ashr_i32 s21, s20, 31
	s_and_b32 s40, s0, 0x380
	s_mul_i32 s0, s20, 0x1400000
	s_and_b32 s1, s1, 0x380
	s_and_b32 s69, s68, 3
	v_mul_f32_e32 v14, s48, v2
	v_mul_f32_e32 v15, s48, v3
	v_add_f32_e32 v2, v6, v10
	v_add_f32_e32 v3, v7, v10
	v_add_f32_e32 v4, v4, v10
	v_add_f32_e32 v5, v5, v10
	s_lshl_b64 s[52:53], s[20:21], 12
	s_mul_hi_i32 s19, s20, 0x1400000
	s_or_b32 s18, s0, s1
	v_mul_f32_e32 v2, s48, v2
	v_mul_f32_e32 v3, s48, v3
	v_mul_f32_e32 v4, s48, v4
	v_mul_f32_e32 v5, s48, v5
	v_lshl_add_u64 v[120:121], v[108:109], 0, s[40:41]
	v_lshl_add_u64 v[122:123], s[52:53], 0, v[104:105]
	v_lshl_add_u64 v[124:125], v[110:111], 0, s[40:41]
	s_xor_b32 s70, s69, 15
	s_xor_b32 s71, s69, 7
	s_or_b32 s72, s69, 8
	v_lshl_add_u64 v[126:127], v[114:115], 0, s[40:41]
	v_lshl_add_u64 v[128:129], v[116:117], 0, s[40:41]
	v_lshl_add_u64 v[130:131], v[118:119], 0, s[18:19]
	s_mov_b32 s73, 0
	ds_write_b128 v156, v[12:15]
	ds_write_b128 v156, v[2:5] offset:16
	s_waitcnt lgkmcnt(0)
	s_barrier
	s_branch .LBB0_1891

; #define LAS __attribute__((address_space(3)))
; __device__ __forceinline__ void attn_phase(LAS unsigned char* lds, const int wid, const bf16_t* P, const float* LF, bf16_t* CAT, const float* qgain, const float* kgain) {
;     ...
;                 if (kt * 64 <= q0 + 31 && !done_w) {
;                     const LAS unsigned char* kb_ = KB + cb * 64 * KPITCH;
;                     const LAS unsigned char* vb_ = VB + cb * 64 * VPITCH;
;                     f32x16 sacc[2];
; #pragma unroll
;                     for (int kb = 0; kb < 2; ++kb) {
; #pragma unroll
;                         for (int i = 0; i < 16; ++i) sacc[kb][i] = 0.f;
; #pragma unroll
;                         for (int ds = 0; ds < 4; ++ds) {
;                             const bf16x8 a = *(const LAS bf16x8*)(kb_ + (kb * 32 + r32) * KPITCH + (16 * ds + 8 * hh) * 2);
;                             sacc[kb] = __builtin_amdgcn_mfma_f32_32x32x16_bf16(a, qf[ds], sacc[kb], 0, 0, 0);
;                         }
;                     }
;                     const bool diag = (kt * 64 + 63 > q0);
;                     float mloc = -1e30f;
; #pragma unroll
;                     for (int kb = 0; kb < 2; ++kb)
; #pragma unroll
;                         for (int i4 = 0; i4 < 4; ++i4) {
;                             const int kl = kb * 32 + 8 * i4 + 4 * hh;
;                             const f32x4 bias = *(const LAS f32x4*)(CB + kt * 64 + kl);
; #pragma unroll
;                             for (int jj = 0; jj < 4; ++jj) {
;                                 float sv = sacc[kb][4 * i4 + jj] + bias[jj];
;                                 if (diag && (kt * 64 + kl + jj > qrow)) sv = -1e30f;
;                                 sacc[kb][4 * i4 + jj] = sv; mloc = fmaxf(mloc, sv);
;                             }
;                         }
.LBB0_1900:
	s_and_b32 s80, s20, 1
	s_cmp_le_i32 s77, s76
	s_cselect_b64 s[18:19], -1, 0
	v_cmp_eq_u32_e32 vcc, 0, v165
	s_and_b64 s[56:57], s[18:19], vcc
	s_and_saveexec_b64 s[58:59], s[56:57]
	s_cbranch_execz .LBB0_1902
	s_mul_i32 s0, s80, 0x2400
	v_add3_u32 v1, v160, s0, v162
	ds_read_b128 v[2:5], v1 offset:16384
	ds_read_b128 v[6:9], v1 offset:16416
	v_add_u32_e32 v14, s78, v159
	s_add_i32 s0, s77, 63
	v_add_u32_e32 v15, s77, v112
	s_waitcnt lgkmcnt(1)
	v_mfma_f32_32x32x16_bf16 v[64:79], v[2:5], v[88:91], 0
	ds_read_b128 v[2:5], v1 offset:16448
	s_cmp_gt_i32 s0, s74
	v_cmp_gt_i32_e32 vcc, v15, v134
	s_cselect_b64 s[60:61], -1, 0
	v_cmp_ge_i32_e64 s[18:19], v15, v134
	s_and_b64 vcc, s[60:61], vcc
	s_mul_i32 s0, s80, 0x2200
	s_waitcnt lgkmcnt(1)
	v_mfma_f32_32x32x16_bf16 v[64:79], v[6:9], v[92:95], v[64:79]
	ds_read_b128 v[6:9], v1 offset:16480
	ds_read_b128 v[10:13], v1 offset:20992
	s_waitcnt lgkmcnt(2)
	v_mfma_f32_32x32x16_bf16 v[64:79], v[2:5], v[96:99], v[64:79]
	ds_read_b128 v[2:5], v14 offset:4
	ds_read_b128 v[168:171], v14 offset:36
	ds_read_b128 v[172:175], v1 offset:21024
	ds_read_b128 v[176:179], v1 offset:21056
	ds_read_b128 v[180:183], v1 offset:21088
	v_add_u32_e32 v1, 2, v15
	v_cmp_gt_i32_e64 s[20:21], v1, v134
	s_waitcnt lgkmcnt(6)
	v_mfma_f32_32x32x16_bf16 v[64:79], v[6:9], v[100:103], v[64:79]
	s_waitcnt lgkmcnt(5)
	v_mfma_f32_32x32x16_bf16 v[48:63], v[10:13], v[88:91], 0
	s_waitcnt lgkmcnt(4)
	s_nop 8
	v_add_f32_e32 v1, v64, v2
	v_add_u32_e32 v10, 3, v15
	v_add_f32_e32 v2, v65, v3
	v_cndmask_b32_e32 v1, v1, v164, vcc
	s_and_b64 vcc, s[60:61], s[18:19]
	v_add_u32_e32 v11, 8, v15
	v_cmp_gt_i32_e64 s[24:25], v10, v134
	v_add_f32_e32 v3, v66, v4
	v_cndmask_b32_e32 v10, v2, v164, vcc
	s_and_b64 vcc, s[60:61], s[20:21]
	v_cmp_gt_i32_e64 s[26:27], v11, v134
	v_add_f32_e32 v4, v67, v5
	v_cndmask_b32_e32 v12, v3, v164, vcc
	s_and_b64 vcc, s[60:61], s[24:25]
	s_waitcnt lgkmcnt(3)
	v_add_f32_e32 v5, v68, v168
	v_cndmask_b32_e32 v13, v4, v164, vcc
	s_and_b64 vcc, s[60:61], s[26:27]
	v_cndmask_b32_e32 v64, v5, v164, vcc
	v_cmp_ge_i32_e32 vcc, v11, v134
	v_add_f32_e32 v3, v69, v169
	s_and_b64 vcc, s[60:61], vcc
	v_max3_f32 v2, v1, s67, v10
	v_cndmask_b32_e32 v11, v3, v164, vcc
	v_add_u32_e32 v3, 10, v15
	v_max3_f32 v2, v2, v12, v13
	v_cmp_gt_i32_e32 vcc, v3, v134
	v_max3_f32 v6, v2, v64, v11
	v_add_f32_e32 v2, v70, v170
	s_and_b64 vcc, s[60:61], vcc
	v_cndmask_b32_e32 v65, v2, v164, vcc
	v_add_u32_e32 v2, 11, v15
	v_cmp_gt_i32_e32 vcc, v2, v134
	ds_read_b128 v[2:5], v14 offset:68
	s_waitcnt lgkmcnt(3)
	v_mfma_f32_32x32x16_bf16 v[48:63], v[172:175], v[92:95], v[48:63]
	v_add_f32_e32 v7, v71, v171
	s_and_b64 vcc, s[60:61], vcc
	v_add_u32_e32 v68, 16, v15
	v_cndmask_b32_e32 v66, v7, v164, vcc
	v_cmp_gt_i32_e32 vcc, v68, v134
	v_max3_f32 v67, v6, v65, v66
	ds_read_b128 v[6:9], v14 offset:100
	s_waitcnt lgkmcnt(1)
	v_add_f32_e32 v2, v72, v2
	s_and_b64 vcc, s[60:61], vcc
	v_cndmask_b32_e32 v69, v2, v164, vcc
	v_cmp_ge_i32_e32 vcc, v68, v134
	v_add_f32_e32 v2, v73, v3
	s_and_b64 vcc, s[60:61], vcc
	v_add_f32_e32 v3, v74, v4
	v_add_u32_e32 v4, 18, v15
	v_cndmask_b32_e32 v68, v2, v164, vcc
	v_cmp_gt_i32_e32 vcc, v4, v134
	v_mfma_f32_32x32x16_bf16 v[48:63], v[176:179], v[96:99], v[48:63]
	s_and_b64 vcc, s[60:61], vcc
	v_add_u32_e32 v4, 19, v15
	v_max3_f32 v2, v67, v69, v68
	v_cndmask_b32_e32 v67, v3, v164, vcc
	v_cmp_gt_i32_e32 vcc, v4, v134
	v_add_f32_e32 v3, v75, v5
	s_and_b64 vcc, s[60:61], vcc
	v_cndmask_b32_e32 v70, v3, v164, vcc
	v_add_u32_e32 v3, 24, v15
	v_cmp_gt_i32_e32 vcc, v3, v134
	s_waitcnt lgkmcnt(0)
	v_add_f32_e32 v4, v76, v6
	s_and_b64 vcc, s[60:61], vcc
	v_cndmask_b32_e32 v71, v4, v164, vcc
	v_cmp_ge_i32_e32 vcc, v3, v134
	v_add_f32_e32 v4, v77, v7
	s_and_b64 vcc, s[60:61], vcc
	v_add_u32_e32 v3, 26, v15
	v_mfma_f32_32x32x16_bf16 v[48:63], v[180:183], v[100:103], v[48:63]
	v_max3_f32 v2, v2, v67, v70
	v_cndmask_b32_e32 v72, v4, v164, vcc
	v_cmp_gt_i32_e32 vcc, v3, v134
	v_max3_f32 v6, v2, v71, v72
	v_add_f32_e32 v2, v78, v8
	s_and_b64 vcc, s[60:61], vcc
	v_cndmask_b32_e32 v73, v2, v164, vcc
	v_add_u32_e32 v2, 27, v15
	v_cmp_gt_i32_e32 vcc, v2, v134
	ds_read_b128 v[2:5], v14 offset:132
	v_add_f32_e32 v7, v79, v9
	s_and_b64 vcc, s[60:61], vcc
	v_add_u32_e32 v76, 32, v15
	v_cndmask_b32_e32 v74, v7, v164, vcc
	v_cmp_gt_i32_e32 vcc, v76, v134
	v_max3_f32 v75, v6, v73, v74
	ds_read_b128 v[6:9], v14 offset:164
	s_waitcnt lgkmcnt(1)
	v_add_f32_e32 v2, v48, v2
	s_and_b64 vcc, s[60:61], vcc
	v_cndmask_b32_e32 v48, v2, v164, vcc
	v_cmp_ge_i32_e32 vcc, v76, v134
	v_add_f32_e32 v2, v49, v3
	s_and_b64 vcc, s[60:61], vcc
	v_add_f32_e32 v3, v50, v4
	v_add_u32_e32 v4, 34, v15
	v_cndmask_b32_e32 v49, v2, v164, vcc
	v_cmp_gt_i32_e32 vcc, v4, v134
	s_and_b64 vcc, s[60:61], vcc
	v_add_u32_e32 v4, 35, v15
	v_cndmask_b32_e32 v50, v3, v164, vcc
	v_cmp_gt_i32_e32 vcc, v4, v134
	v_add_f32_e32 v3, v51, v5
	s_and_b64 vcc, s[60:61], vcc
	v_cndmask_b32_e32 v51, v3, v164, vcc
	v_add_u32_e32 v3, 40, v15
	v_cmp_gt_i32_e32 vcc, v3, v134
	s_waitcnt lgkmcnt(0)
	v_add_f32_e32 v4, v52, v6
	s_and_b64 vcc, s[60:61], vcc
	v_cndmask_b32_e32 v52, v4, v164, vcc
	v_cmp_ge_i32_e32 vcc, v3, v134
	v_max3_f32 v2, v75, v48, v49
	v_add_f32_e32 v4, v53, v7
	s_and_b64 vcc, s[60:61], vcc
	v_add_u32_e32 v3, 42, v15
	v_max3_f32 v2, v2, v50, v51
	v_cndmask_b32_e32 v53, v4, v164, vcc
	v_cmp_gt_i32_e32 vcc, v3, v134
	v_max3_f32 v6, v2, v52, v53
	v_add_f32_e32 v2, v54, v8
	s_and_b64 vcc, s[60:61], vcc
	v_cndmask_b32_e32 v54, v2, v164, vcc
	v_add_u32_e32 v2, 43, v15
	v_cmp_gt_i32_e32 vcc, v2, v134
	ds_read_b128 v[2:5], v14 offset:196
	v_add_f32_e32 v7, v55, v9
	s_and_b64 vcc, s[60:61], vcc
	v_add_u32_e32 v76, 48, v15
	v_cndmask_b32_e32 v55, v7, v164, vcc
	v_cmp_gt_i32_e32 vcc, v76, v134
	v_max3_f32 v75, v6, v54, v55
	ds_read_b128 v[6:9], v14 offset:228
	s_waitcnt lgkmcnt(1)
; #define LAS __attribute__((address_space(3)))
; __device__ __forceinline__ unsigned cvt_pk_bf16(float lo, float hi) { const f32x2 v = {lo, hi}; return __builtin_bit_cast(unsigned, __builtin_convertvector(v, b16x2_t)); }
; __device__ __forceinline__ void attn_phase(LAS unsigned char* lds, const int wid, const bf16_t* P, const float* LF, bf16_t* CAT, const float* qgain, const float* kgain) {
;     ...
;                                 if (diag && (kt * 64 + kl + jj > qrow)) sv = -1e30f;
;                                 sacc[kb][4 * i4 + jj] = sv; mloc = fmaxf(mloc, sv);
;                             }
;                         }
;                     mloc = fmaxf(mloc, __shfl_xor(mloc, 32));
;                     const float mnew = fmaxf(mrun, mloc);
;                     const float alpha = fexp2(mrun - mnew); mrun = mnew;
;                     float ps = 0.f;
; #pragma unroll
;                     for (int kb = 0; kb < 2; ++kb)
; #pragma unroll
;                         for (int i = 0; i < 16; ++i) { const float p = fexp2(sacc[kb][i] - mnew); sacc[kb][i] = p; ps += p; }
;                     lsum = lsum * alpha + ps;
; #pragma unroll
;                     for (int i = 0; i < 16; ++i) { O[0][i] *= alpha; O[1][i] *= alpha; }
; #pragma unroll
;                     for (int kb = 0; kb < 2; ++kb)
; #pragma unroll
;                         for (int s2 = 0; s2 < 2; ++s2) {
;                             u32x4 pw; pw.x = cvt_pk_bf16(sacc[kb][8 * s2 + 0], sacc[kb][8 * s2 + 1]); pw.y = cvt_pk_bf16(sacc[kb][8 * s2 + 2], sacc[kb][8 * s2 + 3]);
;                             pw.z = cvt_pk_bf16(sacc[kb][8 * s2 + 4], sacc[kb][8 * s2 + 5]); pw.w = cvt_pk_bf16(sacc[kb][8 * s2 + 6], sacc[kb][8 * s2 + 7]);
;                             const bf16x8 pf = __builtin_bit_cast(bf16x8, pw);
; #pragma unroll
;                             for (int db = 0; db < 2; ++db) {
;                                 const LAS unsigned char* vp = vb_ + (db * 32 + r32) * VPITCH + (kb * 32 + 16 * s2 + 4 * hh) * 2;
;                                 const s16x4 lo = *(const LAS s16x4*)vp, hi = *(const LAS s16x4*)(vp + 16);
;                                 const bf16x8 av = __builtin_shufflevector(lo, hi, 0, 1, 2, 3, 4, 5, 6, 7);
;                                 O[db] = __builtin_amdgcn_mfma_f32_32x32x16_bf16(av, pf, O[db], 0, 0, 0);
;                             }
;                         }
	v_add_f32_e32 v2, v56, v2
	s_and_b64 vcc, s[60:61], vcc
	v_cndmask_b32_e32 v56, v2, v164, vcc
	v_cmp_ge_i32_e32 vcc, v76, v134
	v_add_f32_e32 v2, v57, v3
	s_and_b64 vcc, s[60:61], vcc
	v_add_f32_e32 v3, v58, v4
	v_add_u32_e32 v4, 50, v15
	v_cndmask_b32_e32 v57, v2, v164, vcc
	v_cmp_gt_i32_e32 vcc, v4, v134
	s_and_b64 vcc, s[60:61], vcc
	v_add_u32_e32 v4, 51, v15
	v_cndmask_b32_e32 v58, v3, v164, vcc
	v_cmp_gt_i32_e32 vcc, v4, v134
	v_add_f32_e32 v3, v59, v5
	s_and_b64 vcc, s[60:61], vcc
	v_cndmask_b32_e32 v59, v3, v164, vcc
	v_add_u32_e32 v3, 56, v15
	v_cmp_gt_i32_e32 vcc, v3, v134
	s_waitcnt lgkmcnt(0)
	v_add_f32_e32 v4, v60, v6
	s_and_b64 vcc, s[60:61], vcc
	v_cndmask_b32_e32 v60, v4, v164, vcc
	v_cmp_ge_i32_e32 vcc, v3, v134
	v_add_f32_e32 v4, v61, v7
	s_and_b64 vcc, s[60:61], vcc
	v_cndmask_b32_e32 v61, v4, v164, vcc
	v_add_u32_e32 v4, 58, v15
	v_cmp_gt_i32_e32 vcc, v4, v134
	v_add_f32_e32 v3, v62, v8
	s_and_b64 vcc, s[60:61], vcc
	v_add_u32_e32 v4, 59, v15
	v_max3_f32 v2, v75, v56, v57
	v_cndmask_b32_e32 v62, v3, v164, vcc
	v_cmp_gt_i32_e32 vcc, v4, v134
	v_max3_f32 v2, v2, v58, v59
	v_add_f32_e32 v3, v63, v9
	s_and_b64 vcc, s[60:61], vcc
	v_max3_f32 v2, v2, v60, v61
	v_cndmask_b32_e32 v15, v3, v164, vcc
	v_max3_f32 v2, v2, v62, v15
	ds_bpermute_b32 v3, v146, v2
	s_waitcnt lgkmcnt(0)
	v_max3_f32 v63, v166, v2, v3
	v_sub_f32_e32 v1, v1, v63
	v_exp_f32_e32 v1, v1
	v_sub_f32_e32 v3, v10, v63
	v_exp_f32_e32 v6, v3
	v_sub_f32_e32 v3, v12, v63
	v_exp_f32_e32 v7, v3
	v_sub_f32_e32 v3, v13, v63
	v_exp_f32_e32 v8, v3
	v_sub_f32_e32 v4, v64, v63
	v_add_f32_e32 v3, 0, v1
	v_exp_f32_e32 v9, v4
	v_sub_f32_e32 v4, v11, v63
	v_add_f32_e32 v3, v6, v3
	v_exp_f32_e32 v10, v4
	v_sub_f32_e32 v4, v65, v63
	v_add_f32_e32 v3, v7, v3
	v_exp_f32_e32 v11, v4
	v_sub_f32_e32 v4, v66, v63
	v_add_f32_e32 v3, v8, v3
	v_exp_f32_e32 v12, v4
	v_sub_f32_e32 v4, v69, v63
	v_add_f32_e32 v3, v9, v3
	v_exp_f32_e32 v64, v4
	v_sub_f32_e32 v4, v68, v63
	v_add_f32_e32 v3, v10, v3
	v_exp_f32_e32 v65, v4
	v_sub_f32_e32 v4, v67, v63
	v_add_f32_e32 v3, v11, v3
	v_exp_f32_e32 v66, v4
	v_sub_f32_e32 v4, v70, v63
	v_add_f32_e32 v3, v12, v3
	v_exp_f32_e32 v67, v4
	v_sub_f32_e32 v4, v71, v63
	v_add_f32_e32 v3, v64, v3
	v_exp_f32_e32 v68, v4
	v_sub_f32_e32 v4, v72, v63
	v_add_f32_e32 v3, v65, v3
	v_exp_f32_e32 v69, v4
	v_sub_f32_e32 v4, v73, v63
	v_add_f32_e32 v3, v66, v3
	v_exp_f32_e32 v70, v4
	v_sub_f32_e32 v4, v74, v63
	v_add_f32_e32 v3, v67, v3
	v_exp_f32_e32 v71, v4
	v_sub_f32_e32 v4, v48, v63
	v_add_f32_e32 v3, v68, v3
	v_exp_f32_e32 v48, v4
	v_sub_f32_e32 v4, v49, v63
	v_add_f32_e32 v3, v69, v3
	v_exp_f32_e32 v49, v4
	v_sub_f32_e32 v4, v50, v63
	v_add_f32_e32 v3, v70, v3
	v_exp_f32_e32 v50, v4
	v_sub_f32_e32 v4, v51, v63
	v_add_f32_e32 v3, v71, v3
	v_exp_f32_e32 v51, v4
	v_sub_f32_e32 v4, v52, v63
	v_add_f32_e32 v3, v48, v3
	v_exp_f32_e32 v52, v4
	v_sub_f32_e32 v4, v53, v63
	v_add_f32_e32 v3, v49, v3
	v_exp_f32_e32 v53, v4
	v_sub_f32_e32 v4, v54, v63
	v_add_f32_e32 v3, v50, v3
	v_exp_f32_e32 v54, v4
	v_add_f32_e32 v3, v51, v3
	v_sub_f32_e32 v2, v166, v63
	v_add_f32_e32 v3, v52, v3
	v_add3_u32 v13, v161, s0, v163
	v_add_f32_e32 v3, v53, v3
	v_exp_f32_e32 v14, v2
	v_sub_f32_e32 v2, v55, v63
	v_add_u32_e32 v73, 0x8800, v13
	v_add_f32_e32 v72, v54, v3
	v_exp_f32_e32 v55, v2
	ds_read2_b64 v[2:5], v73 offset1:2
	v_cvt_pk_bf16_f32 v6, v1, v6
	v_add_u32_e32 v1, 0x9800, v13
	v_cvt_pk_bf16_f32 v7, v7, v8
	v_cvt_pk_bf16_f32 v8, v9, v10
	v_cvt_pk_bf16_f32 v9, v11, v12
	ds_read2_b64 v[10:13], v1 offset0:32 offset1:34
	v_mul_f32_e32 v46, v46, v14
	v_mul_f32_e32 v47, v47, v14
	v_mul_f32_e32 v44, v44, v14
	v_mul_f32_e32 v45, v45, v14
	v_mul_f32_e32 v42, v42, v14
	v_mul_f32_e32 v43, v43, v14
	v_mul_f32_e32 v40, v40, v14
	v_mul_f32_e32 v41, v41, v14
	v_mul_f32_e32 v38, v38, v14
	v_mul_f32_e32 v39, v39, v14
	v_mul_f32_e32 v36, v36, v14
	v_mul_f32_e32 v37, v37, v14
	v_mul_f32_e32 v34, v34, v14
	v_mul_f32_e32 v35, v35, v14
	v_mul_f32_e32 v32, v32, v14
	v_mul_f32_e32 v33, v33, v14
	v_mul_f32_e32 v30, v30, v14
	v_mul_f32_e32 v31, v31, v14
	v_mul_f32_e32 v28, v28, v14
	v_mul_f32_e32 v29, v29, v14
	s_waitcnt lgkmcnt(1)
	v_mfma_f32_32x32x16_bf16 v[32:47], v[2:5], v[6:9], v[32:47]
	ds_read2_b64 v[2:5], v73 offset0:4 offset1:6
	v_mul_f32_e64 v26, v26, v14
	v_mul_f32_e64 v27, v27, v14
	v_mul_f32_e64 v24, v24, v14
	v_mul_f32_e64 v25, v25, v14
	v_mul_f32_e32 v22, v22, v14
	v_mul_f32_e32 v23, v23, v14
	v_mul_f32_e32 v20, v20, v14
	v_mul_f32_e32 v21, v21, v14
	v_mul_f32_e32 v18, v18, v14
	v_mul_f32_e32 v19, v19, v14
	v_mul_f32_e32 v16, v16, v14
	v_mul_f32_e32 v17, v17, v14
	v_mov_b32_e32 v166, v63
	s_waitcnt lgkmcnt(1)
	v_mfma_f32_32x32x16_bf16 v[16:31], v[10:13], v[6:9], v[16:31]
	v_sub_f32_e32 v6, v56, v63
	v_exp_f32_e32 v56, v6
	ds_read2_b64 v[10:13], v1 offset0:36 offset1:38
	v_cvt_pk_bf16_f32 v6, v64, v65
	v_cvt_pk_bf16_f32 v7, v66, v67
	v_cvt_pk_bf16_f32 v8, v68, v69
	v_cvt_pk_bf16_f32 v9, v70, v71
	s_waitcnt lgkmcnt(1)
	s_nop 0
	v_mfma_f32_32x32x16_bf16 v[32:47], v[2:5], v[6:9], v[32:47]
	v_add_f32_e32 v2, v55, v72
	v_add_f32_e32 v64, v56, v2
	v_sub_f32_e32 v2, v57, v63
	v_exp_f32_e32 v57, v2
	v_sub_f32_e32 v2, v58, v63
	v_exp_f32_e32 v58, v2
	ds_read2_b64 v[2:5], v73 offset0:8 offset1:10
	s_waitcnt lgkmcnt(1)
	v_mfma_f32_32x32x16_bf16 v[16:31], v[10:13], v[6:9], v[16:31]
	ds_read2_b64 v[10:13], v1 offset0:40 offset1:42
	v_sub_f32_e32 v6, v59, v63
	v_exp_f32_e32 v59, v6
	v_cvt_pk_bf16_f32 v6, v48, v49
	v_cvt_pk_bf16_f32 v7, v50, v51
	v_cvt_pk_bf16_f32 v8, v52, v53
	v_cvt_pk_bf16_f32 v9, v54, v55
	s_waitcnt lgkmcnt(1)
	s_nop 0
	v_mfma_f32_32x32x16_bf16 v[32:47], v[2:5], v[6:9], v[32:47]
	v_sub_f32_e32 v2, v60, v63
	v_exp_f32_e32 v48, v2
	v_sub_f32_e32 v2, v61, v63
	v_exp_f32_e32 v49, v2
	v_sub_f32_e32 v2, v62, v63
	v_exp_f32_e32 v50, v2
	ds_read2_b64 v[2:5], v73 offset0:12 offset1:14
	s_waitcnt lgkmcnt(1)
	v_mfma_f32_32x32x16_bf16 v[16:31], v[10:13], v[6:9], v[16:31]
	ds_read2_b64 v[10:13], v1 offset0:44 offset1:46
	v_sub_f32_e32 v6, v15, v63
	v_exp_f32_e32 v15, v6
	v_cvt_pk_bf16_f32 v6, v56, v57
	v_cvt_pk_bf16_f32 v7, v58, v59
	v_cvt_pk_bf16_f32 v8, v48, v49
	v_cvt_pk_bf16_f32 v9, v50, v15
	v_add_f32_e32 v1, v57, v64
	v_add_f32_e32 v1, v58, v1
	s_waitcnt lgkmcnt(1)
	v_mfma_f32_32x32x16_bf16 v[32:47], v[2:5], v[6:9], v[32:47]
	v_add_f32_e32 v1, v59, v1
	v_add_f32_e32 v1, v48, v1
	v_add_f32_e32 v1, v49, v1
	v_add_f32_e32 v1, v50, v1
	v_add_f32_e32 v1, v15, v1
	v_fmac_f32_e32 v1, v135, v14
	v_mov_b32_e32 v135, v1
	s_waitcnt lgkmcnt(0)
	v_mfma_f32_32x32x16_bf16 v[16:31], v[10:13], v[6:9], v[16:31]

; #define GAS __attribute__((address_space(1)))
; __device__ __forceinline__ void rmsnorm_rows_rwkv(const bf16_t* x, const float* gain, const float* mu_r, const float* mu_k, bf16_t* H, bf16_t* XR, bf16_t* XK, int gw, int NGW, int lane) {
;     ...
;         for (int r = 0; r <= RB; ++r) {
;             const float rstd = (first && r == 0) ? 0.f : rsqrtf(s[r] * (1.f / D) + 1e-6f);
; #pragma unroll
;             for (int j = 0; j < 2; ++j)
; #pragma unroll
;                 for (int e = 0; e < 2; ++e) v[r][j][e] = v[r][j][e] * rstd * g[j][e];
;         }
; #pragma unroll
;         for (int r = 1; r <= RB; ++r) {
;             const int row = row0 + r - 1;
;             const size_t hrow = (size_t)row + (row >> 12) + 1;
; #pragma unroll
;             for (int j = 0; j < 2; ++j) {
;                 const size_t co = (size_t)512 * j + lane * 8;
;                 *(GAS u32x4*)(H + hrow * D + co) = pack8(v[r][j][0], v[r][j][1]);
;                 const f32x4 d0 = v[r - 1][j][0] - v[r][j][0], d1 = v[r - 1][j][1] - v[r][j][1];
;                 *(GAS u32x4*)(XR + (size_t)row * D + co) = pack8(v[r][j][0] + d0 * mr[j][0], v[r][j][1] + d1 * mr[j][1]);
;                 *(GAS u32x4*)(XK + (size_t)row * D + co) = pack8(v[r][j][0] + d0 * mk[j][0], v[r][j][1] + d1 * mk[j][1]);
.LBB0_2407:
	s_waitcnt lgkmcnt(2)
	v_add_f32_e32 v152, v152, v154
	v_add_f32_e32 v153, v153, v155
	v_cvt_f32_f16_e32 v140, v54
	v_fma_f32 v152, v152, s26, v62
	v_fma_f32 v153, v153, s26, v62
	v_mov_b32_e32 v54, v97
	v_mul_f32_e32 v97, 0x4b800000, v153
	v_cmp_gt_f32_e32 vcc, s40, v153
	v_cvt_f32_f16_e32 v132, v50
	v_cvt_f32_f16_e32 v144, v52
	v_cndmask_b32_e32 v97, v153, v97, vcc
	v_rsq_f32_e32 v97, v97
	v_mov_b32_e32 v52, v103
	v_cvt_f32_f16_e32 v142, v53
	v_cvt_f32_f16_e32 v134, v49
	v_mul_f32_e32 v103, 0x45800000, v97
	v_cvt_f32_f16_e32 v136, v48
	v_mov_b32_e32 v48, v111
	v_mov_b32_e32 v49, v115
	v_mul_f32_e32 v174, v146, v132
	v_mul_f32_e32 v175, v146, v133
	v_cndmask_b32_e32 v132, v97, v103, vcc
	v_cvt_f32_f16_e32 v130, v51
	v_mul_f32_e32 v48, v132, v48
	v_mul_f32_e32 v49, v132, v49
	s_ashr_i32 s0, s45, 12
	v_cvt_f32_f16_e32 v138, v55
	v_mul_f32_e32 v166, v146, v140
	v_mul_f32_e32 v167, v146, v141
	v_mul_f32_e32 v140, v0, v48
	v_mul_f32_e32 v141, v1, v49
	v_mov_b32_e32 v48, v95
	v_mov_b32_e32 v49, v105
	s_ashr_i32 s1, s0, 31
	v_mul_f32_e32 v48, v132, v48
	v_mul_f32_e32 v49, v132, v49
	s_add_u32 s5, s10, s24
	v_mov_b32_e32 v50, v107
	v_mov_b32_e32 v51, v117
	v_mul_f32_e32 v154, v146, v142
	v_mul_f32_e32 v155, v146, v143
	v_mul_f32_e32 v142, v10, v48
	v_mul_f32_e32 v143, v11, v49
	v_mov_b32_e32 v48, v91
	v_mov_b32_e32 v49, v99
	s_addc_u32 s7, s11, s25
	v_mov_b32_e32 v53, v121
	v_mul_f32_e32 v172, v146, v130
	v_mul_f32_e32 v173, v146, v131
	v_mov_b32_e32 v130, v101
	v_mov_b32_e32 v131, v109
	v_mul_f32_e32 v50, v132, v50
	v_mul_f32_e32 v51, v132, v51
	v_mul_f32_e32 v48, v132, v48
	v_mul_f32_e32 v49, v132, v49
	s_add_u32 s6, s5, s0
	v_mov_b32_e32 v55, v125
	v_mul_f32_e32 v164, v146, v138
	v_mul_f32_e32 v165, v146, v139
	v_mul_f32_e32 v168, v146, v134
	v_mul_f32_e32 v169, v146, v135
	v_mul_f32_e32 v130, v132, v130
	v_mul_f32_e32 v131, v132, v131
	v_mul_f32_e32 v138, v8, v50
	v_mul_f32_e32 v139, v9, v51
	v_mul_f32_e32 v50, v132, v52
	v_mul_f32_e32 v51, v132, v53
	v_mul_f32_e32 v134, v14, v48
	v_mul_f32_e32 v135, v15, v49
	v_mov_b32_e32 v48, v89
	v_mov_b32_e32 v49, v93
	s_addc_u32 s7, s7, s1
	v_mul_f32_e32 v162, v146, v144
	v_mul_f32_e32 v163, v146, v145
	v_mul_f32_e32 v144, v2, v130
	v_mul_f32_e32 v145, v3, v131
	v_mul_f32_e32 v130, v12, v50
	v_mul_f32_e32 v131, v13, v51
	v_mul_f32_e32 v48, v132, v48
	v_mul_f32_e32 v49, v132, v49
	v_mul_f32_e32 v50, v132, v54
	v_mul_f32_e32 v51, v132, v55
	s_lshl_b64 s[6:7], s[6:7], 11
	v_mul_f32_e32 v170, v146, v136
	v_mul_f32_e32 v171, v146, v137
	v_mul_f32_e32 v54, v4, v50
	v_mul_f32_e32 v55, v5, v51
	v_mul_f32_e32 v132, v6, v48
	v_mul_f32_e32 v133, v7, v49
	v_cvt_pk_bf16_f32 v50, v140, v141
	v_cvt_pk_bf16_f32 v51, v144, v145
	v_cvt_pk_bf16_f32 v52, v138, v139
	v_cvt_pk_bf16_f32 v53, v142, v143
	v_lshl_add_u64 v[48:49], v[60:61], 0, s[6:7]
	v_fma_f32 v146, v2, v154, -v144
	v_fma_f32 v147, v3, v155, -v145
	global_store_dwordx4 v[48:49], v[50:53], off offset:2048
	v_fma_f32 v154, v8, v166, -v138
	v_fma_f32 v155, v9, v167, -v139
	v_fma_f32 v166, v10, v164, -v142
	v_fma_f32 v167, v11, v165, -v143
	v_fma_f32 v52, v0, v162, -v140
	v_fma_f32 v53, v1, v163, -v141
	v_fma_f32 v50, v18, v146, v144
	v_fma_f32 v51, v19, v147, v145
	v_fma_f32 v136, v16, v52, v140
	v_fma_f32 v137, v17, v53, v141
	v_cvt_pk_bf16_f32 v163, v50, v51
	v_lshl_add_u64 v[50:51], s[18:19], 0, v[56:57]
	v_fma_f32 v176, v26, v166, v142
	v_fma_f32 v177, v27, v167, v143
	v_fma_f32 v164, v24, v154, v138
	v_fma_f32 v165, v25, v155, v139
	v_cvt_pk_bf16_f32 v162, v136, v137
	v_add_co_u32_e32 v136, vcc, s41, v50
	v_cvt_pk_bf16_f32 v164, v164, v165
	v_cvt_pk_bf16_f32 v165, v176, v177
	v_addc_co_u32_e32 v137, vcc, 0, v51, vcc
	v_fma_f32 v52, v32, v52, v140
	v_fma_f32 v53, v33, v53, v141
	global_store_dwordx4 v[136:137], v[162:165], off
	v_fma_f32 v146, v34, v146, v144
	v_fma_f32 v147, v35, v147, v145
	v_fma_f32 v166, v42, v166, v142
	v_fma_f32 v167, v43, v167, v143
	v_cvt_pk_bf16_f32 v162, v52, v53
	v_lshl_add_u64 v[52:53], s[14:15], 0, v[56:57]
	v_fma_f32 v154, v40, v154, v138
	v_fma_f32 v155, v41, v155, v139
	v_cvt_pk_bf16_f32 v163, v146, v147
	v_add_co_u32_e32 v146, vcc, s42, v52
	v_cvt_pk_bf16_f32 v164, v154, v155
	v_cvt_pk_bf16_f32 v165, v166, v167
	v_addc_co_u32_e32 v147, vcc, 0, v53, vcc
	global_store_dwordx4 v[146:147], v[162:165], off
	v_fma_f32 v154, v12, v170, -v130
	v_fma_f32 v155, v13, v171, -v131
	v_fma_f32 v166, v14, v168, -v134
	v_fma_f32 v167, v15, v169, -v135
	v_cvt_pk_bf16_f32 v162, v130, v131
	v_cvt_pk_bf16_f32 v163, v134, v135
	v_cvt_pk_bf16_f32 v164, v54, v55
	v_cvt_pk_bf16_f32 v165, v132, v133
	v_fma_f32 v168, v4, v174, -v54
	v_fma_f32 v169, v5, v175, -v55
	v_fma_f32 v170, v6, v172, -v132
	v_fma_f32 v171, v7, v173, -v133
	global_store_dwordx4 v[48:49], v[162:165], off offset:3072
	v_fma_f32 v172, v22, v170, v132
	v_fma_f32 v173, v23, v171, v133
	v_fma_f32 v174, v20, v168, v54
	v_fma_f32 v175, v21, v169, v55
	v_fma_f32 v164, v30, v166, v134
	v_fma_f32 v165, v31, v167, v135
	v_fma_f32 v162, v28, v154, v130
	v_fma_f32 v163, v29, v155, v131
	v_fma_f32 v154, v44, v154, v130
	v_fma_f32 v155, v45, v155, v131
	v_cvt_pk_bf16_f32 v162, v162, v163
	v_cvt_pk_bf16_f32 v163, v164, v165
	v_cvt_pk_bf16_f32 v164, v174, v175
	v_cvt_pk_bf16_f32 v165, v172, v173
	global_store_dwordx4 v[136:137], v[162:165], off offset:1024
	v_fma_f32 v168, v36, v168, v54
	v_fma_f32 v169, v37, v169, v55
	v_cmp_ne_u32_e32 vcc, 1, v112
	v_fma_f32 v164, v46, v166, v134
	v_fma_f32 v165, v47, v167, v135
	v_fma_f32 v166, v38, v170, v132
	v_fma_f32 v167, v39, v171, v133
	v_cmp_gt_f32_e64 s[2:3], s40, v152
	v_cvt_pk_bf16_f32 v162, v154, v155
	v_cvt_pk_bf16_f32 v163, v164, v165
	v_cvt_pk_bf16_f32 v164, v168, v169
	v_cvt_pk_bf16_f32 v165, v166, v167
	global_store_dwordx4 v[146:147], v[162:165], off offset:1024
	s_cbranch_vccz .LBB0_2411
; #define GAS __attribute__((address_space(1)))
; __device__ __forceinline__ void rmsnorm_rows_rwkv(const bf16_t* x, const float* gain, const float* mu_r, const float* mu_k, bf16_t* H, bf16_t* XR, bf16_t* XK, int gw, int NGW, int lane) {
;     ...
;         for (int r = 0; r <= RB; ++r) {
;             const float rstd = (first && r == 0) ? 0.f : rsqrtf(s[r] * (1.f / D) + 1e-6f);
; #pragma unroll
;             for (int j = 0; j < 2; ++j)
; #pragma unroll
;                 for (int e = 0; e < 2; ++e) v[r][j][e] = v[r][j][e] * rstd * g[j][e];
;         }
; #pragma unroll
;         for (int r = 1; r <= RB; ++r) {
;             const int row = row0 + r - 1;
;             const size_t hrow = (size_t)row + (row >> 12) + 1;
; #pragma unroll
;             for (int j = 0; j < 2; ++j) {
;                 const size_t co = (size_t)512 * j + lane * 8;
;                 *(GAS u32x4*)(H + hrow * D + co) = pack8(v[r][j][0], v[r][j][1]);
;                 const f32x4 d0 = v[r - 1][j][0] - v[r][j][0], d1 = v[r - 1][j][1] - v[r][j][1];
;                 *(GAS u32x4*)(XR + (size_t)row * D + co) = pack8(v[r][j][0] + d0 * mr[j][0], v[r][j][1] + d1 * mr[j][1]);
;                 *(GAS u32x4*)(XK + (size_t)row * D + co) = pack8(v[r][j][0] + d0 * mk[j][0], v[r][j][1] + d1 * mk[j][1]);
.LBB0_2408:
	v_mov_b32_e32 v103, v120
	v_mov_b32_e32 v120, v73
	v_mul_f32_e32 v73, 0x4b800000, v152
	v_cndmask_b32_e64 v73, v152, v73, s[2:3]
	v_rsq_f32_e32 v89, v73
	v_mov_b32_e32 v107, v116
	v_mov_b32_e32 v116, v79
	v_mov_b32_e32 v117, v119
	v_mov_b32_e32 v79, v118
	s_waitcnt lgkmcnt(0)
	v_add_f32_e32 v118, v148, v150
	v_add_f32_e32 v119, v149, v151
	v_mul_f32_e32 v91, 0x45800000, v89
	v_mov_b32_e32 v73, v122
	v_cndmask_b32_e64 v122, v89, v91, s[2:3]
	v_mov_b32_e32 v91, v98
	v_mov_b32_e32 v89, v92
	v_fma_f32 v92, v118, s26, v62
	v_fma_f32 v93, v119, s26, v62
	v_mul_f32_e32 v98, v122, v90
	v_mul_f32_e32 v99, v122, v91
	v_mul_f32_e32 v90, 0x4b800000, v93
	v_cmp_gt_f32_e32 vcc, s40, v93
	v_mov_b32_e32 v95, v104
	v_mul_f32_e32 v118, v122, v88
	v_mul_f32_e32 v119, v122, v89
	v_cndmask_b32_e32 v90, v93, v90, vcc
	v_rsq_f32_e32 v90, v90
	v_mul_f32_e32 v104, v122, v94
	v_mul_f32_e32 v105, v122, v95
	v_mov_b32_e32 v91, v85
	v_mov_b32_e32 v97, v124
	v_mul_f32_e32 v88, 0x45800000, v90
	v_cndmask_b32_e32 v94, v90, v88, vcc
	v_mov_b32_e32 v90, v77
	v_mul_f32_e32 v90, v94, v90
	v_mul_f32_e32 v91, v94, v91
	v_mov_b32_e32 v112, v87
	v_mov_b32_e32 v113, v127
	v_mul_f32_e32 v152, v122, v96
	v_mul_f32_e32 v153, v122, v97
	v_mul_f32_e32 v96, v2, v90
	v_mul_f32_e32 v97, v3, v91
	v_mov_b32_e32 v90, v71
	v_mov_b32_e32 v91, v81
	v_mov_b32_e32 v111, v114
	v_mov_b32_e32 v114, v83
	v_mov_b32_e32 v115, v129
	v_mov_b32_e32 v121, v123
	v_mul_f32_e32 v88, v94, v112
	v_mul_f32_e32 v89, v94, v113
	v_mul_f32_e32 v90, v94, v90
	v_mul_f32_e32 v91, v94, v91
	v_mul_f32_e32 v112, v0, v88
	v_mul_f32_e32 v113, v1, v89
	v_mul_f32_e32 v88, v94, v114
	v_mul_f32_e32 v89, v94, v115
	v_mul_f32_e32 v114, v10, v90
	v_mul_f32_e32 v115, v11, v91
	v_mul_f32_e32 v90, v94, v116
	v_mul_f32_e32 v91, v94, v117
	v_mul_f32_e32 v116, v94, v120
	v_mul_f32_e32 v117, v94, v121
	v_mov_b32_e32 v120, v65
	v_mul_f32_e32 v65, 0x4b800000, v92
	v_cmp_gt_f32_e32 vcc, s40, v92
	v_mov_b32_e32 v101, v108
	v_mul_f32_e32 v110, v122, v110
	v_mul_f32_e32 v111, v122, v111
	v_cndmask_b32_e32 v65, v92, v65, vcc
	v_rsq_f32_e32 v65, v65
	v_mul_f32_e32 v100, v122, v100
	v_mul_f32_e32 v101, v122, v101
	v_mul_f32_e32 v106, v122, v106
	v_mul_f32_e32 v107, v122, v107
	v_mul_f32_e32 v162, v8, v88
	v_mul_f32_e32 v163, v9, v89
	v_mov_b32_e32 v88, v67
	v_mov_b32_e32 v89, v75
	v_mov_b32_e32 v121, v69
	v_mul_f32_e32 v67, 0x45800000, v65
	v_mov_b32_e32 v87, v126
	v_mov_b32_e32 v83, v128
	v_mul_f32_e32 v108, v2, v100
	v_mul_f32_e32 v109, v3, v101
	v_mul_f32_e32 v124, v0, v110
	v_mul_f32_e32 v125, v1, v111
	v_mul_f32_e32 v126, v10, v104
	v_mul_f32_e32 v127, v11, v105
	v_mul_f32_e32 v128, v8, v106
	v_mul_f32_e32 v129, v9, v107
	v_mul_f32_e32 v88, v94, v88
	v_mul_f32_e32 v89, v94, v89
	v_mul_f32_e32 v92, v94, v120
	v_mul_f32_e32 v93, v94, v121
	v_mul_f32_e32 v94, v4, v116
	v_mul_f32_e32 v95, v5, v117
	v_cndmask_b32_e32 v116, v65, v67, vcc
	v_xor_b32_e32 v175, 0x80000000, v3
	v_xor_b32_e32 v174, 0x80000000, v2
	v_xor_b32_e32 v177, 0x80000000, v11
	v_xor_b32_e32 v176, 0x80000000, v10
	v_mov_b32_e32 v67, v74
	v_mul_f32_e32 v170, v116, v72
	v_mul_f32_e32 v171, v116, v73
	v_cvt_pk_bf16_f32 v72, v124, v125
	v_cvt_pk_bf16_f32 v73, v108, v109
	v_cvt_pk_bf16_f32 v74, v128, v129
	v_cvt_pk_bf16_f32 v75, v126, v127
	v_lshl_add_u64 v[172:173], v[48:49], 0, s[28:29]
	v_fma_f32 v144, v174, v100, v144
	v_fma_f32 v145, v175, v101, v145
	v_fma_f32 v140, -v0, v110, v140
	v_fma_f32 v141, -v1, v111, v141
	v_fma_f32 v142, v176, v104, v142
	v_fma_f32 v143, v177, v105, v143
	v_fma_f32 v138, -v8, v106, v138
	v_fma_f32 v139, -v9, v107, v139
	global_store_dwordx4 v[172:173], v[72:75], off offset:2048
	v_fma_f32 v178, v26, v142, v126
	v_fma_f32 v179, v27, v143, v127
	v_fma_f32 v180, v24, v138, v128
	v_fma_f32 v181, v25, v139, v129
	v_fma_f32 v74, v18, v144, v108
	v_fma_f32 v75, v19, v145, v109
	v_fma_f32 v72, v16, v140, v124
	v_fma_f32 v73, v17, v141, v125
	v_mul_f32_e32 v102, v122, v102
	v_mul_f32_e32 v103, v122, v103
	v_cvt_pk_bf16_f32 v72, v72, v73
	v_cvt_pk_bf16_f32 v73, v74, v75
	v_cvt_pk_bf16_f32 v74, v180, v181
	v_cvt_pk_bf16_f32 v75, v178, v179
	global_store_dwordx4 v[136:137], v[72:75], off offset:2048
	v_mul_f32_e32 v148, v14, v98
	v_mul_f32_e32 v149, v15, v99
	v_mul_f32_e32 v150, v12, v102
	v_mul_f32_e32 v151, v13, v103
	v_fma_f32 v74, v34, v144, v108
	v_fma_f32 v75, v35, v145, v109
	v_fma_f32 v72, v32, v140, v124
	v_fma_f32 v73, v33, v141, v125
	v_fma_f32 v108, v42, v142, v126
	v_fma_f32 v109, v43, v143, v127
	v_fma_f32 v124, v40, v138, v128
	v_fma_f32 v125, v41, v139, v129
	v_mul_f32_e32 v122, v6, v118
	v_mul_f32_e32 v123, v7, v119
	v_mul_f32_e32 v154, v4, v152
	v_mul_f32_e32 v155, v5, v153
	v_cvt_pk_bf16_f32 v72, v72, v73
	v_cvt_pk_bf16_f32 v73, v74, v75
	v_cvt_pk_bf16_f32 v74, v124, v125
	v_cvt_pk_bf16_f32 v75, v108, v109
	v_xor_b32_e32 v109, 0x80000000, v15
	v_xor_b32_e32 v108, 0x80000000, v14
	v_xor_b32_e32 v129, 0x80000000, v7
	v_xor_b32_e32 v128, 0x80000000, v6
	global_store_dwordx4 v[146:147], v[72:75], off offset:2048
	v_fma_f32 v124, v108, v98, v134
	v_fma_f32 v125, v109, v99, v135
	v_fma_f32 v126, -v12, v102, v130
	v_fma_f32 v127, -v13, v103, v131
	v_cvt_pk_bf16_f32 v72, v150, v151
	v_cvt_pk_bf16_f32 v73, v148, v149
	v_cvt_pk_bf16_f32 v74, v154, v155
	v_cvt_pk_bf16_f32 v75, v122, v123
	v_fma_f32 v130, v128, v118, v132
	v_fma_f32 v131, v129, v119, v133
	v_fma_f32 v54, -v4, v152, v54
	v_fma_f32 v55, -v5, v153, v55
	global_store_dwordx4 v[172:173], v[72:75], off offset:3072
	v_fma_f32 v132, v22, v130, v122
	v_fma_f32 v133, v23, v131, v123
	v_fma_f32 v134, v20, v54, v154
	v_fma_f32 v135, v21, v55, v155
	v_fma_f32 v74, v30, v124, v148
; #define GAS __attribute__((address_space(1)))
; __device__ __forceinline__ void rmsnorm_rows_rwkv(const bf16_t* x, const float* gain, const float* mu_r, const float* mu_k, bf16_t* H, bf16_t* XR, bf16_t* XK, int gw, int NGW, int lane) {
;     ...
;         for (int r = 0; r <= RB; ++r) {
;             const float rstd = (first && r == 0) ? 0.f : rsqrtf(s[r] * (1.f / D) + 1e-6f);
; #pragma unroll
;             for (int j = 0; j < 2; ++j)
; #pragma unroll
;                 for (int e = 0; e < 2; ++e) v[r][j][e] = v[r][j][e] * rstd * g[j][e];
;         }
; #pragma unroll
;         for (int r = 1; r <= RB; ++r) {
;             const int row = row0 + r - 1;
;             const size_t hrow = (size_t)row + (row >> 12) + 1;
; #pragma unroll
;             for (int j = 0; j < 2; ++j) {
;                 const size_t co = (size_t)512 * j + lane * 8;
;                 *(GAS u32x4*)(H + hrow * D + co) = pack8(v[r][j][0], v[r][j][1]);
;                 const f32x4 d0 = v[r - 1][j][0] - v[r][j][0], d1 = v[r - 1][j][1] - v[r][j][1];
;                 *(GAS u32x4*)(XR + (size_t)row * D + co) = pack8(v[r][j][0] + d0 * mr[j][0], v[r][j][1] + d1 * mr[j][1]);
;                 *(GAS u32x4*)(XK + (size_t)row * D + co) = pack8(v[r][j][0] + d0 * mk[j][0], v[r][j][1] + d1 * mk[j][1]);
	v_fma_f32 v75, v31, v125, v149
	v_fma_f32 v72, v28, v126, v150
	v_fma_f32 v73, v29, v127, v151
	v_fma_f32 v122, v38, v130, v122
	v_fma_f32 v123, v39, v131, v123
	v_cvt_pk_bf16_f32 v72, v72, v73
	v_cvt_pk_bf16_f32 v73, v74, v75
	v_cvt_pk_bf16_f32 v74, v134, v135
	v_cvt_pk_bf16_f32 v75, v132, v133
	global_store_dwordx4 v[136:137], v[72:75], off offset:3072
	v_fma_f32 v54, v36, v54, v154
	v_fma_f32 v55, v37, v55, v155
	v_fma_f32 v110, v0, v110, -v112
	v_fma_f32 v111, v1, v111, -v113
	v_fma_f32 v74, v46, v124, v148
	v_fma_f32 v75, v47, v125, v149
	v_fma_f32 v72, v44, v126, v150
	v_fma_f32 v73, v45, v127, v151
	v_fma_f32 v100, v2, v100, -v96
	v_fma_f32 v101, v3, v101, -v97
	v_cvt_pk_bf16_f32 v72, v72, v73
	v_cvt_pk_bf16_f32 v73, v74, v75
	v_cvt_pk_bf16_f32 v74, v54, v55
	v_cvt_pk_bf16_f32 v75, v122, v123
	global_store_dwordx4 v[146:147], v[72:75], off offset:3072
	v_lshl_add_u64 v[54:55], v[48:49], 0, s[30:31]
	v_fma_f32 v104, v10, v104, -v114
	v_fma_f32 v105, v11, v105, -v115
	v_cvt_pk_bf16_f32 v72, v112, v113
	v_cvt_pk_bf16_f32 v73, v96, v97
	v_cvt_pk_bf16_f32 v74, v162, v163
	v_cvt_pk_bf16_f32 v75, v114, v115
	global_store_dwordx4 v[54:55], v[72:75], off offset:2048
	v_fma_f32 v106, v8, v106, -v162
	v_fma_f32 v107, v9, v107, -v163
	v_fma_f32 v122, v26, v104, v114
	v_fma_f32 v123, v27, v105, v115
	v_fma_f32 v74, v18, v100, v96
	v_fma_f32 v75, v19, v101, v97
	v_fma_f32 v72, v16, v110, v112
	v_fma_f32 v73, v17, v111, v113
	v_fma_f32 v124, v24, v106, v162
	v_fma_f32 v125, v25, v107, v163
	v_cvt_pk_bf16_f32 v72, v72, v73
	v_cvt_pk_bf16_f32 v73, v74, v75
	v_cvt_pk_bf16_f32 v75, v122, v123
	v_add_co_u32_e32 v122, vcc, s43, v50
	v_cvt_pk_bf16_f32 v74, v124, v125
	s_nop 0
	v_addc_co_u32_e32 v123, vcc, 0, v51, vcc
	global_store_dwordx4 v[122:123], v[72:75], off
	v_fma_f32 v50, v34, v100, v96
	v_fma_f32 v51, v35, v101, v97
	v_fma_f32 v100, v42, v104, v114
	v_fma_f32 v101, v43, v105, v115
	v_fma_f32 v74, v40, v106, v162
	v_fma_f32 v75, v41, v107, v163
	v_mul_f32_e32 v88, v14, v88
	v_mul_f32_e32 v89, v15, v89
	v_mul_f32_e32 v90, v12, v90
	v_mul_f32_e32 v91, v13, v91
	v_mul_f32_e32 v92, v6, v92
	v_mul_f32_e32 v93, v7, v93
	v_fma_f32 v72, v32, v110, v112
	v_fma_f32 v73, v33, v111, v113
	v_cvt_pk_bf16_f32 v74, v74, v75
	v_cvt_pk_bf16_f32 v75, v100, v101
	v_add_co_u32_e32 v100, vcc, s44, v52
	v_cvt_pk_bf16_f32 v72, v72, v73
	v_cvt_pk_bf16_f32 v73, v50, v51
	v_addc_co_u32_e32 v101, vcc, 0, v53, vcc
	v_cvt_pk_bf16_f32 v50, v90, v91
	v_cvt_pk_bf16_f32 v51, v88, v89
	v_cvt_pk_bf16_f32 v52, v94, v95
	v_cvt_pk_bf16_f32 v53, v92, v93
	global_store_dwordx4 v[100:101], v[72:75], off
	global_store_dwordx4 v[54:55], v[50:53], off offset:3072
	v_fma_f32 v54, v12, v102, -v90
	v_fma_f32 v55, v13, v103, -v91
	v_fma_f32 v72, v14, v98, -v88
	v_fma_f32 v73, v15, v99, -v89
	v_fma_f32 v74, v4, v152, -v94
	v_fma_f32 v75, v5, v153, -v95
	v_fma_f32 v98, v6, v118, -v92
	v_fma_f32 v99, v7, v119, -v93
	v_fma_f32 v52, v30, v72, v88
	v_fma_f32 v53, v31, v73, v89
	v_fma_f32 v50, v28, v54, v90
	v_fma_f32 v51, v29, v55, v91
	v_fma_f32 v102, v22, v98, v92
	v_fma_f32 v103, v23, v99, v93
	v_fma_f32 v104, v20, v74, v94
	v_fma_f32 v105, v21, v75, v95
	v_mov_b32_e32 v77, v84
	v_mov_b32_e32 v71, v80
	v_cvt_pk_bf16_f32 v50, v50, v51
	v_cvt_pk_bf16_f32 v51, v52, v53
	v_cvt_pk_bf16_f32 v52, v104, v105
	v_cvt_pk_bf16_f32 v53, v102, v103
	v_mul_f32_e32 v86, v116, v86
	v_mul_f32_e32 v87, v116, v87
	v_mul_f32_e32 v76, v116, v76
	v_mul_f32_e32 v77, v116, v77
	v_mul_f32_e32 v82, v116, v82
	v_mul_f32_e32 v83, v116, v83
	v_mul_f32_e32 v80, v116, v70
	v_mul_f32_e32 v81, v116, v71
	global_store_dwordx4 v[122:123], v[50:53], off offset:1024
	v_mul_f32_e32 v84, v2, v76
	v_mul_f32_e32 v85, v3, v77
	v_mul_f32_e32 v120, v0, v86
	v_mul_f32_e32 v121, v1, v87
	v_fma_f32 v52, v46, v72, v88
	v_fma_f32 v53, v47, v73, v89
	v_fma_f32 v50, v44, v54, v90
	v_fma_f32 v51, v45, v55, v91
	v_fma_f32 v54, v38, v98, v92
	v_fma_f32 v55, v39, v99, v93
	v_fma_f32 v72, v36, v74, v94
	v_fma_f32 v73, v37, v75, v95
	v_mul_f32_e32 v164, v10, v80
	v_mul_f32_e32 v165, v11, v81
	v_mul_f32_e32 v166, v8, v82
	v_mul_f32_e32 v167, v9, v83
	v_cvt_pk_bf16_f32 v50, v50, v51
	v_cvt_pk_bf16_f32 v51, v52, v53
	v_cvt_pk_bf16_f32 v52, v72, v73
	v_cvt_pk_bf16_f32 v53, v54, v55
	global_store_dwordx4 v[100:101], v[50:53], off offset:1024
	v_lshl_add_u64 v[54:55], v[48:49], 0, s[34:35]
	v_fma_f32 v72, v174, v76, v96
	v_fma_f32 v73, v175, v77, v97
	v_cvt_pk_bf16_f32 v50, v120, v121
	v_cvt_pk_bf16_f32 v51, v84, v85
	v_cvt_pk_bf16_f32 v52, v166, v167
	v_cvt_pk_bf16_f32 v53, v164, v165
	global_store_dwordx4 v[54:55], v[50:53], off offset:2048
	v_fma_f32 v74, -v8, v82, v162
	v_fma_f32 v75, -v9, v83, v163
	v_fma_f32 v76, v176, v80, v114
	v_fma_f32 v77, v177, v81, v115
	v_fma_f32 v52, -v0, v86, v112
	v_fma_f32 v53, -v1, v87, v113
	v_fma_f32 v50, v18, v72, v84
	v_fma_f32 v51, v19, v73, v85
	v_fma_f32 v48, v16, v52, v120
	v_fma_f32 v49, v17, v53, v121
	v_fma_f32 v80, v26, v76, v164
	v_fma_f32 v81, v27, v77, v165
	v_fma_f32 v82, v24, v74, v166
	v_fma_f32 v83, v25, v75, v167
	s_add_i32 s45, s45, s12
	v_mov_b32_e32 v65, v68
	v_cvt_pk_bf16_f32 v48, v48, v49
	v_cvt_pk_bf16_f32 v49, v50, v51
	v_cvt_pk_bf16_f32 v50, v82, v83
	v_cvt_pk_bf16_f32 v51, v80, v81
	s_add_u32 s14, s14, s16
	v_mul_f32_e32 v78, v116, v78
	v_mul_f32_e32 v79, v116, v79
	v_mul_f32_e32 v168, v116, v66
	v_mul_f32_e32 v169, v116, v67
	v_mul_f32_e32 v117, v116, v65
	v_mul_f32_e32 v116, v116, v64
	global_store_dwordx4 v[122:123], v[48:51], off offset:2048
	s_addc_u32 s15, s15, s17
	v_mul_f32_e32 v66, v14, v168
	v_mul_f32_e32 v67, v15, v169
	v_fma_f32 v50, v34, v72, v84
	v_fma_f32 v51, v35, v73, v85
; #define GAS __attribute__((address_space(1)))
; __device__ __forceinline__ void rmsnorm_rows_rwkv(const bf16_t* x, const float* gain, const float* mu_r, const float* mu_k, bf16_t* H, bf16_t* XR, bf16_t* XK, int gw, int NGW, int lane) {
;     ...
;     for (int row0 = gw * RB; row0 < T; row0 += NGW * RB) {
;         const bool first = (row0 & 4095) == 0;
;         f32x4 v[RB + 1][2][2]; float s[RB + 1];
; #pragma unroll
;         for (int r = 0; r <= RB; ++r)
; #pragma unroll
;             for (int j = 0; j < 2; ++j) unpack8h(*(const GAS u32x4*)(x + (size_t)(row0 - 1 + r + (first && r == 0 ? 1 : 0)) * D + 512 * j + lane * 8), v[r][j][0], v[r][j][1]);
;     ...
;         }
; #pragma unroll
;         for (int r = 1; r <= RB; ++r) {
;             const int row = row0 + r - 1;
;             const size_t hrow = (size_t)row + (row >> 12) + 1;
; #pragma unroll
;             for (int j = 0; j < 2; ++j) {
;                 const size_t co = (size_t)512 * j + lane * 8;
;                 *(GAS u32x4*)(H + hrow * D + co) = pack8(v[r][j][0], v[r][j][1]);
;                 const f32x4 d0 = v[r - 1][j][0] - v[r][j][0], d1 = v[r - 1][j][1] - v[r][j][1];
;                 *(GAS u32x4*)(XR + (size_t)row * D + co) = pack8(v[r][j][0] + d0 * mr[j][0], v[r][j][1] + d1 * mr[j][1]);
;                 *(GAS u32x4*)(XK + (size_t)row * D + co) = pack8(v[r][j][0] + d0 * mk[j][0], v[r][j][1] + d1 * mk[j][1]);
	v_fma_f32 v48, v32, v52, v120
	v_fma_f32 v49, v33, v53, v121
	v_fma_f32 v52, v42, v76, v164
	v_fma_f32 v53, v43, v77, v165
	v_fma_f32 v72, v40, v74, v166
	v_fma_f32 v73, v41, v75, v167
	v_mul_f32_e32 v70, v12, v78
	v_mul_f32_e32 v71, v13, v79
	v_mul_f32_e32 v64, v6, v116
	v_mul_f32_e32 v65, v7, v117
	v_mul_f32_e32 v68, v4, v170
	v_mul_f32_e32 v69, v5, v171
	v_cvt_pk_bf16_f32 v48, v48, v49
	v_cvt_pk_bf16_f32 v49, v50, v51
	v_cvt_pk_bf16_f32 v50, v72, v73
	v_cvt_pk_bf16_f32 v51, v52, v53
	s_add_u32 s18, s18, s16
	global_store_dwordx4 v[100:101], v[48:51], off offset:2048
	s_addc_u32 s19, s19, s17
	v_fma_f32 v52, -v12, v78, v90
	v_fma_f32 v53, -v13, v79, v91
	v_cvt_pk_bf16_f32 v48, v70, v71
	v_cvt_pk_bf16_f32 v49, v66, v67
	v_cvt_pk_bf16_f32 v50, v68, v69
	v_cvt_pk_bf16_f32 v51, v64, v65
	global_store_dwordx4 v[54:55], v[48:51], off offset:3072
	v_fma_f32 v54, v108, v168, v88
	v_fma_f32 v55, v109, v169, v89
	v_fma_f32 v72, -v4, v170, v94
	v_fma_f32 v73, -v5, v171, v95
	v_fma_f32 v74, v128, v116, v92
	v_fma_f32 v75, v129, v117, v93
	s_add_u32 s24, s24, s12
	v_fma_f32 v50, v30, v54, v66
	v_fma_f32 v51, v31, v55, v67
	v_fma_f32 v48, v28, v52, v70
	v_fma_f32 v49, v29, v53, v71
	v_fma_f32 v76, v22, v74, v64
	v_fma_f32 v77, v23, v75, v65
	v_fma_f32 v78, v20, v72, v68
	v_fma_f32 v79, v21, v73, v69
	s_addc_u32 s25, s25, s13
	v_cvt_pk_bf16_f32 v48, v48, v49
	v_cvt_pk_bf16_f32 v49, v50, v51
	v_cvt_pk_bf16_f32 v50, v78, v79
	v_cvt_pk_bf16_f32 v51, v76, v77
	s_add_u32 s20, s20, s16
	global_store_dwordx4 v[122:123], v[48:51], off offset:3072
	s_addc_u32 s21, s21, s17
	s_cmp_lt_i32 s45, 0x8000
	v_fma_f32 v50, v46, v54, v66
	v_fma_f32 v51, v47, v55, v67
	v_fma_f32 v48, v44, v52, v70
	v_fma_f32 v49, v45, v53, v71
	v_fma_f32 v52, v38, v74, v64
	v_fma_f32 v53, v39, v75, v65
	v_fma_f32 v54, v36, v72, v68
	v_fma_f32 v55, v37, v73, v69
	v_cvt_pk_bf16_f32 v48, v48, v49
	v_cvt_pk_bf16_f32 v49, v50, v51
	v_cvt_pk_bf16_f32 v50, v54, v55
	v_cvt_pk_bf16_f32 v51, v52, v53
	global_store_dwordx4 v[100:101], v[48:51], off offset:3072
	s_cbranch_scc0 .LBB0_2412
.LBB0_2409:
	s_nop 0
	v_lshl_add_u64 v[48:49], s[20:21], 0, v[56:57]
	v_add_co_u32_e32 v80, vcc, s39, v48
	s_and_b32 s0, s45, 0xffc
	s_nop 0
	v_addc_co_u32_e32 v81, vcc, 0, v49, vcc
	s_cmp_eq_u32 s0, 0
	v_add_co_u32_e32 v48, vcc, s38, v48
	s_cselect_b64 s[2:3], -1, 0
	s_add_u32 s6, s27, s24
	v_addc_co_u32_e32 v49, vcc, 0, v49, vcc
	v_mov_b32_e32 v113, s4
	v_cndmask_b32_e64 v112, 0, 1, s[2:3]
	s_addc_u32 s7, s23, s25
	global_load_dwordx4 v[64:67], v[80:81], off offset:-4096
	global_load_dwordx4 v[68:71], v[48:49], off offset:1024
	global_load_dwordx4 v[72:75], v[48:49], off offset:2048
	global_load_dwordx4 v[76:79], v[48:49], off offset:3072
	global_load_dwordx4 v[126:129], v[80:81], off
	v_lshl_add_u64 v[48:49], s[6:7], 0, v[112:113]
	global_load_dwordx4 v[130:133], v[80:81], off offset:1024
	global_load_dwordx4 v[144:147], v[80:81], off offset:2048
	v_lshlrev_b64 v[48:49], 11, v[48:49]
	v_lshl_add_u64 v[82:83], v[58:59], 0, v[48:49]
	global_load_dwordx4 v[52:55], v[82:83], off
	global_load_dwordx4 v[48:51], v[82:83], off offset:1024
	global_load_dwordx4 v[148:151], v[80:81], off offset:3072
	s_and_b64 vcc, exec, s[2:3]
	s_waitcnt vmcnt(8)
	v_cvt_f32_f16_sdwa v99, v69 dst_sel:DWORD dst_unused:UNUSED_PAD src0_sel:WORD_1
	s_waitcnt vmcnt(7)
	v_cvt_f32_f16_sdwa v108, v73 dst_sel:DWORD dst_unused:UNUSED_PAD src0_sel:WORD_1
	v_cvt_f32_f16_sdwa v109, v65 dst_sel:DWORD dst_unused:UNUSED_PAD src0_sel:WORD_1
	v_cvt_f32_f16_sdwa v115, v64 dst_sel:DWORD dst_unused:UNUSED_PAD src0_sel:WORD_1
	v_cvt_f32_f16_sdwa v114, v72 dst_sel:DWORD dst_unused:UNUSED_PAD src0_sel:WORD_1
	s_waitcnt vmcnt(6)
	v_cvt_f32_f16_e32 v102, v76
	v_cvt_f32_f16_sdwa v120, v76 dst_sel:DWORD dst_unused:UNUSED_PAD src0_sel:WORD_1
	s_waitcnt vmcnt(3)
	v_cvt_f32_f16_e32 v76, v145
	v_cvt_f32_f16_sdwa v84, v145 dst_sel:DWORD dst_unused:UNUSED_PAD src0_sel:WORD_1
	s_waitcnt vmcnt(2)
	v_cvt_f32_f16_sdwa v143, v53 dst_sel:DWORD dst_unused:UNUSED_PAD src0_sel:WORD_1
	v_cvt_f32_f16_sdwa v145, v52 dst_sel:DWORD dst_unused:UNUSED_PAD src0_sel:WORD_1
	v_cvt_f32_f16_e32 v101, v65
	v_cvt_f32_f16_e32 v111, v64
	v_cvt_f32_f16_e32 v100, v73
	v_cvt_f32_f16_e32 v110, v72
	v_cvt_f32_f16_sdwa v105, v67 dst_sel:DWORD dst_unused:UNUSED_PAD src0_sel:WORD_1
	v_cvt_f32_f16_sdwa v117, v66 dst_sel:DWORD dst_unused:UNUSED_PAD src0_sel:WORD_1
	v_cvt_f32_f16_sdwa v104, v75 dst_sel:DWORD dst_unused:UNUSED_PAD src0_sel:WORD_1
	v_cvt_f32_f16_sdwa v116, v74 dst_sel:DWORD dst_unused:UNUSED_PAD src0_sel:WORD_1
	v_cvt_f32_f16_e32 v90, v77
	v_cvt_f32_f16_sdwa v98, v77 dst_sel:DWORD dst_unused:UNUSED_PAD src0_sel:WORD_1
	v_cvt_f32_f16_e32 v77, v127
	v_cvt_f32_f16_e32 v87, v126
	v_cvt_f32_f16_sdwa v85, v127 dst_sel:DWORD dst_unused:UNUSED_PAD src0_sel:WORD_1
	v_cvt_f32_f16_sdwa v127, v126 dst_sel:DWORD dst_unused:UNUSED_PAD src0_sel:WORD_1
	v_cvt_f32_f16_sdwa v139, v55 dst_sel:DWORD dst_unused:UNUSED_PAD src0_sel:WORD_1
	v_cvt_f32_f16_sdwa v141, v54 dst_sel:DWORD dst_unused:UNUSED_PAD src0_sel:WORD_1
	v_cvt_f32_f16_sdwa v126, v144 dst_sel:DWORD dst_unused:UNUSED_PAD src0_sel:WORD_1
	v_cvt_f32_f16_e32 v95, v67
	v_cvt_f32_f16_e32 v107, v66
	v_cvt_f32_f16_e32 v94, v75
	v_cvt_f32_f16_e32 v106, v74
	v_cvt_f32_f16_e32 v86, v144
	v_cvt_f32_f16_sdwa v121, v68 dst_sel:DWORD dst_unused:UNUSED_PAD src0_sel:WORD_1
	v_cvt_f32_f16_e32 v89, v71
	v_cvt_f32_f16_e32 v97, v70
	v_cvt_f32_f16_sdwa v93, v71 dst_sel:DWORD dst_unused:UNUSED_PAD src0_sel:WORD_1
	v_cvt_f32_f16_sdwa v125, v70 dst_sel:DWORD dst_unused:UNUSED_PAD src0_sel:WORD_1
	v_cvt_f32_f16_e32 v88, v79
	v_cvt_f32_f16_e32 v96, v78
	v_cvt_f32_f16_sdwa v92, v79 dst_sel:DWORD dst_unused:UNUSED_PAD src0_sel:WORD_1
	v_cvt_f32_f16_sdwa v124, v78 dst_sel:DWORD dst_unused:UNUSED_PAD src0_sel:WORD_1
	v_cvt_f32_f16_e32 v71, v129
	v_cvt_f32_f16_e32 v83, v128
	v_cvt_f32_f16_sdwa v81, v129 dst_sel:DWORD dst_unused:UNUSED_PAD src0_sel:WORD_1
	v_cvt_f32_f16_sdwa v129, v128 dst_sel:DWORD dst_unused:UNUSED_PAD src0_sel:WORD_1
	v_cvt_f32_f16_e32 v79, v130
	v_cvt_f32_f16_sdwa v119, v130 dst_sel:DWORD dst_unused:UNUSED_PAD src0_sel:WORD_1
	v_cvt_f32_f16_e32 v70, v147
	v_cvt_f32_f16_e32 v82, v146
	v_cvt_f32_f16_sdwa v80, v147 dst_sel:DWORD dst_unused:UNUSED_PAD src0_sel:WORD_1
	v_cvt_f32_f16_sdwa v128, v146 dst_sel:DWORD dst_unused:UNUSED_PAD src0_sel:WORD_1
	s_waitcnt vmcnt(0)
; #define GAS __attribute__((address_space(1)))
; template <int MODE, bool XBF>
; __device__ __forceinline__ void rmsnorm_rows(const void* x, const float* gain, bf16_t* H, int gw, int NGW, int lane, const LAS float* WF, const float* fbias, float* LF) {
;     ...
;             for (int j = 0; j < 2; ++j) { const size_t xo = (size_t)(row0 + r) * D + 512 * j + lane * 8;
;                 if (XBF) unpack8h(*(const GAS u32x4*)((const bf16_t*)x + xo), v[r][j][0], v[r][j][1]);
;                 else { v[r][j][0] = *(const GAS f32x4*)((const float*)x + xo); v[r][j][1] = *(const GAS f32x4*)((const float*)x + xo + 4); } }
; #pragma unroll
;         for (int r = 0; r < RB; ++r) { s[r] = 0.f;
; #pragma unroll
;             for (int j = 0; j < 2; ++j)
; #pragma unroll
;                 for (int e = 0; e < 2; ++e) s[r] += (v[r][j][e][0] * v[r][j][e][0] + v[r][j][e][1] * v[r][j][e][1]) + (v[r][j][e][2] * v[r][j][e][2] + v[r][j][e][3] * v[r][j][e][3]); }
; #pragma unroll
;         for (int o = 1; o < 64; o <<= 1)
; #pragma unroll
;             for (int r = 0; r < RB; ++r) s[r] += __shfl_xor(s[r], o);
	v_cvt_f32_f16_e32 v66, v149
	v_cvt_f32_f16_e32 v78, v148
	v_cvt_f32_f16_sdwa v74, v149 dst_sel:DWORD dst_unused:UNUSED_PAD src0_sel:WORD_1
	v_cvt_f32_f16_sdwa v118, v148 dst_sel:DWORD dst_unused:UNUSED_PAD src0_sel:WORD_1
	v_mul_f32_e32 v113, v145, v145
	v_mul_f32_e32 v130, v143, v143
	v_mul_f32_e32 v146, v114, v114
	v_mul_f32_e32 v147, v115, v115
	v_mul_f32_e32 v148, v108, v108
	v_mul_f32_e32 v149, v109, v109
	v_cvt_f32_f16_e32 v91, v69
	v_cvt_f32_f16_e32 v103, v68
	v_cvt_f32_f16_sdwa v135, v49 dst_sel:DWORD dst_unused:UNUSED_PAD src0_sel:WORD_1
	v_cvt_f32_f16_sdwa v137, v48 dst_sel:DWORD dst_unused:UNUSED_PAD src0_sel:WORD_1
	v_fma_mix_f32 v113, v52, v52, v113 op_sel_hi:[1,1,0]
	v_fma_mix_f32 v130, v53, v53, v130 op_sel_hi:[1,1,0]
	v_fma_f32 v146, v110, v110, v146
	v_fma_f32 v147, v111, v111, v147
	v_fma_f32 v148, v100, v100, v148
	v_fma_f32 v149, v101, v101, v149
	v_cvt_f32_f16_sdwa v75, v131 dst_sel:DWORD dst_unused:UNUSED_PAD src0_sel:WORD_1
	v_cvt_f32_f16_e32 v73, v132
	v_cvt_f32_f16_sdwa v123, v132 dst_sel:DWORD dst_unused:UNUSED_PAD src0_sel:WORD_1
	v_cvt_f32_f16_e32 v64, v151
	v_cvt_f32_f16_e32 v72, v150
	v_cvt_f32_f16_sdwa v68, v151 dst_sel:DWORD dst_unused:UNUSED_PAD src0_sel:WORD_1
	v_cvt_f32_f16_sdwa v122, v150 dst_sel:DWORD dst_unused:UNUSED_PAD src0_sel:WORD_1
	v_add_f32_e32 v113, v113, v130
	v_mul_f32_e32 v130, v141, v141
	v_mul_f32_e32 v132, v139, v139
	v_add_f32_e32 v146, v146, v148
	v_add_f32_e32 v147, v147, v149
	v_mul_f32_e32 v148, v116, v116
	v_mul_f32_e32 v149, v117, v117
	v_mul_f32_e32 v150, v104, v104
	v_mul_f32_e32 v151, v105, v105
	v_mul_f32_e32 v164, v126, v126
	v_mul_f32_e32 v165, v127, v127
	v_mul_f32_e32 v166, v84, v84
	v_mul_f32_e32 v167, v85, v85
	v_cvt_f32_f16_e32 v67, v131
	v_fma_mix_f32 v130, v54, v54, v130 op_sel_hi:[1,1,0]
	v_fma_mix_f32 v132, v55, v55, v132 op_sel_hi:[1,1,0]
	v_fma_f32 v148, v106, v106, v148
	v_fma_f32 v149, v107, v107, v149
	v_fma_f32 v150, v94, v94, v150
	v_fma_f32 v151, v95, v95, v151
	v_fma_f32 v164, v86, v86, v164
	v_fma_f32 v165, v87, v87, v165
	v_fma_f32 v166, v76, v76, v166
	v_fma_f32 v167, v77, v77, v167
	v_cvt_f32_f16_e32 v65, v133
	v_cvt_f32_f16_sdwa v69, v133 dst_sel:DWORD dst_unused:UNUSED_PAD src0_sel:WORD_1
	v_cvt_f32_f16_sdwa v131, v51 dst_sel:DWORD dst_unused:UNUSED_PAD src0_sel:WORD_1
	v_cvt_f32_f16_sdwa v133, v50 dst_sel:DWORD dst_unused:UNUSED_PAD src0_sel:WORD_1
	v_add_f32_e32 v130, v130, v132
	v_add_f32_e32 v148, v148, v150
	v_add_f32_e32 v149, v149, v151
	v_mul_f32_e32 v150, v120, v120
	v_mul_f32_e32 v151, v121, v121
	v_mul_f32_e32 v152, v98, v98
	v_mul_f32_e32 v153, v99, v99
	v_add_f32_e32 v164, v164, v166
	v_add_f32_e32 v165, v165, v167
	v_mul_f32_e32 v166, v128, v128
	v_mul_f32_e32 v167, v129, v129
	v_mul_f32_e32 v168, v80, v80
	v_mul_f32_e32 v169, v81, v81
	v_add_f32_e32 v113, v113, v130
	v_mul_f32_e32 v130, v137, v137
	v_mul_f32_e32 v132, v135, v135
	v_fma_f32 v150, v102, v102, v150
	v_fma_f32 v151, v103, v103, v151
	v_fma_f32 v152, v90, v90, v152
	v_fma_f32 v153, v91, v91, v153
	v_fma_f32 v166, v82, v82, v166
	v_fma_f32 v167, v83, v83, v167
	v_fma_f32 v168, v70, v70, v168
	v_fma_f32 v169, v71, v71, v169
	v_fma_mix_f32 v130, v48, v48, v130 op_sel_hi:[1,1,0]
	v_fma_mix_f32 v132, v49, v49, v132 op_sel_hi:[1,1,0]
	v_mul_f32_e32 v154, v124, v124
	v_mul_f32_e32 v155, v125, v125
	v_mul_f32_e32 v162, v92, v92
	v_mul_f32_e32 v163, v93, v93
	v_add_f32_e32 v166, v166, v168
	v_add_f32_e32 v167, v167, v169
	v_mul_f32_e32 v168, v118, v118
	v_mul_f32_e32 v169, v119, v119
	v_mul_f32_e32 v170, v74, v74
	v_mul_f32_e32 v171, v75, v75
	v_add_f32_e32 v146, v146, v148
	v_add_f32_e32 v147, v147, v149
	v_add_f32_e32 v148, v150, v152
	v_add_f32_e32 v149, v151, v153
	v_add_f32_e32 v130, v130, v132
	v_fma_f32 v168, v78, v78, v168
	v_fma_f32 v169, v79, v79, v169
	v_fma_f32 v170, v66, v66, v170
	v_fma_f32 v171, v67, v67, v171
	v_add_f32_e32 v146, v146, v148
	v_add_f32_e32 v147, v147, v149
	v_fma_f32 v148, v96, v96, v154
	v_fma_f32 v149, v97, v97, v155
	v_fma_f32 v150, v88, v88, v162
	v_fma_f32 v151, v89, v89, v163
	v_add_f32_e32 v113, v113, v130
	v_mul_f32_e32 v130, v133, v133
	v_mul_f32_e32 v132, v131, v131
	v_mul_f32_e32 v172, v122, v122
	v_mul_f32_e32 v173, v123, v123
	v_mul_f32_e32 v174, v68, v68
	v_mul_f32_e32 v175, v69, v69
	v_add_f32_e32 v148, v148, v150
	v_add_f32_e32 v149, v149, v151
	v_add_f32_e32 v150, v164, v166
	v_add_f32_e32 v151, v165, v167
	v_add_f32_e32 v152, v168, v170
	v_add_f32_e32 v153, v169, v171
	v_fma_mix_f32 v130, v50, v50, v130 op_sel_hi:[1,1,0]
	v_fma_mix_f32 v132, v51, v51, v132 op_sel_hi:[1,1,0]
	v_add_f32_e32 v150, v150, v152
	v_add_f32_e32 v151, v151, v153
	v_fma_f32 v152, v72, v72, v172
	v_fma_f32 v153, v73, v73, v173
	v_fma_f32 v154, v64, v64, v174
	v_fma_f32 v155, v65, v65, v175
	v_add_f32_e32 v130, v130, v132
	v_add_f32_e32 v152, v152, v154
	v_add_f32_e32 v153, v153, v155
	v_add_f32_e32 v113, v130, v113
	v_add_f32_e32 v146, v148, v146
	v_add_f32_e32 v147, v149, v147
	v_add_f32_e32 v150, v152, v150
	v_add_f32_e32 v151, v153, v151
	ds_bpermute_b32 v130, v156, v113
	ds_bpermute_b32 v149, v156, v147
	ds_bpermute_b32 v148, v156, v146
	ds_bpermute_b32 v153, v156, v151
	ds_bpermute_b32 v152, v156, v150
	s_waitcnt lgkmcnt(4)
; template <int MODE, bool XBF>
; __device__ __forceinline__ void rmsnorm_rows(const void* x, const float* gain, bf16_t* H, int gw, int NGW, int lane, const LAS float* WF, const float* fbias, float* LF) {
;     ...
;         for (int o = 1; o < 64; o <<= 1)
; #pragma unroll
;             for (int r = 0; r < RB; ++r) s[r] += __shfl_xor(s[r], o);
; #pragma unroll
;         for (int r = 0; r < RB; ++r) {
;             const int row = row0 + r;
;             const float rstd = rsqrtf(s[r] * (1.f / D) + 1e-6f);
	v_add_f32_e32 v113, v113, v130
	ds_bpermute_b32 v130, v157, v113
	s_waitcnt lgkmcnt(3)
	v_add_f32_e32 v146, v146, v148
	v_add_f32_e32 v147, v147, v149
	ds_bpermute_b32 v149, v157, v147
	s_waitcnt lgkmcnt(2)
	v_add_f32_e32 v150, v150, v152
	v_add_f32_e32 v151, v151, v153
	ds_bpermute_b32 v148, v157, v146
	ds_bpermute_b32 v153, v157, v151
	ds_bpermute_b32 v152, v157, v150
	s_waitcnt lgkmcnt(4)
	v_add_f32_e32 v113, v113, v130
	ds_bpermute_b32 v130, v158, v113
	s_waitcnt lgkmcnt(3)
	v_add_f32_e32 v146, v146, v148
	v_add_f32_e32 v147, v147, v149
	ds_bpermute_b32 v149, v158, v147
	s_waitcnt lgkmcnt(2)
	v_add_f32_e32 v150, v150, v152
	v_add_f32_e32 v151, v151, v153
	ds_bpermute_b32 v148, v158, v146
	ds_bpermute_b32 v153, v158, v151
	ds_bpermute_b32 v152, v158, v150
	s_waitcnt lgkmcnt(4)
	v_add_f32_e32 v113, v113, v130
	ds_bpermute_b32 v130, v159, v113
	s_waitcnt lgkmcnt(3)
	v_add_f32_e32 v146, v146, v148
	v_add_f32_e32 v147, v147, v149
	ds_bpermute_b32 v149, v159, v147
	s_waitcnt lgkmcnt(2)
	v_add_f32_e32 v150, v150, v152
	v_add_f32_e32 v151, v151, v153
	ds_bpermute_b32 v148, v159, v146
	ds_bpermute_b32 v153, v159, v151
	ds_bpermute_b32 v152, v159, v150
	s_waitcnt lgkmcnt(4)
	v_add_f32_e32 v113, v113, v130
	ds_bpermute_b32 v130, v160, v113
	s_waitcnt lgkmcnt(3)
	v_add_f32_e32 v146, v146, v148
	v_add_f32_e32 v147, v147, v149
	ds_bpermute_b32 v149, v160, v147
	s_waitcnt lgkmcnt(2)
	v_add_f32_e32 v150, v150, v152
	v_add_f32_e32 v151, v151, v153
	ds_bpermute_b32 v148, v160, v146
	ds_bpermute_b32 v163, v160, v151
	ds_bpermute_b32 v162, v160, v150
	s_waitcnt lgkmcnt(4)
	v_add_f32_e32 v113, v113, v130
	ds_bpermute_b32 v130, v161, v113
	s_waitcnt lgkmcnt(3)
	v_add_f32_e32 v152, v146, v148
	v_add_f32_e32 v153, v147, v149
	ds_bpermute_b32 v155, v161, v153
	s_waitcnt lgkmcnt(2)
	v_add_f32_e32 v148, v150, v162
	v_add_f32_e32 v149, v151, v163
	ds_bpermute_b32 v154, v161, v152
	ds_bpermute_b32 v151, v161, v149
	ds_bpermute_b32 v150, v161, v148
	v_mov_b32_e32 v146, 0
	s_cbranch_vccnz .LBB0_2407
	s_waitcnt lgkmcnt(4)
	v_add_f32_e32 v113, v113, v130
	v_fmamk_f32 v113, v113, 0x3a800000, v62
	v_mul_f32_e32 v130, 0x4b800000, v113
	v_cmp_gt_f32_e32 vcc, s40, v113
	s_nop 1
	v_cndmask_b32_e32 v113, v113, v130, vcc
	v_rsq_f32_e32 v113, v113
	s_nop 0
	v_mul_f32_e32 v130, 0x45800000, v113
	v_cndmask_b32_e32 v146, v113, v130, vcc
	s_branch .LBB0_2407

; __device__ __forceinline__ float fsigmoid(float x) { return frcp(1.f + fexp2(-x * LOG2E)); }
;     __device__ __forceinline__ void operator()(const Acc& acc, const Unit& u, int wr, int wc, int fr, int fq) const {
;     ...
;                         if (c < 64) {
; #pragma unroll
;                             for (int j = 0; j < 4; ++j) { v0[j] = 2.f * fsigmoid(2.f * v0[j]) - 1.f; v1[j] = 2.f * fsigmoid(2.f * v1[j]) - 1.f; }
.LBB0_2613:
	s_andn2_saveexec_b64 s[48:49], s[48:49]
	s_cbranch_execz .LBB0_2615
	v_add_f32_e32 v147, v104, v104
	v_mul_f32_e32 v147, 0xbfb8aa3b, v147
	v_add_f32_e32 v148, v109, v109
	v_exp_f32_e32 v147, v147
	v_mul_f32_e32 v148, 0xbfb8aa3b, v148
	v_exp_f32_e32 v149, v148
	v_add_f32_e32 v152, v111, v111
	v_add_f32_e32 v147, 1.0, v147
	v_add_f32_e32 v151, v106, v106
	v_mul_f32_e32 v152, 0xbfb8aa3b, v152
	v_add_f32_e32 v146, v108, v108
	v_rcp_f32_e32 v148, v147
	v_add_f32_e32 v147, 1.0, v149
	v_add_f32_e32 v149, v105, v105
	v_add_f32_e32 v150, v110, v110
	v_mul_f32_e32 v151, 0xbfb8aa3b, v151
	v_exp_f32_e32 v153, v152
	v_add_f32_e32 v152, v107, v107
	v_mul_f32_e32 v146, 0xbfb8aa3b, v146
	v_mul_f32_e32 v149, 0xbfb8aa3b, v149
	v_mul_f32_e32 v150, 0xbfb8aa3b, v150
	v_exp_f32_e32 v151, v151
	v_mul_f32_e32 v152, 0xbfb8aa3b, v152
	v_exp_f32_e32 v146, v146
	v_exp_f32_e32 v149, v149
	v_exp_f32_e32 v150, v150
	v_exp_f32_e32 v162, v152
	v_add_f32_e32 v151, 1.0, v151
	v_add_f32_e32 v146, 1.0, v146
	v_add_f32_e32 v149, 1.0, v149
	v_add_f32_e32 v150, 1.0, v150
	v_rcp_f32_e32 v152, v151
	v_add_f32_e32 v151, 1.0, v153
	v_add_f32_e32 v153, 1.0, v162
	v_rcp_f32_e32 v146, v146
	v_rcp_f32_e32 v147, v147
	v_rcp_f32_e32 v150, v150
	v_rcp_f32_e32 v151, v151
	v_rcp_f32_e32 v153, v153
	v_rcp_f32_e32 v149, v149
	v_fma_f32 v146, v146, 2.0, -1.0
	v_fma_f32 v147, v147, 2.0, -1.0
	v_fma_f32 v150, v150, 2.0, -1.0
	v_fma_f32 v151, v151, 2.0, -1.0
	v_fma_f32 v152, v152, 2.0, -1.0
	v_fma_f32 v153, v153, 2.0, -1.0
	v_fma_f32 v148, v148, 2.0, -1.0
	v_fma_f32 v149, v149, 2.0, -1.0

; __device__ __forceinline__ float fsigmoid(float x) { return frcp(1.f + fexp2(-x * LOG2E)); }
;     __device__ __forceinline__ void operator()(const Acc& acc, const Unit& u, int wr, int wc, int fr, int fq) const {
;     ...
;                         if (c < 64) {
; #pragma unroll
;                             for (int j = 0; j < 4; ++j) { v0[j] = 2.f * fsigmoid(2.f * v0[j]) - 1.f; v1[j] = 2.f * fsigmoid(2.f * v1[j]) - 1.f; }
.LBB0_2619:
	s_andn2_saveexec_b64 s[48:49], s[48:49]
	s_cbranch_execz .LBB0_2621
	v_add_f32_e32 v145, v112, v112
	v_mul_f32_e32 v145, 0xbfb8aa3b, v145
	v_add_f32_e32 v146, v117, v117
	v_exp_f32_e32 v145, v145
	v_mul_f32_e32 v146, 0xbfb8aa3b, v146
	v_exp_f32_e32 v146, v146
	v_add_f32_e32 v147, v118, v118
	v_add_f32_e32 v145, 1.0, v145
	v_rcp_f32_e32 v148, v145
	v_add_f32_e32 v145, 1.0, v146
	v_add_f32_e32 v146, v113, v113
	v_add_f32_e32 v149, v114, v114
	v_mul_f32_e32 v146, 0xbfb8aa3b, v146
	v_mul_f32_e32 v147, 0xbfb8aa3b, v147
	v_mul_f32_e32 v149, 0xbfb8aa3b, v149
	v_exp_f32_e32 v146, v146
	v_exp_f32_e32 v147, v147
	v_exp_f32_e32 v149, v149
	v_add_f32_e32 v144, v116, v116
	v_add_f32_e32 v150, 1.0, v146
	v_add_f32_e32 v146, 1.0, v147
	v_add_f32_e32 v147, 1.0, v149
	v_add_f32_e32 v149, v119, v119
	v_add_f32_e32 v151, v115, v115
	v_mul_f32_e32 v144, 0xbfb8aa3b, v144
	v_mul_f32_e32 v149, 0xbfb8aa3b, v149
	v_mul_f32_e32 v151, 0xbfb8aa3b, v151
	v_exp_f32_e32 v144, v144
	v_exp_f32_e32 v149, v149
	v_exp_f32_e32 v151, v151
	v_rcp_f32_e32 v152, v147
	v_add_f32_e32 v144, 1.0, v144
	v_add_f32_e32 v147, 1.0, v149
	v_add_f32_e32 v149, 1.0, v151
	v_rcp_f32_e32 v144, v144
	v_rcp_f32_e32 v145, v145
	v_rcp_f32_e32 v146, v146
	v_rcp_f32_e32 v147, v147
	v_rcp_f32_e32 v153, v149
	v_rcp_f32_e32 v149, v150
	v_fma_f32 v150, v146, 2.0, -1.0
	v_fma_f32 v151, v147, 2.0, -1.0
	v_fma_f32 v146, v144, 2.0, -1.0
	v_fma_f32 v147, v145, 2.0, -1.0
	v_fma_f32 v152, v152, 2.0, -1.0
	v_fma_f32 v153, v153, 2.0, -1.0
	v_fma_f32 v148, v148, 2.0, -1.0
	v_fma_f32 v149, v149, 2.0, -1.0

; __device__ __forceinline__ float fsigmoid(float x) { return frcp(1.f + fexp2(-x * LOG2E)); }
;     __device__ __forceinline__ void operator()(const Acc& acc, const Unit& u, int wr, int wc, int fr, int fq) const {
;     ...
;                         if (c < 64) {
; #pragma unroll
;                             for (int j = 0; j < 4; ++j) { v0[j] = 2.f * fsigmoid(2.f * v0[j]) - 1.f; v1[j] = 2.f * fsigmoid(2.f * v1[j]) - 1.f; }
.LBB0_2625:
	s_andn2_saveexec_b64 s[48:49], s[48:49]
	s_cbranch_execz .LBB0_2627
	v_add_f32_e32 v147, v88, v88
	v_mul_f32_e32 v147, 0xbfb8aa3b, v147
	v_add_f32_e32 v148, v93, v93
	v_exp_f32_e32 v147, v147
	v_mul_f32_e32 v148, 0xbfb8aa3b, v148
	v_exp_f32_e32 v149, v148
	v_add_f32_e32 v152, v95, v95
	v_add_f32_e32 v147, 1.0, v147
	v_add_f32_e32 v151, v90, v90
	v_mul_f32_e32 v152, 0xbfb8aa3b, v152
	v_add_f32_e32 v146, v92, v92
	v_rcp_f32_e32 v148, v147
	v_add_f32_e32 v147, 1.0, v149
	v_add_f32_e32 v149, v89, v89
	v_add_f32_e32 v150, v94, v94
	v_mul_f32_e32 v151, 0xbfb8aa3b, v151
	v_exp_f32_e32 v153, v152
	v_add_f32_e32 v152, v91, v91
	v_mul_f32_e32 v146, 0xbfb8aa3b, v146
	v_mul_f32_e32 v149, 0xbfb8aa3b, v149
	v_mul_f32_e32 v150, 0xbfb8aa3b, v150
	v_exp_f32_e32 v151, v151
	v_mul_f32_e32 v152, 0xbfb8aa3b, v152
	v_exp_f32_e32 v146, v146
	v_exp_f32_e32 v149, v149
	v_exp_f32_e32 v150, v150
	v_exp_f32_e32 v162, v152
	v_add_f32_e32 v151, 1.0, v151
	v_add_f32_e32 v146, 1.0, v146
	v_add_f32_e32 v149, 1.0, v149
	v_add_f32_e32 v150, 1.0, v150
	v_rcp_f32_e32 v152, v151
	v_add_f32_e32 v151, 1.0, v153
	v_add_f32_e32 v153, 1.0, v162
	v_rcp_f32_e32 v146, v146
	v_rcp_f32_e32 v147, v147
	v_rcp_f32_e32 v150, v150
	v_rcp_f32_e32 v151, v151
	v_rcp_f32_e32 v153, v153
	v_rcp_f32_e32 v149, v149
	v_fma_f32 v146, v146, 2.0, -1.0
	v_fma_f32 v147, v147, 2.0, -1.0
	v_fma_f32 v150, v150, 2.0, -1.0
	v_fma_f32 v151, v151, 2.0, -1.0
	v_fma_f32 v152, v152, 2.0, -1.0
	v_fma_f32 v153, v153, 2.0, -1.0
	v_fma_f32 v148, v148, 2.0, -1.0
	v_fma_f32 v149, v149, 2.0, -1.0

; __device__ __forceinline__ float fsigmoid(float x) { return frcp(1.f + fexp2(-x * LOG2E)); }
;     __device__ __forceinline__ void operator()(const Acc& acc, const Unit& u, int wr, int wc, int fr, int fq) const {
;     ...
;                         if (c < 64) {
; #pragma unroll
;                             for (int j = 0; j < 4; ++j) { v0[j] = 2.f * fsigmoid(2.f * v0[j]) - 1.f; v1[j] = 2.f * fsigmoid(2.f * v1[j]) - 1.f; }
.LBB0_2631:
	s_andn2_saveexec_b64 s[48:49], s[48:49]
	s_cbranch_execz .LBB0_2633
	v_add_f32_e32 v145, v96, v96
	v_mul_f32_e32 v145, 0xbfb8aa3b, v145
	v_add_f32_e32 v146, v101, v101
	v_exp_f32_e32 v145, v145
	v_mul_f32_e32 v146, 0xbfb8aa3b, v146
	v_exp_f32_e32 v146, v146
	v_add_f32_e32 v147, v102, v102
	v_add_f32_e32 v145, 1.0, v145
	v_rcp_f32_e32 v148, v145
	v_add_f32_e32 v145, 1.0, v146
	v_add_f32_e32 v146, v97, v97
	v_add_f32_e32 v149, v98, v98
	v_mul_f32_e32 v146, 0xbfb8aa3b, v146
	v_mul_f32_e32 v147, 0xbfb8aa3b, v147
	v_mul_f32_e32 v149, 0xbfb8aa3b, v149
	v_exp_f32_e32 v146, v146
	v_exp_f32_e32 v147, v147
	v_exp_f32_e32 v149, v149
	v_add_f32_e32 v144, v100, v100
	v_add_f32_e32 v150, 1.0, v146
	v_add_f32_e32 v146, 1.0, v147
	v_add_f32_e32 v147, 1.0, v149
	v_add_f32_e32 v149, v103, v103
	v_add_f32_e32 v151, v99, v99
	v_mul_f32_e32 v144, 0xbfb8aa3b, v144
	v_mul_f32_e32 v149, 0xbfb8aa3b, v149
	v_mul_f32_e32 v151, 0xbfb8aa3b, v151
	v_exp_f32_e32 v144, v144
	v_exp_f32_e32 v149, v149
	v_exp_f32_e32 v151, v151
	v_rcp_f32_e32 v152, v147
	v_add_f32_e32 v144, 1.0, v144
	v_add_f32_e32 v147, 1.0, v149
	v_add_f32_e32 v149, 1.0, v151
	v_rcp_f32_e32 v144, v144
	v_rcp_f32_e32 v145, v145
	v_rcp_f32_e32 v146, v146
	v_rcp_f32_e32 v147, v147
	v_rcp_f32_e32 v153, v149
	v_rcp_f32_e32 v149, v150
	v_fma_f32 v150, v146, 2.0, -1.0
	v_fma_f32 v151, v147, 2.0, -1.0
	v_fma_f32 v146, v144, 2.0, -1.0
	v_fma_f32 v147, v145, 2.0, -1.0
	v_fma_f32 v152, v152, 2.0, -1.0
	v_fma_f32 v153, v153, 2.0, -1.0
	v_fma_f32 v148, v148, 2.0, -1.0
	v_fma_f32 v149, v149, 2.0, -1.0

; __device__ __forceinline__ float fsigmoid(float x) { return frcp(1.f + fexp2(-x * LOG2E)); }
;     __device__ __forceinline__ void operator()(const Acc& acc, const Unit& u, int wr, int wc, int fr, int fq) const {
;     ...
;                         if (c < 64) {
; #pragma unroll
;                             for (int j = 0; j < 4; ++j) { v0[j] = 2.f * fsigmoid(2.f * v0[j]) - 1.f; v1[j] = 2.f * fsigmoid(2.f * v1[j]) - 1.f; }
.LBB0_2637:
	s_andn2_saveexec_b64 s[48:49], s[48:49]
	s_cbranch_execz .LBB0_2639
	v_add_f32_e32 v147, v72, v72
	v_mul_f32_e32 v147, 0xbfb8aa3b, v147
	v_add_f32_e32 v148, v77, v77
	v_exp_f32_e32 v147, v147
	v_mul_f32_e32 v148, 0xbfb8aa3b, v148
	v_exp_f32_e32 v149, v148
	v_add_f32_e32 v152, v79, v79
	v_add_f32_e32 v147, 1.0, v147
	v_add_f32_e32 v151, v74, v74
	v_mul_f32_e32 v152, 0xbfb8aa3b, v152
	v_add_f32_e32 v146, v76, v76
	v_rcp_f32_e32 v148, v147
	v_add_f32_e32 v147, 1.0, v149
	v_add_f32_e32 v149, v73, v73
	v_add_f32_e32 v150, v78, v78
	v_mul_f32_e32 v151, 0xbfb8aa3b, v151
	v_exp_f32_e32 v153, v152
	v_add_f32_e32 v152, v75, v75
	v_mul_f32_e32 v146, 0xbfb8aa3b, v146
	v_mul_f32_e32 v149, 0xbfb8aa3b, v149
	v_mul_f32_e32 v150, 0xbfb8aa3b, v150
	v_exp_f32_e32 v151, v151
	v_mul_f32_e32 v152, 0xbfb8aa3b, v152
	v_exp_f32_e32 v146, v146
	v_exp_f32_e32 v149, v149
	v_exp_f32_e32 v150, v150
	v_exp_f32_e32 v162, v152
	v_add_f32_e32 v151, 1.0, v151
	v_add_f32_e32 v146, 1.0, v146
	v_add_f32_e32 v149, 1.0, v149
	v_add_f32_e32 v150, 1.0, v150
	v_rcp_f32_e32 v152, v151
	v_add_f32_e32 v151, 1.0, v153
	v_add_f32_e32 v153, 1.0, v162
	v_rcp_f32_e32 v146, v146
	v_rcp_f32_e32 v147, v147
	v_rcp_f32_e32 v150, v150
	v_rcp_f32_e32 v151, v151
	v_rcp_f32_e32 v153, v153
	v_rcp_f32_e32 v149, v149
	v_fma_f32 v146, v146, 2.0, -1.0
	v_fma_f32 v147, v147, 2.0, -1.0
	v_fma_f32 v150, v150, 2.0, -1.0
	v_fma_f32 v151, v151, 2.0, -1.0
	v_fma_f32 v152, v152, 2.0, -1.0
	v_fma_f32 v153, v153, 2.0, -1.0
	v_fma_f32 v148, v148, 2.0, -1.0
	v_fma_f32 v149, v149, 2.0, -1.0

; __device__ __forceinline__ float fsigmoid(float x) { return frcp(1.f + fexp2(-x * LOG2E)); }
;     __device__ __forceinline__ void operator()(const Acc& acc, const Unit& u, int wr, int wc, int fr, int fq) const {
;     ...
;                         if (c < 64) {
; #pragma unroll
;                             for (int j = 0; j < 4; ++j) { v0[j] = 2.f * fsigmoid(2.f * v0[j]) - 1.f; v1[j] = 2.f * fsigmoid(2.f * v1[j]) - 1.f; }
.LBB0_2643:
	s_andn2_saveexec_b64 s[48:49], s[48:49]
	s_cbranch_execz .LBB0_2645
	v_add_f32_e32 v145, v80, v80
	v_mul_f32_e32 v145, 0xbfb8aa3b, v145
	v_add_f32_e32 v146, v85, v85
	v_exp_f32_e32 v145, v145
	v_mul_f32_e32 v146, 0xbfb8aa3b, v146
	v_exp_f32_e32 v146, v146
	v_add_f32_e32 v147, v86, v86
	v_add_f32_e32 v145, 1.0, v145
	v_rcp_f32_e32 v148, v145
	v_add_f32_e32 v145, 1.0, v146
	v_add_f32_e32 v146, v81, v81
	v_add_f32_e32 v149, v82, v82
	v_mul_f32_e32 v146, 0xbfb8aa3b, v146
	v_mul_f32_e32 v147, 0xbfb8aa3b, v147
	v_mul_f32_e32 v149, 0xbfb8aa3b, v149
	v_exp_f32_e32 v146, v146
	v_exp_f32_e32 v147, v147
	v_exp_f32_e32 v149, v149
	v_add_f32_e32 v144, v84, v84
	v_add_f32_e32 v150, 1.0, v146
	v_add_f32_e32 v146, 1.0, v147
	v_add_f32_e32 v147, 1.0, v149
	v_add_f32_e32 v149, v87, v87
	v_add_f32_e32 v151, v83, v83
	v_mul_f32_e32 v144, 0xbfb8aa3b, v144
	v_mul_f32_e32 v149, 0xbfb8aa3b, v149
	v_mul_f32_e32 v151, 0xbfb8aa3b, v151
	v_exp_f32_e32 v144, v144
	v_exp_f32_e32 v149, v149
	v_exp_f32_e32 v151, v151
	v_rcp_f32_e32 v152, v147
	v_add_f32_e32 v144, 1.0, v144
	v_add_f32_e32 v147, 1.0, v149
	v_add_f32_e32 v149, 1.0, v151
	v_rcp_f32_e32 v144, v144
	v_rcp_f32_e32 v145, v145
	v_rcp_f32_e32 v146, v146
	v_rcp_f32_e32 v147, v147
	v_rcp_f32_e32 v153, v149
	v_rcp_f32_e32 v149, v150
	v_fma_f32 v150, v146, 2.0, -1.0
	v_fma_f32 v151, v147, 2.0, -1.0
	v_fma_f32 v146, v144, 2.0, -1.0
	v_fma_f32 v147, v145, 2.0, -1.0
	v_fma_f32 v152, v152, 2.0, -1.0
	v_fma_f32 v153, v153, 2.0, -1.0
	v_fma_f32 v148, v148, 2.0, -1.0
	v_fma_f32 v149, v149, 2.0, -1.0

; __device__ __forceinline__ float fsigmoid(float x) { return frcp(1.f + fexp2(-x * LOG2E)); }
;     __device__ __forceinline__ void operator()(const Acc& acc, const Unit& u, int wr, int wc, int fr, int fq) const {
;     ...
;                         if (c < 64) {
; #pragma unroll
;                             for (int j = 0; j < 4; ++j) { v0[j] = 2.f * fsigmoid(2.f * v0[j]) - 1.f; v1[j] = 2.f * fsigmoid(2.f * v1[j]) - 1.f; }
.LBB0_2649:
	s_andn2_saveexec_b64 s[48:49], s[48:49]
	s_cbranch_execz .LBB0_2651
	v_add_f32_e32 v147, v64, v64
	v_mul_f32_e32 v147, 0xbfb8aa3b, v147
	v_add_f32_e32 v148, v69, v69
	v_exp_f32_e32 v147, v147
	v_mul_f32_e32 v148, 0xbfb8aa3b, v148
	v_exp_f32_e32 v149, v148
	v_add_f32_e32 v152, v71, v71
	v_add_f32_e32 v147, 1.0, v147
	v_add_f32_e32 v151, v66, v66
	v_mul_f32_e32 v152, 0xbfb8aa3b, v152
	v_add_f32_e32 v146, v68, v68
	v_rcp_f32_e32 v148, v147
	v_add_f32_e32 v147, 1.0, v149
	v_add_f32_e32 v149, v65, v65
	v_add_f32_e32 v150, v70, v70
	v_mul_f32_e32 v151, 0xbfb8aa3b, v151
	v_exp_f32_e32 v153, v152
	v_add_f32_e32 v152, v67, v67
	v_mul_f32_e32 v146, 0xbfb8aa3b, v146
	v_mul_f32_e32 v149, 0xbfb8aa3b, v149
	v_mul_f32_e32 v150, 0xbfb8aa3b, v150
	v_exp_f32_e32 v151, v151
	v_mul_f32_e32 v152, 0xbfb8aa3b, v152
	v_exp_f32_e32 v146, v146
	v_exp_f32_e32 v149, v149
	v_exp_f32_e32 v150, v150
	v_exp_f32_e32 v162, v152
	v_add_f32_e32 v151, 1.0, v151
	v_add_f32_e32 v146, 1.0, v146
	v_add_f32_e32 v149, 1.0, v149
	v_add_f32_e32 v150, 1.0, v150
	v_rcp_f32_e32 v152, v151
	v_add_f32_e32 v151, 1.0, v153
	v_add_f32_e32 v153, 1.0, v162
	v_rcp_f32_e32 v146, v146
	v_rcp_f32_e32 v147, v147
	v_rcp_f32_e32 v150, v150
	v_rcp_f32_e32 v151, v151
	v_rcp_f32_e32 v153, v153
	v_rcp_f32_e32 v149, v149
	v_fma_f32 v146, v146, 2.0, -1.0
	v_fma_f32 v147, v147, 2.0, -1.0
	v_fma_f32 v150, v150, 2.0, -1.0
	v_fma_f32 v151, v151, 2.0, -1.0
	v_fma_f32 v152, v152, 2.0, -1.0
	v_fma_f32 v153, v153, 2.0, -1.0
	v_fma_f32 v148, v148, 2.0, -1.0
	v_fma_f32 v149, v149, 2.0, -1.0

; __device__ __forceinline__ float fsigmoid(float x) { return frcp(1.f + fexp2(-x * LOG2E)); }
;     __device__ __forceinline__ void operator()(const Acc& acc, const Unit& u, int wr, int wc, int fr, int fq) const {
;     ...
;                         if (c < 64) {
; #pragma unroll
;                             for (int j = 0; j < 4; ++j) { v0[j] = 2.f * fsigmoid(2.f * v0[j]) - 1.f; v1[j] = 2.f * fsigmoid(2.f * v1[j]) - 1.f; }
.LBB0_2655:
	s_andn2_saveexec_b64 s[48:49], s[48:49]
	s_cbranch_execz .LBB0_2657
	v_add_f32_e32 v145, v56, v56
	v_mul_f32_e32 v145, 0xbfb8aa3b, v145
	v_add_f32_e32 v146, v61, v61
	v_exp_f32_e32 v145, v145
	v_mul_f32_e32 v146, 0xbfb8aa3b, v146
	v_exp_f32_e32 v146, v146
	v_add_f32_e32 v147, v62, v62
	v_add_f32_e32 v145, 1.0, v145
	v_rcp_f32_e32 v148, v145
	v_add_f32_e32 v145, 1.0, v146
	v_add_f32_e32 v146, v57, v57
	v_add_f32_e32 v149, v58, v58
	v_mul_f32_e32 v146, 0xbfb8aa3b, v146
	v_mul_f32_e32 v147, 0xbfb8aa3b, v147
	v_mul_f32_e32 v149, 0xbfb8aa3b, v149
	v_exp_f32_e32 v146, v146
	v_exp_f32_e32 v147, v147
	v_exp_f32_e32 v149, v149
	v_add_f32_e32 v144, v60, v60
	v_add_f32_e32 v150, 1.0, v146
	v_add_f32_e32 v146, 1.0, v147
	v_add_f32_e32 v147, 1.0, v149
	v_add_f32_e32 v149, v63, v63
	v_add_f32_e32 v151, v59, v59
	v_mul_f32_e32 v144, 0xbfb8aa3b, v144
	v_mul_f32_e32 v149, 0xbfb8aa3b, v149
	v_mul_f32_e32 v151, 0xbfb8aa3b, v151
	v_exp_f32_e32 v144, v144
	v_exp_f32_e32 v149, v149
	v_exp_f32_e32 v151, v151
	v_rcp_f32_e32 v152, v147
	v_add_f32_e32 v144, 1.0, v144
	v_add_f32_e32 v147, 1.0, v149
	v_add_f32_e32 v149, 1.0, v151
	v_rcp_f32_e32 v144, v144
	v_rcp_f32_e32 v145, v145
	v_rcp_f32_e32 v146, v146
	v_rcp_f32_e32 v147, v147
	v_rcp_f32_e32 v153, v149
	v_rcp_f32_e32 v149, v150
	v_fma_f32 v150, v146, 2.0, -1.0
	v_fma_f32 v151, v147, 2.0, -1.0
	v_fma_f32 v146, v144, 2.0, -1.0
	v_fma_f32 v147, v145, 2.0, -1.0
	v_fma_f32 v152, v152, 2.0, -1.0
	v_fma_f32 v153, v153, 2.0, -1.0
	v_fma_f32 v148, v148, 2.0, -1.0
	v_fma_f32 v149, v149, 2.0, -1.0

; __device__ __forceinline__ float fsigmoid(float x) { return frcp(1.f + fexp2(-x * LOG2E)); }
;     __device__ __forceinline__ void operator()(const Acc& acc, const Unit& u, int wr, int wc, int fr, int fq) const {
;     ...
;                         if (c < 64) {
; #pragma unroll
;                             for (int j = 0; j < 4; ++j) { v0[j] = 2.f * fsigmoid(2.f * v0[j]) - 1.f; v1[j] = 2.f * fsigmoid(2.f * v1[j]) - 1.f; }
.LBB0_2661:
	s_andn2_saveexec_b64 s[48:49], s[48:49]
	s_cbranch_execz .LBB0_2663
	v_add_f32_e32 v147, v40, v40
	v_mul_f32_e32 v147, 0xbfb8aa3b, v147
	v_add_f32_e32 v148, v45, v45
	v_exp_f32_e32 v147, v147
	v_mul_f32_e32 v148, 0xbfb8aa3b, v148
	v_exp_f32_e32 v149, v148
	v_add_f32_e32 v152, v47, v47
	v_add_f32_e32 v147, 1.0, v147
	v_add_f32_e32 v151, v42, v42
	v_mul_f32_e32 v152, 0xbfb8aa3b, v152
	v_add_f32_e32 v146, v44, v44
	v_rcp_f32_e32 v148, v147
	v_add_f32_e32 v147, 1.0, v149
	v_add_f32_e32 v149, v41, v41
	v_add_f32_e32 v150, v46, v46
	v_mul_f32_e32 v151, 0xbfb8aa3b, v151
	v_exp_f32_e32 v153, v152
	v_add_f32_e32 v152, v43, v43
	v_mul_f32_e32 v146, 0xbfb8aa3b, v146
	v_mul_f32_e32 v149, 0xbfb8aa3b, v149
	v_mul_f32_e32 v150, 0xbfb8aa3b, v150
	v_exp_f32_e32 v151, v151
	v_mul_f32_e32 v152, 0xbfb8aa3b, v152
	v_exp_f32_e32 v146, v146
	v_exp_f32_e32 v149, v149
	v_exp_f32_e32 v150, v150
	v_exp_f32_e32 v162, v152
	v_add_f32_e32 v151, 1.0, v151
	v_add_f32_e32 v146, 1.0, v146
	v_add_f32_e32 v149, 1.0, v149
	v_add_f32_e32 v150, 1.0, v150
	v_rcp_f32_e32 v152, v151
	v_add_f32_e32 v151, 1.0, v153
	v_add_f32_e32 v153, 1.0, v162
	v_rcp_f32_e32 v146, v146
	v_rcp_f32_e32 v147, v147
	v_rcp_f32_e32 v150, v150
	v_rcp_f32_e32 v151, v151
	v_rcp_f32_e32 v153, v153
	v_rcp_f32_e32 v149, v149
	v_fma_f32 v146, v146, 2.0, -1.0
	v_fma_f32 v147, v147, 2.0, -1.0
	v_fma_f32 v150, v150, 2.0, -1.0
	v_fma_f32 v151, v151, 2.0, -1.0
	v_fma_f32 v152, v152, 2.0, -1.0
	v_fma_f32 v153, v153, 2.0, -1.0
	v_fma_f32 v148, v148, 2.0, -1.0
	v_fma_f32 v149, v149, 2.0, -1.0

; __device__ __forceinline__ float fsigmoid(float x) { return frcp(1.f + fexp2(-x * LOG2E)); }
;     __device__ __forceinline__ void operator()(const Acc& acc, const Unit& u, int wr, int wc, int fr, int fq) const {
;     ...
;                         if (c < 64) {
; #pragma unroll
;                             for (int j = 0; j < 4; ++j) { v0[j] = 2.f * fsigmoid(2.f * v0[j]) - 1.f; v1[j] = 2.f * fsigmoid(2.f * v1[j]) - 1.f; }
.LBB0_2667:
	s_andn2_saveexec_b64 s[48:49], s[48:49]
	s_cbranch_execz .LBB0_2669
	v_add_f32_e32 v145, v48, v48
	v_mul_f32_e32 v145, 0xbfb8aa3b, v145
	v_add_f32_e32 v146, v53, v53
	v_exp_f32_e32 v145, v145
	v_mul_f32_e32 v146, 0xbfb8aa3b, v146
	v_exp_f32_e32 v146, v146
	v_add_f32_e32 v147, v54, v54
	v_add_f32_e32 v145, 1.0, v145
	v_rcp_f32_e32 v148, v145
	v_add_f32_e32 v145, 1.0, v146
	v_add_f32_e32 v146, v49, v49
	v_add_f32_e32 v149, v50, v50
	v_mul_f32_e32 v146, 0xbfb8aa3b, v146
	v_mul_f32_e32 v147, 0xbfb8aa3b, v147
	v_mul_f32_e32 v149, 0xbfb8aa3b, v149
	v_exp_f32_e32 v146, v146
	v_exp_f32_e32 v147, v147
	v_exp_f32_e32 v149, v149
	v_add_f32_e32 v144, v52, v52
	v_add_f32_e32 v150, 1.0, v146
	v_add_f32_e32 v146, 1.0, v147
	v_add_f32_e32 v147, 1.0, v149
	v_add_f32_e32 v149, v55, v55
	v_add_f32_e32 v151, v51, v51
	v_mul_f32_e32 v144, 0xbfb8aa3b, v144
	v_mul_f32_e32 v149, 0xbfb8aa3b, v149
	v_mul_f32_e32 v151, 0xbfb8aa3b, v151
	v_exp_f32_e32 v144, v144
	v_exp_f32_e32 v149, v149
	v_exp_f32_e32 v151, v151
	v_rcp_f32_e32 v152, v147
	v_add_f32_e32 v144, 1.0, v144
	v_add_f32_e32 v147, 1.0, v149
	v_add_f32_e32 v149, 1.0, v151
	v_rcp_f32_e32 v144, v144
	v_rcp_f32_e32 v145, v145
	v_rcp_f32_e32 v146, v146
	v_rcp_f32_e32 v147, v147
	v_rcp_f32_e32 v153, v149
	v_rcp_f32_e32 v149, v150
	v_fma_f32 v150, v146, 2.0, -1.0
	v_fma_f32 v151, v147, 2.0, -1.0
	v_fma_f32 v146, v144, 2.0, -1.0
	v_fma_f32 v147, v145, 2.0, -1.0
	v_fma_f32 v152, v152, 2.0, -1.0
	v_fma_f32 v153, v153, 2.0, -1.0
	v_fma_f32 v148, v148, 2.0, -1.0
	v_fma_f32 v149, v149, 2.0, -1.0

; __device__ __forceinline__ float fsigmoid(float x) { return frcp(1.f + fexp2(-x * LOG2E)); }
;     __device__ __forceinline__ void operator()(const Acc& acc, const Unit& u, int wr, int wc, int fr, int fq) const {
;     ...
;                         if (c < 64) {
; #pragma unroll
;                             for (int j = 0; j < 4; ++j) { v0[j] = 2.f * fsigmoid(2.f * v0[j]) - 1.f; v1[j] = 2.f * fsigmoid(2.f * v1[j]) - 1.f; }
.LBB0_2673:
	s_andn2_saveexec_b64 s[48:49], s[48:49]
	s_cbranch_execz .LBB0_2675
	v_add_f32_e32 v147, v24, v24
	v_mul_f32_e32 v147, 0xbfb8aa3b, v147
	v_add_f32_e32 v148, v29, v29
	v_exp_f32_e32 v147, v147
	v_mul_f32_e32 v148, 0xbfb8aa3b, v148
	v_exp_f32_e32 v149, v148
	v_add_f32_e32 v152, v31, v31
	v_add_f32_e32 v147, 1.0, v147
	v_add_f32_e32 v151, v26, v26
	v_mul_f32_e32 v152, 0xbfb8aa3b, v152
	v_add_f32_e32 v146, v28, v28
	v_rcp_f32_e32 v148, v147
	v_add_f32_e32 v147, 1.0, v149
	v_add_f32_e32 v149, v25, v25
	v_add_f32_e32 v150, v30, v30
	v_mul_f32_e32 v151, 0xbfb8aa3b, v151
	v_exp_f32_e32 v153, v152
	v_add_f32_e32 v152, v27, v27
	v_mul_f32_e32 v146, 0xbfb8aa3b, v146
	v_mul_f32_e32 v149, 0xbfb8aa3b, v149
	v_mul_f32_e32 v150, 0xbfb8aa3b, v150
	v_exp_f32_e32 v151, v151
	v_mul_f32_e32 v152, 0xbfb8aa3b, v152
	v_exp_f32_e32 v146, v146
	v_exp_f32_e32 v149, v149
	v_exp_f32_e32 v150, v150
	v_exp_f32_e32 v162, v152
	v_add_f32_e32 v151, 1.0, v151
	v_add_f32_e32 v146, 1.0, v146
	v_add_f32_e32 v149, 1.0, v149
	v_add_f32_e32 v150, 1.0, v150
	v_rcp_f32_e32 v152, v151
	v_add_f32_e32 v151, 1.0, v153
	v_add_f32_e32 v153, 1.0, v162
	v_rcp_f32_e32 v146, v146
	v_rcp_f32_e32 v147, v147
	v_rcp_f32_e32 v150, v150
	v_rcp_f32_e32 v151, v151
	v_rcp_f32_e32 v153, v153
	v_rcp_f32_e32 v149, v149
	v_fma_f32 v146, v146, 2.0, -1.0
	v_fma_f32 v147, v147, 2.0, -1.0
	v_fma_f32 v150, v150, 2.0, -1.0
	v_fma_f32 v151, v151, 2.0, -1.0
	v_fma_f32 v152, v152, 2.0, -1.0
	v_fma_f32 v153, v153, 2.0, -1.0
	v_fma_f32 v148, v148, 2.0, -1.0
	v_fma_f32 v149, v149, 2.0, -1.0

; __device__ __forceinline__ float fsigmoid(float x) { return frcp(1.f + fexp2(-x * LOG2E)); }
;     __device__ __forceinline__ void operator()(const Acc& acc, const Unit& u, int wr, int wc, int fr, int fq) const {
;     ...
;                         if (c < 64) {
; #pragma unroll
;                             for (int j = 0; j < 4; ++j) { v0[j] = 2.f * fsigmoid(2.f * v0[j]) - 1.f; v1[j] = 2.f * fsigmoid(2.f * v1[j]) - 1.f; }
.LBB0_2679:
	s_andn2_saveexec_b64 s[48:49], s[48:49]
	s_cbranch_execz .LBB0_2681
	v_add_f32_e32 v145, v32, v32
	v_mul_f32_e32 v145, 0xbfb8aa3b, v145
	v_add_f32_e32 v146, v37, v37
	v_exp_f32_e32 v145, v145
	v_mul_f32_e32 v146, 0xbfb8aa3b, v146
	v_exp_f32_e32 v146, v146
	v_add_f32_e32 v147, v38, v38
	v_add_f32_e32 v145, 1.0, v145
	v_rcp_f32_e32 v148, v145
	v_add_f32_e32 v145, 1.0, v146
	v_add_f32_e32 v146, v33, v33
	v_add_f32_e32 v149, v34, v34
	v_mul_f32_e32 v146, 0xbfb8aa3b, v146
	v_mul_f32_e32 v147, 0xbfb8aa3b, v147
	v_mul_f32_e32 v149, 0xbfb8aa3b, v149
	v_exp_f32_e32 v146, v146
	v_exp_f32_e32 v147, v147
	v_exp_f32_e32 v149, v149
	v_add_f32_e32 v144, v36, v36
	v_add_f32_e32 v150, 1.0, v146
	v_add_f32_e32 v146, 1.0, v147
	v_add_f32_e32 v147, 1.0, v149
	v_add_f32_e32 v149, v39, v39
	v_add_f32_e32 v151, v35, v35
	v_mul_f32_e32 v144, 0xbfb8aa3b, v144
	v_mul_f32_e32 v149, 0xbfb8aa3b, v149
	v_mul_f32_e32 v151, 0xbfb8aa3b, v151
	v_exp_f32_e32 v144, v144
	v_exp_f32_e32 v149, v149
	v_exp_f32_e32 v151, v151
	v_rcp_f32_e32 v152, v147
	v_add_f32_e32 v144, 1.0, v144
	v_add_f32_e32 v147, 1.0, v149
	v_add_f32_e32 v149, 1.0, v151
	v_rcp_f32_e32 v144, v144
	v_rcp_f32_e32 v145, v145
	v_rcp_f32_e32 v146, v146
	v_rcp_f32_e32 v147, v147
	v_rcp_f32_e32 v153, v149
	v_rcp_f32_e32 v149, v150
	v_fma_f32 v150, v146, 2.0, -1.0
	v_fma_f32 v151, v147, 2.0, -1.0
	v_fma_f32 v146, v144, 2.0, -1.0
	v_fma_f32 v147, v145, 2.0, -1.0
	v_fma_f32 v152, v152, 2.0, -1.0
	v_fma_f32 v153, v153, 2.0, -1.0
	v_fma_f32 v148, v148, 2.0, -1.0
	v_fma_f32 v149, v149, 2.0, -1.0

; __device__ __forceinline__ float fsigmoid(float x) { return frcp(1.f + fexp2(-x * LOG2E)); }
;     __device__ __forceinline__ void operator()(const Acc& acc, const Unit& u, int wr, int wc, int fr, int fq) const {
;     ...
;                         if (c < 64) {
; #pragma unroll
;                             for (int j = 0; j < 4; ++j) { v0[j] = 2.f * fsigmoid(2.f * v0[j]) - 1.f; v1[j] = 2.f * fsigmoid(2.f * v1[j]) - 1.f; }
.LBB0_2685:
	s_andn2_saveexec_b64 s[48:49], s[48:49]
	s_cbranch_execz .LBB0_2687
	v_add_f32_e32 v147, v8, v8
	v_mul_f32_e32 v147, 0xbfb8aa3b, v147
	v_add_f32_e32 v148, v13, v13
	v_exp_f32_e32 v147, v147
	v_mul_f32_e32 v148, 0xbfb8aa3b, v148
	v_exp_f32_e32 v149, v148
	v_add_f32_e32 v152, v15, v15
	v_add_f32_e32 v147, 1.0, v147
	v_add_f32_e32 v151, v10, v10
	v_mul_f32_e32 v152, 0xbfb8aa3b, v152
	v_add_f32_e32 v146, v12, v12
	v_rcp_f32_e32 v148, v147
	v_add_f32_e32 v147, 1.0, v149
	v_add_f32_e32 v149, v9, v9
	v_add_f32_e32 v150, v14, v14
	v_mul_f32_e32 v151, 0xbfb8aa3b, v151
	v_exp_f32_e32 v153, v152
	v_add_f32_e32 v152, v11, v11
	v_mul_f32_e32 v146, 0xbfb8aa3b, v146
	v_mul_f32_e32 v149, 0xbfb8aa3b, v149
	v_mul_f32_e32 v150, 0xbfb8aa3b, v150
	v_exp_f32_e32 v151, v151
	v_mul_f32_e32 v152, 0xbfb8aa3b, v152
	v_exp_f32_e32 v146, v146
	v_exp_f32_e32 v149, v149
	v_exp_f32_e32 v150, v150
	v_exp_f32_e32 v162, v152
	v_add_f32_e32 v151, 1.0, v151
	v_add_f32_e32 v146, 1.0, v146
	v_add_f32_e32 v149, 1.0, v149
	v_add_f32_e32 v150, 1.0, v150
	v_rcp_f32_e32 v152, v151
	v_add_f32_e32 v151, 1.0, v153
	v_add_f32_e32 v153, 1.0, v162
	v_rcp_f32_e32 v146, v146
	v_rcp_f32_e32 v147, v147
	v_rcp_f32_e32 v150, v150
	v_rcp_f32_e32 v151, v151
	v_rcp_f32_e32 v153, v153
	v_rcp_f32_e32 v149, v149
	v_fma_f32 v146, v146, 2.0, -1.0
	v_fma_f32 v147, v147, 2.0, -1.0
	v_fma_f32 v150, v150, 2.0, -1.0
	v_fma_f32 v151, v151, 2.0, -1.0
	v_fma_f32 v152, v152, 2.0, -1.0
	v_fma_f32 v153, v153, 2.0, -1.0
	v_fma_f32 v148, v148, 2.0, -1.0
	v_fma_f32 v149, v149, 2.0, -1.0

; #define GAS __attribute__((address_space(1)))
; __device__ __forceinline__ float fsigmoid(float x) { return frcp(1.f + fexp2(-x * LOG2E)); }
;     __device__ __forceinline__ void operator()(const Acc& acc, const Unit& u, int wr, int wc, int fr, int fq) const {
;     ...
;         const float* bias = ldp(PL, t4 == 0 ? 17 : (t4 == 1 ? 20 : 31)) + (t4 < 2 ? idx * D : 0);
;         bf16_t* dst = W + (t4 == 0 ? 0L : (t4 == 1 ? (long)(32u << 20) : -(long)(32u << 20)));
;         const bf16_t* V = W - (long)(32u << 20);
;         const float osc = t4 == 0 ? 0.60653065971f : 1.f;
; #pragma unroll
;         for (int bj = 0; bj < 2; ++bj) {
;             const f32x4 b0 = *(const GAS f32x4*)(bias + colb + 128 * bj), b1 = *(const GAS f32x4*)(bias + colb + 128 * bj + 4);
; #pragma unroll
;             for (int ai = 0; ai < 2; ++ai)
; #pragma unroll
;                 for (int m = 0; m < 4; ++m) {
;                     const size_t off = (size_t)(row0 + ai * HALF + m * 16) * D + colb + 128 * bj;
;                     f32x4 v0_ = acc[ai][bj][m][0] + b0, v1_ = acc[ai][bj][m][1] + b1;
; #pragma unroll
;                     for (int j = 0; j < 4; ++j) { v0_[j] = fsigmoid(v0_[j]) * osc; v1_[j] = fsigmoid(v1_[j]) * osc; }
;                     if (t4 == 2) {
;                         f32x4 x0, x1, f0, f1; unpack8(*(const GAS u32x4*)(V + off), x0, x1); unpack8(*(const GAS u32x4*)(VF + off), f0, f1);
;                         v0_ = x0 + (f0 - x0) * v0_; v1_ = x1 + (f1 - x1) * v1_;
;                     }
;                     *(GAS u32x4*)(dst + off) = pack8(v0_, v1_);
.LBB0_2772:
	s_lshl_b32 s4, s70, 8
	s_lshl_b32 s1, s38, 8
	s_and_b32 s4, s4, 0x300
	s_ashr_i32 s0, s70, 2
	s_add_i32 s1, s1, s57
	s_or_b32 s29, s4, s58
	s_cmp_eq_u32 s0, 1
	s_cselect_b64 s[4:5], -1, 0
	s_and_b64 s[38:39], s[4:5], exec
	s_cselect_b32 s40, s67, 0xf8
	s_cmp_lt_u32 s70, 4
	s_cselect_b64 vcc, -1, 0
	s_and_b64 s[38:39], vcc, exec
	s_cselect_b32 s38, 0x88, s40
	s_add_i32 s38, s38, 0
	s_add_i32 s38, s38, 0x20000
	v_mov_b32_e32 v149, v161
	v_mov_b32_e32 v104, s38
	ds_read_b64 v[104:105], v104
	v_ashrrev_i32_e32 v106, 1, v149
	v_and_b32_e32 v106, -8, v106
	s_cmp_lt_i32 s0, 2
	v_add_u32_e32 v152, s29, v106
	s_waitcnt lgkmcnt(0)
	v_readfirstlane_b32 s29, v104
	v_readfirstlane_b32 s39, v105
	s_cselect_b32 s38, 0x1000, 0
	s_add_u32 s38, s29, s38
	s_addc_u32 s39, s39, 0
	v_ashrrev_i32_e32 v153, 31, v152
	v_lshl_add_u64 v[154:155], v[152:153], 2, s[38:39]
	global_load_dwordx4 v[108:111], v[154:155], off
	global_load_dwordx4 v[104:107], v[154:155], off offset:16
	v_and_or_b32 v156, v149, 15, s1
	v_ashrrev_i32_e32 v157, 31, v156
	v_cndmask_b32_e32 v148, 1.0, v166, vcc
	v_lshlrev_b64 v[150:151], 10, v[156:157]
	s_cmp_eq_u32 s0, 2
	s_cselect_b64 s[40:41], -1, 0
	s_cmp_lg_u32 s0, 2
	s_waitcnt vmcnt(0)
	v_add_f32_e32 v134, v134, v110
	v_add_f32_e32 v135, v135, v111
	v_add_f32_e32 v132, v132, v108
	v_add_f32_e32 v133, v133, v109
	v_add_f32_e32 v130, v130, v106
	v_add_f32_e32 v131, v131, v107
	v_add_f32_e32 v128, v128, v104
	v_add_f32_e32 v129, v129, v105
	v_mul_f32_e32 v132, 0xbfb8aa3b, v132
	v_mul_f32_e32 v128, 0xbfb8aa3b, v128
	v_mul_f32_e32 v133, 0xbfb8aa3b, v133
	v_mul_f32_e32 v129, 0xbfb8aa3b, v129
	v_mul_f32_e32 v134, 0xbfb8aa3b, v134
	v_mul_f32_e32 v130, 0xbfb8aa3b, v130
	v_mul_f32_e32 v135, 0xbfb8aa3b, v135
	v_mul_f32_e32 v131, 0xbfb8aa3b, v131
	v_exp_f32_e32 v132, v132
	v_exp_f32_e32 v128, v128
	v_exp_f32_e32 v133, v133
	v_exp_f32_e32 v129, v129
	v_exp_f32_e32 v134, v134
	v_exp_f32_e32 v130, v130
	v_exp_f32_e32 v135, v135
	v_exp_f32_e32 v131, v131
	v_add_f32_e32 v132, 1.0, v132
	v_add_f32_e32 v128, 1.0, v128
	v_add_f32_e32 v133, 1.0, v133
	v_add_f32_e32 v149, 1.0, v129
	v_add_f32_e32 v129, 1.0, v134
	v_add_f32_e32 v134, 1.0, v130
	v_add_f32_e32 v135, 1.0, v135
	v_add_f32_e32 v159, 1.0, v131
	v_rcp_f32_e32 v130, v132
	v_rcp_f32_e32 v158, v128
	v_rcp_f32_e32 v131, v133
	v_rcp_f32_e32 v128, v129
	v_rcp_f32_e32 v129, v135
	v_rcp_f32_e32 v132, v134
	v_rcp_f32_e32 v133, v159
	v_rcp_f32_e32 v159, v149
	v_mul_f32_e32 v128, v148, v128
	v_mul_f32_e32 v129, v148, v129
	v_mul_f32_e32 v134, v148, v130
	v_mul_f32_e32 v135, v148, v131
	v_mul_f32_e32 v132, v148, v132
	v_mul_f32_e32 v133, v148, v133
	v_mul_f32_e32 v158, v148, v158
	v_mul_f32_e32 v159, v148, v159
	v_lshl_add_u64 v[130:131], v[150:151], 0, v[152:153]
	s_cbranch_scc1 .LBB0_2774
	v_lshlrev_b64 v[172:173], 1, v[130:131]
	v_lshl_add_u64 v[168:169], s[18:19], 0, v[172:173]
	v_lshl_add_u64 v[172:173], s[8:9], 0, v[172:173]
	global_load_dwordx4 v[168:171], v[168:169], off
	s_waitcnt vmcnt(0)
	v_lshlrev_b32_e32 v176, 16, v168
	global_load_dwordx4 v[172:175], v[172:173], off
	v_and_b32_e32 v177, 0xffff0000, v168
	v_lshlrev_b32_e32 v168, 16, v169
	v_and_b32_e32 v169, 0xffff0000, v169
	v_lshlrev_b32_e32 v178, 16, v170
	v_and_b32_e32 v179, 0xffff0000, v170
	v_lshlrev_b32_e32 v170, 16, v171
	v_and_b32_e32 v171, 0xffff0000, v171
	s_waitcnt vmcnt(0)
	v_lshlrev_b32_e32 v149, 16, v172
	v_and_b32_e32 v167, 0xffff0000, v172
	v_lshlrev_b32_e32 v180, 16, v173
	v_and_b32_e32 v181, 0xffff0000, v173
	v_lshlrev_b32_e32 v182, 16, v174
	v_and_b32_e32 v183, 0xffff0000, v174
	v_lshlrev_b32_e32 v184, 16, v175
	v_and_b32_e32 v185, 0xffff0000, v175
	v_sub_f32_e32 v173, v167, v177
	v_sub_f32_e32 v172, v149, v176
	v_sub_f32_e32 v175, v181, v169
	v_sub_f32_e32 v174, v180, v168
	v_sub_f32_e32 v181, v183, v179
	v_sub_f32_e32 v180, v182, v178
	v_sub_f32_e32 v183, v185, v171
	v_sub_f32_e32 v182, v184, v170
	v_fma_f32 v128, v128, v174, v168
	v_fma_f32 v129, v129, v175, v169
	v_fma_f32 v134, v134, v172, v176
	v_fma_f32 v135, v135, v173, v177
	v_fma_f32 v132, v132, v182, v170
	v_fma_f32 v133, v133, v183, v171
	v_fma_f32 v158, v158, v180, v178
	v_fma_f32 v159, v159, v181, v179
; #define GAS __attribute__((address_space(1)))
; __device__ __forceinline__ float fsigmoid(float x) { return frcp(1.f + fexp2(-x * LOG2E)); }
;     __device__ __forceinline__ void operator()(const Acc& acc, const Unit& u, int wr, int wc, int fr, int fq) const {
;     ...
;         const float* bias = ldp(PL, t4 == 0 ? 17 : (t4 == 1 ? 20 : 31)) + (t4 < 2 ? idx * D : 0);
;         bf16_t* dst = W + (t4 == 0 ? 0L : (t4 == 1 ? (long)(32u << 20) : -(long)(32u << 20)));
;         const bf16_t* V = W - (long)(32u << 20);
;         const float osc = t4 == 0 ? 0.60653065971f : 1.f;
; #pragma unroll
;         for (int bj = 0; bj < 2; ++bj) {
;             const f32x4 b0 = *(const GAS f32x4*)(bias + colb + 128 * bj), b1 = *(const GAS f32x4*)(bias + colb + 128 * bj + 4);
; #pragma unroll
;             for (int ai = 0; ai < 2; ++ai)
; #pragma unroll
;                 for (int m = 0; m < 4; ++m) {
;                     const size_t off = (size_t)(row0 + ai * HALF + m * 16) * D + colb + 128 * bj;
;                     f32x4 v0_ = acc[ai][bj][m][0] + b0, v1_ = acc[ai][bj][m][1] + b1;
; #pragma unroll
;                     for (int j = 0; j < 4; ++j) { v0_[j] = fsigmoid(v0_[j]) * osc; v1_[j] = fsigmoid(v1_[j]) * osc; }
;                     if (t4 == 2) {
;                         f32x4 x0, x1, f0, f1; unpack8(*(const GAS u32x4*)(V + off), x0, x1); unpack8(*(const GAS u32x4*)(VF + off), f0, f1);
;                         v0_ = x0 + (f0 - x0) * v0_; v1_ = x1 + (f1 - x1) * v1_;
;                     }
;                     *(GAS u32x4*)(dst + off) = pack8(v0_, v1_);
.LBB0_2774:
	v_add_f32_e32 v120, v120, v104
	v_add_f32_e32 v121, v121, v105
	v_add_f32_e32 v124, v124, v108
	v_add_f32_e32 v125, v125, v109
	v_mul_f32_e32 v120, 0xbfb8aa3b, v120
	v_exp_f32_e32 v120, v120
	v_mul_f32_e32 v125, 0xbfb8aa3b, v125
	v_exp_f32_e32 v125, v125
	v_mul_f32_e32 v121, 0xbfb8aa3b, v121
	v_exp_f32_e32 v121, v121
	v_add_f32_e32 v120, 1.0, v120
	v_cvt_pk_bf16_f32 v170, v158, v159
	v_add_f32_e32 v126, v126, v110
	v_add_f32_e32 v127, v127, v111
	v_add_f32_e32 v122, v122, v106
	v_add_f32_e32 v123, v123, v107
	v_rcp_f32_e32 v158, v120
	v_add_f32_e32 v120, 1.0, v125
	v_rcp_f32_e32 v125, v120
	v_add_f32_e32 v120, 1.0, v121
	v_mul_f32_e32 v121, 0xbfb8aa3b, v126
	v_mul_f32_e32 v122, 0xbfb8aa3b, v122
	v_exp_f32_e32 v121, v121
	v_exp_f32_e32 v122, v122
	s_and_b64 s[38:39], s[4:5], exec
	v_rcp_f32_e32 v159, v120
	v_add_f32_e32 v120, 1.0, v121
	v_add_f32_e32 v121, 1.0, v122
	v_mul_f32_e32 v122, 0xbfb8aa3b, v127
	s_cselect_b32 s0, s68, 0xfe000000
	s_and_b64 s[38:39], vcc, exec
	v_mul_f32_e32 v124, 0xbfb8aa3b, v124
	v_exp_f32_e32 v126, v122
	v_rcp_f32_e32 v122, v121
	v_mul_f32_e32 v121, 0xbfb8aa3b, v123
	s_cselect_b32 s38, 0, s0
	s_or_b64 s[4:5], vcc, s[4:5]
	v_exp_f32_e32 v124, v124
	v_exp_f32_e32 v123, v121
	s_and_b64 s[4:5], s[4:5], exec
	s_cselect_b32 s39, 0, -1
	s_lshl_b64 s[4:5], s[38:39], 1
	s_add_u32 s38, s59, s4
	v_add_f32_e32 v124, 1.0, v124
	v_add_f32_e32 v123, 1.0, v123
	s_addc_u32 s39, s60, s5
	v_rcp_f32_e32 v124, v124
	v_add_f32_e32 v121, 1.0, v126
	v_rcp_f32_e32 v123, v123
	v_cvt_pk_bf16_f32 v168, v134, v135
	v_cvt_pk_bf16_f32 v169, v128, v129
	v_cvt_pk_bf16_f32 v171, v132, v133
	v_lshl_add_u64 v[132:133], v[130:131], 1, s[38:39]
	v_rcp_f32_e32 v120, v120
	v_rcp_f32_e32 v121, v121
	global_store_dwordx4 v[132:133], v[168:171], off
	v_or_b32_e32 v128, 16, v156
	v_mov_b32_e32 v149, v148
	v_ashrrev_i32_e32 v129, 31, v128
	v_mov_b32_e32 v126, v148
	v_mov_b32_e32 v127, v148
	v_lshlrev_b64 v[128:129], 10, v[128:129]
	v_mul_f32_e32 v134, v148, v124
	v_mul_f32_e32 v135, v149, v125
	v_mul_f32_e32 v124, v126, v122
	v_mul_f32_e32 v125, v127, v123
	v_cndmask_b32_e64 v122, 0, 1, s[40:41]
	v_mul_f32_e32 v120, v126, v120
	v_mul_f32_e32 v121, v127, v121
	v_mul_f32_e32 v158, v148, v158
	v_mul_f32_e32 v159, v149, v159
	v_cmp_ne_u32_e64 s[4:5], 1, v122
	s_andn2_b64 vcc, exec, s[40:41]
	v_lshl_add_u64 v[122:123], v[128:129], 0, v[152:153]
	s_cbranch_vccnz .LBB0_2776
	v_lshlrev_b64 v[172:173], 1, v[122:123]
	v_lshl_add_u64 v[168:169], s[18:19], 0, v[172:173]
	v_lshl_add_u64 v[172:173], s[8:9], 0, v[172:173]
	global_load_dwordx4 v[168:171], v[168:169], off
	s_waitcnt vmcnt(0)
	v_lshlrev_b32_e32 v176, 16, v168
	global_load_dwordx4 v[172:175], v[172:173], off
	v_and_b32_e32 v177, 0xffff0000, v168
	v_lshlrev_b32_e32 v168, 16, v169
	v_and_b32_e32 v169, 0xffff0000, v169
	v_lshlrev_b32_e32 v178, 16, v170
	v_and_b32_e32 v179, 0xffff0000, v170
	v_lshlrev_b32_e32 v170, 16, v171
	v_and_b32_e32 v171, 0xffff0000, v171
	s_waitcnt vmcnt(0)
	v_lshlrev_b32_e32 v167, 16, v172
	v_and_b32_e32 v172, 0xffff0000, v172
	v_lshlrev_b32_e32 v180, 16, v173
	v_and_b32_e32 v181, 0xffff0000, v173
	v_lshlrev_b32_e32 v182, 16, v174
	v_and_b32_e32 v183, 0xffff0000, v174
	v_lshlrev_b32_e32 v184, 16, v175
	v_and_b32_e32 v185, 0xffff0000, v175
	v_sub_f32_e32 v173, v172, v177
	v_sub_f32_e32 v172, v167, v176
	v_sub_f32_e32 v175, v181, v169
	v_sub_f32_e32 v174, v180, v168
	v_sub_f32_e32 v181, v183, v179
	v_sub_f32_e32 v180, v182, v178
	v_sub_f32_e32 v183, v185, v171
	v_sub_f32_e32 v182, v184, v170
	v_fma_f32 v120, v120, v174, v168
	v_fma_f32 v121, v121, v175, v169
	v_fma_f32 v134, v134, v172, v176
	v_fma_f32 v135, v135, v173, v177
	v_fma_f32 v124, v124, v182, v170
	v_fma_f32 v125, v125, v183, v171
	v_fma_f32 v158, v158, v180, v178
	v_fma_f32 v159, v159, v181, v179

; #define LAS __attribute__((address_space(3)))
; __device__ __forceinline__ void scan_phase2(LAS unsigned char* lds, const int wid, const bf16_t* R, const bf16_t* K, const bf16_t* V, const bf16_t* W, const bf16_t* A,
;                                             const float* k_k, const float* k_a, const float* r_k, bf16_t* Y, float* BON) {
;     ...
;                     const LAS unsigned char* Pb = lds + L_P + (c % 3) * P_SIZE;
;                     const LAS unsigned char* Qb = lds + L_Q + (c & 1) * Q_SIZE;
;                     bf16x8 sa[2];
; #pragma unroll
;                     for (int ks = 0; ks < 2; ++ks) sa[ks] = *(const LAS bf16x8*)(S16 + (l15 * 72 + 32 * ks + 8 * q) * 2);
;                     const s16x4 va = *(const LAS s16x4*)(Pb + P_VT + ((16 * wid + l15) * 20 + 4 * q) * 2);
;                     f32x4 X = {0.f, 0.f, 0.f, 0.f}, Yc = X;
; #pragma unroll
;                     for (int ks = 0; ks < 2; ++ks) {
;                         X = mfma32(sa[ks], *(const LAS bf16x8*)(Pb + P_AR + (l15 * 72 + 32 * ks + 8 * q) * 2), X);
;                         Yc = mfma32(sa[ks], *(const LAS bf16x8*)(Pb + P_AR + ((16 + l15) * 72 + 32 * ks + 8 * q) * 2), Yc);
;                     }
;                     X = mfma16(va, *(const LAS s16x4*)(Qb + Q_MKB + (l15 * 16 + 4 * q) * 2), X);
;                     Yc = mfma16(va, *(const LAS s16x4*)(Qb + Q_NKR + (l15 * 16 + 4 * q) * 2), Yc);
;                     MF_SETTLE(X);
; #pragma unroll
;                     for (int i = 0; i < 4; ++i) *(LAS bf16_t*)(XU + ((4 * q + i) * 20 + l15) * 2) = f2bf(X[i]);
;                     LDS_WAIT(); asm volatile("" ::: "memory");
;                     const s16x4 xa = *(const LAS s16x4*)(XU + (l15 * 20 + 4 * q) * 2);
;                     f32x4 U = mfma16(xa, *(const LAS s16x4*)(Qb + Q_TT + (l15 * 16 + 4 * q) * 2), (f32x4){0.f, 0.f, 0.f, 0.f});
;                     LDS_WAIT(); asm volatile("" ::: "memory");
;                     MF_SETTLE(U);
; #pragma unroll
;                     for (int i = 0; i < 4; ++i) *(LAS bf16_t*)(XU + ((4 * q + i) * 20 + l15) * 2) = f2bf(U[i]);
;                     LDS_WAIT(); asm volatile("" ::: "memory");
;                     const s16x4 ua = *(const LAS s16x4*)(XU + (l15 * 20 + 4 * q) * 2);
;                     Yc = mfma16(ua, *(const LAS s16x4*)(Qb + Q_NBR + (l15 * 16 + 4 * q) * 2), Yc);
;                     MF_SETTLE(Yc);
.LBB0_2875:
	s_add_i32 s0, s28, 2
	s_cmp_lt_u32 s0, 2
	s_cbranch_scc1 .LBB0_2874
	s_and_b32 s0, s28, 0xff
	s_mulk_i32 s0, 0xab
	s_lshr_b32 s0, s0, 9
	s_mul_i32 s0, s0, 3
	s_sub_i32 s0, s28, s0
	s_and_b32 s0, s0, 0xff
	s_mulk_i32 s0, 0x3e00
	s_add_i32 s0, s0, 0
	v_add_u32_e32 v24, s0, v83
	ds_read_b128 v[48:51], v118 offset:52736
	ds_read_b128 v[52:55], v118 offset:52800
	ds_read_b128 v[56:59], v24 offset:4608
	v_add_u32_e32 v45, s0, v72
	ds_read_b64 v[146:147], v45 offset:14336
	ds_read_b128 v[60:63], v24 offset:4672
	s_and_b32 s1, s54, 0x800
	s_waitcnt lgkmcnt(2)
	v_mfma_f32_16x16x32_bf16 v[56:59], v[48:51], v[56:59], 0
	v_add_u32_e32 v45, s1, v113
	ds_read2st64_b64 v[64:67], v45 offset0:93 offset1:95
	s_lshl_b64 s[56:57], s[28:29], 15
	s_waitcnt lgkmcnt(1)
	v_mfma_f32_16x16x32_bf16 v[56:59], v[52:55], v[60:63], v[56:59]
	ds_read_b128 v[60:63], v24 offset:6912
	ds_read_b128 v[142:145], v24 offset:6976
	v_add_u32_e32 v24, s66, v84
	s_waitcnt lgkmcnt(2)
	v_mfma_f32_16x16x16_bf16 v[56:59], v[146:147], v[64:65], v[56:59]
	s_waitcnt lgkmcnt(1)
	v_mfma_f32_16x16x32_bf16 v[48:51], v[48:51], v[60:63], 0
	v_add_u32_e32 v60, s0, v89
	s_nop 4
	v_cvt_pk_bf16_f32 v56, v56, s0
	v_cvt_pk_bf16_f32 v57, v57, s0
	ds_write_b16 v119, v56 offset:57344
	ds_write_b16 v24, v57 offset:57344
	v_cvt_pk_bf16_f32 v56, v58, s0
	ds_write_b16 v120, v56 offset:57344
	v_cvt_pk_bf16_f32 v56, v59, s0
	ds_write_b16 v121, v56 offset:57344
	s_waitcnt lgkmcnt(0)
	ds_read_b64 v[56:57], v122 offset:57344
	s_waitcnt lgkmcnt(5)
	v_mfma_f32_16x16x32_bf16 v[48:51], v[52:55], v[142:145], v[48:51]
	ds_read_b64 v[52:53], v45 offset:49152
	s_waitcnt lgkmcnt(0)
	s_waitcnt lgkmcnt(0)
	v_mfma_f32_16x16x16_bf16 v[52:55], v[56:57], v[52:53], 0
	v_mfma_f32_16x16x16_bf16 v[48:51], v[146:147], v[66:67], v[48:51]
	s_nop 6
	v_cvt_pk_bf16_f32 v52, v52, s0
	v_cvt_pk_bf16_f32 v53, v53, s0
	ds_write_b16 v119, v52 offset:57344
	ds_write_b16 v24, v53 offset:57344
	v_cvt_pk_bf16_f32 v24, v54, s0
	ds_write_b16 v120, v24 offset:57344
	v_cvt_pk_bf16_f32 v24, v55, s0
	ds_write_b16 v121, v24 offset:57344
	s_waitcnt lgkmcnt(0)
	ds_read_b64 v[52:53], v122 offset:57344
	v_add_u32_e32 v24, s0, v69
	v_add_u32_e32 v54, s0, v85
	ds_read_b32 v24, v24 offset:15616
	ds_read_b64 v[54:55], v54 offset:9216
	ds_read_b64 v[56:57], v45 offset:48128
	s_waitcnt lgkmcnt(0)
	v_mfma_f32_16x16x16_bf16 v[48:51], v[52:53], v[56:57], v[48:51]
	v_add_u32_e32 v45, s0, v86
	v_add_u32_e32 v57, s0, v88
	s_nop 5
	v_cvt_pk_bf16_f32 v48, v48, v49
	v_mfma_f32_16x16x16_bf16 v[8:11], v[52:53], v[54:55], v[8:11]
	ds_read_b64 v[54:55], v45 offset:9216
	v_add_u32_e32 v45, s0, v87
	v_cvt_pk_bf16_f32 v49, v50, v51
	v_lshl_add_u64 v[50:51], v[46:47], 0, s[56:57]
	ds_read_b32 v56, v45 offset:15616
	ds_read_b64 v[58:59], v57 offset:9216
	ds_read_b64 v[60:61], v60 offset:9216
	global_store_dwordx2 v[50:51], v[48:49], off
	v_add_u32_e32 v48, s0, v91
	ds_read_b64 v[48:49], v48 offset:9216
	s_waitcnt lgkmcnt(4)
	v_mfma_f32_16x16x16_bf16 v[8:11], v[146:147], v[54:55], v[8:11]
	v_add_u32_e32 v45, s0, v90
	v_add_u32_e32 v51, s0, v92
	v_add_u32_e32 v57, s0, v93
	s_waitcnt lgkmcnt(2)
	v_mfma_f32_16x16x16_bf16 v[12:15], v[52:53], v[58:59], v[12:15]
	ds_read_b32 v50, v45 offset:15616
	ds_read_b64 v[54:55], v51 offset:9216
	ds_read_b32 v58, v57 offset:15616
	v_mul_f32_e32 v10, v24, v10
	v_mul_f32_e32 v11, v24, v11
	v_mul_f32_e32 v8, v24, v8
	v_mul_f32_e32 v9, v24, v9
	s_waitcnt lgkmcnt(3)
	v_mfma_f32_16x16x16_bf16 v[4:7], v[52:53], v[48:49], v[4:7]
	v_add_u32_e32 v24, s0, v94
	ds_read_b64 v[48:49], v24 offset:9216
	v_add_u32_e32 v24, s0, v95
	v_mfma_f32_16x16x16_bf16 v[12:15], v[146:147], v[60:61], v[12:15]
	s_waitcnt lgkmcnt(2)
	v_mfma_f32_16x16x16_bf16 v[4:7], v[146:147], v[54:55], v[4:7]
	ds_read_b64 v[54:55], v24 offset:9216
	v_cvt_pk_bf16_f32 v24, v8, s0
	ds_write_b16 v123, v24 offset:52736
	v_cvt_pk_bf16_f32 v24, v9, s0
	ds_write_b16 v124, v24 offset:52736
	v_cvt_pk_bf16_f32 v24, v10, s0
	s_waitcnt lgkmcnt(3)
	v_mfma_f32_16x16x16_bf16 v[0:3], v[52:53], v[48:49], v[0:3]
	v_mul_f32_e64 v12, v56, v12
	v_mul_f32_e64 v13, v56, v13
	ds_write_b16 v125, v24 offset:52736
	v_cvt_pk_bf16_f32 v24, v11, s0
	ds_write_b16 v126, v24 offset:52736
	v_cvt_pk_bf16_f32 v24, v12, s0
	v_mul_f32_e32 v14, v56, v14
	v_mul_f32_e32 v15, v56, v15
	ds_write_b16 v127, v24 offset:52736
	v_cvt_pk_bf16_f32 v24, v13, s0
	ds_write_b16 v128, v24 offset:52736
	v_cvt_pk_bf16_f32 v24, v14, s0
	v_mul_f32_e32 v4, v50, v4
	v_mul_f32_e32 v5, v50, v5
	s_waitcnt lgkmcnt(6)
	v_mfma_f32_16x16x16_bf16 v[0:3], v[146:147], v[54:55], v[0:3]
	ds_write_b16 v129, v24 offset:52736
	v_cvt_pk_bf16_f32 v24, v15, s0
	ds_write_b16 v130, v24 offset:52736
	v_cvt_pk_bf16_f32 v24, v4, s0
	v_mul_f32_e32 v6, v50, v6
	v_mul_f32_e32 v7, v50, v7
	ds_write_b16 v131, v24 offset:52736
	v_cvt_pk_bf16_f32 v24, v5, s0
	ds_write_b16 v132, v24 offset:52736
	v_cvt_pk_bf16_f32 v24, v6, s0
	v_mul_f32_e32 v0, v58, v0
	v_mul_f32_e32 v1, v58, v1
	ds_write_b16 v133, v24 offset:52736
	v_cvt_pk_bf16_f32 v24, v7, s0
	ds_write_b16 v134, v24 offset:52736
	v_cvt_pk_bf16_f32 v24, v0, s0
	v_mul_f32_e32 v2, v58, v2
	v_mul_f32_e32 v3, v58, v3
	ds_write_b16 v135, v24 offset:52736
	v_cvt_pk_bf16_f32 v24, v1, s0
	ds_write_b16 v136, v24 offset:52736
	v_cvt_pk_bf16_f32 v24, v2, s0
	ds_write_b16 v137, v24 offset:52736
	v_cvt_pk_bf16_f32 v24, v3, s0
	ds_write_b16 v138, v24 offset:52736
	s_waitcnt lgkmcnt(0)
	s_branch .LBB0_2874

; #define LAS __attribute__((address_space(3)))
; __device__ __forceinline__ float fexp2(float x) { return __builtin_amdgcn_exp2f(x); }
; __device__ __forceinline__ float frcp(float x) { return __builtin_amdgcn_rcpf(x); }
; __device__ __forceinline__ f32x4 unpack4(const u32x2 w) { return (f32x4){bf_lo(w.x), bf_hi(w.x), bf_lo(w.y), bf_hi(w.y)}; }
; __device__ __forceinline__ void scan_phase2(LAS unsigned char* lds, const int wid, const bf16_t* R, const bf16_t* K, const bf16_t* V, const bf16_t* W, const bf16_t* A,
;                                             const float* k_k, const float* k_a, const float* r_k, bf16_t* Y, float* BON) {
;     ...
;                     kk = kk * (1.f / fmaxf(sqrtf(ss), 1e-12f));
;                     const f32x4 km = kx * (1.f + (ax - 1.f) * kap);
;                     const f32x4 rkm = rx * km * rkp;
;                     float bs = (rkm[0] + rkm[1]) + (rkm[2] + rkm[3]);
;                     bs = reduce16(bs);
;                     if (half == 0 && kq == 0) BON[(tokb + (size_t)it * CL + s) * 16 + h] = bs;
;                     const f32x4 cum = *(const LAS f32x4*)(lds + L_CE + (it & 1) * 4096 + (s * 64 + kq * 4) * 4);
;                     const f32x4 ews = unpack4(wr_);
;                     f32x4 e1, e2, ed;
; #pragma unroll
;                     for (int i = 0; i < 4; ++i) { e1[i] = fexp2(cum[i] * LOG2E); e2[i] = frcp(e1[i]); ed[i] = fexp2(ews[i] * LOG2E); }
;                     const f32x4 av = -kk, bv = kk * ax;
;                     const f32x4 bbar = bv * e1, kbar = km * e1, abar = av * (e2 * ed), rbar = rx * e2;
;                     *(LAS u32x2*)(Pb + P_BK + (s * 72 + kq * 4) * 2) = pack4(bbar);
;                     *(LAS u32x2*)(Pb + P_BK + ((16 + s) * 72 + kq * 4) * 2) = pack4(kbar);
;                     *(LAS u32x2*)(Pb + P_AR + (s * 72 + kq * 4) * 2) = pack4(abar);
;                     *(LAS u32x2*)(Pb + P_AR + ((16 + s) * 72 + kq * 4) * 2) = pack4(rbar);
; #pragma unroll
;                     for (int i = 0; i < 4; ++i) {
;                         *(LAS bf16_t*)(Pb + P_BKT + ((kq * 4 + i) * 40 + s) * 2) = f2bf(bbar[i]);
;                         *(LAS bf16_t*)(Pb + P_BKT + ((kq * 4 + i) * 40 + 16 + s) * 2) = f2bf(kbar[i]);
;                     }
;                     if (s == 15) *(LAS f32x4*)(Pb + P_LAM + kq * 16) = e2;
.LBB0_2904:
	s_or_b64 exec, exec, s[24:25]
	v_add_f32_e32 v24, v24, v45
	v_mul_f32_e32 v45, 0x4f800000, v24
	v_cmp_gt_f32_e32 vcc, s83, v24
	s_mul_i32 s0, s89, 0xab
	s_bfe_u32 s0, s0, 0x70009
	v_cndmask_b32_e32 v24, v24, v45, vcc
	v_sqrt_f32_e32 v45, v24
	s_mul_i32 s0, s0, 3
	s_sub_i32 s0, s89, s0
	s_and_b32 s0, s0, 0xff
	v_add_u32_e32 v142, -1, v45
	v_fma_f32 v143, -v142, v45, v24
	v_cmp_ge_f32_e64 s[24:25], 0, v143
	v_add_u32_e32 v143, 1, v45
	s_mulk_i32 s0, 0x3e00
	v_cndmask_b32_e64 v142, v45, v142, s[24:25]
	v_fma_f32 v45, -v143, v45, v24
	v_cmp_lt_f32_e64 s[24:25], 0, v45
	s_add_i32 s90, s0, 0
	s_and_b32 s0, s28, 0x1000
	v_cndmask_b32_e64 v45, v142, v143, s[24:25]
	v_mul_f32_e32 v142, 0x37800000, v45
	v_cndmask_b32_e32 v45, v45, v142, vcc
	v_cmp_class_f32_e32 vcc, v24, v140
	s_waitcnt vmcnt(0)
	v_and_b32_e32 v151, 0xffff0000, v54
	v_lshlrev_b32_e32 v141, 16, v54
	v_cndmask_b32_e32 v24, v45, v24, vcc
	v_max_f32_e32 v24, 0x2b8cbccc, v24
	v_div_scale_f32 v45, s[24:25], v24, v24, 1.0
	v_rcp_f32_e32 v146, v45
	v_lshlrev_b32_e32 v152, 16, v55
	v_and_b32_e32 v153, 0xffff0000, v55
	v_fma_f32 v142, -v45, v146, 1.0
	v_fmac_f32_e32 v146, v142, v146
	v_div_scale_f32 v142, vcc, 1.0, v24, 1.0
	v_mul_f32_e32 v147, v142, v146
	v_fma_f32 v143, -v45, v147, v142
	v_fmac_f32_e32 v147, v143, v146
	v_fma_f32 v45, -v45, v147, v142
	v_add_u32_e32 v142, s0, v23
	ds_read_b128 v[142:145], v142 offset:58624
	v_div_fmas_f32 v45, v45, v146, v147
	v_div_fixup_f32 v24, v45, v24, 1.0
	v_mul_f32_e32 v146, v12, v24
	v_mul_f32_e32 v147, v13, v24
	v_mul_f32_e32 v148, v14, v24
	v_mul_f32_e32 v149, v15, v24
	s_waitcnt lgkmcnt(0)
	v_mul_f32_e32 v12, 0x3fb8aa3b, v142
	v_mul_f32_e32 v14, 0x3fb8aa3b, v151
	v_exp_f32_e32 v142, v12
	v_mul_f32_e32 v12, 0x3fb8aa3b, v143
	v_mul_f32_e32 v15, 0x3fb8aa3b, v144
	v_exp_f32_e32 v151, v14
	v_mul_f32_e32 v14, 0x3fb8aa3b, v145
	v_exp_f32_e32 v143, v12
	v_exp_f32_e32 v144, v15
	v_exp_f32_e32 v145, v14
	v_mul_f32_e32 v13, 0x3fb8aa3b, v141
	v_mul_f32_e32 v15, 0x3fb8aa3b, v152
	v_mul_f32_e32 v24, 0x3fb8aa3b, v153
	v_rcp_f32_e32 v12, v142
	v_exp_f32_e32 v150, v13
	v_rcp_f32_e32 v13, v143
	v_rcp_f32_e32 v14, v144
	v_exp_f32_e32 v152, v15
	v_rcp_f32_e32 v15, v145
	v_exp_f32_e32 v153, v24
	v_mul_f32_e32 v60, v148, v60
	v_mul_f32_e32 v61, v149, v61
	v_mul_f32_e32 v62, v146, v62
	v_mul_f32_e32 v63, v147, v63
	v_mul_f32_e32 v60, v60, v142
	v_mul_f32_e32 v61, v61, v143
	v_mul_f32_e32 v62, v62, v144
	v_mul_f32_e32 v63, v63, v145
	v_mul_f32_e32 v64, v64, v144
	v_mul_f32_e32 v65, v65, v145
	v_mul_f32_e32 v66, v66, v142
	v_mul_f32_e32 v67, v67, v143
	v_mul_f32_e32 v142, v150, v12
	v_mul_f32_e32 v143, v151, v13
	v_mul_f32_e32 v144, v152, v14
	v_mul_f32_e32 v145, v153, v15
	v_mul_f32_e64 v142, v142, -v148
	v_mul_f32_e64 v143, v143, -v149
	v_mul_f32_e64 v144, v144, -v146
	v_mul_f32_e64 v145, v145, -v147
	v_mul_f32_e32 v58, v14, v58
	v_mul_f32_e32 v59, v15, v59
	v_mul_f32_e32 v56, v12, v56
	v_mul_f32_e32 v57, v13, v57
	v_cvt_pk_bf16_f32 v146, v60, v61
	v_cvt_pk_bf16_f32 v147, v62, v63
	v_add_u32_e32 v24, s90, v70
	ds_write_b64 v24, v[146:147]
	v_cvt_pk_bf16_f32 v146, v66, v67
	v_cvt_pk_bf16_f32 v147, v64, v65
	v_add_u32_e32 v45, s90, v71
	v_cvt_pk_bf16_f32 v142, v142, v143
	v_cvt_pk_bf16_f32 v143, v144, v145
	v_cvt_pk_bf16_f32 v56, v56, v57
	v_cvt_pk_bf16_f32 v57, v58, v59
	ds_write_b64 v45, v[146:147]
	ds_write_b64 v24, v[142:143] offset:4608
	ds_write_b64 v45, v[56:57] offset:4608
	v_cvt_pk_bf16_f32 v24, v60, s0
	v_add_u32_e32 v45, s90, v75
	ds_write_b16 v45, v24 offset:9216
	v_cvt_pk_bf16_f32 v24, v66, s0
	v_add_u32_e32 v45, s90, v76
	ds_write_b16 v45, v24 offset:9216
	v_cvt_pk_bf16_f32 v24, v61, s0
	v_add_u32_e32 v45, s90, v77
	ds_write_b16 v45, v24 offset:9216
	v_cvt_pk_bf16_f32 v24, v67, s0
	v_add_u32_e32 v45, s90, v78
	ds_write_b16 v45, v24 offset:9216
	v_cvt_pk_bf16_f32 v24, v62, s0
	v_add_u32_e32 v45, s90, v79
	ds_write_b16 v45, v24 offset:9216
	v_cvt_pk_bf16_f32 v24, v64, s0
	v_add_u32_e32 v45, s90, v80
	ds_write_b16 v45, v24 offset:9216
	v_cvt_pk_bf16_f32 v24, v63, s0
	v_add_u32_e32 v45, s90, v81
	ds_write_b16 v45, v24 offset:9216
	v_cvt_pk_bf16_f32 v24, v65, s0
	v_add_u32_e32 v45, s90, v82
	ds_write_b16 v45, v24 offset:9216
	s_and_saveexec_b64 s[24:25], s[2:3]
	v_add_u32_e32 v24, s90, v22
	ds_write_b128 v24, v[12:15] offset:15616
	s_or_b64 exec, exec, s[24:25]

; #define GAS __attribute__((address_space(1)))
;     __device__ __forceinline__ void operator()(const Acc& acc, const Unit& u, int wr, int wc, int fr, int fq) const {
;     ...
;                 const int row = row0 + ai * HALF + m * 16;
;                 const size_t off = (size_t)row * D + colb;
;                 f32x4 y[2][2], v[2][2];
; #pragma unroll
;                 for (int bj = 0; bj < 2; ++bj) { unpack8(*(const GAS u32x4*)(Y + off + 32 * bj), y[bj][0], y[bj][1]); unpack8(*(const GAS u32x4*)(V + off + 32 * bj), v[bj][0], v[bj][1]); }
;                 const float bs = BON[(size_t)row * 16 + head];
;                 float s = 0.f;
; #pragma unroll
;                 for (int bj = 0; bj < 2; ++bj)
; #pragma unroll
;                     for (int n = 0; n < 2; ++n) s += (y[bj][n][0] + y[bj][n][1]) + (y[bj][n][2] + y[bj][n][3]);
;                 s += __shfl_xor(s, 16); s += __shfl_xor(s, 32);
;                 const float mean = s * (1.f / 64.f);
;                 float q = 0.f;
; #pragma unroll
;                 for (int bj = 0; bj < 2; ++bj)
; #pragma unroll
;                     for (int n = 0; n < 2; ++n) { y[bj][n] = y[bj][n] - mean; q += (y[bj][n][0] * y[bj][n][0] + y[bj][n][1] * y[bj][n][1]) + (y[bj][n][2] * y[bj][n][2] + y[bj][n][3] * y[bj][n][3]); }
;                 q += __shfl_xor(q, 16); q += __shfl_xor(q, 32);
;                 const float rs = rsqrtf(q * (1.f / 64.f) + 64e-5f);
.LBB0_2975:
	s_lshl_b32 s0, s35, 2
	v_mov_b32_e32 v140, v153
	s_or_b32 s38, s0, s70
	s_lshl_b32 s0, s34, 8
	s_add_i32 s0, s0, s71
	v_and_or_b32 v146, v140, 15, s0
	v_ashrrev_i32_e32 v140, 1, v140
	v_and_b32_e32 v140, -8, v140
	v_lshl_add_u32 v144, s38, 6, v140
	v_ashrrev_i32_e32 v147, 31, v146
	v_ashrrev_i32_e32 v145, 31, v144
	v_lshlrev_b64 v[140:141], 10, v[146:147]
	v_lshl_add_u64 v[140:141], v[140:141], 0, v[144:145]
	v_lshlrev_b64 v[148:149], 1, v[140:141]
	v_lshl_add_u64 v[140:141], s[10:11], 0, v[148:149]
	global_load_dwordx4 v[162:165], v[140:141], off offset:64
	global_load_dwordx4 v[166:169], v[140:141], off
	v_lshlrev_b64 v[140:141], 6, v[146:147]
	s_ashr_i32 s39, s38, 31
	v_lshlrev_b64 v[142:143], 2, v[144:145]
	s_lshl_b64 s[34:35], s[38:39], 2
	v_lshl_add_u64 v[150:151], s[14:15], 0, v[140:141]
	v_lshl_add_u64 v[140:141], s[16:17], 0, v[142:143]
	v_lshl_add_u64 v[182:183], s[12:13], 0, v[148:149]
	v_lshl_add_u64 v[142:143], s[18:19], 0, v[142:143]
	global_load_dwordx4 v[170:173], v[182:183], off
	v_lshl_add_u64 v[150:151], v[150:151], 0, s[34:35]
	s_waitcnt vmcnt(0)
	v_lshlrev_b32_e32 v186, 16, v162
	v_lshlrev_b32_e32 v199, 16, v167
	v_lshlrev_b32_e32 v198, 16, v166
	v_and_b32_e32 v185, 0xffff0000, v167
	v_and_b32_e32 v184, 0xffff0000, v166
	v_lshlrev_b32_e32 v201, 16, v169
	v_lshlrev_b32_e32 v200, 16, v168
	v_and_b32_e32 v203, 0xffff0000, v169
	v_and_b32_e32 v202, 0xffff0000, v168
	v_and_b32_e32 v187, 0xffff0000, v162
	v_lshlrev_b32_e32 v188, 16, v163
	v_and_b32_e32 v189, 0xffff0000, v163
	v_lshlrev_b32_e32 v190, 16, v164
	v_and_b32_e32 v192, 0xffff0000, v164
	v_lshlrev_b32_e32 v194, 16, v165
	v_and_b32_e32 v196, 0xffff0000, v165
	v_add_f32_e32 v162, v198, v184
	v_add_f32_e32 v163, v199, v185
	v_add_f32_e32 v164, v200, v202
	v_add_f32_e32 v165, v201, v203
	v_add_f32_e32 v147, v162, v163
	v_add_f32_e32 v162, v164, v164
	v_add_f32_e32 v163, v164, v165
	v_add_f32_e32 v195, v186, v187
	v_add_f32_e32 v197, v188, v189
	v_add_f32_e32 v193, 0, v147
	v_mov_b32_e32 v191, v163
	v_add_f32_e32 v164, v194, v196
	v_add_f32_e32 v165, v195, v197
	v_add_f32_e32 v162, v190, v192
	v_add_f32_e32 v163, v191, v193
	s_nop 0
	v_add_f32_e32 v162, v162, v164
	v_add_f32_e32 v163, v163, v165
	s_nop 0
	v_add_f32_e32 v147, v162, v163
	global_load_dwordx4 v[162:165], v[140:141], off offset:16
	global_load_dwordx4 v[166:169], v[140:141], off
	global_load_dwordx4 v[174:177], v[142:143], off offset:16
	global_load_dwordx4 v[178:181], v[142:143], off
	ds_bpermute_b32 v161, v154, v147
	flat_load_dword v150, v[150:151]
	s_waitcnt lgkmcnt(0)
	v_add_f32_e32 v147, v147, v161
	ds_bpermute_b32 v161, v155, v147
	s_waitcnt lgkmcnt(0)
	v_add_f32_e32 v147, v147, v161
	v_fmac_f32_e32 v184, 0xbc800000, v147
	v_fmac_f32_e32 v185, 0xbc800000, v147
	v_fmac_f32_e32 v199, 0xbc800000, v147
	v_fmac_f32_e32 v202, 0xbc800000, v147
	v_fmac_f32_e32 v203, 0xbc800000, v147
	v_fmac_f32_e32 v201, 0xbc800000, v147
	v_fmac_f32_e32 v198, 0xbc800000, v147
	v_fmac_f32_e32 v200, 0xbc800000, v147
	v_fmac_f32_e32 v186, 0xbc800000, v147
	v_fmac_f32_e32 v188, 0xbc800000, v147
	v_mov_b32_e32 v204, v199
	v_mov_b32_e32 v205, v185
	v_mov_b32_e32 v199, v184
	v_mov_b32_e32 v206, v201
	v_mov_b32_e32 v207, v203
	v_mov_b32_e32 v201, v202
	v_fmac_f32_e32 v187, 0xbc800000, v147
	v_fmac_f32_e32 v189, 0xbc800000, v147
	v_mul_f32_e32 v184, v186, v186
	v_mul_f32_e32 v202, v188, v188
	v_mul_f32_e32 v208, v204, v204
	v_mul_f32_e32 v209, v205, v205
	v_mul_f32_e32 v210, v198, v198
	v_mul_f32_e32 v211, v199, v199
	v_mul_f32_e32 v212, v206, v206
	v_mul_f32_e32 v213, v207, v207
	v_mul_f32_e32 v214, v200, v200
	v_mul_f32_e32 v215, v201, v201
	v_fmac_f32_e32 v192, 0xbc800000, v147
	v_fmac_f32_e32 v190, 0xbc800000, v147
	v_fma_f32 v185, v187, v187, v184
	v_fma_f32 v184, v186, v186, v184
	v_fma_f32 v203, v189, v189, v202
	v_fma_f32 v202, v188, v188, v202
	v_pk_mov_b32 v[216:217], v[210:211], v[208:209] op_sel:[1,0]
	v_mov_b32_e32 v211, v209
	v_pk_mov_b32 v[208:209], v[214:215], v[212:213] op_sel:[1,0]
	v_mov_b32_e32 v215, v213
	v_mul_f32_e32 v184, v190, v190
	v_mul_f32_e32 v202, v192, v192
	v_add_f32_e32 v210, v216, v210
	v_add_f32_e32 v211, v217, v211
	v_add_f32_e32 v208, v208, v214
	v_add_f32_e32 v209, v209, v215
	v_fmac_f32_e32 v196, 0xbc800000, v147
	v_fmac_f32_e32 v194, 0xbc800000, v147
	v_add_f32_e32 v184, v184, v202
	v_add_f32_e32 v185, v185, v203
	v_add_f32_e32 v202, v210, v210
	v_add_f32_e32 v203, v210, v211
	v_add_f32_e32 v209, v208, v209
	v_add_f32_e32 v208, v208, v208
	v_mul_f32_e32 v202, v194, v194
	v_mul_f32_e32 v208, v196, v196
	v_add_f32_e32 v202, v202, v208
	v_add_f32_e32 v203, v203, v209
	v_lshlrev_b32_e32 v208, 16, v172
	v_add_f32_e32 v184, v184, v202
	v_add_f32_e32 v185, v185, v203
	v_lshlrev_b32_e32 v202, 16, v170
	v_add_f32_e32 v147, v184, v185
	ds_bpermute_b32 v151, v154, v147
	v_and_b32_e32 v203, 0xffff0000, v170
	v_lshlrev_b32_e32 v170, 16, v171
	v_and_b32_e32 v171, 0xffff0000, v171
	v_and_b32_e32 v209, 0xffff0000, v172
	s_waitcnt lgkmcnt(0)
	v_add_f32_e32 v147, v147, v151
	ds_bpermute_b32 v151, v155, v147
	v_lshlrev_b32_e32 v172, 16, v173
	v_and_b32_e32 v173, 0xffff0000, v173
	global_load_dwordx4 v[182:185], v[182:183], off offset:64
	v_mov_b32_e32 v191, v192
	s_waitcnt lgkmcnt(0)
	v_add_f32_e32 v147, v147, v151
	v_fmamk_f32 v147, v147, 0x3c800000, v160
	v_mul_f32_e32 v151, 0x4b800000, v147
	v_cmp_gt_f32_e32 vcc, s78, v147
	v_mov_b32_e32 v195, v196
	s_nop 0
	v_cndmask_b32_e32 v147, v147, v151, vcc
	v_rsq_f32_e32 v147, v147
	s_nop 0
	v_mul_f32_e32 v151, 0x45800000, v147
	v_cndmask_b32_e32 v210, v147, v151, vcc
	v_mul_f32_e32 v198, v198, v210
	v_mul_f32_e32 v199, v199, v210
	v_mul_f32_e32 v204, v204, v210
	v_mul_f32_e32 v205, v205, v210
	v_mul_f32_e32 v200, v200, v210
	v_mul_f32_e32 v201, v201, v210
	v_mul_f32_e32 v206, v206, v210
	v_mul_f32_e32 v207, v207, v210
	s_waitcnt vmcnt(0)
; #define GAS __attribute__((address_space(1)))
;     __device__ __forceinline__ void operator()(const Acc& acc, const Unit& u, int wr, int wc, int fr, int fq) const {
;     ...
;                 const int row = row0 + ai * HALF + m * 16;
;                 const size_t off = (size_t)row * D + colb;
;                 f32x4 y[2][2], v[2][2];
; #pragma unroll
;                 for (int bj = 0; bj < 2; ++bj) { unpack8(*(const GAS u32x4*)(Y + off + 32 * bj), y[bj][0], y[bj][1]); unpack8(*(const GAS u32x4*)(V + off + 32 * bj), v[bj][0], v[bj][1]); }
;                 const float bs = BON[(size_t)row * 16 + head];
;                 float s = 0.f;
; #pragma unroll
;                 for (int bj = 0; bj < 2; ++bj)
; #pragma unroll
;                     for (int n = 0; n < 2; ++n) s += (y[bj][n][0] + y[bj][n][1]) + (y[bj][n][2] + y[bj][n][3]);
;                 s += __shfl_xor(s, 16); s += __shfl_xor(s, 32);
;                 const float mean = s * (1.f / 64.f);
;                 float q = 0.f;
; #pragma unroll
;                 for (int bj = 0; bj < 2; ++bj)
; #pragma unroll
;                     for (int n = 0; n < 2; ++n) { y[bj][n] = y[bj][n] - mean; q += (y[bj][n][0] * y[bj][n][0] + y[bj][n][1] * y[bj][n][1]) + (y[bj][n][2] * y[bj][n][2] + y[bj][n][3] * y[bj][n][3]); }
;                 q += __shfl_xor(q, 16); q += __shfl_xor(q, 32);
;                 const float rs = rsqrtf(q * (1.f / 64.f) + 64e-5f);
; #pragma unroll
;                 for (int bj = 0; bj < 2; ++bj) {
;                     f32x4 o[2];
; #pragma unroll
;                     for (int n = 0; n < 2; ++n) {
;                         const f32x4 lw = *(const GAS f32x4*)(ln_w + colb + 32 * bj + 4 * n), lb = *(const GAS f32x4*)(ln_b + colb + 32 * bj + 4 * n);
;                         o[n] = (y[bj][n] * rs * lw + lb + v[bj][n] * bs) * acc[ai][bj][m][n];
;                     }
;                     *(GAS u32x4*)(YG + off + 32 * bj) = pack8(o[0], o[1]);
;                 }
;                 asm volatile("" ::: "memory");
	v_fma_f32 v168, v168, v204, v180
	v_fma_f32 v169, v169, v205, v181
	v_fma_f32 v166, v166, v198, v178
	v_fma_f32 v167, v167, v199, v179
	v_fma_f32 v164, v164, v206, v176
	v_fma_f32 v165, v165, v207, v177
	v_fma_f32 v162, v162, v200, v174
	v_fma_f32 v163, v163, v201, v175
	v_fma_f32 v166, v150, v202, v166
	v_fma_f32 v167, v150, v203, v167
	v_fma_f32 v168, v150, v170, v168
	v_fma_f32 v169, v150, v171, v169
	v_fma_f32 v162, v150, v208, v162
	v_fma_f32 v163, v150, v209, v163
	v_fma_f32 v164, v150, v172, v164
	v_fma_f32 v165, v150, v173, v165
	v_mul_f32_e32 v126, v126, v168
	v_mul_f32_e32 v127, v127, v169
	v_mul_f32_e32 v124, v124, v166
	v_mul_f32_e32 v125, v125, v167
	v_mul_f32_e32 v164, v122, v164
	v_mul_f32_e32 v165, v123, v165
	v_mul_f32_e32 v122, v120, v162
	v_mul_f32_e32 v123, v121, v163
	v_cvt_pk_bf16_f32 v120, v124, v125
	v_cvt_pk_bf16_f32 v121, v126, v127
	v_cvt_pk_bf16_f32 v122, v122, v123
	v_cvt_pk_bf16_f32 v123, v164, v165
	v_lshl_add_u64 v[170:171], s[20:21], 0, v[148:149]
	global_store_dwordx4 v[170:171], v[120:123], off
	global_load_dwordx4 v[120:123], v[142:143], off offset:128
	s_nop 0
	global_load_dwordx4 v[124:127], v[140:141], off offset:128
	global_load_dwordx4 v[162:165], v[140:141], off offset:144
	global_load_dwordx4 v[166:169], v[142:143], off offset:144
	v_or_b32_e32 v172, 16, v146
	v_ashrrev_i32_e32 v173, 31, v172
	v_lshlrev_b64 v[148:149], 10, v[172:173]
	v_lshl_add_u64 v[148:149], v[148:149], 0, v[144:145]
	v_lshlrev_b64 v[148:149], 1, v[148:149]
	v_lshl_add_u64 v[174:175], s[10:11], 0, v[148:149]
	v_lshlrev_b32_e32 v176, 16, v182
	v_and_b32_e32 v177, 0xffff0000, v182
	v_lshlrev_b32_e32 v178, 16, v183
	v_and_b32_e32 v179, 0xffff0000, v183
	v_lshlrev_b32_e32 v180, 16, v184
	v_and_b32_e32 v181, 0xffff0000, v184
	v_lshlrev_b32_e32 v182, 16, v185
	v_and_b32_e32 v183, 0xffff0000, v185
	v_mul_f32_e32 v184, v186, v210
	v_mul_f32_e32 v185, v187, v210
	v_mul_f32_e32 v186, v188, v210
	v_mul_f32_e32 v187, v189, v210
	v_mul_f32_e32 v188, v190, v210
	v_mul_f32_e32 v189, v191, v210
	v_mul_f32_e32 v190, v194, v210
	v_mul_f32_e32 v191, v195, v210
	s_waitcnt vmcnt(2)
	v_fma_f32 v122, v126, v186, v122
	v_fma_f32 v123, v127, v187, v123
	v_fma_f32 v120, v124, v184, v120
	v_fma_f32 v121, v125, v185, v121
	s_waitcnt vmcnt(0)
	v_fma_f32 v124, v164, v190, v168
	v_fma_f32 v125, v165, v191, v169
	v_fma_f32 v126, v162, v188, v166
	v_fma_f32 v127, v163, v189, v167
	v_fma_f32 v120, v150, v176, v120
	v_fma_f32 v121, v150, v177, v121
	v_fma_f32 v122, v150, v178, v122
	v_fma_f32 v123, v150, v179, v123
	v_fma_f32 v126, v150, v180, v126
	v_fma_f32 v127, v150, v181, v127
	v_fma_f32 v124, v150, v182, v124
	v_fma_f32 v125, v150, v183, v125
	v_mul_f32_e32 v118, v118, v122
	v_mul_f32_e32 v119, v119, v123
	v_mul_f32_e32 v116, v116, v120
	v_mul_f32_e32 v117, v117, v121
	v_mul_f32_e32 v120, v114, v124
	v_mul_f32_e32 v121, v115, v125
	v_mul_f32_e32 v114, v112, v126
	v_mul_f32_e32 v115, v113, v127
	v_cvt_pk_bf16_f32 v112, v116, v117
	v_cvt_pk_bf16_f32 v113, v118, v119
	v_cvt_pk_bf16_f32 v114, v114, v115
	v_cvt_pk_bf16_f32 v115, v120, v121
	global_store_dwordx4 v[170:171], v[112:115], off offset:64
	global_load_dwordx4 v[120:123], v[174:175], off offset:64
	global_load_dwordx4 v[162:165], v[174:175], off
	v_lshlrev_b64 v[112:113], 6, v[172:173]
	v_lshl_add_u64 v[178:179], s[14:15], 0, v[112:113]
	v_lshl_add_u64 v[180:181], s[12:13], 0, v[148:149]
	global_load_dwordx4 v[112:115], v[180:181], off
	v_lshl_add_u64 v[178:179], v[178:179], 0, s[34:35]
	s_waitcnt vmcnt(2)
	v_lshlrev_b32_e32 v116, 16, v120
	s_waitcnt vmcnt(1)
	v_lshlrev_b32_e32 v151, 16, v163
	v_lshlrev_b32_e32 v150, 16, v162
	v_and_b32_e32 v183, 0xffff0000, v163
	v_and_b32_e32 v182, 0xffff0000, v162
	v_lshlrev_b32_e32 v185, 16, v165
	v_lshlrev_b32_e32 v184, 16, v164
	v_and_b32_e32 v187, 0xffff0000, v165
	v_and_b32_e32 v186, 0xffff0000, v164
	v_add_f32_e32 v162, v150, v182
	v_add_f32_e32 v163, v151, v183
	v_add_f32_e32 v164, v184, v186
	v_add_f32_e32 v165, v185, v187
	v_and_b32_e32 v117, 0xffff0000, v120
	v_lshlrev_b32_e32 v118, 16, v121
	v_and_b32_e32 v119, 0xffff0000, v121
	v_add_f32_e32 v121, v162, v163
	v_add_f32_e32 v162, v164, v164
	v_add_f32_e32 v163, v164, v165
	v_lshlrev_b32_e32 v120, 16, v122
	v_and_b32_e32 v124, 0xffff0000, v122
	v_lshlrev_b32_e32 v122, 16, v123
	v_and_b32_e32 v126, 0xffff0000, v123
	v_add_f32_e32 v123, v116, v117
	v_add_f32_e32 v127, v118, v119
	v_add_f32_e32 v125, 0, v121
	v_mov_b32_e32 v121, v163
	v_add_f32_e32 v164, v122, v126
	v_add_f32_e32 v165, v123, v127
	v_add_f32_e32 v162, v120, v124
	v_add_f32_e32 v163, v121, v125
	s_nop 0
	v_add_f32_e32 v162, v162, v164
	v_add_f32_e32 v163, v163, v165
	s_nop 0
	v_add_f32_e32 v121, v162, v163
	global_load_dwordx4 v[162:165], v[140:141], off offset:16
	global_load_dwordx4 v[166:169], v[140:141], off
	global_load_dwordx4 v[170:173], v[142:143], off offset:16
	global_load_dwordx4 v[174:177], v[142:143], off
	flat_load_dword v188, v[178:179]
	ds_bpermute_b32 v123, v154, v121
	s_waitcnt lgkmcnt(0)
	v_add_f32_e32 v121, v121, v123
	ds_bpermute_b32 v123, v155, v121
	s_waitcnt lgkmcnt(0)
; #define GAS __attribute__((address_space(1)))
;     __device__ __forceinline__ void operator()(const Acc& acc, const Unit& u, int wr, int wc, int fr, int fq) const {
;     ...
;                 const int row = row0 + ai * HALF + m * 16;
;                 const size_t off = (size_t)row * D + colb;
;                 f32x4 y[2][2], v[2][2];
; #pragma unroll
;                 for (int bj = 0; bj < 2; ++bj) { unpack8(*(const GAS u32x4*)(Y + off + 32 * bj), y[bj][0], y[bj][1]); unpack8(*(const GAS u32x4*)(V + off + 32 * bj), v[bj][0], v[bj][1]); }
;                 const float bs = BON[(size_t)row * 16 + head];
;                 float s = 0.f;
; #pragma unroll
;                 for (int bj = 0; bj < 2; ++bj)
; #pragma unroll
;                     for (int n = 0; n < 2; ++n) s += (y[bj][n][0] + y[bj][n][1]) + (y[bj][n][2] + y[bj][n][3]);
;                 s += __shfl_xor(s, 16); s += __shfl_xor(s, 32);
;                 const float mean = s * (1.f / 64.f);
;                 float q = 0.f;
; #pragma unroll
;                 for (int bj = 0; bj < 2; ++bj)
; #pragma unroll
;                     for (int n = 0; n < 2; ++n) { y[bj][n] = y[bj][n] - mean; q += (y[bj][n][0] * y[bj][n][0] + y[bj][n][1] * y[bj][n][1]) + (y[bj][n][2] * y[bj][n][2] + y[bj][n][3] * y[bj][n][3]); }
;                 q += __shfl_xor(q, 16); q += __shfl_xor(q, 32);
;                 const float rs = rsqrtf(q * (1.f / 64.f) + 64e-5f);
; #pragma unroll
;                 for (int bj = 0; bj < 2; ++bj) {
;                     f32x4 o[2];
; #pragma unroll
;                     for (int n = 0; n < 2; ++n) {
;                         const f32x4 lw = *(const GAS f32x4*)(ln_w + colb + 32 * bj + 4 * n), lb = *(const GAS f32x4*)(ln_b + colb + 32 * bj + 4 * n);
;                         o[n] = (y[bj][n] * rs * lw + lb + v[bj][n] * bs) * acc[ai][bj][m][n];
;                     }
;                     *(GAS u32x4*)(YG + off + 32 * bj) = pack8(o[0], o[1]);
;                 }
;                 asm volatile("" ::: "memory");
	v_add_f32_e32 v121, v121, v123
	v_fmac_f32_e32 v182, 0xbc800000, v121
	v_fmac_f32_e32 v183, 0xbc800000, v121
	v_fmac_f32_e32 v151, 0xbc800000, v121
	v_fmac_f32_e32 v186, 0xbc800000, v121
	v_fmac_f32_e32 v187, 0xbc800000, v121
	v_fmac_f32_e32 v185, 0xbc800000, v121
	v_fmac_f32_e32 v150, 0xbc800000, v121
	v_fmac_f32_e32 v184, 0xbc800000, v121
	v_fmac_f32_e32 v116, 0xbc800000, v121
	v_fmac_f32_e32 v118, 0xbc800000, v121
	v_mov_b32_e32 v190, v151
	v_mov_b32_e32 v191, v183
	v_mov_b32_e32 v151, v182
	v_mov_b32_e32 v182, v185
	v_mov_b32_e32 v183, v187
	v_mov_b32_e32 v185, v186
	v_fmac_f32_e32 v117, 0xbc800000, v121
	v_fmac_f32_e32 v119, 0xbc800000, v121
	v_mul_f32_e32 v178, v116, v116
	v_mul_f32_e32 v186, v118, v118
	v_mul_f32_e32 v192, v190, v190
	v_mul_f32_e32 v193, v191, v191
	v_mul_f32_e32 v194, v150, v150
	v_mul_f32_e32 v195, v151, v151
	v_mul_f32_e32 v196, v182, v182
	v_mul_f32_e32 v197, v183, v183
	v_mul_f32_e32 v198, v184, v184
	v_mul_f32_e32 v199, v185, v185
	v_fmac_f32_e32 v124, 0xbc800000, v121
	v_fmac_f32_e32 v120, 0xbc800000, v121
	v_fma_f32 v179, v117, v117, v178
	v_fma_f32 v178, v116, v116, v178
	v_fma_f32 v187, v119, v119, v186
	v_fma_f32 v186, v118, v118, v186
	v_pk_mov_b32 v[200:201], v[194:195], v[192:193] op_sel:[1,0]
	v_mov_b32_e32 v195, v193
	v_pk_mov_b32 v[192:193], v[198:199], v[196:197] op_sel:[1,0]
	v_mov_b32_e32 v199, v197
	v_mul_f32_e32 v178, v120, v120
	v_mul_f32_e32 v186, v124, v124
	v_add_f32_e32 v194, v200, v194
	v_add_f32_e32 v195, v201, v195
	v_add_f32_e32 v192, v192, v198
	v_add_f32_e32 v193, v193, v199
	v_fmac_f32_e32 v126, 0xbc800000, v121
	v_fmac_f32_e32 v122, 0xbc800000, v121
	v_add_f32_e32 v178, v178, v186
	v_add_f32_e32 v179, v179, v187
	v_add_f32_e32 v186, v194, v194
	v_add_f32_e32 v187, v194, v195
	v_add_f32_e32 v193, v192, v193
	v_add_f32_e32 v192, v192, v192
	v_mul_f32_e32 v186, v122, v122
	v_mul_f32_e32 v192, v126, v126
	v_add_f32_e32 v186, v186, v192
	v_add_f32_e32 v187, v187, v193
	s_waitcnt vmcnt(0)
	v_lshlrev_b32_e32 v192, 16, v114
	v_add_f32_e32 v178, v178, v186
	v_add_f32_e32 v179, v179, v187
	v_lshl_add_u64 v[186:187], s[20:21], 0, v[148:149]
	v_add_f32_e32 v121, v178, v179
	ds_bpermute_b32 v123, v154, v121
	v_lshlrev_b32_e32 v148, 16, v112
	v_and_b32_e32 v149, 0xffff0000, v112
	v_lshlrev_b32_e32 v112, 16, v113
	v_and_b32_e32 v113, 0xffff0000, v113
	s_waitcnt lgkmcnt(0)
	v_add_f32_e32 v121, v121, v123
	ds_bpermute_b32 v123, v155, v121
	v_and_b32_e32 v193, 0xffff0000, v114
	v_lshlrev_b32_e32 v114, 16, v115
	v_and_b32_e32 v115, 0xffff0000, v115
	global_load_dwordx4 v[178:181], v[180:181], off offset:64
	s_waitcnt lgkmcnt(0)
	v_add_f32_e32 v121, v121, v123
	v_fmamk_f32 v121, v121, 0x3c800000, v160
	v_mul_f32_e32 v123, 0x4b800000, v121
	v_cmp_gt_f32_e32 vcc, s78, v121
	s_nop 1
	v_cndmask_b32_e32 v121, v121, v123, vcc
	v_rsq_f32_e32 v121, v121
	s_nop 0
	v_mul_f32_e32 v123, 0x45800000, v121
	v_cndmask_b32_e32 v194, v121, v123, vcc
	v_mul_f32_e32 v150, v150, v194
	v_mul_f32_e32 v151, v151, v194
	v_mul_f32_e32 v190, v190, v194
	v_mul_f32_e32 v191, v191, v194
	v_mul_f32_e32 v184, v184, v194
	v_mul_f32_e32 v185, v185, v194
	v_mul_f32_e32 v182, v182, v194
	v_mul_f32_e32 v183, v183, v194
	v_fma_f32 v168, v168, v190, v176
	v_fma_f32 v169, v169, v191, v177
	v_fma_f32 v150, v166, v150, v174
	v_fma_f32 v151, v167, v151, v175
	v_fma_f32 v164, v164, v182, v172
	v_fma_f32 v165, v165, v183, v173
	v_fma_f32 v162, v162, v184, v170
	v_fma_f32 v163, v163, v185, v171
	v_fma_f32 v148, v188, v148, v150
	v_fma_f32 v149, v188, v149, v151
	v_fma_f32 v112, v188, v112, v168
	v_fma_f32 v113, v188, v113, v169
	v_fma_f32 v150, v188, v192, v162
	v_fma_f32 v151, v188, v193, v163
	v_fma_f32 v114, v188, v114, v164
	v_fma_f32 v115, v188, v115, v165
	v_mul_f32_e32 v110, v110, v112
	v_mul_f32_e32 v111, v111, v113
	v_mul_f32_e32 v108, v108, v148
	v_mul_f32_e32 v109, v109, v149
	v_mul_f32_e32 v112, v106, v114
	v_mul_f32_e32 v113, v107, v115
	v_mul_f32_e32 v106, v104, v150
	v_mul_f32_e32 v107, v105, v151
	v_cvt_pk_bf16_f32 v104, v108, v109
	v_cvt_pk_bf16_f32 v105, v110, v111
	v_cvt_pk_bf16_f32 v106, v106, v107
	v_cvt_pk_bf16_f32 v107, v112, v113
	global_store_dwordx4 v[186:187], v[104:107], off
	global_load_dwordx4 v[104:107], v[142:143], off offset:128
	s_nop 0
	global_load_dwordx4 v[108:111], v[140:141], off offset:128
	global_load_dwordx4 v[148:151], v[140:141], off offset:144
	global_load_dwordx4 v[162:165], v[142:143], off offset:144
	v_mov_b32_e32 v121, v124
	v_mov_b32_e32 v123, v126
	v_mul_f32_e32 v116, v116, v194
	v_mul_f32_e32 v117, v117, v194
	v_mul_f32_e32 v118, v118, v194
	v_mul_f32_e32 v119, v119, v194
	v_mul_f32_e32 v120, v120, v194
	v_mul_f32_e32 v121, v121, v194
	v_mul_f32_e32 v122, v122, v194
	v_mul_f32_e32 v123, v123, v194
	v_or_b32_e32 v114, 32, v146
	v_ashrrev_i32_e32 v115, 31, v114
	v_lshlrev_b64 v[112:113], 10, v[114:115]
	v_lshl_add_u64 v[112:113], v[112:113], 0, v[144:145]
	v_lshlrev_b64 v[112:113], 1, v[112:113]
	v_lshl_add_u64 v[166:167], s[10:11], 0, v[112:113]
	s_waitcnt vmcnt(5)
	v_lshlrev_b32_e32 v168, 16, v178
	v_and_b32_e32 v169, 0xffff0000, v178
	v_lshlrev_b32_e32 v170, 16, v179
	v_and_b32_e32 v171, 0xffff0000, v179
	v_lshlrev_b32_e32 v172, 16, v180
	v_and_b32_e32 v173, 0xffff0000, v180
	v_lshlrev_b32_e32 v174, 16, v181
	v_and_b32_e32 v175, 0xffff0000, v181
	s_waitcnt vmcnt(2)
	v_fma_f32 v106, v110, v118, v106
	v_fma_f32 v107, v111, v119, v107
	v_fma_f32 v104, v108, v116, v104
	v_fma_f32 v105, v109, v117, v105
	s_waitcnt vmcnt(0)
; #define GAS __attribute__((address_space(1)))
;     __device__ __forceinline__ void operator()(const Acc& acc, const Unit& u, int wr, int wc, int fr, int fq) const {
;     ...
;                 const int row = row0 + ai * HALF + m * 16;
;                 const size_t off = (size_t)row * D + colb;
;                 f32x4 y[2][2], v[2][2];
; #pragma unroll
;                 for (int bj = 0; bj < 2; ++bj) { unpack8(*(const GAS u32x4*)(Y + off + 32 * bj), y[bj][0], y[bj][1]); unpack8(*(const GAS u32x4*)(V + off + 32 * bj), v[bj][0], v[bj][1]); }
;                 const float bs = BON[(size_t)row * 16 + head];
;                 float s = 0.f;
; #pragma unroll
;                 for (int bj = 0; bj < 2; ++bj)
; #pragma unroll
;                     for (int n = 0; n < 2; ++n) s += (y[bj][n][0] + y[bj][n][1]) + (y[bj][n][2] + y[bj][n][3]);
;                 s += __shfl_xor(s, 16); s += __shfl_xor(s, 32);
;                 const float mean = s * (1.f / 64.f);
;                 float q = 0.f;
; #pragma unroll
;                 for (int bj = 0; bj < 2; ++bj)
; #pragma unroll
;                     for (int n = 0; n < 2; ++n) { y[bj][n] = y[bj][n] - mean; q += (y[bj][n][0] * y[bj][n][0] + y[bj][n][1] * y[bj][n][1]) + (y[bj][n][2] * y[bj][n][2] + y[bj][n][3] * y[bj][n][3]); }
;                 q += __shfl_xor(q, 16); q += __shfl_xor(q, 32);
;                 const float rs = rsqrtf(q * (1.f / 64.f) + 64e-5f);
; #pragma unroll
;                 for (int bj = 0; bj < 2; ++bj) {
;                     f32x4 o[2];
; #pragma unroll
;                     for (int n = 0; n < 2; ++n) {
;                         const f32x4 lw = *(const GAS f32x4*)(ln_w + colb + 32 * bj + 4 * n), lb = *(const GAS f32x4*)(ln_b + colb + 32 * bj + 4 * n);
;                         o[n] = (y[bj][n] * rs * lw + lb + v[bj][n] * bs) * acc[ai][bj][m][n];
;                     }
;                     *(GAS u32x4*)(YG + off + 32 * bj) = pack8(o[0], o[1]);
;                 }
;                 asm volatile("" ::: "memory");
	v_fma_f32 v108, v150, v122, v164
	v_fma_f32 v109, v151, v123, v165
	v_fma_f32 v110, v148, v120, v162
	v_fma_f32 v111, v149, v121, v163
	v_fma_f32 v104, v188, v168, v104
	v_fma_f32 v105, v188, v169, v105
	v_fma_f32 v106, v188, v170, v106
	v_fma_f32 v107, v188, v171, v107
	v_fma_f32 v110, v188, v172, v110
	v_fma_f32 v111, v188, v173, v111
	v_fma_f32 v108, v188, v174, v108
	v_fma_f32 v109, v188, v175, v109
	v_mul_f32_e32 v102, v102, v106
	v_mul_f32_e32 v103, v103, v107
	v_mul_f32_e32 v100, v100, v104
	v_mul_f32_e32 v101, v101, v105
	v_mul_f32_e32 v104, v98, v108
	v_mul_f32_e32 v105, v99, v109
	v_mul_f32_e32 v98, v96, v110
	v_mul_f32_e32 v99, v97, v111
	v_cvt_pk_bf16_f32 v96, v100, v101
	v_cvt_pk_bf16_f32 v97, v102, v103
	v_cvt_pk_bf16_f32 v98, v98, v99
	v_cvt_pk_bf16_f32 v99, v104, v105
	global_store_dwordx4 v[186:187], v[96:99], off offset:64
	global_load_dwordx4 v[104:107], v[166:167], off offset:64
	global_load_dwordx4 v[116:119], v[166:167], off
	v_lshlrev_b64 v[96:97], 6, v[114:115]
	v_lshl_add_u64 v[162:163], s[14:15], 0, v[96:97]
	v_lshl_add_u64 v[164:165], s[12:13], 0, v[112:113]
	global_load_dwordx4 v[96:99], v[164:165], off
	v_lshl_add_u64 v[162:163], v[162:163], 0, s[34:35]
	s_waitcnt vmcnt(2)
	v_lshlrev_b32_e32 v100, 16, v104
	s_waitcnt vmcnt(1)
	v_lshlrev_b32_e32 v115, 16, v117
	v_lshlrev_b32_e32 v114, 16, v116
	v_and_b32_e32 v167, 0xffff0000, v117
	v_and_b32_e32 v166, 0xffff0000, v116
	v_lshlrev_b32_e32 v169, 16, v119
	v_lshlrev_b32_e32 v168, 16, v118
	v_and_b32_e32 v171, 0xffff0000, v119
	v_and_b32_e32 v170, 0xffff0000, v118
	v_add_f32_e32 v116, v114, v166
	v_add_f32_e32 v117, v115, v167
	v_add_f32_e32 v118, v168, v170
	v_add_f32_e32 v119, v169, v171
	v_and_b32_e32 v101, 0xffff0000, v104
	v_lshlrev_b32_e32 v102, 16, v105
	v_and_b32_e32 v103, 0xffff0000, v105
	v_add_f32_e32 v105, v116, v117
	v_add_f32_e32 v116, v118, v118
	v_add_f32_e32 v117, v118, v119
	v_lshlrev_b32_e32 v104, 16, v106
	v_and_b32_e32 v108, 0xffff0000, v106
	v_lshlrev_b32_e32 v106, 16, v107
	v_and_b32_e32 v110, 0xffff0000, v107
	v_add_f32_e32 v107, v100, v101
	v_add_f32_e32 v111, v102, v103
	v_add_f32_e32 v109, 0, v105
	v_mov_b32_e32 v105, v117
	v_add_f32_e32 v118, v106, v110
	v_add_f32_e32 v119, v107, v111
	v_add_f32_e32 v116, v104, v108
	v_add_f32_e32 v117, v105, v109
	s_nop 0
	v_add_f32_e32 v116, v116, v118
	v_add_f32_e32 v117, v117, v119
	s_nop 0
	v_add_f32_e32 v105, v116, v117
	global_load_dwordx4 v[116:119], v[140:141], off offset:16
	global_load_dwordx4 v[120:123], v[140:141], off
	global_load_dwordx4 v[124:127], v[142:143], off offset:16
	global_load_dwordx4 v[148:151], v[142:143], off
	flat_load_dword v172, v[162:163]
	ds_bpermute_b32 v107, v154, v105
	s_waitcnt lgkmcnt(0)
	v_add_f32_e32 v105, v105, v107
	ds_bpermute_b32 v107, v155, v105
	s_waitcnt lgkmcnt(0)
	v_add_f32_e32 v105, v105, v107
	v_fmac_f32_e32 v166, 0xbc800000, v105
	v_fmac_f32_e32 v167, 0xbc800000, v105
	v_fmac_f32_e32 v115, 0xbc800000, v105
	v_fmac_f32_e32 v170, 0xbc800000, v105
	v_fmac_f32_e32 v171, 0xbc800000, v105
	v_fmac_f32_e32 v169, 0xbc800000, v105
	v_fmac_f32_e32 v114, 0xbc800000, v105
	v_fmac_f32_e32 v168, 0xbc800000, v105
	v_fmac_f32_e32 v100, 0xbc800000, v105
	v_fmac_f32_e32 v102, 0xbc800000, v105
	v_mov_b32_e32 v174, v115
	v_mov_b32_e32 v175, v167
	v_mov_b32_e32 v115, v166
	v_mov_b32_e32 v166, v169
	v_mov_b32_e32 v167, v171
	v_mov_b32_e32 v169, v170
	v_fmac_f32_e32 v101, 0xbc800000, v105
	v_fmac_f32_e32 v103, 0xbc800000, v105
	v_mul_f32_e32 v162, v100, v100
	v_mul_f32_e32 v170, v102, v102
	v_mul_f32_e32 v176, v174, v174
	v_mul_f32_e32 v177, v175, v175
	v_mul_f32_e32 v178, v114, v114
	v_mul_f32_e32 v179, v115, v115
	v_mul_f32_e32 v180, v166, v166
	v_mul_f32_e32 v181, v167, v167
	v_mul_f32_e32 v182, v168, v168
	v_mul_f32_e32 v183, v169, v169
	v_fmac_f32_e32 v108, 0xbc800000, v105
	v_fmac_f32_e32 v104, 0xbc800000, v105
	v_fma_f32 v163, v101, v101, v162
	v_fma_f32 v162, v100, v100, v162
	v_fma_f32 v171, v103, v103, v170
	v_fma_f32 v170, v102, v102, v170
	v_pk_mov_b32 v[184:185], v[178:179], v[176:177] op_sel:[1,0]
	v_mov_b32_e32 v179, v177
	v_pk_mov_b32 v[176:177], v[182:183], v[180:181] op_sel:[1,0]
	v_mov_b32_e32 v183, v181
	v_mul_f32_e32 v162, v104, v104
	v_mul_f32_e32 v170, v108, v108
	v_add_f32_e32 v178, v184, v178
	v_add_f32_e32 v179, v185, v179
	v_add_f32_e32 v176, v176, v182
	v_add_f32_e32 v177, v177, v183
	v_fmac_f32_e32 v110, 0xbc800000, v105
	v_fmac_f32_e32 v106, 0xbc800000, v105
	v_add_f32_e32 v162, v162, v170
	v_add_f32_e32 v163, v163, v171
	v_add_f32_e32 v170, v178, v178
	v_add_f32_e32 v171, v178, v179
	v_add_f32_e32 v177, v176, v177
	v_add_f32_e32 v176, v176, v176
	v_mul_f32_e32 v170, v106, v106
	v_mul_f32_e32 v176, v110, v110
	v_add_f32_e32 v170, v170, v176
	v_add_f32_e32 v171, v171, v177
	s_waitcnt vmcnt(0)
	v_lshlrev_b32_e32 v176, 16, v98
	v_add_f32_e32 v162, v162, v170
	v_add_f32_e32 v163, v163, v171
	v_lshl_add_u64 v[170:171], s[20:21], 0, v[112:113]
	v_add_f32_e32 v105, v162, v163
	ds_bpermute_b32 v107, v154, v105
	v_lshlrev_b32_e32 v112, 16, v96
	v_and_b32_e32 v113, 0xffff0000, v96
	v_lshlrev_b32_e32 v96, 16, v97
	v_and_b32_e32 v97, 0xffff0000, v97
	s_waitcnt lgkmcnt(0)
	v_add_f32_e32 v105, v105, v107
	ds_bpermute_b32 v107, v155, v105
	v_and_b32_e32 v177, 0xffff0000, v98
	v_lshlrev_b32_e32 v98, 16, v99
	v_and_b32_e32 v99, 0xffff0000, v99
	global_load_dwordx4 v[162:165], v[164:165], off offset:64
	s_waitcnt lgkmcnt(0)
; #define GAS __attribute__((address_space(1)))
;     __device__ __forceinline__ void operator()(const Acc& acc, const Unit& u, int wr, int wc, int fr, int fq) const {
;     ...
;                 const int row = row0 + ai * HALF + m * 16;
;                 const size_t off = (size_t)row * D + colb;
;                 f32x4 y[2][2], v[2][2];
; #pragma unroll
;                 for (int bj = 0; bj < 2; ++bj) { unpack8(*(const GAS u32x4*)(Y + off + 32 * bj), y[bj][0], y[bj][1]); unpack8(*(const GAS u32x4*)(V + off + 32 * bj), v[bj][0], v[bj][1]); }
;                 const float bs = BON[(size_t)row * 16 + head];
;                 float s = 0.f;
; #pragma unroll
;                 for (int bj = 0; bj < 2; ++bj)
; #pragma unroll
;                     for (int n = 0; n < 2; ++n) s += (y[bj][n][0] + y[bj][n][1]) + (y[bj][n][2] + y[bj][n][3]);
;                 s += __shfl_xor(s, 16); s += __shfl_xor(s, 32);
;                 const float mean = s * (1.f / 64.f);
;                 float q = 0.f;
; #pragma unroll
;                 for (int bj = 0; bj < 2; ++bj)
; #pragma unroll
;                     for (int n = 0; n < 2; ++n) { y[bj][n] = y[bj][n] - mean; q += (y[bj][n][0] * y[bj][n][0] + y[bj][n][1] * y[bj][n][1]) + (y[bj][n][2] * y[bj][n][2] + y[bj][n][3] * y[bj][n][3]); }
;                 q += __shfl_xor(q, 16); q += __shfl_xor(q, 32);
;                 const float rs = rsqrtf(q * (1.f / 64.f) + 64e-5f);
; #pragma unroll
;                 for (int bj = 0; bj < 2; ++bj) {
;                     f32x4 o[2];
; #pragma unroll
;                     for (int n = 0; n < 2; ++n) {
;                         const f32x4 lw = *(const GAS f32x4*)(ln_w + colb + 32 * bj + 4 * n), lb = *(const GAS f32x4*)(ln_b + colb + 32 * bj + 4 * n);
;                         o[n] = (y[bj][n] * rs * lw + lb + v[bj][n] * bs) * acc[ai][bj][m][n];
;                     }
;                     *(GAS u32x4*)(YG + off + 32 * bj) = pack8(o[0], o[1]);
;                 }
;                 asm volatile("" ::: "memory");
	v_add_f32_e32 v105, v105, v107
	v_fmamk_f32 v105, v105, 0x3c800000, v160
	v_mul_f32_e32 v107, 0x4b800000, v105
	v_cmp_gt_f32_e32 vcc, s78, v105
	s_nop 1
	v_cndmask_b32_e32 v105, v105, v107, vcc
	v_rsq_f32_e32 v105, v105
	s_nop 0
	v_mul_f32_e32 v107, 0x45800000, v105
	v_cndmask_b32_e32 v178, v105, v107, vcc
	v_mul_f32_e32 v114, v114, v178
	v_mul_f32_e32 v115, v115, v178
	v_mul_f32_e32 v174, v174, v178
	v_mul_f32_e32 v175, v175, v178
	v_mul_f32_e32 v168, v168, v178
	v_mul_f32_e32 v169, v169, v178
	v_mul_f32_e32 v166, v166, v178
	v_mul_f32_e32 v167, v167, v178
	v_fma_f32 v122, v122, v174, v150
	v_fma_f32 v123, v123, v175, v151
	v_fma_f32 v114, v120, v114, v148
	v_fma_f32 v115, v121, v115, v149
	v_fma_f32 v118, v118, v166, v126
	v_fma_f32 v119, v119, v167, v127
	v_fma_f32 v116, v116, v168, v124
	v_fma_f32 v117, v117, v169, v125
	v_fma_f32 v112, v172, v112, v114
	v_fma_f32 v113, v172, v113, v115
	v_fma_f32 v96, v172, v96, v122
	v_fma_f32 v97, v172, v97, v123
	v_fma_f32 v114, v172, v176, v116
	v_fma_f32 v115, v172, v177, v117
	v_fma_f32 v98, v172, v98, v118
	v_fma_f32 v99, v172, v99, v119
	v_mul_f32_e32 v94, v94, v96
	v_mul_f32_e32 v95, v95, v97
	v_mul_f32_e32 v92, v92, v112
	v_mul_f32_e32 v93, v93, v113
	v_mul_f32_e32 v96, v90, v98
	v_mul_f32_e32 v97, v91, v99
	v_mul_f32_e32 v90, v88, v114
	v_mul_f32_e32 v91, v89, v115
	v_cvt_pk_bf16_f32 v88, v92, v93
	v_cvt_pk_bf16_f32 v89, v94, v95
	v_cvt_pk_bf16_f32 v90, v90, v91
	v_cvt_pk_bf16_f32 v91, v96, v97
	global_store_dwordx4 v[170:171], v[88:91], off
	global_load_dwordx4 v[88:91], v[142:143], off offset:128
	s_nop 0
	global_load_dwordx4 v[92:95], v[140:141], off offset:128
	global_load_dwordx4 v[112:115], v[140:141], off offset:144
	global_load_dwordx4 v[116:119], v[142:143], off offset:144
	v_mov_b32_e32 v105, v108
	v_mov_b32_e32 v107, v110
	v_mul_f32_e32 v100, v100, v178
	v_mul_f32_e32 v101, v101, v178
	v_mul_f32_e32 v102, v102, v178
	v_mul_f32_e32 v103, v103, v178
	v_mul_f32_e32 v104, v104, v178
	v_mul_f32_e32 v105, v105, v178
	v_mul_f32_e32 v106, v106, v178
	v_mul_f32_e32 v107, v107, v178
	v_or_b32_e32 v98, 48, v146
	v_ashrrev_i32_e32 v99, 31, v98
	v_lshlrev_b64 v[96:97], 10, v[98:99]
	v_lshl_add_u64 v[96:97], v[96:97], 0, v[144:145]
	v_lshlrev_b64 v[96:97], 1, v[96:97]
	v_lshl_add_u64 v[120:121], s[10:11], 0, v[96:97]
	s_waitcnt vmcnt(5)
	v_lshlrev_b32_e32 v122, 16, v162
	v_and_b32_e32 v123, 0xffff0000, v162
	v_lshlrev_b32_e32 v124, 16, v163
	v_and_b32_e32 v125, 0xffff0000, v163
	v_lshlrev_b32_e32 v126, 16, v164
	v_and_b32_e32 v127, 0xffff0000, v164
	v_lshlrev_b32_e32 v148, 16, v165
	v_and_b32_e32 v149, 0xffff0000, v165
	s_waitcnt vmcnt(2)
	v_fma_f32 v90, v94, v102, v90
	v_fma_f32 v91, v95, v103, v91
	v_fma_f32 v88, v92, v100, v88
	v_fma_f32 v89, v93, v101, v89
	s_waitcnt vmcnt(0)
	v_fma_f32 v92, v114, v106, v118
	v_fma_f32 v93, v115, v107, v119
	v_fma_f32 v94, v112, v104, v116
	v_fma_f32 v95, v113, v105, v117
	v_fma_f32 v88, v172, v122, v88
	v_fma_f32 v89, v172, v123, v89
	v_fma_f32 v90, v172, v124, v90
	v_fma_f32 v91, v172, v125, v91
	v_fma_f32 v94, v172, v126, v94
	v_fma_f32 v95, v172, v127, v95
	v_fma_f32 v92, v172, v148, v92
	v_fma_f32 v93, v172, v149, v93
	v_mul_f32_e32 v86, v86, v90
	v_mul_f32_e32 v87, v87, v91
	v_mul_f32_e32 v84, v84, v88
	v_mul_f32_e32 v85, v85, v89
	v_mul_f32_e32 v88, v82, v92
	v_mul_f32_e32 v89, v83, v93
	v_mul_f32_e32 v82, v80, v94
	v_mul_f32_e32 v83, v81, v95
	v_cvt_pk_bf16_f32 v80, v84, v85
	v_cvt_pk_bf16_f32 v81, v86, v87
	v_cvt_pk_bf16_f32 v82, v82, v83
	v_cvt_pk_bf16_f32 v83, v88, v89
	global_store_dwordx4 v[170:171], v[80:83], off offset:64
	global_load_dwordx4 v[88:91], v[120:121], off offset:64
	global_load_dwordx4 v[100:103], v[120:121], off
	v_lshlrev_b64 v[80:81], 6, v[98:99]
	v_lshl_add_u64 v[116:117], s[14:15], 0, v[80:81]
	v_lshl_add_u64 v[118:119], s[12:13], 0, v[96:97]
	global_load_dwordx4 v[80:83], v[118:119], off
	v_lshl_add_u64 v[116:117], v[116:117], 0, s[34:35]
	s_waitcnt vmcnt(2)
	v_lshlrev_b32_e32 v84, 16, v88
	s_waitcnt vmcnt(1)
	v_lshlrev_b32_e32 v99, 16, v101
	v_lshlrev_b32_e32 v98, 16, v100
	v_and_b32_e32 v121, 0xffff0000, v101
	v_and_b32_e32 v120, 0xffff0000, v100
	v_lshlrev_b32_e32 v123, 16, v103
	v_lshlrev_b32_e32 v122, 16, v102
	v_and_b32_e32 v125, 0xffff0000, v103
	v_and_b32_e32 v124, 0xffff0000, v102
	v_add_f32_e32 v100, v98, v120
	v_add_f32_e32 v101, v99, v121
	v_add_f32_e32 v102, v122, v124
	v_add_f32_e32 v103, v123, v125
	v_and_b32_e32 v85, 0xffff0000, v88
	v_lshlrev_b32_e32 v86, 16, v89
	v_and_b32_e32 v87, 0xffff0000, v89
	v_add_f32_e32 v89, v100, v101
	v_add_f32_e32 v100, v102, v102
	v_add_f32_e32 v101, v102, v103
	v_lshlrev_b32_e32 v88, 16, v90
	v_and_b32_e32 v92, 0xffff0000, v90
	v_lshlrev_b32_e32 v90, 16, v91
	v_and_b32_e32 v94, 0xffff0000, v91
	v_add_f32_e32 v91, v84, v85
	v_add_f32_e32 v95, v86, v87
	v_add_f32_e32 v93, 0, v89
	v_mov_b32_e32 v89, v101
	v_add_f32_e32 v102, v90, v94
	v_add_f32_e32 v103, v91, v95
	v_add_f32_e32 v100, v88, v92
	v_add_f32_e32 v101, v89, v93
	s_nop 0
	v_add_f32_e32 v100, v100, v102
	v_add_f32_e32 v101, v101, v103
	s_nop 0
	v_add_f32_e32 v89, v100, v101
	global_load_dwordx4 v[100:103], v[140:141], off offset:16
	global_load_dwordx4 v[104:107], v[140:141], off
	global_load_dwordx4 v[108:111], v[142:143], off offset:16
	global_load_dwordx4 v[112:115], v[142:143], off
	flat_load_dword v126, v[116:117]
	ds_bpermute_b32 v91, v154, v89
	s_waitcnt lgkmcnt(0)
	v_add_f32_e32 v89, v89, v91
	ds_bpermute_b32 v91, v155, v89
	s_waitcnt lgkmcnt(0)
; #define GAS __attribute__((address_space(1)))
;     __device__ __forceinline__ void operator()(const Acc& acc, const Unit& u, int wr, int wc, int fr, int fq) const {
;     ...
;                 const int row = row0 + ai * HALF + m * 16;
;                 const size_t off = (size_t)row * D + colb;
;                 f32x4 y[2][2], v[2][2];
; #pragma unroll
;                 for (int bj = 0; bj < 2; ++bj) { unpack8(*(const GAS u32x4*)(Y + off + 32 * bj), y[bj][0], y[bj][1]); unpack8(*(const GAS u32x4*)(V + off + 32 * bj), v[bj][0], v[bj][1]); }
;                 const float bs = BON[(size_t)row * 16 + head];
;                 float s = 0.f;
; #pragma unroll
;                 for (int bj = 0; bj < 2; ++bj)
; #pragma unroll
;                     for (int n = 0; n < 2; ++n) s += (y[bj][n][0] + y[bj][n][1]) + (y[bj][n][2] + y[bj][n][3]);
;                 s += __shfl_xor(s, 16); s += __shfl_xor(s, 32);
;                 const float mean = s * (1.f / 64.f);
;                 float q = 0.f;
; #pragma unroll
;                 for (int bj = 0; bj < 2; ++bj)
; #pragma unroll
;                     for (int n = 0; n < 2; ++n) { y[bj][n] = y[bj][n] - mean; q += (y[bj][n][0] * y[bj][n][0] + y[bj][n][1] * y[bj][n][1]) + (y[bj][n][2] * y[bj][n][2] + y[bj][n][3] * y[bj][n][3]); }
;                 q += __shfl_xor(q, 16); q += __shfl_xor(q, 32);
;                 const float rs = rsqrtf(q * (1.f / 64.f) + 64e-5f);
; #pragma unroll
;                 for (int bj = 0; bj < 2; ++bj) {
;                     f32x4 o[2];
; #pragma unroll
;                     for (int n = 0; n < 2; ++n) {
;                         const f32x4 lw = *(const GAS f32x4*)(ln_w + colb + 32 * bj + 4 * n), lb = *(const GAS f32x4*)(ln_b + colb + 32 * bj + 4 * n);
;                         o[n] = (y[bj][n] * rs * lw + lb + v[bj][n] * bs) * acc[ai][bj][m][n];
;                     }
;                     *(GAS u32x4*)(YG + off + 32 * bj) = pack8(o[0], o[1]);
;                 }
;                 asm volatile("" ::: "memory");
	v_add_f32_e32 v89, v89, v91
	v_fmac_f32_e32 v120, 0xbc800000, v89
	v_fmac_f32_e32 v121, 0xbc800000, v89
	v_fmac_f32_e32 v99, 0xbc800000, v89
	v_fmac_f32_e32 v124, 0xbc800000, v89
	v_fmac_f32_e32 v125, 0xbc800000, v89
	v_fmac_f32_e32 v123, 0xbc800000, v89
	v_fmac_f32_e32 v98, 0xbc800000, v89
	v_fmac_f32_e32 v122, 0xbc800000, v89
	v_fmac_f32_e32 v84, 0xbc800000, v89
	v_fmac_f32_e32 v86, 0xbc800000, v89
	v_mov_b32_e32 v148, v99
	v_mov_b32_e32 v149, v121
	v_mov_b32_e32 v99, v120
	v_mov_b32_e32 v120, v123
	v_mov_b32_e32 v121, v125
	v_mov_b32_e32 v123, v124
	v_fmac_f32_e32 v85, 0xbc800000, v89
	v_fmac_f32_e32 v87, 0xbc800000, v89
	v_mul_f32_e32 v116, v84, v84
	v_mul_f32_e32 v124, v86, v86
	v_mul_f32_e32 v150, v148, v148
	v_mul_f32_e32 v151, v149, v149
	v_mul_f32_e32 v162, v98, v98
	v_mul_f32_e32 v163, v99, v99
	v_mul_f32_e32 v164, v120, v120
	v_mul_f32_e32 v165, v121, v121
	v_mul_f32_e32 v166, v122, v122
	v_mul_f32_e32 v167, v123, v123
	v_fmac_f32_e32 v92, 0xbc800000, v89
	v_fmac_f32_e32 v88, 0xbc800000, v89
	v_fma_f32 v117, v85, v85, v116
	v_fma_f32 v116, v84, v84, v116
	v_fma_f32 v125, v87, v87, v124
	v_fma_f32 v124, v86, v86, v124
	v_pk_mov_b32 v[168:169], v[162:163], v[150:151] op_sel:[1,0]
	v_mov_b32_e32 v163, v151
	v_pk_mov_b32 v[150:151], v[166:167], v[164:165] op_sel:[1,0]
	v_mov_b32_e32 v167, v165
	v_mul_f32_e32 v116, v88, v88
	v_mul_f32_e32 v124, v92, v92
	v_add_f32_e32 v162, v168, v162
	v_add_f32_e32 v163, v169, v163
	v_add_f32_e32 v150, v150, v166
	v_add_f32_e32 v151, v151, v167
	v_fmac_f32_e32 v94, 0xbc800000, v89
	v_fmac_f32_e32 v90, 0xbc800000, v89
	v_add_f32_e32 v116, v116, v124
	v_add_f32_e32 v117, v117, v125
	v_add_f32_e32 v124, v162, v162
	v_add_f32_e32 v125, v162, v163
	v_add_f32_e32 v151, v150, v151
	v_add_f32_e32 v150, v150, v150
	v_mul_f32_e32 v124, v90, v90
	v_mul_f32_e32 v150, v94, v94
	v_add_f32_e32 v124, v124, v150
	v_add_f32_e32 v125, v125, v151
	s_waitcnt vmcnt(0)
	v_lshlrev_b32_e32 v150, 16, v82
	v_add_f32_e32 v116, v116, v124
	v_add_f32_e32 v117, v117, v125
	v_lshl_add_u64 v[124:125], s[20:21], 0, v[96:97]
	v_add_f32_e32 v89, v116, v117
	ds_bpermute_b32 v91, v154, v89
	v_lshlrev_b32_e32 v96, 16, v80
	v_and_b32_e32 v97, 0xffff0000, v80
	v_lshlrev_b32_e32 v80, 16, v81
	v_and_b32_e32 v81, 0xffff0000, v81
	s_waitcnt lgkmcnt(0)
	v_add_f32_e32 v89, v89, v91
	ds_bpermute_b32 v91, v155, v89
	v_and_b32_e32 v151, 0xffff0000, v82
	v_lshlrev_b32_e32 v82, 16, v83
	v_and_b32_e32 v83, 0xffff0000, v83
	global_load_dwordx4 v[116:119], v[118:119], off offset:64
	s_waitcnt lgkmcnt(0)
	v_add_f32_e32 v89, v89, v91
	v_fmamk_f32 v89, v89, 0x3c800000, v160
	v_mul_f32_e32 v91, 0x4b800000, v89
	v_cmp_gt_f32_e32 vcc, s78, v89
	s_nop 1
	v_cndmask_b32_e32 v89, v89, v91, vcc
	v_rsq_f32_e32 v89, v89
	s_nop 0
	v_mul_f32_e32 v91, 0x45800000, v89
	v_cndmask_b32_e32 v162, v89, v91, vcc
	v_mul_f32_e32 v98, v98, v162
	v_mul_f32_e32 v99, v99, v162
	v_mul_f32_e32 v148, v148, v162
	v_mul_f32_e32 v149, v149, v162
	v_mul_f32_e32 v122, v122, v162
	v_mul_f32_e32 v123, v123, v162
	v_mul_f32_e32 v120, v120, v162
	v_mul_f32_e32 v121, v121, v162
	v_fma_f32 v106, v106, v148, v114
	v_fma_f32 v107, v107, v149, v115
	v_fma_f32 v98, v104, v98, v112
	v_fma_f32 v99, v105, v99, v113
	v_fma_f32 v102, v102, v120, v110
	v_fma_f32 v103, v103, v121, v111
	v_fma_f32 v100, v100, v122, v108
	v_fma_f32 v101, v101, v123, v109
	v_fma_f32 v96, v126, v96, v98
	v_fma_f32 v97, v126, v97, v99
	v_fma_f32 v80, v126, v80, v106
	v_fma_f32 v81, v126, v81, v107
	v_fma_f32 v98, v126, v150, v100
	v_fma_f32 v99, v126, v151, v101
	v_fma_f32 v82, v126, v82, v102
	v_fma_f32 v83, v126, v83, v103
	v_mul_f32_e32 v78, v78, v80
	v_mul_f32_e32 v79, v79, v81
	v_mul_f32_e32 v76, v76, v96
	v_mul_f32_e32 v77, v77, v97
	v_mul_f32_e32 v80, v74, v82
	v_mul_f32_e32 v81, v75, v83
	v_mul_f32_e32 v74, v72, v98
	v_mul_f32_e32 v75, v73, v99
	v_cvt_pk_bf16_f32 v72, v76, v77
	v_cvt_pk_bf16_f32 v73, v78, v79
	v_cvt_pk_bf16_f32 v74, v74, v75
	v_cvt_pk_bf16_f32 v75, v80, v81
	global_store_dwordx4 v[124:125], v[72:75], off
	global_load_dwordx4 v[72:75], v[142:143], off offset:128
	s_nop 0
	global_load_dwordx4 v[76:79], v[140:141], off offset:128
	global_load_dwordx4 v[96:99], v[140:141], off offset:144
	global_load_dwordx4 v[100:103], v[142:143], off offset:144
	v_mov_b32_e32 v89, v92
	v_mov_b32_e32 v91, v94
	v_mul_f32_e32 v84, v84, v162
	v_mul_f32_e32 v85, v85, v162
	v_mul_f32_e32 v86, v86, v162
	v_mul_f32_e32 v87, v87, v162
	v_mul_f32_e32 v88, v88, v162
	v_mul_f32_e32 v89, v89, v162
	v_mul_f32_e32 v90, v90, v162
	v_mul_f32_e32 v91, v91, v162
	v_add_u32_e32 v82, 0x80, v146
	v_ashrrev_i32_e32 v83, 31, v82
	v_lshlrev_b64 v[80:81], 10, v[82:83]
	v_lshl_add_u64 v[80:81], v[80:81], 0, v[144:145]
	v_lshlrev_b64 v[80:81], 1, v[80:81]
	v_lshl_add_u64 v[104:105], s[10:11], 0, v[80:81]
	s_waitcnt vmcnt(5)
	v_lshlrev_b32_e32 v106, 16, v116
	v_and_b32_e32 v107, 0xffff0000, v116
	v_lshlrev_b32_e32 v108, 16, v117
	v_and_b32_e32 v109, 0xffff0000, v117
	v_lshlrev_b32_e32 v110, 16, v118
	v_and_b32_e32 v111, 0xffff0000, v118
	v_lshlrev_b32_e32 v112, 16, v119
	v_and_b32_e32 v113, 0xffff0000, v119
	s_waitcnt vmcnt(2)
	v_fma_f32 v74, v78, v86, v74
	v_fma_f32 v75, v79, v87, v75
	v_fma_f32 v72, v76, v84, v72
	v_fma_f32 v73, v77, v85, v73
	s_waitcnt vmcnt(0)
; #define GAS __attribute__((address_space(1)))
;     __device__ __forceinline__ void operator()(const Acc& acc, const Unit& u, int wr, int wc, int fr, int fq) const {
;     ...
;                 const int row = row0 + ai * HALF + m * 16;
;                 const size_t off = (size_t)row * D + colb;
;                 f32x4 y[2][2], v[2][2];
; #pragma unroll
;                 for (int bj = 0; bj < 2; ++bj) { unpack8(*(const GAS u32x4*)(Y + off + 32 * bj), y[bj][0], y[bj][1]); unpack8(*(const GAS u32x4*)(V + off + 32 * bj), v[bj][0], v[bj][1]); }
;                 const float bs = BON[(size_t)row * 16 + head];
;                 float s = 0.f;
; #pragma unroll
;                 for (int bj = 0; bj < 2; ++bj)
; #pragma unroll
;                     for (int n = 0; n < 2; ++n) s += (y[bj][n][0] + y[bj][n][1]) + (y[bj][n][2] + y[bj][n][3]);
;                 s += __shfl_xor(s, 16); s += __shfl_xor(s, 32);
;                 const float mean = s * (1.f / 64.f);
;                 float q = 0.f;
; #pragma unroll
;                 for (int bj = 0; bj < 2; ++bj)
; #pragma unroll
;                     for (int n = 0; n < 2; ++n) { y[bj][n] = y[bj][n] - mean; q += (y[bj][n][0] * y[bj][n][0] + y[bj][n][1] * y[bj][n][1]) + (y[bj][n][2] * y[bj][n][2] + y[bj][n][3] * y[bj][n][3]); }
;                 q += __shfl_xor(q, 16); q += __shfl_xor(q, 32);
;                 const float rs = rsqrtf(q * (1.f / 64.f) + 64e-5f);
; #pragma unroll
;                 for (int bj = 0; bj < 2; ++bj) {
;                     f32x4 o[2];
; #pragma unroll
;                     for (int n = 0; n < 2; ++n) {
;                         const f32x4 lw = *(const GAS f32x4*)(ln_w + colb + 32 * bj + 4 * n), lb = *(const GAS f32x4*)(ln_b + colb + 32 * bj + 4 * n);
;                         o[n] = (y[bj][n] * rs * lw + lb + v[bj][n] * bs) * acc[ai][bj][m][n];
;                     }
;                     *(GAS u32x4*)(YG + off + 32 * bj) = pack8(o[0], o[1]);
;                 }
;                 asm volatile("" ::: "memory");
	v_fma_f32 v76, v98, v90, v102
	v_fma_f32 v77, v99, v91, v103
	v_fma_f32 v78, v96, v88, v100
	v_fma_f32 v79, v97, v89, v101
	v_fma_f32 v72, v126, v106, v72
	v_fma_f32 v73, v126, v107, v73
	v_fma_f32 v74, v126, v108, v74
	v_fma_f32 v75, v126, v109, v75
	v_fma_f32 v78, v126, v110, v78
	v_fma_f32 v79, v126, v111, v79
	v_fma_f32 v76, v126, v112, v76
	v_fma_f32 v77, v126, v113, v77
	v_mul_f32_e32 v70, v70, v74
	v_mul_f32_e32 v71, v71, v75
	v_mul_f32_e32 v68, v68, v72
	v_mul_f32_e32 v69, v69, v73
	v_mul_f32_e32 v72, v66, v76
	v_mul_f32_e32 v73, v67, v77
	v_mul_f32_e32 v66, v64, v78
	v_mul_f32_e32 v67, v65, v79
	v_cvt_pk_bf16_f32 v64, v68, v69
	v_cvt_pk_bf16_f32 v65, v70, v71
	v_cvt_pk_bf16_f32 v66, v66, v67
	v_cvt_pk_bf16_f32 v67, v72, v73
	global_store_dwordx4 v[124:125], v[64:67], off offset:64
	global_load_dwordx4 v[72:75], v[104:105], off offset:64
	global_load_dwordx4 v[84:87], v[104:105], off
	v_lshlrev_b64 v[64:65], 6, v[82:83]
	v_lshl_add_u64 v[100:101], s[14:15], 0, v[64:65]
	v_lshl_add_u64 v[102:103], s[12:13], 0, v[80:81]
	global_load_dwordx4 v[64:67], v[102:103], off
	v_lshl_add_u64 v[100:101], v[100:101], 0, s[34:35]
	s_waitcnt vmcnt(2)
	v_lshlrev_b32_e32 v68, 16, v72
	s_waitcnt vmcnt(1)
	v_lshlrev_b32_e32 v83, 16, v85
	v_lshlrev_b32_e32 v82, 16, v84
	v_and_b32_e32 v105, 0xffff0000, v85
	v_and_b32_e32 v104, 0xffff0000, v84
	v_lshlrev_b32_e32 v107, 16, v87
	v_lshlrev_b32_e32 v106, 16, v86
	v_and_b32_e32 v109, 0xffff0000, v87
	v_and_b32_e32 v108, 0xffff0000, v86
	v_add_f32_e32 v84, v82, v104
	v_add_f32_e32 v85, v83, v105
	v_add_f32_e32 v86, v106, v108
	v_add_f32_e32 v87, v107, v109
	v_and_b32_e32 v69, 0xffff0000, v72
	v_lshlrev_b32_e32 v70, 16, v73
	v_and_b32_e32 v71, 0xffff0000, v73
	v_add_f32_e32 v73, v84, v85
	v_add_f32_e32 v84, v86, v86
	v_add_f32_e32 v85, v86, v87
	v_lshlrev_b32_e32 v72, 16, v74
	v_and_b32_e32 v76, 0xffff0000, v74
	v_lshlrev_b32_e32 v74, 16, v75
	v_and_b32_e32 v78, 0xffff0000, v75
	v_add_f32_e32 v75, v68, v69
	v_add_f32_e32 v79, v70, v71
	v_add_f32_e32 v77, 0, v73
	v_mov_b32_e32 v73, v85
	v_add_f32_e32 v86, v74, v78
	v_add_f32_e32 v87, v75, v79
	v_add_f32_e32 v84, v72, v76
	v_add_f32_e32 v85, v73, v77
	s_nop 0
	v_add_f32_e32 v84, v84, v86
	v_add_f32_e32 v85, v85, v87
	s_nop 0
	v_add_f32_e32 v73, v84, v85
	global_load_dwordx4 v[84:87], v[140:141], off offset:16
	global_load_dwordx4 v[88:91], v[140:141], off
	global_load_dwordx4 v[92:95], v[142:143], off offset:16
	global_load_dwordx4 v[96:99], v[142:143], off
	flat_load_dword v110, v[100:101]
	ds_bpermute_b32 v75, v154, v73
	s_waitcnt lgkmcnt(0)
	v_add_f32_e32 v73, v73, v75
	ds_bpermute_b32 v75, v155, v73
	s_waitcnt lgkmcnt(0)
	v_add_f32_e32 v73, v73, v75
	v_fmac_f32_e32 v104, 0xbc800000, v73
	v_fmac_f32_e32 v105, 0xbc800000, v73
	v_fmac_f32_e32 v83, 0xbc800000, v73
	v_fmac_f32_e32 v108, 0xbc800000, v73
	v_fmac_f32_e32 v109, 0xbc800000, v73
	v_fmac_f32_e32 v107, 0xbc800000, v73
	v_fmac_f32_e32 v82, 0xbc800000, v73
	v_fmac_f32_e32 v106, 0xbc800000, v73
	v_fmac_f32_e32 v68, 0xbc800000, v73
	v_fmac_f32_e32 v70, 0xbc800000, v73
	v_mov_b32_e32 v112, v83
	v_mov_b32_e32 v113, v105
	v_mov_b32_e32 v83, v104
	v_mov_b32_e32 v104, v107
	v_mov_b32_e32 v105, v109
	v_mov_b32_e32 v107, v108
	v_fmac_f32_e32 v69, 0xbc800000, v73
	v_fmac_f32_e32 v71, 0xbc800000, v73
	v_mul_f32_e32 v100, v68, v68
	v_mul_f32_e32 v108, v70, v70
	v_mul_f32_e32 v114, v112, v112
	v_mul_f32_e32 v115, v113, v113
	v_mul_f32_e32 v116, v82, v82
	v_mul_f32_e32 v117, v83, v83
	v_mul_f32_e32 v118, v104, v104
	v_mul_f32_e32 v119, v105, v105
	v_mul_f32_e32 v120, v106, v106
	v_mul_f32_e32 v121, v107, v107
	v_fmac_f32_e32 v76, 0xbc800000, v73
	v_fmac_f32_e32 v72, 0xbc800000, v73
	v_fma_f32 v101, v69, v69, v100
	v_fma_f32 v100, v68, v68, v100
	v_fma_f32 v109, v71, v71, v108
	v_fma_f32 v108, v70, v70, v108
	v_pk_mov_b32 v[122:123], v[116:117], v[114:115] op_sel:[1,0]
	v_mov_b32_e32 v117, v115
	v_pk_mov_b32 v[114:115], v[120:121], v[118:119] op_sel:[1,0]
	v_mov_b32_e32 v121, v119
	v_mul_f32_e32 v100, v72, v72
	v_mul_f32_e32 v108, v76, v76
	v_add_f32_e32 v116, v122, v116
	v_add_f32_e32 v117, v123, v117
	v_add_f32_e32 v114, v114, v120
	v_add_f32_e32 v115, v115, v121
	v_fmac_f32_e32 v78, 0xbc800000, v73
	v_fmac_f32_e32 v74, 0xbc800000, v73
	v_add_f32_e32 v100, v100, v108
	v_add_f32_e32 v101, v101, v109
	v_add_f32_e32 v108, v116, v116
	v_add_f32_e32 v109, v116, v117
	v_add_f32_e32 v115, v114, v115
	v_add_f32_e32 v114, v114, v114
	v_mul_f32_e32 v108, v74, v74
	v_mul_f32_e32 v114, v78, v78
	v_add_f32_e32 v108, v108, v114
	v_add_f32_e32 v109, v109, v115
	s_waitcnt vmcnt(0)
	v_lshlrev_b32_e32 v114, 16, v66
	v_add_f32_e32 v100, v100, v108
	v_add_f32_e32 v101, v101, v109
	v_lshl_add_u64 v[108:109], s[20:21], 0, v[80:81]
	v_add_f32_e32 v73, v100, v101
	ds_bpermute_b32 v75, v154, v73
	v_lshlrev_b32_e32 v80, 16, v64
	v_and_b32_e32 v81, 0xffff0000, v64
	v_lshlrev_b32_e32 v64, 16, v65
	v_and_b32_e32 v65, 0xffff0000, v65
	s_waitcnt lgkmcnt(0)
	v_add_f32_e32 v73, v73, v75
	ds_bpermute_b32 v75, v155, v73
	v_and_b32_e32 v115, 0xffff0000, v66
	v_lshlrev_b32_e32 v66, 16, v67
	v_and_b32_e32 v67, 0xffff0000, v67
	global_load_dwordx4 v[100:103], v[102:103], off offset:64
	s_waitcnt lgkmcnt(0)
; #define GAS __attribute__((address_space(1)))
;     __device__ __forceinline__ void operator()(const Acc& acc, const Unit& u, int wr, int wc, int fr, int fq) const {
;     ...
;                 const int row = row0 + ai * HALF + m * 16;
;                 const size_t off = (size_t)row * D + colb;
;                 f32x4 y[2][2], v[2][2];
; #pragma unroll
;                 for (int bj = 0; bj < 2; ++bj) { unpack8(*(const GAS u32x4*)(Y + off + 32 * bj), y[bj][0], y[bj][1]); unpack8(*(const GAS u32x4*)(V + off + 32 * bj), v[bj][0], v[bj][1]); }
;                 const float bs = BON[(size_t)row * 16 + head];
;                 float s = 0.f;
; #pragma unroll
;                 for (int bj = 0; bj < 2; ++bj)
; #pragma unroll
;                     for (int n = 0; n < 2; ++n) s += (y[bj][n][0] + y[bj][n][1]) + (y[bj][n][2] + y[bj][n][3]);
;                 s += __shfl_xor(s, 16); s += __shfl_xor(s, 32);
;                 const float mean = s * (1.f / 64.f);
;                 float q = 0.f;
; #pragma unroll
;                 for (int bj = 0; bj < 2; ++bj)
; #pragma unroll
;                     for (int n = 0; n < 2; ++n) { y[bj][n] = y[bj][n] - mean; q += (y[bj][n][0] * y[bj][n][0] + y[bj][n][1] * y[bj][n][1]) + (y[bj][n][2] * y[bj][n][2] + y[bj][n][3] * y[bj][n][3]); }
;                 q += __shfl_xor(q, 16); q += __shfl_xor(q, 32);
;                 const float rs = rsqrtf(q * (1.f / 64.f) + 64e-5f);
; #pragma unroll
;                 for (int bj = 0; bj < 2; ++bj) {
;                     f32x4 o[2];
; #pragma unroll
;                     for (int n = 0; n < 2; ++n) {
;                         const f32x4 lw = *(const GAS f32x4*)(ln_w + colb + 32 * bj + 4 * n), lb = *(const GAS f32x4*)(ln_b + colb + 32 * bj + 4 * n);
;                         o[n] = (y[bj][n] * rs * lw + lb + v[bj][n] * bs) * acc[ai][bj][m][n];
;                     }
;                     *(GAS u32x4*)(YG + off + 32 * bj) = pack8(o[0], o[1]);
;                 }
;                 asm volatile("" ::: "memory");
	v_add_f32_e32 v73, v73, v75
	v_fmamk_f32 v73, v73, 0x3c800000, v160
	v_mul_f32_e32 v75, 0x4b800000, v73
	v_cmp_gt_f32_e32 vcc, s78, v73
	s_nop 1
	v_cndmask_b32_e32 v73, v73, v75, vcc
	v_rsq_f32_e32 v73, v73
	s_nop 0
	v_mul_f32_e32 v75, 0x45800000, v73
	v_cndmask_b32_e32 v116, v73, v75, vcc
	v_mul_f32_e32 v82, v82, v116
	v_mul_f32_e32 v83, v83, v116
	v_mul_f32_e32 v112, v112, v116
	v_mul_f32_e32 v113, v113, v116
	v_mul_f32_e32 v106, v106, v116
	v_mul_f32_e32 v107, v107, v116
	v_mul_f32_e32 v104, v104, v116
	v_mul_f32_e32 v105, v105, v116
	v_fma_f32 v90, v90, v112, v98
	v_fma_f32 v91, v91, v113, v99
	v_fma_f32 v82, v88, v82, v96
	v_fma_f32 v83, v89, v83, v97
	v_fma_f32 v86, v86, v104, v94
	v_fma_f32 v87, v87, v105, v95
	v_fma_f32 v84, v84, v106, v92
	v_fma_f32 v85, v85, v107, v93
	v_fma_f32 v80, v110, v80, v82
	v_fma_f32 v81, v110, v81, v83
	v_fma_f32 v64, v110, v64, v90
	v_fma_f32 v65, v110, v65, v91
	v_fma_f32 v82, v110, v114, v84
	v_fma_f32 v83, v110, v115, v85
	v_fma_f32 v66, v110, v66, v86
	v_fma_f32 v67, v110, v67, v87
	v_mul_f32_e32 v62, v62, v64
	v_mul_f32_e32 v63, v63, v65
	v_mul_f32_e32 v60, v60, v80
	v_mul_f32_e32 v61, v61, v81
	v_mul_f32_e32 v64, v58, v66
	v_mul_f32_e32 v65, v59, v67
	v_mul_f32_e32 v58, v56, v82
	v_mul_f32_e32 v59, v57, v83
	v_cvt_pk_bf16_f32 v56, v60, v61
	v_cvt_pk_bf16_f32 v57, v62, v63
	v_cvt_pk_bf16_f32 v58, v58, v59
	v_cvt_pk_bf16_f32 v59, v64, v65
	global_store_dwordx4 v[108:109], v[56:59], off
	global_load_dwordx4 v[56:59], v[142:143], off offset:128
	s_nop 0
	global_load_dwordx4 v[60:63], v[140:141], off offset:128
	global_load_dwordx4 v[80:83], v[140:141], off offset:144
	global_load_dwordx4 v[84:87], v[142:143], off offset:144
	v_mov_b32_e32 v73, v76
	v_mov_b32_e32 v75, v78
	v_mul_f32_e32 v68, v68, v116
	v_mul_f32_e32 v69, v69, v116
	v_mul_f32_e32 v70, v70, v116
	v_mul_f32_e32 v71, v71, v116
	v_mul_f32_e32 v72, v72, v116
	v_mul_f32_e32 v73, v73, v116
	v_mul_f32_e32 v74, v74, v116
	v_mul_f32_e32 v75, v75, v116
	v_add_u32_e32 v66, 0x90, v146
	v_ashrrev_i32_e32 v67, 31, v66
	v_lshlrev_b64 v[64:65], 10, v[66:67]
	v_lshl_add_u64 v[64:65], v[64:65], 0, v[144:145]
	v_lshlrev_b64 v[64:65], 1, v[64:65]
	v_lshl_add_u64 v[88:89], s[10:11], 0, v[64:65]
	s_waitcnt vmcnt(5)
	v_lshlrev_b32_e32 v90, 16, v100
	v_and_b32_e32 v91, 0xffff0000, v100
	v_lshlrev_b32_e32 v92, 16, v101
	v_and_b32_e32 v93, 0xffff0000, v101
	v_lshlrev_b32_e32 v94, 16, v102
	v_and_b32_e32 v95, 0xffff0000, v102
	v_lshlrev_b32_e32 v96, 16, v103
	v_and_b32_e32 v97, 0xffff0000, v103
	s_waitcnt vmcnt(2)
	v_fma_f32 v58, v62, v70, v58
	v_fma_f32 v59, v63, v71, v59
	v_fma_f32 v56, v60, v68, v56
	v_fma_f32 v57, v61, v69, v57
	s_waitcnt vmcnt(0)
	v_fma_f32 v60, v82, v74, v86
	v_fma_f32 v61, v83, v75, v87
	v_fma_f32 v62, v80, v72, v84
	v_fma_f32 v63, v81, v73, v85
	v_fma_f32 v56, v110, v90, v56
	v_fma_f32 v57, v110, v91, v57
	v_fma_f32 v58, v110, v92, v58
	v_fma_f32 v59, v110, v93, v59
	v_fma_f32 v62, v110, v94, v62
	v_fma_f32 v63, v110, v95, v63
	v_fma_f32 v60, v110, v96, v60
	v_fma_f32 v61, v110, v97, v61
	v_mul_f32_e32 v54, v54, v58
	v_mul_f32_e32 v55, v55, v59
	v_mul_f32_e32 v52, v52, v56
	v_mul_f32_e32 v53, v53, v57
	v_mul_f32_e32 v56, v50, v60
	v_mul_f32_e32 v57, v51, v61
	v_mul_f32_e32 v50, v48, v62
	v_mul_f32_e32 v51, v49, v63
	v_cvt_pk_bf16_f32 v48, v52, v53
	v_cvt_pk_bf16_f32 v49, v54, v55
	v_cvt_pk_bf16_f32 v50, v50, v51
	v_cvt_pk_bf16_f32 v51, v56, v57
	global_store_dwordx4 v[108:109], v[48:51], off offset:64
	global_load_dwordx4 v[56:59], v[88:89], off offset:64
	global_load_dwordx4 v[68:71], v[88:89], off
	v_lshlrev_b64 v[48:49], 6, v[66:67]
	v_lshl_add_u64 v[84:85], s[14:15], 0, v[48:49]
	v_lshl_add_u64 v[86:87], s[12:13], 0, v[64:65]
	global_load_dwordx4 v[48:51], v[86:87], off
	v_lshl_add_u64 v[84:85], v[84:85], 0, s[34:35]
	s_waitcnt vmcnt(2)
	v_lshlrev_b32_e32 v52, 16, v56
	s_waitcnt vmcnt(1)
	v_lshlrev_b32_e32 v67, 16, v69
	v_lshlrev_b32_e32 v66, 16, v68
	v_and_b32_e32 v89, 0xffff0000, v69
	v_and_b32_e32 v88, 0xffff0000, v68
	v_lshlrev_b32_e32 v91, 16, v71
	v_lshlrev_b32_e32 v90, 16, v70
	v_and_b32_e32 v93, 0xffff0000, v71
	v_and_b32_e32 v92, 0xffff0000, v70
	v_add_f32_e32 v68, v66, v88
	v_add_f32_e32 v69, v67, v89
	v_add_f32_e32 v70, v90, v92
	v_add_f32_e32 v71, v91, v93
	v_and_b32_e32 v53, 0xffff0000, v56
	v_lshlrev_b32_e32 v54, 16, v57
	v_and_b32_e32 v55, 0xffff0000, v57
	v_add_f32_e32 v57, v68, v69
	v_add_f32_e32 v68, v70, v70
	v_add_f32_e32 v69, v70, v71
	v_lshlrev_b32_e32 v56, 16, v58
	v_and_b32_e32 v60, 0xffff0000, v58
	v_lshlrev_b32_e32 v58, 16, v59
	v_and_b32_e32 v62, 0xffff0000, v59
	v_add_f32_e32 v59, v52, v53
	v_add_f32_e32 v63, v54, v55
	v_add_f32_e32 v61, 0, v57
	v_mov_b32_e32 v57, v69
	v_add_f32_e32 v70, v58, v62
	v_add_f32_e32 v71, v59, v63
	v_add_f32_e32 v68, v56, v60
	v_add_f32_e32 v69, v57, v61
	s_nop 0
	v_add_f32_e32 v68, v68, v70
	v_add_f32_e32 v69, v69, v71
	s_nop 0
	v_add_f32_e32 v57, v68, v69
	global_load_dwordx4 v[68:71], v[140:141], off offset:16
	global_load_dwordx4 v[72:75], v[140:141], off
	global_load_dwordx4 v[76:79], v[142:143], off offset:16
	global_load_dwordx4 v[80:83], v[142:143], off
	flat_load_dword v94, v[84:85]
	ds_bpermute_b32 v59, v154, v57
	s_waitcnt lgkmcnt(0)
	v_add_f32_e32 v57, v57, v59
	ds_bpermute_b32 v59, v155, v57
	s_waitcnt lgkmcnt(0)
; #define GAS __attribute__((address_space(1)))
;     __device__ __forceinline__ void operator()(const Acc& acc, const Unit& u, int wr, int wc, int fr, int fq) const {
;     ...
;                 const int row = row0 + ai * HALF + m * 16;
;                 const size_t off = (size_t)row * D + colb;
;                 f32x4 y[2][2], v[2][2];
; #pragma unroll
;                 for (int bj = 0; bj < 2; ++bj) { unpack8(*(const GAS u32x4*)(Y + off + 32 * bj), y[bj][0], y[bj][1]); unpack8(*(const GAS u32x4*)(V + off + 32 * bj), v[bj][0], v[bj][1]); }
;                 const float bs = BON[(size_t)row * 16 + head];
;                 float s = 0.f;
; #pragma unroll
;                 for (int bj = 0; bj < 2; ++bj)
; #pragma unroll
;                     for (int n = 0; n < 2; ++n) s += (y[bj][n][0] + y[bj][n][1]) + (y[bj][n][2] + y[bj][n][3]);
;                 s += __shfl_xor(s, 16); s += __shfl_xor(s, 32);
;                 const float mean = s * (1.f / 64.f);
;                 float q = 0.f;
; #pragma unroll
;                 for (int bj = 0; bj < 2; ++bj)
; #pragma unroll
;                     for (int n = 0; n < 2; ++n) { y[bj][n] = y[bj][n] - mean; q += (y[bj][n][0] * y[bj][n][0] + y[bj][n][1] * y[bj][n][1]) + (y[bj][n][2] * y[bj][n][2] + y[bj][n][3] * y[bj][n][3]); }
;                 q += __shfl_xor(q, 16); q += __shfl_xor(q, 32);
;                 const float rs = rsqrtf(q * (1.f / 64.f) + 64e-5f);
; #pragma unroll
;                 for (int bj = 0; bj < 2; ++bj) {
;                     f32x4 o[2];
; #pragma unroll
;                     for (int n = 0; n < 2; ++n) {
;                         const f32x4 lw = *(const GAS f32x4*)(ln_w + colb + 32 * bj + 4 * n), lb = *(const GAS f32x4*)(ln_b + colb + 32 * bj + 4 * n);
;                         o[n] = (y[bj][n] * rs * lw + lb + v[bj][n] * bs) * acc[ai][bj][m][n];
;                     }
;                     *(GAS u32x4*)(YG + off + 32 * bj) = pack8(o[0], o[1]);
;                 }
;                 asm volatile("" ::: "memory");
	v_add_f32_e32 v57, v57, v59
	v_fmac_f32_e32 v88, 0xbc800000, v57
	v_fmac_f32_e32 v89, 0xbc800000, v57
	v_fmac_f32_e32 v67, 0xbc800000, v57
	v_fmac_f32_e32 v92, 0xbc800000, v57
	v_fmac_f32_e32 v93, 0xbc800000, v57
	v_fmac_f32_e32 v91, 0xbc800000, v57
	v_fmac_f32_e32 v66, 0xbc800000, v57
	v_fmac_f32_e32 v90, 0xbc800000, v57
	v_fmac_f32_e32 v52, 0xbc800000, v57
	v_fmac_f32_e32 v54, 0xbc800000, v57
	v_mov_b32_e32 v96, v67
	v_mov_b32_e32 v97, v89
	v_mov_b32_e32 v67, v88
	v_mov_b32_e32 v88, v91
	v_mov_b32_e32 v89, v93
	v_mov_b32_e32 v91, v92
	v_fmac_f32_e32 v53, 0xbc800000, v57
	v_fmac_f32_e32 v55, 0xbc800000, v57
	v_mul_f32_e32 v84, v52, v52
	v_mul_f32_e32 v92, v54, v54
	v_mul_f32_e32 v98, v96, v96
	v_mul_f32_e32 v99, v97, v97
	v_mul_f32_e32 v100, v66, v66
	v_mul_f32_e32 v101, v67, v67
	v_mul_f32_e32 v102, v88, v88
	v_mul_f32_e32 v103, v89, v89
	v_mul_f32_e32 v104, v90, v90
	v_mul_f32_e32 v105, v91, v91
	v_fmac_f32_e32 v60, 0xbc800000, v57
	v_fmac_f32_e32 v56, 0xbc800000, v57
	v_fma_f32 v85, v53, v53, v84
	v_fma_f32 v84, v52, v52, v84
	v_fma_f32 v93, v55, v55, v92
	v_fma_f32 v92, v54, v54, v92
	v_pk_mov_b32 v[106:107], v[100:101], v[98:99] op_sel:[1,0]
	v_mov_b32_e32 v101, v99
	v_pk_mov_b32 v[98:99], v[104:105], v[102:103] op_sel:[1,0]
	v_mov_b32_e32 v105, v103
	v_mul_f32_e32 v84, v56, v56
	v_mul_f32_e32 v92, v60, v60
	v_add_f32_e32 v100, v106, v100
	v_add_f32_e32 v101, v107, v101
	v_add_f32_e32 v98, v98, v104
	v_add_f32_e32 v99, v99, v105
	v_fmac_f32_e32 v62, 0xbc800000, v57
	v_fmac_f32_e32 v58, 0xbc800000, v57
	v_add_f32_e32 v84, v84, v92
	v_add_f32_e32 v85, v85, v93
	v_add_f32_e32 v92, v100, v100
	v_add_f32_e32 v93, v100, v101
	v_add_f32_e32 v99, v98, v99
	v_add_f32_e32 v98, v98, v98
	v_mul_f32_e32 v92, v58, v58
	v_mul_f32_e32 v98, v62, v62
	v_add_f32_e32 v92, v92, v98
	v_add_f32_e32 v93, v93, v99
	s_waitcnt vmcnt(0)
	v_lshlrev_b32_e32 v98, 16, v50
	v_add_f32_e32 v84, v84, v92
	v_add_f32_e32 v85, v85, v93
	v_lshl_add_u64 v[92:93], s[20:21], 0, v[64:65]
	v_add_f32_e32 v57, v84, v85
	ds_bpermute_b32 v59, v154, v57
	v_lshlrev_b32_e32 v64, 16, v48
	v_and_b32_e32 v65, 0xffff0000, v48
	v_lshlrev_b32_e32 v48, 16, v49
	v_and_b32_e32 v49, 0xffff0000, v49
	s_waitcnt lgkmcnt(0)
	v_add_f32_e32 v57, v57, v59
	ds_bpermute_b32 v59, v155, v57
	v_and_b32_e32 v99, 0xffff0000, v50
	v_lshlrev_b32_e32 v50, 16, v51
	v_and_b32_e32 v51, 0xffff0000, v51
	global_load_dwordx4 v[84:87], v[86:87], off offset:64
	s_waitcnt lgkmcnt(0)
	v_add_f32_e32 v57, v57, v59
	v_fmamk_f32 v57, v57, 0x3c800000, v160
	v_mul_f32_e32 v59, 0x4b800000, v57
	v_cmp_gt_f32_e32 vcc, s78, v57
	s_nop 1
	v_cndmask_b32_e32 v57, v57, v59, vcc
	v_rsq_f32_e32 v57, v57
	s_nop 0
	v_mul_f32_e32 v59, 0x45800000, v57
	v_cndmask_b32_e32 v100, v57, v59, vcc
	v_mul_f32_e32 v66, v66, v100
	v_mul_f32_e32 v67, v67, v100
	v_mul_f32_e32 v96, v96, v100
	v_mul_f32_e32 v97, v97, v100
	v_mul_f32_e32 v90, v90, v100
	v_mul_f32_e32 v91, v91, v100
	v_mul_f32_e32 v88, v88, v100
	v_mul_f32_e32 v89, v89, v100
	v_fma_f32 v74, v74, v96, v82
	v_fma_f32 v75, v75, v97, v83
	v_fma_f32 v66, v72, v66, v80
	v_fma_f32 v67, v73, v67, v81
	v_fma_f32 v70, v70, v88, v78
	v_fma_f32 v71, v71, v89, v79
	v_fma_f32 v68, v68, v90, v76
	v_fma_f32 v69, v69, v91, v77
	v_fma_f32 v64, v94, v64, v66
	v_fma_f32 v65, v94, v65, v67
	v_fma_f32 v48, v94, v48, v74
	v_fma_f32 v49, v94, v49, v75
	v_fma_f32 v66, v94, v98, v68
	v_fma_f32 v67, v94, v99, v69
	v_fma_f32 v50, v94, v50, v70
	v_fma_f32 v51, v94, v51, v71
	v_mul_f32_e32 v46, v46, v48
	v_mul_f32_e32 v47, v47, v49
	v_mul_f32_e32 v44, v44, v64
	v_mul_f32_e32 v45, v45, v65
	v_mul_f32_e32 v48, v42, v50
	v_mul_f32_e32 v49, v43, v51
	v_mul_f32_e32 v42, v40, v66
	v_mul_f32_e32 v43, v41, v67
	v_cvt_pk_bf16_f32 v40, v44, v45
	v_cvt_pk_bf16_f32 v41, v46, v47
	v_cvt_pk_bf16_f32 v42, v42, v43
	v_cvt_pk_bf16_f32 v43, v48, v49
	global_store_dwordx4 v[92:93], v[40:43], off
	global_load_dwordx4 v[40:43], v[142:143], off offset:128
	s_nop 0
	global_load_dwordx4 v[44:47], v[140:141], off offset:128
	global_load_dwordx4 v[64:67], v[140:141], off offset:144
	global_load_dwordx4 v[68:71], v[142:143], off offset:144
	v_mov_b32_e32 v57, v60
	v_mov_b32_e32 v59, v62
	v_mul_f32_e32 v52, v52, v100
	v_mul_f32_e32 v53, v53, v100
	v_mul_f32_e32 v54, v54, v100
	v_mul_f32_e32 v55, v55, v100
	v_mul_f32_e32 v56, v56, v100
	v_mul_f32_e32 v57, v57, v100
	v_mul_f32_e32 v58, v58, v100
	v_mul_f32_e32 v59, v59, v100
	v_add_u32_e32 v50, 0xa0, v146
	v_ashrrev_i32_e32 v51, 31, v50
	v_lshlrev_b64 v[48:49], 10, v[50:51]
	v_lshl_add_u64 v[48:49], v[48:49], 0, v[144:145]
	v_lshlrev_b64 v[48:49], 1, v[48:49]
	v_lshl_add_u64 v[72:73], s[10:11], 0, v[48:49]
	s_waitcnt vmcnt(5)
	v_lshlrev_b32_e32 v74, 16, v84
	v_and_b32_e32 v75, 0xffff0000, v84
	v_lshlrev_b32_e32 v76, 16, v85
	v_and_b32_e32 v77, 0xffff0000, v85
	v_lshlrev_b32_e32 v78, 16, v86
	v_and_b32_e32 v79, 0xffff0000, v86
	v_lshlrev_b32_e32 v80, 16, v87
	v_and_b32_e32 v81, 0xffff0000, v87
	s_waitcnt vmcnt(2)
	v_fma_f32 v42, v46, v54, v42
	v_fma_f32 v43, v47, v55, v43
	v_fma_f32 v40, v44, v52, v40
	v_fma_f32 v41, v45, v53, v41
	s_waitcnt vmcnt(0)
; #define GAS __attribute__((address_space(1)))
;     __device__ __forceinline__ void operator()(const Acc& acc, const Unit& u, int wr, int wc, int fr, int fq) const {
;     ...
;                 const int row = row0 + ai * HALF + m * 16;
;                 const size_t off = (size_t)row * D + colb;
;                 f32x4 y[2][2], v[2][2];
; #pragma unroll
;                 for (int bj = 0; bj < 2; ++bj) { unpack8(*(const GAS u32x4*)(Y + off + 32 * bj), y[bj][0], y[bj][1]); unpack8(*(const GAS u32x4*)(V + off + 32 * bj), v[bj][0], v[bj][1]); }
;                 const float bs = BON[(size_t)row * 16 + head];
;                 float s = 0.f;
; #pragma unroll
;                 for (int bj = 0; bj < 2; ++bj)
; #pragma unroll
;                     for (int n = 0; n < 2; ++n) s += (y[bj][n][0] + y[bj][n][1]) + (y[bj][n][2] + y[bj][n][3]);
;                 s += __shfl_xor(s, 16); s += __shfl_xor(s, 32);
;                 const float mean = s * (1.f / 64.f);
;                 float q = 0.f;
; #pragma unroll
;                 for (int bj = 0; bj < 2; ++bj)
; #pragma unroll
;                     for (int n = 0; n < 2; ++n) { y[bj][n] = y[bj][n] - mean; q += (y[bj][n][0] * y[bj][n][0] + y[bj][n][1] * y[bj][n][1]) + (y[bj][n][2] * y[bj][n][2] + y[bj][n][3] * y[bj][n][3]); }
;                 q += __shfl_xor(q, 16); q += __shfl_xor(q, 32);
;                 const float rs = rsqrtf(q * (1.f / 64.f) + 64e-5f);
; #pragma unroll
;                 for (int bj = 0; bj < 2; ++bj) {
;                     f32x4 o[2];
; #pragma unroll
;                     for (int n = 0; n < 2; ++n) {
;                         const f32x4 lw = *(const GAS f32x4*)(ln_w + colb + 32 * bj + 4 * n), lb = *(const GAS f32x4*)(ln_b + colb + 32 * bj + 4 * n);
;                         o[n] = (y[bj][n] * rs * lw + lb + v[bj][n] * bs) * acc[ai][bj][m][n];
;                     }
;                     *(GAS u32x4*)(YG + off + 32 * bj) = pack8(o[0], o[1]);
	v_fma_f32 v44, v66, v58, v70
	v_fma_f32 v45, v67, v59, v71
	v_fma_f32 v46, v64, v56, v68
	v_fma_f32 v47, v65, v57, v69
	v_fma_f32 v40, v94, v74, v40
	v_fma_f32 v41, v94, v75, v41
	v_fma_f32 v42, v94, v76, v42
	v_fma_f32 v43, v94, v77, v43
	v_fma_f32 v46, v94, v78, v46
	v_fma_f32 v47, v94, v79, v47
	v_fma_f32 v44, v94, v80, v44
	v_fma_f32 v45, v94, v81, v45
	v_mul_f32_e32 v38, v38, v42
	v_mul_f32_e32 v39, v39, v43
	v_mul_f32_e32 v36, v36, v40
	v_mul_f32_e32 v37, v37, v41
	v_mul_f32_e32 v40, v34, v44
	v_mul_f32_e32 v41, v35, v45
	v_mul_f32_e32 v34, v32, v46
	v_mul_f32_e32 v35, v33, v47
	v_cvt_pk_bf16_f32 v32, v36, v37
	v_cvt_pk_bf16_f32 v33, v38, v39
	v_cvt_pk_bf16_f32 v34, v34, v35
	v_cvt_pk_bf16_f32 v35, v40, v41
	global_store_dwordx4 v[92:93], v[32:35], off offset:64
	global_load_dwordx4 v[40:43], v[72:73], off offset:64
	global_load_dwordx4 v[52:55], v[72:73], off
	v_lshlrev_b64 v[32:33], 6, v[50:51]
	v_lshl_add_u64 v[68:69], s[14:15], 0, v[32:33]
	v_lshl_add_u64 v[70:71], s[12:13], 0, v[48:49]
	global_load_dwordx4 v[32:35], v[70:71], off
	v_lshl_add_u64 v[68:69], v[68:69], 0, s[34:35]
	s_waitcnt vmcnt(2)
	v_lshlrev_b32_e32 v36, 16, v40
	s_waitcnt vmcnt(1)
	v_lshlrev_b32_e32 v51, 16, v53
	v_lshlrev_b32_e32 v50, 16, v52
	v_and_b32_e32 v73, 0xffff0000, v53
	v_and_b32_e32 v72, 0xffff0000, v52
	v_lshlrev_b32_e32 v75, 16, v55
	v_lshlrev_b32_e32 v74, 16, v54
	v_and_b32_e32 v77, 0xffff0000, v55
	v_and_b32_e32 v76, 0xffff0000, v54
	v_add_f32_e32 v52, v50, v72
	v_add_f32_e32 v53, v51, v73
	v_add_f32_e32 v54, v74, v76
	v_add_f32_e32 v55, v75, v77
	v_and_b32_e32 v37, 0xffff0000, v40
	v_lshlrev_b32_e32 v38, 16, v41
	v_and_b32_e32 v39, 0xffff0000, v41
	v_add_f32_e32 v41, v52, v53
	v_add_f32_e32 v52, v54, v54
	v_add_f32_e32 v53, v54, v55
	v_lshlrev_b32_e32 v40, 16, v42
	v_and_b32_e32 v44, 0xffff0000, v42
	v_lshlrev_b32_e32 v42, 16, v43
	v_and_b32_e32 v46, 0xffff0000, v43
	v_add_f32_e32 v43, v36, v37
	v_add_f32_e32 v47, v38, v39
	v_add_f32_e32 v45, 0, v41
	v_mov_b32_e32 v41, v53
	v_add_f32_e32 v54, v42, v46
	v_add_f32_e32 v55, v43, v47
	v_add_f32_e32 v52, v40, v44
	v_add_f32_e32 v53, v41, v45
	s_nop 0
	v_add_f32_e32 v52, v52, v54
	v_add_f32_e32 v53, v53, v55
	s_nop 0
	v_add_f32_e32 v41, v52, v53
	global_load_dwordx4 v[52:55], v[140:141], off offset:16
	global_load_dwordx4 v[56:59], v[140:141], off
	global_load_dwordx4 v[60:63], v[142:143], off offset:16
	global_load_dwordx4 v[64:67], v[142:143], off
	flat_load_dword v78, v[68:69]
	ds_bpermute_b32 v43, v154, v41
	s_waitcnt lgkmcnt(0)
	v_add_f32_e32 v41, v41, v43
	ds_bpermute_b32 v43, v155, v41
	s_waitcnt lgkmcnt(0)
	v_add_f32_e32 v41, v41, v43
	v_fmac_f32_e32 v72, 0xbc800000, v41
	v_fmac_f32_e32 v73, 0xbc800000, v41
	v_fmac_f32_e32 v51, 0xbc800000, v41
	v_fmac_f32_e32 v76, 0xbc800000, v41
	v_fmac_f32_e32 v77, 0xbc800000, v41
	v_fmac_f32_e32 v75, 0xbc800000, v41
	v_fmac_f32_e32 v50, 0xbc800000, v41
	v_fmac_f32_e32 v74, 0xbc800000, v41
	v_fmac_f32_e32 v36, 0xbc800000, v41
	v_fmac_f32_e32 v38, 0xbc800000, v41
	v_mov_b32_e32 v80, v51
	v_mov_b32_e32 v81, v73
	v_mov_b32_e32 v51, v72
	v_mov_b32_e32 v72, v75
	v_mov_b32_e32 v73, v77
	v_mov_b32_e32 v75, v76
	v_fmac_f32_e32 v37, 0xbc800000, v41
	v_fmac_f32_e32 v39, 0xbc800000, v41
	v_mul_f32_e32 v68, v36, v36
	v_mul_f32_e32 v76, v38, v38
	v_mul_f32_e32 v82, v80, v80
	v_mul_f32_e32 v83, v81, v81
	v_mul_f32_e32 v84, v50, v50
	v_mul_f32_e32 v85, v51, v51
	v_mul_f32_e32 v86, v72, v72
	v_mul_f32_e32 v87, v73, v73
	v_mul_f32_e32 v88, v74, v74
	v_mul_f32_e32 v89, v75, v75
	v_fmac_f32_e32 v44, 0xbc800000, v41
	v_fmac_f32_e32 v40, 0xbc800000, v41
	v_fma_f32 v69, v37, v37, v68
	v_fma_f32 v68, v36, v36, v68
	v_fma_f32 v77, v39, v39, v76
	v_fma_f32 v76, v38, v38, v76
	v_pk_mov_b32 v[90:91], v[84:85], v[82:83] op_sel:[1,0]
	v_mov_b32_e32 v85, v83
	v_pk_mov_b32 v[82:83], v[88:89], v[86:87] op_sel:[1,0]
	v_mov_b32_e32 v89, v87
	v_mul_f32_e32 v68, v40, v40
	v_mul_f32_e32 v76, v44, v44
	v_add_f32_e32 v84, v90, v84
	v_add_f32_e32 v85, v91, v85
	v_add_f32_e32 v82, v82, v88
	v_add_f32_e32 v83, v83, v89
	v_fmac_f32_e32 v46, 0xbc800000, v41
	v_fmac_f32_e32 v42, 0xbc800000, v41
	v_add_f32_e32 v68, v68, v76
	v_add_f32_e32 v69, v69, v77
	v_add_f32_e32 v76, v84, v84
	v_add_f32_e32 v77, v84, v85
	v_add_f32_e32 v83, v82, v83
	v_add_f32_e32 v82, v82, v82
	v_mul_f32_e32 v76, v42, v42
	v_mul_f32_e32 v82, v46, v46
	v_add_f32_e32 v76, v76, v82
	v_add_f32_e32 v77, v77, v83
	s_waitcnt vmcnt(0)
	v_lshlrev_b32_e32 v82, 16, v34
	v_add_f32_e32 v68, v68, v76
	v_add_f32_e32 v69, v69, v77
	v_lshl_add_u64 v[76:77], s[20:21], 0, v[48:49]
	v_add_f32_e32 v41, v68, v69
	ds_bpermute_b32 v43, v154, v41
	v_lshlrev_b32_e32 v48, 16, v32
	v_and_b32_e32 v49, 0xffff0000, v32
	v_lshlrev_b32_e32 v32, 16, v33
	v_and_b32_e32 v33, 0xffff0000, v33
	s_waitcnt lgkmcnt(0)
	v_add_f32_e32 v41, v41, v43
	ds_bpermute_b32 v43, v155, v41
	v_and_b32_e32 v83, 0xffff0000, v34
	v_lshlrev_b32_e32 v34, 16, v35
	v_and_b32_e32 v35, 0xffff0000, v35
	global_load_dwordx4 v[68:71], v[70:71], off offset:64
	s_waitcnt lgkmcnt(0)
; #define GAS __attribute__((address_space(1)))
;     __device__ __forceinline__ void operator()(const Acc& acc, const Unit& u, int wr, int wc, int fr, int fq) const {
;     ...
;                 s += __shfl_xor(s, 16); s += __shfl_xor(s, 32);
;                 const float mean = s * (1.f / 64.f);
;                 float q = 0.f;
; #pragma unroll
;                 for (int bj = 0; bj < 2; ++bj)
; #pragma unroll
;                     for (int n = 0; n < 2; ++n) { y[bj][n] = y[bj][n] - mean; q += (y[bj][n][0] * y[bj][n][0] + y[bj][n][1] * y[bj][n][1]) + (y[bj][n][2] * y[bj][n][2] + y[bj][n][3] * y[bj][n][3]); }
;                 q += __shfl_xor(q, 16); q += __shfl_xor(q, 32);
;                 const float rs = rsqrtf(q * (1.f / 64.f) + 64e-5f);
; #pragma unroll
;                 for (int bj = 0; bj < 2; ++bj) {
;                     f32x4 o[2];
; #pragma unroll
;                     for (int n = 0; n < 2; ++n) {
;                         const f32x4 lw = *(const GAS f32x4*)(ln_w + colb + 32 * bj + 4 * n), lb = *(const GAS f32x4*)(ln_b + colb + 32 * bj + 4 * n);
;                         o[n] = (y[bj][n] * rs * lw + lb + v[bj][n] * bs) * acc[ai][bj][m][n];
;                     }
;                     *(GAS u32x4*)(YG + off + 32 * bj) = pack8(o[0], o[1]);
	v_add_f32_e32 v41, v41, v43
	v_fmamk_f32 v41, v41, 0x3c800000, v160
	v_mul_f32_e32 v43, 0x4b800000, v41
	v_cmp_gt_f32_e32 vcc, s78, v41
	s_nop 1
	v_cndmask_b32_e32 v41, v41, v43, vcc
	v_rsq_f32_e32 v41, v41
	s_nop 0
	v_mul_f32_e32 v43, 0x45800000, v41
	v_cndmask_b32_e32 v84, v41, v43, vcc
	v_mul_f32_e32 v50, v50, v84
	v_mul_f32_e32 v51, v51, v84
	v_mul_f32_e32 v80, v80, v84
	v_mul_f32_e32 v81, v81, v84
	v_mul_f32_e32 v74, v74, v84
	v_mul_f32_e32 v75, v75, v84
	v_mul_f32_e32 v72, v72, v84
	v_mul_f32_e32 v73, v73, v84
	v_fma_f32 v58, v58, v80, v66
	v_fma_f32 v59, v59, v81, v67
	v_fma_f32 v50, v56, v50, v64
	v_fma_f32 v51, v57, v51, v65
	v_fma_f32 v54, v54, v72, v62
	v_fma_f32 v55, v55, v73, v63
	v_fma_f32 v52, v52, v74, v60
	v_fma_f32 v53, v53, v75, v61
	v_fma_f32 v48, v78, v48, v50
	v_fma_f32 v49, v78, v49, v51
	v_fma_f32 v32, v78, v32, v58
	v_fma_f32 v33, v78, v33, v59
	v_fma_f32 v50, v78, v82, v52
	v_fma_f32 v51, v78, v83, v53
	v_fma_f32 v34, v78, v34, v54
	v_fma_f32 v35, v78, v35, v55
	v_mul_f32_e32 v30, v30, v32
	v_mul_f32_e32 v31, v31, v33
	v_mul_f32_e32 v28, v28, v48
	v_mul_f32_e32 v29, v29, v49
	v_mul_f32_e32 v32, v26, v34
	v_mul_f32_e32 v33, v27, v35
	v_mul_f32_e32 v26, v24, v50
	v_mul_f32_e32 v27, v25, v51
	v_cvt_pk_bf16_f32 v24, v28, v29
	v_cvt_pk_bf16_f32 v25, v30, v31
	v_cvt_pk_bf16_f32 v26, v26, v27
	v_cvt_pk_bf16_f32 v27, v32, v33
	global_store_dwordx4 v[76:77], v[24:27], off
	global_load_dwordx4 v[24:27], v[142:143], off offset:128
	s_nop 0
	global_load_dwordx4 v[28:31], v[140:141], off offset:128
	global_load_dwordx4 v[48:51], v[140:141], off offset:144
	global_load_dwordx4 v[52:55], v[142:143], off offset:144
	v_mov_b32_e32 v41, v44
	v_mov_b32_e32 v43, v46
	v_mul_f32_e32 v36, v36, v84
	v_mul_f32_e32 v37, v37, v84
	v_mul_f32_e32 v38, v38, v84
	v_mul_f32_e32 v39, v39, v84
	v_mul_f32_e32 v40, v40, v84
	v_mul_f32_e32 v41, v41, v84
	v_mul_f32_e32 v42, v42, v84
	v_mul_f32_e32 v43, v43, v84
	v_add_u32_e32 v34, 0xb0, v146
	v_ashrrev_i32_e32 v35, 31, v34
	v_lshlrev_b64 v[32:33], 10, v[34:35]
	v_lshl_add_u64 v[32:33], v[32:33], 0, v[144:145]
	v_lshlrev_b64 v[32:33], 1, v[32:33]
	v_lshl_add_u64 v[56:57], s[10:11], 0, v[32:33]
	s_waitcnt vmcnt(5)
	v_lshlrev_b32_e32 v58, 16, v68
	v_and_b32_e32 v59, 0xffff0000, v68
	v_lshlrev_b32_e32 v60, 16, v69
	v_and_b32_e32 v61, 0xffff0000, v69
	v_lshlrev_b32_e32 v62, 16, v70
	v_and_b32_e32 v63, 0xffff0000, v70
	v_lshlrev_b32_e32 v64, 16, v71
	v_and_b32_e32 v65, 0xffff0000, v71
	s_waitcnt vmcnt(2)
	v_fma_f32 v26, v30, v38, v26
	v_fma_f32 v27, v31, v39, v27
	v_fma_f32 v24, v28, v36, v24
	v_fma_f32 v25, v29, v37, v25
	s_waitcnt vmcnt(0)
	v_fma_f32 v28, v50, v42, v54
	v_fma_f32 v29, v51, v43, v55
	v_fma_f32 v30, v48, v40, v52
	v_fma_f32 v31, v49, v41, v53
	v_fma_f32 v24, v78, v58, v24
	v_fma_f32 v25, v78, v59, v25
	v_fma_f32 v26, v78, v60, v26
	v_fma_f32 v27, v78, v61, v27
	v_fma_f32 v30, v78, v62, v30
	v_fma_f32 v31, v78, v63, v31
	v_fma_f32 v28, v78, v64, v28
	v_fma_f32 v29, v78, v65, v29
	v_mul_f32_e32 v22, v22, v26
	v_mul_f32_e32 v23, v23, v27
	v_mul_f32_e32 v20, v20, v24
	v_mul_f32_e32 v21, v21, v25
	v_mul_f32_e32 v24, v18, v28
	v_mul_f32_e32 v25, v19, v29
	v_mul_f32_e32 v18, v16, v30
	v_mul_f32_e32 v19, v17, v31
	v_cvt_pk_bf16_f32 v16, v20, v21
	v_cvt_pk_bf16_f32 v17, v22, v23
	v_cvt_pk_bf16_f32 v18, v18, v19
	v_cvt_pk_bf16_f32 v19, v24, v25
	global_store_dwordx4 v[76:77], v[16:19], off offset:64
	global_load_dwordx4 v[24:27], v[56:57], off offset:64
	global_load_dwordx4 v[36:39], v[56:57], off
	v_lshlrev_b64 v[16:17], 6, v[34:35]
	v_lshl_add_u64 v[52:53], s[14:15], 0, v[16:17]
	v_lshl_add_u64 v[54:55], s[12:13], 0, v[32:33]
	global_load_dwordx4 v[16:19], v[54:55], off
	v_lshl_add_u64 v[52:53], v[52:53], 0, s[34:35]
	s_waitcnt vmcnt(2)
	v_lshlrev_b32_e32 v20, 16, v24
	s_waitcnt vmcnt(1)
	v_lshlrev_b32_e32 v35, 16, v37
	v_lshlrev_b32_e32 v34, 16, v36
	v_and_b32_e32 v57, 0xffff0000, v37
	v_and_b32_e32 v56, 0xffff0000, v36
	v_lshlrev_b32_e32 v59, 16, v39
	v_lshlrev_b32_e32 v58, 16, v38
	v_and_b32_e32 v61, 0xffff0000, v39
	v_and_b32_e32 v60, 0xffff0000, v38
	v_add_f32_e32 v36, v34, v56
	v_add_f32_e32 v37, v35, v57
	v_add_f32_e32 v38, v58, v60
	v_add_f32_e32 v39, v59, v61
	v_and_b32_e32 v21, 0xffff0000, v24
	v_lshlrev_b32_e32 v22, 16, v25
	v_and_b32_e32 v23, 0xffff0000, v25
	v_add_f32_e32 v25, v36, v37
	v_add_f32_e32 v36, v38, v38
	v_add_f32_e32 v37, v38, v39
	v_lshlrev_b32_e32 v24, 16, v26
	v_and_b32_e32 v30, 0xffff0000, v26
	v_lshlrev_b32_e32 v26, 16, v27
	v_and_b32_e32 v28, 0xffff0000, v27
	v_add_f32_e32 v27, v20, v21
	v_add_f32_e32 v29, v22, v23
	v_add_f32_e32 v31, 0, v25
	v_mov_b32_e32 v25, v37
	v_add_f32_e32 v38, v26, v28
	v_add_f32_e32 v39, v27, v29
	v_add_f32_e32 v36, v24, v30
	v_add_f32_e32 v37, v25, v31
	s_nop 0
	v_add_f32_e32 v36, v36, v38
	v_add_f32_e32 v37, v37, v39
	s_nop 0
	v_add_f32_e32 v25, v36, v37
	global_load_dwordx4 v[36:39], v[140:141], off offset:16
	global_load_dwordx4 v[40:43], v[140:141], off
	global_load_dwordx4 v[44:47], v[142:143], off offset:16
	global_load_dwordx4 v[48:51], v[142:143], off
	flat_load_dword v62, v[52:53]
	ds_bpermute_b32 v27, v154, v25
	s_waitcnt lgkmcnt(0)
	v_add_f32_e32 v25, v25, v27
	ds_bpermute_b32 v27, v155, v25
	s_waitcnt lgkmcnt(0)
; #define GAS __attribute__((address_space(1)))
; #define PG8_BAR __builtin_amdgcn_s_barrier()
; template <class Epi>
; __device__ __forceinline__ void gemm_phase(LAS unsigned char* lds, const int wid, const Gemm g, const Epi& E) {
;     ...
;         if (wr == 0) PG8_BAR;
;         { int le = lane; asm volatile("" : "+v"(le)); E(acc, cur, wr, wc, le & 15, le >> 4); }
;         if (!has_next) break;
; #pragma unroll
;         for (int a = 0; a < 2; ++a)
; #pragma unroll
;             for (int b = 0; b < 2; ++b)
; #pragma unroll
;                 for (int m = 0; m < 4; ++m)
; #pragma unroll
;                     for (int n = 0; n < 2; ++n) acc[a][b][m][n] = (f32x4){0.f, 0.f, 0.f, 0.f};
;         cur = nxt; cA = nA; cB = nB; ++ui;
;         if (wr == 1) PG8_BAR;
;     __device__ __forceinline__ void operator()(const Acc& acc, const Unit& u, int wr, int wc, int fr, int fq) const {
;     ...
;                 s += __shfl_xor(s, 16); s += __shfl_xor(s, 32);
;                 const float mean = s * (1.f / 64.f);
;                 float q = 0.f;
; #pragma unroll
;                 for (int bj = 0; bj < 2; ++bj)
; #pragma unroll
;                     for (int n = 0; n < 2; ++n) { y[bj][n] = y[bj][n] - mean; q += (y[bj][n][0] * y[bj][n][0] + y[bj][n][1] * y[bj][n][1]) + (y[bj][n][2] * y[bj][n][2] + y[bj][n][3] * y[bj][n][3]); }
;                 q += __shfl_xor(q, 16); q += __shfl_xor(q, 32);
;                 const float rs = rsqrtf(q * (1.f / 64.f) + 64e-5f);
; #pragma unroll
;                 for (int bj = 0; bj < 2; ++bj) {
;                     f32x4 o[2];
; #pragma unroll
;                     for (int n = 0; n < 2; ++n) {
;                         const f32x4 lw = *(const GAS f32x4*)(ln_w + colb + 32 * bj + 4 * n), lb = *(const GAS f32x4*)(ln_b + colb + 32 * bj + 4 * n);
;                         o[n] = (y[bj][n] * rs * lw + lb + v[bj][n] * bs) * acc[ai][bj][m][n];
;                     }
;                     *(GAS u32x4*)(YG + off + 32 * bj) = pack8(o[0], o[1]);
;                 }
;                 asm volatile("" ::: "memory");
	v_add_f32_e32 v25, v25, v27
	v_fmac_f32_e32 v56, 0xbc800000, v25
	v_fmac_f32_e32 v57, 0xbc800000, v25
	v_fmac_f32_e32 v35, 0xbc800000, v25
	v_fmac_f32_e32 v60, 0xbc800000, v25
	v_fmac_f32_e32 v61, 0xbc800000, v25
	v_fmac_f32_e32 v59, 0xbc800000, v25
	v_fmac_f32_e32 v34, 0xbc800000, v25
	v_fmac_f32_e32 v58, 0xbc800000, v25
	v_fmac_f32_e32 v20, 0xbc800000, v25
	v_fmac_f32_e32 v22, 0xbc800000, v25
	v_mov_b32_e32 v64, v35
	v_mov_b32_e32 v65, v57
	v_mov_b32_e32 v35, v56
	v_mov_b32_e32 v56, v59
	v_mov_b32_e32 v57, v61
	v_mov_b32_e32 v59, v60
	v_fmac_f32_e32 v21, 0xbc800000, v25
	v_fmac_f32_e32 v23, 0xbc800000, v25
	v_mul_f32_e32 v52, v20, v20
	v_mul_f32_e32 v60, v22, v22
	v_mul_f32_e32 v66, v64, v64
	v_mul_f32_e32 v67, v65, v65
	v_mul_f32_e32 v68, v34, v34
	v_mul_f32_e32 v69, v35, v35
	v_mul_f32_e32 v70, v56, v56
	v_mul_f32_e32 v71, v57, v57
	v_mul_f32_e32 v72, v58, v58
	v_mul_f32_e32 v73, v59, v59
	v_fmac_f32_e32 v30, 0xbc800000, v25
	v_fmac_f32_e32 v24, 0xbc800000, v25
	v_fma_f32 v53, v21, v21, v52
	v_fma_f32 v52, v20, v20, v52
	v_fma_f32 v61, v23, v23, v60
	v_fma_f32 v60, v22, v22, v60
	v_pk_mov_b32 v[74:75], v[68:69], v[66:67] op_sel:[1,0]
	v_mov_b32_e32 v69, v67
	v_pk_mov_b32 v[66:67], v[72:73], v[70:71] op_sel:[1,0]
	v_mov_b32_e32 v73, v71
	v_mul_f32_e32 v52, v24, v24
	v_mul_f32_e32 v60, v30, v30
	v_add_f32_e32 v68, v74, v68
	v_add_f32_e32 v69, v75, v69
	v_add_f32_e32 v66, v66, v72
	v_add_f32_e32 v67, v67, v73
	v_fmac_f32_e32 v28, 0xbc800000, v25
	v_fmac_f32_e32 v26, 0xbc800000, v25
	v_add_f32_e32 v52, v52, v60
	v_add_f32_e32 v53, v53, v61
	v_add_f32_e32 v60, v68, v68
	v_add_f32_e32 v61, v68, v69
	v_add_f32_e32 v67, v66, v67
	v_add_f32_e32 v66, v66, v66
	v_mul_f32_e32 v60, v26, v26
	v_mul_f32_e32 v66, v28, v28
	v_add_f32_e32 v60, v60, v66
	v_add_f32_e32 v61, v61, v67
	s_waitcnt vmcnt(0)
	v_lshlrev_b32_e32 v66, 16, v18
	v_add_f32_e32 v52, v52, v60
	v_add_f32_e32 v53, v53, v61
	v_lshl_add_u64 v[60:61], s[20:21], 0, v[32:33]
	v_add_f32_e32 v25, v52, v53
	ds_bpermute_b32 v27, v154, v25
	v_lshlrev_b32_e32 v32, 16, v16
	v_and_b32_e32 v33, 0xffff0000, v16
	v_lshlrev_b32_e32 v16, 16, v17
	v_and_b32_e32 v17, 0xffff0000, v17
	s_waitcnt lgkmcnt(0)
	v_add_f32_e32 v25, v25, v27
	ds_bpermute_b32 v27, v155, v25
	v_and_b32_e32 v67, 0xffff0000, v18
	v_lshlrev_b32_e32 v18, 16, v19
	v_and_b32_e32 v19, 0xffff0000, v19
	global_load_dwordx4 v[52:55], v[54:55], off offset:64
	s_waitcnt lgkmcnt(0)
	v_add_f32_e32 v25, v25, v27
	v_fmamk_f32 v25, v25, 0x3c800000, v160
	v_mul_f32_e32 v27, 0x4b800000, v25
	v_cmp_gt_f32_e32 vcc, s78, v25
	s_nop 1
	v_cndmask_b32_e32 v25, v25, v27, vcc
	v_rsq_f32_e32 v25, v25
	s_nop 0
	v_mul_f32_e32 v27, 0x45800000, v25
	v_cndmask_b32_e32 v68, v25, v27, vcc
	v_mul_f32_e32 v34, v34, v68
	v_mul_f32_e32 v35, v35, v68
	v_mul_f32_e32 v64, v64, v68
	v_mul_f32_e32 v65, v65, v68
	v_mul_f32_e32 v58, v58, v68
	v_mul_f32_e32 v59, v59, v68
	v_mul_f32_e32 v56, v56, v68
	v_mul_f32_e32 v57, v57, v68
	v_fma_f32 v42, v42, v64, v50
	v_fma_f32 v43, v43, v65, v51
	v_fma_f32 v34, v40, v34, v48
	v_fma_f32 v35, v41, v35, v49
	v_fma_f32 v38, v38, v56, v46
	v_fma_f32 v39, v39, v57, v47
	v_fma_f32 v36, v36, v58, v44
	v_fma_f32 v37, v37, v59, v45
	v_fma_f32 v32, v62, v32, v34
	v_fma_f32 v33, v62, v33, v35
	v_fma_f32 v16, v62, v16, v42
	v_fma_f32 v17, v62, v17, v43
	v_fma_f32 v34, v62, v66, v36
	v_fma_f32 v35, v62, v67, v37
	v_fma_f32 v18, v62, v18, v38
	v_fma_f32 v19, v62, v19, v39
	v_mul_f32_e32 v14, v14, v16
	v_mul_f32_e32 v15, v15, v17
	v_mul_f32_e32 v12, v12, v32
	v_mul_f32_e32 v13, v13, v33
	v_mul_f32_e32 v16, v10, v18
	v_mul_f32_e32 v17, v11, v19
	v_mul_f32_e32 v10, v8, v34
	v_mul_f32_e32 v11, v9, v35
	v_cvt_pk_bf16_f32 v8, v12, v13
	v_cvt_pk_bf16_f32 v9, v14, v15
	v_cvt_pk_bf16_f32 v10, v10, v11
	v_cvt_pk_bf16_f32 v11, v16, v17
	global_store_dwordx4 v[60:61], v[8:11], off
	global_load_dwordx4 v[8:11], v[142:143], off offset:128
	s_nop 0
	global_load_dwordx4 v[12:15], v[140:141], off offset:128
	global_load_dwordx4 v[16:19], v[140:141], off offset:144
	global_load_dwordx4 v[32:35], v[142:143], off offset:144
	v_mov_b32_e32 v25, v30
	v_mov_b32_e32 v27, v28
	v_mul_f32_e32 v20, v20, v68
	v_mul_f32_e32 v21, v21, v68
	v_mul_f32_e32 v22, v22, v68
	v_mul_f32_e32 v23, v23, v68
	v_mul_f32_e32 v24, v24, v68
	v_mul_f32_e32 v25, v25, v68
	v_mul_f32_e32 v26, v26, v68
	v_mul_f32_e32 v27, v27, v68
	s_andn2_b64 vcc, exec, s[2:3]
	s_mov_b64 s[2:3], -1
	s_waitcnt vmcnt(5)
	v_lshlrev_b32_e32 v36, 16, v52
	v_and_b32_e32 v37, 0xffff0000, v52
	v_lshlrev_b32_e32 v38, 16, v53
	v_and_b32_e32 v39, 0xffff0000, v53
	v_lshlrev_b32_e32 v40, 16, v54
	v_and_b32_e32 v41, 0xffff0000, v54
	v_lshlrev_b32_e32 v42, 16, v55
	v_and_b32_e32 v43, 0xffff0000, v55
	s_waitcnt vmcnt(2)
	v_fma_f32 v10, v14, v22, v10
	v_fma_f32 v11, v15, v23, v11
	v_fma_f32 v8, v12, v20, v8
	v_fma_f32 v9, v13, v21, v9
	s_waitcnt vmcnt(0)
	v_fma_f32 v12, v18, v26, v34
	v_fma_f32 v13, v19, v27, v35
	v_fma_f32 v14, v16, v24, v32
	v_fma_f32 v15, v17, v25, v33
	v_fma_f32 v8, v62, v36, v8
	v_fma_f32 v9, v62, v37, v9
	v_fma_f32 v10, v62, v38, v10
	v_fma_f32 v11, v62, v39, v11
	v_fma_f32 v14, v62, v40, v14
	v_fma_f32 v15, v62, v41, v15
	v_fma_f32 v12, v62, v42, v12
	v_fma_f32 v13, v62, v43, v13
	v_mul_f32_e32 v6, v6, v10
	v_mul_f32_e32 v7, v7, v11
	v_mul_f32_e32 v4, v4, v8
	v_mul_f32_e32 v5, v5, v9
	v_mul_f32_e32 v8, v2, v12
	v_mul_f32_e32 v9, v3, v13
	v_mul_f32_e32 v2, v0, v14
	v_mul_f32_e32 v3, v1, v15
	v_cvt_pk_bf16_f32 v0, v4, v5
	v_cvt_pk_bf16_f32 v1, v6, v7
	v_cvt_pk_bf16_f32 v2, v2, v3
	v_cvt_pk_bf16_f32 v3, v8, v9
	global_store_dwordx4 v[60:61], v[0:3], off offset:64
	s_cbranch_vccnz .LBB0_2964
	s_andn2_b64 vcc, exec, s[6:7]
	s_cbranch_vccnz .LBB0_2963
	s_barrier
	s_branch .LBB0_2963

; #define GAS __attribute__((address_space(1)))
;     __device__ __forceinline__ void operator()(const Acc& acc, const Unit& u, int wr, int wc, int fr, int fq) const {
;         const int row0 = u.pm * BM + wr * 64 + fr, col0 = u.pn * BM + wc * 32 + 8 * fq;
; #pragma unroll
;         for (int ai = 0; ai < 2; ++ai)
; #pragma unroll
;             for (int m = 0; m < 4; ++m) {
;                 const size_t off = (size_t)(row0 + ai * HALF + m * 16) * D + col0;
; #pragma unroll
;                 for (int bj = 0; bj < 2; ++bj) {
;                     const size_t p = off + bj * HALF;
;                     f32x4 b0, b1;
;                     if (BASE_F32) { b0 = *(const GAS f32x4*)((const float*)base + p); b1 = *(const GAS f32x4*)((const float*)base + p + 4); }
;                     else unpack8h(*(const GAS u32x4*)((const bf16_t*)base + p), b0, b1);
;                     b0 += acc[ai][bj][m][0]; b1 += acc[ai][bj][m][1];
;                     if (OUT_F32) { *(GAS f32x4*)((float*)out + p) = b0; *(GAS f32x4*)((float*)out + p + 4) = b1; }
;                     else *(GAS u32x4*)((bf16_t*)out + p) = pack8h(b0, b1);
;                 }
;                 asm volatile("" ::: "memory");
;             }
.LBB0_3251:
	v_mov_b32_e32 v140, v147
	s_lshl_b32 s26, s57, 8
	s_add_i32 s26, s26, s47
	v_and_or_b32 v144, v140, 15, s26
	s_lshl_b32 s26, s58, 8
	v_ashrrev_i32_e32 v140, 1, v140
	s_or_b32 s26, s26, s48
	v_and_b32_e32 v140, -8, v140
	v_add_u32_e32 v142, s26, v140
	v_ashrrev_i32_e32 v145, 31, v144
	v_ashrrev_i32_e32 v143, 31, v142
	v_lshlrev_b64 v[140:141], 10, v[144:145]
	v_lshl_add_u64 v[140:141], v[140:141], 0, v[142:143]
	v_lshl_add_u64 v[156:157], v[140:141], 1, s[12:13]
	global_load_dwordx4 v[152:155], v[156:157], off
	v_lshl_add_u64 v[158:159], v[140:141], 2, s[6:7]
	s_and_b64 vcc, exec, s[0:1]
	s_mov_b64 s[0:1], -1
	s_waitcnt vmcnt(0)
	v_cvt_f32_f16_e32 v160, v152
	v_cvt_f32_f16_sdwa v161, v152 dst_sel:DWORD dst_unused:UNUSED_PAD src0_sel:WORD_1
	v_cvt_f32_f16_e32 v152, v153
	v_cvt_f32_f16_sdwa v153, v153 dst_sel:DWORD dst_unused:UNUSED_PAD src0_sel:WORD_1
	v_cvt_f32_f16_e32 v162, v154
	v_cvt_f32_f16_e32 v164, v155
	v_cvt_f32_f16_sdwa v165, v155 dst_sel:DWORD dst_unused:UNUSED_PAD src0_sel:WORD_1
	v_cvt_f32_f16_sdwa v163, v154 dst_sel:DWORD dst_unused:UNUSED_PAD src0_sel:WORD_1
	v_add_f32_e32 v126, v126, v152
	v_add_f32_e32 v127, v127, v153
	v_add_f32_e32 v124, v124, v160
	v_add_f32_e32 v125, v125, v161
	v_add_f32_e32 v122, v122, v164
	v_add_f32_e32 v123, v123, v165
	v_add_f32_e32 v120, v120, v162
	v_add_f32_e32 v121, v121, v163
	global_store_dwordx4 v[158:159], v[124:127], off
	global_store_dwordx4 v[158:159], v[120:123], off offset:16
	global_load_dwordx4 v[120:123], v[156:157], off offset:256
	v_or_b32_e32 v124, 16, v144
	v_ashrrev_i32_e32 v125, 31, v124
	v_lshlrev_b64 v[124:125], 10, v[124:125]
	v_lshl_add_u64 v[124:125], v[124:125], 0, v[142:143]
	v_lshl_add_u64 v[126:127], v[124:125], 1, s[12:13]
	s_waitcnt vmcnt(0)
	v_cvt_f32_f16_e32 v152, v120
	v_cvt_f32_f16_sdwa v153, v120 dst_sel:DWORD dst_unused:UNUSED_PAD src0_sel:WORD_1
	v_cvt_f32_f16_e32 v120, v121
	v_cvt_f32_f16_sdwa v121, v121 dst_sel:DWORD dst_unused:UNUSED_PAD src0_sel:WORD_1
	v_cvt_f32_f16_e32 v154, v122
	v_cvt_f32_f16_e32 v156, v123
	v_cvt_f32_f16_sdwa v157, v123 dst_sel:DWORD dst_unused:UNUSED_PAD src0_sel:WORD_1
	v_cvt_f32_f16_sdwa v155, v122 dst_sel:DWORD dst_unused:UNUSED_PAD src0_sel:WORD_1
	v_add_f32_e32 v118, v118, v120
	v_add_f32_e32 v119, v119, v121
	v_add_f32_e32 v116, v116, v152
	v_add_f32_e32 v117, v117, v153
	v_add_f32_e32 v114, v114, v156
	v_add_f32_e32 v115, v115, v157
	v_add_f32_e32 v112, v112, v154
	v_add_f32_e32 v113, v113, v155
	global_store_dwordx4 v[158:159], v[116:119], off offset:512
	global_store_dwordx4 v[158:159], v[112:115], off offset:528
	global_load_dwordx4 v[112:115], v[126:127], off
	v_lshl_add_u64 v[116:117], v[124:125], 2, s[6:7]
	s_waitcnt vmcnt(0)
	v_cvt_f32_f16_e32 v118, v112
	v_cvt_f32_f16_sdwa v119, v112 dst_sel:DWORD dst_unused:UNUSED_PAD src0_sel:WORD_1
	v_cvt_f32_f16_e32 v112, v113
	v_cvt_f32_f16_sdwa v113, v113 dst_sel:DWORD dst_unused:UNUSED_PAD src0_sel:WORD_1
	v_cvt_f32_f16_e32 v120, v114
	v_cvt_f32_f16_e32 v122, v115
	v_cvt_f32_f16_sdwa v123, v115 dst_sel:DWORD dst_unused:UNUSED_PAD src0_sel:WORD_1
	v_cvt_f32_f16_sdwa v121, v114 dst_sel:DWORD dst_unused:UNUSED_PAD src0_sel:WORD_1
	v_add_f32_e32 v110, v110, v112
	v_add_f32_e32 v111, v111, v113
	v_add_f32_e32 v108, v108, v118
	v_add_f32_e32 v109, v109, v119
	v_add_f32_e32 v106, v106, v122
	v_add_f32_e32 v107, v107, v123
	v_add_f32_e32 v104, v104, v120
	v_add_f32_e32 v105, v105, v121
	global_store_dwordx4 v[116:117], v[108:111], off
	global_store_dwordx4 v[116:117], v[104:107], off offset:16
	global_load_dwordx4 v[104:107], v[126:127], off offset:256
	v_or_b32_e32 v108, 32, v144
	v_ashrrev_i32_e32 v109, 31, v108
	v_lshlrev_b64 v[108:109], 10, v[108:109]
	v_lshl_add_u64 v[108:109], v[108:109], 0, v[142:143]
	v_lshl_add_u64 v[110:111], v[108:109], 1, s[12:13]
	s_waitcnt vmcnt(0)
	v_cvt_f32_f16_e32 v112, v104
	v_cvt_f32_f16_sdwa v113, v104 dst_sel:DWORD dst_unused:UNUSED_PAD src0_sel:WORD_1
	v_cvt_f32_f16_e32 v104, v105
	v_cvt_f32_f16_sdwa v105, v105 dst_sel:DWORD dst_unused:UNUSED_PAD src0_sel:WORD_1
	v_cvt_f32_f16_e32 v114, v106
	v_cvt_f32_f16_e32 v118, v107
	v_cvt_f32_f16_sdwa v119, v107 dst_sel:DWORD dst_unused:UNUSED_PAD src0_sel:WORD_1
	v_cvt_f32_f16_sdwa v115, v106 dst_sel:DWORD dst_unused:UNUSED_PAD src0_sel:WORD_1
	v_add_f32_e32 v102, v102, v104
	v_add_f32_e32 v103, v103, v105
	v_add_f32_e32 v100, v100, v112
	v_add_f32_e32 v101, v101, v113
	v_add_f32_e32 v98, v98, v118
	v_add_f32_e32 v99, v99, v119
	v_add_f32_e32 v96, v96, v114
	v_add_f32_e32 v97, v97, v115
	global_store_dwordx4 v[116:117], v[100:103], off offset:512
	global_store_dwordx4 v[116:117], v[96:99], off offset:528
	global_load_dwordx4 v[96:99], v[110:111], off
	v_lshl_add_u64 v[100:101], v[108:109], 2, s[6:7]
	s_waitcnt vmcnt(0)
	v_cvt_f32_f16_e32 v102, v96
	v_cvt_f32_f16_sdwa v103, v96 dst_sel:DWORD dst_unused:UNUSED_PAD src0_sel:WORD_1
	v_cvt_f32_f16_e32 v96, v97
	v_cvt_f32_f16_sdwa v97, v97 dst_sel:DWORD dst_unused:UNUSED_PAD src0_sel:WORD_1
	v_cvt_f32_f16_e32 v104, v98
	v_cvt_f32_f16_e32 v106, v99
	v_cvt_f32_f16_sdwa v107, v99 dst_sel:DWORD dst_unused:UNUSED_PAD src0_sel:WORD_1
	v_cvt_f32_f16_sdwa v105, v98 dst_sel:DWORD dst_unused:UNUSED_PAD src0_sel:WORD_1
	v_add_f32_e32 v94, v94, v96
	v_add_f32_e32 v95, v95, v97
	v_add_f32_e32 v92, v92, v102
	v_add_f32_e32 v93, v93, v103
	v_add_f32_e32 v90, v90, v106
	v_add_f32_e32 v91, v91, v107
	v_add_f32_e32 v88, v88, v104
	v_add_f32_e32 v89, v89, v105
	global_store_dwordx4 v[100:101], v[92:95], off
	global_store_dwordx4 v[100:101], v[88:91], off offset:16
	global_load_dwordx4 v[88:91], v[110:111], off offset:256
	v_or_b32_e32 v92, 48, v144
	v_ashrrev_i32_e32 v93, 31, v92
	v_lshlrev_b64 v[92:93], 10, v[92:93]
	v_lshl_add_u64 v[92:93], v[92:93], 0, v[142:143]
	v_lshl_add_u64 v[94:95], v[92:93], 1, s[12:13]
	s_waitcnt vmcnt(0)
; #define GAS __attribute__((address_space(1)))
;     __device__ __forceinline__ void operator()(const Acc& acc, const Unit& u, int wr, int wc, int fr, int fq) const {
;         const int row0 = u.pm * BM + wr * 64 + fr, col0 = u.pn * BM + wc * 32 + 8 * fq;
; #pragma unroll
;         for (int ai = 0; ai < 2; ++ai)
; #pragma unroll
;             for (int m = 0; m < 4; ++m) {
;                 const size_t off = (size_t)(row0 + ai * HALF + m * 16) * D + col0;
; #pragma unroll
;                 for (int bj = 0; bj < 2; ++bj) {
;                     const size_t p = off + bj * HALF;
;                     f32x4 b0, b1;
;                     if (BASE_F32) { b0 = *(const GAS f32x4*)((const float*)base + p); b1 = *(const GAS f32x4*)((const float*)base + p + 4); }
;                     else unpack8h(*(const GAS u32x4*)((const bf16_t*)base + p), b0, b1);
;                     b0 += acc[ai][bj][m][0]; b1 += acc[ai][bj][m][1];
;                     if (OUT_F32) { *(GAS f32x4*)((float*)out + p) = b0; *(GAS f32x4*)((float*)out + p + 4) = b1; }
;                     else *(GAS u32x4*)((bf16_t*)out + p) = pack8h(b0, b1);
;                 }
;                 asm volatile("" ::: "memory");
;             }
	v_cvt_f32_f16_e32 v96, v88
	v_cvt_f32_f16_sdwa v97, v88 dst_sel:DWORD dst_unused:UNUSED_PAD src0_sel:WORD_1
	v_cvt_f32_f16_e32 v88, v89
	v_cvt_f32_f16_sdwa v89, v89 dst_sel:DWORD dst_unused:UNUSED_PAD src0_sel:WORD_1
	v_cvt_f32_f16_e32 v98, v90
	v_cvt_f32_f16_e32 v102, v91
	v_cvt_f32_f16_sdwa v103, v91 dst_sel:DWORD dst_unused:UNUSED_PAD src0_sel:WORD_1
	v_cvt_f32_f16_sdwa v99, v90 dst_sel:DWORD dst_unused:UNUSED_PAD src0_sel:WORD_1
	v_add_f32_e32 v86, v86, v88
	v_add_f32_e32 v87, v87, v89
	v_add_f32_e32 v84, v84, v96
	v_add_f32_e32 v85, v85, v97
	v_add_f32_e32 v82, v82, v102
	v_add_f32_e32 v83, v83, v103
	v_add_f32_e32 v80, v80, v98
	v_add_f32_e32 v81, v81, v99
	global_store_dwordx4 v[100:101], v[84:87], off offset:512
	global_store_dwordx4 v[100:101], v[80:83], off offset:528
	global_load_dwordx4 v[80:83], v[94:95], off
	v_lshl_add_u64 v[84:85], v[92:93], 2, s[6:7]
	s_waitcnt vmcnt(0)
	v_cvt_f32_f16_e32 v86, v80
	v_cvt_f32_f16_sdwa v87, v80 dst_sel:DWORD dst_unused:UNUSED_PAD src0_sel:WORD_1
	v_cvt_f32_f16_e32 v80, v81
	v_cvt_f32_f16_sdwa v81, v81 dst_sel:DWORD dst_unused:UNUSED_PAD src0_sel:WORD_1
	v_cvt_f32_f16_e32 v88, v82
	v_cvt_f32_f16_e32 v90, v83
	v_cvt_f32_f16_sdwa v91, v83 dst_sel:DWORD dst_unused:UNUSED_PAD src0_sel:WORD_1
	v_cvt_f32_f16_sdwa v89, v82 dst_sel:DWORD dst_unused:UNUSED_PAD src0_sel:WORD_1
	v_add_f32_e32 v78, v78, v80
	v_add_f32_e32 v79, v79, v81
	v_add_f32_e32 v76, v76, v86
	v_add_f32_e32 v77, v77, v87
	v_add_f32_e32 v74, v74, v90
	v_add_f32_e32 v75, v75, v91
	v_add_f32_e32 v72, v72, v88
	v_add_f32_e32 v73, v73, v89
	global_store_dwordx4 v[84:85], v[76:79], off
	global_store_dwordx4 v[84:85], v[72:75], off offset:16
	global_load_dwordx4 v[72:75], v[94:95], off offset:256
	v_lshl_add_u64 v[76:77], v[140:141], 0, s[14:15]
	v_lshl_add_u64 v[78:79], v[76:77], 1, s[12:13]
	s_waitcnt vmcnt(0)
	v_cvt_f32_f16_e32 v80, v72
	v_cvt_f32_f16_sdwa v81, v72 dst_sel:DWORD dst_unused:UNUSED_PAD src0_sel:WORD_1
	v_cvt_f32_f16_e32 v72, v73
	v_cvt_f32_f16_sdwa v73, v73 dst_sel:DWORD dst_unused:UNUSED_PAD src0_sel:WORD_1
	v_cvt_f32_f16_e32 v82, v74
	v_cvt_f32_f16_e32 v86, v75
	v_cvt_f32_f16_sdwa v87, v75 dst_sel:DWORD dst_unused:UNUSED_PAD src0_sel:WORD_1
	v_cvt_f32_f16_sdwa v83, v74 dst_sel:DWORD dst_unused:UNUSED_PAD src0_sel:WORD_1
	v_add_f32_e32 v70, v70, v72
	v_add_f32_e32 v71, v71, v73
	v_add_f32_e32 v68, v68, v80
	v_add_f32_e32 v69, v69, v81
	v_add_f32_e32 v66, v66, v86
	v_add_f32_e32 v67, v67, v87
	v_add_f32_e32 v64, v64, v82
	v_add_f32_e32 v65, v65, v83
	global_store_dwordx4 v[84:85], v[68:71], off offset:512
	global_store_dwordx4 v[84:85], v[64:67], off offset:528
	global_load_dwordx4 v[64:67], v[78:79], off
	v_lshl_add_u64 v[68:69], v[76:77], 2, s[6:7]
	s_waitcnt vmcnt(0)
	v_cvt_f32_f16_e32 v70, v64
	v_cvt_f32_f16_sdwa v71, v64 dst_sel:DWORD dst_unused:UNUSED_PAD src0_sel:WORD_1
	v_cvt_f32_f16_e32 v64, v65
	v_cvt_f32_f16_sdwa v65, v65 dst_sel:DWORD dst_unused:UNUSED_PAD src0_sel:WORD_1
	v_cvt_f32_f16_e32 v72, v66
	v_cvt_f32_f16_e32 v74, v67
	v_cvt_f32_f16_sdwa v75, v67 dst_sel:DWORD dst_unused:UNUSED_PAD src0_sel:WORD_1
	v_cvt_f32_f16_sdwa v73, v66 dst_sel:DWORD dst_unused:UNUSED_PAD src0_sel:WORD_1
	v_add_f32_e32 v62, v62, v64
	v_add_f32_e32 v63, v63, v65
	v_add_f32_e32 v60, v60, v70
	v_add_f32_e32 v61, v61, v71
	v_add_f32_e32 v58, v58, v74
	v_add_f32_e32 v59, v59, v75
	v_add_f32_e32 v56, v56, v72
	v_add_f32_e32 v57, v57, v73
	global_store_dwordx4 v[68:69], v[60:63], off
	global_store_dwordx4 v[68:69], v[56:59], off offset:16
	global_load_dwordx4 v[56:59], v[78:79], off offset:256
	v_lshl_add_u64 v[60:61], v[140:141], 0, s[16:17]
	v_lshl_add_u64 v[62:63], v[60:61], 1, s[12:13]
	s_waitcnt vmcnt(0)
	v_cvt_f32_f16_e32 v64, v56
	v_cvt_f32_f16_sdwa v65, v56 dst_sel:DWORD dst_unused:UNUSED_PAD src0_sel:WORD_1
	v_cvt_f32_f16_e32 v56, v57
	v_cvt_f32_f16_sdwa v57, v57 dst_sel:DWORD dst_unused:UNUSED_PAD src0_sel:WORD_1
	v_cvt_f32_f16_e32 v66, v58
	v_cvt_f32_f16_e32 v70, v59
	v_cvt_f32_f16_sdwa v71, v59 dst_sel:DWORD dst_unused:UNUSED_PAD src0_sel:WORD_1
	v_cvt_f32_f16_sdwa v67, v58 dst_sel:DWORD dst_unused:UNUSED_PAD src0_sel:WORD_1
	v_add_f32_e32 v54, v54, v56
	v_add_f32_e32 v55, v55, v57
	v_add_f32_e32 v52, v52, v64
	v_add_f32_e32 v53, v53, v65
	v_add_f32_e32 v50, v50, v70
	v_add_f32_e32 v51, v51, v71
	v_add_f32_e32 v48, v48, v66
	v_add_f32_e32 v49, v49, v67
	global_store_dwordx4 v[68:69], v[52:55], off offset:512
	global_store_dwordx4 v[68:69], v[48:51], off offset:528
	global_load_dwordx4 v[48:51], v[62:63], off
	v_lshl_add_u64 v[52:53], v[60:61], 2, s[6:7]
	s_waitcnt vmcnt(0)
; #define GAS __attribute__((address_space(1)))
; #define PG8_BAR __builtin_amdgcn_s_barrier()
; template <class Epi>
; __device__ __forceinline__ void gemm_phase(LAS unsigned char* lds, const int wid, const Gemm g, const Epi& E) {
;     ...
;         if (wr == 0) PG8_BAR;
;         { int le = lane; asm volatile("" : "+v"(le)); E(acc, cur, wr, wc, le & 15, le >> 4); }
;         if (!has_next) break;
; #pragma unroll
;         for (int a = 0; a < 2; ++a)
; #pragma unroll
;             for (int b = 0; b < 2; ++b)
; #pragma unroll
;                 for (int m = 0; m < 4; ++m)
; #pragma unroll
;                     for (int n = 0; n < 2; ++n) acc[a][b][m][n] = (f32x4){0.f, 0.f, 0.f, 0.f};
;         cur = nxt; cA = nA; cB = nB; ++ui;
;         if (wr == 1) PG8_BAR;
;     __device__ __forceinline__ void operator()(const Acc& acc, const Unit& u, int wr, int wc, int fr, int fq) const {
;         const int row0 = u.pm * BM + wr * 64 + fr, col0 = u.pn * BM + wc * 32 + 8 * fq;
; #pragma unroll
;         for (int ai = 0; ai < 2; ++ai)
; #pragma unroll
;             for (int m = 0; m < 4; ++m) {
;                 const size_t off = (size_t)(row0 + ai * HALF + m * 16) * D + col0;
; #pragma unroll
;                 for (int bj = 0; bj < 2; ++bj) {
;                     const size_t p = off + bj * HALF;
;                     f32x4 b0, b1;
;                     if (BASE_F32) { b0 = *(const GAS f32x4*)((const float*)base + p); b1 = *(const GAS f32x4*)((const float*)base + p + 4); }
;                     else unpack8h(*(const GAS u32x4*)((const bf16_t*)base + p), b0, b1);
;                     b0 += acc[ai][bj][m][0]; b1 += acc[ai][bj][m][1];
;                     if (OUT_F32) { *(GAS f32x4*)((float*)out + p) = b0; *(GAS f32x4*)((float*)out + p + 4) = b1; }
;                     else *(GAS u32x4*)((bf16_t*)out + p) = pack8h(b0, b1);
;                 }
;                 asm volatile("" ::: "memory");
;             }
	v_cvt_f32_f16_e32 v54, v48
	v_cvt_f32_f16_sdwa v55, v48 dst_sel:DWORD dst_unused:UNUSED_PAD src0_sel:WORD_1
	v_cvt_f32_f16_e32 v48, v49
	v_cvt_f32_f16_sdwa v49, v49 dst_sel:DWORD dst_unused:UNUSED_PAD src0_sel:WORD_1
	v_cvt_f32_f16_e32 v56, v50
	v_cvt_f32_f16_e32 v58, v51
	v_cvt_f32_f16_sdwa v59, v51 dst_sel:DWORD dst_unused:UNUSED_PAD src0_sel:WORD_1
	v_cvt_f32_f16_sdwa v57, v50 dst_sel:DWORD dst_unused:UNUSED_PAD src0_sel:WORD_1
	v_add_f32_e32 v46, v46, v48
	v_add_f32_e32 v47, v47, v49
	v_add_f32_e32 v44, v44, v54
	v_add_f32_e32 v45, v45, v55
	v_add_f32_e32 v42, v42, v58
	v_add_f32_e32 v43, v43, v59
	v_add_f32_e32 v40, v40, v56
	v_add_f32_e32 v41, v41, v57
	global_store_dwordx4 v[52:53], v[44:47], off
	global_store_dwordx4 v[52:53], v[40:43], off offset:16
	global_load_dwordx4 v[40:43], v[62:63], off offset:256
	v_lshl_add_u64 v[44:45], v[140:141], 0, s[18:19]
	v_lshl_add_u64 v[46:47], v[44:45], 1, s[12:13]
	s_waitcnt vmcnt(0)
	v_cvt_f32_f16_e32 v48, v40
	v_cvt_f32_f16_sdwa v49, v40 dst_sel:DWORD dst_unused:UNUSED_PAD src0_sel:WORD_1
	v_cvt_f32_f16_e32 v40, v41
	v_cvt_f32_f16_sdwa v41, v41 dst_sel:DWORD dst_unused:UNUSED_PAD src0_sel:WORD_1
	v_cvt_f32_f16_e32 v50, v42
	v_cvt_f32_f16_e32 v54, v43
	v_cvt_f32_f16_sdwa v55, v43 dst_sel:DWORD dst_unused:UNUSED_PAD src0_sel:WORD_1
	v_cvt_f32_f16_sdwa v51, v42 dst_sel:DWORD dst_unused:UNUSED_PAD src0_sel:WORD_1
	v_add_f32_e32 v38, v38, v40
	v_add_f32_e32 v39, v39, v41
	v_add_f32_e32 v36, v36, v48
	v_add_f32_e32 v37, v37, v49
	v_add_f32_e32 v34, v34, v54
	v_add_f32_e32 v35, v35, v55
	v_add_f32_e32 v32, v32, v50
	v_add_f32_e32 v33, v33, v51
	global_store_dwordx4 v[52:53], v[36:39], off offset:512
	global_store_dwordx4 v[52:53], v[32:35], off offset:528
	global_load_dwordx4 v[32:35], v[46:47], off
	v_lshl_add_u64 v[36:37], v[44:45], 2, s[6:7]
	s_waitcnt vmcnt(0)
	v_cvt_f32_f16_e32 v38, v32
	v_cvt_f32_f16_sdwa v39, v32 dst_sel:DWORD dst_unused:UNUSED_PAD src0_sel:WORD_1
	v_cvt_f32_f16_e32 v32, v33
	v_cvt_f32_f16_sdwa v33, v33 dst_sel:DWORD dst_unused:UNUSED_PAD src0_sel:WORD_1
	v_cvt_f32_f16_e32 v40, v34
	v_cvt_f32_f16_e32 v42, v35
	v_cvt_f32_f16_sdwa v43, v35 dst_sel:DWORD dst_unused:UNUSED_PAD src0_sel:WORD_1
	v_cvt_f32_f16_sdwa v41, v34 dst_sel:DWORD dst_unused:UNUSED_PAD src0_sel:WORD_1
	v_add_f32_e32 v30, v30, v32
	v_add_f32_e32 v31, v31, v33
	v_add_f32_e32 v28, v28, v38
	v_add_f32_e32 v29, v29, v39
	v_add_f32_e32 v26, v26, v42
	v_add_f32_e32 v27, v27, v43
	v_add_f32_e32 v24, v24, v40
	v_add_f32_e32 v25, v25, v41
	global_store_dwordx4 v[36:37], v[28:31], off
	global_store_dwordx4 v[36:37], v[24:27], off offset:16
	global_load_dwordx4 v[24:27], v[46:47], off offset:256
	v_lshl_add_u64 v[28:29], v[140:141], 0, s[20:21]
	v_lshl_add_u64 v[30:31], v[28:29], 1, s[12:13]
	s_waitcnt vmcnt(0)
	v_cvt_f32_f16_e32 v32, v24
	v_cvt_f32_f16_sdwa v33, v24 dst_sel:DWORD dst_unused:UNUSED_PAD src0_sel:WORD_1
	v_cvt_f32_f16_e32 v24, v25
	v_cvt_f32_f16_sdwa v25, v25 dst_sel:DWORD dst_unused:UNUSED_PAD src0_sel:WORD_1
	v_cvt_f32_f16_e32 v34, v26
	v_cvt_f32_f16_e32 v38, v27
	v_cvt_f32_f16_sdwa v39, v27 dst_sel:DWORD dst_unused:UNUSED_PAD src0_sel:WORD_1
	v_cvt_f32_f16_sdwa v35, v26 dst_sel:DWORD dst_unused:UNUSED_PAD src0_sel:WORD_1
	v_add_f32_e32 v22, v22, v24
	v_add_f32_e32 v23, v23, v25
	v_add_f32_e32 v20, v20, v32
	v_add_f32_e32 v21, v21, v33
	v_add_f32_e32 v18, v18, v38
	v_add_f32_e32 v19, v19, v39
	v_add_f32_e32 v16, v16, v34
	v_add_f32_e32 v17, v17, v35
	global_store_dwordx4 v[36:37], v[20:23], off offset:512
	global_store_dwordx4 v[36:37], v[16:19], off offset:528
	global_load_dwordx4 v[16:19], v[30:31], off
	v_lshl_add_u64 v[20:21], v[28:29], 2, s[6:7]
	s_waitcnt vmcnt(0)
	v_cvt_f32_f16_e32 v22, v16
	v_cvt_f32_f16_sdwa v23, v16 dst_sel:DWORD dst_unused:UNUSED_PAD src0_sel:WORD_1
	v_cvt_f32_f16_e32 v16, v17
	v_cvt_f32_f16_sdwa v17, v17 dst_sel:DWORD dst_unused:UNUSED_PAD src0_sel:WORD_1
	v_cvt_f32_f16_e32 v24, v18
	v_cvt_f32_f16_e32 v26, v19
	v_cvt_f32_f16_sdwa v27, v19 dst_sel:DWORD dst_unused:UNUSED_PAD src0_sel:WORD_1
	v_cvt_f32_f16_sdwa v25, v18 dst_sel:DWORD dst_unused:UNUSED_PAD src0_sel:WORD_1
	v_add_f32_e32 v14, v14, v16
	v_add_f32_e32 v15, v15, v17
	v_add_f32_e32 v12, v12, v22
	v_add_f32_e32 v13, v13, v23
	v_add_f32_e32 v10, v10, v26
	v_add_f32_e32 v11, v11, v27
	v_add_f32_e32 v8, v8, v24
	v_add_f32_e32 v9, v9, v25
	global_store_dwordx4 v[20:21], v[12:15], off
	global_store_dwordx4 v[20:21], v[8:11], off offset:16
	global_load_dwordx4 v[8:11], v[30:31], off offset:256
	s_waitcnt vmcnt(0)
	v_cvt_f32_f16_e32 v12, v8
	v_cvt_f32_f16_sdwa v13, v8 dst_sel:DWORD dst_unused:UNUSED_PAD src0_sel:WORD_1
	v_cvt_f32_f16_e32 v8, v9
	v_cvt_f32_f16_sdwa v9, v9 dst_sel:DWORD dst_unused:UNUSED_PAD src0_sel:WORD_1
	v_cvt_f32_f16_e32 v14, v10
	v_cvt_f32_f16_e32 v16, v11
	v_cvt_f32_f16_sdwa v17, v11 dst_sel:DWORD dst_unused:UNUSED_PAD src0_sel:WORD_1
	v_cvt_f32_f16_sdwa v15, v10 dst_sel:DWORD dst_unused:UNUSED_PAD src0_sel:WORD_1
	v_add_f32_e32 v6, v6, v8
	v_add_f32_e32 v7, v7, v9
	v_add_f32_e32 v4, v4, v12
	v_add_f32_e32 v5, v5, v13
	v_add_f32_e32 v2, v2, v16
	v_add_f32_e32 v3, v3, v17
	v_add_f32_e32 v0, v0, v14
	v_add_f32_e32 v1, v1, v15
	global_store_dwordx4 v[20:21], v[4:7], off offset:512
	global_store_dwordx4 v[20:21], v[0:3], off offset:528
	s_cbranch_vccnz .LBB0_3236
	s_andn2_b64 vcc, exec, s[8:9]
	s_cbranch_vccnz .LBB0_3235
	s_barrier
	s_branch .LBB0_3235
